# speedup vs baseline: 1.0042x; 1.0042x over previous
; #define STAGE(P, BASE, LD, br, kt) do { const int _so = (int)(((br) * (LD) + (kt) * BK) * 2); \
;     _Pragma("unroll") for (int _i = 0; _i < 2; ++_i) { \
;       __builtin_amdgcn_raw_ptr_buffer_load_lds(rs##BASE, (__attribute__((address_space(3))) unsigned*)((char*)(P) + tid_ * 16 + _i * 8192), 16, (int)off##LD[_i], _so, 0, 0); } } while (0)
; #define LDA_(dst, b, h) _Pragma("unroll") for (int m = 0; m < 4; ++m) _Pragma("unroll") for (int k = 0; k < 2; ++k) \
;     dst[m][k] = *reinterpret_cast<const bf16x8*>((char*)SA(b, h) + lds_byte(wr * 64 + m * 16 + fr, k * 32 + fq * 8))
; #define LDB_(dst, b, h) _Pragma("unroll") for (int n = 0; n < 2; ++n) _Pragma("unroll") for (int k = 0; k < 2; ++k) \
;     dst[n][k] = *reinterpret_cast<const bf16x8*>((char*)SB(b, h) + lds_byte(wc * 32 + n * 16 + fr, k * 32 + fq * 8))
; #define MMA(ai, bj, At, Bx) do { __builtin_amdgcn_s_setprio(1); \
;     _Pragma("unroll") for (int m = 0; m < 4; ++m) _Pragma("unroll") for (int n = 0; n < 2; ++n) _Pragma("unroll") for (int k = 0; k < 2; ++k) \
;       acc[ai][bj][m][n] = __builtin_amdgcn_mfma_f32_16x16x32_bf16(At[m][k], Bx[n][k], acc[ai][bj][m][n], 0, 0, 0); \
;     __builtin_amdgcn_s_setprio(0); } while (0)
; #define WAIT_V(n) asm volatile("s_waitcnt vmcnt(" #n ")" ::: "memory")
; template <int K, int LDA, int LDB>
; DEVI void gemm_tile(const bf16* __restrict__ A, const bf16* __restrict__ Bt, bf16* shm, acc_t& acc) {
;     ...
;   for (int t = 0; t < nt - 2; t += 2) {
;     LDB_(B0, 0, 0); SCHED; LDA_(At, 0, 0); STAGE(SA(1, 1), A, LDA, HALF, t + 1);
;     WAIT_L(8); BAR; WAIT_L(0); MMA(0, 0, At, B0); BAR; SCHED;
;     LDB_(B1, 0, 1); STAGE(SB(0, 0), Bt, LDB, 0, t + 2);
;     BAR; WAIT_L(0); MMA(0, 1, At, B1); BAR;
;     LDA_(At, 0, 1); STAGE(SA(0, 0), A, LDA, 0, t + 2);
;     BAR; WAIT_L(0); MMA(1, 0, At, B0); BAR; SCHED;
;     STAGE(SB(0, 1), Bt, LDB, HALF, t + 2);
;     WAIT_V(6); BAR; MMA(1, 1, At, B1); BAR;
;     LDB_(B0, 1, 0); SCHED; LDA_(At, 1, 0); STAGE(SA(0, 1), A, LDA, HALF, t + 2);
;     WAIT_L(8); BAR; WAIT_L(0); MMA(0, 0, At, B0); BAR; SCHED;
;     LDB_(B1, 1, 1); STAGE(SB(1, 0), Bt, LDB, 0, t + 3);
;     BAR; WAIT_L(0); MMA(0, 1, At, B1); BAR;
;     LDA_(At, 1, 1); STAGE(SA(1, 0), A, LDA, 0, t + 3);
;     BAR; WAIT_L(0); MMA(1, 0, At, B0); BAR; SCHED;
;     STAGE(SB(1, 1), Bt, LDB, HALF, t + 3);
;     WAIT_V(6); BAR; MMA(1, 1, At, B1); BAR;
.Lrot_2440:
	s_barrier
.LBB0_168:
	ds_read_b128 v[166:169], v160
	ds_read_b128 v[170:173], v160 offset:1024
	ds_read_b128 v[174:177], v160 offset:2048
	ds_read_b128 v[178:181], v160 offset:3072
	v_readfirstlane_b32 s40, v164
	s_add_i32 s39, s17, 0xffffff00
	s_mov_b32 m0, s40
	v_readfirstlane_b32 s40, v161
	ds_read_b128 v[182:185], v135
	ds_read_b128 v[186:189], v135 offset:1024
	ds_read_b128 v[190:193], v134
	ds_read_b128 v[194:197], v134 offset:1024
	ds_read_b128 v[198:201], v133
	ds_read_b128 v[202:205], v133 offset:1024
	ds_read_b128 v[206:209], v132
	ds_read_b128 v[210:213], v132 offset:1024
	buffer_load_dwordx4 v141, s[12:15], s39 offen lds
	s_mov_b32 m0, s40
	s_nop 0
	buffer_load_dwordx4 v143, s[12:15], s39 offen lds
	s_waitcnt lgkmcnt(8)
	s_barrier
	s_waitcnt lgkmcnt(0)
	s_setprio 1
	s_waitcnt lgkmcnt(7)
	v_mfma_f32_16x16x32_bf16 v[126:129], v[182:185], v[166:169], v[126:129]
	v_mfma_f32_16x16x32_bf16 v[122:125], v[182:185], v[174:177], v[122:125]
	s_waitcnt lgkmcnt(5)
	v_mfma_f32_16x16x32_bf16 v[118:121], v[190:193], v[166:169], v[118:121]
	v_mfma_f32_16x16x32_bf16 v[114:117], v[190:193], v[174:177], v[114:117]
	s_waitcnt lgkmcnt(3)
	v_mfma_f32_16x16x32_bf16 v[110:113], v[198:201], v[166:169], v[110:113]
	v_mfma_f32_16x16x32_bf16 v[106:109], v[198:201], v[174:177], v[106:109]
	s_waitcnt lgkmcnt(1)
	v_mfma_f32_16x16x32_bf16 v[102:105], v[206:209], v[166:169], v[102:105]
	v_mfma_f32_16x16x32_bf16 v[98:101], v[206:209], v[174:177], v[98:101]
	v_mfma_f32_16x16x32_bf16 v[126:129], v[186:189], v[170:173], v[126:129]
	v_mfma_f32_16x16x32_bf16 v[122:125], v[186:189], v[178:181], v[122:125]
	v_mfma_f32_16x16x32_bf16 v[118:121], v[194:197], v[170:173], v[118:121]
	v_mfma_f32_16x16x32_bf16 v[114:117], v[194:197], v[178:181], v[114:117]
	v_mfma_f32_16x16x32_bf16 v[110:113], v[202:205], v[170:173], v[110:113]
	v_mfma_f32_16x16x32_bf16 v[106:109], v[202:205], v[178:181], v[106:109]
	s_waitcnt lgkmcnt(0)
	v_mfma_f32_16x16x32_bf16 v[102:105], v[210:213], v[170:173], v[102:105]
	v_mfma_f32_16x16x32_bf16 v[98:101], v[210:213], v[178:181], v[98:101]
	s_setprio 0
	s_barrier
	v_readfirstlane_b32 s40, v145
	s_add_i32 s39, s17, 0xfff7ff80
	s_mov_b32 m0, s40
	v_readfirstlane_b32 s40, v146
	ds_read_b128 v[214:217], v156
	ds_read_b128 v[218:221], v156 offset:1024
	ds_read_b128 v[222:225], v156 offset:2048
	ds_read_b128 v[226:229], v156 offset:3072
	buffer_load_dwordx4 v141, s[4:7], s39 offen lds
	s_mov_b32 m0, s40
	s_nop 0
	buffer_load_dwordx4 v143, s[4:7], s39 offen lds
	s_barrier
	s_waitcnt lgkmcnt(0)
	s_setprio 1
	s_waitcnt lgkmcnt(3)
	v_mfma_f32_16x16x32_bf16 v[94:97], v[182:185], v[214:217], v[94:97]
	s_waitcnt lgkmcnt(1)
	v_mfma_f32_16x16x32_bf16 v[90:93], v[182:185], v[222:225], v[90:93]
	v_mfma_f32_16x16x32_bf16 v[86:89], v[190:193], v[214:217], v[86:89]
	v_mfma_f32_16x16x32_bf16 v[82:85], v[190:193], v[222:225], v[82:85]
	v_mfma_f32_16x16x32_bf16 v[78:81], v[198:201], v[214:217], v[78:81]
	v_mfma_f32_16x16x32_bf16 v[74:77], v[198:201], v[222:225], v[74:77]
	v_mfma_f32_16x16x32_bf16 v[70:73], v[206:209], v[214:217], v[70:73]
	v_mfma_f32_16x16x32_bf16 v[66:69], v[206:209], v[222:225], v[66:69]
	v_mfma_f32_16x16x32_bf16 v[94:97], v[186:189], v[218:221], v[94:97]
	s_waitcnt lgkmcnt(0)
	v_mfma_f32_16x16x32_bf16 v[90:93], v[186:189], v[226:229], v[90:93]
	v_mfma_f32_16x16x32_bf16 v[86:89], v[194:197], v[218:221], v[86:89]
	v_mfma_f32_16x16x32_bf16 v[82:85], v[194:197], v[226:229], v[82:85]
	v_mfma_f32_16x16x32_bf16 v[78:81], v[202:205], v[218:221], v[78:81]
	v_mfma_f32_16x16x32_bf16 v[74:77], v[202:205], v[226:229], v[74:77]
	v_mfma_f32_16x16x32_bf16 v[70:73], v[210:213], v[218:221], v[70:73]
	v_mfma_f32_16x16x32_bf16 v[66:69], v[210:213], v[226:229], v[66:69]
	s_setprio 0
	v_readfirstlane_b32 s40, v147
	s_mov_b32 m0, s40
	v_readfirstlane_b32 s40, v148
	s_barrier
	ds_read_b128 v[182:185], v135 offset:16384
	ds_read_b128 v[186:189], v135 offset:17408
	ds_read_b128 v[190:193], v134 offset:16384
	ds_read_b128 v[194:197], v134 offset:17408
	ds_read_b128 v[198:201], v133 offset:16384
	ds_read_b128 v[202:205], v133 offset:17408
	ds_read_b128 v[206:209], v132 offset:16384
	ds_read_b128 v[210:213], v132 offset:17408
	buffer_load_dwordx4 v141, s[12:15], s39 offen lds
	s_mov_b32 m0, s40
	s_nop 0
	buffer_load_dwordx4 v143, s[12:15], s39 offen lds
	s_barrier
	s_waitcnt lgkmcnt(0)
	s_setprio 1
	s_waitcnt lgkmcnt(7)
	v_mfma_f32_16x16x32_bf16 v[62:65], v[182:185], v[166:169], v[62:65]
	v_mfma_f32_16x16x32_bf16 v[58:61], v[182:185], v[174:177], v[58:61]
	s_waitcnt lgkmcnt(5)
	v_mfma_f32_16x16x32_bf16 v[54:57], v[190:193], v[166:169], v[54:57]
	v_mfma_f32_16x16x32_bf16 v[50:53], v[190:193], v[174:177], v[50:53]
	s_waitcnt lgkmcnt(3)
	v_mfma_f32_16x16x32_bf16 v[46:49], v[198:201], v[166:169], v[46:49]
	v_mfma_f32_16x16x32_bf16 v[42:45], v[198:201], v[174:177], v[42:45]
	s_waitcnt lgkmcnt(1)
	v_mfma_f32_16x16x32_bf16 v[38:41], v[206:209], v[166:169], v[38:41]
	v_mfma_f32_16x16x32_bf16 v[34:37], v[206:209], v[174:177], v[34:37]
	v_mfma_f32_16x16x32_bf16 v[62:65], v[186:189], v[170:173], v[62:65]
	v_mfma_f32_16x16x32_bf16 v[58:61], v[186:189], v[178:181], v[58:61]
	v_mfma_f32_16x16x32_bf16 v[54:57], v[194:197], v[170:173], v[54:57]
	v_mfma_f32_16x16x32_bf16 v[50:53], v[194:197], v[178:181], v[50:53]
	v_mfma_f32_16x16x32_bf16 v[46:49], v[202:205], v[170:173], v[46:49]
	v_mfma_f32_16x16x32_bf16 v[42:45], v[202:205], v[178:181], v[42:45]
	s_waitcnt lgkmcnt(0)
	v_mfma_f32_16x16x32_bf16 v[38:41], v[210:213], v[170:173], v[38:41]
	v_mfma_f32_16x16x32_bf16 v[34:37], v[210:213], v[178:181], v[34:37]
	s_setprio 0
	s_barrier
; #define STAGE(P, BASE, LD, br, kt) do { const int _so = (int)(((br) * (LD) + (kt) * BK) * 2); \
;     _Pragma("unroll") for (int _i = 0; _i < 2; ++_i) { \
;       __builtin_amdgcn_raw_ptr_buffer_load_lds(rs##BASE, (__attribute__((address_space(3))) unsigned*)((char*)(P) + tid_ * 16 + _i * 8192), 16, (int)off##LD[_i], _so, 0, 0); } } while (0)
; #define LDA_(dst, b, h) _Pragma("unroll") for (int m = 0; m < 4; ++m) _Pragma("unroll") for (int k = 0; k < 2; ++k) \
;     dst[m][k] = *reinterpret_cast<const bf16x8*>((char*)SA(b, h) + lds_byte(wr * 64 + m * 16 + fr, k * 32 + fq * 8))
; #define LDB_(dst, b, h) _Pragma("unroll") for (int n = 0; n < 2; ++n) _Pragma("unroll") for (int k = 0; k < 2; ++k) \
;     dst[n][k] = *reinterpret_cast<const bf16x8*>((char*)SB(b, h) + lds_byte(wc * 32 + n * 16 + fr, k * 32 + fq * 8))
; #define MMA(ai, bj, At, Bx) do { __builtin_amdgcn_s_setprio(1); \
;     _Pragma("unroll") for (int m = 0; m < 4; ++m) _Pragma("unroll") for (int n = 0; n < 2; ++n) _Pragma("unroll") for (int k = 0; k < 2; ++k) \
;       acc[ai][bj][m][n] = __builtin_amdgcn_mfma_f32_16x16x32_bf16(At[m][k], Bx[n][k], acc[ai][bj][m][n], 0, 0, 0); \
;     __builtin_amdgcn_s_setprio(0); } while (0)
; #define WAIT_V(n) asm volatile("s_waitcnt vmcnt(" #n ")" ::: "memory")
; #define WAIT_L(n) asm volatile("s_waitcnt lgkmcnt(" #n ")" ::: "memory")
; #define BAR __builtin_amdgcn_s_barrier()
; #define SCHED __builtin_amdgcn_sched_barrier(0)
; template <int K, int LDA, int LDB>
; DEVI void gemm_tile(const bf16* __restrict__ A, const bf16* __restrict__ Bt, bf16* shm, acc_t& acc) {
;     ...
;     LDB_(B1, 0, 1); STAGE(SB(0, 0), Bt, LDB, 0, t + 2);
;     BAR; WAIT_L(0); MMA(0, 1, At, B1); BAR;
;     LDA_(At, 0, 1); STAGE(SA(0, 0), A, LDA, 0, t + 2);
;     BAR; WAIT_L(0); MMA(1, 0, At, B0); BAR; SCHED;
;     STAGE(SB(0, 1), Bt, LDB, HALF, t + 2);
;     WAIT_V(6); BAR; MMA(1, 1, At, B1); BAR;
;     LDB_(B0, 1, 0); SCHED; LDA_(At, 1, 0); STAGE(SA(0, 1), A, LDA, HALF, t + 2);
;     WAIT_L(8); BAR; WAIT_L(0); MMA(0, 0, At, B0); BAR; SCHED;
;     LDB_(B1, 1, 1); STAGE(SB(1, 0), Bt, LDB, 0, t + 3);
;     BAR; WAIT_L(0); MMA(0, 1, At, B1); BAR;
;     LDA_(At, 1, 1); STAGE(SA(1, 0), A, LDA, 0, t + 3);
;     BAR; WAIT_L(0); MMA(1, 0, At, B0); BAR; SCHED;
	v_readfirstlane_b32 s40, v149
	s_add_i32 s39, s17, 0xffffff80
	s_mov_b32 m0, s40
	v_readfirstlane_b32 s40, v150
	buffer_load_dwordx4 v141, s[4:7], s39 offen lds
	s_mov_b32 m0, s40
	s_nop 0
	buffer_load_dwordx4 v143, s[4:7], s39 offen lds
	s_waitcnt vmcnt(6)
	s_barrier
	s_setprio 1
	v_mfma_f32_16x16x32_bf16 v[30:33], v[182:185], v[214:217], v[30:33]
	v_mfma_f32_16x16x32_bf16 v[26:29], v[182:185], v[222:225], v[26:29]
	v_mfma_f32_16x16x32_bf16 v[22:25], v[190:193], v[214:217], v[22:25]
	v_mfma_f32_16x16x32_bf16 v[18:21], v[190:193], v[222:225], v[18:21]
	v_mfma_f32_16x16x32_bf16 v[14:17], v[198:201], v[214:217], v[14:17]
	v_mfma_f32_16x16x32_bf16 v[10:13], v[198:201], v[222:225], v[10:13]
	v_mfma_f32_16x16x32_bf16 v[6:9], v[206:209], v[214:217], v[6:9]
	v_mfma_f32_16x16x32_bf16 v[2:5], v[206:209], v[222:225], v[2:5]
	v_mfma_f32_16x16x32_bf16 v[30:33], v[186:189], v[218:221], v[30:33]
	v_mfma_f32_16x16x32_bf16 v[26:29], v[186:189], v[226:229], v[26:29]
	v_mfma_f32_16x16x32_bf16 v[22:25], v[194:197], v[218:221], v[22:25]
	v_mfma_f32_16x16x32_bf16 v[18:21], v[194:197], v[226:229], v[18:21]
	v_mfma_f32_16x16x32_bf16 v[14:17], v[202:205], v[218:221], v[14:17]
	v_mfma_f32_16x16x32_bf16 v[10:13], v[202:205], v[226:229], v[10:13]
	v_mfma_f32_16x16x32_bf16 v[6:9], v[210:213], v[218:221], v[6:9]
	v_mfma_f32_16x16x32_bf16 v[2:5], v[210:213], v[226:229], v[2:5]
	s_setprio 0
	s_barrier
	ds_read_b128 v[166:169], v144
	ds_read_b128 v[170:173], v144 offset:1024
	ds_read_b128 v[174:177], v144 offset:2048
	ds_read_b128 v[178:181], v144 offset:3072
	v_readfirstlane_b32 s40, v151
	s_mov_b32 m0, s40
	v_readfirstlane_b32 s40, v152
	ds_read_b128 v[182:185], v135 offset:32768
	ds_read_b128 v[186:189], v135 offset:33792
	ds_read_b128 v[190:193], v134 offset:32768
	ds_read_b128 v[194:197], v134 offset:33792
	ds_read_b128 v[198:201], v133 offset:32768
	ds_read_b128 v[202:205], v133 offset:33792
	ds_read_b128 v[206:209], v132 offset:32768
	ds_read_b128 v[210:213], v132 offset:33792
	buffer_load_dwordx4 v141, s[12:15], s39 offen lds
	s_mov_b32 m0, s40
	s_nop 0
	buffer_load_dwordx4 v143, s[12:15], s39 offen lds
	s_waitcnt lgkmcnt(8)
	s_barrier
	s_waitcnt lgkmcnt(0)
	s_setprio 1
	s_waitcnt lgkmcnt(7)
	v_mfma_f32_16x16x32_bf16 v[126:129], v[182:185], v[166:169], v[126:129]
	v_mfma_f32_16x16x32_bf16 v[122:125], v[182:185], v[174:177], v[122:125]
	s_waitcnt lgkmcnt(5)
	v_mfma_f32_16x16x32_bf16 v[118:121], v[190:193], v[166:169], v[118:121]
	v_mfma_f32_16x16x32_bf16 v[114:117], v[190:193], v[174:177], v[114:117]
	s_waitcnt lgkmcnt(3)
	v_mfma_f32_16x16x32_bf16 v[110:113], v[198:201], v[166:169], v[110:113]
	v_mfma_f32_16x16x32_bf16 v[106:109], v[198:201], v[174:177], v[106:109]
	s_waitcnt lgkmcnt(1)
	v_mfma_f32_16x16x32_bf16 v[102:105], v[206:209], v[166:169], v[102:105]
	v_mfma_f32_16x16x32_bf16 v[98:101], v[206:209], v[174:177], v[98:101]
	v_mfma_f32_16x16x32_bf16 v[126:129], v[186:189], v[170:173], v[126:129]
	v_mfma_f32_16x16x32_bf16 v[122:125], v[186:189], v[178:181], v[122:125]
	v_mfma_f32_16x16x32_bf16 v[118:121], v[194:197], v[170:173], v[118:121]
	v_mfma_f32_16x16x32_bf16 v[114:117], v[194:197], v[178:181], v[114:117]
	v_mfma_f32_16x16x32_bf16 v[110:113], v[202:205], v[170:173], v[110:113]
	v_mfma_f32_16x16x32_bf16 v[106:109], v[202:205], v[178:181], v[106:109]
	s_waitcnt lgkmcnt(0)
	v_mfma_f32_16x16x32_bf16 v[102:105], v[210:213], v[170:173], v[102:105]
	v_mfma_f32_16x16x32_bf16 v[98:101], v[210:213], v[178:181], v[98:101]
	s_setprio 0
	s_barrier
	v_readfirstlane_b32 s40, v153
	s_add_i32 s39, s17, 0xfff80000
	s_mov_b32 m0, s40
	v_readfirstlane_b32 s40, v154
	ds_read_b128 v[214:217], v142
	ds_read_b128 v[218:221], v142 offset:1024
	ds_read_b128 v[222:225], v142 offset:2048
	ds_read_b128 v[226:229], v142 offset:3072
	buffer_load_dwordx4 v141, s[4:7], s39 offen lds
	s_mov_b32 m0, s40
	s_nop 0
	buffer_load_dwordx4 v143, s[4:7], s39 offen lds
	s_barrier
	s_waitcnt lgkmcnt(0)
	s_setprio 1
	s_waitcnt lgkmcnt(3)
	v_mfma_f32_16x16x32_bf16 v[94:97], v[182:185], v[214:217], v[94:97]
	s_waitcnt lgkmcnt(1)
	v_mfma_f32_16x16x32_bf16 v[90:93], v[182:185], v[222:225], v[90:93]
	v_mfma_f32_16x16x32_bf16 v[86:89], v[190:193], v[214:217], v[86:89]
	v_mfma_f32_16x16x32_bf16 v[82:85], v[190:193], v[222:225], v[82:85]
	v_mfma_f32_16x16x32_bf16 v[78:81], v[198:201], v[214:217], v[78:81]
	v_mfma_f32_16x16x32_bf16 v[74:77], v[198:201], v[222:225], v[74:77]
	v_mfma_f32_16x16x32_bf16 v[70:73], v[206:209], v[214:217], v[70:73]
	v_mfma_f32_16x16x32_bf16 v[66:69], v[206:209], v[222:225], v[66:69]
	v_mfma_f32_16x16x32_bf16 v[94:97], v[186:189], v[218:221], v[94:97]
	s_waitcnt lgkmcnt(0)
	v_mfma_f32_16x16x32_bf16 v[90:93], v[186:189], v[226:229], v[90:93]
	v_mfma_f32_16x16x32_bf16 v[86:89], v[194:197], v[218:221], v[86:89]
	v_mfma_f32_16x16x32_bf16 v[82:85], v[194:197], v[226:229], v[82:85]
	v_mfma_f32_16x16x32_bf16 v[78:81], v[202:205], v[218:221], v[78:81]
	v_mfma_f32_16x16x32_bf16 v[74:77], v[202:205], v[226:229], v[74:77]
	v_mfma_f32_16x16x32_bf16 v[70:73], v[210:213], v[218:221], v[70:73]
	v_mfma_f32_16x16x32_bf16 v[66:69], v[210:213], v[226:229], v[66:69]
	s_setprio 0
	v_readfirstlane_b32 s40, v155
	s_mov_b32 m0, s40
	v_readfirstlane_b32 s40, v157
	s_barrier
	ds_read_b128 v[182:185], v135 offset:49152
	ds_read_b128 v[186:189], v135 offset:50176
	ds_read_b128 v[190:193], v134 offset:49152
	ds_read_b128 v[194:197], v134 offset:50176
	ds_read_b128 v[198:201], v133 offset:49152
	ds_read_b128 v[202:205], v133 offset:50176
	ds_read_b128 v[206:209], v132 offset:49152
	ds_read_b128 v[210:213], v132 offset:50176
	buffer_load_dwordx4 v141, s[12:15], s39 offen lds
	s_mov_b32 m0, s40
	s_nop 0
	buffer_load_dwordx4 v143, s[12:15], s39 offen lds
	s_barrier
; #define STAGE(P, BASE, LD, br, kt) do { const int _so = (int)(((br) * (LD) + (kt) * BK) * 2); \
;     _Pragma("unroll") for (int _i = 0; _i < 2; ++_i) { \
;       __builtin_amdgcn_raw_ptr_buffer_load_lds(rs##BASE, (__attribute__((address_space(3))) unsigned*)((char*)(P) + tid_ * 16 + _i * 8192), 16, (int)off##LD[_i], _so, 0, 0); } } while (0)
; #define LDA_(dst, b, h) _Pragma("unroll") for (int m = 0; m < 4; ++m) _Pragma("unroll") for (int k = 0; k < 2; ++k) \
;     dst[m][k] = *reinterpret_cast<const bf16x8*>((char*)SA(b, h) + lds_byte(wr * 64 + m * 16 + fr, k * 32 + fq * 8))
; #define LDB_(dst, b, h) _Pragma("unroll") for (int n = 0; n < 2; ++n) _Pragma("unroll") for (int k = 0; k < 2; ++k) \
;     dst[n][k] = *reinterpret_cast<const bf16x8*>((char*)SB(b, h) + lds_byte(wc * 32 + n * 16 + fr, k * 32 + fq * 8))
; #define MMA(ai, bj, At, Bx) do { __builtin_amdgcn_s_setprio(1); \
;     _Pragma("unroll") for (int m = 0; m < 4; ++m) _Pragma("unroll") for (int n = 0; n < 2; ++n) _Pragma("unroll") for (int k = 0; k < 2; ++k) \
;       acc[ai][bj][m][n] = __builtin_amdgcn_mfma_f32_16x16x32_bf16(At[m][k], Bx[n][k], acc[ai][bj][m][n], 0, 0, 0); \
;     __builtin_amdgcn_s_setprio(0); } while (0)
; #define WAIT_V(n) asm volatile("s_waitcnt vmcnt(" #n ")" ::: "memory")
; #define WAIT_L(n) asm volatile("s_waitcnt lgkmcnt(" #n ")" ::: "memory")
; #define BAR __builtin_amdgcn_s_barrier()
; #define SCHED __builtin_amdgcn_sched_barrier(0)
; template <int K, int LDA, int LDB>
; DEVI void gemm_tile(const bf16* __restrict__ A, const bf16* __restrict__ Bt, bf16* shm, acc_t& acc) {
;     ...
;     BAR; WAIT_L(0); MMA(1, 0, At, B0); BAR; SCHED;
;     STAGE(SB(1, 1), Bt, LDB, HALF, t + 3);
;     WAIT_V(6); BAR; MMA(1, 1, At, B1); BAR;
;   }
;   { LDB_(B0, 0, 0); LDA_(At, 0, 0); STAGE(SA(1, 1), A, LDA, HALF, nt - 1);
;     BAR; WAIT_L(0); MMA(0, 0, At, B0); BAR;
;     LDB_(B1, 0, 1); BAR; WAIT_L(0); MMA(0, 1, At, B1); BAR;
	s_waitcnt lgkmcnt(0)
	s_setprio 1
	s_waitcnt lgkmcnt(7)
	v_mfma_f32_16x16x32_bf16 v[62:65], v[182:185], v[166:169], v[62:65]
	v_mfma_f32_16x16x32_bf16 v[58:61], v[182:185], v[174:177], v[58:61]
	s_waitcnt lgkmcnt(5)
	v_mfma_f32_16x16x32_bf16 v[54:57], v[190:193], v[166:169], v[54:57]
	v_mfma_f32_16x16x32_bf16 v[50:53], v[190:193], v[174:177], v[50:53]
	s_waitcnt lgkmcnt(3)
	v_mfma_f32_16x16x32_bf16 v[46:49], v[198:201], v[166:169], v[46:49]
	v_mfma_f32_16x16x32_bf16 v[42:45], v[198:201], v[174:177], v[42:45]
	s_waitcnt lgkmcnt(1)
	v_mfma_f32_16x16x32_bf16 v[38:41], v[206:209], v[166:169], v[38:41]
	v_mfma_f32_16x16x32_bf16 v[34:37], v[206:209], v[174:177], v[34:37]
	v_mfma_f32_16x16x32_bf16 v[62:65], v[186:189], v[170:173], v[62:65]
	v_mfma_f32_16x16x32_bf16 v[58:61], v[186:189], v[178:181], v[58:61]
	v_mfma_f32_16x16x32_bf16 v[54:57], v[194:197], v[170:173], v[54:57]
	v_mfma_f32_16x16x32_bf16 v[50:53], v[194:197], v[178:181], v[50:53]
	v_mfma_f32_16x16x32_bf16 v[46:49], v[202:205], v[170:173], v[46:49]
	v_mfma_f32_16x16x32_bf16 v[42:45], v[202:205], v[178:181], v[42:45]
	s_waitcnt lgkmcnt(0)
	v_mfma_f32_16x16x32_bf16 v[38:41], v[210:213], v[170:173], v[38:41]
	v_mfma_f32_16x16x32_bf16 v[34:37], v[210:213], v[178:181], v[34:37]
	s_setprio 0
	s_barrier
	v_readfirstlane_b32 s39, v158
	s_mov_b32 m0, s39
	v_readfirstlane_b32 s39, v159
	buffer_load_dwordx4 v141, s[4:7], s17 offen lds
	s_mov_b32 m0, s39
	s_nop 0
	buffer_load_dwordx4 v143, s[4:7], s17 offen lds
	s_waitcnt vmcnt(6)
	s_barrier
	s_setprio 1
	v_mfma_f32_16x16x32_bf16 v[30:33], v[182:185], v[214:217], v[30:33]
	v_mfma_f32_16x16x32_bf16 v[26:29], v[182:185], v[222:225], v[26:29]
	v_mfma_f32_16x16x32_bf16 v[22:25], v[190:193], v[214:217], v[22:25]
	v_mfma_f32_16x16x32_bf16 v[18:21], v[190:193], v[222:225], v[18:21]
	v_mfma_f32_16x16x32_bf16 v[14:17], v[198:201], v[214:217], v[14:17]
	v_mfma_f32_16x16x32_bf16 v[10:13], v[198:201], v[222:225], v[10:13]
	v_mfma_f32_16x16x32_bf16 v[6:9], v[206:209], v[214:217], v[6:9]
	v_mfma_f32_16x16x32_bf16 v[2:5], v[206:209], v[222:225], v[2:5]
	v_mfma_f32_16x16x32_bf16 v[30:33], v[186:189], v[218:221], v[30:33]
	v_mfma_f32_16x16x32_bf16 v[26:29], v[186:189], v[226:229], v[26:29]
	v_mfma_f32_16x16x32_bf16 v[22:25], v[194:197], v[218:221], v[22:25]
	v_mfma_f32_16x16x32_bf16 v[18:21], v[194:197], v[226:229], v[18:21]
	v_mfma_f32_16x16x32_bf16 v[14:17], v[202:205], v[218:221], v[14:17]
	v_mfma_f32_16x16x32_bf16 v[10:13], v[202:205], v[226:229], v[10:13]
	v_mfma_f32_16x16x32_bf16 v[6:9], v[210:213], v[218:221], v[6:9]
	v_mfma_f32_16x16x32_bf16 v[2:5], v[210:213], v[226:229], v[2:5]
	s_setprio 0
	s_add_i32 s11, s11, 2
	s_addk_i32 s17, 0x100
	s_cmp_lt_u32 s11, 28
	s_cbranch_scc1 .Lrot_2440
	s_barrier
	v_readfirstlane_b32 s4, v164
	s_mov_b32 s14, s6
	s_mov_b32 s15, s7
	s_mov_b32 m0, s4
	v_readfirstlane_b32 s4, v161
	ds_read_b128 v[146:149], v160
	ds_read_b128 v[150:153], v160 offset:1024
	ds_read_b128 v[166:169], v160 offset:2048
	ds_read_b128 v[170:173], v160 offset:3072
	ds_read_b128 v[174:177], v135
	ds_read_b128 v[178:181], v135 offset:1024
	ds_read_b128 v[182:185], v134
	ds_read_b128 v[186:189], v134 offset:1024
	ds_read_b128 v[190:193], v133
	ds_read_b128 v[194:197], v133 offset:1024
	ds_read_b128 v[198:201], v132
	ds_read_b128 v[202:205], v132 offset:1024
	buffer_load_dwordx4 v141, s[12:15], s37 offen lds
	s_mov_b32 m0, s4
	s_nop 0
	buffer_load_dwordx4 v143, s[12:15], s37 offen lds
	s_barrier
	s_waitcnt lgkmcnt(0)
	s_setprio 1
	s_waitcnt lgkmcnt(7)
	v_mfma_f32_16x16x32_bf16 v[126:129], v[174:177], v[146:149], v[126:129]
	v_mfma_f32_16x16x32_bf16 v[122:125], v[174:177], v[166:169], v[122:125]
	s_waitcnt lgkmcnt(5)
	v_mfma_f32_16x16x32_bf16 v[118:121], v[182:185], v[146:149], v[118:121]
	v_mfma_f32_16x16x32_bf16 v[114:117], v[182:185], v[166:169], v[114:117]
	s_waitcnt lgkmcnt(3)
	v_mfma_f32_16x16x32_bf16 v[110:113], v[190:193], v[146:149], v[110:113]
	v_mfma_f32_16x16x32_bf16 v[106:109], v[190:193], v[166:169], v[106:109]
	s_waitcnt lgkmcnt(1)
	v_mfma_f32_16x16x32_bf16 v[102:105], v[198:201], v[146:149], v[102:105]
	v_mfma_f32_16x16x32_bf16 v[98:101], v[198:201], v[166:169], v[98:101]
	v_mfma_f32_16x16x32_bf16 v[126:129], v[178:181], v[150:153], v[126:129]
	v_mfma_f32_16x16x32_bf16 v[122:125], v[178:181], v[170:173], v[122:125]
	v_mfma_f32_16x16x32_bf16 v[118:121], v[186:189], v[150:153], v[118:121]
	v_mfma_f32_16x16x32_bf16 v[114:117], v[186:189], v[170:173], v[114:117]
	v_mfma_f32_16x16x32_bf16 v[110:113], v[194:197], v[150:153], v[110:113]
	v_mfma_f32_16x16x32_bf16 v[106:109], v[194:197], v[170:173], v[106:109]
	s_waitcnt lgkmcnt(0)
	v_mfma_f32_16x16x32_bf16 v[102:105], v[202:205], v[150:153], v[102:105]
	v_mfma_f32_16x16x32_bf16 v[98:101], v[202:205], v[170:173], v[98:101]
	s_setprio 0
	s_barrier
	ds_read_b128 v[158:161], v156
	ds_read_b128 v[206:209], v156 offset:1024
	ds_read_b128 v[210:213], v156 offset:2048
	ds_read_b128 v[154:157], v156 offset:3072
	s_barrier
	s_waitcnt lgkmcnt(0)
	s_setprio 1
	s_waitcnt lgkmcnt(3)
	v_mfma_f32_16x16x32_bf16 v[94:97], v[174:177], v[158:161], v[94:97]
	s_waitcnt lgkmcnt(1)
	v_mfma_f32_16x16x32_bf16 v[90:93], v[174:177], v[210:213], v[90:93]
	v_mfma_f32_16x16x32_bf16 v[86:89], v[182:185], v[158:161], v[86:89]
	v_mfma_f32_16x16x32_bf16 v[82:85], v[182:185], v[210:213], v[82:85]
	v_mfma_f32_16x16x32_bf16 v[78:81], v[190:193], v[158:161], v[78:81]
	v_mfma_f32_16x16x32_bf16 v[74:77], v[190:193], v[210:213], v[74:77]
	v_mfma_f32_16x16x32_bf16 v[70:73], v[198:201], v[158:161], v[70:73]
	v_mfma_f32_16x16x32_bf16 v[66:69], v[198:201], v[210:213], v[66:69]
	v_mfma_f32_16x16x32_bf16 v[94:97], v[178:181], v[206:209], v[94:97]
	s_waitcnt lgkmcnt(0)
	v_mfma_f32_16x16x32_bf16 v[90:93], v[178:181], v[154:157], v[90:93]
	v_mfma_f32_16x16x32_bf16 v[86:89], v[186:189], v[206:209], v[86:89]
	v_mfma_f32_16x16x32_bf16 v[82:85], v[186:189], v[154:157], v[82:85]
	v_mfma_f32_16x16x32_bf16 v[78:81], v[194:197], v[206:209], v[78:81]
	v_mfma_f32_16x16x32_bf16 v[74:77], v[194:197], v[154:157], v[74:77]
	v_mfma_f32_16x16x32_bf16 v[70:73], v[202:205], v[206:209], v[70:73]
	v_mfma_f32_16x16x32_bf16 v[66:69], v[202:205], v[154:157], v[66:69]
	s_setprio 0
	s_barrier
; #define LDA_(dst, b, h) _Pragma("unroll") for (int m = 0; m < 4; ++m) _Pragma("unroll") for (int k = 0; k < 2; ++k) \
;     dst[m][k] = *reinterpret_cast<const bf16x8*>((char*)SA(b, h) + lds_byte(wr * 64 + m * 16 + fr, k * 32 + fq * 8))
; #define LDB_(dst, b, h) _Pragma("unroll") for (int n = 0; n < 2; ++n) _Pragma("unroll") for (int k = 0; k < 2; ++k) \
;     dst[n][k] = *reinterpret_cast<const bf16x8*>((char*)SB(b, h) + lds_byte(wc * 32 + n * 16 + fr, k * 32 + fq * 8))
; #define MMA(ai, bj, At, Bx) do { __builtin_amdgcn_s_setprio(1); \
;     _Pragma("unroll") for (int m = 0; m < 4; ++m) _Pragma("unroll") for (int n = 0; n < 2; ++n) _Pragma("unroll") for (int k = 0; k < 2; ++k) \
;       acc[ai][bj][m][n] = __builtin_amdgcn_mfma_f32_16x16x32_bf16(At[m][k], Bx[n][k], acc[ai][bj][m][n], 0, 0, 0); \
;     __builtin_amdgcn_s_setprio(0); } while (0)
; #define WAIT_V(n) asm volatile("s_waitcnt vmcnt(" #n ")" ::: "memory")
; #define WAIT_L(n) asm volatile("s_waitcnt lgkmcnt(" #n ")" ::: "memory")
; #define BAR __builtin_amdgcn_s_barrier()
; template <int K, int LDA, int LDB>
; DEVI void gemm_tile(const bf16* __restrict__ A, const bf16* __restrict__ Bt, bf16* shm, acc_t& acc) {
;     ...
;     LDA_(At, 0, 1); WAIT_V(4); BAR; WAIT_L(0); MMA(1, 0, At, B0); MMA(1, 1, At, B1); BAR; }
;   { LDB_(B0, 1, 0); LDA_(At, 1, 0); WAIT_V(2); BAR; WAIT_L(0); MMA(0, 0, At, B0); BAR;
;     LDB_(B1, 1, 1); WAIT_V(0); BAR; WAIT_L(0); MMA(0, 1, At, B1); BAR;
	ds_read_b128 v[174:177], v135 offset:16384
	ds_read_b128 v[178:181], v135 offset:17408
	ds_read_b128 v[182:185], v134 offset:16384
	ds_read_b128 v[186:189], v134 offset:17408
	ds_read_b128 v[190:193], v133 offset:16384
	ds_read_b128 v[194:197], v133 offset:17408
	ds_read_b128 v[198:201], v132 offset:16384
	ds_read_b128 v[202:205], v132 offset:17408
	s_waitcnt vmcnt(4)
	s_barrier
	s_waitcnt lgkmcnt(0)
	s_setprio 1
	s_waitcnt lgkmcnt(7)
	v_mfma_f32_16x16x32_bf16 v[58:61], v[174:177], v[166:169], v[58:61]
	s_waitcnt lgkmcnt(5)
	v_mfma_f32_16x16x32_bf16 v[54:57], v[182:185], v[146:149], v[54:57]
	v_mfma_f32_16x16x32_bf16 v[50:53], v[182:185], v[166:169], v[50:53]
	s_waitcnt lgkmcnt(3)
	v_mfma_f32_16x16x32_bf16 v[46:49], v[190:193], v[146:149], v[46:49]
	v_mfma_f32_16x16x32_bf16 v[42:45], v[190:193], v[166:169], v[42:45]
	s_waitcnt lgkmcnt(1)
	v_mfma_f32_16x16x32_bf16 v[38:41], v[198:201], v[146:149], v[38:41]
	v_mfma_f32_16x16x32_bf16 v[34:37], v[198:201], v[166:169], v[34:37]
	v_mfma_f32_16x16x32_bf16 v[62:65], v[174:177], v[146:149], v[62:65]
	v_mfma_f32_16x16x32_bf16 v[58:61], v[178:181], v[170:173], v[58:61]
	v_mfma_f32_16x16x32_bf16 v[54:57], v[186:189], v[150:153], v[54:57]
	v_mfma_f32_16x16x32_bf16 v[50:53], v[186:189], v[170:173], v[50:53]
	v_mfma_f32_16x16x32_bf16 v[46:49], v[194:197], v[150:153], v[46:49]
	v_mfma_f32_16x16x32_bf16 v[42:45], v[194:197], v[170:173], v[42:45]
	s_waitcnt lgkmcnt(0)
	v_mfma_f32_16x16x32_bf16 v[38:41], v[202:205], v[150:153], v[38:41]
	v_mfma_f32_16x16x32_bf16 v[34:37], v[202:205], v[170:173], v[34:37]
	v_mfma_f32_16x16x32_bf16 v[214:217], v[178:181], v[150:153], v[62:65]
	s_setprio 0
	s_setprio 1
	v_mfma_f32_16x16x32_bf16 v[30:33], v[174:177], v[158:161], v[30:33]
	v_mfma_f32_16x16x32_bf16 v[26:29], v[174:177], v[210:213], v[26:29]
	v_mfma_f32_16x16x32_bf16 v[22:25], v[182:185], v[158:161], v[22:25]
	v_mfma_f32_16x16x32_bf16 v[18:21], v[182:185], v[210:213], v[18:21]
	v_mfma_f32_16x16x32_bf16 v[14:17], v[190:193], v[158:161], v[14:17]
	v_mfma_f32_16x16x32_bf16 v[10:13], v[190:193], v[210:213], v[10:13]
	v_mfma_f32_16x16x32_bf16 v[6:9], v[198:201], v[158:161], v[6:9]
	v_mfma_f32_16x16x32_bf16 v[2:5], v[198:201], v[210:213], v[2:5]
	v_mfma_f32_16x16x32_bf16 v[30:33], v[178:181], v[206:209], v[30:33]
	v_mfma_f32_16x16x32_bf16 v[26:29], v[178:181], v[154:157], v[26:29]
	v_mfma_f32_16x16x32_bf16 v[22:25], v[186:189], v[206:209], v[22:25]
	v_mfma_f32_16x16x32_bf16 v[18:21], v[186:189], v[154:157], v[18:21]
	v_mfma_f32_16x16x32_bf16 v[14:17], v[194:197], v[206:209], v[14:17]
	v_mfma_f32_16x16x32_bf16 v[10:13], v[194:197], v[154:157], v[10:13]
	v_mfma_f32_16x16x32_bf16 v[6:9], v[202:205], v[206:209], v[6:9]
	v_mfma_f32_16x16x32_bf16 v[2:5], v[202:205], v[154:157], v[2:5]
	s_setprio 0
	s_barrier
	ds_read_b128 v[146:149], v144
	ds_read_b128 v[150:153], v144 offset:1024
	ds_read_b128 v[154:157], v144 offset:2048
	ds_read_b128 v[158:161], v144 offset:3072
	ds_read_b128 v[62:65], v135 offset:32768
	ds_read_b128 v[164:167], v135 offset:33792
	ds_read_b128 v[168:171], v134 offset:32768
	ds_read_b128 v[172:175], v134 offset:33792
	ds_read_b128 v[176:179], v133 offset:32768
	ds_read_b128 v[180:183], v133 offset:33792
	ds_read_b128 v[184:187], v132 offset:32768
	ds_read_b128 v[188:191], v132 offset:33792
	s_waitcnt vmcnt(2)
	s_barrier
	s_waitcnt lgkmcnt(0)
	s_setprio 1
	s_waitcnt lgkmcnt(7)
	v_mfma_f32_16x16x32_bf16 v[126:129], v[62:65], v[146:149], v[126:129]
	v_mfma_f32_16x16x32_bf16 v[122:125], v[62:65], v[154:157], v[122:125]
	s_waitcnt lgkmcnt(5)
	v_mfma_f32_16x16x32_bf16 v[118:121], v[168:171], v[146:149], v[118:121]
	v_mfma_f32_16x16x32_bf16 v[114:117], v[168:171], v[154:157], v[114:117]
	s_waitcnt lgkmcnt(3)
	v_mfma_f32_16x16x32_bf16 v[110:113], v[176:179], v[146:149], v[110:113]
	v_mfma_f32_16x16x32_bf16 v[106:109], v[176:179], v[154:157], v[106:109]
	s_waitcnt lgkmcnt(1)
	v_mfma_f32_16x16x32_bf16 v[102:105], v[184:187], v[146:149], v[102:105]
	v_mfma_f32_16x16x32_bf16 v[98:101], v[184:187], v[154:157], v[98:101]
	v_mfma_f32_16x16x32_bf16 v[126:129], v[164:167], v[150:153], v[126:129]
	v_mfma_f32_16x16x32_bf16 v[122:125], v[164:167], v[158:161], v[122:125]
	v_mfma_f32_16x16x32_bf16 v[118:121], v[172:175], v[150:153], v[118:121]
	v_mfma_f32_16x16x32_bf16 v[114:117], v[172:175], v[158:161], v[114:117]
	v_mfma_f32_16x16x32_bf16 v[110:113], v[180:183], v[150:153], v[110:113]
	v_mfma_f32_16x16x32_bf16 v[106:109], v[180:183], v[158:161], v[106:109]
	s_waitcnt lgkmcnt(0)
	v_mfma_f32_16x16x32_bf16 v[102:105], v[188:191], v[150:153], v[102:105]
	v_mfma_f32_16x16x32_bf16 v[98:101], v[188:191], v[158:161], v[98:101]
	s_setprio 0
	s_barrier
; #define LDA_(dst, b, h) _Pragma("unroll") for (int m = 0; m < 4; ++m) _Pragma("unroll") for (int k = 0; k < 2; ++k) \
;     dst[m][k] = *reinterpret_cast<const bf16x8*>((char*)SA(b, h) + lds_byte(wr * 64 + m * 16 + fr, k * 32 + fq * 8))
; #define LDB_(dst, b, h) _Pragma("unroll") for (int n = 0; n < 2; ++n) _Pragma("unroll") for (int k = 0; k < 2; ++k) \
;     dst[n][k] = *reinterpret_cast<const bf16x8*>((char*)SB(b, h) + lds_byte(wc * 32 + n * 16 + fr, k * 32 + fq * 8))
; #define MMA(ai, bj, At, Bx) do { __builtin_amdgcn_s_setprio(1); \
;     _Pragma("unroll") for (int m = 0; m < 4; ++m) _Pragma("unroll") for (int n = 0; n < 2; ++n) _Pragma("unroll") for (int k = 0; k < 2; ++k) \
;       acc[ai][bj][m][n] = __builtin_amdgcn_mfma_f32_16x16x32_bf16(At[m][k], Bx[n][k], acc[ai][bj][m][n], 0, 0, 0); \
;     __builtin_amdgcn_s_setprio(0); } while (0)
; #define WAIT_V(n) asm volatile("s_waitcnt vmcnt(" #n ")" ::: "memory")
; #define WAIT_L(n) asm volatile("s_waitcnt lgkmcnt(" #n ")" ::: "memory")
; #define BAR __builtin_amdgcn_s_barrier()
; template <int K, int LDA, int LDB>
; DEVI void gemm_tile(const bf16* __restrict__ A, const bf16* __restrict__ Bt, bf16* shm, acc_t& acc) {
;     ...
;   { LDB_(B0, 1, 0); LDA_(At, 1, 0); WAIT_V(2); BAR; WAIT_L(0); MMA(0, 0, At, B0); BAR;
;     LDB_(B1, 1, 1); WAIT_V(0); BAR; WAIT_L(0); MMA(0, 1, At, B1); BAR;
;     LDA_(At, 1, 1); BAR; WAIT_L(0); MMA(1, 0, At, B0); MMA(1, 1, At, B1); BAR; }
;   if (wr == 0) BAR;
	ds_read_b128 v[192:195], v142
	ds_read_b128 v[196:199], v142 offset:1024
	ds_read_b128 v[200:203], v142 offset:2048
	ds_read_b128 v[142:145], v142 offset:3072
	s_waitcnt vmcnt(0)
	s_barrier
	s_waitcnt lgkmcnt(0)
	s_setprio 1
	s_waitcnt lgkmcnt(3)
	v_mfma_f32_16x16x32_bf16 v[94:97], v[62:65], v[192:195], v[94:97]
	s_waitcnt lgkmcnt(1)
	v_mfma_f32_16x16x32_bf16 v[62:65], v[62:65], v[200:203], v[90:93]
	s_waitcnt lgkmcnt(0)
	v_mfma_f32_16x16x32_bf16 v[90:93], v[164:167], v[142:145], v[62:65]
	v_mfma_f32_16x16x32_bf16 v[62:65], v[168:171], v[192:195], v[86:89]
	v_mfma_f32_16x16x32_bf16 v[86:89], v[172:175], v[196:199], v[62:65]
	v_mfma_f32_16x16x32_bf16 v[62:65], v[168:171], v[200:203], v[82:85]
	v_mfma_f32_16x16x32_bf16 v[82:85], v[172:175], v[142:145], v[62:65]
	v_mfma_f32_16x16x32_bf16 v[62:65], v[176:179], v[192:195], v[78:81]
	v_mfma_f32_16x16x32_bf16 v[78:81], v[180:183], v[196:199], v[62:65]
	v_mfma_f32_16x16x32_bf16 v[62:65], v[176:179], v[200:203], v[74:77]
	v_mfma_f32_16x16x32_bf16 v[74:77], v[180:183], v[142:145], v[62:65]
	v_mfma_f32_16x16x32_bf16 v[62:65], v[184:187], v[192:195], v[70:73]
	v_mfma_f32_16x16x32_bf16 v[70:73], v[188:191], v[196:199], v[62:65]
	v_mfma_f32_16x16x32_bf16 v[62:65], v[184:187], v[200:203], v[66:69]
	v_mfma_f32_16x16x32_bf16 v[94:97], v[164:167], v[196:199], v[94:97]
	v_mfma_f32_16x16x32_bf16 v[62:65], v[188:191], v[142:145], v[62:65]
	s_setprio 0
	s_barrier
	ds_read_b128 v[164:167], v135 offset:49152
	ds_read_b128 v[168:171], v135 offset:50176
	ds_read_b128 v[172:175], v134 offset:49152
	ds_read_b128 v[176:179], v134 offset:50176
	ds_read_b128 v[180:183], v133 offset:49152
	ds_read_b128 v[184:187], v133 offset:50176
	ds_read_b128 v[188:191], v132 offset:49152
	ds_read_b128 v[132:135], v132 offset:50176
	s_barrier
	s_waitcnt lgkmcnt(0)
	s_setprio 1
	s_waitcnt lgkmcnt(7)
	v_mfma_f32_16x16x32_bf16 v[66:69], v[164:167], v[146:149], v[214:217]
	v_mfma_f32_16x16x32_bf16 v[58:61], v[164:167], v[154:157], v[58:61]
	s_waitcnt lgkmcnt(5)
	v_mfma_f32_16x16x32_bf16 v[54:57], v[172:175], v[146:149], v[54:57]
	v_mfma_f32_16x16x32_bf16 v[50:53], v[172:175], v[154:157], v[50:53]
	s_waitcnt lgkmcnt(3)
	v_mfma_f32_16x16x32_bf16 v[46:49], v[180:183], v[146:149], v[46:49]
	v_mfma_f32_16x16x32_bf16 v[42:45], v[180:183], v[154:157], v[42:45]
	s_waitcnt lgkmcnt(1)
	v_mfma_f32_16x16x32_bf16 v[38:41], v[188:191], v[146:149], v[38:41]
	v_mfma_f32_16x16x32_bf16 v[34:37], v[188:191], v[154:157], v[34:37]
	v_mfma_f32_16x16x32_bf16 v[66:69], v[168:171], v[150:153], v[66:69]
	v_mfma_f32_16x16x32_bf16 v[58:61], v[168:171], v[158:161], v[58:61]
	v_mfma_f32_16x16x32_bf16 v[54:57], v[176:179], v[150:153], v[54:57]
	v_mfma_f32_16x16x32_bf16 v[50:53], v[176:179], v[158:161], v[50:53]
	v_mfma_f32_16x16x32_bf16 v[46:49], v[184:187], v[150:153], v[46:49]
	v_mfma_f32_16x16x32_bf16 v[42:45], v[184:187], v[158:161], v[42:45]
	s_waitcnt lgkmcnt(0)
	v_mfma_f32_16x16x32_bf16 v[38:41], v[132:135], v[150:153], v[38:41]
	v_mfma_f32_16x16x32_bf16 v[34:37], v[132:135], v[158:161], v[34:37]
	s_setprio 0
	s_setprio 1
	v_mfma_f32_16x16x32_bf16 v[30:33], v[164:167], v[192:195], v[30:33]
	v_mfma_f32_16x16x32_bf16 v[26:29], v[164:167], v[200:203], v[26:29]
	v_mfma_f32_16x16x32_bf16 v[22:25], v[172:175], v[192:195], v[22:25]
	v_mfma_f32_16x16x32_bf16 v[18:21], v[172:175], v[200:203], v[18:21]
	v_mfma_f32_16x16x32_bf16 v[14:17], v[180:183], v[192:195], v[14:17]
	v_mfma_f32_16x16x32_bf16 v[10:13], v[180:183], v[200:203], v[10:13]
	v_mfma_f32_16x16x32_bf16 v[6:9], v[188:191], v[192:195], v[6:9]
	v_mfma_f32_16x16x32_bf16 v[2:5], v[188:191], v[200:203], v[2:5]
	v_mfma_f32_16x16x32_bf16 v[30:33], v[168:171], v[196:199], v[30:33]
	v_mfma_f32_16x16x32_bf16 v[26:29], v[168:171], v[142:145], v[26:29]
	v_mfma_f32_16x16x32_bf16 v[22:25], v[176:179], v[196:199], v[22:25]
	v_mfma_f32_16x16x32_bf16 v[18:21], v[176:179], v[142:145], v[18:21]
	v_mfma_f32_16x16x32_bf16 v[14:17], v[184:187], v[196:199], v[14:17]
	v_mfma_f32_16x16x32_bf16 v[10:13], v[184:187], v[142:145], v[10:13]
	v_mfma_f32_16x16x32_bf16 v[6:9], v[132:135], v[196:199], v[6:9]
	v_mfma_f32_16x16x32_bf16 v[2:5], v[132:135], v[142:145], v[2:5]
	s_setprio 0
	v_cmp_gt_u32_e32 vcc, s18, v130
	s_barrier
	s_and_saveexec_b64 s[4:5], vcc
	s_cbranch_execz .LBB0_171
	s_barrier

; #define STAGE(P, BASE, LD, br, kt) do { const int _so = (int)(((br) * (LD) + (kt) * BK) * 2); \
;     _Pragma("unroll") for (int _i = 0; _i < 2; ++_i) { \
;       __builtin_amdgcn_raw_ptr_buffer_load_lds(rs##BASE, (__attribute__((address_space(3))) unsigned*)((char*)(P) + tid_ * 16 + _i * 8192), 16, (int)off##LD[_i], _so, 0, 0); } } while (0)
; #define LDA_(dst, b, h) _Pragma("unroll") for (int m = 0; m < 4; ++m) _Pragma("unroll") for (int k = 0; k < 2; ++k) \
;     dst[m][k] = *reinterpret_cast<const bf16x8*>((char*)SA(b, h) + lds_byte(wr * 64 + m * 16 + fr, k * 32 + fq * 8))
; #define LDB_(dst, b, h) _Pragma("unroll") for (int n = 0; n < 2; ++n) _Pragma("unroll") for (int k = 0; k < 2; ++k) \
;     dst[n][k] = *reinterpret_cast<const bf16x8*>((char*)SB(b, h) + lds_byte(wc * 32 + n * 16 + fr, k * 32 + fq * 8))
; #define MMA(ai, bj, At, Bx) do { __builtin_amdgcn_s_setprio(1); \
;     _Pragma("unroll") for (int m = 0; m < 4; ++m) _Pragma("unroll") for (int n = 0; n < 2; ++n) _Pragma("unroll") for (int k = 0; k < 2; ++k) \
;       acc[ai][bj][m][n] = __builtin_amdgcn_mfma_f32_16x16x32_bf16(At[m][k], Bx[n][k], acc[ai][bj][m][n], 0, 0, 0); \
;     __builtin_amdgcn_s_setprio(0); } while (0)
; #define WAIT_V(n) asm volatile("s_waitcnt vmcnt(" #n ")" ::: "memory")
; #define WAIT_L(n) asm volatile("s_waitcnt lgkmcnt(" #n ")" ::: "memory")
; #define BAR __builtin_amdgcn_s_barrier()
; #define SCHED __builtin_amdgcn_sched_barrier(0)
; template <int K, int LDA, int LDB>
; DEVI void gemm_tile(const bf16* __restrict__ A, const bf16* __restrict__ Bt, bf16* shm, acc_t& acc) {
;     ...
;   for (int t = 0; t < nt - 2; t += 2) {
;     LDB_(B0, 0, 0); SCHED; LDA_(At, 0, 0); STAGE(SA(1, 1), A, LDA, HALF, t + 1);
;     WAIT_L(8); BAR; WAIT_L(0); MMA(0, 0, At, B0); BAR; SCHED;
;     LDB_(B1, 0, 1); STAGE(SB(0, 0), Bt, LDB, 0, t + 2);
;     BAR; WAIT_L(0); MMA(0, 1, At, B1); BAR;
;     LDA_(At, 0, 1); STAGE(SA(0, 0), A, LDA, 0, t + 2);
;     BAR; WAIT_L(0); MMA(1, 0, At, B0); BAR; SCHED;
;     STAGE(SB(0, 1), Bt, LDB, HALF, t + 2);
;     WAIT_V(6); BAR; MMA(1, 1, At, B1); BAR;
;     LDB_(B0, 1, 0); SCHED; LDA_(At, 1, 0); STAGE(SA(0, 1), A, LDA, HALF, t + 2);
;     WAIT_L(8); BAR; WAIT_L(0); MMA(0, 0, At, B0); BAR; SCHED;
.LBB0_216:
	ds_read_b128 v[164:167], v161
	ds_read_b128 v[168:171], v161 offset:1024
	ds_read_b128 v[172:175], v161 offset:2048
	ds_read_b128 v[176:179], v161 offset:3072
	v_readfirstlane_b32 s42, v157
	s_add_i32 s41, s40, 0xfff9ff00
	s_mov_b32 m0, s42
	v_readfirstlane_b32 s42, v160
	ds_read_b128 v[180:183], v141
	ds_read_b128 v[184:187], v141 offset:1024
	ds_read_b128 v[188:191], v140
	ds_read_b128 v[192:195], v140 offset:1024
	ds_read_b128 v[196:199], v137
	ds_read_b128 v[200:203], v137 offset:1024
	ds_read_b128 v[204:207], v133
	ds_read_b128 v[208:211], v133 offset:1024
	buffer_load_dwordx4 v130, s[4:7], s41 offen lds
	s_mov_b32 m0, s42
	s_nop 0
	buffer_load_dwordx4 v134, s[4:7], s41 offen lds
	s_waitcnt lgkmcnt(8)
	s_barrier
	s_waitcnt lgkmcnt(0)
	s_setprio 1
	s_waitcnt lgkmcnt(7)
	v_mfma_f32_16x16x32_bf16 v[126:129], v[180:183], v[164:167], v[126:129]
	v_mfma_f32_16x16x32_bf16 v[122:125], v[180:183], v[172:175], v[122:125]
	s_waitcnt lgkmcnt(5)
	v_mfma_f32_16x16x32_bf16 v[118:121], v[188:191], v[164:167], v[118:121]
	v_mfma_f32_16x16x32_bf16 v[114:117], v[188:191], v[172:175], v[114:117]
	s_waitcnt lgkmcnt(3)
	v_mfma_f32_16x16x32_bf16 v[110:113], v[196:199], v[164:167], v[110:113]
	v_mfma_f32_16x16x32_bf16 v[106:109], v[196:199], v[172:175], v[106:109]
	s_waitcnt lgkmcnt(1)
	v_mfma_f32_16x16x32_bf16 v[102:105], v[204:207], v[164:167], v[102:105]
	v_mfma_f32_16x16x32_bf16 v[98:101], v[204:207], v[172:175], v[98:101]
	v_mfma_f32_16x16x32_bf16 v[126:129], v[184:187], v[168:171], v[126:129]
	v_mfma_f32_16x16x32_bf16 v[122:125], v[184:187], v[176:179], v[122:125]
	v_mfma_f32_16x16x32_bf16 v[118:121], v[192:195], v[168:171], v[118:121]
	v_mfma_f32_16x16x32_bf16 v[114:117], v[192:195], v[176:179], v[114:117]
	v_mfma_f32_16x16x32_bf16 v[110:113], v[200:203], v[168:171], v[110:113]
	v_mfma_f32_16x16x32_bf16 v[106:109], v[200:203], v[176:179], v[106:109]
	s_waitcnt lgkmcnt(0)
	v_mfma_f32_16x16x32_bf16 v[102:105], v[208:211], v[168:171], v[102:105]
	v_mfma_f32_16x16x32_bf16 v[98:101], v[208:211], v[176:179], v[98:101]
	s_setprio 0
	s_barrier
	v_readfirstlane_b32 s42, v144
	s_add_i32 s41, s40, 0xfff7ff80
	s_mov_b32 m0, s42
	v_readfirstlane_b32 s42, v145
	ds_read_b128 v[212:215], v155
	ds_read_b128 v[216:219], v155 offset:1024
	ds_read_b128 v[220:223], v155 offset:2048
	ds_read_b128 v[224:227], v155 offset:3072
	buffer_load_dwordx4 v132, s[0:3], s41 offen lds
	s_mov_b32 m0, s42
	s_nop 0
	buffer_load_dwordx4 v136, s[0:3], s41 offen lds
	s_barrier
	s_waitcnt lgkmcnt(0)
	s_setprio 1
	s_waitcnt lgkmcnt(3)
	v_mfma_f32_16x16x32_bf16 v[94:97], v[180:183], v[212:215], v[94:97]
	s_waitcnt lgkmcnt(1)
	v_mfma_f32_16x16x32_bf16 v[90:93], v[180:183], v[220:223], v[90:93]
	v_mfma_f32_16x16x32_bf16 v[86:89], v[188:191], v[212:215], v[86:89]
	v_mfma_f32_16x16x32_bf16 v[82:85], v[188:191], v[220:223], v[82:85]
	v_mfma_f32_16x16x32_bf16 v[78:81], v[196:199], v[212:215], v[78:81]
	v_mfma_f32_16x16x32_bf16 v[74:77], v[196:199], v[220:223], v[74:77]
	v_mfma_f32_16x16x32_bf16 v[70:73], v[204:207], v[212:215], v[70:73]
	v_mfma_f32_16x16x32_bf16 v[66:69], v[204:207], v[220:223], v[66:69]
	v_mfma_f32_16x16x32_bf16 v[94:97], v[184:187], v[216:219], v[94:97]
	s_waitcnt lgkmcnt(0)
	v_mfma_f32_16x16x32_bf16 v[90:93], v[184:187], v[224:227], v[90:93]
	v_mfma_f32_16x16x32_bf16 v[86:89], v[192:195], v[216:219], v[86:89]
	v_mfma_f32_16x16x32_bf16 v[82:85], v[192:195], v[224:227], v[82:85]
	v_mfma_f32_16x16x32_bf16 v[78:81], v[200:203], v[216:219], v[78:81]
	v_mfma_f32_16x16x32_bf16 v[74:77], v[200:203], v[224:227], v[74:77]
	v_mfma_f32_16x16x32_bf16 v[70:73], v[208:211], v[216:219], v[70:73]
	v_mfma_f32_16x16x32_bf16 v[66:69], v[208:211], v[224:227], v[66:69]
	s_setprio 0
	v_readfirstlane_b32 s42, v146
	s_mov_b32 m0, s42
	v_readfirstlane_b32 s42, v147
	s_barrier
	ds_read_b128 v[180:183], v141 offset:16384
	ds_read_b128 v[184:187], v141 offset:17408
	ds_read_b128 v[188:191], v140 offset:16384
	ds_read_b128 v[192:195], v140 offset:17408
	ds_read_b128 v[196:199], v137 offset:16384
	ds_read_b128 v[200:203], v137 offset:17408
	ds_read_b128 v[204:207], v133 offset:16384
	ds_read_b128 v[208:211], v133 offset:17408
	buffer_load_dwordx4 v130, s[4:7], s41 offen lds
	s_mov_b32 m0, s42
	s_nop 0
	buffer_load_dwordx4 v134, s[4:7], s41 offen lds
	s_barrier
	s_waitcnt lgkmcnt(0)
	s_setprio 1
	s_waitcnt lgkmcnt(7)
	v_mfma_f32_16x16x32_bf16 v[62:65], v[180:183], v[164:167], v[62:65]
	v_mfma_f32_16x16x32_bf16 v[58:61], v[180:183], v[172:175], v[58:61]
	s_waitcnt lgkmcnt(5)
	v_mfma_f32_16x16x32_bf16 v[54:57], v[188:191], v[164:167], v[54:57]
	v_mfma_f32_16x16x32_bf16 v[50:53], v[188:191], v[172:175], v[50:53]
	s_waitcnt lgkmcnt(3)
	v_mfma_f32_16x16x32_bf16 v[46:49], v[196:199], v[164:167], v[46:49]
	v_mfma_f32_16x16x32_bf16 v[42:45], v[196:199], v[172:175], v[42:45]
	s_waitcnt lgkmcnt(1)
	v_mfma_f32_16x16x32_bf16 v[38:41], v[204:207], v[164:167], v[38:41]
	v_mfma_f32_16x16x32_bf16 v[34:37], v[204:207], v[172:175], v[34:37]
	v_mfma_f32_16x16x32_bf16 v[62:65], v[184:187], v[168:171], v[62:65]
	v_mfma_f32_16x16x32_bf16 v[58:61], v[184:187], v[176:179], v[58:61]
	v_mfma_f32_16x16x32_bf16 v[54:57], v[192:195], v[168:171], v[54:57]
	v_mfma_f32_16x16x32_bf16 v[50:53], v[192:195], v[176:179], v[50:53]
	v_mfma_f32_16x16x32_bf16 v[46:49], v[200:203], v[168:171], v[46:49]
	v_mfma_f32_16x16x32_bf16 v[42:45], v[200:203], v[176:179], v[42:45]
	s_waitcnt lgkmcnt(0)
	v_mfma_f32_16x16x32_bf16 v[38:41], v[208:211], v[168:171], v[38:41]
	v_mfma_f32_16x16x32_bf16 v[34:37], v[208:211], v[176:179], v[34:37]
	s_setprio 0
	s_barrier
; #define STAGE(P, BASE, LD, br, kt) do { const int _so = (int)(((br) * (LD) + (kt) * BK) * 2); \
;     _Pragma("unroll") for (int _i = 0; _i < 2; ++_i) { \
;       __builtin_amdgcn_raw_ptr_buffer_load_lds(rs##BASE, (__attribute__((address_space(3))) unsigned*)((char*)(P) + tid_ * 16 + _i * 8192), 16, (int)off##LD[_i], _so, 0, 0); } } while (0)
; #define LDA_(dst, b, h) _Pragma("unroll") for (int m = 0; m < 4; ++m) _Pragma("unroll") for (int k = 0; k < 2; ++k) \
;     dst[m][k] = *reinterpret_cast<const bf16x8*>((char*)SA(b, h) + lds_byte(wr * 64 + m * 16 + fr, k * 32 + fq * 8))
; #define LDB_(dst, b, h) _Pragma("unroll") for (int n = 0; n < 2; ++n) _Pragma("unroll") for (int k = 0; k < 2; ++k) \
;     dst[n][k] = *reinterpret_cast<const bf16x8*>((char*)SB(b, h) + lds_byte(wc * 32 + n * 16 + fr, k * 32 + fq * 8))
; #define MMA(ai, bj, At, Bx) do { __builtin_amdgcn_s_setprio(1); \
;     _Pragma("unroll") for (int m = 0; m < 4; ++m) _Pragma("unroll") for (int n = 0; n < 2; ++n) _Pragma("unroll") for (int k = 0; k < 2; ++k) \
;       acc[ai][bj][m][n] = __builtin_amdgcn_mfma_f32_16x16x32_bf16(At[m][k], Bx[n][k], acc[ai][bj][m][n], 0, 0, 0); \
;     __builtin_amdgcn_s_setprio(0); } while (0)
; #define WAIT_V(n) asm volatile("s_waitcnt vmcnt(" #n ")" ::: "memory")
; #define WAIT_L(n) asm volatile("s_waitcnt lgkmcnt(" #n ")" ::: "memory")
; #define BAR __builtin_amdgcn_s_barrier()
; #define SCHED __builtin_amdgcn_sched_barrier(0)
; template <int K, int LDA, int LDB>
; DEVI void gemm_tile(const bf16* __restrict__ A, const bf16* __restrict__ Bt, bf16* shm, acc_t& acc) {
;     ...
;     STAGE(SB(0, 1), Bt, LDB, HALF, t + 2);
;     WAIT_V(6); BAR; MMA(1, 1, At, B1); BAR;
;     LDB_(B0, 1, 0); SCHED; LDA_(At, 1, 0); STAGE(SA(0, 1), A, LDA, HALF, t + 2);
;     WAIT_L(8); BAR; WAIT_L(0); MMA(0, 0, At, B0); BAR; SCHED;
;     LDB_(B1, 1, 1); STAGE(SB(1, 0), Bt, LDB, 0, t + 3);
;     BAR; WAIT_L(0); MMA(0, 1, At, B1); BAR;
;     LDA_(At, 1, 1); STAGE(SA(1, 0), A, LDA, 0, t + 3);
;     BAR; WAIT_L(0); MMA(1, 0, At, B0); BAR; SCHED;
	v_readfirstlane_b32 s42, v148
	s_add_i32 s41, s40, 0xffffff80
	s_mov_b32 m0, s42
	v_readfirstlane_b32 s42, v149
	buffer_load_dwordx4 v132, s[0:3], s41 offen lds
	s_mov_b32 m0, s42
	s_nop 0
	buffer_load_dwordx4 v136, s[0:3], s41 offen lds
	s_waitcnt vmcnt(6)
	s_barrier
	s_setprio 1
	v_mfma_f32_16x16x32_bf16 v[30:33], v[180:183], v[212:215], v[30:33]
	v_mfma_f32_16x16x32_bf16 v[26:29], v[180:183], v[220:223], v[26:29]
	v_mfma_f32_16x16x32_bf16 v[22:25], v[188:191], v[212:215], v[22:25]
	v_mfma_f32_16x16x32_bf16 v[18:21], v[188:191], v[220:223], v[18:21]
	v_mfma_f32_16x16x32_bf16 v[14:17], v[196:199], v[212:215], v[14:17]
	v_mfma_f32_16x16x32_bf16 v[10:13], v[196:199], v[220:223], v[10:13]
	v_mfma_f32_16x16x32_bf16 v[6:9], v[204:207], v[212:215], v[6:9]
	v_mfma_f32_16x16x32_bf16 v[2:5], v[204:207], v[220:223], v[2:5]
	v_mfma_f32_16x16x32_bf16 v[30:33], v[184:187], v[216:219], v[30:33]
	v_mfma_f32_16x16x32_bf16 v[26:29], v[184:187], v[224:227], v[26:29]
	v_mfma_f32_16x16x32_bf16 v[22:25], v[192:195], v[216:219], v[22:25]
	v_mfma_f32_16x16x32_bf16 v[18:21], v[192:195], v[224:227], v[18:21]
	v_mfma_f32_16x16x32_bf16 v[14:17], v[200:203], v[216:219], v[14:17]
	v_mfma_f32_16x16x32_bf16 v[10:13], v[200:203], v[224:227], v[10:13]
	v_mfma_f32_16x16x32_bf16 v[6:9], v[208:211], v[216:219], v[6:9]
	v_mfma_f32_16x16x32_bf16 v[2:5], v[208:211], v[224:227], v[2:5]
	s_setprio 0
	s_barrier
	ds_read_b128 v[164:167], v143
	ds_read_b128 v[168:171], v143 offset:1024
	ds_read_b128 v[172:175], v143 offset:2048
	ds_read_b128 v[176:179], v143 offset:3072
	v_readfirstlane_b32 s42, v150
	s_add_i32 s41, s40, 0xfff9ff80
	s_mov_b32 m0, s42
	v_readfirstlane_b32 s42, v151
	ds_read_b128 v[180:183], v141 offset:32768
	ds_read_b128 v[184:187], v141 offset:33792
	ds_read_b128 v[188:191], v140 offset:32768
	ds_read_b128 v[192:195], v140 offset:33792
	ds_read_b128 v[196:199], v137 offset:32768
	ds_read_b128 v[200:203], v137 offset:33792
	ds_read_b128 v[204:207], v133 offset:32768
	ds_read_b128 v[208:211], v133 offset:33792
	buffer_load_dwordx4 v130, s[4:7], s41 offen lds
	s_mov_b32 m0, s42
	s_nop 0
	buffer_load_dwordx4 v134, s[4:7], s41 offen lds
	s_waitcnt lgkmcnt(8)
	s_barrier
	s_waitcnt lgkmcnt(0)
	s_setprio 1
	s_waitcnt lgkmcnt(7)
	v_mfma_f32_16x16x32_bf16 v[126:129], v[180:183], v[164:167], v[126:129]
	v_mfma_f32_16x16x32_bf16 v[122:125], v[180:183], v[172:175], v[122:125]
	s_waitcnt lgkmcnt(5)
	v_mfma_f32_16x16x32_bf16 v[118:121], v[188:191], v[164:167], v[118:121]
	v_mfma_f32_16x16x32_bf16 v[114:117], v[188:191], v[172:175], v[114:117]
	s_waitcnt lgkmcnt(3)
	v_mfma_f32_16x16x32_bf16 v[110:113], v[196:199], v[164:167], v[110:113]
	v_mfma_f32_16x16x32_bf16 v[106:109], v[196:199], v[172:175], v[106:109]
	s_waitcnt lgkmcnt(1)
	v_mfma_f32_16x16x32_bf16 v[102:105], v[204:207], v[164:167], v[102:105]
	v_mfma_f32_16x16x32_bf16 v[98:101], v[204:207], v[172:175], v[98:101]
	v_mfma_f32_16x16x32_bf16 v[126:129], v[184:187], v[168:171], v[126:129]
	v_mfma_f32_16x16x32_bf16 v[122:125], v[184:187], v[176:179], v[122:125]
	v_mfma_f32_16x16x32_bf16 v[118:121], v[192:195], v[168:171], v[118:121]
	v_mfma_f32_16x16x32_bf16 v[114:117], v[192:195], v[176:179], v[114:117]
	v_mfma_f32_16x16x32_bf16 v[110:113], v[200:203], v[168:171], v[110:113]
	v_mfma_f32_16x16x32_bf16 v[106:109], v[200:203], v[176:179], v[106:109]
	s_waitcnt lgkmcnt(0)
	v_mfma_f32_16x16x32_bf16 v[102:105], v[208:211], v[168:171], v[102:105]
	v_mfma_f32_16x16x32_bf16 v[98:101], v[208:211], v[176:179], v[98:101]
	s_setprio 0
	s_barrier
	v_readfirstlane_b32 s42, v152
	s_add_i32 s41, s40, 0xfff80000
	s_mov_b32 m0, s42
	v_readfirstlane_b32 s42, v153
	ds_read_b128 v[212:215], v142
	ds_read_b128 v[216:219], v142 offset:1024
	ds_read_b128 v[220:223], v142 offset:2048
	ds_read_b128 v[224:227], v142 offset:3072
	buffer_load_dwordx4 v132, s[0:3], s41 offen lds
	s_mov_b32 m0, s42
	s_nop 0
	buffer_load_dwordx4 v136, s[0:3], s41 offen lds
	s_barrier
	s_waitcnt lgkmcnt(0)
	s_setprio 1
	s_waitcnt lgkmcnt(3)
	v_mfma_f32_16x16x32_bf16 v[94:97], v[180:183], v[212:215], v[94:97]
	s_waitcnt lgkmcnt(1)
	v_mfma_f32_16x16x32_bf16 v[90:93], v[180:183], v[220:223], v[90:93]
	v_mfma_f32_16x16x32_bf16 v[86:89], v[188:191], v[212:215], v[86:89]
	v_mfma_f32_16x16x32_bf16 v[82:85], v[188:191], v[220:223], v[82:85]
	v_mfma_f32_16x16x32_bf16 v[78:81], v[196:199], v[212:215], v[78:81]
	v_mfma_f32_16x16x32_bf16 v[74:77], v[196:199], v[220:223], v[74:77]
	v_mfma_f32_16x16x32_bf16 v[70:73], v[204:207], v[212:215], v[70:73]
	v_mfma_f32_16x16x32_bf16 v[66:69], v[204:207], v[220:223], v[66:69]
	v_mfma_f32_16x16x32_bf16 v[94:97], v[184:187], v[216:219], v[94:97]
	s_waitcnt lgkmcnt(0)
	v_mfma_f32_16x16x32_bf16 v[90:93], v[184:187], v[224:227], v[90:93]
	v_mfma_f32_16x16x32_bf16 v[86:89], v[192:195], v[216:219], v[86:89]
	v_mfma_f32_16x16x32_bf16 v[82:85], v[192:195], v[224:227], v[82:85]
	v_mfma_f32_16x16x32_bf16 v[78:81], v[200:203], v[216:219], v[78:81]
	v_mfma_f32_16x16x32_bf16 v[74:77], v[200:203], v[224:227], v[74:77]
	v_mfma_f32_16x16x32_bf16 v[70:73], v[208:211], v[216:219], v[70:73]
	v_mfma_f32_16x16x32_bf16 v[66:69], v[208:211], v[224:227], v[66:69]
	s_setprio 0
	v_readfirstlane_b32 s42, v154
	s_mov_b32 m0, s42
	v_readfirstlane_b32 s42, v156
	s_barrier
	ds_read_b128 v[180:183], v141 offset:49152
	ds_read_b128 v[184:187], v141 offset:50176
	ds_read_b128 v[188:191], v140 offset:49152
	ds_read_b128 v[192:195], v140 offset:50176
	ds_read_b128 v[196:199], v137 offset:49152
	ds_read_b128 v[200:203], v137 offset:50176
	ds_read_b128 v[204:207], v133 offset:49152
	ds_read_b128 v[208:211], v133 offset:50176
	buffer_load_dwordx4 v130, s[4:7], s41 offen lds
	s_mov_b32 m0, s42
	s_nop 0
	buffer_load_dwordx4 v134, s[4:7], s41 offen lds
	s_barrier
; #define STAGE(P, BASE, LD, br, kt) do { const int _so = (int)(((br) * (LD) + (kt) * BK) * 2); \
;     _Pragma("unroll") for (int _i = 0; _i < 2; ++_i) { \
;       __builtin_amdgcn_raw_ptr_buffer_load_lds(rs##BASE, (__attribute__((address_space(3))) unsigned*)((char*)(P) + tid_ * 16 + _i * 8192), 16, (int)off##LD[_i], _so, 0, 0); } } while (0)
; #define LDA_(dst, b, h) _Pragma("unroll") for (int m = 0; m < 4; ++m) _Pragma("unroll") for (int k = 0; k < 2; ++k) \
;     dst[m][k] = *reinterpret_cast<const bf16x8*>((char*)SA(b, h) + lds_byte(wr * 64 + m * 16 + fr, k * 32 + fq * 8))
; #define LDB_(dst, b, h) _Pragma("unroll") for (int n = 0; n < 2; ++n) _Pragma("unroll") for (int k = 0; k < 2; ++k) \
;     dst[n][k] = *reinterpret_cast<const bf16x8*>((char*)SB(b, h) + lds_byte(wc * 32 + n * 16 + fr, k * 32 + fq * 8))
; #define MMA(ai, bj, At, Bx) do { __builtin_amdgcn_s_setprio(1); \
;     _Pragma("unroll") for (int m = 0; m < 4; ++m) _Pragma("unroll") for (int n = 0; n < 2; ++n) _Pragma("unroll") for (int k = 0; k < 2; ++k) \
;       acc[ai][bj][m][n] = __builtin_amdgcn_mfma_f32_16x16x32_bf16(At[m][k], Bx[n][k], acc[ai][bj][m][n], 0, 0, 0); \
;     __builtin_amdgcn_s_setprio(0); } while (0)
; #define WAIT_V(n) asm volatile("s_waitcnt vmcnt(" #n ")" ::: "memory")
; #define WAIT_L(n) asm volatile("s_waitcnt lgkmcnt(" #n ")" ::: "memory")
; #define BAR __builtin_amdgcn_s_barrier()
; #define SCHED __builtin_amdgcn_sched_barrier(0)
; template <int K, int LDA, int LDB>
; DEVI void gemm_tile(const bf16* __restrict__ A, const bf16* __restrict__ Bt, bf16* shm, acc_t& acc) {
;     ...
;     BAR; WAIT_L(0); MMA(1, 0, At, B0); BAR; SCHED;
;     STAGE(SB(1, 1), Bt, LDB, HALF, t + 3);
;     WAIT_V(6); BAR; MMA(1, 1, At, B1); BAR;
;   }
;   { LDB_(B0, 0, 0); LDA_(At, 0, 0); STAGE(SA(1, 1), A, LDA, HALF, nt - 1);
;     BAR; WAIT_L(0); MMA(0, 0, At, B0); BAR;
;     LDB_(B1, 0, 1); BAR; WAIT_L(0); MMA(0, 1, At, B1); BAR;
	s_waitcnt lgkmcnt(0)
	s_setprio 1
	s_waitcnt lgkmcnt(7)
	v_mfma_f32_16x16x32_bf16 v[62:65], v[180:183], v[164:167], v[62:65]
	v_mfma_f32_16x16x32_bf16 v[58:61], v[180:183], v[172:175], v[58:61]
	s_waitcnt lgkmcnt(5)
	v_mfma_f32_16x16x32_bf16 v[54:57], v[188:191], v[164:167], v[54:57]
	v_mfma_f32_16x16x32_bf16 v[50:53], v[188:191], v[172:175], v[50:53]
	s_waitcnt lgkmcnt(3)
	v_mfma_f32_16x16x32_bf16 v[46:49], v[196:199], v[164:167], v[46:49]
	v_mfma_f32_16x16x32_bf16 v[42:45], v[196:199], v[172:175], v[42:45]
	s_waitcnt lgkmcnt(1)
	v_mfma_f32_16x16x32_bf16 v[38:41], v[204:207], v[164:167], v[38:41]
	v_mfma_f32_16x16x32_bf16 v[34:37], v[204:207], v[172:175], v[34:37]
	v_mfma_f32_16x16x32_bf16 v[62:65], v[184:187], v[168:171], v[62:65]
	v_mfma_f32_16x16x32_bf16 v[58:61], v[184:187], v[176:179], v[58:61]
	v_mfma_f32_16x16x32_bf16 v[54:57], v[192:195], v[168:171], v[54:57]
	v_mfma_f32_16x16x32_bf16 v[50:53], v[192:195], v[176:179], v[50:53]
	v_mfma_f32_16x16x32_bf16 v[46:49], v[200:203], v[168:171], v[46:49]
	v_mfma_f32_16x16x32_bf16 v[42:45], v[200:203], v[176:179], v[42:45]
	s_waitcnt lgkmcnt(0)
	v_mfma_f32_16x16x32_bf16 v[38:41], v[208:211], v[168:171], v[38:41]
	v_mfma_f32_16x16x32_bf16 v[34:37], v[208:211], v[176:179], v[34:37]
	s_setprio 0
	s_barrier
	v_readfirstlane_b32 s41, v158
	s_mov_b32 m0, s41
	v_readfirstlane_b32 s41, v159
	buffer_load_dwordx4 v132, s[0:3], s40 offen lds
	s_mov_b32 m0, s41
	s_nop 0
	buffer_load_dwordx4 v136, s[0:3], s40 offen lds
	s_waitcnt vmcnt(6)
	s_barrier
	s_setprio 1
	v_mfma_f32_16x16x32_bf16 v[30:33], v[180:183], v[212:215], v[30:33]
	v_mfma_f32_16x16x32_bf16 v[26:29], v[180:183], v[220:223], v[26:29]
	v_mfma_f32_16x16x32_bf16 v[22:25], v[188:191], v[212:215], v[22:25]
	v_mfma_f32_16x16x32_bf16 v[18:21], v[188:191], v[220:223], v[18:21]
	v_mfma_f32_16x16x32_bf16 v[14:17], v[196:199], v[212:215], v[14:17]
	v_mfma_f32_16x16x32_bf16 v[10:13], v[196:199], v[220:223], v[10:13]
	v_mfma_f32_16x16x32_bf16 v[6:9], v[204:207], v[212:215], v[6:9]
	v_mfma_f32_16x16x32_bf16 v[2:5], v[204:207], v[220:223], v[2:5]
	v_mfma_f32_16x16x32_bf16 v[30:33], v[184:187], v[216:219], v[30:33]
	v_mfma_f32_16x16x32_bf16 v[26:29], v[184:187], v[224:227], v[26:29]
	v_mfma_f32_16x16x32_bf16 v[22:25], v[192:195], v[216:219], v[22:25]
	v_mfma_f32_16x16x32_bf16 v[18:21], v[192:195], v[224:227], v[18:21]
	v_mfma_f32_16x16x32_bf16 v[14:17], v[200:203], v[216:219], v[14:17]
	v_mfma_f32_16x16x32_bf16 v[10:13], v[200:203], v[224:227], v[10:13]
	v_mfma_f32_16x16x32_bf16 v[6:9], v[208:211], v[216:219], v[6:9]
	v_mfma_f32_16x16x32_bf16 v[2:5], v[208:211], v[224:227], v[2:5]
	s_setprio 0
	s_add_i32 s13, s13, 2
	s_addk_i32 s40, 0x100
	s_cmp_lt_u32 s13, 4
	s_cbranch_scc1 .Lrot_3971
	s_barrier
	v_readfirstlane_b32 s0, v157
	s_mov_b32 s6, s2
	s_mov_b32 s7, s3
	s_mov_b32 m0, s0
	v_readfirstlane_b32 s0, v160
	ds_read_b128 v[144:147], v161
	ds_read_b128 v[148:151], v161 offset:1024
	ds_read_b128 v[164:167], v161 offset:2048
	ds_read_b128 v[168:171], v161 offset:3072
	ds_read_b128 v[172:175], v141
	ds_read_b128 v[176:179], v141 offset:1024
	ds_read_b128 v[180:183], v140
	ds_read_b128 v[184:187], v140 offset:1024
	ds_read_b128 v[188:191], v137
	ds_read_b128 v[192:195], v137 offset:1024
	ds_read_b128 v[196:199], v133
	ds_read_b128 v[200:203], v133 offset:1024
	buffer_load_dwordx4 v130, s[4:7], s38 offen lds
	s_mov_b32 m0, s0
	s_nop 0
	buffer_load_dwordx4 v134, s[4:7], s38 offen lds
	s_barrier
	s_waitcnt lgkmcnt(0)
	s_setprio 1
	s_waitcnt lgkmcnt(7)
	v_mfma_f32_16x16x32_bf16 v[126:129], v[172:175], v[144:147], v[126:129]
	v_mfma_f32_16x16x32_bf16 v[122:125], v[172:175], v[164:167], v[122:125]
	s_waitcnt lgkmcnt(5)
	v_mfma_f32_16x16x32_bf16 v[118:121], v[180:183], v[144:147], v[118:121]
	v_mfma_f32_16x16x32_bf16 v[114:117], v[180:183], v[164:167], v[114:117]
	s_waitcnt lgkmcnt(3)
	v_mfma_f32_16x16x32_bf16 v[110:113], v[188:191], v[144:147], v[110:113]
	v_mfma_f32_16x16x32_bf16 v[106:109], v[188:191], v[164:167], v[106:109]
	s_waitcnt lgkmcnt(1)
	v_mfma_f32_16x16x32_bf16 v[102:105], v[196:199], v[144:147], v[102:105]
	v_mfma_f32_16x16x32_bf16 v[98:101], v[196:199], v[164:167], v[98:101]
	v_mfma_f32_16x16x32_bf16 v[126:129], v[176:179], v[148:151], v[126:129]
	v_mfma_f32_16x16x32_bf16 v[122:125], v[176:179], v[168:171], v[122:125]
	v_mfma_f32_16x16x32_bf16 v[118:121], v[184:187], v[148:151], v[118:121]
	v_mfma_f32_16x16x32_bf16 v[114:117], v[184:187], v[168:171], v[114:117]
	v_mfma_f32_16x16x32_bf16 v[110:113], v[192:195], v[148:151], v[110:113]
	v_mfma_f32_16x16x32_bf16 v[106:109], v[192:195], v[168:171], v[106:109]
	s_waitcnt lgkmcnt(0)
	v_mfma_f32_16x16x32_bf16 v[102:105], v[200:203], v[148:151], v[102:105]
	v_mfma_f32_16x16x32_bf16 v[98:101], v[200:203], v[168:171], v[98:101]
	s_setprio 0
	s_barrier
	ds_read_b128 v[156:159], v155
	ds_read_b128 v[204:207], v155 offset:1024
	ds_read_b128 v[208:211], v155 offset:2048
	ds_read_b128 v[152:155], v155 offset:3072
	s_barrier
	s_waitcnt lgkmcnt(0)
	s_setprio 1
	s_waitcnt lgkmcnt(1)
	v_mfma_f32_16x16x32_bf16 v[90:93], v[172:175], v[208:211], v[90:93]
	v_mfma_f32_16x16x32_bf16 v[86:89], v[180:183], v[156:159], v[86:89]
	v_mfma_f32_16x16x32_bf16 v[82:85], v[180:183], v[208:211], v[82:85]
	v_mfma_f32_16x16x32_bf16 v[78:81], v[188:191], v[156:159], v[78:81]
	v_mfma_f32_16x16x32_bf16 v[74:77], v[188:191], v[208:211], v[74:77]
	v_mfma_f32_16x16x32_bf16 v[70:73], v[196:199], v[156:159], v[70:73]
	v_mfma_f32_16x16x32_bf16 v[66:69], v[196:199], v[208:211], v[66:69]
	v_mfma_f32_16x16x32_bf16 v[94:97], v[172:175], v[156:159], v[94:97]
	s_waitcnt lgkmcnt(0)
	v_mfma_f32_16x16x32_bf16 v[90:93], v[176:179], v[152:155], v[90:93]
	v_mfma_f32_16x16x32_bf16 v[86:89], v[184:187], v[204:207], v[86:89]
	v_mfma_f32_16x16x32_bf16 v[82:85], v[184:187], v[152:155], v[82:85]
	v_mfma_f32_16x16x32_bf16 v[78:81], v[192:195], v[204:207], v[78:81]
	v_mfma_f32_16x16x32_bf16 v[74:77], v[192:195], v[152:155], v[74:77]
	v_mfma_f32_16x16x32_bf16 v[70:73], v[200:203], v[204:207], v[70:73]
	v_mfma_f32_16x16x32_bf16 v[66:69], v[200:203], v[152:155], v[66:69]
	v_mfma_f32_16x16x32_bf16 v[212:215], v[176:179], v[204:207], v[94:97]
	s_setprio 0
	s_barrier
; #define LDA_(dst, b, h) _Pragma("unroll") for (int m = 0; m < 4; ++m) _Pragma("unroll") for (int k = 0; k < 2; ++k) \
;     dst[m][k] = *reinterpret_cast<const bf16x8*>((char*)SA(b, h) + lds_byte(wr * 64 + m * 16 + fr, k * 32 + fq * 8))
; #define LDB_(dst, b, h) _Pragma("unroll") for (int n = 0; n < 2; ++n) _Pragma("unroll") for (int k = 0; k < 2; ++k) \
;     dst[n][k] = *reinterpret_cast<const bf16x8*>((char*)SB(b, h) + lds_byte(wc * 32 + n * 16 + fr, k * 32 + fq * 8))
; #define MMA(ai, bj, At, Bx) do { __builtin_amdgcn_s_setprio(1); \
;     _Pragma("unroll") for (int m = 0; m < 4; ++m) _Pragma("unroll") for (int n = 0; n < 2; ++n) _Pragma("unroll") for (int k = 0; k < 2; ++k) \
;       acc[ai][bj][m][n] = __builtin_amdgcn_mfma_f32_16x16x32_bf16(At[m][k], Bx[n][k], acc[ai][bj][m][n], 0, 0, 0); \
;     __builtin_amdgcn_s_setprio(0); } while (0)
; #define WAIT_V(n) asm volatile("s_waitcnt vmcnt(" #n ")" ::: "memory")
; #define WAIT_L(n) asm volatile("s_waitcnt lgkmcnt(" #n ")" ::: "memory")
; #define BAR __builtin_amdgcn_s_barrier()
; template <int K, int LDA, int LDB>
; DEVI void gemm_tile(const bf16* __restrict__ A, const bf16* __restrict__ Bt, bf16* shm, acc_t& acc) {
;     ...
;     LDA_(At, 0, 1); WAIT_V(4); BAR; WAIT_L(0); MMA(1, 0, At, B0); MMA(1, 1, At, B1); BAR; }
;   { LDB_(B0, 1, 0); LDA_(At, 1, 0); WAIT_V(2); BAR; WAIT_L(0); MMA(0, 0, At, B0); BAR;
;     LDB_(B1, 1, 1); WAIT_V(0); BAR; WAIT_L(0); MMA(0, 1, At, B1); BAR;
	s_nop 0
	ds_read_b128 v[94:97], v141 offset:16384
	ds_read_b128 v[172:175], v141 offset:17408
	ds_read_b128 v[176:179], v140 offset:16384
	ds_read_b128 v[180:183], v140 offset:17408
	ds_read_b128 v[184:187], v137 offset:16384
	ds_read_b128 v[188:191], v137 offset:17408
	ds_read_b128 v[192:195], v133 offset:16384
	ds_read_b128 v[196:199], v133 offset:17408
	s_waitcnt vmcnt(4)
	s_barrier
	s_waitcnt lgkmcnt(0)
	s_setprio 1
	s_waitcnt lgkmcnt(7)
	v_mfma_f32_16x16x32_bf16 v[58:61], v[94:97], v[164:167], v[58:61]
	s_waitcnt lgkmcnt(5)
	v_mfma_f32_16x16x32_bf16 v[54:57], v[176:179], v[144:147], v[54:57]
	v_mfma_f32_16x16x32_bf16 v[50:53], v[176:179], v[164:167], v[50:53]
	s_waitcnt lgkmcnt(3)
	v_mfma_f32_16x16x32_bf16 v[46:49], v[184:187], v[144:147], v[46:49]
	v_mfma_f32_16x16x32_bf16 v[42:45], v[184:187], v[164:167], v[42:45]
	s_waitcnt lgkmcnt(1)
	v_mfma_f32_16x16x32_bf16 v[38:41], v[192:195], v[144:147], v[38:41]
	v_mfma_f32_16x16x32_bf16 v[34:37], v[192:195], v[164:167], v[34:37]
	v_mfma_f32_16x16x32_bf16 v[62:65], v[94:97], v[144:147], v[62:65]
	v_mfma_f32_16x16x32_bf16 v[58:61], v[172:175], v[168:171], v[58:61]
	v_mfma_f32_16x16x32_bf16 v[54:57], v[180:183], v[148:151], v[54:57]
	v_mfma_f32_16x16x32_bf16 v[50:53], v[180:183], v[168:171], v[50:53]
	v_mfma_f32_16x16x32_bf16 v[46:49], v[188:191], v[148:151], v[46:49]
	v_mfma_f32_16x16x32_bf16 v[42:45], v[188:191], v[168:171], v[42:45]
	s_waitcnt lgkmcnt(0)
	v_mfma_f32_16x16x32_bf16 v[38:41], v[196:199], v[148:151], v[38:41]
	v_mfma_f32_16x16x32_bf16 v[34:37], v[196:199], v[168:171], v[34:37]
	v_mfma_f32_16x16x32_bf16 v[200:203], v[172:175], v[148:151], v[62:65]
	s_setprio 0
	s_setprio 1
	v_mfma_f32_16x16x32_bf16 v[30:33], v[94:97], v[156:159], v[30:33]
	v_mfma_f32_16x16x32_bf16 v[26:29], v[94:97], v[208:211], v[26:29]
	v_mfma_f32_16x16x32_bf16 v[22:25], v[176:179], v[156:159], v[22:25]
	v_mfma_f32_16x16x32_bf16 v[18:21], v[176:179], v[208:211], v[18:21]
	v_mfma_f32_16x16x32_bf16 v[14:17], v[184:187], v[156:159], v[14:17]
	v_mfma_f32_16x16x32_bf16 v[10:13], v[184:187], v[208:211], v[10:13]
	v_mfma_f32_16x16x32_bf16 v[6:9], v[192:195], v[156:159], v[6:9]
	v_mfma_f32_16x16x32_bf16 v[2:5], v[192:195], v[208:211], v[2:5]
	v_mfma_f32_16x16x32_bf16 v[30:33], v[172:175], v[204:207], v[30:33]
	v_mfma_f32_16x16x32_bf16 v[26:29], v[172:175], v[152:155], v[26:29]
	v_mfma_f32_16x16x32_bf16 v[22:25], v[180:183], v[204:207], v[22:25]
	v_mfma_f32_16x16x32_bf16 v[18:21], v[180:183], v[152:155], v[18:21]
	v_mfma_f32_16x16x32_bf16 v[14:17], v[188:191], v[204:207], v[14:17]
	v_mfma_f32_16x16x32_bf16 v[10:13], v[188:191], v[152:155], v[10:13]
	v_mfma_f32_16x16x32_bf16 v[6:9], v[196:199], v[204:207], v[6:9]
	v_mfma_f32_16x16x32_bf16 v[2:5], v[196:199], v[152:155], v[2:5]
	s_setprio 0
	s_barrier
	ds_read_b128 v[144:147], v143
	ds_read_b128 v[148:151], v143 offset:1024
	ds_read_b128 v[152:155], v143 offset:2048
	ds_read_b128 v[156:159], v143 offset:3072
	ds_read_b128 v[62:65], v141 offset:32768
	ds_read_b128 v[164:167], v141 offset:33792
	ds_read_b128 v[168:171], v140 offset:32768
	ds_read_b128 v[172:175], v140 offset:33792
	ds_read_b128 v[176:179], v137 offset:32768
	ds_read_b128 v[180:183], v137 offset:33792
	ds_read_b128 v[184:187], v133 offset:32768
	ds_read_b128 v[188:191], v133 offset:33792
	s_waitcnt vmcnt(2)
	s_barrier
	s_waitcnt lgkmcnt(0)
	s_setprio 1
	s_waitcnt lgkmcnt(7)
	v_mfma_f32_16x16x32_bf16 v[94:97], v[62:65], v[144:147], v[126:129]
	s_waitcnt lgkmcnt(6)
	v_mfma_f32_16x16x32_bf16 v[126:129], v[164:167], v[148:151], v[94:97]
	v_mfma_f32_16x16x32_bf16 v[94:97], v[62:65], v[152:155], v[122:125]
	v_mfma_f32_16x16x32_bf16 v[122:125], v[164:167], v[156:159], v[94:97]
	s_waitcnt lgkmcnt(5)
	v_mfma_f32_16x16x32_bf16 v[94:97], v[168:171], v[144:147], v[118:121]
	s_waitcnt lgkmcnt(4)
	v_mfma_f32_16x16x32_bf16 v[118:121], v[172:175], v[148:151], v[94:97]
	v_mfma_f32_16x16x32_bf16 v[94:97], v[168:171], v[152:155], v[114:117]
	v_mfma_f32_16x16x32_bf16 v[114:117], v[172:175], v[156:159], v[94:97]
	s_waitcnt lgkmcnt(3)
	v_mfma_f32_16x16x32_bf16 v[94:97], v[176:179], v[144:147], v[110:113]
	s_waitcnt lgkmcnt(2)
	v_mfma_f32_16x16x32_bf16 v[110:113], v[180:183], v[148:151], v[94:97]
	v_mfma_f32_16x16x32_bf16 v[94:97], v[176:179], v[152:155], v[106:109]
	v_mfma_f32_16x16x32_bf16 v[106:109], v[180:183], v[156:159], v[94:97]
	s_waitcnt lgkmcnt(1)
	v_mfma_f32_16x16x32_bf16 v[94:97], v[184:187], v[144:147], v[102:105]
	s_waitcnt lgkmcnt(0)
	v_mfma_f32_16x16x32_bf16 v[102:105], v[188:191], v[148:151], v[94:97]
	v_mfma_f32_16x16x32_bf16 v[94:97], v[184:187], v[152:155], v[98:101]
	v_mfma_f32_16x16x32_bf16 v[94:97], v[188:191], v[156:159], v[94:97]
	s_setprio 0
	s_barrier
; #define LDA_(dst, b, h) _Pragma("unroll") for (int m = 0; m < 4; ++m) _Pragma("unroll") for (int k = 0; k < 2; ++k) \
;     dst[m][k] = *reinterpret_cast<const bf16x8*>((char*)SA(b, h) + lds_byte(wr * 64 + m * 16 + fr, k * 32 + fq * 8))
; #define LDB_(dst, b, h) _Pragma("unroll") for (int n = 0; n < 2; ++n) _Pragma("unroll") for (int k = 0; k < 2; ++k) \
;     dst[n][k] = *reinterpret_cast<const bf16x8*>((char*)SB(b, h) + lds_byte(wc * 32 + n * 16 + fr, k * 32 + fq * 8))
; #define MMA(ai, bj, At, Bx) do { __builtin_amdgcn_s_setprio(1); \
;     _Pragma("unroll") for (int m = 0; m < 4; ++m) _Pragma("unroll") for (int n = 0; n < 2; ++n) _Pragma("unroll") for (int k = 0; k < 2; ++k) \
;       acc[ai][bj][m][n] = __builtin_amdgcn_mfma_f32_16x16x32_bf16(At[m][k], Bx[n][k], acc[ai][bj][m][n], 0, 0, 0); \
;     __builtin_amdgcn_s_setprio(0); } while (0)
; #define WAIT_V(n) asm volatile("s_waitcnt vmcnt(" #n ")" ::: "memory")
; #define WAIT_L(n) asm volatile("s_waitcnt lgkmcnt(" #n ")" ::: "memory")
; #define BAR __builtin_amdgcn_s_barrier()
; template <int K, int LDA, int LDB>
; DEVI void gemm_tile(const bf16* __restrict__ A, const bf16* __restrict__ Bt, bf16* shm, acc_t& acc) {
;     ...
;   { LDB_(B0, 1, 0); LDA_(At, 1, 0); WAIT_V(2); BAR; WAIT_L(0); MMA(0, 0, At, B0); BAR;
;     LDB_(B1, 1, 1); WAIT_V(0); BAR; WAIT_L(0); MMA(0, 1, At, B1); BAR;
;     LDA_(At, 1, 1); BAR; WAIT_L(0); MMA(1, 0, At, B0); MMA(1, 1, At, B1); BAR; }
;   if (wr == 0) BAR;
	ds_read_b128 v[192:195], v142
	ds_read_b128 v[196:199], v142 offset:1024
	ds_read_b128 v[204:207], v142 offset:2048
	ds_read_b128 v[208:211], v142 offset:3072
	s_waitcnt vmcnt(0)
	s_barrier
	s_waitcnt lgkmcnt(0)
	s_setprio 1
	s_waitcnt lgkmcnt(3)
	v_mfma_f32_16x16x32_bf16 v[98:101], v[62:65], v[192:195], v[212:215]
	s_waitcnt lgkmcnt(1)
	v_mfma_f32_16x16x32_bf16 v[62:65], v[62:65], v[204:207], v[90:93]
	s_waitcnt lgkmcnt(0)
	v_mfma_f32_16x16x32_bf16 v[90:93], v[164:167], v[208:211], v[62:65]
	v_mfma_f32_16x16x32_bf16 v[62:65], v[168:171], v[192:195], v[86:89]
	v_mfma_f32_16x16x32_bf16 v[86:89], v[172:175], v[196:199], v[62:65]
	v_mfma_f32_16x16x32_bf16 v[62:65], v[168:171], v[204:207], v[82:85]
	v_mfma_f32_16x16x32_bf16 v[82:85], v[172:175], v[208:211], v[62:65]
	v_mfma_f32_16x16x32_bf16 v[62:65], v[176:179], v[192:195], v[78:81]
	v_mfma_f32_16x16x32_bf16 v[78:81], v[180:183], v[196:199], v[62:65]
	v_mfma_f32_16x16x32_bf16 v[62:65], v[176:179], v[204:207], v[74:77]
	v_mfma_f32_16x16x32_bf16 v[74:77], v[180:183], v[208:211], v[62:65]
	v_mfma_f32_16x16x32_bf16 v[62:65], v[184:187], v[192:195], v[70:73]
	v_mfma_f32_16x16x32_bf16 v[70:73], v[188:191], v[196:199], v[62:65]
	v_mfma_f32_16x16x32_bf16 v[62:65], v[184:187], v[204:207], v[66:69]
	v_mfma_f32_16x16x32_bf16 v[98:101], v[164:167], v[196:199], v[98:101]
	v_mfma_f32_16x16x32_bf16 v[62:65], v[188:191], v[208:211], v[62:65]
	s_setprio 0
	s_barrier
	ds_read_b128 v[164:167], v141 offset:49152
	ds_read_b128 v[168:171], v141 offset:50176
	ds_read_b128 v[172:175], v140 offset:49152
	ds_read_b128 v[140:143], v140 offset:50176
	ds_read_b128 v[176:179], v137 offset:49152
	ds_read_b128 v[180:183], v137 offset:50176
	ds_read_b128 v[184:187], v133 offset:49152
	ds_read_b128 v[188:191], v133 offset:50176
	s_barrier
	s_waitcnt lgkmcnt(0)
	s_setprio 1
	s_waitcnt lgkmcnt(7)
	v_mfma_f32_16x16x32_bf16 v[66:69], v[164:167], v[144:147], v[200:203]
	v_mfma_f32_16x16x32_bf16 v[58:61], v[164:167], v[152:155], v[58:61]
	s_waitcnt lgkmcnt(5)
	v_mfma_f32_16x16x32_bf16 v[54:57], v[172:175], v[144:147], v[54:57]
	v_mfma_f32_16x16x32_bf16 v[50:53], v[172:175], v[152:155], v[50:53]
	s_waitcnt lgkmcnt(3)
	v_mfma_f32_16x16x32_bf16 v[46:49], v[176:179], v[144:147], v[46:49]
	v_mfma_f32_16x16x32_bf16 v[42:45], v[176:179], v[152:155], v[42:45]
	s_waitcnt lgkmcnt(1)
	v_mfma_f32_16x16x32_bf16 v[38:41], v[184:187], v[144:147], v[38:41]
	v_mfma_f32_16x16x32_bf16 v[34:37], v[184:187], v[152:155], v[34:37]
	v_mfma_f32_16x16x32_bf16 v[66:69], v[168:171], v[148:151], v[66:69]
	v_mfma_f32_16x16x32_bf16 v[58:61], v[168:171], v[156:159], v[58:61]
	v_mfma_f32_16x16x32_bf16 v[54:57], v[140:143], v[148:151], v[54:57]
	v_mfma_f32_16x16x32_bf16 v[50:53], v[140:143], v[156:159], v[50:53]
	v_mfma_f32_16x16x32_bf16 v[46:49], v[180:183], v[148:151], v[46:49]
	v_mfma_f32_16x16x32_bf16 v[42:45], v[180:183], v[156:159], v[42:45]
	s_waitcnt lgkmcnt(0)
	v_mfma_f32_16x16x32_bf16 v[38:41], v[188:191], v[148:151], v[38:41]
	v_mfma_f32_16x16x32_bf16 v[34:37], v[188:191], v[156:159], v[34:37]
	s_setprio 0
	s_setprio 1
	v_mfma_f32_16x16x32_bf16 v[30:33], v[164:167], v[192:195], v[30:33]
	v_mfma_f32_16x16x32_bf16 v[26:29], v[164:167], v[204:207], v[26:29]
	v_mfma_f32_16x16x32_bf16 v[22:25], v[172:175], v[192:195], v[22:25]
	v_mfma_f32_16x16x32_bf16 v[18:21], v[172:175], v[204:207], v[18:21]
	v_mfma_f32_16x16x32_bf16 v[14:17], v[176:179], v[192:195], v[14:17]
	v_mfma_f32_16x16x32_bf16 v[10:13], v[176:179], v[204:207], v[10:13]
	v_mfma_f32_16x16x32_bf16 v[6:9], v[184:187], v[192:195], v[6:9]
	v_mfma_f32_16x16x32_bf16 v[2:5], v[184:187], v[204:207], v[2:5]
	v_mfma_f32_16x16x32_bf16 v[30:33], v[168:171], v[196:199], v[30:33]
	v_mfma_f32_16x16x32_bf16 v[26:29], v[168:171], v[208:211], v[26:29]
	v_mfma_f32_16x16x32_bf16 v[22:25], v[140:143], v[196:199], v[22:25]
	v_mfma_f32_16x16x32_bf16 v[18:21], v[140:143], v[208:211], v[18:21]
	v_mfma_f32_16x16x32_bf16 v[14:17], v[180:183], v[196:199], v[14:17]
	v_mfma_f32_16x16x32_bf16 v[10:13], v[180:183], v[208:211], v[10:13]
	v_mfma_f32_16x16x32_bf16 v[6:9], v[188:191], v[196:199], v[6:9]
	v_mfma_f32_16x16x32_bf16 v[2:5], v[188:191], v[208:211], v[2:5]
	s_setprio 0
	s_movk_i32 s0, 0x100
	v_cmp_gt_u32_e32 vcc, s0, v139
	s_barrier
	s_and_saveexec_b64 s[0:1], vcc
	s_cbranch_execz .LBB0_219
	s_barrier

; #define STAGE(P, BASE, LD, br, kt) do { const int _so = (int)(((br) * (LD) + (kt) * BK) * 2); \
;     _Pragma("unroll") for (int _i = 0; _i < 2; ++_i) { \
;       __builtin_amdgcn_raw_ptr_buffer_load_lds(rs##BASE, (__attribute__((address_space(3))) unsigned*)((char*)(P) + tid_ * 16 + _i * 8192), 16, (int)off##LD[_i], _so, 0, 0); } } while (0)
; #define LDA_(dst, b, h) _Pragma("unroll") for (int m = 0; m < 4; ++m) _Pragma("unroll") for (int k = 0; k < 2; ++k) \
;     dst[m][k] = *reinterpret_cast<const bf16x8*>((char*)SA(b, h) + lds_byte(wr * 64 + m * 16 + fr, k * 32 + fq * 8))
; #define LDB_(dst, b, h) _Pragma("unroll") for (int n = 0; n < 2; ++n) _Pragma("unroll") for (int k = 0; k < 2; ++k) \
;     dst[n][k] = *reinterpret_cast<const bf16x8*>((char*)SB(b, h) + lds_byte(wc * 32 + n * 16 + fr, k * 32 + fq * 8))
; #define MMA(ai, bj, At, Bx) do { __builtin_amdgcn_s_setprio(1); \
;     _Pragma("unroll") for (int m = 0; m < 4; ++m) _Pragma("unroll") for (int n = 0; n < 2; ++n) _Pragma("unroll") for (int k = 0; k < 2; ++k) \
;       acc[ai][bj][m][n] = __builtin_amdgcn_mfma_f32_16x16x32_bf16(At[m][k], Bx[n][k], acc[ai][bj][m][n], 0, 0, 0); \
;     __builtin_amdgcn_s_setprio(0); } while (0)
; #define WAIT_V(n) asm volatile("s_waitcnt vmcnt(" #n ")" ::: "memory")
; #define WAIT_L(n) asm volatile("s_waitcnt lgkmcnt(" #n ")" ::: "memory")
; #define BAR __builtin_amdgcn_s_barrier()
; #define SCHED __builtin_amdgcn_sched_barrier(0)
; template <int K, int LDA, int LDB>
; DEVI void gemm_tile(const bf16* __restrict__ A, const bf16* __restrict__ Bt, bf16* shm, acc_t& acc) {
;     ...
;   for (int t = 0; t < nt - 2; t += 2) {
;     LDB_(B0, 0, 0); SCHED; LDA_(At, 0, 0); STAGE(SA(1, 1), A, LDA, HALF, t + 1);
;     WAIT_L(8); BAR; WAIT_L(0); MMA(0, 0, At, B0); BAR; SCHED;
;     LDB_(B1, 0, 1); STAGE(SB(0, 0), Bt, LDB, 0, t + 2);
;     BAR; WAIT_L(0); MMA(0, 1, At, B1); BAR;
;     LDA_(At, 0, 1); STAGE(SA(0, 0), A, LDA, 0, t + 2);
;     BAR; WAIT_L(0); MMA(1, 0, At, B0); BAR; SCHED;
;     STAGE(SB(0, 1), Bt, LDB, HALF, t + 2);
;     WAIT_V(6); BAR; MMA(1, 1, At, B1); BAR;
;     LDB_(B0, 1, 0); SCHED; LDA_(At, 1, 0); STAGE(SA(0, 1), A, LDA, HALF, t + 2);
;     WAIT_L(8); BAR; WAIT_L(0); MMA(0, 0, At, B0); BAR; SCHED;
.LBB0_279:
	ds_read_b128 v[164:167], v160
	ds_read_b128 v[168:171], v160 offset:1024
	ds_read_b128 v[172:175], v160 offset:2048
	ds_read_b128 v[176:179], v160 offset:3072
	v_readfirstlane_b32 s38, v156
	s_add_i32 s37, s13, 0xffffff00
	s_mov_b32 m0, s38
	v_readfirstlane_b32 s38, v159
	ds_read_b128 v[180:183], v138
	ds_read_b128 v[184:187], v138 offset:1024
	ds_read_b128 v[188:191], v137
	ds_read_b128 v[192:195], v137 offset:1024
	ds_read_b128 v[196:199], v133
	ds_read_b128 v[200:203], v133 offset:1024
	ds_read_b128 v[204:207], v132
	ds_read_b128 v[208:211], v132 offset:1024
	buffer_load_dwordx4 v139, s[4:7], s37 offen lds
	s_mov_b32 m0, s38
	s_nop 0
	buffer_load_dwordx4 v141, s[4:7], s37 offen lds
	s_waitcnt lgkmcnt(8)
	s_barrier
	s_waitcnt lgkmcnt(0)
	s_setprio 1
	s_waitcnt lgkmcnt(7)
	v_mfma_f32_16x16x32_bf16 v[126:129], v[180:183], v[164:167], v[126:129]
	v_mfma_f32_16x16x32_bf16 v[122:125], v[180:183], v[172:175], v[122:125]
	s_waitcnt lgkmcnt(5)
	v_mfma_f32_16x16x32_bf16 v[118:121], v[188:191], v[164:167], v[118:121]
	v_mfma_f32_16x16x32_bf16 v[114:117], v[188:191], v[172:175], v[114:117]
	s_waitcnt lgkmcnt(3)
	v_mfma_f32_16x16x32_bf16 v[110:113], v[196:199], v[164:167], v[110:113]
	v_mfma_f32_16x16x32_bf16 v[106:109], v[196:199], v[172:175], v[106:109]
	s_waitcnt lgkmcnt(1)
	v_mfma_f32_16x16x32_bf16 v[102:105], v[204:207], v[164:167], v[102:105]
	v_mfma_f32_16x16x32_bf16 v[98:101], v[204:207], v[172:175], v[98:101]
	v_mfma_f32_16x16x32_bf16 v[126:129], v[184:187], v[168:171], v[126:129]
	v_mfma_f32_16x16x32_bf16 v[122:125], v[184:187], v[176:179], v[122:125]
	v_mfma_f32_16x16x32_bf16 v[118:121], v[192:195], v[168:171], v[118:121]
	v_mfma_f32_16x16x32_bf16 v[114:117], v[192:195], v[176:179], v[114:117]
	v_mfma_f32_16x16x32_bf16 v[110:113], v[200:203], v[168:171], v[110:113]
	v_mfma_f32_16x16x32_bf16 v[106:109], v[200:203], v[176:179], v[106:109]
	s_waitcnt lgkmcnt(0)
	v_mfma_f32_16x16x32_bf16 v[102:105], v[208:211], v[168:171], v[102:105]
	v_mfma_f32_16x16x32_bf16 v[98:101], v[208:211], v[176:179], v[98:101]
	s_setprio 0
	s_barrier
	v_readfirstlane_b32 s38, v143
	s_add_i32 s37, s13, 0xfff7ff80
	s_mov_b32 m0, s38
	v_readfirstlane_b32 s38, v144
	ds_read_b128 v[212:215], v154
	ds_read_b128 v[216:219], v154 offset:1024
	ds_read_b128 v[220:223], v154 offset:2048
	ds_read_b128 v[224:227], v154 offset:3072
	buffer_load_dwordx4 v139, s[0:3], s37 offen lds
	s_mov_b32 m0, s38
	s_nop 0
	buffer_load_dwordx4 v141, s[0:3], s37 offen lds
	s_barrier
	s_waitcnt lgkmcnt(0)
	s_setprio 1
	s_waitcnt lgkmcnt(3)
	v_mfma_f32_16x16x32_bf16 v[94:97], v[180:183], v[212:215], v[94:97]
	s_waitcnt lgkmcnt(1)
	v_mfma_f32_16x16x32_bf16 v[90:93], v[180:183], v[220:223], v[90:93]
	v_mfma_f32_16x16x32_bf16 v[86:89], v[188:191], v[212:215], v[86:89]
	v_mfma_f32_16x16x32_bf16 v[82:85], v[188:191], v[220:223], v[82:85]
	v_mfma_f32_16x16x32_bf16 v[78:81], v[196:199], v[212:215], v[78:81]
	v_mfma_f32_16x16x32_bf16 v[74:77], v[196:199], v[220:223], v[74:77]
	v_mfma_f32_16x16x32_bf16 v[70:73], v[204:207], v[212:215], v[70:73]
	v_mfma_f32_16x16x32_bf16 v[66:69], v[204:207], v[220:223], v[66:69]
	v_mfma_f32_16x16x32_bf16 v[94:97], v[184:187], v[216:219], v[94:97]
	s_waitcnt lgkmcnt(0)
	v_mfma_f32_16x16x32_bf16 v[90:93], v[184:187], v[224:227], v[90:93]
	v_mfma_f32_16x16x32_bf16 v[86:89], v[192:195], v[216:219], v[86:89]
	v_mfma_f32_16x16x32_bf16 v[82:85], v[192:195], v[224:227], v[82:85]
	v_mfma_f32_16x16x32_bf16 v[78:81], v[200:203], v[216:219], v[78:81]
	v_mfma_f32_16x16x32_bf16 v[74:77], v[200:203], v[224:227], v[74:77]
	v_mfma_f32_16x16x32_bf16 v[70:73], v[208:211], v[216:219], v[70:73]
	v_mfma_f32_16x16x32_bf16 v[66:69], v[208:211], v[224:227], v[66:69]
	s_setprio 0
	v_readfirstlane_b32 s38, v145
	s_mov_b32 m0, s38
	v_readfirstlane_b32 s38, v146
	s_barrier
	ds_read_b128 v[180:183], v138 offset:16384
	ds_read_b128 v[184:187], v138 offset:17408
	ds_read_b128 v[188:191], v137 offset:16384
	ds_read_b128 v[192:195], v137 offset:17408
	ds_read_b128 v[196:199], v133 offset:16384
	ds_read_b128 v[200:203], v133 offset:17408
	ds_read_b128 v[204:207], v132 offset:16384
	ds_read_b128 v[208:211], v132 offset:17408
	buffer_load_dwordx4 v139, s[4:7], s37 offen lds
	s_mov_b32 m0, s38
	s_nop 0
	buffer_load_dwordx4 v141, s[4:7], s37 offen lds
	s_barrier
	s_waitcnt lgkmcnt(0)
	s_setprio 1
	s_waitcnt lgkmcnt(7)
	v_mfma_f32_16x16x32_bf16 v[62:65], v[180:183], v[164:167], v[62:65]
	v_mfma_f32_16x16x32_bf16 v[58:61], v[180:183], v[172:175], v[58:61]
	s_waitcnt lgkmcnt(5)
	v_mfma_f32_16x16x32_bf16 v[54:57], v[188:191], v[164:167], v[54:57]
	v_mfma_f32_16x16x32_bf16 v[50:53], v[188:191], v[172:175], v[50:53]
	s_waitcnt lgkmcnt(3)
	v_mfma_f32_16x16x32_bf16 v[46:49], v[196:199], v[164:167], v[46:49]
	v_mfma_f32_16x16x32_bf16 v[42:45], v[196:199], v[172:175], v[42:45]
	s_waitcnt lgkmcnt(1)
	v_mfma_f32_16x16x32_bf16 v[38:41], v[204:207], v[164:167], v[38:41]
	v_mfma_f32_16x16x32_bf16 v[34:37], v[204:207], v[172:175], v[34:37]
	v_mfma_f32_16x16x32_bf16 v[62:65], v[184:187], v[168:171], v[62:65]
	v_mfma_f32_16x16x32_bf16 v[58:61], v[184:187], v[176:179], v[58:61]
	v_mfma_f32_16x16x32_bf16 v[54:57], v[192:195], v[168:171], v[54:57]
	v_mfma_f32_16x16x32_bf16 v[50:53], v[192:195], v[176:179], v[50:53]
	v_mfma_f32_16x16x32_bf16 v[46:49], v[200:203], v[168:171], v[46:49]
	v_mfma_f32_16x16x32_bf16 v[42:45], v[200:203], v[176:179], v[42:45]
	s_waitcnt lgkmcnt(0)
	v_mfma_f32_16x16x32_bf16 v[38:41], v[208:211], v[168:171], v[38:41]
	v_mfma_f32_16x16x32_bf16 v[34:37], v[208:211], v[176:179], v[34:37]
	s_setprio 0
	s_barrier
; #define STAGE(P, BASE, LD, br, kt) do { const int _so = (int)(((br) * (LD) + (kt) * BK) * 2); \
;     _Pragma("unroll") for (int _i = 0; _i < 2; ++_i) { \
;       __builtin_amdgcn_raw_ptr_buffer_load_lds(rs##BASE, (__attribute__((address_space(3))) unsigned*)((char*)(P) + tid_ * 16 + _i * 8192), 16, (int)off##LD[_i], _so, 0, 0); } } while (0)
; #define LDA_(dst, b, h) _Pragma("unroll") for (int m = 0; m < 4; ++m) _Pragma("unroll") for (int k = 0; k < 2; ++k) \
;     dst[m][k] = *reinterpret_cast<const bf16x8*>((char*)SA(b, h) + lds_byte(wr * 64 + m * 16 + fr, k * 32 + fq * 8))
; #define LDB_(dst, b, h) _Pragma("unroll") for (int n = 0; n < 2; ++n) _Pragma("unroll") for (int k = 0; k < 2; ++k) \
;     dst[n][k] = *reinterpret_cast<const bf16x8*>((char*)SB(b, h) + lds_byte(wc * 32 + n * 16 + fr, k * 32 + fq * 8))
; #define MMA(ai, bj, At, Bx) do { __builtin_amdgcn_s_setprio(1); \
;     _Pragma("unroll") for (int m = 0; m < 4; ++m) _Pragma("unroll") for (int n = 0; n < 2; ++n) _Pragma("unroll") for (int k = 0; k < 2; ++k) \
;       acc[ai][bj][m][n] = __builtin_amdgcn_mfma_f32_16x16x32_bf16(At[m][k], Bx[n][k], acc[ai][bj][m][n], 0, 0, 0); \
;     __builtin_amdgcn_s_setprio(0); } while (0)
; #define WAIT_V(n) asm volatile("s_waitcnt vmcnt(" #n ")" ::: "memory")
; #define WAIT_L(n) asm volatile("s_waitcnt lgkmcnt(" #n ")" ::: "memory")
; #define BAR __builtin_amdgcn_s_barrier()
; #define SCHED __builtin_amdgcn_sched_barrier(0)
; template <int K, int LDA, int LDB>
; DEVI void gemm_tile(const bf16* __restrict__ A, const bf16* __restrict__ Bt, bf16* shm, acc_t& acc) {
;     ...
;     STAGE(SB(0, 1), Bt, LDB, HALF, t + 2);
;     WAIT_V(6); BAR; MMA(1, 1, At, B1); BAR;
;     LDB_(B0, 1, 0); SCHED; LDA_(At, 1, 0); STAGE(SA(0, 1), A, LDA, HALF, t + 2);
;     WAIT_L(8); BAR; WAIT_L(0); MMA(0, 0, At, B0); BAR; SCHED;
;     LDB_(B1, 1, 1); STAGE(SB(1, 0), Bt, LDB, 0, t + 3);
;     BAR; WAIT_L(0); MMA(0, 1, At, B1); BAR;
;     LDA_(At, 1, 1); STAGE(SA(1, 0), A, LDA, 0, t + 3);
;     BAR; WAIT_L(0); MMA(1, 0, At, B0); BAR; SCHED;
	v_readfirstlane_b32 s38, v147
	s_add_i32 s37, s13, 0xffffff80
	s_mov_b32 m0, s38
	v_readfirstlane_b32 s38, v148
	buffer_load_dwordx4 v139, s[0:3], s37 offen lds
	s_mov_b32 m0, s38
	s_nop 0
	buffer_load_dwordx4 v141, s[0:3], s37 offen lds
	s_waitcnt vmcnt(6)
	s_barrier
	s_setprio 1
	v_mfma_f32_16x16x32_bf16 v[30:33], v[180:183], v[212:215], v[30:33]
	v_mfma_f32_16x16x32_bf16 v[26:29], v[180:183], v[220:223], v[26:29]
	v_mfma_f32_16x16x32_bf16 v[22:25], v[188:191], v[212:215], v[22:25]
	v_mfma_f32_16x16x32_bf16 v[18:21], v[188:191], v[220:223], v[18:21]
	v_mfma_f32_16x16x32_bf16 v[14:17], v[196:199], v[212:215], v[14:17]
	v_mfma_f32_16x16x32_bf16 v[10:13], v[196:199], v[220:223], v[10:13]
	v_mfma_f32_16x16x32_bf16 v[6:9], v[204:207], v[212:215], v[6:9]
	v_mfma_f32_16x16x32_bf16 v[2:5], v[204:207], v[220:223], v[2:5]
	v_mfma_f32_16x16x32_bf16 v[30:33], v[184:187], v[216:219], v[30:33]
	v_mfma_f32_16x16x32_bf16 v[26:29], v[184:187], v[224:227], v[26:29]
	v_mfma_f32_16x16x32_bf16 v[22:25], v[192:195], v[216:219], v[22:25]
	v_mfma_f32_16x16x32_bf16 v[18:21], v[192:195], v[224:227], v[18:21]
	v_mfma_f32_16x16x32_bf16 v[14:17], v[200:203], v[216:219], v[14:17]
	v_mfma_f32_16x16x32_bf16 v[10:13], v[200:203], v[224:227], v[10:13]
	v_mfma_f32_16x16x32_bf16 v[6:9], v[208:211], v[216:219], v[6:9]
	v_mfma_f32_16x16x32_bf16 v[2:5], v[208:211], v[224:227], v[2:5]
	s_setprio 0
	s_barrier
	ds_read_b128 v[164:167], v142
	ds_read_b128 v[168:171], v142 offset:1024
	ds_read_b128 v[172:175], v142 offset:2048
	ds_read_b128 v[176:179], v142 offset:3072
	v_readfirstlane_b32 s38, v149
	s_mov_b32 m0, s38
	v_readfirstlane_b32 s38, v150
	ds_read_b128 v[180:183], v138 offset:32768
	ds_read_b128 v[184:187], v138 offset:33792
	ds_read_b128 v[188:191], v137 offset:32768
	ds_read_b128 v[192:195], v137 offset:33792
	ds_read_b128 v[196:199], v133 offset:32768
	ds_read_b128 v[200:203], v133 offset:33792
	ds_read_b128 v[204:207], v132 offset:32768
	ds_read_b128 v[208:211], v132 offset:33792
	buffer_load_dwordx4 v139, s[4:7], s37 offen lds
	s_mov_b32 m0, s38
	s_nop 0
	buffer_load_dwordx4 v141, s[4:7], s37 offen lds
	s_waitcnt lgkmcnt(8)
	s_barrier
	s_waitcnt lgkmcnt(0)
	s_setprio 1
	s_waitcnt lgkmcnt(7)
	v_mfma_f32_16x16x32_bf16 v[126:129], v[180:183], v[164:167], v[126:129]
	v_mfma_f32_16x16x32_bf16 v[122:125], v[180:183], v[172:175], v[122:125]
	s_waitcnt lgkmcnt(5)
	v_mfma_f32_16x16x32_bf16 v[118:121], v[188:191], v[164:167], v[118:121]
	v_mfma_f32_16x16x32_bf16 v[114:117], v[188:191], v[172:175], v[114:117]
	s_waitcnt lgkmcnt(3)
	v_mfma_f32_16x16x32_bf16 v[110:113], v[196:199], v[164:167], v[110:113]
	v_mfma_f32_16x16x32_bf16 v[106:109], v[196:199], v[172:175], v[106:109]
	s_waitcnt lgkmcnt(1)
	v_mfma_f32_16x16x32_bf16 v[102:105], v[204:207], v[164:167], v[102:105]
	v_mfma_f32_16x16x32_bf16 v[98:101], v[204:207], v[172:175], v[98:101]
	v_mfma_f32_16x16x32_bf16 v[126:129], v[184:187], v[168:171], v[126:129]
	v_mfma_f32_16x16x32_bf16 v[122:125], v[184:187], v[176:179], v[122:125]
	v_mfma_f32_16x16x32_bf16 v[118:121], v[192:195], v[168:171], v[118:121]
	v_mfma_f32_16x16x32_bf16 v[114:117], v[192:195], v[176:179], v[114:117]
	v_mfma_f32_16x16x32_bf16 v[110:113], v[200:203], v[168:171], v[110:113]
	v_mfma_f32_16x16x32_bf16 v[106:109], v[200:203], v[176:179], v[106:109]
	s_waitcnt lgkmcnt(0)
	v_mfma_f32_16x16x32_bf16 v[102:105], v[208:211], v[168:171], v[102:105]
	v_mfma_f32_16x16x32_bf16 v[98:101], v[208:211], v[176:179], v[98:101]
	s_setprio 0
	s_barrier
	v_readfirstlane_b32 s38, v151
	s_add_i32 s37, s13, 0xfff80000
	s_mov_b32 m0, s38
	v_readfirstlane_b32 s38, v152
	ds_read_b128 v[212:215], v140
	ds_read_b128 v[216:219], v140 offset:1024
	ds_read_b128 v[220:223], v140 offset:2048
	ds_read_b128 v[224:227], v140 offset:3072
	buffer_load_dwordx4 v139, s[0:3], s37 offen lds
	s_mov_b32 m0, s38
	s_nop 0
	buffer_load_dwordx4 v141, s[0:3], s37 offen lds
	s_barrier
	s_waitcnt lgkmcnt(0)
	s_setprio 1
	s_waitcnt lgkmcnt(3)
	v_mfma_f32_16x16x32_bf16 v[94:97], v[180:183], v[212:215], v[94:97]
	s_waitcnt lgkmcnt(1)
	v_mfma_f32_16x16x32_bf16 v[90:93], v[180:183], v[220:223], v[90:93]
	v_mfma_f32_16x16x32_bf16 v[86:89], v[188:191], v[212:215], v[86:89]
	v_mfma_f32_16x16x32_bf16 v[82:85], v[188:191], v[220:223], v[82:85]
	v_mfma_f32_16x16x32_bf16 v[78:81], v[196:199], v[212:215], v[78:81]
	v_mfma_f32_16x16x32_bf16 v[74:77], v[196:199], v[220:223], v[74:77]
	v_mfma_f32_16x16x32_bf16 v[70:73], v[204:207], v[212:215], v[70:73]
	v_mfma_f32_16x16x32_bf16 v[66:69], v[204:207], v[220:223], v[66:69]
	v_mfma_f32_16x16x32_bf16 v[94:97], v[184:187], v[216:219], v[94:97]
	s_waitcnt lgkmcnt(0)
	v_mfma_f32_16x16x32_bf16 v[90:93], v[184:187], v[224:227], v[90:93]
	v_mfma_f32_16x16x32_bf16 v[86:89], v[192:195], v[216:219], v[86:89]
	v_mfma_f32_16x16x32_bf16 v[82:85], v[192:195], v[224:227], v[82:85]
	v_mfma_f32_16x16x32_bf16 v[78:81], v[200:203], v[216:219], v[78:81]
	v_mfma_f32_16x16x32_bf16 v[74:77], v[200:203], v[224:227], v[74:77]
	v_mfma_f32_16x16x32_bf16 v[70:73], v[208:211], v[216:219], v[70:73]
	v_mfma_f32_16x16x32_bf16 v[66:69], v[208:211], v[224:227], v[66:69]
	s_setprio 0
	v_readfirstlane_b32 s38, v153
	s_mov_b32 m0, s38
	v_readfirstlane_b32 s38, v155
	s_barrier
	ds_read_b128 v[180:183], v138 offset:49152
	ds_read_b128 v[184:187], v138 offset:50176
	ds_read_b128 v[188:191], v137 offset:49152
	ds_read_b128 v[192:195], v137 offset:50176
	ds_read_b128 v[196:199], v133 offset:49152
	ds_read_b128 v[200:203], v133 offset:50176
	ds_read_b128 v[204:207], v132 offset:49152
	ds_read_b128 v[208:211], v132 offset:50176
	buffer_load_dwordx4 v139, s[4:7], s37 offen lds
	s_mov_b32 m0, s38
	s_nop 0
	buffer_load_dwordx4 v141, s[4:7], s37 offen lds
	s_barrier
; #define STAGE(P, BASE, LD, br, kt) do { const int _so = (int)(((br) * (LD) + (kt) * BK) * 2); \
;     _Pragma("unroll") for (int _i = 0; _i < 2; ++_i) { \
;       __builtin_amdgcn_raw_ptr_buffer_load_lds(rs##BASE, (__attribute__((address_space(3))) unsigned*)((char*)(P) + tid_ * 16 + _i * 8192), 16, (int)off##LD[_i], _so, 0, 0); } } while (0)
; #define LDA_(dst, b, h) _Pragma("unroll") for (int m = 0; m < 4; ++m) _Pragma("unroll") for (int k = 0; k < 2; ++k) \
;     dst[m][k] = *reinterpret_cast<const bf16x8*>((char*)SA(b, h) + lds_byte(wr * 64 + m * 16 + fr, k * 32 + fq * 8))
; #define LDB_(dst, b, h) _Pragma("unroll") for (int n = 0; n < 2; ++n) _Pragma("unroll") for (int k = 0; k < 2; ++k) \
;     dst[n][k] = *reinterpret_cast<const bf16x8*>((char*)SB(b, h) + lds_byte(wc * 32 + n * 16 + fr, k * 32 + fq * 8))
; #define MMA(ai, bj, At, Bx) do { __builtin_amdgcn_s_setprio(1); \
;     _Pragma("unroll") for (int m = 0; m < 4; ++m) _Pragma("unroll") for (int n = 0; n < 2; ++n) _Pragma("unroll") for (int k = 0; k < 2; ++k) \
;       acc[ai][bj][m][n] = __builtin_amdgcn_mfma_f32_16x16x32_bf16(At[m][k], Bx[n][k], acc[ai][bj][m][n], 0, 0, 0); \
;     __builtin_amdgcn_s_setprio(0); } while (0)
; #define WAIT_V(n) asm volatile("s_waitcnt vmcnt(" #n ")" ::: "memory")
; #define WAIT_L(n) asm volatile("s_waitcnt lgkmcnt(" #n ")" ::: "memory")
; #define BAR __builtin_amdgcn_s_barrier()
; #define SCHED __builtin_amdgcn_sched_barrier(0)
; template <int K, int LDA, int LDB>
; DEVI void gemm_tile(const bf16* __restrict__ A, const bf16* __restrict__ Bt, bf16* shm, acc_t& acc) {
;     ...
;     BAR; WAIT_L(0); MMA(1, 0, At, B0); BAR; SCHED;
;     STAGE(SB(1, 1), Bt, LDB, HALF, t + 3);
;     WAIT_V(6); BAR; MMA(1, 1, At, B1); BAR;
;   }
;   { LDB_(B0, 0, 0); LDA_(At, 0, 0); STAGE(SA(1, 1), A, LDA, HALF, nt - 1);
;     BAR; WAIT_L(0); MMA(0, 0, At, B0); BAR;
;     LDB_(B1, 0, 1); BAR; WAIT_L(0); MMA(0, 1, At, B1); BAR;
	s_waitcnt lgkmcnt(0)
	s_setprio 1
	s_waitcnt lgkmcnt(7)
	v_mfma_f32_16x16x32_bf16 v[62:65], v[180:183], v[164:167], v[62:65]
	v_mfma_f32_16x16x32_bf16 v[58:61], v[180:183], v[172:175], v[58:61]
	s_waitcnt lgkmcnt(5)
	v_mfma_f32_16x16x32_bf16 v[54:57], v[188:191], v[164:167], v[54:57]
	v_mfma_f32_16x16x32_bf16 v[50:53], v[188:191], v[172:175], v[50:53]
	s_waitcnt lgkmcnt(3)
	v_mfma_f32_16x16x32_bf16 v[46:49], v[196:199], v[164:167], v[46:49]
	v_mfma_f32_16x16x32_bf16 v[42:45], v[196:199], v[172:175], v[42:45]
	s_waitcnt lgkmcnt(1)
	v_mfma_f32_16x16x32_bf16 v[38:41], v[204:207], v[164:167], v[38:41]
	v_mfma_f32_16x16x32_bf16 v[34:37], v[204:207], v[172:175], v[34:37]
	v_mfma_f32_16x16x32_bf16 v[62:65], v[184:187], v[168:171], v[62:65]
	v_mfma_f32_16x16x32_bf16 v[58:61], v[184:187], v[176:179], v[58:61]
	v_mfma_f32_16x16x32_bf16 v[54:57], v[192:195], v[168:171], v[54:57]
	v_mfma_f32_16x16x32_bf16 v[50:53], v[192:195], v[176:179], v[50:53]
	v_mfma_f32_16x16x32_bf16 v[46:49], v[200:203], v[168:171], v[46:49]
	v_mfma_f32_16x16x32_bf16 v[42:45], v[200:203], v[176:179], v[42:45]
	s_waitcnt lgkmcnt(0)
	v_mfma_f32_16x16x32_bf16 v[38:41], v[208:211], v[168:171], v[38:41]
	v_mfma_f32_16x16x32_bf16 v[34:37], v[208:211], v[176:179], v[34:37]
	s_setprio 0
	s_barrier
	v_readfirstlane_b32 s37, v157
	s_mov_b32 m0, s37
	v_readfirstlane_b32 s37, v158
	buffer_load_dwordx4 v139, s[0:3], s13 offen lds
	s_mov_b32 m0, s37
	s_nop 0
	buffer_load_dwordx4 v141, s[0:3], s13 offen lds
	s_waitcnt vmcnt(6)
	s_barrier
	s_setprio 1
	v_mfma_f32_16x16x32_bf16 v[30:33], v[180:183], v[212:215], v[30:33]
	v_mfma_f32_16x16x32_bf16 v[26:29], v[180:183], v[220:223], v[26:29]
	v_mfma_f32_16x16x32_bf16 v[22:25], v[188:191], v[212:215], v[22:25]
	v_mfma_f32_16x16x32_bf16 v[18:21], v[188:191], v[220:223], v[18:21]
	v_mfma_f32_16x16x32_bf16 v[14:17], v[196:199], v[212:215], v[14:17]
	v_mfma_f32_16x16x32_bf16 v[10:13], v[196:199], v[220:223], v[10:13]
	v_mfma_f32_16x16x32_bf16 v[6:9], v[204:207], v[212:215], v[6:9]
	v_mfma_f32_16x16x32_bf16 v[2:5], v[204:207], v[220:223], v[2:5]
	v_mfma_f32_16x16x32_bf16 v[30:33], v[184:187], v[216:219], v[30:33]
	v_mfma_f32_16x16x32_bf16 v[26:29], v[184:187], v[224:227], v[26:29]
	v_mfma_f32_16x16x32_bf16 v[22:25], v[192:195], v[216:219], v[22:25]
	v_mfma_f32_16x16x32_bf16 v[18:21], v[192:195], v[224:227], v[18:21]
	v_mfma_f32_16x16x32_bf16 v[14:17], v[200:203], v[216:219], v[14:17]
	v_mfma_f32_16x16x32_bf16 v[10:13], v[200:203], v[224:227], v[10:13]
	v_mfma_f32_16x16x32_bf16 v[6:9], v[208:211], v[216:219], v[6:9]
	v_mfma_f32_16x16x32_bf16 v[2:5], v[208:211], v[224:227], v[2:5]
	s_setprio 0
	s_add_i32 s11, s11, 2
	s_addk_i32 s13, 0x100
	s_cmp_lt_u32 s11, 28
	s_cbranch_scc1 .Lrot_5930
	s_barrier
	v_readfirstlane_b32 s0, v156
	s_mov_b32 s6, s2
	s_mov_b32 s7, s3
	s_mov_b32 m0, s0
	v_readfirstlane_b32 s0, v159
	ds_read_b128 v[144:147], v160
	ds_read_b128 v[148:151], v160 offset:1024
	ds_read_b128 v[164:167], v160 offset:2048
	ds_read_b128 v[168:171], v160 offset:3072
	ds_read_b128 v[172:175], v138
	ds_read_b128 v[176:179], v138 offset:1024
	ds_read_b128 v[180:183], v137
	ds_read_b128 v[184:187], v137 offset:1024
	ds_read_b128 v[188:191], v133
	ds_read_b128 v[192:195], v133 offset:1024
	ds_read_b128 v[196:199], v132
	ds_read_b128 v[200:203], v132 offset:1024
	buffer_load_dwordx4 v139, s[4:7], s35 offen lds
	s_mov_b32 m0, s0
	s_nop 0
	buffer_load_dwordx4 v141, s[4:7], s35 offen lds
	s_barrier
	s_waitcnt lgkmcnt(0)
	s_setprio 1
	s_waitcnt lgkmcnt(7)
	v_mfma_f32_16x16x32_bf16 v[126:129], v[172:175], v[144:147], v[126:129]
	v_mfma_f32_16x16x32_bf16 v[122:125], v[172:175], v[164:167], v[122:125]
	s_waitcnt lgkmcnt(5)
	v_mfma_f32_16x16x32_bf16 v[118:121], v[180:183], v[144:147], v[118:121]
	v_mfma_f32_16x16x32_bf16 v[114:117], v[180:183], v[164:167], v[114:117]
	s_waitcnt lgkmcnt(3)
	v_mfma_f32_16x16x32_bf16 v[110:113], v[188:191], v[144:147], v[110:113]
	v_mfma_f32_16x16x32_bf16 v[106:109], v[188:191], v[164:167], v[106:109]
	s_waitcnt lgkmcnt(1)
	v_mfma_f32_16x16x32_bf16 v[102:105], v[196:199], v[144:147], v[102:105]
	v_mfma_f32_16x16x32_bf16 v[98:101], v[196:199], v[164:167], v[98:101]
	v_mfma_f32_16x16x32_bf16 v[126:129], v[176:179], v[148:151], v[126:129]
	v_mfma_f32_16x16x32_bf16 v[122:125], v[176:179], v[168:171], v[122:125]
	v_mfma_f32_16x16x32_bf16 v[118:121], v[184:187], v[148:151], v[118:121]
	v_mfma_f32_16x16x32_bf16 v[114:117], v[184:187], v[168:171], v[114:117]
	v_mfma_f32_16x16x32_bf16 v[110:113], v[192:195], v[148:151], v[110:113]
	v_mfma_f32_16x16x32_bf16 v[106:109], v[192:195], v[168:171], v[106:109]
	s_waitcnt lgkmcnt(0)
	v_mfma_f32_16x16x32_bf16 v[102:105], v[200:203], v[148:151], v[102:105]
	v_mfma_f32_16x16x32_bf16 v[98:101], v[200:203], v[168:171], v[98:101]
	s_setprio 0
	s_barrier
	ds_read_b128 v[156:159], v154
	ds_read_b128 v[204:207], v154 offset:1024
	ds_read_b128 v[208:211], v154 offset:2048
	ds_read_b128 v[152:155], v154 offset:3072
	s_barrier
	s_waitcnt lgkmcnt(0)
	s_setprio 1
	s_waitcnt lgkmcnt(3)
	v_mfma_f32_16x16x32_bf16 v[94:97], v[172:175], v[156:159], v[94:97]
	s_waitcnt lgkmcnt(1)
	v_mfma_f32_16x16x32_bf16 v[90:93], v[172:175], v[208:211], v[90:93]
	v_mfma_f32_16x16x32_bf16 v[86:89], v[180:183], v[156:159], v[86:89]
	v_mfma_f32_16x16x32_bf16 v[82:85], v[180:183], v[208:211], v[82:85]
	v_mfma_f32_16x16x32_bf16 v[78:81], v[188:191], v[156:159], v[78:81]
	v_mfma_f32_16x16x32_bf16 v[70:73], v[196:199], v[156:159], v[70:73]
	v_mfma_f32_16x16x32_bf16 v[66:69], v[196:199], v[208:211], v[66:69]
	v_mfma_f32_16x16x32_bf16 v[94:97], v[176:179], v[204:207], v[94:97]
	s_waitcnt lgkmcnt(0)
	v_mfma_f32_16x16x32_bf16 v[90:93], v[176:179], v[152:155], v[90:93]
	v_mfma_f32_16x16x32_bf16 v[86:89], v[184:187], v[204:207], v[86:89]
	v_mfma_f32_16x16x32_bf16 v[82:85], v[184:187], v[152:155], v[82:85]
	v_mfma_f32_16x16x32_bf16 v[78:81], v[192:195], v[204:207], v[78:81]
	v_mfma_f32_16x16x32_bf16 v[74:77], v[188:191], v[208:211], v[74:77]
	v_mfma_f32_16x16x32_bf16 v[70:73], v[200:203], v[204:207], v[70:73]
	v_mfma_f32_16x16x32_bf16 v[66:69], v[200:203], v[152:155], v[66:69]
	v_mfma_f32_16x16x32_bf16 v[172:175], v[192:195], v[152:155], v[74:77]
	s_setprio 0
	s_barrier
; #define LDA_(dst, b, h) _Pragma("unroll") for (int m = 0; m < 4; ++m) _Pragma("unroll") for (int k = 0; k < 2; ++k) \
;     dst[m][k] = *reinterpret_cast<const bf16x8*>((char*)SA(b, h) + lds_byte(wr * 64 + m * 16 + fr, k * 32 + fq * 8))
; #define LDB_(dst, b, h) _Pragma("unroll") for (int n = 0; n < 2; ++n) _Pragma("unroll") for (int k = 0; k < 2; ++k) \
;     dst[n][k] = *reinterpret_cast<const bf16x8*>((char*)SB(b, h) + lds_byte(wc * 32 + n * 16 + fr, k * 32 + fq * 8))
; #define MMA(ai, bj, At, Bx) do { __builtin_amdgcn_s_setprio(1); \
;     _Pragma("unroll") for (int m = 0; m < 4; ++m) _Pragma("unroll") for (int n = 0; n < 2; ++n) _Pragma("unroll") for (int k = 0; k < 2; ++k) \
;       acc[ai][bj][m][n] = __builtin_amdgcn_mfma_f32_16x16x32_bf16(At[m][k], Bx[n][k], acc[ai][bj][m][n], 0, 0, 0); \
;     __builtin_amdgcn_s_setprio(0); } while (0)
; #define WAIT_V(n) asm volatile("s_waitcnt vmcnt(" #n ")" ::: "memory")
; #define WAIT_L(n) asm volatile("s_waitcnt lgkmcnt(" #n ")" ::: "memory")
; #define BAR __builtin_amdgcn_s_barrier()
; template <int K, int LDA, int LDB>
; DEVI void gemm_tile(const bf16* __restrict__ A, const bf16* __restrict__ Bt, bf16* shm, acc_t& acc) {
;     ...
;     LDA_(At, 0, 1); WAIT_V(4); BAR; WAIT_L(0); MMA(1, 0, At, B0); MMA(1, 1, At, B1); BAR; }
;   { LDB_(B0, 1, 0); LDA_(At, 1, 0); WAIT_V(2); BAR; WAIT_L(0); MMA(0, 0, At, B0); BAR;
	s_nop 2
	ds_read_b128 v[74:77], v138 offset:16384
	ds_read_b128 v[176:179], v138 offset:17408
	ds_read_b128 v[180:183], v137 offset:16384
	ds_read_b128 v[184:187], v137 offset:17408
	ds_read_b128 v[188:191], v133 offset:16384
	ds_read_b128 v[192:195], v133 offset:17408
	ds_read_b128 v[196:199], v132 offset:16384
	ds_read_b128 v[200:203], v132 offset:17408
	s_waitcnt vmcnt(4)
	s_barrier
	s_waitcnt lgkmcnt(0)
	s_setprio 1
	s_waitcnt lgkmcnt(3)
	v_mfma_f32_16x16x32_bf16 v[42:45], v[188:191], v[164:167], v[42:45]
	s_waitcnt lgkmcnt(1)
	v_mfma_f32_16x16x32_bf16 v[38:41], v[196:199], v[144:147], v[38:41]
	v_mfma_f32_16x16x32_bf16 v[62:65], v[74:77], v[144:147], v[62:65]
	v_mfma_f32_16x16x32_bf16 v[58:61], v[74:77], v[164:167], v[58:61]
	v_mfma_f32_16x16x32_bf16 v[54:57], v[180:183], v[144:147], v[54:57]
	v_mfma_f32_16x16x32_bf16 v[50:53], v[180:183], v[164:167], v[50:53]
	v_mfma_f32_16x16x32_bf16 v[46:49], v[188:191], v[144:147], v[46:49]
	v_mfma_f32_16x16x32_bf16 v[42:45], v[192:195], v[168:171], v[42:45]
	s_waitcnt lgkmcnt(0)
	v_mfma_f32_16x16x32_bf16 v[38:41], v[200:203], v[148:151], v[38:41]
	v_mfma_f32_16x16x32_bf16 v[34:37], v[196:199], v[164:167], v[34:37]
	v_mfma_f32_16x16x32_bf16 v[212:215], v[176:179], v[148:151], v[62:65]
	v_mfma_f32_16x16x32_bf16 v[216:219], v[176:179], v[168:171], v[58:61]
	v_mfma_f32_16x16x32_bf16 v[220:223], v[184:187], v[148:151], v[54:57]
	v_mfma_f32_16x16x32_bf16 v[224:227], v[184:187], v[168:171], v[50:53]
	v_mfma_f32_16x16x32_bf16 v[228:231], v[192:195], v[148:151], v[46:49]
	v_mfma_f32_16x16x32_bf16 v[144:147], v[200:203], v[168:171], v[34:37]
	s_setprio 0
	s_setprio 1
	v_mfma_f32_16x16x32_bf16 v[30:33], v[74:77], v[156:159], v[30:33]
	v_mfma_f32_16x16x32_bf16 v[26:29], v[74:77], v[208:211], v[26:29]
	v_mfma_f32_16x16x32_bf16 v[18:21], v[180:183], v[208:211], v[18:21]
	v_mfma_f32_16x16x32_bf16 v[14:17], v[188:191], v[156:159], v[14:17]
	v_mfma_f32_16x16x32_bf16 v[10:13], v[188:191], v[208:211], v[10:13]
	v_mfma_f32_16x16x32_bf16 v[6:9], v[196:199], v[156:159], v[6:9]
	v_mfma_f32_16x16x32_bf16 v[2:5], v[196:199], v[208:211], v[2:5]
	v_mfma_f32_16x16x32_bf16 v[30:33], v[176:179], v[204:207], v[30:33]
	v_mfma_f32_16x16x32_bf16 v[26:29], v[176:179], v[152:155], v[26:29]
	v_mfma_f32_16x16x32_bf16 v[22:25], v[180:183], v[156:159], v[22:25]
	v_mfma_f32_16x16x32_bf16 v[18:21], v[184:187], v[152:155], v[18:21]
	v_mfma_f32_16x16x32_bf16 v[14:17], v[192:195], v[204:207], v[14:17]
	v_mfma_f32_16x16x32_bf16 v[10:13], v[192:195], v[152:155], v[10:13]
	v_mfma_f32_16x16x32_bf16 v[6:9], v[200:203], v[204:207], v[6:9]
	v_mfma_f32_16x16x32_bf16 v[2:5], v[200:203], v[152:155], v[2:5]
	v_mfma_f32_16x16x32_bf16 v[148:151], v[184:187], v[204:207], v[22:25]
	s_setprio 0
	s_barrier
	ds_read_b128 v[152:155], v142
	ds_read_b128 v[156:159], v142 offset:1024
	ds_read_b128 v[164:167], v142 offset:2048
	ds_read_b128 v[168:171], v142 offset:3072
	ds_read_b128 v[58:61], v138 offset:32768
	ds_read_b128 v[62:65], v138 offset:33792
	ds_read_b128 v[74:77], v137 offset:32768
	ds_read_b128 v[176:179], v137 offset:33792
	ds_read_b128 v[180:183], v133 offset:32768
	ds_read_b128 v[184:187], v133 offset:33792
	ds_read_b128 v[188:191], v132 offset:32768
	ds_read_b128 v[192:195], v132 offset:33792
	s_waitcnt vmcnt(2)
	s_barrier
	s_waitcnt lgkmcnt(0)
	s_setprio 1
	s_waitcnt lgkmcnt(7)
	v_mfma_f32_16x16x32_bf16 v[22:25], v[58:61], v[152:155], v[126:129]
	s_waitcnt lgkmcnt(5)
	v_mfma_f32_16x16x32_bf16 v[34:37], v[74:77], v[152:155], v[118:121]
	s_waitcnt lgkmcnt(3)
	v_mfma_f32_16x16x32_bf16 v[46:49], v[180:183], v[152:155], v[110:113]
	s_waitcnt lgkmcnt(1)
	v_mfma_f32_16x16x32_bf16 v[50:53], v[188:191], v[152:155], v[102:105]
	v_mfma_f32_16x16x32_bf16 v[126:129], v[62:65], v[156:159], v[22:25]
	v_mfma_f32_16x16x32_bf16 v[22:25], v[58:61], v[164:167], v[122:125]
	v_mfma_f32_16x16x32_bf16 v[122:125], v[176:179], v[156:159], v[34:37]
	v_mfma_f32_16x16x32_bf16 v[34:37], v[74:77], v[164:167], v[114:117]
	v_mfma_f32_16x16x32_bf16 v[118:121], v[184:187], v[156:159], v[46:49]
	v_mfma_f32_16x16x32_bf16 v[46:49], v[180:183], v[164:167], v[106:109]
	s_waitcnt lgkmcnt(0)
	v_mfma_f32_16x16x32_bf16 v[114:117], v[192:195], v[156:159], v[50:53]
	v_mfma_f32_16x16x32_bf16 v[50:53], v[188:191], v[164:167], v[98:101]
	v_mfma_f32_16x16x32_bf16 v[22:25], v[62:65], v[168:171], v[22:25]
	v_mfma_f32_16x16x32_bf16 v[34:37], v[176:179], v[168:171], v[34:37]
	v_mfma_f32_16x16x32_bf16 v[46:49], v[184:187], v[168:171], v[46:49]
	v_mfma_f32_16x16x32_bf16 v[54:57], v[192:195], v[168:171], v[50:53]
	s_setprio 0
	s_barrier
; #define LDA_(dst, b, h) _Pragma("unroll") for (int m = 0; m < 4; ++m) _Pragma("unroll") for (int k = 0; k < 2; ++k) \
;     dst[m][k] = *reinterpret_cast<const bf16x8*>((char*)SA(b, h) + lds_byte(wr * 64 + m * 16 + fr, k * 32 + fq * 8))
; #define LDB_(dst, b, h) _Pragma("unroll") for (int n = 0; n < 2; ++n) _Pragma("unroll") for (int k = 0; k < 2; ++k) \
;     dst[n][k] = *reinterpret_cast<const bf16x8*>((char*)SB(b, h) + lds_byte(wc * 32 + n * 16 + fr, k * 32 + fq * 8))
; #define MMA(ai, bj, At, Bx) do { __builtin_amdgcn_s_setprio(1); \
;     _Pragma("unroll") for (int m = 0; m < 4; ++m) _Pragma("unroll") for (int n = 0; n < 2; ++n) _Pragma("unroll") for (int k = 0; k < 2; ++k) \
;       acc[ai][bj][m][n] = __builtin_amdgcn_mfma_f32_16x16x32_bf16(At[m][k], Bx[n][k], acc[ai][bj][m][n], 0, 0, 0); \
;     __builtin_amdgcn_s_setprio(0); } while (0)
; #define WAIT_V(n) asm volatile("s_waitcnt vmcnt(" #n ")" ::: "memory")
; #define WAIT_L(n) asm volatile("s_waitcnt lgkmcnt(" #n ")" ::: "memory")
; #define BAR __builtin_amdgcn_s_barrier()
; template <int K, int LDA, int LDB>
; DEVI void gemm_tile(const bf16* __restrict__ A, const bf16* __restrict__ Bt, bf16* shm, acc_t& acc) {
;     ...
;     LDB_(B1, 1, 1); WAIT_V(0); BAR; WAIT_L(0); MMA(0, 1, At, B1); BAR;
;     LDA_(At, 1, 1); BAR; WAIT_L(0); MMA(1, 0, At, B0); MMA(1, 1, At, B1); BAR; }
;   if (wr == 0) BAR;
	ds_read_b128 v[196:199], v140
	ds_read_b128 v[200:203], v140 offset:1024
	ds_read_b128 v[204:207], v140 offset:2048
	ds_read_b128 v[140:143], v140 offset:3072
	s_waitcnt vmcnt(0)
	s_barrier
	s_waitcnt lgkmcnt(0)
	s_setprio 1
	s_waitcnt lgkmcnt(3)
	v_mfma_f32_16x16x32_bf16 v[50:53], v[58:61], v[196:199], v[94:97]
	s_waitcnt lgkmcnt(1)
	v_mfma_f32_16x16x32_bf16 v[58:61], v[58:61], v[204:207], v[90:93]
	v_mfma_f32_16x16x32_bf16 v[50:53], v[62:65], v[200:203], v[50:53]
	s_waitcnt lgkmcnt(0)
	v_mfma_f32_16x16x32_bf16 v[58:61], v[62:65], v[140:143], v[58:61]
	v_mfma_f32_16x16x32_bf16 v[62:65], v[74:77], v[196:199], v[86:89]
	v_mfma_f32_16x16x32_bf16 v[74:77], v[74:77], v[204:207], v[82:85]
	v_mfma_f32_16x16x32_bf16 v[78:81], v[180:183], v[196:199], v[78:81]
	v_mfma_f32_16x16x32_bf16 v[82:85], v[180:183], v[204:207], v[172:175]
	v_mfma_f32_16x16x32_bf16 v[70:73], v[188:191], v[196:199], v[70:73]
	v_mfma_f32_16x16x32_bf16 v[66:69], v[188:191], v[204:207], v[66:69]
	v_mfma_f32_16x16x32_bf16 v[62:65], v[176:179], v[200:203], v[62:65]
	v_mfma_f32_16x16x32_bf16 v[74:77], v[176:179], v[140:143], v[74:77]
	v_mfma_f32_16x16x32_bf16 v[78:81], v[184:187], v[200:203], v[78:81]
	v_mfma_f32_16x16x32_bf16 v[86:89], v[184:187], v[140:143], v[82:85]
	v_mfma_f32_16x16x32_bf16 v[94:97], v[192:195], v[200:203], v[70:73]
	v_mfma_f32_16x16x32_bf16 v[102:105], v[192:195], v[140:143], v[66:69]
	s_setprio 0
	s_barrier
	ds_read_b128 v[172:175], v138 offset:49152
	ds_read_b128 v[176:179], v138 offset:50176
	ds_read_b128 v[180:183], v137 offset:49152
	ds_read_b128 v[184:187], v137 offset:50176
	ds_read_b128 v[188:191], v133 offset:49152
	ds_read_b128 v[192:195], v133 offset:50176
	ds_read_b128 v[208:211], v132 offset:49152
	ds_read_b128 v[232:235], v132 offset:50176
	s_barrier
	s_waitcnt lgkmcnt(0)
	s_setprio 1
	s_waitcnt lgkmcnt(7)
	v_mfma_f32_16x16x32_bf16 v[66:69], v[172:175], v[152:155], v[212:215]
	s_waitcnt lgkmcnt(6)
	v_mfma_f32_16x16x32_bf16 v[110:113], v[176:179], v[156:159], v[66:69]
	v_mfma_f32_16x16x32_bf16 v[66:69], v[172:175], v[164:167], v[216:219]
	v_mfma_f32_16x16x32_bf16 v[106:109], v[176:179], v[168:171], v[66:69]
	s_waitcnt lgkmcnt(5)
	v_mfma_f32_16x16x32_bf16 v[66:69], v[180:183], v[152:155], v[220:223]
	s_waitcnt lgkmcnt(4)
	v_mfma_f32_16x16x32_bf16 v[98:101], v[184:187], v[156:159], v[66:69]
	v_mfma_f32_16x16x32_bf16 v[66:69], v[180:183], v[164:167], v[224:227]
	v_mfma_f32_16x16x32_bf16 v[90:93], v[184:187], v[168:171], v[66:69]
	s_waitcnt lgkmcnt(3)
	v_mfma_f32_16x16x32_bf16 v[66:69], v[188:191], v[152:155], v[228:231]
	s_waitcnt lgkmcnt(1)
	v_mfma_f32_16x16x32_bf16 v[38:41], v[208:211], v[152:155], v[38:41]
	v_mfma_f32_16x16x32_bf16 v[82:85], v[192:195], v[156:159], v[66:69]
	v_mfma_f32_16x16x32_bf16 v[42:45], v[188:191], v[164:167], v[42:45]
	s_waitcnt lgkmcnt(0)
	v_mfma_f32_16x16x32_bf16 v[66:69], v[232:235], v[156:159], v[38:41]
	v_mfma_f32_16x16x32_bf16 v[38:41], v[208:211], v[164:167], v[144:147]
	v_mfma_f32_16x16x32_bf16 v[70:73], v[192:195], v[168:171], v[42:45]
	v_mfma_f32_16x16x32_bf16 v[42:45], v[232:235], v[168:171], v[38:41]
	s_setprio 0
	s_setprio 1
	v_mfma_f32_16x16x32_bf16 v[30:33], v[172:175], v[196:199], v[30:33]
	v_mfma_f32_16x16x32_bf16 v[26:29], v[172:175], v[204:207], v[26:29]
	v_mfma_f32_16x16x32_bf16 v[38:41], v[176:179], v[200:203], v[30:33]
	v_mfma_f32_16x16x32_bf16 v[30:33], v[176:179], v[140:143], v[26:29]
	v_mfma_f32_16x16x32_bf16 v[26:29], v[180:183], v[196:199], v[148:151]
	v_mfma_f32_16x16x32_bf16 v[18:21], v[180:183], v[204:207], v[18:21]
	v_mfma_f32_16x16x32_bf16 v[14:17], v[188:191], v[196:199], v[14:17]
	v_mfma_f32_16x16x32_bf16 v[10:13], v[188:191], v[204:207], v[10:13]
	v_mfma_f32_16x16x32_bf16 v[6:9], v[208:211], v[196:199], v[6:9]
	v_mfma_f32_16x16x32_bf16 v[2:5], v[208:211], v[204:207], v[2:5]
	v_mfma_f32_16x16x32_bf16 v[26:29], v[184:187], v[200:203], v[26:29]
	v_mfma_f32_16x16x32_bf16 v[18:21], v[184:187], v[140:143], v[18:21]
	v_mfma_f32_16x16x32_bf16 v[14:17], v[192:195], v[200:203], v[14:17]
	v_mfma_f32_16x16x32_bf16 v[10:13], v[192:195], v[140:143], v[10:13]
	v_mfma_f32_16x16x32_bf16 v[6:9], v[232:235], v[200:203], v[6:9]
	v_mfma_f32_16x16x32_bf16 v[2:5], v[232:235], v[140:143], v[2:5]
	s_setprio 0
	s_movk_i32 s0, 0x100
	v_cmp_gt_u32_e32 vcc, s0, v130
	s_barrier
	s_and_saveexec_b64 s[0:1], vcc
	s_cbranch_execz .LBB0_282
	s_barrier

; #define STAGE(P, BASE, LD, br, kt) do { const int _so = (int)(((br) * (LD) + (kt) * BK) * 2); \
;     _Pragma("unroll") for (int _i = 0; _i < 2; ++_i) { \
;       __builtin_amdgcn_raw_ptr_buffer_load_lds(rs##BASE, (__attribute__((address_space(3))) unsigned*)((char*)(P) + tid_ * 16 + _i * 8192), 16, (int)off##LD[_i], _so, 0, 0); } } while (0)
; #define LDA_(dst, b, h) _Pragma("unroll") for (int m = 0; m < 4; ++m) _Pragma("unroll") for (int k = 0; k < 2; ++k) \
;     dst[m][k] = *reinterpret_cast<const bf16x8*>((char*)SA(b, h) + lds_byte(wr * 64 + m * 16 + fr, k * 32 + fq * 8))
; #define LDB_(dst, b, h) _Pragma("unroll") for (int n = 0; n < 2; ++n) _Pragma("unroll") for (int k = 0; k < 2; ++k) \
;     dst[n][k] = *reinterpret_cast<const bf16x8*>((char*)SB(b, h) + lds_byte(wc * 32 + n * 16 + fr, k * 32 + fq * 8))
; #define MMA(ai, bj, At, Bx) do { __builtin_amdgcn_s_setprio(1); \
;     _Pragma("unroll") for (int m = 0; m < 4; ++m) _Pragma("unroll") for (int n = 0; n < 2; ++n) _Pragma("unroll") for (int k = 0; k < 2; ++k) \
;       acc[ai][bj][m][n] = __builtin_amdgcn_mfma_f32_16x16x32_bf16(At[m][k], Bx[n][k], acc[ai][bj][m][n], 0, 0, 0); \
;     __builtin_amdgcn_s_setprio(0); } while (0)
; #define WAIT_L(n) asm volatile("s_waitcnt lgkmcnt(" #n ")" ::: "memory")
; #define BAR __builtin_amdgcn_s_barrier()
; #define SCHED __builtin_amdgcn_sched_barrier(0)
; template <int K, int LDA, int LDB>
; DEVI void gemm_tile(const bf16* __restrict__ A, const bf16* __restrict__ Bt, bf16* shm, acc_t& acc) {
;     ...
;     LDB_(B0, 0, 0); SCHED; LDA_(At, 0, 0); STAGE(SA(1, 1), A, LDA, HALF, t + 1);
;     WAIT_L(8); BAR; WAIT_L(0); MMA(0, 0, At, B0); BAR; SCHED;
;     LDB_(B1, 0, 1); STAGE(SB(0, 0), Bt, LDB, 0, t + 2);
;     BAR; WAIT_L(0); MMA(0, 1, At, B1); BAR;
;     LDA_(At, 0, 1); STAGE(SA(0, 0), A, LDA, 0, t + 2);
;     BAR; WAIT_L(0); MMA(1, 0, At, B0); BAR; SCHED;
.LBB0_331:
	ds_read_b128 v[166:169], v164
	ds_read_b128 v[170:173], v164 offset:1024
	ds_read_b128 v[174:177], v164 offset:2048
	ds_read_b128 v[178:181], v164 offset:3072
	v_readfirstlane_b32 s41, v158
	s_add_i32 s40, s15, 0xffffff00
	s_mov_b32 m0, s41
	v_readfirstlane_b32 s41, v161
	ds_read_b128 v[182:185], v135
	ds_read_b128 v[186:189], v135 offset:1024
	ds_read_b128 v[190:193], v134
	ds_read_b128 v[194:197], v134 offset:1024
	ds_read_b128 v[198:201], v133
	ds_read_b128 v[202:205], v133 offset:1024
	ds_read_b128 v[206:209], v132
	ds_read_b128 v[210:213], v132 offset:1024
	buffer_load_dwordx4 v141, s[8:11], s40 offen lds
	s_mov_b32 m0, s41
	s_nop 0
	buffer_load_dwordx4 v143, s[8:11], s40 offen lds
	s_waitcnt lgkmcnt(8)
	s_barrier
	s_waitcnt lgkmcnt(0)
	s_setprio 1
	s_waitcnt lgkmcnt(7)
	v_mfma_f32_16x16x32_bf16 v[126:129], v[182:185], v[166:169], v[126:129]
	v_mfma_f32_16x16x32_bf16 v[122:125], v[182:185], v[174:177], v[122:125]
	s_waitcnt lgkmcnt(5)
	v_mfma_f32_16x16x32_bf16 v[118:121], v[190:193], v[166:169], v[118:121]
	v_mfma_f32_16x16x32_bf16 v[114:117], v[190:193], v[174:177], v[114:117]
	s_waitcnt lgkmcnt(3)
	v_mfma_f32_16x16x32_bf16 v[110:113], v[198:201], v[166:169], v[110:113]
	v_mfma_f32_16x16x32_bf16 v[106:109], v[198:201], v[174:177], v[106:109]
	s_waitcnt lgkmcnt(1)
	v_mfma_f32_16x16x32_bf16 v[102:105], v[206:209], v[166:169], v[102:105]
	v_mfma_f32_16x16x32_bf16 v[98:101], v[206:209], v[174:177], v[98:101]
	v_mfma_f32_16x16x32_bf16 v[126:129], v[186:189], v[170:173], v[126:129]
	v_mfma_f32_16x16x32_bf16 v[122:125], v[186:189], v[178:181], v[122:125]
	v_mfma_f32_16x16x32_bf16 v[118:121], v[194:197], v[170:173], v[118:121]
	v_mfma_f32_16x16x32_bf16 v[114:117], v[194:197], v[178:181], v[114:117]
	v_mfma_f32_16x16x32_bf16 v[110:113], v[202:205], v[170:173], v[110:113]
	v_mfma_f32_16x16x32_bf16 v[106:109], v[202:205], v[178:181], v[106:109]
	s_waitcnt lgkmcnt(0)
	v_mfma_f32_16x16x32_bf16 v[102:105], v[210:213], v[170:173], v[102:105]
	v_mfma_f32_16x16x32_bf16 v[98:101], v[210:213], v[178:181], v[98:101]
	s_setprio 0
	s_barrier
	v_readfirstlane_b32 s41, v145
	s_add_i32 s40, s15, 0xfff7ff80
	s_mov_b32 m0, s41
	v_readfirstlane_b32 s41, v146
	ds_read_b128 v[214:217], v156
	ds_read_b128 v[218:221], v156 offset:1024
	ds_read_b128 v[222:225], v156 offset:2048
	ds_read_b128 v[226:229], v156 offset:3072
	buffer_load_dwordx4 v141, s[4:7], s40 offen lds
	s_mov_b32 m0, s41
	s_nop 0
	buffer_load_dwordx4 v143, s[4:7], s40 offen lds
	s_barrier
	s_waitcnt lgkmcnt(0)
	s_setprio 1
	s_waitcnt lgkmcnt(3)
	v_mfma_f32_16x16x32_bf16 v[94:97], v[182:185], v[214:217], v[94:97]
	s_waitcnt lgkmcnt(1)
	v_mfma_f32_16x16x32_bf16 v[90:93], v[182:185], v[222:225], v[90:93]
	v_mfma_f32_16x16x32_bf16 v[86:89], v[190:193], v[214:217], v[86:89]
	v_mfma_f32_16x16x32_bf16 v[82:85], v[190:193], v[222:225], v[82:85]
	v_mfma_f32_16x16x32_bf16 v[78:81], v[198:201], v[214:217], v[78:81]
	v_mfma_f32_16x16x32_bf16 v[74:77], v[198:201], v[222:225], v[74:77]
	v_mfma_f32_16x16x32_bf16 v[70:73], v[206:209], v[214:217], v[70:73]
	v_mfma_f32_16x16x32_bf16 v[66:69], v[206:209], v[222:225], v[66:69]
	v_mfma_f32_16x16x32_bf16 v[94:97], v[186:189], v[218:221], v[94:97]
	s_waitcnt lgkmcnt(0)
	v_mfma_f32_16x16x32_bf16 v[90:93], v[186:189], v[226:229], v[90:93]
	v_mfma_f32_16x16x32_bf16 v[86:89], v[194:197], v[218:221], v[86:89]
	v_mfma_f32_16x16x32_bf16 v[82:85], v[194:197], v[226:229], v[82:85]
	v_mfma_f32_16x16x32_bf16 v[78:81], v[202:205], v[218:221], v[78:81]
	v_mfma_f32_16x16x32_bf16 v[74:77], v[202:205], v[226:229], v[74:77]
	v_mfma_f32_16x16x32_bf16 v[70:73], v[210:213], v[218:221], v[70:73]
	v_mfma_f32_16x16x32_bf16 v[66:69], v[210:213], v[226:229], v[66:69]
	s_setprio 0
	v_readfirstlane_b32 s41, v147
	s_mov_b32 m0, s41
	v_readfirstlane_b32 s41, v148
	s_barrier
	ds_read_b128 v[182:185], v135 offset:16384
	ds_read_b128 v[186:189], v135 offset:17408
	ds_read_b128 v[190:193], v134 offset:16384
	ds_read_b128 v[194:197], v134 offset:17408
	ds_read_b128 v[198:201], v133 offset:16384
	ds_read_b128 v[202:205], v133 offset:17408
	ds_read_b128 v[206:209], v132 offset:16384
	ds_read_b128 v[210:213], v132 offset:17408
	buffer_load_dwordx4 v141, s[8:11], s40 offen lds
	s_mov_b32 m0, s41
	s_nop 0
	buffer_load_dwordx4 v143, s[8:11], s40 offen lds
	s_barrier
	s_waitcnt lgkmcnt(0)
	s_setprio 1
	s_waitcnt lgkmcnt(7)
	v_mfma_f32_16x16x32_bf16 v[62:65], v[182:185], v[166:169], v[62:65]
	v_mfma_f32_16x16x32_bf16 v[58:61], v[182:185], v[174:177], v[58:61]
	s_waitcnt lgkmcnt(5)
	v_mfma_f32_16x16x32_bf16 v[54:57], v[190:193], v[166:169], v[54:57]
	v_mfma_f32_16x16x32_bf16 v[50:53], v[190:193], v[174:177], v[50:53]
	s_waitcnt lgkmcnt(3)
	v_mfma_f32_16x16x32_bf16 v[46:49], v[198:201], v[166:169], v[46:49]
	v_mfma_f32_16x16x32_bf16 v[42:45], v[198:201], v[174:177], v[42:45]
	s_waitcnt lgkmcnt(1)
	v_mfma_f32_16x16x32_bf16 v[38:41], v[206:209], v[166:169], v[38:41]
	v_mfma_f32_16x16x32_bf16 v[34:37], v[206:209], v[174:177], v[34:37]
	v_mfma_f32_16x16x32_bf16 v[62:65], v[186:189], v[170:173], v[62:65]
	v_mfma_f32_16x16x32_bf16 v[58:61], v[186:189], v[178:181], v[58:61]
	v_mfma_f32_16x16x32_bf16 v[54:57], v[194:197], v[170:173], v[54:57]
	v_mfma_f32_16x16x32_bf16 v[50:53], v[194:197], v[178:181], v[50:53]
	v_mfma_f32_16x16x32_bf16 v[46:49], v[202:205], v[170:173], v[46:49]
	v_mfma_f32_16x16x32_bf16 v[42:45], v[202:205], v[178:181], v[42:45]
	s_waitcnt lgkmcnt(0)
	v_mfma_f32_16x16x32_bf16 v[38:41], v[210:213], v[170:173], v[38:41]
	v_mfma_f32_16x16x32_bf16 v[34:37], v[210:213], v[178:181], v[34:37]
	s_setprio 0
	s_barrier
; #define STAGE(P, BASE, LD, br, kt) do { const int _so = (int)(((br) * (LD) + (kt) * BK) * 2); \
;     _Pragma("unroll") for (int _i = 0; _i < 2; ++_i) { \
;       __builtin_amdgcn_raw_ptr_buffer_load_lds(rs##BASE, (__attribute__((address_space(3))) unsigned*)((char*)(P) + tid_ * 16 + _i * 8192), 16, (int)off##LD[_i], _so, 0, 0); } } while (0)
; #define LDA_(dst, b, h) _Pragma("unroll") for (int m = 0; m < 4; ++m) _Pragma("unroll") for (int k = 0; k < 2; ++k) \
;     dst[m][k] = *reinterpret_cast<const bf16x8*>((char*)SA(b, h) + lds_byte(wr * 64 + m * 16 + fr, k * 32 + fq * 8))
; #define LDB_(dst, b, h) _Pragma("unroll") for (int n = 0; n < 2; ++n) _Pragma("unroll") for (int k = 0; k < 2; ++k) \
;     dst[n][k] = *reinterpret_cast<const bf16x8*>((char*)SB(b, h) + lds_byte(wc * 32 + n * 16 + fr, k * 32 + fq * 8))
; #define MMA(ai, bj, At, Bx) do { __builtin_amdgcn_s_setprio(1); \
;     _Pragma("unroll") for (int m = 0; m < 4; ++m) _Pragma("unroll") for (int n = 0; n < 2; ++n) _Pragma("unroll") for (int k = 0; k < 2; ++k) \
;       acc[ai][bj][m][n] = __builtin_amdgcn_mfma_f32_16x16x32_bf16(At[m][k], Bx[n][k], acc[ai][bj][m][n], 0, 0, 0); \
;     __builtin_amdgcn_s_setprio(0); } while (0)
; #define WAIT_V(n) asm volatile("s_waitcnt vmcnt(" #n ")" ::: "memory")
; #define WAIT_L(n) asm volatile("s_waitcnt lgkmcnt(" #n ")" ::: "memory")
; #define BAR __builtin_amdgcn_s_barrier()
; #define SCHED __builtin_amdgcn_sched_barrier(0)
; template <int K, int LDA, int LDB>
; DEVI void gemm_tile(const bf16* __restrict__ A, const bf16* __restrict__ Bt, bf16* shm, acc_t& acc) {
;     ...
;     STAGE(SB(0, 1), Bt, LDB, HALF, t + 2);
;     WAIT_V(6); BAR; MMA(1, 1, At, B1); BAR;
;     LDB_(B0, 1, 0); SCHED; LDA_(At, 1, 0); STAGE(SA(0, 1), A, LDA, HALF, t + 2);
;     WAIT_L(8); BAR; WAIT_L(0); MMA(0, 0, At, B0); BAR; SCHED;
;     LDB_(B1, 1, 1); STAGE(SB(1, 0), Bt, LDB, 0, t + 3);
;     BAR; WAIT_L(0); MMA(0, 1, At, B1); BAR;
;     LDA_(At, 1, 1); STAGE(SA(1, 0), A, LDA, 0, t + 3);
	v_readfirstlane_b32 s41, v149
	s_add_i32 s40, s15, 0xffffff80
	s_mov_b32 m0, s41
	v_readfirstlane_b32 s41, v150
	buffer_load_dwordx4 v141, s[4:7], s40 offen lds
	s_mov_b32 m0, s41
	s_nop 0
	buffer_load_dwordx4 v143, s[4:7], s40 offen lds
	s_waitcnt vmcnt(6)
	s_barrier
	s_setprio 1
	v_mfma_f32_16x16x32_bf16 v[30:33], v[182:185], v[214:217], v[30:33]
	v_mfma_f32_16x16x32_bf16 v[26:29], v[182:185], v[222:225], v[26:29]
	v_mfma_f32_16x16x32_bf16 v[22:25], v[190:193], v[214:217], v[22:25]
	v_mfma_f32_16x16x32_bf16 v[18:21], v[190:193], v[222:225], v[18:21]
	v_mfma_f32_16x16x32_bf16 v[14:17], v[198:201], v[214:217], v[14:17]
	v_mfma_f32_16x16x32_bf16 v[10:13], v[198:201], v[222:225], v[10:13]
	v_mfma_f32_16x16x32_bf16 v[6:9], v[206:209], v[214:217], v[6:9]
	v_mfma_f32_16x16x32_bf16 v[2:5], v[206:209], v[222:225], v[2:5]
	v_mfma_f32_16x16x32_bf16 v[30:33], v[186:189], v[218:221], v[30:33]
	v_mfma_f32_16x16x32_bf16 v[26:29], v[186:189], v[226:229], v[26:29]
	v_mfma_f32_16x16x32_bf16 v[22:25], v[194:197], v[218:221], v[22:25]
	v_mfma_f32_16x16x32_bf16 v[18:21], v[194:197], v[226:229], v[18:21]
	v_mfma_f32_16x16x32_bf16 v[14:17], v[202:205], v[218:221], v[14:17]
	v_mfma_f32_16x16x32_bf16 v[10:13], v[202:205], v[226:229], v[10:13]
	v_mfma_f32_16x16x32_bf16 v[6:9], v[210:213], v[218:221], v[6:9]
	v_mfma_f32_16x16x32_bf16 v[2:5], v[210:213], v[226:229], v[2:5]
	s_setprio 0
	s_barrier
	ds_read_b128 v[166:169], v144
	ds_read_b128 v[170:173], v144 offset:1024
	ds_read_b128 v[174:177], v144 offset:2048
	ds_read_b128 v[178:181], v144 offset:3072
	v_readfirstlane_b32 s41, v151
	s_mov_b32 m0, s41
	v_readfirstlane_b32 s41, v152
	ds_read_b128 v[182:185], v135 offset:32768
	ds_read_b128 v[186:189], v135 offset:33792
	ds_read_b128 v[190:193], v134 offset:32768
	ds_read_b128 v[194:197], v134 offset:33792
	ds_read_b128 v[198:201], v133 offset:32768
	ds_read_b128 v[202:205], v133 offset:33792
	ds_read_b128 v[206:209], v132 offset:32768
	ds_read_b128 v[210:213], v132 offset:33792
	buffer_load_dwordx4 v141, s[8:11], s40 offen lds
	s_mov_b32 m0, s41
	s_nop 0
	buffer_load_dwordx4 v143, s[8:11], s40 offen lds
	s_waitcnt lgkmcnt(8)
	s_barrier
	s_waitcnt lgkmcnt(0)
	s_setprio 1
	s_waitcnt lgkmcnt(7)
	v_mfma_f32_16x16x32_bf16 v[126:129], v[182:185], v[166:169], v[126:129]
	v_mfma_f32_16x16x32_bf16 v[122:125], v[182:185], v[174:177], v[122:125]
	s_waitcnt lgkmcnt(5)
	v_mfma_f32_16x16x32_bf16 v[118:121], v[190:193], v[166:169], v[118:121]
	v_mfma_f32_16x16x32_bf16 v[114:117], v[190:193], v[174:177], v[114:117]
	s_waitcnt lgkmcnt(3)
	v_mfma_f32_16x16x32_bf16 v[110:113], v[198:201], v[166:169], v[110:113]
	v_mfma_f32_16x16x32_bf16 v[106:109], v[198:201], v[174:177], v[106:109]
	s_waitcnt lgkmcnt(1)
	v_mfma_f32_16x16x32_bf16 v[102:105], v[206:209], v[166:169], v[102:105]
	v_mfma_f32_16x16x32_bf16 v[98:101], v[206:209], v[174:177], v[98:101]
	v_mfma_f32_16x16x32_bf16 v[126:129], v[186:189], v[170:173], v[126:129]
	v_mfma_f32_16x16x32_bf16 v[122:125], v[186:189], v[178:181], v[122:125]
	v_mfma_f32_16x16x32_bf16 v[118:121], v[194:197], v[170:173], v[118:121]
	v_mfma_f32_16x16x32_bf16 v[114:117], v[194:197], v[178:181], v[114:117]
	v_mfma_f32_16x16x32_bf16 v[110:113], v[202:205], v[170:173], v[110:113]
	v_mfma_f32_16x16x32_bf16 v[106:109], v[202:205], v[178:181], v[106:109]
	s_waitcnt lgkmcnt(0)
	v_mfma_f32_16x16x32_bf16 v[102:105], v[210:213], v[170:173], v[102:105]
	v_mfma_f32_16x16x32_bf16 v[98:101], v[210:213], v[178:181], v[98:101]
	s_setprio 0
	s_barrier
	v_readfirstlane_b32 s41, v153
	s_add_i32 s40, s15, 0xfff80000
	s_mov_b32 m0, s41
	v_readfirstlane_b32 s41, v154
	ds_read_b128 v[214:217], v142
	ds_read_b128 v[218:221], v142 offset:1024
	ds_read_b128 v[222:225], v142 offset:2048
	ds_read_b128 v[226:229], v142 offset:3072
	buffer_load_dwordx4 v141, s[4:7], s40 offen lds
	s_mov_b32 m0, s41
	s_nop 0
	buffer_load_dwordx4 v143, s[4:7], s40 offen lds
	s_barrier
	s_waitcnt lgkmcnt(0)
	s_setprio 1
	s_waitcnt lgkmcnt(3)
	v_mfma_f32_16x16x32_bf16 v[94:97], v[182:185], v[214:217], v[94:97]
	s_waitcnt lgkmcnt(1)
	v_mfma_f32_16x16x32_bf16 v[90:93], v[182:185], v[222:225], v[90:93]
	v_mfma_f32_16x16x32_bf16 v[86:89], v[190:193], v[214:217], v[86:89]
	v_mfma_f32_16x16x32_bf16 v[82:85], v[190:193], v[222:225], v[82:85]
	v_mfma_f32_16x16x32_bf16 v[78:81], v[198:201], v[214:217], v[78:81]
	v_mfma_f32_16x16x32_bf16 v[74:77], v[198:201], v[222:225], v[74:77]
	v_mfma_f32_16x16x32_bf16 v[70:73], v[206:209], v[214:217], v[70:73]
	v_mfma_f32_16x16x32_bf16 v[66:69], v[206:209], v[222:225], v[66:69]
	v_mfma_f32_16x16x32_bf16 v[94:97], v[186:189], v[218:221], v[94:97]
	s_waitcnt lgkmcnt(0)
	v_mfma_f32_16x16x32_bf16 v[90:93], v[186:189], v[226:229], v[90:93]
	v_mfma_f32_16x16x32_bf16 v[86:89], v[194:197], v[218:221], v[86:89]
	v_mfma_f32_16x16x32_bf16 v[82:85], v[194:197], v[226:229], v[82:85]
	v_mfma_f32_16x16x32_bf16 v[78:81], v[202:205], v[218:221], v[78:81]
	v_mfma_f32_16x16x32_bf16 v[74:77], v[202:205], v[226:229], v[74:77]
	v_mfma_f32_16x16x32_bf16 v[70:73], v[210:213], v[218:221], v[70:73]
	v_mfma_f32_16x16x32_bf16 v[66:69], v[210:213], v[226:229], v[66:69]
	s_setprio 0
	v_readfirstlane_b32 s41, v155
	s_mov_b32 m0, s41
	v_readfirstlane_b32 s41, v157
	s_barrier
	ds_read_b128 v[182:185], v135 offset:49152
	ds_read_b128 v[186:189], v135 offset:50176
	ds_read_b128 v[190:193], v134 offset:49152
	ds_read_b128 v[194:197], v134 offset:50176
	ds_read_b128 v[198:201], v133 offset:49152
	ds_read_b128 v[202:205], v133 offset:50176
	ds_read_b128 v[206:209], v132 offset:49152
	ds_read_b128 v[210:213], v132 offset:50176
	buffer_load_dwordx4 v141, s[8:11], s40 offen lds
	s_mov_b32 m0, s41
	s_nop 0
	buffer_load_dwordx4 v143, s[8:11], s40 offen lds
	s_barrier
; #define STAGE(P, BASE, LD, br, kt) do { const int _so = (int)(((br) * (LD) + (kt) * BK) * 2); \
;     _Pragma("unroll") for (int _i = 0; _i < 2; ++_i) { \
;       __builtin_amdgcn_raw_ptr_buffer_load_lds(rs##BASE, (__attribute__((address_space(3))) unsigned*)((char*)(P) + tid_ * 16 + _i * 8192), 16, (int)off##LD[_i], _so, 0, 0); } } while (0)
; #define LDA_(dst, b, h) _Pragma("unroll") for (int m = 0; m < 4; ++m) _Pragma("unroll") for (int k = 0; k < 2; ++k) \
;     dst[m][k] = *reinterpret_cast<const bf16x8*>((char*)SA(b, h) + lds_byte(wr * 64 + m * 16 + fr, k * 32 + fq * 8))
; #define LDB_(dst, b, h) _Pragma("unroll") for (int n = 0; n < 2; ++n) _Pragma("unroll") for (int k = 0; k < 2; ++k) \
;     dst[n][k] = *reinterpret_cast<const bf16x8*>((char*)SB(b, h) + lds_byte(wc * 32 + n * 16 + fr, k * 32 + fq * 8))
; #define MMA(ai, bj, At, Bx) do { __builtin_amdgcn_s_setprio(1); \
;     _Pragma("unroll") for (int m = 0; m < 4; ++m) _Pragma("unroll") for (int n = 0; n < 2; ++n) _Pragma("unroll") for (int k = 0; k < 2; ++k) \
;       acc[ai][bj][m][n] = __builtin_amdgcn_mfma_f32_16x16x32_bf16(At[m][k], Bx[n][k], acc[ai][bj][m][n], 0, 0, 0); \
;     __builtin_amdgcn_s_setprio(0); } while (0)
; #define WAIT_V(n) asm volatile("s_waitcnt vmcnt(" #n ")" ::: "memory")
; #define WAIT_L(n) asm volatile("s_waitcnt lgkmcnt(" #n ")" ::: "memory")
; #define BAR __builtin_amdgcn_s_barrier()
; #define SCHED __builtin_amdgcn_sched_barrier(0)
; template <int K, int LDA, int LDB>
; DEVI void gemm_tile(const bf16* __restrict__ A, const bf16* __restrict__ Bt, bf16* shm, acc_t& acc) {
;     ...
;     BAR; WAIT_L(0); MMA(1, 0, At, B0); BAR; SCHED;
;     STAGE(SB(1, 1), Bt, LDB, HALF, t + 3);
;     WAIT_V(6); BAR; MMA(1, 1, At, B1); BAR;
;   }
;   { LDB_(B0, 0, 0); LDA_(At, 0, 0); STAGE(SA(1, 1), A, LDA, HALF, nt - 1);
;     BAR; WAIT_L(0); MMA(0, 0, At, B0); BAR;
;     LDB_(B1, 0, 1); BAR; WAIT_L(0); MMA(0, 1, At, B1); BAR;
	s_waitcnt lgkmcnt(0)
	s_setprio 1
	s_waitcnt lgkmcnt(7)
	v_mfma_f32_16x16x32_bf16 v[62:65], v[182:185], v[166:169], v[62:65]
	v_mfma_f32_16x16x32_bf16 v[58:61], v[182:185], v[174:177], v[58:61]
	s_waitcnt lgkmcnt(5)
	v_mfma_f32_16x16x32_bf16 v[54:57], v[190:193], v[166:169], v[54:57]
	v_mfma_f32_16x16x32_bf16 v[50:53], v[190:193], v[174:177], v[50:53]
	s_waitcnt lgkmcnt(3)
	v_mfma_f32_16x16x32_bf16 v[46:49], v[198:201], v[166:169], v[46:49]
	v_mfma_f32_16x16x32_bf16 v[42:45], v[198:201], v[174:177], v[42:45]
	s_waitcnt lgkmcnt(1)
	v_mfma_f32_16x16x32_bf16 v[38:41], v[206:209], v[166:169], v[38:41]
	v_mfma_f32_16x16x32_bf16 v[34:37], v[206:209], v[174:177], v[34:37]
	v_mfma_f32_16x16x32_bf16 v[62:65], v[186:189], v[170:173], v[62:65]
	v_mfma_f32_16x16x32_bf16 v[58:61], v[186:189], v[178:181], v[58:61]
	v_mfma_f32_16x16x32_bf16 v[54:57], v[194:197], v[170:173], v[54:57]
	v_mfma_f32_16x16x32_bf16 v[50:53], v[194:197], v[178:181], v[50:53]
	v_mfma_f32_16x16x32_bf16 v[46:49], v[202:205], v[170:173], v[46:49]
	v_mfma_f32_16x16x32_bf16 v[42:45], v[202:205], v[178:181], v[42:45]
	s_waitcnt lgkmcnt(0)
	v_mfma_f32_16x16x32_bf16 v[38:41], v[210:213], v[170:173], v[38:41]
	v_mfma_f32_16x16x32_bf16 v[34:37], v[210:213], v[178:181], v[34:37]
	s_setprio 0
	s_barrier
	v_readfirstlane_b32 s40, v159
	s_mov_b32 m0, s40
	v_readfirstlane_b32 s40, v160
	buffer_load_dwordx4 v141, s[4:7], s15 offen lds
	s_mov_b32 m0, s40
	s_nop 0
	buffer_load_dwordx4 v143, s[4:7], s15 offen lds
	s_waitcnt vmcnt(6)
	s_barrier
	s_setprio 1
	v_mfma_f32_16x16x32_bf16 v[30:33], v[182:185], v[214:217], v[30:33]
	v_mfma_f32_16x16x32_bf16 v[26:29], v[182:185], v[222:225], v[26:29]
	v_mfma_f32_16x16x32_bf16 v[22:25], v[190:193], v[214:217], v[22:25]
	v_mfma_f32_16x16x32_bf16 v[18:21], v[190:193], v[222:225], v[18:21]
	v_mfma_f32_16x16x32_bf16 v[14:17], v[198:201], v[214:217], v[14:17]
	v_mfma_f32_16x16x32_bf16 v[10:13], v[198:201], v[222:225], v[10:13]
	v_mfma_f32_16x16x32_bf16 v[6:9], v[206:209], v[214:217], v[6:9]
	v_mfma_f32_16x16x32_bf16 v[2:5], v[206:209], v[222:225], v[2:5]
	v_mfma_f32_16x16x32_bf16 v[30:33], v[186:189], v[218:221], v[30:33]
	v_mfma_f32_16x16x32_bf16 v[26:29], v[186:189], v[226:229], v[26:29]
	v_mfma_f32_16x16x32_bf16 v[22:25], v[194:197], v[218:221], v[22:25]
	v_mfma_f32_16x16x32_bf16 v[18:21], v[194:197], v[226:229], v[18:21]
	v_mfma_f32_16x16x32_bf16 v[14:17], v[202:205], v[218:221], v[14:17]
	v_mfma_f32_16x16x32_bf16 v[10:13], v[202:205], v[226:229], v[10:13]
	v_mfma_f32_16x16x32_bf16 v[6:9], v[210:213], v[218:221], v[6:9]
	v_mfma_f32_16x16x32_bf16 v[2:5], v[210:213], v[226:229], v[2:5]
	s_setprio 0
	s_add_i32 s13, s13, 2
	s_addk_i32 s15, 0x100
	s_cmp_lt_u32 s13, 28
	s_cbranch_scc1 .Lrot_8658
	s_barrier
	v_readfirstlane_b32 s4, v158
	s_mov_b32 s10, s6
	s_mov_b32 s11, s7
	s_mov_b32 m0, s4
	v_readfirstlane_b32 s4, v161
	ds_read_b128 v[146:149], v164
	ds_read_b128 v[150:153], v164 offset:1024
	ds_read_b128 v[166:169], v164 offset:2048
	ds_read_b128 v[170:173], v164 offset:3072
	ds_read_b128 v[174:177], v135
	ds_read_b128 v[178:181], v135 offset:1024
	ds_read_b128 v[182:185], v134
	ds_read_b128 v[186:189], v134 offset:1024
	ds_read_b128 v[190:193], v133
	ds_read_b128 v[194:197], v133 offset:1024
	ds_read_b128 v[198:201], v132
	ds_read_b128 v[202:205], v132 offset:1024
	buffer_load_dwordx4 v141, s[8:11], s38 offen lds
	s_mov_b32 m0, s4
	s_nop 0
	buffer_load_dwordx4 v143, s[8:11], s38 offen lds
	s_barrier
	s_waitcnt lgkmcnt(0)
	s_setprio 1
	s_waitcnt lgkmcnt(7)
	v_mfma_f32_16x16x32_bf16 v[126:129], v[174:177], v[146:149], v[126:129]
	s_waitcnt lgkmcnt(5)
	v_mfma_f32_16x16x32_bf16 v[118:121], v[182:185], v[146:149], v[118:121]
	s_waitcnt lgkmcnt(3)
	v_mfma_f32_16x16x32_bf16 v[110:113], v[190:193], v[146:149], v[110:113]
	s_waitcnt lgkmcnt(1)
	v_mfma_f32_16x16x32_bf16 v[102:105], v[198:201], v[146:149], v[102:105]
	v_mfma_f32_16x16x32_bf16 v[126:129], v[178:181], v[150:153], v[126:129]
	v_mfma_f32_16x16x32_bf16 v[122:125], v[174:177], v[166:169], v[122:125]
	v_mfma_f32_16x16x32_bf16 v[118:121], v[186:189], v[150:153], v[118:121]
	v_mfma_f32_16x16x32_bf16 v[114:117], v[182:185], v[166:169], v[114:117]
	v_mfma_f32_16x16x32_bf16 v[110:113], v[194:197], v[150:153], v[110:113]
	v_mfma_f32_16x16x32_bf16 v[106:109], v[190:193], v[166:169], v[106:109]
	s_waitcnt lgkmcnt(0)
	v_mfma_f32_16x16x32_bf16 v[102:105], v[202:205], v[150:153], v[102:105]
	v_mfma_f32_16x16x32_bf16 v[98:101], v[198:201], v[166:169], v[98:101]
	v_mfma_f32_16x16x32_bf16 v[158:161], v[178:181], v[170:173], v[122:125]
	v_mfma_f32_16x16x32_bf16 v[206:209], v[186:189], v[170:173], v[114:117]
	v_mfma_f32_16x16x32_bf16 v[210:213], v[194:197], v[170:173], v[106:109]
	v_mfma_f32_16x16x32_bf16 v[214:217], v[202:205], v[170:173], v[98:101]
	s_setprio 0
	s_barrier
	s_nop 1
	ds_read_b128 v[98:101], v156
	ds_read_b128 v[106:109], v156 offset:1024
	ds_read_b128 v[114:117], v156 offset:2048
	ds_read_b128 v[122:125], v156 offset:3072
	s_barrier
	s_waitcnt lgkmcnt(0)
	s_setprio 1
	s_waitcnt lgkmcnt(3)
	v_mfma_f32_16x16x32_bf16 v[94:97], v[174:177], v[98:101], v[94:97]
	v_mfma_f32_16x16x32_bf16 v[86:89], v[182:185], v[98:101], v[86:89]
	v_mfma_f32_16x16x32_bf16 v[78:81], v[190:193], v[98:101], v[78:81]
	v_mfma_f32_16x16x32_bf16 v[70:73], v[198:201], v[98:101], v[70:73]
	s_waitcnt lgkmcnt(2)
	v_mfma_f32_16x16x32_bf16 v[94:97], v[178:181], v[106:109], v[94:97]
	s_waitcnt lgkmcnt(1)
	v_mfma_f32_16x16x32_bf16 v[90:93], v[174:177], v[114:117], v[90:93]
	v_mfma_f32_16x16x32_bf16 v[86:89], v[186:189], v[106:109], v[86:89]
	v_mfma_f32_16x16x32_bf16 v[82:85], v[182:185], v[114:117], v[82:85]
	v_mfma_f32_16x16x32_bf16 v[78:81], v[194:197], v[106:109], v[78:81]
	v_mfma_f32_16x16x32_bf16 v[74:77], v[190:193], v[114:117], v[74:77]
	v_mfma_f32_16x16x32_bf16 v[70:73], v[202:205], v[106:109], v[70:73]
	v_mfma_f32_16x16x32_bf16 v[66:69], v[198:201], v[114:117], v[66:69]
	s_waitcnt lgkmcnt(0)
	v_mfma_f32_16x16x32_bf16 v[154:157], v[178:181], v[122:125], v[90:93]
	v_mfma_f32_16x16x32_bf16 v[174:177], v[186:189], v[122:125], v[82:85]
	v_mfma_f32_16x16x32_bf16 v[178:181], v[194:197], v[122:125], v[74:77]
	v_mfma_f32_16x16x32_bf16 v[182:185], v[202:205], v[122:125], v[66:69]
	s_setprio 0
	s_barrier
; #define LDA_(dst, b, h) _Pragma("unroll") for (int m = 0; m < 4; ++m) _Pragma("unroll") for (int k = 0; k < 2; ++k) \
;     dst[m][k] = *reinterpret_cast<const bf16x8*>((char*)SA(b, h) + lds_byte(wr * 64 + m * 16 + fr, k * 32 + fq * 8))
; #define LDB_(dst, b, h) _Pragma("unroll") for (int n = 0; n < 2; ++n) _Pragma("unroll") for (int k = 0; k < 2; ++k) \
;     dst[n][k] = *reinterpret_cast<const bf16x8*>((char*)SB(b, h) + lds_byte(wc * 32 + n * 16 + fr, k * 32 + fq * 8))
; #define MMA(ai, bj, At, Bx) do { __builtin_amdgcn_s_setprio(1); \
;     _Pragma("unroll") for (int m = 0; m < 4; ++m) _Pragma("unroll") for (int n = 0; n < 2; ++n) _Pragma("unroll") for (int k = 0; k < 2; ++k) \
;       acc[ai][bj][m][n] = __builtin_amdgcn_mfma_f32_16x16x32_bf16(At[m][k], Bx[n][k], acc[ai][bj][m][n], 0, 0, 0); \
;     __builtin_amdgcn_s_setprio(0); } while (0)
; #define WAIT_V(n) asm volatile("s_waitcnt vmcnt(" #n ")" ::: "memory")
; #define WAIT_L(n) asm volatile("s_waitcnt lgkmcnt(" #n ")" ::: "memory")
; #define BAR __builtin_amdgcn_s_barrier()
; template <int K, int LDA, int LDB>
; DEVI void gemm_tile(const bf16* __restrict__ A, const bf16* __restrict__ Bt, bf16* shm, acc_t& acc) {
;     ...
;     LDA_(At, 0, 1); WAIT_V(4); BAR; WAIT_L(0); MMA(1, 0, At, B0); MMA(1, 1, At, B1); BAR; }
;   { LDB_(B0, 1, 0); LDA_(At, 1, 0); WAIT_V(2); BAR; WAIT_L(0); MMA(0, 0, At, B0); BAR;
	s_nop 0
	ds_read_b128 v[66:69], v135 offset:16384
	ds_read_b128 v[74:77], v135 offset:17408
	ds_read_b128 v[82:85], v134 offset:16384
	ds_read_b128 v[90:93], v134 offset:17408
	ds_read_b128 v[186:189], v133 offset:16384
	ds_read_b128 v[190:193], v133 offset:17408
	ds_read_b128 v[194:197], v132 offset:16384
	ds_read_b128 v[198:201], v132 offset:17408
	s_waitcnt vmcnt(4)
	s_barrier
	s_waitcnt lgkmcnt(0)
	s_setprio 1
	s_waitcnt lgkmcnt(7)
	v_mfma_f32_16x16x32_bf16 v[62:65], v[66:69], v[146:149], v[62:65]
	s_waitcnt lgkmcnt(5)
	v_mfma_f32_16x16x32_bf16 v[54:57], v[82:85], v[146:149], v[54:57]
	s_waitcnt lgkmcnt(3)
	v_mfma_f32_16x16x32_bf16 v[46:49], v[186:189], v[146:149], v[46:49]
	s_waitcnt lgkmcnt(1)
	v_mfma_f32_16x16x32_bf16 v[38:41], v[194:197], v[146:149], v[38:41]
	v_mfma_f32_16x16x32_bf16 v[62:65], v[74:77], v[150:153], v[62:65]
	v_mfma_f32_16x16x32_bf16 v[58:61], v[66:69], v[166:169], v[58:61]
	v_mfma_f32_16x16x32_bf16 v[54:57], v[90:93], v[150:153], v[54:57]
	v_mfma_f32_16x16x32_bf16 v[50:53], v[82:85], v[166:169], v[50:53]
	v_mfma_f32_16x16x32_bf16 v[46:49], v[190:193], v[150:153], v[46:49]
	v_mfma_f32_16x16x32_bf16 v[42:45], v[186:189], v[166:169], v[42:45]
	s_waitcnt lgkmcnt(0)
	v_mfma_f32_16x16x32_bf16 v[38:41], v[198:201], v[150:153], v[38:41]
	v_mfma_f32_16x16x32_bf16 v[34:37], v[194:197], v[166:169], v[34:37]
	v_mfma_f32_16x16x32_bf16 v[202:205], v[74:77], v[170:173], v[58:61]
	v_mfma_f32_16x16x32_bf16 v[218:221], v[90:93], v[170:173], v[50:53]
	v_mfma_f32_16x16x32_bf16 v[222:225], v[190:193], v[170:173], v[42:45]
	v_mfma_f32_16x16x32_bf16 v[146:149], v[198:201], v[170:173], v[34:37]
	s_setprio 0
	s_setprio 1
	v_mfma_f32_16x16x32_bf16 v[30:33], v[66:69], v[98:101], v[30:33]
	v_mfma_f32_16x16x32_bf16 v[22:25], v[82:85], v[98:101], v[22:25]
	v_mfma_f32_16x16x32_bf16 v[14:17], v[186:189], v[98:101], v[14:17]
	v_mfma_f32_16x16x32_bf16 v[6:9], v[194:197], v[98:101], v[6:9]
	v_mfma_f32_16x16x32_bf16 v[30:33], v[74:77], v[106:109], v[30:33]
	v_mfma_f32_16x16x32_bf16 v[26:29], v[66:69], v[114:117], v[26:29]
	v_mfma_f32_16x16x32_bf16 v[22:25], v[90:93], v[106:109], v[22:25]
	v_mfma_f32_16x16x32_bf16 v[18:21], v[82:85], v[114:117], v[18:21]
	v_mfma_f32_16x16x32_bf16 v[14:17], v[190:193], v[106:109], v[14:17]
	v_mfma_f32_16x16x32_bf16 v[10:13], v[186:189], v[114:117], v[10:13]
	v_mfma_f32_16x16x32_bf16 v[6:9], v[198:201], v[106:109], v[6:9]
	v_mfma_f32_16x16x32_bf16 v[2:5], v[194:197], v[114:117], v[2:5]
	v_mfma_f32_16x16x32_bf16 v[150:153], v[74:77], v[122:125], v[26:29]
	v_mfma_f32_16x16x32_bf16 v[164:167], v[90:93], v[122:125], v[18:21]
	v_mfma_f32_16x16x32_bf16 v[168:171], v[190:193], v[122:125], v[10:13]
	v_mfma_f32_16x16x32_bf16 v[186:189], v[198:201], v[122:125], v[2:5]
	s_setprio 0
	s_barrier
	ds_read_b128 v[190:193], v144
	ds_read_b128 v[194:197], v144 offset:1024
	ds_read_b128 v[198:201], v144 offset:2048
	ds_read_b128 v[226:229], v144 offset:3072
	ds_read_b128 v[2:5], v135 offset:32768
	ds_read_b128 v[10:13], v135 offset:33792
	ds_read_b128 v[18:21], v134 offset:32768
	ds_read_b128 v[26:29], v134 offset:33792
	ds_read_b128 v[230:233], v133 offset:32768
	ds_read_b128 v[234:237], v133 offset:33792
	ds_read_b128 v[238:241], v132 offset:32768
	ds_read_b128 v[242:245], v132 offset:33792
	s_waitcnt vmcnt(2)
	s_barrier
	s_waitcnt lgkmcnt(0)
	s_setprio 1
	s_waitcnt lgkmcnt(7)
	v_mfma_f32_16x16x32_bf16 v[34:37], v[2:5], v[190:193], v[126:129]
	s_waitcnt lgkmcnt(6)
	v_mfma_f32_16x16x32_bf16 v[122:125], v[10:13], v[194:197], v[34:37]
	v_mfma_f32_16x16x32_bf16 v[34:37], v[2:5], v[198:201], v[158:161]
	v_mfma_f32_16x16x32_bf16 v[114:117], v[10:13], v[226:229], v[34:37]
	s_waitcnt lgkmcnt(5)
	v_mfma_f32_16x16x32_bf16 v[34:37], v[18:21], v[190:193], v[118:121]
	s_waitcnt lgkmcnt(4)
	v_mfma_f32_16x16x32_bf16 v[106:109], v[26:29], v[194:197], v[34:37]
	v_mfma_f32_16x16x32_bf16 v[34:37], v[18:21], v[198:201], v[206:209]
	v_mfma_f32_16x16x32_bf16 v[98:101], v[26:29], v[226:229], v[34:37]
	s_waitcnt lgkmcnt(3)
	v_mfma_f32_16x16x32_bf16 v[34:37], v[230:233], v[190:193], v[110:113]
	s_waitcnt lgkmcnt(2)
	v_mfma_f32_16x16x32_bf16 v[90:93], v[234:237], v[194:197], v[34:37]
	v_mfma_f32_16x16x32_bf16 v[34:37], v[230:233], v[198:201], v[210:213]
	v_mfma_f32_16x16x32_bf16 v[82:85], v[234:237], v[226:229], v[34:37]
	s_waitcnt lgkmcnt(1)
	v_mfma_f32_16x16x32_bf16 v[34:37], v[238:241], v[190:193], v[102:105]
	s_waitcnt lgkmcnt(0)
	v_mfma_f32_16x16x32_bf16 v[74:77], v[242:245], v[194:197], v[34:37]
	v_mfma_f32_16x16x32_bf16 v[34:37], v[238:241], v[198:201], v[214:217]
	v_mfma_f32_16x16x32_bf16 v[66:69], v[242:245], v[226:229], v[34:37]
	s_setprio 0
	s_barrier
; #define LDA_(dst, b, h) _Pragma("unroll") for (int m = 0; m < 4; ++m) _Pragma("unroll") for (int k = 0; k < 2; ++k) \
;     dst[m][k] = *reinterpret_cast<const bf16x8*>((char*)SA(b, h) + lds_byte(wr * 64 + m * 16 + fr, k * 32 + fq * 8))
; #define LDB_(dst, b, h) _Pragma("unroll") for (int n = 0; n < 2; ++n) _Pragma("unroll") for (int k = 0; k < 2; ++k) \
;     dst[n][k] = *reinterpret_cast<const bf16x8*>((char*)SB(b, h) + lds_byte(wc * 32 + n * 16 + fr, k * 32 + fq * 8))
; #define MMA(ai, bj, At, Bx) do { __builtin_amdgcn_s_setprio(1); \
;     _Pragma("unroll") for (int m = 0; m < 4; ++m) _Pragma("unroll") for (int n = 0; n < 2; ++n) _Pragma("unroll") for (int k = 0; k < 2; ++k) \
;       acc[ai][bj][m][n] = __builtin_amdgcn_mfma_f32_16x16x32_bf16(At[m][k], Bx[n][k], acc[ai][bj][m][n], 0, 0, 0); \
;     __builtin_amdgcn_s_setprio(0); } while (0)
; #define WAIT_V(n) asm volatile("s_waitcnt vmcnt(" #n ")" ::: "memory")
; #define WAIT_L(n) asm volatile("s_waitcnt lgkmcnt(" #n ")" ::: "memory")
; #define BAR __builtin_amdgcn_s_barrier()
; template <int K, int LDA, int LDB>
; DEVI void gemm_tile(const bf16* __restrict__ A, const bf16* __restrict__ Bt, bf16* shm, acc_t& acc) {
;     ...
;     LDB_(B1, 1, 1); WAIT_V(0); BAR; WAIT_L(0); MMA(0, 1, At, B1); BAR;
;     LDA_(At, 1, 1); BAR; WAIT_L(0); MMA(1, 0, At, B0); MMA(1, 1, At, B1); BAR; }
;   if (wr == 0) BAR;
	ds_read_b128 v[158:161], v142
	ds_read_b128 v[206:209], v142 offset:1024
	ds_read_b128 v[210:213], v142 offset:2048
	ds_read_b128 v[142:145], v142 offset:3072
	s_waitcnt vmcnt(0)
	s_barrier
	s_waitcnt lgkmcnt(0)
	s_setprio 1
	s_waitcnt lgkmcnt(3)
	v_mfma_f32_16x16x32_bf16 v[34:37], v[2:5], v[158:161], v[94:97]
	s_waitcnt lgkmcnt(1)
	v_mfma_f32_16x16x32_bf16 v[2:5], v[2:5], v[210:213], v[154:157]
	s_waitcnt lgkmcnt(0)
	v_mfma_f32_16x16x32_bf16 v[50:53], v[10:13], v[142:145], v[2:5]
	v_mfma_f32_16x16x32_bf16 v[2:5], v[18:21], v[158:161], v[86:89]
	v_mfma_f32_16x16x32_bf16 v[42:45], v[26:29], v[206:209], v[2:5]
	v_mfma_f32_16x16x32_bf16 v[2:5], v[18:21], v[210:213], v[174:177]
	v_mfma_f32_16x16x32_bf16 v[58:61], v[10:13], v[206:209], v[34:37]
	v_mfma_f32_16x16x32_bf16 v[34:37], v[26:29], v[142:145], v[2:5]
	v_mfma_f32_16x16x32_bf16 v[2:5], v[230:233], v[158:161], v[78:81]
	v_mfma_f32_16x16x32_bf16 v[26:29], v[234:237], v[206:209], v[2:5]
	v_mfma_f32_16x16x32_bf16 v[2:5], v[230:233], v[210:213], v[178:181]
	v_mfma_f32_16x16x32_bf16 v[18:21], v[234:237], v[142:145], v[2:5]
	v_mfma_f32_16x16x32_bf16 v[2:5], v[238:241], v[158:161], v[70:73]
	v_mfma_f32_16x16x32_bf16 v[10:13], v[242:245], v[206:209], v[2:5]
	v_mfma_f32_16x16x32_bf16 v[2:5], v[238:241], v[210:213], v[182:185]
	v_mfma_f32_16x16x32_bf16 v[2:5], v[242:245], v[142:145], v[2:5]
	s_setprio 0
	s_barrier
	ds_read_b128 v[154:157], v135 offset:49152
	ds_read_b128 v[172:175], v135 offset:50176
	ds_read_b128 v[176:179], v134 offset:49152
	ds_read_b128 v[180:183], v134 offset:50176
	ds_read_b128 v[214:217], v133 offset:49152
	ds_read_b128 v[230:233], v133 offset:50176
	ds_read_b128 v[234:237], v132 offset:49152
	ds_read_b128 v[132:135], v132 offset:50176
	s_barrier
	s_waitcnt lgkmcnt(0)
	s_setprio 1
	s_waitcnt lgkmcnt(7)
	v_mfma_f32_16x16x32_bf16 v[62:65], v[154:157], v[190:193], v[62:65]
	s_waitcnt lgkmcnt(5)
	v_mfma_f32_16x16x32_bf16 v[54:57], v[176:179], v[190:193], v[54:57]
	s_waitcnt lgkmcnt(3)
	v_mfma_f32_16x16x32_bf16 v[46:49], v[214:217], v[190:193], v[46:49]
	s_waitcnt lgkmcnt(1)
	v_mfma_f32_16x16x32_bf16 v[38:41], v[234:237], v[190:193], v[38:41]
	v_mfma_f32_16x16x32_bf16 v[126:129], v[172:175], v[194:197], v[62:65]
	v_mfma_f32_16x16x32_bf16 v[62:65], v[154:157], v[198:201], v[202:205]
	v_mfma_f32_16x16x32_bf16 v[110:113], v[180:183], v[194:197], v[54:57]
	v_mfma_f32_16x16x32_bf16 v[54:57], v[176:179], v[198:201], v[218:221]
	v_mfma_f32_16x16x32_bf16 v[94:97], v[230:233], v[194:197], v[46:49]
	v_mfma_f32_16x16x32_bf16 v[46:49], v[214:217], v[198:201], v[222:225]
	s_waitcnt lgkmcnt(0)
	v_mfma_f32_16x16x32_bf16 v[78:81], v[132:135], v[194:197], v[38:41]
	v_mfma_f32_16x16x32_bf16 v[38:41], v[234:237], v[198:201], v[146:149]
	v_mfma_f32_16x16x32_bf16 v[118:121], v[172:175], v[226:229], v[62:65]
	v_mfma_f32_16x16x32_bf16 v[102:105], v[180:183], v[226:229], v[54:57]
	v_mfma_f32_16x16x32_bf16 v[86:89], v[230:233], v[226:229], v[46:49]
	v_mfma_f32_16x16x32_bf16 v[70:73], v[132:135], v[226:229], v[38:41]
	s_setprio 0
	s_setprio 1
	v_mfma_f32_16x16x32_bf16 v[30:33], v[154:157], v[158:161], v[30:33]
	v_mfma_f32_16x16x32_bf16 v[62:65], v[172:175], v[206:209], v[30:33]
	v_mfma_f32_16x16x32_bf16 v[30:33], v[154:157], v[210:213], v[150:153]
	v_mfma_f32_16x16x32_bf16 v[22:25], v[176:179], v[158:161], v[22:25]
	v_mfma_f32_16x16x32_bf16 v[14:17], v[214:217], v[158:161], v[14:17]
	v_mfma_f32_16x16x32_bf16 v[54:57], v[172:175], v[142:145], v[30:33]
	v_mfma_f32_16x16x32_bf16 v[46:49], v[180:183], v[206:209], v[22:25]
	v_mfma_f32_16x16x32_bf16 v[22:25], v[176:179], v[210:213], v[164:167]
	v_mfma_f32_16x16x32_bf16 v[30:33], v[230:233], v[206:209], v[14:17]
	v_mfma_f32_16x16x32_bf16 v[14:17], v[214:217], v[210:213], v[168:171]
	v_mfma_f32_16x16x32_bf16 v[6:9], v[234:237], v[158:161], v[6:9]
	v_mfma_f32_16x16x32_bf16 v[38:41], v[180:183], v[142:145], v[22:25]
	v_mfma_f32_16x16x32_bf16 v[22:25], v[230:233], v[142:145], v[14:17]
	v_mfma_f32_16x16x32_bf16 v[14:17], v[132:135], v[206:209], v[6:9]
	v_mfma_f32_16x16x32_bf16 v[6:9], v[234:237], v[210:213], v[186:189]
	v_mfma_f32_16x16x32_bf16 v[6:9], v[132:135], v[142:145], v[6:9]
	s_setprio 0
	v_cmp_gt_u32_e32 vcc, s18, v130
	s_barrier
	s_and_saveexec_b64 s[4:5], vcc
	s_cbranch_execz .LBB0_334
	s_barrier

; #define STAGE(P, BASE, LD, br, kt) do { const int _so = (int)(((br) * (LD) + (kt) * BK) * 2); \
;     _Pragma("unroll") for (int _i = 0; _i < 2; ++_i) { \
;       __builtin_amdgcn_raw_ptr_buffer_load_lds(rs##BASE, (__attribute__((address_space(3))) unsigned*)((char*)(P) + tid_ * 16 + _i * 8192), 16, (int)off##LD[_i], _so, 0, 0); } } while (0)
; #define LDA_(dst, b, h) _Pragma("unroll") for (int m = 0; m < 4; ++m) _Pragma("unroll") for (int k = 0; k < 2; ++k) \
;     dst[m][k] = *reinterpret_cast<const bf16x8*>((char*)SA(b, h) + lds_byte(wr * 64 + m * 16 + fr, k * 32 + fq * 8))
; #define LDB_(dst, b, h) _Pragma("unroll") for (int n = 0; n < 2; ++n) _Pragma("unroll") for (int k = 0; k < 2; ++k) \
;     dst[n][k] = *reinterpret_cast<const bf16x8*>((char*)SB(b, h) + lds_byte(wc * 32 + n * 16 + fr, k * 32 + fq * 8))
; #define MMA(ai, bj, At, Bx) do { __builtin_amdgcn_s_setprio(1); \
;     _Pragma("unroll") for (int m = 0; m < 4; ++m) _Pragma("unroll") for (int n = 0; n < 2; ++n) _Pragma("unroll") for (int k = 0; k < 2; ++k) \
;       acc[ai][bj][m][n] = __builtin_amdgcn_mfma_f32_16x16x32_bf16(At[m][k], Bx[n][k], acc[ai][bj][m][n], 0, 0, 0); \
;     __builtin_amdgcn_s_setprio(0); } while (0)
; #define WAIT_L(n) asm volatile("s_waitcnt lgkmcnt(" #n ")" ::: "memory")
; #define BAR __builtin_amdgcn_s_barrier()
; #define SCHED __builtin_amdgcn_sched_barrier(0)
; template <int K, int LDA, int LDB>
; DEVI void gemm_tile(const bf16* __restrict__ A, const bf16* __restrict__ Bt, bf16* shm, acc_t& acc) {
;     ...
;     LDB_(B0, 0, 0); SCHED; LDA_(At, 0, 0); STAGE(SA(1, 1), A, LDA, HALF, t + 1);
;     WAIT_L(8); BAR; WAIT_L(0); MMA(0, 0, At, B0); BAR; SCHED;
;     LDB_(B1, 0, 1); STAGE(SB(0, 0), Bt, LDB, 0, t + 2);
;     BAR; WAIT_L(0); MMA(0, 1, At, B1); BAR;
;     LDA_(At, 0, 1); STAGE(SA(0, 0), A, LDA, 0, t + 2);
;     BAR; WAIT_L(0); MMA(1, 0, At, B0); BAR; SCHED;
.LBB0_372:
	ds_read_b128 v[164:167], v160
	ds_read_b128 v[168:171], v160 offset:1024
	ds_read_b128 v[172:175], v160 offset:2048
	ds_read_b128 v[176:179], v160 offset:3072
	v_readfirstlane_b32 s39, v156
	s_add_i32 s38, s7, 0xffffff00
	s_mov_b32 m0, s39
	v_readfirstlane_b32 s39, v159
	ds_read_b128 v[180:183], v138
	ds_read_b128 v[184:187], v138 offset:1024
	ds_read_b128 v[188:191], v137
	ds_read_b128 v[192:195], v137 offset:1024
	ds_read_b128 v[196:199], v133
	ds_read_b128 v[200:203], v133 offset:1024
	ds_read_b128 v[204:207], v132
	ds_read_b128 v[208:211], v132 offset:1024
	buffer_load_dwordx4 v139, s[8:11], s38 offen lds
	s_mov_b32 m0, s39
	s_nop 0
	buffer_load_dwordx4 v141, s[8:11], s38 offen lds
	s_waitcnt lgkmcnt(8)
	s_barrier
	s_waitcnt lgkmcnt(0)
	s_setprio 1
	s_waitcnt lgkmcnt(7)
	v_mfma_f32_16x16x32_bf16 v[126:129], v[180:183], v[164:167], v[126:129]
	v_mfma_f32_16x16x32_bf16 v[122:125], v[180:183], v[172:175], v[122:125]
	s_waitcnt lgkmcnt(5)
	v_mfma_f32_16x16x32_bf16 v[118:121], v[188:191], v[164:167], v[118:121]
	v_mfma_f32_16x16x32_bf16 v[114:117], v[188:191], v[172:175], v[114:117]
	s_waitcnt lgkmcnt(3)
	v_mfma_f32_16x16x32_bf16 v[110:113], v[196:199], v[164:167], v[110:113]
	v_mfma_f32_16x16x32_bf16 v[106:109], v[196:199], v[172:175], v[106:109]
	s_waitcnt lgkmcnt(1)
	v_mfma_f32_16x16x32_bf16 v[102:105], v[204:207], v[164:167], v[102:105]
	v_mfma_f32_16x16x32_bf16 v[98:101], v[204:207], v[172:175], v[98:101]
	v_mfma_f32_16x16x32_bf16 v[126:129], v[184:187], v[168:171], v[126:129]
	v_mfma_f32_16x16x32_bf16 v[122:125], v[184:187], v[176:179], v[122:125]
	v_mfma_f32_16x16x32_bf16 v[118:121], v[192:195], v[168:171], v[118:121]
	v_mfma_f32_16x16x32_bf16 v[114:117], v[192:195], v[176:179], v[114:117]
	v_mfma_f32_16x16x32_bf16 v[110:113], v[200:203], v[168:171], v[110:113]
	v_mfma_f32_16x16x32_bf16 v[106:109], v[200:203], v[176:179], v[106:109]
	s_waitcnt lgkmcnt(0)
	v_mfma_f32_16x16x32_bf16 v[102:105], v[208:211], v[168:171], v[102:105]
	v_mfma_f32_16x16x32_bf16 v[98:101], v[208:211], v[176:179], v[98:101]
	s_setprio 0
	s_barrier
	v_readfirstlane_b32 s39, v143
	s_add_i32 s38, s7, 0xffe9ff80
	s_mov_b32 m0, s39
	v_readfirstlane_b32 s39, v144
	ds_read_b128 v[212:215], v154
	ds_read_b128 v[216:219], v154 offset:1024
	ds_read_b128 v[220:223], v154 offset:2048
	ds_read_b128 v[224:227], v154 offset:3072
	buffer_load_dwordx4 v139, s[0:3], s38 offen lds
	s_mov_b32 m0, s39
	s_nop 0
	buffer_load_dwordx4 v141, s[0:3], s38 offen lds
	s_barrier
	s_waitcnt lgkmcnt(0)
	s_setprio 1
	s_waitcnt lgkmcnt(3)
	v_mfma_f32_16x16x32_bf16 v[94:97], v[180:183], v[212:215], v[94:97]
	s_waitcnt lgkmcnt(1)
	v_mfma_f32_16x16x32_bf16 v[90:93], v[180:183], v[220:223], v[90:93]
	v_mfma_f32_16x16x32_bf16 v[86:89], v[188:191], v[212:215], v[86:89]
	v_mfma_f32_16x16x32_bf16 v[82:85], v[188:191], v[220:223], v[82:85]
	v_mfma_f32_16x16x32_bf16 v[78:81], v[196:199], v[212:215], v[78:81]
	v_mfma_f32_16x16x32_bf16 v[74:77], v[196:199], v[220:223], v[74:77]
	v_mfma_f32_16x16x32_bf16 v[70:73], v[204:207], v[212:215], v[70:73]
	v_mfma_f32_16x16x32_bf16 v[66:69], v[204:207], v[220:223], v[66:69]
	v_mfma_f32_16x16x32_bf16 v[94:97], v[184:187], v[216:219], v[94:97]
	s_waitcnt lgkmcnt(0)
	v_mfma_f32_16x16x32_bf16 v[90:93], v[184:187], v[224:227], v[90:93]
	v_mfma_f32_16x16x32_bf16 v[86:89], v[192:195], v[216:219], v[86:89]
	v_mfma_f32_16x16x32_bf16 v[82:85], v[192:195], v[224:227], v[82:85]
	v_mfma_f32_16x16x32_bf16 v[78:81], v[200:203], v[216:219], v[78:81]
	v_mfma_f32_16x16x32_bf16 v[74:77], v[200:203], v[224:227], v[74:77]
	v_mfma_f32_16x16x32_bf16 v[70:73], v[208:211], v[216:219], v[70:73]
	v_mfma_f32_16x16x32_bf16 v[66:69], v[208:211], v[224:227], v[66:69]
	s_setprio 0
	v_readfirstlane_b32 s39, v145
	s_mov_b32 m0, s39
	v_readfirstlane_b32 s39, v146
	s_barrier
	ds_read_b128 v[180:183], v138 offset:16384
	ds_read_b128 v[184:187], v138 offset:17408
	ds_read_b128 v[188:191], v137 offset:16384
	ds_read_b128 v[192:195], v137 offset:17408
	ds_read_b128 v[196:199], v133 offset:16384
	ds_read_b128 v[200:203], v133 offset:17408
	ds_read_b128 v[204:207], v132 offset:16384
	ds_read_b128 v[208:211], v132 offset:17408
	buffer_load_dwordx4 v139, s[8:11], s38 offen lds
	s_mov_b32 m0, s39
	s_nop 0
	buffer_load_dwordx4 v141, s[8:11], s38 offen lds
	s_barrier
	s_waitcnt lgkmcnt(0)
	s_setprio 1
	s_waitcnt lgkmcnt(7)
	v_mfma_f32_16x16x32_bf16 v[62:65], v[180:183], v[164:167], v[62:65]
	v_mfma_f32_16x16x32_bf16 v[58:61], v[180:183], v[172:175], v[58:61]
	s_waitcnt lgkmcnt(5)
	v_mfma_f32_16x16x32_bf16 v[54:57], v[188:191], v[164:167], v[54:57]
	v_mfma_f32_16x16x32_bf16 v[50:53], v[188:191], v[172:175], v[50:53]
	s_waitcnt lgkmcnt(3)
	v_mfma_f32_16x16x32_bf16 v[46:49], v[196:199], v[164:167], v[46:49]
	v_mfma_f32_16x16x32_bf16 v[42:45], v[196:199], v[172:175], v[42:45]
	s_waitcnt lgkmcnt(1)
	v_mfma_f32_16x16x32_bf16 v[38:41], v[204:207], v[164:167], v[38:41]
	v_mfma_f32_16x16x32_bf16 v[34:37], v[204:207], v[172:175], v[34:37]
	v_mfma_f32_16x16x32_bf16 v[62:65], v[184:187], v[168:171], v[62:65]
	v_mfma_f32_16x16x32_bf16 v[58:61], v[184:187], v[176:179], v[58:61]
	v_mfma_f32_16x16x32_bf16 v[54:57], v[192:195], v[168:171], v[54:57]
	v_mfma_f32_16x16x32_bf16 v[50:53], v[192:195], v[176:179], v[50:53]
	v_mfma_f32_16x16x32_bf16 v[46:49], v[200:203], v[168:171], v[46:49]
	v_mfma_f32_16x16x32_bf16 v[42:45], v[200:203], v[176:179], v[42:45]
	s_waitcnt lgkmcnt(0)
	v_mfma_f32_16x16x32_bf16 v[38:41], v[208:211], v[168:171], v[38:41]
	v_mfma_f32_16x16x32_bf16 v[34:37], v[208:211], v[176:179], v[34:37]
	s_setprio 0
	s_barrier
; #define STAGE(P, BASE, LD, br, kt) do { const int _so = (int)(((br) * (LD) + (kt) * BK) * 2); \
;     _Pragma("unroll") for (int _i = 0; _i < 2; ++_i) { \
;       __builtin_amdgcn_raw_ptr_buffer_load_lds(rs##BASE, (__attribute__((address_space(3))) unsigned*)((char*)(P) + tid_ * 16 + _i * 8192), 16, (int)off##LD[_i], _so, 0, 0); } } while (0)
; #define LDA_(dst, b, h) _Pragma("unroll") for (int m = 0; m < 4; ++m) _Pragma("unroll") for (int k = 0; k < 2; ++k) \
;     dst[m][k] = *reinterpret_cast<const bf16x8*>((char*)SA(b, h) + lds_byte(wr * 64 + m * 16 + fr, k * 32 + fq * 8))
; #define LDB_(dst, b, h) _Pragma("unroll") for (int n = 0; n < 2; ++n) _Pragma("unroll") for (int k = 0; k < 2; ++k) \
;     dst[n][k] = *reinterpret_cast<const bf16x8*>((char*)SB(b, h) + lds_byte(wc * 32 + n * 16 + fr, k * 32 + fq * 8))
; #define MMA(ai, bj, At, Bx) do { __builtin_amdgcn_s_setprio(1); \
;     _Pragma("unroll") for (int m = 0; m < 4; ++m) _Pragma("unroll") for (int n = 0; n < 2; ++n) _Pragma("unroll") for (int k = 0; k < 2; ++k) \
;       acc[ai][bj][m][n] = __builtin_amdgcn_mfma_f32_16x16x32_bf16(At[m][k], Bx[n][k], acc[ai][bj][m][n], 0, 0, 0); \
;     __builtin_amdgcn_s_setprio(0); } while (0)
; #define WAIT_V(n) asm volatile("s_waitcnt vmcnt(" #n ")" ::: "memory")
; #define WAIT_L(n) asm volatile("s_waitcnt lgkmcnt(" #n ")" ::: "memory")
; #define BAR __builtin_amdgcn_s_barrier()
; #define SCHED __builtin_amdgcn_sched_barrier(0)
; template <int K, int LDA, int LDB>
; DEVI void gemm_tile(const bf16* __restrict__ A, const bf16* __restrict__ Bt, bf16* shm, acc_t& acc) {
;     ...
;     STAGE(SB(0, 1), Bt, LDB, HALF, t + 2);
;     WAIT_V(6); BAR; MMA(1, 1, At, B1); BAR;
;     LDB_(B0, 1, 0); SCHED; LDA_(At, 1, 0); STAGE(SA(0, 1), A, LDA, HALF, t + 2);
;     WAIT_L(8); BAR; WAIT_L(0); MMA(0, 0, At, B0); BAR; SCHED;
;     LDB_(B1, 1, 1); STAGE(SB(1, 0), Bt, LDB, 0, t + 3);
;     BAR; WAIT_L(0); MMA(0, 1, At, B1); BAR;
;     LDA_(At, 1, 1); STAGE(SA(1, 0), A, LDA, 0, t + 3);
	v_readfirstlane_b32 s39, v147
	s_add_i32 s38, s7, 0xffffff80
	s_mov_b32 m0, s39
	v_readfirstlane_b32 s39, v148
	buffer_load_dwordx4 v139, s[0:3], s38 offen lds
	s_mov_b32 m0, s39
	s_nop 0
	buffer_load_dwordx4 v141, s[0:3], s38 offen lds
	s_waitcnt vmcnt(6)
	s_barrier
	s_setprio 1
	v_mfma_f32_16x16x32_bf16 v[30:33], v[180:183], v[212:215], v[30:33]
	v_mfma_f32_16x16x32_bf16 v[26:29], v[180:183], v[220:223], v[26:29]
	v_mfma_f32_16x16x32_bf16 v[22:25], v[188:191], v[212:215], v[22:25]
	v_mfma_f32_16x16x32_bf16 v[18:21], v[188:191], v[220:223], v[18:21]
	v_mfma_f32_16x16x32_bf16 v[14:17], v[196:199], v[212:215], v[14:17]
	v_mfma_f32_16x16x32_bf16 v[10:13], v[196:199], v[220:223], v[10:13]
	v_mfma_f32_16x16x32_bf16 v[6:9], v[204:207], v[212:215], v[6:9]
	v_mfma_f32_16x16x32_bf16 v[2:5], v[204:207], v[220:223], v[2:5]
	v_mfma_f32_16x16x32_bf16 v[30:33], v[184:187], v[216:219], v[30:33]
	v_mfma_f32_16x16x32_bf16 v[26:29], v[184:187], v[224:227], v[26:29]
	v_mfma_f32_16x16x32_bf16 v[22:25], v[192:195], v[216:219], v[22:25]
	v_mfma_f32_16x16x32_bf16 v[18:21], v[192:195], v[224:227], v[18:21]
	v_mfma_f32_16x16x32_bf16 v[14:17], v[200:203], v[216:219], v[14:17]
	v_mfma_f32_16x16x32_bf16 v[10:13], v[200:203], v[224:227], v[10:13]
	v_mfma_f32_16x16x32_bf16 v[6:9], v[208:211], v[216:219], v[6:9]
	v_mfma_f32_16x16x32_bf16 v[2:5], v[208:211], v[224:227], v[2:5]
	s_setprio 0
	s_barrier
	ds_read_b128 v[164:167], v142
	ds_read_b128 v[168:171], v142 offset:1024
	ds_read_b128 v[172:175], v142 offset:2048
	ds_read_b128 v[176:179], v142 offset:3072
	v_readfirstlane_b32 s39, v149
	s_mov_b32 m0, s39
	v_readfirstlane_b32 s39, v150
	ds_read_b128 v[180:183], v138 offset:32768
	ds_read_b128 v[184:187], v138 offset:33792
	ds_read_b128 v[188:191], v137 offset:32768
	ds_read_b128 v[192:195], v137 offset:33792
	ds_read_b128 v[196:199], v133 offset:32768
	ds_read_b128 v[200:203], v133 offset:33792
	ds_read_b128 v[204:207], v132 offset:32768
	ds_read_b128 v[208:211], v132 offset:33792
	buffer_load_dwordx4 v139, s[8:11], s38 offen lds
	s_mov_b32 m0, s39
	s_nop 0
	buffer_load_dwordx4 v141, s[8:11], s38 offen lds
	s_waitcnt lgkmcnt(8)
	s_barrier
	s_waitcnt lgkmcnt(0)
	s_setprio 1
	s_waitcnt lgkmcnt(7)
	v_mfma_f32_16x16x32_bf16 v[126:129], v[180:183], v[164:167], v[126:129]
	v_mfma_f32_16x16x32_bf16 v[122:125], v[180:183], v[172:175], v[122:125]
	s_waitcnt lgkmcnt(5)
	v_mfma_f32_16x16x32_bf16 v[118:121], v[188:191], v[164:167], v[118:121]
	v_mfma_f32_16x16x32_bf16 v[114:117], v[188:191], v[172:175], v[114:117]
	s_waitcnt lgkmcnt(3)
	v_mfma_f32_16x16x32_bf16 v[110:113], v[196:199], v[164:167], v[110:113]
	v_mfma_f32_16x16x32_bf16 v[106:109], v[196:199], v[172:175], v[106:109]
	s_waitcnt lgkmcnt(1)
	v_mfma_f32_16x16x32_bf16 v[102:105], v[204:207], v[164:167], v[102:105]
	v_mfma_f32_16x16x32_bf16 v[98:101], v[204:207], v[172:175], v[98:101]
	v_mfma_f32_16x16x32_bf16 v[126:129], v[184:187], v[168:171], v[126:129]
	v_mfma_f32_16x16x32_bf16 v[122:125], v[184:187], v[176:179], v[122:125]
	v_mfma_f32_16x16x32_bf16 v[118:121], v[192:195], v[168:171], v[118:121]
	v_mfma_f32_16x16x32_bf16 v[114:117], v[192:195], v[176:179], v[114:117]
	v_mfma_f32_16x16x32_bf16 v[110:113], v[200:203], v[168:171], v[110:113]
	v_mfma_f32_16x16x32_bf16 v[106:109], v[200:203], v[176:179], v[106:109]
	s_waitcnt lgkmcnt(0)
	v_mfma_f32_16x16x32_bf16 v[102:105], v[208:211], v[168:171], v[102:105]
	v_mfma_f32_16x16x32_bf16 v[98:101], v[208:211], v[176:179], v[98:101]
	s_setprio 0
	s_barrier
	v_readfirstlane_b32 s39, v151
	s_add_i32 s38, s7, 0xffea0000
	s_mov_b32 m0, s39
	v_readfirstlane_b32 s39, v152
	ds_read_b128 v[212:215], v140
	ds_read_b128 v[216:219], v140 offset:1024
	ds_read_b128 v[220:223], v140 offset:2048
	ds_read_b128 v[224:227], v140 offset:3072
	buffer_load_dwordx4 v139, s[0:3], s38 offen lds
	s_mov_b32 m0, s39
	s_nop 0
	buffer_load_dwordx4 v141, s[0:3], s38 offen lds
	s_barrier
	s_waitcnt lgkmcnt(0)
	s_setprio 1
	s_waitcnt lgkmcnt(3)
	v_mfma_f32_16x16x32_bf16 v[94:97], v[180:183], v[212:215], v[94:97]
	s_waitcnt lgkmcnt(1)
	v_mfma_f32_16x16x32_bf16 v[90:93], v[180:183], v[220:223], v[90:93]
	v_mfma_f32_16x16x32_bf16 v[86:89], v[188:191], v[212:215], v[86:89]
	v_mfma_f32_16x16x32_bf16 v[82:85], v[188:191], v[220:223], v[82:85]
	v_mfma_f32_16x16x32_bf16 v[78:81], v[196:199], v[212:215], v[78:81]
	v_mfma_f32_16x16x32_bf16 v[74:77], v[196:199], v[220:223], v[74:77]
	v_mfma_f32_16x16x32_bf16 v[70:73], v[204:207], v[212:215], v[70:73]
	v_mfma_f32_16x16x32_bf16 v[66:69], v[204:207], v[220:223], v[66:69]
	v_mfma_f32_16x16x32_bf16 v[94:97], v[184:187], v[216:219], v[94:97]
	s_waitcnt lgkmcnt(0)
	v_mfma_f32_16x16x32_bf16 v[90:93], v[184:187], v[224:227], v[90:93]
	v_mfma_f32_16x16x32_bf16 v[86:89], v[192:195], v[216:219], v[86:89]
	v_mfma_f32_16x16x32_bf16 v[82:85], v[192:195], v[224:227], v[82:85]
	v_mfma_f32_16x16x32_bf16 v[78:81], v[200:203], v[216:219], v[78:81]
	v_mfma_f32_16x16x32_bf16 v[74:77], v[200:203], v[224:227], v[74:77]
	v_mfma_f32_16x16x32_bf16 v[70:73], v[208:211], v[216:219], v[70:73]
	v_mfma_f32_16x16x32_bf16 v[66:69], v[208:211], v[224:227], v[66:69]
	s_setprio 0
	v_readfirstlane_b32 s39, v153
	s_mov_b32 m0, s39
	v_readfirstlane_b32 s39, v155
	s_barrier
	ds_read_b128 v[180:183], v138 offset:49152
	ds_read_b128 v[184:187], v138 offset:50176
	ds_read_b128 v[188:191], v137 offset:49152
	ds_read_b128 v[192:195], v137 offset:50176
	ds_read_b128 v[196:199], v133 offset:49152
	ds_read_b128 v[200:203], v133 offset:50176
	ds_read_b128 v[204:207], v132 offset:49152
	ds_read_b128 v[208:211], v132 offset:50176
	buffer_load_dwordx4 v139, s[8:11], s38 offen lds
	s_mov_b32 m0, s39
	s_nop 0
	buffer_load_dwordx4 v141, s[8:11], s38 offen lds
	s_barrier
; #define STAGE(P, BASE, LD, br, kt) do { const int _so = (int)(((br) * (LD) + (kt) * BK) * 2); \
;     _Pragma("unroll") for (int _i = 0; _i < 2; ++_i) { \
;       __builtin_amdgcn_raw_ptr_buffer_load_lds(rs##BASE, (__attribute__((address_space(3))) unsigned*)((char*)(P) + tid_ * 16 + _i * 8192), 16, (int)off##LD[_i], _so, 0, 0); } } while (0)
; #define LDA_(dst, b, h) _Pragma("unroll") for (int m = 0; m < 4; ++m) _Pragma("unroll") for (int k = 0; k < 2; ++k) \
;     dst[m][k] = *reinterpret_cast<const bf16x8*>((char*)SA(b, h) + lds_byte(wr * 64 + m * 16 + fr, k * 32 + fq * 8))
; #define LDB_(dst, b, h) _Pragma("unroll") for (int n = 0; n < 2; ++n) _Pragma("unroll") for (int k = 0; k < 2; ++k) \
;     dst[n][k] = *reinterpret_cast<const bf16x8*>((char*)SB(b, h) + lds_byte(wc * 32 + n * 16 + fr, k * 32 + fq * 8))
; #define MMA(ai, bj, At, Bx) do { __builtin_amdgcn_s_setprio(1); \
;     _Pragma("unroll") for (int m = 0; m < 4; ++m) _Pragma("unroll") for (int n = 0; n < 2; ++n) _Pragma("unroll") for (int k = 0; k < 2; ++k) \
;       acc[ai][bj][m][n] = __builtin_amdgcn_mfma_f32_16x16x32_bf16(At[m][k], Bx[n][k], acc[ai][bj][m][n], 0, 0, 0); \
;     __builtin_amdgcn_s_setprio(0); } while (0)
; #define WAIT_V(n) asm volatile("s_waitcnt vmcnt(" #n ")" ::: "memory")
; #define WAIT_L(n) asm volatile("s_waitcnt lgkmcnt(" #n ")" ::: "memory")
; #define BAR __builtin_amdgcn_s_barrier()
; #define SCHED __builtin_amdgcn_sched_barrier(0)
; template <int K, int LDA, int LDB>
; DEVI void gemm_tile(const bf16* __restrict__ A, const bf16* __restrict__ Bt, bf16* shm, acc_t& acc) {
;     ...
;     BAR; WAIT_L(0); MMA(1, 0, At, B0); BAR; SCHED;
;     STAGE(SB(1, 1), Bt, LDB, HALF, t + 3);
;     WAIT_V(6); BAR; MMA(1, 1, At, B1); BAR;
;   }
;   { LDB_(B0, 0, 0); LDA_(At, 0, 0); STAGE(SA(1, 1), A, LDA, HALF, nt - 1);
;     BAR; WAIT_L(0); MMA(0, 0, At, B0); BAR;
;     LDB_(B1, 0, 1); BAR; WAIT_L(0); MMA(0, 1, At, B1); BAR;
	s_waitcnt lgkmcnt(0)
	s_setprio 1
	s_waitcnt lgkmcnt(7)
	v_mfma_f32_16x16x32_bf16 v[62:65], v[180:183], v[164:167], v[62:65]
	v_mfma_f32_16x16x32_bf16 v[58:61], v[180:183], v[172:175], v[58:61]
	s_waitcnt lgkmcnt(5)
	v_mfma_f32_16x16x32_bf16 v[54:57], v[188:191], v[164:167], v[54:57]
	v_mfma_f32_16x16x32_bf16 v[50:53], v[188:191], v[172:175], v[50:53]
	s_waitcnt lgkmcnt(3)
	v_mfma_f32_16x16x32_bf16 v[46:49], v[196:199], v[164:167], v[46:49]
	v_mfma_f32_16x16x32_bf16 v[42:45], v[196:199], v[172:175], v[42:45]
	s_waitcnt lgkmcnt(1)
	v_mfma_f32_16x16x32_bf16 v[38:41], v[204:207], v[164:167], v[38:41]
	v_mfma_f32_16x16x32_bf16 v[34:37], v[204:207], v[172:175], v[34:37]
	v_mfma_f32_16x16x32_bf16 v[62:65], v[184:187], v[168:171], v[62:65]
	v_mfma_f32_16x16x32_bf16 v[58:61], v[184:187], v[176:179], v[58:61]
	v_mfma_f32_16x16x32_bf16 v[54:57], v[192:195], v[168:171], v[54:57]
	v_mfma_f32_16x16x32_bf16 v[50:53], v[192:195], v[176:179], v[50:53]
	v_mfma_f32_16x16x32_bf16 v[46:49], v[200:203], v[168:171], v[46:49]
	v_mfma_f32_16x16x32_bf16 v[42:45], v[200:203], v[176:179], v[42:45]
	s_waitcnt lgkmcnt(0)
	v_mfma_f32_16x16x32_bf16 v[38:41], v[208:211], v[168:171], v[38:41]
	v_mfma_f32_16x16x32_bf16 v[34:37], v[208:211], v[176:179], v[34:37]
	s_setprio 0
	s_barrier
	v_readfirstlane_b32 s38, v157
	s_mov_b32 m0, s38
	v_readfirstlane_b32 s38, v158
	buffer_load_dwordx4 v139, s[0:3], s7 offen lds
	s_mov_b32 m0, s38
	s_nop 0
	buffer_load_dwordx4 v141, s[0:3], s7 offen lds
	s_waitcnt vmcnt(6)
	s_barrier
	s_setprio 1
	v_mfma_f32_16x16x32_bf16 v[30:33], v[180:183], v[212:215], v[30:33]
	v_mfma_f32_16x16x32_bf16 v[26:29], v[180:183], v[220:223], v[26:29]
	v_mfma_f32_16x16x32_bf16 v[22:25], v[188:191], v[212:215], v[22:25]
	v_mfma_f32_16x16x32_bf16 v[18:21], v[188:191], v[220:223], v[18:21]
	v_mfma_f32_16x16x32_bf16 v[14:17], v[196:199], v[212:215], v[14:17]
	v_mfma_f32_16x16x32_bf16 v[10:13], v[196:199], v[220:223], v[10:13]
	v_mfma_f32_16x16x32_bf16 v[6:9], v[204:207], v[212:215], v[6:9]
	v_mfma_f32_16x16x32_bf16 v[2:5], v[204:207], v[220:223], v[2:5]
	v_mfma_f32_16x16x32_bf16 v[30:33], v[184:187], v[216:219], v[30:33]
	v_mfma_f32_16x16x32_bf16 v[26:29], v[184:187], v[224:227], v[26:29]
	v_mfma_f32_16x16x32_bf16 v[22:25], v[192:195], v[216:219], v[22:25]
	v_mfma_f32_16x16x32_bf16 v[18:21], v[192:195], v[224:227], v[18:21]
	v_mfma_f32_16x16x32_bf16 v[14:17], v[200:203], v[216:219], v[14:17]
	v_mfma_f32_16x16x32_bf16 v[10:13], v[200:203], v[224:227], v[10:13]
	v_mfma_f32_16x16x32_bf16 v[6:9], v[208:211], v[216:219], v[6:9]
	v_mfma_f32_16x16x32_bf16 v[2:5], v[208:211], v[224:227], v[2:5]
	s_setprio 0
	s_add_i32 s6, s6, 2
	s_addk_i32 s7, 0x100
	s_cmpk_lt_u32 s6, 0x54
	s_cbranch_scc1 .Lrot_9977
	s_barrier
	v_readfirstlane_b32 s0, v156
	s_mov_b32 s10, s2
	s_mov_b32 s11, s3
	s_mov_b32 m0, s0
	v_readfirstlane_b32 s0, v159
	ds_read_b128 v[144:147], v160
	ds_read_b128 v[148:151], v160 offset:1024
	ds_read_b128 v[164:167], v160 offset:2048
	ds_read_b128 v[168:171], v160 offset:3072
	ds_read_b128 v[172:175], v138
	ds_read_b128 v[176:179], v138 offset:1024
	ds_read_b128 v[180:183], v137
	ds_read_b128 v[184:187], v137 offset:1024
	ds_read_b128 v[188:191], v133
	ds_read_b128 v[192:195], v133 offset:1024
	ds_read_b128 v[196:199], v132
	ds_read_b128 v[200:203], v132 offset:1024
	buffer_load_dwordx4 v139, s[8:11], s34 offen lds
	s_mov_b32 m0, s0
	s_nop 0
	buffer_load_dwordx4 v141, s[8:11], s34 offen lds
	s_barrier
	s_waitcnt lgkmcnt(0)
	s_setprio 1
	s_waitcnt lgkmcnt(7)
	v_mfma_f32_16x16x32_bf16 v[126:129], v[172:175], v[144:147], v[126:129]
	v_mfma_f32_16x16x32_bf16 v[122:125], v[172:175], v[164:167], v[122:125]
	s_waitcnt lgkmcnt(5)
	v_mfma_f32_16x16x32_bf16 v[118:121], v[180:183], v[144:147], v[118:121]
	v_mfma_f32_16x16x32_bf16 v[114:117], v[180:183], v[164:167], v[114:117]
	s_waitcnt lgkmcnt(3)
	v_mfma_f32_16x16x32_bf16 v[110:113], v[188:191], v[144:147], v[110:113]
	v_mfma_f32_16x16x32_bf16 v[106:109], v[188:191], v[164:167], v[106:109]
	s_waitcnt lgkmcnt(1)
	v_mfma_f32_16x16x32_bf16 v[102:105], v[196:199], v[144:147], v[102:105]
	v_mfma_f32_16x16x32_bf16 v[98:101], v[196:199], v[164:167], v[98:101]
	v_mfma_f32_16x16x32_bf16 v[126:129], v[176:179], v[148:151], v[126:129]
	v_mfma_f32_16x16x32_bf16 v[122:125], v[176:179], v[168:171], v[122:125]
	v_mfma_f32_16x16x32_bf16 v[118:121], v[184:187], v[148:151], v[118:121]
	v_mfma_f32_16x16x32_bf16 v[114:117], v[184:187], v[168:171], v[114:117]
	v_mfma_f32_16x16x32_bf16 v[110:113], v[192:195], v[148:151], v[110:113]
	v_mfma_f32_16x16x32_bf16 v[106:109], v[192:195], v[168:171], v[106:109]
	s_waitcnt lgkmcnt(0)
	v_mfma_f32_16x16x32_bf16 v[102:105], v[200:203], v[148:151], v[102:105]
	v_mfma_f32_16x16x32_bf16 v[98:101], v[200:203], v[168:171], v[98:101]
	s_setprio 0
	s_barrier
	ds_read_b128 v[156:159], v154
	ds_read_b128 v[204:207], v154 offset:1024
	ds_read_b128 v[208:211], v154 offset:2048
	ds_read_b128 v[152:155], v154 offset:3072
	s_barrier
	s_waitcnt lgkmcnt(0)
	s_setprio 1
	s_waitcnt lgkmcnt(3)
	v_mfma_f32_16x16x32_bf16 v[94:97], v[172:175], v[156:159], v[94:97]
	s_waitcnt lgkmcnt(1)
	v_mfma_f32_16x16x32_bf16 v[90:93], v[172:175], v[208:211], v[90:93]
	v_mfma_f32_16x16x32_bf16 v[86:89], v[180:183], v[156:159], v[86:89]
	v_mfma_f32_16x16x32_bf16 v[82:85], v[180:183], v[208:211], v[82:85]
	v_mfma_f32_16x16x32_bf16 v[78:81], v[188:191], v[156:159], v[78:81]
	v_mfma_f32_16x16x32_bf16 v[74:77], v[188:191], v[208:211], v[74:77]
	v_mfma_f32_16x16x32_bf16 v[70:73], v[196:199], v[156:159], v[70:73]
	v_mfma_f32_16x16x32_bf16 v[94:97], v[176:179], v[204:207], v[94:97]
	s_waitcnt lgkmcnt(0)
	v_mfma_f32_16x16x32_bf16 v[90:93], v[176:179], v[152:155], v[90:93]
	v_mfma_f32_16x16x32_bf16 v[86:89], v[184:187], v[204:207], v[86:89]
	v_mfma_f32_16x16x32_bf16 v[82:85], v[184:187], v[152:155], v[82:85]
	v_mfma_f32_16x16x32_bf16 v[78:81], v[192:195], v[204:207], v[78:81]
	v_mfma_f32_16x16x32_bf16 v[74:77], v[192:195], v[152:155], v[74:77]
	v_mfma_f32_16x16x32_bf16 v[70:73], v[200:203], v[204:207], v[70:73]
	v_mfma_f32_16x16x32_bf16 v[66:69], v[196:199], v[208:211], v[66:69]
	v_mfma_f32_16x16x32_bf16 v[172:175], v[200:203], v[152:155], v[66:69]
	s_setprio 0
	s_barrier
; #define LDA_(dst, b, h) _Pragma("unroll") for (int m = 0; m < 4; ++m) _Pragma("unroll") for (int k = 0; k < 2; ++k) \
;     dst[m][k] = *reinterpret_cast<const bf16x8*>((char*)SA(b, h) + lds_byte(wr * 64 + m * 16 + fr, k * 32 + fq * 8))
; #define LDB_(dst, b, h) _Pragma("unroll") for (int n = 0; n < 2; ++n) _Pragma("unroll") for (int k = 0; k < 2; ++k) \
;     dst[n][k] = *reinterpret_cast<const bf16x8*>((char*)SB(b, h) + lds_byte(wc * 32 + n * 16 + fr, k * 32 + fq * 8))
; #define MMA(ai, bj, At, Bx) do { __builtin_amdgcn_s_setprio(1); \
;     _Pragma("unroll") for (int m = 0; m < 4; ++m) _Pragma("unroll") for (int n = 0; n < 2; ++n) _Pragma("unroll") for (int k = 0; k < 2; ++k) \
;       acc[ai][bj][m][n] = __builtin_amdgcn_mfma_f32_16x16x32_bf16(At[m][k], Bx[n][k], acc[ai][bj][m][n], 0, 0, 0); \
;     __builtin_amdgcn_s_setprio(0); } while (0)
; #define WAIT_V(n) asm volatile("s_waitcnt vmcnt(" #n ")" ::: "memory")
; #define WAIT_L(n) asm volatile("s_waitcnt lgkmcnt(" #n ")" ::: "memory")
; #define BAR __builtin_amdgcn_s_barrier()
; template <int K, int LDA, int LDB>
; DEVI void gemm_tile(const bf16* __restrict__ A, const bf16* __restrict__ Bt, bf16* shm, acc_t& acc) {
;     ...
;     LDA_(At, 0, 1); WAIT_V(4); BAR; WAIT_L(0); MMA(1, 0, At, B0); MMA(1, 1, At, B1); BAR; }
;   { LDB_(B0, 1, 0); LDA_(At, 1, 0); WAIT_V(2); BAR; WAIT_L(0); MMA(0, 0, At, B0); BAR;
	s_nop 4
	ds_read_b128 v[66:69], v138 offset:16384
	ds_read_b128 v[176:179], v138 offset:17408
	ds_read_b128 v[180:183], v137 offset:16384
	ds_read_b128 v[184:187], v137 offset:17408
	ds_read_b128 v[188:191], v133 offset:16384
	ds_read_b128 v[192:195], v133 offset:17408
	ds_read_b128 v[196:199], v132 offset:16384
	ds_read_b128 v[200:203], v132 offset:17408
	s_waitcnt vmcnt(4)
	s_barrier
	s_waitcnt lgkmcnt(0)
	s_setprio 1
	s_waitcnt lgkmcnt(3)
	v_mfma_f32_16x16x32_bf16 v[42:45], v[188:191], v[164:167], v[42:45]
	s_waitcnt lgkmcnt(1)
	v_mfma_f32_16x16x32_bf16 v[38:41], v[196:199], v[144:147], v[38:41]
	v_mfma_f32_16x16x32_bf16 v[34:37], v[196:199], v[164:167], v[34:37]
	v_mfma_f32_16x16x32_bf16 v[62:65], v[66:69], v[144:147], v[62:65]
	v_mfma_f32_16x16x32_bf16 v[58:61], v[66:69], v[164:167], v[58:61]
	v_mfma_f32_16x16x32_bf16 v[54:57], v[180:183], v[144:147], v[54:57]
	v_mfma_f32_16x16x32_bf16 v[50:53], v[180:183], v[164:167], v[50:53]
	v_mfma_f32_16x16x32_bf16 v[46:49], v[188:191], v[144:147], v[46:49]
	v_mfma_f32_16x16x32_bf16 v[42:45], v[192:195], v[168:171], v[42:45]
	s_waitcnt lgkmcnt(0)
	v_mfma_f32_16x16x32_bf16 v[38:41], v[200:203], v[148:151], v[38:41]
	v_mfma_f32_16x16x32_bf16 v[34:37], v[200:203], v[168:171], v[34:37]
	v_mfma_f32_16x16x32_bf16 v[212:215], v[176:179], v[148:151], v[62:65]
	v_mfma_f32_16x16x32_bf16 v[216:219], v[176:179], v[168:171], v[58:61]
	v_mfma_f32_16x16x32_bf16 v[220:223], v[184:187], v[148:151], v[54:57]
	v_mfma_f32_16x16x32_bf16 v[224:227], v[184:187], v[168:171], v[50:53]
	v_mfma_f32_16x16x32_bf16 v[228:231], v[192:195], v[148:151], v[46:49]
	s_setprio 0
	s_setprio 1
	v_mfma_f32_16x16x32_bf16 v[26:29], v[66:69], v[208:211], v[26:29]
	v_mfma_f32_16x16x32_bf16 v[22:25], v[180:183], v[156:159], v[22:25]
	v_mfma_f32_16x16x32_bf16 v[18:21], v[180:183], v[208:211], v[18:21]
	v_mfma_f32_16x16x32_bf16 v[10:13], v[188:191], v[208:211], v[10:13]
	v_mfma_f32_16x16x32_bf16 v[6:9], v[196:199], v[156:159], v[6:9]
	v_mfma_f32_16x16x32_bf16 v[2:5], v[196:199], v[208:211], v[2:5]
	v_mfma_f32_16x16x32_bf16 v[30:33], v[66:69], v[156:159], v[30:33]
	v_mfma_f32_16x16x32_bf16 v[26:29], v[176:179], v[152:155], v[26:29]
	v_mfma_f32_16x16x32_bf16 v[22:25], v[184:187], v[204:207], v[22:25]
	v_mfma_f32_16x16x32_bf16 v[18:21], v[184:187], v[152:155], v[18:21]
	v_mfma_f32_16x16x32_bf16 v[14:17], v[188:191], v[156:159], v[14:17]
	v_mfma_f32_16x16x32_bf16 v[10:13], v[192:195], v[152:155], v[10:13]
	v_mfma_f32_16x16x32_bf16 v[6:9], v[200:203], v[204:207], v[6:9]
	v_mfma_f32_16x16x32_bf16 v[2:5], v[200:203], v[152:155], v[2:5]
	v_mfma_f32_16x16x32_bf16 v[144:147], v[176:179], v[204:207], v[30:33]
	v_mfma_f32_16x16x32_bf16 v[148:151], v[192:195], v[204:207], v[14:17]
	s_setprio 0
	s_barrier
	ds_read_b128 v[152:155], v142
	ds_read_b128 v[156:159], v142 offset:1024
	ds_read_b128 v[164:167], v142 offset:2048
	ds_read_b128 v[168:171], v142 offset:3072
	ds_read_b128 v[58:61], v138 offset:32768
	ds_read_b128 v[62:65], v138 offset:33792
	ds_read_b128 v[66:69], v137 offset:32768
	ds_read_b128 v[176:179], v137 offset:33792
	ds_read_b128 v[180:183], v133 offset:32768
	ds_read_b128 v[184:187], v133 offset:33792
	ds_read_b128 v[188:191], v132 offset:32768
	ds_read_b128 v[192:195], v132 offset:33792
	s_waitcnt vmcnt(2)
	s_barrier
	s_waitcnt lgkmcnt(0)
	s_setprio 1
	s_waitcnt lgkmcnt(7)
	v_mfma_f32_16x16x32_bf16 v[14:17], v[58:61], v[152:155], v[126:129]
	s_waitcnt lgkmcnt(5)
	v_mfma_f32_16x16x32_bf16 v[30:33], v[66:69], v[152:155], v[118:121]
	s_waitcnt lgkmcnt(3)
	v_mfma_f32_16x16x32_bf16 v[46:49], v[180:183], v[152:155], v[110:113]
	s_waitcnt lgkmcnt(1)
	v_mfma_f32_16x16x32_bf16 v[50:53], v[188:191], v[152:155], v[102:105]
	v_mfma_f32_16x16x32_bf16 v[126:129], v[62:65], v[156:159], v[14:17]
	v_mfma_f32_16x16x32_bf16 v[14:17], v[58:61], v[164:167], v[122:125]
	v_mfma_f32_16x16x32_bf16 v[122:125], v[176:179], v[156:159], v[30:33]
	v_mfma_f32_16x16x32_bf16 v[30:33], v[66:69], v[164:167], v[114:117]
	v_mfma_f32_16x16x32_bf16 v[118:121], v[184:187], v[156:159], v[46:49]
	v_mfma_f32_16x16x32_bf16 v[46:49], v[180:183], v[164:167], v[106:109]
	s_waitcnt lgkmcnt(0)
	v_mfma_f32_16x16x32_bf16 v[114:117], v[192:195], v[156:159], v[50:53]
	v_mfma_f32_16x16x32_bf16 v[50:53], v[188:191], v[164:167], v[98:101]
	v_mfma_f32_16x16x32_bf16 v[14:17], v[62:65], v[168:171], v[14:17]
	v_mfma_f32_16x16x32_bf16 v[30:33], v[176:179], v[168:171], v[30:33]
	v_mfma_f32_16x16x32_bf16 v[46:49], v[184:187], v[168:171], v[46:49]
	v_mfma_f32_16x16x32_bf16 v[54:57], v[192:195], v[168:171], v[50:53]
	s_setprio 0
	s_barrier
; #define LDA_(dst, b, h) _Pragma("unroll") for (int m = 0; m < 4; ++m) _Pragma("unroll") for (int k = 0; k < 2; ++k) \
;     dst[m][k] = *reinterpret_cast<const bf16x8*>((char*)SA(b, h) + lds_byte(wr * 64 + m * 16 + fr, k * 32 + fq * 8))
; #define LDB_(dst, b, h) _Pragma("unroll") for (int n = 0; n < 2; ++n) _Pragma("unroll") for (int k = 0; k < 2; ++k) \
;     dst[n][k] = *reinterpret_cast<const bf16x8*>((char*)SB(b, h) + lds_byte(wc * 32 + n * 16 + fr, k * 32 + fq * 8))
; #define MMA(ai, bj, At, Bx) do { __builtin_amdgcn_s_setprio(1); \
;     _Pragma("unroll") for (int m = 0; m < 4; ++m) _Pragma("unroll") for (int n = 0; n < 2; ++n) _Pragma("unroll") for (int k = 0; k < 2; ++k) \
;       acc[ai][bj][m][n] = __builtin_amdgcn_mfma_f32_16x16x32_bf16(At[m][k], Bx[n][k], acc[ai][bj][m][n], 0, 0, 0); \
;     __builtin_amdgcn_s_setprio(0); } while (0)
; #define WAIT_V(n) asm volatile("s_waitcnt vmcnt(" #n ")" ::: "memory")
; #define WAIT_L(n) asm volatile("s_waitcnt lgkmcnt(" #n ")" ::: "memory")
; #define BAR __builtin_amdgcn_s_barrier()
; template <int K, int LDA, int LDB>
; DEVI void gemm_tile(const bf16* __restrict__ A, const bf16* __restrict__ Bt, bf16* shm, acc_t& acc) {
;     ...
;     LDB_(B1, 1, 1); WAIT_V(0); BAR; WAIT_L(0); MMA(0, 1, At, B1); BAR;
;     LDA_(At, 1, 1); BAR; WAIT_L(0); MMA(1, 0, At, B0); MMA(1, 1, At, B1); BAR; }
;   if (wr == 0) BAR;
	ds_read_b128 v[196:199], v140
	ds_read_b128 v[200:203], v140 offset:1024
	ds_read_b128 v[204:207], v140 offset:2048
	ds_read_b128 v[140:143], v140 offset:3072
	s_waitcnt vmcnt(0)
	s_barrier
	s_waitcnt lgkmcnt(0)
	s_setprio 1
	s_waitcnt lgkmcnt(3)
	v_mfma_f32_16x16x32_bf16 v[50:53], v[58:61], v[196:199], v[94:97]
	s_waitcnt lgkmcnt(1)
	v_mfma_f32_16x16x32_bf16 v[58:61], v[58:61], v[204:207], v[90:93]
	v_mfma_f32_16x16x32_bf16 v[70:73], v[188:191], v[196:199], v[70:73]
	v_mfma_f32_16x16x32_bf16 v[50:53], v[62:65], v[200:203], v[50:53]
	s_waitcnt lgkmcnt(0)
	v_mfma_f32_16x16x32_bf16 v[58:61], v[62:65], v[140:143], v[58:61]
	v_mfma_f32_16x16x32_bf16 v[62:65], v[66:69], v[196:199], v[86:89]
	v_mfma_f32_16x16x32_bf16 v[66:69], v[66:69], v[204:207], v[82:85]
	v_mfma_f32_16x16x32_bf16 v[78:81], v[180:183], v[196:199], v[78:81]
	v_mfma_f32_16x16x32_bf16 v[74:77], v[180:183], v[204:207], v[74:77]
	v_mfma_f32_16x16x32_bf16 v[94:97], v[192:195], v[200:203], v[70:73]
	v_mfma_f32_16x16x32_bf16 v[70:73], v[188:191], v[204:207], v[172:175]
	v_mfma_f32_16x16x32_bf16 v[62:65], v[176:179], v[200:203], v[62:65]
	v_mfma_f32_16x16x32_bf16 v[66:69], v[176:179], v[140:143], v[66:69]
	v_mfma_f32_16x16x32_bf16 v[78:81], v[184:187], v[200:203], v[78:81]
	v_mfma_f32_16x16x32_bf16 v[82:85], v[184:187], v[140:143], v[74:77]
	v_mfma_f32_16x16x32_bf16 v[98:101], v[192:195], v[140:143], v[70:73]
	s_setprio 0
	s_barrier
	ds_read_b128 v[172:175], v138 offset:49152
	ds_read_b128 v[176:179], v138 offset:50176
	ds_read_b128 v[180:183], v137 offset:49152
	ds_read_b128 v[184:187], v137 offset:50176
	ds_read_b128 v[188:191], v133 offset:49152
	ds_read_b128 v[192:195], v133 offset:50176
	ds_read_b128 v[208:211], v132 offset:49152
	ds_read_b128 v[232:235], v132 offset:50176
	s_barrier
	s_waitcnt lgkmcnt(0)
	s_setprio 1
	s_waitcnt lgkmcnt(7)
	v_mfma_f32_16x16x32_bf16 v[70:73], v[172:175], v[152:155], v[212:215]
	s_waitcnt lgkmcnt(6)
	v_mfma_f32_16x16x32_bf16 v[110:113], v[176:179], v[156:159], v[70:73]
	v_mfma_f32_16x16x32_bf16 v[70:73], v[172:175], v[164:167], v[216:219]
	v_mfma_f32_16x16x32_bf16 v[106:109], v[176:179], v[168:171], v[70:73]
	s_waitcnt lgkmcnt(5)
	v_mfma_f32_16x16x32_bf16 v[70:73], v[180:183], v[152:155], v[220:223]
	s_waitcnt lgkmcnt(4)
	v_mfma_f32_16x16x32_bf16 v[102:105], v[184:187], v[156:159], v[70:73]
	v_mfma_f32_16x16x32_bf16 v[70:73], v[180:183], v[164:167], v[224:227]
	v_mfma_f32_16x16x32_bf16 v[90:93], v[184:187], v[168:171], v[70:73]
	s_waitcnt lgkmcnt(3)
	v_mfma_f32_16x16x32_bf16 v[70:73], v[188:191], v[152:155], v[228:231]
	v_mfma_f32_16x16x32_bf16 v[42:45], v[188:191], v[164:167], v[42:45]
	s_waitcnt lgkmcnt(1)
	v_mfma_f32_16x16x32_bf16 v[38:41], v[208:211], v[152:155], v[38:41]
	v_mfma_f32_16x16x32_bf16 v[34:37], v[208:211], v[164:167], v[34:37]
	v_mfma_f32_16x16x32_bf16 v[86:89], v[192:195], v[156:159], v[70:73]
	v_mfma_f32_16x16x32_bf16 v[74:77], v[192:195], v[168:171], v[42:45]
	s_waitcnt lgkmcnt(0)
	v_mfma_f32_16x16x32_bf16 v[70:73], v[232:235], v[156:159], v[38:41]
	v_mfma_f32_16x16x32_bf16 v[42:45], v[232:235], v[168:171], v[34:37]
	s_setprio 0
	s_setprio 1
	v_mfma_f32_16x16x32_bf16 v[34:37], v[172:175], v[196:199], v[144:147]
	v_mfma_f32_16x16x32_bf16 v[26:29], v[172:175], v[204:207], v[26:29]
	v_mfma_f32_16x16x32_bf16 v[22:25], v[180:183], v[196:199], v[22:25]
	v_mfma_f32_16x16x32_bf16 v[18:21], v[180:183], v[204:207], v[18:21]
	v_mfma_f32_16x16x32_bf16 v[38:41], v[176:179], v[200:203], v[34:37]
	v_mfma_f32_16x16x32_bf16 v[34:37], v[176:179], v[140:143], v[26:29]
	v_mfma_f32_16x16x32_bf16 v[26:29], v[184:187], v[200:203], v[22:25]
	v_mfma_f32_16x16x32_bf16 v[22:25], v[184:187], v[140:143], v[18:21]
	v_mfma_f32_16x16x32_bf16 v[18:21], v[188:191], v[196:199], v[148:151]
	v_mfma_f32_16x16x32_bf16 v[10:13], v[188:191], v[204:207], v[10:13]
	v_mfma_f32_16x16x32_bf16 v[6:9], v[208:211], v[196:199], v[6:9]
	v_mfma_f32_16x16x32_bf16 v[2:5], v[208:211], v[204:207], v[2:5]
	v_mfma_f32_16x16x32_bf16 v[18:21], v[192:195], v[200:203], v[18:21]
	v_mfma_f32_16x16x32_bf16 v[10:13], v[192:195], v[140:143], v[10:13]
	v_mfma_f32_16x16x32_bf16 v[6:9], v[232:235], v[200:203], v[6:9]
	v_mfma_f32_16x16x32_bf16 v[2:5], v[232:235], v[140:143], v[2:5]
	s_setprio 0
	s_movk_i32 s0, 0x100
	v_cmp_gt_u32_e32 vcc, s0, v130
	s_barrier
	s_and_saveexec_b64 s[0:1], vcc
	s_cbranch_execz .LBB0_375
	s_barrier

; #define STAGE(P, BASE, LD, br, kt) do { const int _so = (int)(((br) * (LD) + (kt) * BK) * 2); \
;     _Pragma("unroll") for (int _i = 0; _i < 2; ++_i) { \
;       __builtin_amdgcn_raw_ptr_buffer_load_lds(rs##BASE, (__attribute__((address_space(3))) unsigned*)((char*)(P) + tid_ * 16 + _i * 8192), 16, (int)off##LD[_i], _so, 0, 0); } } while (0)
; #define LDA_(dst, b, h) _Pragma("unroll") for (int m = 0; m < 4; ++m) _Pragma("unroll") for (int k = 0; k < 2; ++k) \
;     dst[m][k] = *reinterpret_cast<const bf16x8*>((char*)SA(b, h) + lds_byte(wr * 64 + m * 16 + fr, k * 32 + fq * 8))
; #define LDB_(dst, b, h) _Pragma("unroll") for (int n = 0; n < 2; ++n) _Pragma("unroll") for (int k = 0; k < 2; ++k) \
;     dst[n][k] = *reinterpret_cast<const bf16x8*>((char*)SB(b, h) + lds_byte(wc * 32 + n * 16 + fr, k * 32 + fq * 8))
; #define MMA(ai, bj, At, Bx) do { __builtin_amdgcn_s_setprio(1); \
;     _Pragma("unroll") for (int m = 0; m < 4; ++m) _Pragma("unroll") for (int n = 0; n < 2; ++n) _Pragma("unroll") for (int k = 0; k < 2; ++k) \
;       acc[ai][bj][m][n] = __builtin_amdgcn_mfma_f32_16x16x32_bf16(At[m][k], Bx[n][k], acc[ai][bj][m][n], 0, 0, 0); \
;     __builtin_amdgcn_s_setprio(0); } while (0)
; #define WAIT_L(n) asm volatile("s_waitcnt lgkmcnt(" #n ")" ::: "memory")
; #define BAR __builtin_amdgcn_s_barrier()
; #define SCHED __builtin_amdgcn_sched_barrier(0)
; template <int K, int LDA, int LDB>
; DEVI void gemm_tile(const bf16* __restrict__ A, const bf16* __restrict__ Bt, bf16* shm, acc_t& acc) {
;     ...
;     LDB_(B0, 0, 0); SCHED; LDA_(At, 0, 0); STAGE(SA(1, 1), A, LDA, HALF, t + 1);
;     WAIT_L(8); BAR; WAIT_L(0); MMA(0, 0, At, B0); BAR; SCHED;
;     LDB_(B1, 0, 1); STAGE(SB(0, 0), Bt, LDB, 0, t + 2);
;     BAR; WAIT_L(0); MMA(0, 1, At, B1); BAR;
;     LDA_(At, 0, 1); STAGE(SA(0, 0), A, LDA, 0, t + 2);
;     BAR; WAIT_L(0); MMA(1, 0, At, B0); BAR; SCHED;
.LBB0_561:
	ds_read_b128 v[168:171], v167
	ds_read_b128 v[172:175], v167 offset:1024
	ds_read_b128 v[176:179], v167 offset:2048
	ds_read_b128 v[180:183], v167 offset:3072
	v_readfirstlane_b32 s15, v161
	s_add_i32 s13, s3, 0xffffff00
	s_mov_b32 m0, s15
	v_readfirstlane_b32 s15, v166
	ds_read_b128 v[184:187], v135
	ds_read_b128 v[188:191], v135 offset:1024
	ds_read_b128 v[192:195], v134
	ds_read_b128 v[196:199], v134 offset:1024
	ds_read_b128 v[200:203], v133
	ds_read_b128 v[204:207], v133 offset:1024
	ds_read_b128 v[208:211], v132
	ds_read_b128 v[212:215], v132 offset:1024
	buffer_load_dwordx4 v144, s[8:11], s13 offen lds
	s_mov_b32 m0, s15
	s_nop 0
	buffer_load_dwordx4 v146, s[8:11], s13 offen lds
	s_waitcnt lgkmcnt(8)
	s_barrier
	s_waitcnt lgkmcnt(0)
	s_setprio 1
	s_waitcnt lgkmcnt(7)
	v_mfma_f32_16x16x32_bf16 v[126:129], v[184:187], v[168:171], v[126:129]
	v_mfma_f32_16x16x32_bf16 v[122:125], v[184:187], v[176:179], v[122:125]
	s_waitcnt lgkmcnt(5)
	v_mfma_f32_16x16x32_bf16 v[118:121], v[192:195], v[168:171], v[118:121]
	v_mfma_f32_16x16x32_bf16 v[114:117], v[192:195], v[176:179], v[114:117]
	s_waitcnt lgkmcnt(3)
	v_mfma_f32_16x16x32_bf16 v[110:113], v[200:203], v[168:171], v[110:113]
	v_mfma_f32_16x16x32_bf16 v[106:109], v[200:203], v[176:179], v[106:109]
	s_waitcnt lgkmcnt(1)
	v_mfma_f32_16x16x32_bf16 v[102:105], v[208:211], v[168:171], v[102:105]
	v_mfma_f32_16x16x32_bf16 v[98:101], v[208:211], v[176:179], v[98:101]
	v_mfma_f32_16x16x32_bf16 v[126:129], v[188:191], v[172:175], v[126:129]
	v_mfma_f32_16x16x32_bf16 v[122:125], v[188:191], v[180:183], v[122:125]
	v_mfma_f32_16x16x32_bf16 v[118:121], v[196:199], v[172:175], v[118:121]
	v_mfma_f32_16x16x32_bf16 v[114:117], v[196:199], v[180:183], v[114:117]
	v_mfma_f32_16x16x32_bf16 v[110:113], v[204:207], v[172:175], v[110:113]
	v_mfma_f32_16x16x32_bf16 v[106:109], v[204:207], v[180:183], v[106:109]
	s_waitcnt lgkmcnt(0)
	v_mfma_f32_16x16x32_bf16 v[102:105], v[212:215], v[172:175], v[102:105]
	v_mfma_f32_16x16x32_bf16 v[98:101], v[212:215], v[180:183], v[98:101]
	s_setprio 0
	s_barrier
	v_readfirstlane_b32 s15, v148
	s_add_i32 s13, s3, 0xfff7ff80
	s_mov_b32 m0, s15
	v_readfirstlane_b32 s15, v149
	ds_read_b128 v[216:219], v159
	ds_read_b128 v[220:223], v159 offset:1024
	ds_read_b128 v[224:227], v159 offset:2048
	ds_read_b128 v[228:231], v159 offset:3072
	buffer_load_dwordx4 v144, s[4:7], s13 offen lds
	s_mov_b32 m0, s15
	s_nop 0
	buffer_load_dwordx4 v146, s[4:7], s13 offen lds
	s_barrier
	s_waitcnt lgkmcnt(0)
	s_setprio 1
	s_waitcnt lgkmcnt(3)
	v_mfma_f32_16x16x32_bf16 v[94:97], v[184:187], v[216:219], v[94:97]
	s_waitcnt lgkmcnt(1)
	v_mfma_f32_16x16x32_bf16 v[90:93], v[184:187], v[224:227], v[90:93]
	v_mfma_f32_16x16x32_bf16 v[86:89], v[192:195], v[216:219], v[86:89]
	v_mfma_f32_16x16x32_bf16 v[82:85], v[192:195], v[224:227], v[82:85]
	v_mfma_f32_16x16x32_bf16 v[78:81], v[200:203], v[216:219], v[78:81]
	v_mfma_f32_16x16x32_bf16 v[74:77], v[200:203], v[224:227], v[74:77]
	v_mfma_f32_16x16x32_bf16 v[70:73], v[208:211], v[216:219], v[70:73]
	v_mfma_f32_16x16x32_bf16 v[66:69], v[208:211], v[224:227], v[66:69]
	v_mfma_f32_16x16x32_bf16 v[94:97], v[188:191], v[220:223], v[94:97]
	s_waitcnt lgkmcnt(0)
	v_mfma_f32_16x16x32_bf16 v[90:93], v[188:191], v[228:231], v[90:93]
	v_mfma_f32_16x16x32_bf16 v[86:89], v[196:199], v[220:223], v[86:89]
	v_mfma_f32_16x16x32_bf16 v[82:85], v[196:199], v[228:231], v[82:85]
	v_mfma_f32_16x16x32_bf16 v[78:81], v[204:207], v[220:223], v[78:81]
	v_mfma_f32_16x16x32_bf16 v[74:77], v[204:207], v[228:231], v[74:77]
	v_mfma_f32_16x16x32_bf16 v[70:73], v[212:215], v[220:223], v[70:73]
	v_mfma_f32_16x16x32_bf16 v[66:69], v[212:215], v[228:231], v[66:69]
	s_setprio 0
	v_readfirstlane_b32 s15, v150
	s_mov_b32 m0, s15
	v_readfirstlane_b32 s15, v151
	s_barrier
	ds_read_b128 v[184:187], v135 offset:16384
	ds_read_b128 v[188:191], v135 offset:17408
	ds_read_b128 v[192:195], v134 offset:16384
	ds_read_b128 v[196:199], v134 offset:17408
	ds_read_b128 v[200:203], v133 offset:16384
	ds_read_b128 v[204:207], v133 offset:17408
	ds_read_b128 v[208:211], v132 offset:16384
	ds_read_b128 v[212:215], v132 offset:17408
	buffer_load_dwordx4 v144, s[8:11], s13 offen lds
	s_mov_b32 m0, s15
	s_nop 0
	buffer_load_dwordx4 v146, s[8:11], s13 offen lds
	s_barrier
	s_waitcnt lgkmcnt(0)
	s_setprio 1
	s_waitcnt lgkmcnt(7)
	v_mfma_f32_16x16x32_bf16 v[62:65], v[184:187], v[168:171], v[62:65]
	v_mfma_f32_16x16x32_bf16 v[58:61], v[184:187], v[176:179], v[58:61]
	s_waitcnt lgkmcnt(5)
	v_mfma_f32_16x16x32_bf16 v[54:57], v[192:195], v[168:171], v[54:57]
	v_mfma_f32_16x16x32_bf16 v[50:53], v[192:195], v[176:179], v[50:53]
	s_waitcnt lgkmcnt(3)
	v_mfma_f32_16x16x32_bf16 v[46:49], v[200:203], v[168:171], v[46:49]
	v_mfma_f32_16x16x32_bf16 v[42:45], v[200:203], v[176:179], v[42:45]
	s_waitcnt lgkmcnt(1)
	v_mfma_f32_16x16x32_bf16 v[38:41], v[208:211], v[168:171], v[38:41]
	v_mfma_f32_16x16x32_bf16 v[34:37], v[208:211], v[176:179], v[34:37]
	v_mfma_f32_16x16x32_bf16 v[62:65], v[188:191], v[172:175], v[62:65]
	v_mfma_f32_16x16x32_bf16 v[58:61], v[188:191], v[180:183], v[58:61]
	v_mfma_f32_16x16x32_bf16 v[54:57], v[196:199], v[172:175], v[54:57]
	v_mfma_f32_16x16x32_bf16 v[50:53], v[196:199], v[180:183], v[50:53]
	v_mfma_f32_16x16x32_bf16 v[46:49], v[204:207], v[172:175], v[46:49]
	v_mfma_f32_16x16x32_bf16 v[42:45], v[204:207], v[180:183], v[42:45]
	s_waitcnt lgkmcnt(0)
	v_mfma_f32_16x16x32_bf16 v[38:41], v[212:215], v[172:175], v[38:41]
	v_mfma_f32_16x16x32_bf16 v[34:37], v[212:215], v[180:183], v[34:37]
	s_setprio 0
	s_barrier
; #define STAGE(P, BASE, LD, br, kt) do { const int _so = (int)(((br) * (LD) + (kt) * BK) * 2); \
;     _Pragma("unroll") for (int _i = 0; _i < 2; ++_i) { \
;       __builtin_amdgcn_raw_ptr_buffer_load_lds(rs##BASE, (__attribute__((address_space(3))) unsigned*)((char*)(P) + tid_ * 16 + _i * 8192), 16, (int)off##LD[_i], _so, 0, 0); } } while (0)
; #define LDA_(dst, b, h) _Pragma("unroll") for (int m = 0; m < 4; ++m) _Pragma("unroll") for (int k = 0; k < 2; ++k) \
;     dst[m][k] = *reinterpret_cast<const bf16x8*>((char*)SA(b, h) + lds_byte(wr * 64 + m * 16 + fr, k * 32 + fq * 8))
; #define LDB_(dst, b, h) _Pragma("unroll") for (int n = 0; n < 2; ++n) _Pragma("unroll") for (int k = 0; k < 2; ++k) \
;     dst[n][k] = *reinterpret_cast<const bf16x8*>((char*)SB(b, h) + lds_byte(wc * 32 + n * 16 + fr, k * 32 + fq * 8))
; #define MMA(ai, bj, At, Bx) do { __builtin_amdgcn_s_setprio(1); \
;     _Pragma("unroll") for (int m = 0; m < 4; ++m) _Pragma("unroll") for (int n = 0; n < 2; ++n) _Pragma("unroll") for (int k = 0; k < 2; ++k) \
;       acc[ai][bj][m][n] = __builtin_amdgcn_mfma_f32_16x16x32_bf16(At[m][k], Bx[n][k], acc[ai][bj][m][n], 0, 0, 0); \
;     __builtin_amdgcn_s_setprio(0); } while (0)
; #define WAIT_V(n) asm volatile("s_waitcnt vmcnt(" #n ")" ::: "memory")
; #define WAIT_L(n) asm volatile("s_waitcnt lgkmcnt(" #n ")" ::: "memory")
; #define BAR __builtin_amdgcn_s_barrier()
; #define SCHED __builtin_amdgcn_sched_barrier(0)
; template <int K, int LDA, int LDB>
; DEVI void gemm_tile(const bf16* __restrict__ A, const bf16* __restrict__ Bt, bf16* shm, acc_t& acc) {
;     ...
;     STAGE(SB(0, 1), Bt, LDB, HALF, t + 2);
;     WAIT_V(6); BAR; MMA(1, 1, At, B1); BAR;
;     LDB_(B0, 1, 0); SCHED; LDA_(At, 1, 0); STAGE(SA(0, 1), A, LDA, HALF, t + 2);
;     WAIT_L(8); BAR; WAIT_L(0); MMA(0, 0, At, B0); BAR; SCHED;
;     LDB_(B1, 1, 1); STAGE(SB(1, 0), Bt, LDB, 0, t + 3);
;     BAR; WAIT_L(0); MMA(0, 1, At, B1); BAR;
;     LDA_(At, 1, 1); STAGE(SA(1, 0), A, LDA, 0, t + 3);
	v_readfirstlane_b32 s15, v152
	s_add_i32 s13, s3, 0xffffff80
	s_mov_b32 m0, s15
	v_readfirstlane_b32 s15, v153
	buffer_load_dwordx4 v144, s[4:7], s13 offen lds
	s_mov_b32 m0, s15
	s_nop 0
	buffer_load_dwordx4 v146, s[4:7], s13 offen lds
	s_waitcnt vmcnt(6)
	s_barrier
	s_setprio 1
	v_mfma_f32_16x16x32_bf16 v[30:33], v[184:187], v[216:219], v[30:33]
	v_mfma_f32_16x16x32_bf16 v[26:29], v[184:187], v[224:227], v[26:29]
	v_mfma_f32_16x16x32_bf16 v[22:25], v[192:195], v[216:219], v[22:25]
	v_mfma_f32_16x16x32_bf16 v[18:21], v[192:195], v[224:227], v[18:21]
	v_mfma_f32_16x16x32_bf16 v[14:17], v[200:203], v[216:219], v[14:17]
	v_mfma_f32_16x16x32_bf16 v[10:13], v[200:203], v[224:227], v[10:13]
	v_mfma_f32_16x16x32_bf16 v[6:9], v[208:211], v[216:219], v[6:9]
	v_mfma_f32_16x16x32_bf16 v[2:5], v[208:211], v[224:227], v[2:5]
	v_mfma_f32_16x16x32_bf16 v[30:33], v[188:191], v[220:223], v[30:33]
	v_mfma_f32_16x16x32_bf16 v[26:29], v[188:191], v[228:231], v[26:29]
	v_mfma_f32_16x16x32_bf16 v[22:25], v[196:199], v[220:223], v[22:25]
	v_mfma_f32_16x16x32_bf16 v[18:21], v[196:199], v[228:231], v[18:21]
	v_mfma_f32_16x16x32_bf16 v[14:17], v[204:207], v[220:223], v[14:17]
	v_mfma_f32_16x16x32_bf16 v[10:13], v[204:207], v[228:231], v[10:13]
	v_mfma_f32_16x16x32_bf16 v[6:9], v[212:215], v[220:223], v[6:9]
	v_mfma_f32_16x16x32_bf16 v[2:5], v[212:215], v[228:231], v[2:5]
	s_setprio 0
	s_barrier
	ds_read_b128 v[168:171], v147
	ds_read_b128 v[172:175], v147 offset:1024
	ds_read_b128 v[176:179], v147 offset:2048
	ds_read_b128 v[180:183], v147 offset:3072
	v_readfirstlane_b32 s15, v154
	s_mov_b32 m0, s15
	v_readfirstlane_b32 s15, v155
	ds_read_b128 v[184:187], v135 offset:32768
	ds_read_b128 v[188:191], v135 offset:33792
	ds_read_b128 v[192:195], v134 offset:32768
	ds_read_b128 v[196:199], v134 offset:33792
	ds_read_b128 v[200:203], v133 offset:32768
	ds_read_b128 v[204:207], v133 offset:33792
	ds_read_b128 v[208:211], v132 offset:32768
	ds_read_b128 v[212:215], v132 offset:33792
	buffer_load_dwordx4 v144, s[8:11], s13 offen lds
	s_mov_b32 m0, s15
	s_nop 0
	buffer_load_dwordx4 v146, s[8:11], s13 offen lds
	s_waitcnt lgkmcnt(8)
	s_barrier
	s_waitcnt lgkmcnt(0)
	s_setprio 1
	s_waitcnt lgkmcnt(7)
	v_mfma_f32_16x16x32_bf16 v[126:129], v[184:187], v[168:171], v[126:129]
	v_mfma_f32_16x16x32_bf16 v[122:125], v[184:187], v[176:179], v[122:125]
	s_waitcnt lgkmcnt(5)
	v_mfma_f32_16x16x32_bf16 v[118:121], v[192:195], v[168:171], v[118:121]
	v_mfma_f32_16x16x32_bf16 v[114:117], v[192:195], v[176:179], v[114:117]
	s_waitcnt lgkmcnt(3)
	v_mfma_f32_16x16x32_bf16 v[110:113], v[200:203], v[168:171], v[110:113]
	v_mfma_f32_16x16x32_bf16 v[106:109], v[200:203], v[176:179], v[106:109]
	s_waitcnt lgkmcnt(1)
	v_mfma_f32_16x16x32_bf16 v[102:105], v[208:211], v[168:171], v[102:105]
	v_mfma_f32_16x16x32_bf16 v[98:101], v[208:211], v[176:179], v[98:101]
	v_mfma_f32_16x16x32_bf16 v[126:129], v[188:191], v[172:175], v[126:129]
	v_mfma_f32_16x16x32_bf16 v[122:125], v[188:191], v[180:183], v[122:125]
	v_mfma_f32_16x16x32_bf16 v[118:121], v[196:199], v[172:175], v[118:121]
	v_mfma_f32_16x16x32_bf16 v[114:117], v[196:199], v[180:183], v[114:117]
	v_mfma_f32_16x16x32_bf16 v[110:113], v[204:207], v[172:175], v[110:113]
	v_mfma_f32_16x16x32_bf16 v[106:109], v[204:207], v[180:183], v[106:109]
	s_waitcnt lgkmcnt(0)
	v_mfma_f32_16x16x32_bf16 v[102:105], v[212:215], v[172:175], v[102:105]
	v_mfma_f32_16x16x32_bf16 v[98:101], v[212:215], v[180:183], v[98:101]
	s_setprio 0
	s_barrier
	v_readfirstlane_b32 s15, v156
	s_add_i32 s13, s3, 0xfff80000
	s_mov_b32 m0, s15
	v_readfirstlane_b32 s15, v157
	ds_read_b128 v[216:219], v145
	ds_read_b128 v[220:223], v145 offset:1024
	ds_read_b128 v[224:227], v145 offset:2048
	ds_read_b128 v[228:231], v145 offset:3072
	buffer_load_dwordx4 v144, s[4:7], s13 offen lds
	s_mov_b32 m0, s15
	s_nop 0
	buffer_load_dwordx4 v146, s[4:7], s13 offen lds
	s_barrier
	s_waitcnt lgkmcnt(0)
	s_setprio 1
	s_waitcnt lgkmcnt(3)
	v_mfma_f32_16x16x32_bf16 v[94:97], v[184:187], v[216:219], v[94:97]
	s_waitcnt lgkmcnt(1)
	v_mfma_f32_16x16x32_bf16 v[90:93], v[184:187], v[224:227], v[90:93]
	v_mfma_f32_16x16x32_bf16 v[86:89], v[192:195], v[216:219], v[86:89]
	v_mfma_f32_16x16x32_bf16 v[82:85], v[192:195], v[224:227], v[82:85]
	v_mfma_f32_16x16x32_bf16 v[78:81], v[200:203], v[216:219], v[78:81]
	v_mfma_f32_16x16x32_bf16 v[74:77], v[200:203], v[224:227], v[74:77]
	v_mfma_f32_16x16x32_bf16 v[70:73], v[208:211], v[216:219], v[70:73]
	v_mfma_f32_16x16x32_bf16 v[66:69], v[208:211], v[224:227], v[66:69]
	v_mfma_f32_16x16x32_bf16 v[94:97], v[188:191], v[220:223], v[94:97]
	s_waitcnt lgkmcnt(0)
	v_mfma_f32_16x16x32_bf16 v[90:93], v[188:191], v[228:231], v[90:93]
	v_mfma_f32_16x16x32_bf16 v[86:89], v[196:199], v[220:223], v[86:89]
	v_mfma_f32_16x16x32_bf16 v[82:85], v[196:199], v[228:231], v[82:85]
	v_mfma_f32_16x16x32_bf16 v[78:81], v[204:207], v[220:223], v[78:81]
	v_mfma_f32_16x16x32_bf16 v[74:77], v[204:207], v[228:231], v[74:77]
	v_mfma_f32_16x16x32_bf16 v[70:73], v[212:215], v[220:223], v[70:73]
	v_mfma_f32_16x16x32_bf16 v[66:69], v[212:215], v[228:231], v[66:69]
	s_setprio 0
	v_readfirstlane_b32 s15, v158
	s_mov_b32 m0, s15
	v_readfirstlane_b32 s15, v160
	s_barrier
	ds_read_b128 v[184:187], v135 offset:49152
	ds_read_b128 v[188:191], v135 offset:50176
	ds_read_b128 v[192:195], v134 offset:49152
	ds_read_b128 v[196:199], v134 offset:50176
	ds_read_b128 v[200:203], v133 offset:49152
	ds_read_b128 v[204:207], v133 offset:50176
	ds_read_b128 v[208:211], v132 offset:49152
	ds_read_b128 v[212:215], v132 offset:50176
	buffer_load_dwordx4 v144, s[8:11], s13 offen lds
	s_mov_b32 m0, s15
	s_nop 0
	buffer_load_dwordx4 v146, s[8:11], s13 offen lds
	s_barrier
; #define STAGE(P, BASE, LD, br, kt) do { const int _so = (int)(((br) * (LD) + (kt) * BK) * 2); \
;     _Pragma("unroll") for (int _i = 0; _i < 2; ++_i) { \
;       __builtin_amdgcn_raw_ptr_buffer_load_lds(rs##BASE, (__attribute__((address_space(3))) unsigned*)((char*)(P) + tid_ * 16 + _i * 8192), 16, (int)off##LD[_i], _so, 0, 0); } } while (0)
; #define LDA_(dst, b, h) _Pragma("unroll") for (int m = 0; m < 4; ++m) _Pragma("unroll") for (int k = 0; k < 2; ++k) \
;     dst[m][k] = *reinterpret_cast<const bf16x8*>((char*)SA(b, h) + lds_byte(wr * 64 + m * 16 + fr, k * 32 + fq * 8))
; #define LDB_(dst, b, h) _Pragma("unroll") for (int n = 0; n < 2; ++n) _Pragma("unroll") for (int k = 0; k < 2; ++k) \
;     dst[n][k] = *reinterpret_cast<const bf16x8*>((char*)SB(b, h) + lds_byte(wc * 32 + n * 16 + fr, k * 32 + fq * 8))
; #define MMA(ai, bj, At, Bx) do { __builtin_amdgcn_s_setprio(1); \
;     _Pragma("unroll") for (int m = 0; m < 4; ++m) _Pragma("unroll") for (int n = 0; n < 2; ++n) _Pragma("unroll") for (int k = 0; k < 2; ++k) \
;       acc[ai][bj][m][n] = __builtin_amdgcn_mfma_f32_16x16x32_bf16(At[m][k], Bx[n][k], acc[ai][bj][m][n], 0, 0, 0); \
;     __builtin_amdgcn_s_setprio(0); } while (0)
; #define WAIT_V(n) asm volatile("s_waitcnt vmcnt(" #n ")" ::: "memory")
; #define WAIT_L(n) asm volatile("s_waitcnt lgkmcnt(" #n ")" ::: "memory")
; #define BAR __builtin_amdgcn_s_barrier()
; #define SCHED __builtin_amdgcn_sched_barrier(0)
; template <int K, int LDA, int LDB>
; DEVI void gemm_tile(const bf16* __restrict__ A, const bf16* __restrict__ Bt, bf16* shm, acc_t& acc) {
;     ...
;     BAR; WAIT_L(0); MMA(1, 0, At, B0); BAR; SCHED;
;     STAGE(SB(1, 1), Bt, LDB, HALF, t + 3);
;     WAIT_V(6); BAR; MMA(1, 1, At, B1); BAR;
;   }
;   { LDB_(B0, 0, 0); LDA_(At, 0, 0); STAGE(SA(1, 1), A, LDA, HALF, nt - 1);
;     BAR; WAIT_L(0); MMA(0, 0, At, B0); BAR;
;     LDB_(B1, 0, 1); BAR; WAIT_L(0); MMA(0, 1, At, B1); BAR;
	s_waitcnt lgkmcnt(0)
	s_setprio 1
	s_waitcnt lgkmcnt(7)
	v_mfma_f32_16x16x32_bf16 v[62:65], v[184:187], v[168:171], v[62:65]
	v_mfma_f32_16x16x32_bf16 v[58:61], v[184:187], v[176:179], v[58:61]
	s_waitcnt lgkmcnt(5)
	v_mfma_f32_16x16x32_bf16 v[54:57], v[192:195], v[168:171], v[54:57]
	v_mfma_f32_16x16x32_bf16 v[50:53], v[192:195], v[176:179], v[50:53]
	s_waitcnt lgkmcnt(3)
	v_mfma_f32_16x16x32_bf16 v[46:49], v[200:203], v[168:171], v[46:49]
	v_mfma_f32_16x16x32_bf16 v[42:45], v[200:203], v[176:179], v[42:45]
	s_waitcnt lgkmcnt(1)
	v_mfma_f32_16x16x32_bf16 v[38:41], v[208:211], v[168:171], v[38:41]
	v_mfma_f32_16x16x32_bf16 v[34:37], v[208:211], v[176:179], v[34:37]
	v_mfma_f32_16x16x32_bf16 v[62:65], v[188:191], v[172:175], v[62:65]
	v_mfma_f32_16x16x32_bf16 v[58:61], v[188:191], v[180:183], v[58:61]
	v_mfma_f32_16x16x32_bf16 v[54:57], v[196:199], v[172:175], v[54:57]
	v_mfma_f32_16x16x32_bf16 v[50:53], v[196:199], v[180:183], v[50:53]
	v_mfma_f32_16x16x32_bf16 v[46:49], v[204:207], v[172:175], v[46:49]
	v_mfma_f32_16x16x32_bf16 v[42:45], v[204:207], v[180:183], v[42:45]
	s_waitcnt lgkmcnt(0)
	v_mfma_f32_16x16x32_bf16 v[38:41], v[212:215], v[172:175], v[38:41]
	v_mfma_f32_16x16x32_bf16 v[34:37], v[212:215], v[180:183], v[34:37]
	s_setprio 0
	s_barrier
	v_readfirstlane_b32 s13, v164
	s_mov_b32 m0, s13
	v_readfirstlane_b32 s13, v165
	buffer_load_dwordx4 v144, s[4:7], s3 offen lds
	s_mov_b32 m0, s13
	s_nop 0
	buffer_load_dwordx4 v146, s[4:7], s3 offen lds
	s_waitcnt vmcnt(6)
	s_barrier
	s_setprio 1
	v_mfma_f32_16x16x32_bf16 v[30:33], v[184:187], v[216:219], v[30:33]
	v_mfma_f32_16x16x32_bf16 v[26:29], v[184:187], v[224:227], v[26:29]
	v_mfma_f32_16x16x32_bf16 v[22:25], v[192:195], v[216:219], v[22:25]
	v_mfma_f32_16x16x32_bf16 v[18:21], v[192:195], v[224:227], v[18:21]
	v_mfma_f32_16x16x32_bf16 v[14:17], v[200:203], v[216:219], v[14:17]
	v_mfma_f32_16x16x32_bf16 v[10:13], v[200:203], v[224:227], v[10:13]
	v_mfma_f32_16x16x32_bf16 v[6:9], v[208:211], v[216:219], v[6:9]
	v_mfma_f32_16x16x32_bf16 v[2:5], v[208:211], v[224:227], v[2:5]
	v_mfma_f32_16x16x32_bf16 v[30:33], v[188:191], v[220:223], v[30:33]
	v_mfma_f32_16x16x32_bf16 v[26:29], v[188:191], v[228:231], v[26:29]
	v_mfma_f32_16x16x32_bf16 v[22:25], v[196:199], v[220:223], v[22:25]
	v_mfma_f32_16x16x32_bf16 v[18:21], v[196:199], v[228:231], v[18:21]
	v_mfma_f32_16x16x32_bf16 v[14:17], v[204:207], v[220:223], v[14:17]
	v_mfma_f32_16x16x32_bf16 v[10:13], v[204:207], v[228:231], v[10:13]
	v_mfma_f32_16x16x32_bf16 v[6:9], v[212:215], v[220:223], v[6:9]
	v_mfma_f32_16x16x32_bf16 v[2:5], v[212:215], v[228:231], v[2:5]
	s_setprio 0
	s_add_i32 s2, s2, 2
	s_addk_i32 s3, 0x100
	s_cmp_lt_u32 s2, 28
	s_cbranch_scc1 .Lrot_13416
	s_barrier
	v_readfirstlane_b32 s2, v161
	s_mov_b32 s10, s6
	s_mov_b32 s11, s7
	s_mov_b32 m0, s2
	v_readfirstlane_b32 s2, v166
	ds_read_b128 v[148:151], v167
	ds_read_b128 v[152:155], v167 offset:1024
	ds_read_b128 v[168:171], v167 offset:2048
	ds_read_b128 v[172:175], v167 offset:3072
	ds_read_b128 v[176:179], v135
	ds_read_b128 v[180:183], v135 offset:1024
	ds_read_b128 v[184:187], v134
	ds_read_b128 v[188:191], v134 offset:1024
	ds_read_b128 v[192:195], v133
	ds_read_b128 v[196:199], v133 offset:1024
	ds_read_b128 v[200:203], v132
	ds_read_b128 v[204:207], v132 offset:1024
	buffer_load_dwordx4 v144, s[8:11], s69 offen lds
	s_mov_b32 m0, s2
	s_nop 0
	buffer_load_dwordx4 v146, s[8:11], s69 offen lds
	s_barrier
	s_waitcnt lgkmcnt(0)
	s_setprio 1
	s_waitcnt lgkmcnt(7)
	v_mfma_f32_16x16x32_bf16 v[126:129], v[176:179], v[148:151], v[126:129]
	v_mfma_f32_16x16x32_bf16 v[122:125], v[176:179], v[168:171], v[122:125]
	s_waitcnt lgkmcnt(5)
	v_mfma_f32_16x16x32_bf16 v[118:121], v[184:187], v[148:151], v[118:121]
	v_mfma_f32_16x16x32_bf16 v[114:117], v[184:187], v[168:171], v[114:117]
	s_waitcnt lgkmcnt(3)
	v_mfma_f32_16x16x32_bf16 v[110:113], v[192:195], v[148:151], v[110:113]
	v_mfma_f32_16x16x32_bf16 v[106:109], v[192:195], v[168:171], v[106:109]
	s_waitcnt lgkmcnt(1)
	v_mfma_f32_16x16x32_bf16 v[102:105], v[200:203], v[148:151], v[102:105]
	v_mfma_f32_16x16x32_bf16 v[98:101], v[200:203], v[168:171], v[98:101]
	v_mfma_f32_16x16x32_bf16 v[126:129], v[180:183], v[152:155], v[126:129]
	v_mfma_f32_16x16x32_bf16 v[122:125], v[180:183], v[172:175], v[122:125]
	v_mfma_f32_16x16x32_bf16 v[118:121], v[188:191], v[152:155], v[118:121]
	v_mfma_f32_16x16x32_bf16 v[114:117], v[188:191], v[172:175], v[114:117]
	v_mfma_f32_16x16x32_bf16 v[110:113], v[196:199], v[152:155], v[110:113]
	v_mfma_f32_16x16x32_bf16 v[106:109], v[196:199], v[172:175], v[106:109]
	s_waitcnt lgkmcnt(0)
	v_mfma_f32_16x16x32_bf16 v[102:105], v[204:207], v[152:155], v[102:105]
	v_mfma_f32_16x16x32_bf16 v[98:101], v[204:207], v[172:175], v[98:101]
	s_setprio 0
	s_barrier
	ds_read_b128 v[164:167], v159
	ds_read_b128 v[208:211], v159 offset:1024
	ds_read_b128 v[212:215], v159 offset:2048
	ds_read_b128 v[156:159], v159 offset:3072
	s_barrier
	s_waitcnt lgkmcnt(0)
	s_setprio 1
	s_waitcnt lgkmcnt(3)
	v_mfma_f32_16x16x32_bf16 v[94:97], v[176:179], v[164:167], v[94:97]
	s_waitcnt lgkmcnt(1)
	v_mfma_f32_16x16x32_bf16 v[90:93], v[176:179], v[212:215], v[90:93]
	v_mfma_f32_16x16x32_bf16 v[86:89], v[184:187], v[164:167], v[86:89]
	v_mfma_f32_16x16x32_bf16 v[82:85], v[184:187], v[212:215], v[82:85]
	v_mfma_f32_16x16x32_bf16 v[78:81], v[192:195], v[164:167], v[78:81]
	v_mfma_f32_16x16x32_bf16 v[74:77], v[192:195], v[212:215], v[74:77]
	v_mfma_f32_16x16x32_bf16 v[70:73], v[200:203], v[164:167], v[70:73]
	v_mfma_f32_16x16x32_bf16 v[66:69], v[200:203], v[212:215], v[66:69]
	v_mfma_f32_16x16x32_bf16 v[94:97], v[180:183], v[208:211], v[94:97]
	s_waitcnt lgkmcnt(0)
	v_mfma_f32_16x16x32_bf16 v[90:93], v[180:183], v[156:159], v[90:93]
	v_mfma_f32_16x16x32_bf16 v[86:89], v[188:191], v[208:211], v[86:89]
	v_mfma_f32_16x16x32_bf16 v[82:85], v[188:191], v[156:159], v[82:85]
	v_mfma_f32_16x16x32_bf16 v[78:81], v[196:199], v[208:211], v[78:81]
	v_mfma_f32_16x16x32_bf16 v[74:77], v[196:199], v[156:159], v[74:77]
	v_mfma_f32_16x16x32_bf16 v[70:73], v[204:207], v[208:211], v[70:73]
	v_mfma_f32_16x16x32_bf16 v[66:69], v[204:207], v[156:159], v[66:69]
	s_setprio 0
	s_barrier
; #define LDA_(dst, b, h) _Pragma("unroll") for (int m = 0; m < 4; ++m) _Pragma("unroll") for (int k = 0; k < 2; ++k) \
;     dst[m][k] = *reinterpret_cast<const bf16x8*>((char*)SA(b, h) + lds_byte(wr * 64 + m * 16 + fr, k * 32 + fq * 8))
; #define LDB_(dst, b, h) _Pragma("unroll") for (int n = 0; n < 2; ++n) _Pragma("unroll") for (int k = 0; k < 2; ++k) \
;     dst[n][k] = *reinterpret_cast<const bf16x8*>((char*)SB(b, h) + lds_byte(wc * 32 + n * 16 + fr, k * 32 + fq * 8))
; #define MMA(ai, bj, At, Bx) do { __builtin_amdgcn_s_setprio(1); \
;     _Pragma("unroll") for (int m = 0; m < 4; ++m) _Pragma("unroll") for (int n = 0; n < 2; ++n) _Pragma("unroll") for (int k = 0; k < 2; ++k) \
;       acc[ai][bj][m][n] = __builtin_amdgcn_mfma_f32_16x16x32_bf16(At[m][k], Bx[n][k], acc[ai][bj][m][n], 0, 0, 0); \
;     __builtin_amdgcn_s_setprio(0); } while (0)
; #define WAIT_V(n) asm volatile("s_waitcnt vmcnt(" #n ")" ::: "memory")
; #define WAIT_L(n) asm volatile("s_waitcnt lgkmcnt(" #n ")" ::: "memory")
; #define BAR __builtin_amdgcn_s_barrier()
; template <int K, int LDA, int LDB>
; DEVI void gemm_tile(const bf16* __restrict__ A, const bf16* __restrict__ Bt, bf16* shm, acc_t& acc) {
;     ...
;     LDA_(At, 0, 1); WAIT_V(4); BAR; WAIT_L(0); MMA(1, 0, At, B0); MMA(1, 1, At, B1); BAR; }
;   { LDB_(B0, 1, 0); LDA_(At, 1, 0); WAIT_V(2); BAR; WAIT_L(0); MMA(0, 0, At, B0); BAR;
	ds_read_b128 v[176:179], v135 offset:16384
	ds_read_b128 v[180:183], v135 offset:17408
	ds_read_b128 v[184:187], v134 offset:16384
	ds_read_b128 v[188:191], v134 offset:17408
	ds_read_b128 v[192:195], v133 offset:16384
	ds_read_b128 v[196:199], v133 offset:17408
	ds_read_b128 v[200:203], v132 offset:16384
	ds_read_b128 v[204:207], v132 offset:17408
	s_waitcnt vmcnt(4)
	s_barrier
	s_waitcnt lgkmcnt(0)
	s_setprio 1
	s_waitcnt lgkmcnt(7)
	v_mfma_f32_16x16x32_bf16 v[62:65], v[176:179], v[148:151], v[62:65]
	v_mfma_f32_16x16x32_bf16 v[58:61], v[176:179], v[168:171], v[58:61]
	s_waitcnt lgkmcnt(5)
	v_mfma_f32_16x16x32_bf16 v[54:57], v[184:187], v[148:151], v[54:57]
	v_mfma_f32_16x16x32_bf16 v[50:53], v[184:187], v[168:171], v[50:53]
	s_waitcnt lgkmcnt(3)
	v_mfma_f32_16x16x32_bf16 v[46:49], v[192:195], v[148:151], v[46:49]
	v_mfma_f32_16x16x32_bf16 v[42:45], v[192:195], v[168:171], v[42:45]
	s_waitcnt lgkmcnt(1)
	v_mfma_f32_16x16x32_bf16 v[38:41], v[200:203], v[148:151], v[38:41]
	v_mfma_f32_16x16x32_bf16 v[34:37], v[200:203], v[168:171], v[34:37]
	v_mfma_f32_16x16x32_bf16 v[62:65], v[180:183], v[152:155], v[62:65]
	v_mfma_f32_16x16x32_bf16 v[58:61], v[180:183], v[172:175], v[58:61]
	v_mfma_f32_16x16x32_bf16 v[54:57], v[188:191], v[152:155], v[54:57]
	v_mfma_f32_16x16x32_bf16 v[50:53], v[188:191], v[172:175], v[50:53]
	v_mfma_f32_16x16x32_bf16 v[46:49], v[196:199], v[152:155], v[46:49]
	v_mfma_f32_16x16x32_bf16 v[42:45], v[196:199], v[172:175], v[42:45]
	s_waitcnt lgkmcnt(0)
	v_mfma_f32_16x16x32_bf16 v[38:41], v[204:207], v[152:155], v[38:41]
	v_mfma_f32_16x16x32_bf16 v[34:37], v[204:207], v[172:175], v[34:37]
	s_setprio 0
	s_setprio 1
	v_mfma_f32_16x16x32_bf16 v[30:33], v[176:179], v[164:167], v[30:33]
	v_mfma_f32_16x16x32_bf16 v[26:29], v[176:179], v[212:215], v[26:29]
	v_mfma_f32_16x16x32_bf16 v[22:25], v[184:187], v[164:167], v[22:25]
	v_mfma_f32_16x16x32_bf16 v[18:21], v[184:187], v[212:215], v[18:21]
	v_mfma_f32_16x16x32_bf16 v[14:17], v[192:195], v[164:167], v[14:17]
	v_mfma_f32_16x16x32_bf16 v[10:13], v[192:195], v[212:215], v[10:13]
	v_mfma_f32_16x16x32_bf16 v[6:9], v[200:203], v[164:167], v[6:9]
	v_mfma_f32_16x16x32_bf16 v[2:5], v[200:203], v[212:215], v[2:5]
	v_mfma_f32_16x16x32_bf16 v[30:33], v[180:183], v[208:211], v[30:33]
	v_mfma_f32_16x16x32_bf16 v[26:29], v[180:183], v[156:159], v[26:29]
	v_mfma_f32_16x16x32_bf16 v[22:25], v[188:191], v[208:211], v[22:25]
	v_mfma_f32_16x16x32_bf16 v[18:21], v[188:191], v[156:159], v[18:21]
	v_mfma_f32_16x16x32_bf16 v[14:17], v[196:199], v[208:211], v[14:17]
	v_mfma_f32_16x16x32_bf16 v[10:13], v[196:199], v[156:159], v[10:13]
	v_mfma_f32_16x16x32_bf16 v[6:9], v[204:207], v[208:211], v[6:9]
	v_mfma_f32_16x16x32_bf16 v[2:5], v[204:207], v[156:159], v[2:5]
	s_setprio 0
	s_barrier
	ds_read_b128 v[148:151], v147
	ds_read_b128 v[152:155], v147 offset:1024
	ds_read_b128 v[156:159], v147 offset:2048
	ds_read_b128 v[164:167], v147 offset:3072
	ds_read_b128 v[168:171], v135 offset:32768
	ds_read_b128 v[172:175], v135 offset:33792
	ds_read_b128 v[176:179], v134 offset:32768
	ds_read_b128 v[180:183], v134 offset:33792
	ds_read_b128 v[184:187], v133 offset:32768
	ds_read_b128 v[188:191], v133 offset:33792
	ds_read_b128 v[192:195], v132 offset:32768
	ds_read_b128 v[196:199], v132 offset:33792
	s_waitcnt vmcnt(2)
	s_barrier
	s_waitcnt lgkmcnt(0)
	s_setprio 1
	s_waitcnt lgkmcnt(7)
	v_mfma_f32_16x16x32_bf16 v[126:129], v[168:171], v[148:151], v[126:129]
	v_mfma_f32_16x16x32_bf16 v[122:125], v[168:171], v[156:159], v[122:125]
	s_waitcnt lgkmcnt(5)
	v_mfma_f32_16x16x32_bf16 v[118:121], v[176:179], v[148:151], v[118:121]
	v_mfma_f32_16x16x32_bf16 v[114:117], v[176:179], v[156:159], v[114:117]
	s_waitcnt lgkmcnt(3)
	v_mfma_f32_16x16x32_bf16 v[110:113], v[184:187], v[148:151], v[110:113]
	v_mfma_f32_16x16x32_bf16 v[106:109], v[184:187], v[156:159], v[106:109]
	s_waitcnt lgkmcnt(1)
	v_mfma_f32_16x16x32_bf16 v[102:105], v[192:195], v[148:151], v[102:105]
	v_mfma_f32_16x16x32_bf16 v[98:101], v[192:195], v[156:159], v[98:101]
	v_mfma_f32_16x16x32_bf16 v[126:129], v[172:175], v[152:155], v[126:129]
	v_mfma_f32_16x16x32_bf16 v[122:125], v[172:175], v[164:167], v[122:125]
	v_mfma_f32_16x16x32_bf16 v[118:121], v[180:183], v[152:155], v[118:121]
	v_mfma_f32_16x16x32_bf16 v[114:117], v[180:183], v[164:167], v[114:117]
	v_mfma_f32_16x16x32_bf16 v[110:113], v[188:191], v[152:155], v[110:113]
	v_mfma_f32_16x16x32_bf16 v[106:109], v[188:191], v[164:167], v[106:109]
	s_waitcnt lgkmcnt(0)
	v_mfma_f32_16x16x32_bf16 v[102:105], v[196:199], v[152:155], v[102:105]
	v_mfma_f32_16x16x32_bf16 v[98:101], v[196:199], v[164:167], v[98:101]
	s_setprio 0
	s_barrier
; #define LDA_(dst, b, h) _Pragma("unroll") for (int m = 0; m < 4; ++m) _Pragma("unroll") for (int k = 0; k < 2; ++k) \
;     dst[m][k] = *reinterpret_cast<const bf16x8*>((char*)SA(b, h) + lds_byte(wr * 64 + m * 16 + fr, k * 32 + fq * 8))
; #define LDB_(dst, b, h) _Pragma("unroll") for (int n = 0; n < 2; ++n) _Pragma("unroll") for (int k = 0; k < 2; ++k) \
;     dst[n][k] = *reinterpret_cast<const bf16x8*>((char*)SB(b, h) + lds_byte(wc * 32 + n * 16 + fr, k * 32 + fq * 8))
; #define MMA(ai, bj, At, Bx) do { __builtin_amdgcn_s_setprio(1); \
;     _Pragma("unroll") for (int m = 0; m < 4; ++m) _Pragma("unroll") for (int n = 0; n < 2; ++n) _Pragma("unroll") for (int k = 0; k < 2; ++k) \
;       acc[ai][bj][m][n] = __builtin_amdgcn_mfma_f32_16x16x32_bf16(At[m][k], Bx[n][k], acc[ai][bj][m][n], 0, 0, 0); \
;     __builtin_amdgcn_s_setprio(0); } while (0)
; #define WAIT_V(n) asm volatile("s_waitcnt vmcnt(" #n ")" ::: "memory")
; #define WAIT_L(n) asm volatile("s_waitcnt lgkmcnt(" #n ")" ::: "memory")
; #define BAR __builtin_amdgcn_s_barrier()
; template <int K, int LDA, int LDB>
; DEVI void gemm_tile(const bf16* __restrict__ A, const bf16* __restrict__ Bt, bf16* shm, acc_t& acc) {
;     ...
;     LDB_(B1, 1, 1); WAIT_V(0); BAR; WAIT_L(0); MMA(0, 1, At, B1); BAR;
;     LDA_(At, 1, 1); BAR; WAIT_L(0); MMA(1, 0, At, B0); MMA(1, 1, At, B1); BAR; }
;   if (wr == 0) BAR;
	ds_read_b128 v[200:203], v145
	ds_read_b128 v[204:207], v145 offset:1024
	ds_read_b128 v[208:211], v145 offset:2048
	ds_read_b128 v[144:147], v145 offset:3072
	s_waitcnt vmcnt(0)
	s_barrier
	s_waitcnt lgkmcnt(0)
	s_setprio 1
	s_waitcnt lgkmcnt(3)
	v_mfma_f32_16x16x32_bf16 v[94:97], v[168:171], v[200:203], v[94:97]
	s_waitcnt lgkmcnt(1)
	v_mfma_f32_16x16x32_bf16 v[90:93], v[168:171], v[208:211], v[90:93]
	v_mfma_f32_16x16x32_bf16 v[86:89], v[176:179], v[200:203], v[86:89]
	v_mfma_f32_16x16x32_bf16 v[82:85], v[176:179], v[208:211], v[82:85]
	v_mfma_f32_16x16x32_bf16 v[78:81], v[184:187], v[200:203], v[78:81]
	v_mfma_f32_16x16x32_bf16 v[74:77], v[184:187], v[208:211], v[74:77]
	v_mfma_f32_16x16x32_bf16 v[70:73], v[192:195], v[200:203], v[70:73]
	v_mfma_f32_16x16x32_bf16 v[66:69], v[192:195], v[208:211], v[66:69]
	v_mfma_f32_16x16x32_bf16 v[94:97], v[172:175], v[204:207], v[94:97]
	s_waitcnt lgkmcnt(0)
	v_mfma_f32_16x16x32_bf16 v[90:93], v[172:175], v[144:147], v[90:93]
	v_mfma_f32_16x16x32_bf16 v[86:89], v[180:183], v[204:207], v[86:89]
	v_mfma_f32_16x16x32_bf16 v[82:85], v[180:183], v[144:147], v[82:85]
	v_mfma_f32_16x16x32_bf16 v[78:81], v[188:191], v[204:207], v[78:81]
	v_mfma_f32_16x16x32_bf16 v[74:77], v[188:191], v[144:147], v[74:77]
	v_mfma_f32_16x16x32_bf16 v[70:73], v[196:199], v[204:207], v[70:73]
	v_mfma_f32_16x16x32_bf16 v[66:69], v[196:199], v[144:147], v[66:69]
	s_setprio 0
	s_barrier
	ds_read_b128 v[168:171], v135 offset:49152
	ds_read_b128 v[172:175], v135 offset:50176
	ds_read_b128 v[176:179], v134 offset:49152
	ds_read_b128 v[180:183], v134 offset:50176
	ds_read_b128 v[184:187], v133 offset:49152
	ds_read_b128 v[188:191], v133 offset:50176
	ds_read_b128 v[192:195], v132 offset:49152
	ds_read_b128 v[132:135], v132 offset:50176
	s_barrier
	s_waitcnt lgkmcnt(0)
	s_setprio 1
	s_waitcnt lgkmcnt(7)
	v_mfma_f32_16x16x32_bf16 v[62:65], v[168:171], v[148:151], v[62:65]
	v_mfma_f32_16x16x32_bf16 v[58:61], v[168:171], v[156:159], v[58:61]
	s_waitcnt lgkmcnt(5)
	v_mfma_f32_16x16x32_bf16 v[54:57], v[176:179], v[148:151], v[54:57]
	v_mfma_f32_16x16x32_bf16 v[50:53], v[176:179], v[156:159], v[50:53]
	s_waitcnt lgkmcnt(3)
	v_mfma_f32_16x16x32_bf16 v[46:49], v[184:187], v[148:151], v[46:49]
	v_mfma_f32_16x16x32_bf16 v[42:45], v[184:187], v[156:159], v[42:45]
	s_waitcnt lgkmcnt(1)
	v_mfma_f32_16x16x32_bf16 v[38:41], v[192:195], v[148:151], v[38:41]
	v_mfma_f32_16x16x32_bf16 v[34:37], v[192:195], v[156:159], v[34:37]
	v_mfma_f32_16x16x32_bf16 v[62:65], v[172:175], v[152:155], v[62:65]
	v_mfma_f32_16x16x32_bf16 v[58:61], v[172:175], v[164:167], v[58:61]
	v_mfma_f32_16x16x32_bf16 v[54:57], v[180:183], v[152:155], v[54:57]
	v_mfma_f32_16x16x32_bf16 v[50:53], v[180:183], v[164:167], v[50:53]
	v_mfma_f32_16x16x32_bf16 v[46:49], v[188:191], v[152:155], v[46:49]
	v_mfma_f32_16x16x32_bf16 v[42:45], v[188:191], v[164:167], v[42:45]
	s_waitcnt lgkmcnt(0)
	v_mfma_f32_16x16x32_bf16 v[38:41], v[132:135], v[152:155], v[38:41]
	v_mfma_f32_16x16x32_bf16 v[34:37], v[132:135], v[164:167], v[34:37]
	s_setprio 0
	s_setprio 1
	v_mfma_f32_16x16x32_bf16 v[30:33], v[168:171], v[200:203], v[30:33]
	v_mfma_f32_16x16x32_bf16 v[26:29], v[168:171], v[208:211], v[26:29]
	v_mfma_f32_16x16x32_bf16 v[22:25], v[176:179], v[200:203], v[22:25]
	v_mfma_f32_16x16x32_bf16 v[18:21], v[176:179], v[208:211], v[18:21]
	v_mfma_f32_16x16x32_bf16 v[14:17], v[184:187], v[200:203], v[14:17]
	v_mfma_f32_16x16x32_bf16 v[10:13], v[184:187], v[208:211], v[10:13]
	v_mfma_f32_16x16x32_bf16 v[6:9], v[192:195], v[200:203], v[6:9]
	v_mfma_f32_16x16x32_bf16 v[2:5], v[192:195], v[208:211], v[2:5]
	v_mfma_f32_16x16x32_bf16 v[30:33], v[172:175], v[204:207], v[30:33]
	v_mfma_f32_16x16x32_bf16 v[26:29], v[172:175], v[144:147], v[26:29]
	v_mfma_f32_16x16x32_bf16 v[22:25], v[180:183], v[204:207], v[22:25]
	v_mfma_f32_16x16x32_bf16 v[18:21], v[180:183], v[144:147], v[18:21]
	v_mfma_f32_16x16x32_bf16 v[14:17], v[188:191], v[204:207], v[14:17]
	v_mfma_f32_16x16x32_bf16 v[10:13], v[188:191], v[144:147], v[10:13]
	v_mfma_f32_16x16x32_bf16 v[6:9], v[132:135], v[204:207], v[6:9]
	v_mfma_f32_16x16x32_bf16 v[2:5], v[132:135], v[144:147], v[2:5]
	s_setprio 0
	v_cmp_gt_u32_e32 vcc, s16, v130
	s_barrier
	s_and_saveexec_b64 s[2:3], vcc
	s_cbranch_execz .LBB0_564
	s_barrier

; #define STAGE(P, BASE, LD, br, kt) do { const int _so = (int)(((br) * (LD) + (kt) * BK) * 2); \
;     _Pragma("unroll") for (int _i = 0; _i < 2; ++_i) { \
;       __builtin_amdgcn_raw_ptr_buffer_load_lds(rs##BASE, (__attribute__((address_space(3))) unsigned*)((char*)(P) + tid_ * 16 + _i * 8192), 16, (int)off##LD[_i], _so, 0, 0); } } while (0)
; #define LDA_(dst, b, h) _Pragma("unroll") for (int m = 0; m < 4; ++m) _Pragma("unroll") for (int k = 0; k < 2; ++k) \
;     dst[m][k] = *reinterpret_cast<const bf16x8*>((char*)SA(b, h) + lds_byte(wr * 64 + m * 16 + fr, k * 32 + fq * 8))
; #define LDB_(dst, b, h) _Pragma("unroll") for (int n = 0; n < 2; ++n) _Pragma("unroll") for (int k = 0; k < 2; ++k) \
;     dst[n][k] = *reinterpret_cast<const bf16x8*>((char*)SB(b, h) + lds_byte(wc * 32 + n * 16 + fr, k * 32 + fq * 8))
; #define MMA(ai, bj, At, Bx) do { __builtin_amdgcn_s_setprio(1); \
;     _Pragma("unroll") for (int m = 0; m < 4; ++m) _Pragma("unroll") for (int n = 0; n < 2; ++n) _Pragma("unroll") for (int k = 0; k < 2; ++k) \
;       acc[ai][bj][m][n] = __builtin_amdgcn_mfma_f32_16x16x32_bf16(At[m][k], Bx[n][k], acc[ai][bj][m][n], 0, 0, 0); \
;     __builtin_amdgcn_s_setprio(0); } while (0)
; #define WAIT_L(n) asm volatile("s_waitcnt lgkmcnt(" #n ")" ::: "memory")
; #define BAR __builtin_amdgcn_s_barrier()
; #define SCHED __builtin_amdgcn_sched_barrier(0)
; template <int K, int LDA, int LDB>
; DEVI void gemm_tile(const bf16* __restrict__ A, const bf16* __restrict__ Bt, bf16* shm, acc_t& acc) {
;     ...
;     LDB_(B0, 0, 0); SCHED; LDA_(At, 0, 0); STAGE(SA(1, 1), A, LDA, HALF, t + 1);
;     WAIT_L(8); BAR; WAIT_L(0); MMA(0, 0, At, B0); BAR; SCHED;
;     LDB_(B1, 0, 1); STAGE(SB(0, 0), Bt, LDB, 0, t + 2);
;     BAR; WAIT_L(0); MMA(0, 1, At, B1); BAR;
;     LDA_(At, 0, 1); STAGE(SA(0, 0), A, LDA, 0, t + 2);
;     BAR; WAIT_L(0); MMA(1, 0, At, B0); BAR; SCHED;
.LBB0_1179:
	ds_read_b128 v[164:167], v160
	ds_read_b128 v[168:171], v160 offset:1024
	ds_read_b128 v[172:175], v160 offset:2048
	ds_read_b128 v[176:179], v160 offset:3072
	v_readfirstlane_b32 s41, v156
	s_add_i32 s40, s13, 0xffffff00
	s_mov_b32 m0, s41
	v_readfirstlane_b32 s41, v159
	ds_read_b128 v[180:183], v138
	ds_read_b128 v[184:187], v138 offset:1024
	ds_read_b128 v[188:191], v137
	ds_read_b128 v[192:195], v137 offset:1024
	ds_read_b128 v[196:199], v133
	ds_read_b128 v[200:203], v133 offset:1024
	ds_read_b128 v[204:207], v132
	ds_read_b128 v[208:211], v132 offset:1024
	buffer_load_dwordx4 v139, s[8:11], s40 offen lds
	s_mov_b32 m0, s41
	s_nop 0
	buffer_load_dwordx4 v141, s[8:11], s40 offen lds
	s_waitcnt lgkmcnt(8)
	s_barrier
	s_waitcnt lgkmcnt(0)
	s_setprio 1
	s_waitcnt lgkmcnt(7)
	v_mfma_f32_16x16x32_bf16 v[126:129], v[180:183], v[164:167], v[126:129]
	v_mfma_f32_16x16x32_bf16 v[122:125], v[180:183], v[172:175], v[122:125]
	s_waitcnt lgkmcnt(5)
	v_mfma_f32_16x16x32_bf16 v[118:121], v[188:191], v[164:167], v[118:121]
	v_mfma_f32_16x16x32_bf16 v[114:117], v[188:191], v[172:175], v[114:117]
	s_waitcnt lgkmcnt(3)
	v_mfma_f32_16x16x32_bf16 v[110:113], v[196:199], v[164:167], v[110:113]
	v_mfma_f32_16x16x32_bf16 v[106:109], v[196:199], v[172:175], v[106:109]
	s_waitcnt lgkmcnt(1)
	v_mfma_f32_16x16x32_bf16 v[102:105], v[204:207], v[164:167], v[102:105]
	v_mfma_f32_16x16x32_bf16 v[98:101], v[204:207], v[172:175], v[98:101]
	v_mfma_f32_16x16x32_bf16 v[126:129], v[184:187], v[168:171], v[126:129]
	v_mfma_f32_16x16x32_bf16 v[122:125], v[184:187], v[176:179], v[122:125]
	v_mfma_f32_16x16x32_bf16 v[118:121], v[192:195], v[168:171], v[118:121]
	v_mfma_f32_16x16x32_bf16 v[114:117], v[192:195], v[176:179], v[114:117]
	v_mfma_f32_16x16x32_bf16 v[110:113], v[200:203], v[168:171], v[110:113]
	v_mfma_f32_16x16x32_bf16 v[106:109], v[200:203], v[176:179], v[106:109]
	s_waitcnt lgkmcnt(0)
	v_mfma_f32_16x16x32_bf16 v[102:105], v[208:211], v[168:171], v[102:105]
	v_mfma_f32_16x16x32_bf16 v[98:101], v[208:211], v[176:179], v[98:101]
	s_setprio 0
	s_barrier
	v_readfirstlane_b32 s41, v143
	s_add_i32 s40, s13, 0xfff7ff80
	s_mov_b32 m0, s41
	v_readfirstlane_b32 s41, v144
	ds_read_b128 v[212:215], v154
	ds_read_b128 v[216:219], v154 offset:1024
	ds_read_b128 v[220:223], v154 offset:2048
	ds_read_b128 v[224:227], v154 offset:3072
	buffer_load_dwordx4 v139, s[0:3], s40 offen lds
	s_mov_b32 m0, s41
	s_nop 0
	buffer_load_dwordx4 v141, s[0:3], s40 offen lds
	s_barrier
	s_waitcnt lgkmcnt(0)
	s_setprio 1
	s_waitcnt lgkmcnt(3)
	v_mfma_f32_16x16x32_bf16 v[94:97], v[180:183], v[212:215], v[94:97]
	s_waitcnt lgkmcnt(1)
	v_mfma_f32_16x16x32_bf16 v[90:93], v[180:183], v[220:223], v[90:93]
	v_mfma_f32_16x16x32_bf16 v[86:89], v[188:191], v[212:215], v[86:89]
	v_mfma_f32_16x16x32_bf16 v[82:85], v[188:191], v[220:223], v[82:85]
	v_mfma_f32_16x16x32_bf16 v[78:81], v[196:199], v[212:215], v[78:81]
	v_mfma_f32_16x16x32_bf16 v[74:77], v[196:199], v[220:223], v[74:77]
	v_mfma_f32_16x16x32_bf16 v[70:73], v[204:207], v[212:215], v[70:73]
	v_mfma_f32_16x16x32_bf16 v[66:69], v[204:207], v[220:223], v[66:69]
	v_mfma_f32_16x16x32_bf16 v[94:97], v[184:187], v[216:219], v[94:97]
	s_waitcnt lgkmcnt(0)
	v_mfma_f32_16x16x32_bf16 v[90:93], v[184:187], v[224:227], v[90:93]
	v_mfma_f32_16x16x32_bf16 v[86:89], v[192:195], v[216:219], v[86:89]
	v_mfma_f32_16x16x32_bf16 v[82:85], v[192:195], v[224:227], v[82:85]
	v_mfma_f32_16x16x32_bf16 v[78:81], v[200:203], v[216:219], v[78:81]
	v_mfma_f32_16x16x32_bf16 v[74:77], v[200:203], v[224:227], v[74:77]
	v_mfma_f32_16x16x32_bf16 v[70:73], v[208:211], v[216:219], v[70:73]
	v_mfma_f32_16x16x32_bf16 v[66:69], v[208:211], v[224:227], v[66:69]
	s_setprio 0
	v_readfirstlane_b32 s41, v145
	s_mov_b32 m0, s41
	v_readfirstlane_b32 s41, v146
	s_barrier
	ds_read_b128 v[180:183], v138 offset:16384
	ds_read_b128 v[184:187], v138 offset:17408
	ds_read_b128 v[188:191], v137 offset:16384
	ds_read_b128 v[192:195], v137 offset:17408
	ds_read_b128 v[196:199], v133 offset:16384
	ds_read_b128 v[200:203], v133 offset:17408
	ds_read_b128 v[204:207], v132 offset:16384
	ds_read_b128 v[208:211], v132 offset:17408
	buffer_load_dwordx4 v139, s[8:11], s40 offen lds
	s_mov_b32 m0, s41
	s_nop 0
	buffer_load_dwordx4 v141, s[8:11], s40 offen lds
	s_barrier
	s_waitcnt lgkmcnt(0)
	s_setprio 1
	s_waitcnt lgkmcnt(7)
	v_mfma_f32_16x16x32_bf16 v[62:65], v[180:183], v[164:167], v[62:65]
	v_mfma_f32_16x16x32_bf16 v[58:61], v[180:183], v[172:175], v[58:61]
	s_waitcnt lgkmcnt(5)
	v_mfma_f32_16x16x32_bf16 v[54:57], v[188:191], v[164:167], v[54:57]
	v_mfma_f32_16x16x32_bf16 v[50:53], v[188:191], v[172:175], v[50:53]
	s_waitcnt lgkmcnt(3)
	v_mfma_f32_16x16x32_bf16 v[46:49], v[196:199], v[164:167], v[46:49]
	v_mfma_f32_16x16x32_bf16 v[42:45], v[196:199], v[172:175], v[42:45]
	s_waitcnt lgkmcnt(1)
	v_mfma_f32_16x16x32_bf16 v[38:41], v[204:207], v[164:167], v[38:41]
	v_mfma_f32_16x16x32_bf16 v[34:37], v[204:207], v[172:175], v[34:37]
	v_mfma_f32_16x16x32_bf16 v[62:65], v[184:187], v[168:171], v[62:65]
	v_mfma_f32_16x16x32_bf16 v[58:61], v[184:187], v[176:179], v[58:61]
	v_mfma_f32_16x16x32_bf16 v[54:57], v[192:195], v[168:171], v[54:57]
	v_mfma_f32_16x16x32_bf16 v[50:53], v[192:195], v[176:179], v[50:53]
	v_mfma_f32_16x16x32_bf16 v[46:49], v[200:203], v[168:171], v[46:49]
	v_mfma_f32_16x16x32_bf16 v[42:45], v[200:203], v[176:179], v[42:45]
	s_waitcnt lgkmcnt(0)
	v_mfma_f32_16x16x32_bf16 v[38:41], v[208:211], v[168:171], v[38:41]
	v_mfma_f32_16x16x32_bf16 v[34:37], v[208:211], v[176:179], v[34:37]
	s_setprio 0
	s_barrier
; #define STAGE(P, BASE, LD, br, kt) do { const int _so = (int)(((br) * (LD) + (kt) * BK) * 2); \
;     _Pragma("unroll") for (int _i = 0; _i < 2; ++_i) { \
;       __builtin_amdgcn_raw_ptr_buffer_load_lds(rs##BASE, (__attribute__((address_space(3))) unsigned*)((char*)(P) + tid_ * 16 + _i * 8192), 16, (int)off##LD[_i], _so, 0, 0); } } while (0)
; #define LDA_(dst, b, h) _Pragma("unroll") for (int m = 0; m < 4; ++m) _Pragma("unroll") for (int k = 0; k < 2; ++k) \
;     dst[m][k] = *reinterpret_cast<const bf16x8*>((char*)SA(b, h) + lds_byte(wr * 64 + m * 16 + fr, k * 32 + fq * 8))
; #define LDB_(dst, b, h) _Pragma("unroll") for (int n = 0; n < 2; ++n) _Pragma("unroll") for (int k = 0; k < 2; ++k) \
;     dst[n][k] = *reinterpret_cast<const bf16x8*>((char*)SB(b, h) + lds_byte(wc * 32 + n * 16 + fr, k * 32 + fq * 8))
; #define MMA(ai, bj, At, Bx) do { __builtin_amdgcn_s_setprio(1); \
;     _Pragma("unroll") for (int m = 0; m < 4; ++m) _Pragma("unroll") for (int n = 0; n < 2; ++n) _Pragma("unroll") for (int k = 0; k < 2; ++k) \
;       acc[ai][bj][m][n] = __builtin_amdgcn_mfma_f32_16x16x32_bf16(At[m][k], Bx[n][k], acc[ai][bj][m][n], 0, 0, 0); \
;     __builtin_amdgcn_s_setprio(0); } while (0)
; #define WAIT_V(n) asm volatile("s_waitcnt vmcnt(" #n ")" ::: "memory")
; #define WAIT_L(n) asm volatile("s_waitcnt lgkmcnt(" #n ")" ::: "memory")
; #define BAR __builtin_amdgcn_s_barrier()
; #define SCHED __builtin_amdgcn_sched_barrier(0)
; template <int K, int LDA, int LDB>
; DEVI void gemm_tile(const bf16* __restrict__ A, const bf16* __restrict__ Bt, bf16* shm, acc_t& acc) {
;     ...
;     STAGE(SB(0, 1), Bt, LDB, HALF, t + 2);
;     WAIT_V(6); BAR; MMA(1, 1, At, B1); BAR;
;     LDB_(B0, 1, 0); SCHED; LDA_(At, 1, 0); STAGE(SA(0, 1), A, LDA, HALF, t + 2);
;     WAIT_L(8); BAR; WAIT_L(0); MMA(0, 0, At, B0); BAR; SCHED;
;     LDB_(B1, 1, 1); STAGE(SB(1, 0), Bt, LDB, 0, t + 3);
;     BAR; WAIT_L(0); MMA(0, 1, At, B1); BAR;
;     LDA_(At, 1, 1); STAGE(SA(1, 0), A, LDA, 0, t + 3);
	v_readfirstlane_b32 s41, v147
	s_add_i32 s40, s13, 0xffffff80
	s_mov_b32 m0, s41
	v_readfirstlane_b32 s41, v148
	buffer_load_dwordx4 v139, s[0:3], s40 offen lds
	s_mov_b32 m0, s41
	s_nop 0
	buffer_load_dwordx4 v141, s[0:3], s40 offen lds
	s_waitcnt vmcnt(6)
	s_barrier
	s_setprio 1
	v_mfma_f32_16x16x32_bf16 v[30:33], v[180:183], v[212:215], v[30:33]
	v_mfma_f32_16x16x32_bf16 v[26:29], v[180:183], v[220:223], v[26:29]
	v_mfma_f32_16x16x32_bf16 v[22:25], v[188:191], v[212:215], v[22:25]
	v_mfma_f32_16x16x32_bf16 v[18:21], v[188:191], v[220:223], v[18:21]
	v_mfma_f32_16x16x32_bf16 v[14:17], v[196:199], v[212:215], v[14:17]
	v_mfma_f32_16x16x32_bf16 v[10:13], v[196:199], v[220:223], v[10:13]
	v_mfma_f32_16x16x32_bf16 v[6:9], v[204:207], v[212:215], v[6:9]
	v_mfma_f32_16x16x32_bf16 v[2:5], v[204:207], v[220:223], v[2:5]
	v_mfma_f32_16x16x32_bf16 v[30:33], v[184:187], v[216:219], v[30:33]
	v_mfma_f32_16x16x32_bf16 v[26:29], v[184:187], v[224:227], v[26:29]
	v_mfma_f32_16x16x32_bf16 v[22:25], v[192:195], v[216:219], v[22:25]
	v_mfma_f32_16x16x32_bf16 v[18:21], v[192:195], v[224:227], v[18:21]
	v_mfma_f32_16x16x32_bf16 v[14:17], v[200:203], v[216:219], v[14:17]
	v_mfma_f32_16x16x32_bf16 v[10:13], v[200:203], v[224:227], v[10:13]
	v_mfma_f32_16x16x32_bf16 v[6:9], v[208:211], v[216:219], v[6:9]
	v_mfma_f32_16x16x32_bf16 v[2:5], v[208:211], v[224:227], v[2:5]
	s_setprio 0
	s_barrier
	ds_read_b128 v[164:167], v142
	ds_read_b128 v[168:171], v142 offset:1024
	ds_read_b128 v[172:175], v142 offset:2048
	ds_read_b128 v[176:179], v142 offset:3072
	v_readfirstlane_b32 s41, v149
	s_mov_b32 m0, s41
	v_readfirstlane_b32 s41, v150
	ds_read_b128 v[180:183], v138 offset:32768
	ds_read_b128 v[184:187], v138 offset:33792
	ds_read_b128 v[188:191], v137 offset:32768
	ds_read_b128 v[192:195], v137 offset:33792
	ds_read_b128 v[196:199], v133 offset:32768
	ds_read_b128 v[200:203], v133 offset:33792
	ds_read_b128 v[204:207], v132 offset:32768
	ds_read_b128 v[208:211], v132 offset:33792
	buffer_load_dwordx4 v139, s[8:11], s40 offen lds
	s_mov_b32 m0, s41
	s_nop 0
	buffer_load_dwordx4 v141, s[8:11], s40 offen lds
	s_waitcnt lgkmcnt(8)
	s_barrier
	s_waitcnt lgkmcnt(0)
	s_setprio 1
	s_waitcnt lgkmcnt(7)
	v_mfma_f32_16x16x32_bf16 v[126:129], v[180:183], v[164:167], v[126:129]
	v_mfma_f32_16x16x32_bf16 v[122:125], v[180:183], v[172:175], v[122:125]
	s_waitcnt lgkmcnt(5)
	v_mfma_f32_16x16x32_bf16 v[118:121], v[188:191], v[164:167], v[118:121]
	v_mfma_f32_16x16x32_bf16 v[114:117], v[188:191], v[172:175], v[114:117]
	s_waitcnt lgkmcnt(3)
	v_mfma_f32_16x16x32_bf16 v[110:113], v[196:199], v[164:167], v[110:113]
	v_mfma_f32_16x16x32_bf16 v[106:109], v[196:199], v[172:175], v[106:109]
	s_waitcnt lgkmcnt(1)
	v_mfma_f32_16x16x32_bf16 v[102:105], v[204:207], v[164:167], v[102:105]
	v_mfma_f32_16x16x32_bf16 v[98:101], v[204:207], v[172:175], v[98:101]
	v_mfma_f32_16x16x32_bf16 v[126:129], v[184:187], v[168:171], v[126:129]
	v_mfma_f32_16x16x32_bf16 v[122:125], v[184:187], v[176:179], v[122:125]
	v_mfma_f32_16x16x32_bf16 v[118:121], v[192:195], v[168:171], v[118:121]
	v_mfma_f32_16x16x32_bf16 v[114:117], v[192:195], v[176:179], v[114:117]
	v_mfma_f32_16x16x32_bf16 v[110:113], v[200:203], v[168:171], v[110:113]
	v_mfma_f32_16x16x32_bf16 v[106:109], v[200:203], v[176:179], v[106:109]
	s_waitcnt lgkmcnt(0)
	v_mfma_f32_16x16x32_bf16 v[102:105], v[208:211], v[168:171], v[102:105]
	v_mfma_f32_16x16x32_bf16 v[98:101], v[208:211], v[176:179], v[98:101]
	s_setprio 0
	s_barrier
	v_readfirstlane_b32 s41, v151
	s_add_i32 s40, s13, 0xfff80000
	s_mov_b32 m0, s41
	v_readfirstlane_b32 s41, v152
	ds_read_b128 v[212:215], v140
	ds_read_b128 v[216:219], v140 offset:1024
	ds_read_b128 v[220:223], v140 offset:2048
	ds_read_b128 v[224:227], v140 offset:3072
	buffer_load_dwordx4 v139, s[0:3], s40 offen lds
	s_mov_b32 m0, s41
	s_nop 0
	buffer_load_dwordx4 v141, s[0:3], s40 offen lds
	s_barrier
	s_waitcnt lgkmcnt(0)
	s_setprio 1
	s_waitcnt lgkmcnt(3)
	v_mfma_f32_16x16x32_bf16 v[94:97], v[180:183], v[212:215], v[94:97]
	s_waitcnt lgkmcnt(1)
	v_mfma_f32_16x16x32_bf16 v[90:93], v[180:183], v[220:223], v[90:93]
	v_mfma_f32_16x16x32_bf16 v[86:89], v[188:191], v[212:215], v[86:89]
	v_mfma_f32_16x16x32_bf16 v[82:85], v[188:191], v[220:223], v[82:85]
	v_mfma_f32_16x16x32_bf16 v[78:81], v[196:199], v[212:215], v[78:81]
	v_mfma_f32_16x16x32_bf16 v[74:77], v[196:199], v[220:223], v[74:77]
	v_mfma_f32_16x16x32_bf16 v[70:73], v[204:207], v[212:215], v[70:73]
	v_mfma_f32_16x16x32_bf16 v[66:69], v[204:207], v[220:223], v[66:69]
	v_mfma_f32_16x16x32_bf16 v[94:97], v[184:187], v[216:219], v[94:97]
	s_waitcnt lgkmcnt(0)
	v_mfma_f32_16x16x32_bf16 v[90:93], v[184:187], v[224:227], v[90:93]
	v_mfma_f32_16x16x32_bf16 v[86:89], v[192:195], v[216:219], v[86:89]
	v_mfma_f32_16x16x32_bf16 v[82:85], v[192:195], v[224:227], v[82:85]
	v_mfma_f32_16x16x32_bf16 v[78:81], v[200:203], v[216:219], v[78:81]
	v_mfma_f32_16x16x32_bf16 v[74:77], v[200:203], v[224:227], v[74:77]
	v_mfma_f32_16x16x32_bf16 v[70:73], v[208:211], v[216:219], v[70:73]
	v_mfma_f32_16x16x32_bf16 v[66:69], v[208:211], v[224:227], v[66:69]
	s_setprio 0
	v_readfirstlane_b32 s41, v153
	s_mov_b32 m0, s41
	v_readfirstlane_b32 s41, v155
	s_barrier
	ds_read_b128 v[180:183], v138 offset:49152
	ds_read_b128 v[184:187], v138 offset:50176
	ds_read_b128 v[188:191], v137 offset:49152
	ds_read_b128 v[192:195], v137 offset:50176
	ds_read_b128 v[196:199], v133 offset:49152
	ds_read_b128 v[200:203], v133 offset:50176
	ds_read_b128 v[204:207], v132 offset:49152
	ds_read_b128 v[208:211], v132 offset:50176
	buffer_load_dwordx4 v139, s[8:11], s40 offen lds
	s_mov_b32 m0, s41
	s_nop 0
	buffer_load_dwordx4 v141, s[8:11], s40 offen lds
	s_barrier
; #define STAGE(P, BASE, LD, br, kt) do { const int _so = (int)(((br) * (LD) + (kt) * BK) * 2); \
;     _Pragma("unroll") for (int _i = 0; _i < 2; ++_i) { \
;       __builtin_amdgcn_raw_ptr_buffer_load_lds(rs##BASE, (__attribute__((address_space(3))) unsigned*)((char*)(P) + tid_ * 16 + _i * 8192), 16, (int)off##LD[_i], _so, 0, 0); } } while (0)
; #define LDA_(dst, b, h) _Pragma("unroll") for (int m = 0; m < 4; ++m) _Pragma("unroll") for (int k = 0; k < 2; ++k) \
;     dst[m][k] = *reinterpret_cast<const bf16x8*>((char*)SA(b, h) + lds_byte(wr * 64 + m * 16 + fr, k * 32 + fq * 8))
; #define LDB_(dst, b, h) _Pragma("unroll") for (int n = 0; n < 2; ++n) _Pragma("unroll") for (int k = 0; k < 2; ++k) \
;     dst[n][k] = *reinterpret_cast<const bf16x8*>((char*)SB(b, h) + lds_byte(wc * 32 + n * 16 + fr, k * 32 + fq * 8))
; #define MMA(ai, bj, At, Bx) do { __builtin_amdgcn_s_setprio(1); \
;     _Pragma("unroll") for (int m = 0; m < 4; ++m) _Pragma("unroll") for (int n = 0; n < 2; ++n) _Pragma("unroll") for (int k = 0; k < 2; ++k) \
;       acc[ai][bj][m][n] = __builtin_amdgcn_mfma_f32_16x16x32_bf16(At[m][k], Bx[n][k], acc[ai][bj][m][n], 0, 0, 0); \
;     __builtin_amdgcn_s_setprio(0); } while (0)
; #define WAIT_V(n) asm volatile("s_waitcnt vmcnt(" #n ")" ::: "memory")
; #define WAIT_L(n) asm volatile("s_waitcnt lgkmcnt(" #n ")" ::: "memory")
; #define BAR __builtin_amdgcn_s_barrier()
; #define SCHED __builtin_amdgcn_sched_barrier(0)
; template <int K, int LDA, int LDB>
; DEVI void gemm_tile(const bf16* __restrict__ A, const bf16* __restrict__ Bt, bf16* shm, acc_t& acc) {
;     ...
;     BAR; WAIT_L(0); MMA(1, 0, At, B0); BAR; SCHED;
;     STAGE(SB(1, 1), Bt, LDB, HALF, t + 3);
;     WAIT_V(6); BAR; MMA(1, 1, At, B1); BAR;
;   }
;   { LDB_(B0, 0, 0); LDA_(At, 0, 0); STAGE(SA(1, 1), A, LDA, HALF, nt - 1);
;     BAR; WAIT_L(0); MMA(0, 0, At, B0); BAR;
;     LDB_(B1, 0, 1); BAR; WAIT_L(0); MMA(0, 1, At, B1); BAR;
	s_waitcnt lgkmcnt(0)
	s_setprio 1
	s_waitcnt lgkmcnt(7)
	v_mfma_f32_16x16x32_bf16 v[62:65], v[180:183], v[164:167], v[62:65]
	v_mfma_f32_16x16x32_bf16 v[58:61], v[180:183], v[172:175], v[58:61]
	s_waitcnt lgkmcnt(5)
	v_mfma_f32_16x16x32_bf16 v[54:57], v[188:191], v[164:167], v[54:57]
	v_mfma_f32_16x16x32_bf16 v[50:53], v[188:191], v[172:175], v[50:53]
	s_waitcnt lgkmcnt(3)
	v_mfma_f32_16x16x32_bf16 v[46:49], v[196:199], v[164:167], v[46:49]
	v_mfma_f32_16x16x32_bf16 v[42:45], v[196:199], v[172:175], v[42:45]
	s_waitcnt lgkmcnt(1)
	v_mfma_f32_16x16x32_bf16 v[38:41], v[204:207], v[164:167], v[38:41]
	v_mfma_f32_16x16x32_bf16 v[34:37], v[204:207], v[172:175], v[34:37]
	v_mfma_f32_16x16x32_bf16 v[62:65], v[184:187], v[168:171], v[62:65]
	v_mfma_f32_16x16x32_bf16 v[58:61], v[184:187], v[176:179], v[58:61]
	v_mfma_f32_16x16x32_bf16 v[54:57], v[192:195], v[168:171], v[54:57]
	v_mfma_f32_16x16x32_bf16 v[50:53], v[192:195], v[176:179], v[50:53]
	v_mfma_f32_16x16x32_bf16 v[46:49], v[200:203], v[168:171], v[46:49]
	v_mfma_f32_16x16x32_bf16 v[42:45], v[200:203], v[176:179], v[42:45]
	s_waitcnt lgkmcnt(0)
	v_mfma_f32_16x16x32_bf16 v[38:41], v[208:211], v[168:171], v[38:41]
	v_mfma_f32_16x16x32_bf16 v[34:37], v[208:211], v[176:179], v[34:37]
	s_setprio 0
	s_barrier
	v_readfirstlane_b32 s40, v157
	s_mov_b32 m0, s40
	v_readfirstlane_b32 s40, v158
	buffer_load_dwordx4 v139, s[0:3], s13 offen lds
	s_mov_b32 m0, s40
	s_nop 0
	buffer_load_dwordx4 v141, s[0:3], s13 offen lds
	s_waitcnt vmcnt(6)
	s_barrier
	s_setprio 1
	v_mfma_f32_16x16x32_bf16 v[30:33], v[180:183], v[212:215], v[30:33]
	v_mfma_f32_16x16x32_bf16 v[26:29], v[180:183], v[220:223], v[26:29]
	v_mfma_f32_16x16x32_bf16 v[22:25], v[188:191], v[212:215], v[22:25]
	v_mfma_f32_16x16x32_bf16 v[18:21], v[188:191], v[220:223], v[18:21]
	v_mfma_f32_16x16x32_bf16 v[14:17], v[196:199], v[212:215], v[14:17]
	v_mfma_f32_16x16x32_bf16 v[10:13], v[196:199], v[220:223], v[10:13]
	v_mfma_f32_16x16x32_bf16 v[6:9], v[204:207], v[212:215], v[6:9]
	v_mfma_f32_16x16x32_bf16 v[2:5], v[204:207], v[220:223], v[2:5]
	v_mfma_f32_16x16x32_bf16 v[30:33], v[184:187], v[216:219], v[30:33]
	v_mfma_f32_16x16x32_bf16 v[26:29], v[184:187], v[224:227], v[26:29]
	v_mfma_f32_16x16x32_bf16 v[22:25], v[192:195], v[216:219], v[22:25]
	v_mfma_f32_16x16x32_bf16 v[18:21], v[192:195], v[224:227], v[18:21]
	v_mfma_f32_16x16x32_bf16 v[14:17], v[200:203], v[216:219], v[14:17]
	v_mfma_f32_16x16x32_bf16 v[10:13], v[200:203], v[224:227], v[10:13]
	v_mfma_f32_16x16x32_bf16 v[6:9], v[208:211], v[216:219], v[6:9]
	v_mfma_f32_16x16x32_bf16 v[2:5], v[208:211], v[224:227], v[2:5]
	s_setprio 0
	s_add_i32 s7, s7, 2
	s_addk_i32 s13, 0x100
	s_cmp_lt_u32 s7, 28
	s_cbranch_scc1 .Lrot_22108
	s_barrier
	v_readfirstlane_b32 s0, v156
	s_mov_b32 s10, s2
	s_mov_b32 s11, s3
	s_mov_b32 m0, s0
	v_readfirstlane_b32 s0, v159
	ds_read_b128 v[144:147], v160
	ds_read_b128 v[148:151], v160 offset:1024
	ds_read_b128 v[164:167], v160 offset:2048
	ds_read_b128 v[168:171], v160 offset:3072
	ds_read_b128 v[172:175], v138
	ds_read_b128 v[176:179], v138 offset:1024
	ds_read_b128 v[180:183], v137
	ds_read_b128 v[184:187], v137 offset:1024
	ds_read_b128 v[188:191], v133
	ds_read_b128 v[192:195], v133 offset:1024
	ds_read_b128 v[196:199], v132
	ds_read_b128 v[200:203], v132 offset:1024
	buffer_load_dwordx4 v139, s[8:11], s35 offen lds
	s_mov_b32 m0, s0
	s_nop 0
	buffer_load_dwordx4 v141, s[8:11], s35 offen lds
	s_barrier
	s_waitcnt lgkmcnt(0)
	s_setprio 1
	s_waitcnt lgkmcnt(7)
	v_mfma_f32_16x16x32_bf16 v[126:129], v[172:175], v[144:147], v[126:129]
	v_mfma_f32_16x16x32_bf16 v[122:125], v[172:175], v[164:167], v[122:125]
	s_waitcnt lgkmcnt(5)
	v_mfma_f32_16x16x32_bf16 v[118:121], v[180:183], v[144:147], v[118:121]
	v_mfma_f32_16x16x32_bf16 v[114:117], v[180:183], v[164:167], v[114:117]
	s_waitcnt lgkmcnt(3)
	v_mfma_f32_16x16x32_bf16 v[110:113], v[188:191], v[144:147], v[110:113]
	v_mfma_f32_16x16x32_bf16 v[106:109], v[188:191], v[164:167], v[106:109]
	s_waitcnt lgkmcnt(1)
	v_mfma_f32_16x16x32_bf16 v[102:105], v[196:199], v[144:147], v[102:105]
	v_mfma_f32_16x16x32_bf16 v[98:101], v[196:199], v[164:167], v[98:101]
	v_mfma_f32_16x16x32_bf16 v[126:129], v[176:179], v[148:151], v[126:129]
	v_mfma_f32_16x16x32_bf16 v[122:125], v[176:179], v[168:171], v[122:125]
	v_mfma_f32_16x16x32_bf16 v[118:121], v[184:187], v[148:151], v[118:121]
	v_mfma_f32_16x16x32_bf16 v[114:117], v[184:187], v[168:171], v[114:117]
	v_mfma_f32_16x16x32_bf16 v[110:113], v[192:195], v[148:151], v[110:113]
	v_mfma_f32_16x16x32_bf16 v[106:109], v[192:195], v[168:171], v[106:109]
	s_waitcnt lgkmcnt(0)
	v_mfma_f32_16x16x32_bf16 v[102:105], v[200:203], v[148:151], v[102:105]
	v_mfma_f32_16x16x32_bf16 v[98:101], v[200:203], v[168:171], v[98:101]
	s_setprio 0
	s_barrier
	ds_read_b128 v[156:159], v154
	ds_read_b128 v[204:207], v154 offset:1024
	ds_read_b128 v[208:211], v154 offset:2048
	ds_read_b128 v[152:155], v154 offset:3072
	s_barrier
	s_waitcnt lgkmcnt(0)
	s_setprio 1
	s_waitcnt lgkmcnt(3)
	v_mfma_f32_16x16x32_bf16 v[94:97], v[172:175], v[156:159], v[94:97]
	s_waitcnt lgkmcnt(1)
	v_mfma_f32_16x16x32_bf16 v[90:93], v[172:175], v[208:211], v[90:93]
	v_mfma_f32_16x16x32_bf16 v[86:89], v[180:183], v[156:159], v[86:89]
	v_mfma_f32_16x16x32_bf16 v[82:85], v[180:183], v[208:211], v[82:85]
	v_mfma_f32_16x16x32_bf16 v[78:81], v[188:191], v[156:159], v[78:81]
	v_mfma_f32_16x16x32_bf16 v[74:77], v[188:191], v[208:211], v[74:77]
	v_mfma_f32_16x16x32_bf16 v[70:73], v[196:199], v[156:159], v[70:73]
	v_mfma_f32_16x16x32_bf16 v[94:97], v[176:179], v[204:207], v[94:97]
	s_waitcnt lgkmcnt(0)
	v_mfma_f32_16x16x32_bf16 v[90:93], v[176:179], v[152:155], v[90:93]
	v_mfma_f32_16x16x32_bf16 v[86:89], v[184:187], v[204:207], v[86:89]
	v_mfma_f32_16x16x32_bf16 v[82:85], v[184:187], v[152:155], v[82:85]
	v_mfma_f32_16x16x32_bf16 v[78:81], v[192:195], v[204:207], v[78:81]
	v_mfma_f32_16x16x32_bf16 v[74:77], v[192:195], v[152:155], v[74:77]
	v_mfma_f32_16x16x32_bf16 v[70:73], v[200:203], v[204:207], v[70:73]
	v_mfma_f32_16x16x32_bf16 v[66:69], v[196:199], v[208:211], v[66:69]
	v_mfma_f32_16x16x32_bf16 v[172:175], v[200:203], v[152:155], v[66:69]
	s_setprio 0
	s_barrier
; #define LDA_(dst, b, h) _Pragma("unroll") for (int m = 0; m < 4; ++m) _Pragma("unroll") for (int k = 0; k < 2; ++k) \
;     dst[m][k] = *reinterpret_cast<const bf16x8*>((char*)SA(b, h) + lds_byte(wr * 64 + m * 16 + fr, k * 32 + fq * 8))
; #define LDB_(dst, b, h) _Pragma("unroll") for (int n = 0; n < 2; ++n) _Pragma("unroll") for (int k = 0; k < 2; ++k) \
;     dst[n][k] = *reinterpret_cast<const bf16x8*>((char*)SB(b, h) + lds_byte(wc * 32 + n * 16 + fr, k * 32 + fq * 8))
; #define MMA(ai, bj, At, Bx) do { __builtin_amdgcn_s_setprio(1); \
;     _Pragma("unroll") for (int m = 0; m < 4; ++m) _Pragma("unroll") for (int n = 0; n < 2; ++n) _Pragma("unroll") for (int k = 0; k < 2; ++k) \
;       acc[ai][bj][m][n] = __builtin_amdgcn_mfma_f32_16x16x32_bf16(At[m][k], Bx[n][k], acc[ai][bj][m][n], 0, 0, 0); \
;     __builtin_amdgcn_s_setprio(0); } while (0)
; #define WAIT_V(n) asm volatile("s_waitcnt vmcnt(" #n ")" ::: "memory")
; #define WAIT_L(n) asm volatile("s_waitcnt lgkmcnt(" #n ")" ::: "memory")
; #define BAR __builtin_amdgcn_s_barrier()
; template <int K, int LDA, int LDB>
; DEVI void gemm_tile(const bf16* __restrict__ A, const bf16* __restrict__ Bt, bf16* shm, acc_t& acc) {
;     ...
;     LDA_(At, 0, 1); WAIT_V(4); BAR; WAIT_L(0); MMA(1, 0, At, B0); MMA(1, 1, At, B1); BAR; }
;   { LDB_(B0, 1, 0); LDA_(At, 1, 0); WAIT_V(2); BAR; WAIT_L(0); MMA(0, 0, At, B0); BAR;
	s_nop 4
	ds_read_b128 v[66:69], v138 offset:16384
	ds_read_b128 v[176:179], v138 offset:17408
	ds_read_b128 v[180:183], v137 offset:16384
	ds_read_b128 v[184:187], v137 offset:17408
	ds_read_b128 v[188:191], v133 offset:16384
	ds_read_b128 v[192:195], v133 offset:17408
	ds_read_b128 v[196:199], v132 offset:16384
	ds_read_b128 v[200:203], v132 offset:17408
	s_waitcnt vmcnt(4)
	s_barrier
	s_waitcnt lgkmcnt(0)
	s_setprio 1
	s_waitcnt lgkmcnt(3)
	v_mfma_f32_16x16x32_bf16 v[42:45], v[188:191], v[164:167], v[42:45]
	s_waitcnt lgkmcnt(1)
	v_mfma_f32_16x16x32_bf16 v[38:41], v[196:199], v[144:147], v[38:41]
	v_mfma_f32_16x16x32_bf16 v[34:37], v[196:199], v[164:167], v[34:37]
	v_mfma_f32_16x16x32_bf16 v[62:65], v[66:69], v[144:147], v[62:65]
	v_mfma_f32_16x16x32_bf16 v[58:61], v[66:69], v[164:167], v[58:61]
	v_mfma_f32_16x16x32_bf16 v[54:57], v[180:183], v[144:147], v[54:57]
	v_mfma_f32_16x16x32_bf16 v[50:53], v[180:183], v[164:167], v[50:53]
	v_mfma_f32_16x16x32_bf16 v[46:49], v[188:191], v[144:147], v[46:49]
	v_mfma_f32_16x16x32_bf16 v[42:45], v[192:195], v[168:171], v[42:45]
	s_waitcnt lgkmcnt(0)
	v_mfma_f32_16x16x32_bf16 v[38:41], v[200:203], v[148:151], v[38:41]
	v_mfma_f32_16x16x32_bf16 v[34:37], v[200:203], v[168:171], v[34:37]
	v_mfma_f32_16x16x32_bf16 v[212:215], v[176:179], v[148:151], v[62:65]
	v_mfma_f32_16x16x32_bf16 v[216:219], v[176:179], v[168:171], v[58:61]
	v_mfma_f32_16x16x32_bf16 v[220:223], v[184:187], v[148:151], v[54:57]
	v_mfma_f32_16x16x32_bf16 v[224:227], v[184:187], v[168:171], v[50:53]
	v_mfma_f32_16x16x32_bf16 v[228:231], v[192:195], v[148:151], v[46:49]
	s_setprio 0
	s_setprio 1
	v_mfma_f32_16x16x32_bf16 v[26:29], v[66:69], v[208:211], v[26:29]
	v_mfma_f32_16x16x32_bf16 v[22:25], v[180:183], v[156:159], v[22:25]
	v_mfma_f32_16x16x32_bf16 v[18:21], v[180:183], v[208:211], v[18:21]
	v_mfma_f32_16x16x32_bf16 v[10:13], v[188:191], v[208:211], v[10:13]
	v_mfma_f32_16x16x32_bf16 v[6:9], v[196:199], v[156:159], v[6:9]
	v_mfma_f32_16x16x32_bf16 v[2:5], v[196:199], v[208:211], v[2:5]
	v_mfma_f32_16x16x32_bf16 v[30:33], v[66:69], v[156:159], v[30:33]
	v_mfma_f32_16x16x32_bf16 v[26:29], v[176:179], v[152:155], v[26:29]
	v_mfma_f32_16x16x32_bf16 v[22:25], v[184:187], v[204:207], v[22:25]
	v_mfma_f32_16x16x32_bf16 v[18:21], v[184:187], v[152:155], v[18:21]
	v_mfma_f32_16x16x32_bf16 v[14:17], v[188:191], v[156:159], v[14:17]
	v_mfma_f32_16x16x32_bf16 v[10:13], v[192:195], v[152:155], v[10:13]
	v_mfma_f32_16x16x32_bf16 v[6:9], v[200:203], v[204:207], v[6:9]
	v_mfma_f32_16x16x32_bf16 v[2:5], v[200:203], v[152:155], v[2:5]
	v_mfma_f32_16x16x32_bf16 v[144:147], v[176:179], v[204:207], v[30:33]
	v_mfma_f32_16x16x32_bf16 v[148:151], v[192:195], v[204:207], v[14:17]
	s_setprio 0
	s_barrier
	ds_read_b128 v[152:155], v142
	ds_read_b128 v[156:159], v142 offset:1024
	ds_read_b128 v[164:167], v142 offset:2048
	ds_read_b128 v[168:171], v142 offset:3072
	ds_read_b128 v[58:61], v138 offset:32768
	ds_read_b128 v[62:65], v138 offset:33792
	ds_read_b128 v[66:69], v137 offset:32768
	ds_read_b128 v[176:179], v137 offset:33792
	ds_read_b128 v[180:183], v133 offset:32768
	ds_read_b128 v[184:187], v133 offset:33792
	ds_read_b128 v[188:191], v132 offset:32768
	ds_read_b128 v[192:195], v132 offset:33792
	s_waitcnt vmcnt(2)
	s_barrier
	s_waitcnt lgkmcnt(0)
	s_setprio 1
	s_waitcnt lgkmcnt(7)
	v_mfma_f32_16x16x32_bf16 v[14:17], v[58:61], v[152:155], v[126:129]
	s_waitcnt lgkmcnt(5)
	v_mfma_f32_16x16x32_bf16 v[30:33], v[66:69], v[152:155], v[118:121]
	s_waitcnt lgkmcnt(3)
	v_mfma_f32_16x16x32_bf16 v[46:49], v[180:183], v[152:155], v[110:113]
	s_waitcnt lgkmcnt(1)
	v_mfma_f32_16x16x32_bf16 v[50:53], v[188:191], v[152:155], v[102:105]
	v_mfma_f32_16x16x32_bf16 v[126:129], v[62:65], v[156:159], v[14:17]
	v_mfma_f32_16x16x32_bf16 v[14:17], v[58:61], v[164:167], v[122:125]
	v_mfma_f32_16x16x32_bf16 v[122:125], v[176:179], v[156:159], v[30:33]
	v_mfma_f32_16x16x32_bf16 v[30:33], v[66:69], v[164:167], v[114:117]
	v_mfma_f32_16x16x32_bf16 v[118:121], v[184:187], v[156:159], v[46:49]
	v_mfma_f32_16x16x32_bf16 v[46:49], v[180:183], v[164:167], v[106:109]
	s_waitcnt lgkmcnt(0)
	v_mfma_f32_16x16x32_bf16 v[114:117], v[192:195], v[156:159], v[50:53]
	v_mfma_f32_16x16x32_bf16 v[50:53], v[188:191], v[164:167], v[98:101]
	v_mfma_f32_16x16x32_bf16 v[14:17], v[62:65], v[168:171], v[14:17]
	v_mfma_f32_16x16x32_bf16 v[30:33], v[176:179], v[168:171], v[30:33]
	v_mfma_f32_16x16x32_bf16 v[46:49], v[184:187], v[168:171], v[46:49]
	v_mfma_f32_16x16x32_bf16 v[54:57], v[192:195], v[168:171], v[50:53]
	s_setprio 0
	s_barrier
; #define LDA_(dst, b, h) _Pragma("unroll") for (int m = 0; m < 4; ++m) _Pragma("unroll") for (int k = 0; k < 2; ++k) \
;     dst[m][k] = *reinterpret_cast<const bf16x8*>((char*)SA(b, h) + lds_byte(wr * 64 + m * 16 + fr, k * 32 + fq * 8))
; #define LDB_(dst, b, h) _Pragma("unroll") for (int n = 0; n < 2; ++n) _Pragma("unroll") for (int k = 0; k < 2; ++k) \
;     dst[n][k] = *reinterpret_cast<const bf16x8*>((char*)SB(b, h) + lds_byte(wc * 32 + n * 16 + fr, k * 32 + fq * 8))
; #define MMA(ai, bj, At, Bx) do { __builtin_amdgcn_s_setprio(1); \
;     _Pragma("unroll") for (int m = 0; m < 4; ++m) _Pragma("unroll") for (int n = 0; n < 2; ++n) _Pragma("unroll") for (int k = 0; k < 2; ++k) \
;       acc[ai][bj][m][n] = __builtin_amdgcn_mfma_f32_16x16x32_bf16(At[m][k], Bx[n][k], acc[ai][bj][m][n], 0, 0, 0); \
;     __builtin_amdgcn_s_setprio(0); } while (0)
; #define WAIT_V(n) asm volatile("s_waitcnt vmcnt(" #n ")" ::: "memory")
; #define WAIT_L(n) asm volatile("s_waitcnt lgkmcnt(" #n ")" ::: "memory")
; #define BAR __builtin_amdgcn_s_barrier()
; template <int K, int LDA, int LDB>
; DEVI void gemm_tile(const bf16* __restrict__ A, const bf16* __restrict__ Bt, bf16* shm, acc_t& acc) {
;     ...
;     LDB_(B1, 1, 1); WAIT_V(0); BAR; WAIT_L(0); MMA(0, 1, At, B1); BAR;
;     LDA_(At, 1, 1); BAR; WAIT_L(0); MMA(1, 0, At, B0); MMA(1, 1, At, B1); BAR; }
;   if (wr == 0) BAR;
	ds_read_b128 v[196:199], v140
	ds_read_b128 v[200:203], v140 offset:1024
	ds_read_b128 v[204:207], v140 offset:2048
	ds_read_b128 v[140:143], v140 offset:3072
	s_waitcnt vmcnt(0)
	s_barrier
	s_waitcnt lgkmcnt(0)
	s_setprio 1
	s_waitcnt lgkmcnt(3)
	v_mfma_f32_16x16x32_bf16 v[50:53], v[58:61], v[196:199], v[94:97]
	s_waitcnt lgkmcnt(1)
	v_mfma_f32_16x16x32_bf16 v[58:61], v[58:61], v[204:207], v[90:93]
	v_mfma_f32_16x16x32_bf16 v[70:73], v[188:191], v[196:199], v[70:73]
	v_mfma_f32_16x16x32_bf16 v[50:53], v[62:65], v[200:203], v[50:53]
	s_waitcnt lgkmcnt(0)
	v_mfma_f32_16x16x32_bf16 v[58:61], v[62:65], v[140:143], v[58:61]
	v_mfma_f32_16x16x32_bf16 v[62:65], v[66:69], v[196:199], v[86:89]
	v_mfma_f32_16x16x32_bf16 v[66:69], v[66:69], v[204:207], v[82:85]
	v_mfma_f32_16x16x32_bf16 v[78:81], v[180:183], v[196:199], v[78:81]
	v_mfma_f32_16x16x32_bf16 v[74:77], v[180:183], v[204:207], v[74:77]
	v_mfma_f32_16x16x32_bf16 v[94:97], v[192:195], v[200:203], v[70:73]
	v_mfma_f32_16x16x32_bf16 v[70:73], v[188:191], v[204:207], v[172:175]
	v_mfma_f32_16x16x32_bf16 v[62:65], v[176:179], v[200:203], v[62:65]
	v_mfma_f32_16x16x32_bf16 v[66:69], v[176:179], v[140:143], v[66:69]
	v_mfma_f32_16x16x32_bf16 v[78:81], v[184:187], v[200:203], v[78:81]
	v_mfma_f32_16x16x32_bf16 v[82:85], v[184:187], v[140:143], v[74:77]
	v_mfma_f32_16x16x32_bf16 v[98:101], v[192:195], v[140:143], v[70:73]
	s_setprio 0
	s_barrier
	ds_read_b128 v[172:175], v138 offset:49152
	ds_read_b128 v[176:179], v138 offset:50176
	ds_read_b128 v[180:183], v137 offset:49152
	ds_read_b128 v[184:187], v137 offset:50176
	ds_read_b128 v[188:191], v133 offset:49152
	ds_read_b128 v[192:195], v133 offset:50176
	ds_read_b128 v[208:211], v132 offset:49152
	ds_read_b128 v[232:235], v132 offset:50176
	s_barrier
	s_waitcnt lgkmcnt(0)
	s_setprio 1
	s_waitcnt lgkmcnt(7)
	v_mfma_f32_16x16x32_bf16 v[70:73], v[172:175], v[152:155], v[212:215]
	s_waitcnt lgkmcnt(6)
	v_mfma_f32_16x16x32_bf16 v[110:113], v[176:179], v[156:159], v[70:73]
	v_mfma_f32_16x16x32_bf16 v[70:73], v[172:175], v[164:167], v[216:219]
	v_mfma_f32_16x16x32_bf16 v[106:109], v[176:179], v[168:171], v[70:73]
	s_waitcnt lgkmcnt(5)
	v_mfma_f32_16x16x32_bf16 v[70:73], v[180:183], v[152:155], v[220:223]
	s_waitcnt lgkmcnt(4)
	v_mfma_f32_16x16x32_bf16 v[102:105], v[184:187], v[156:159], v[70:73]
	v_mfma_f32_16x16x32_bf16 v[70:73], v[180:183], v[164:167], v[224:227]
	v_mfma_f32_16x16x32_bf16 v[90:93], v[184:187], v[168:171], v[70:73]
	s_waitcnt lgkmcnt(3)
	v_mfma_f32_16x16x32_bf16 v[70:73], v[188:191], v[152:155], v[228:231]
	v_mfma_f32_16x16x32_bf16 v[42:45], v[188:191], v[164:167], v[42:45]
	s_waitcnt lgkmcnt(1)
	v_mfma_f32_16x16x32_bf16 v[38:41], v[208:211], v[152:155], v[38:41]
	v_mfma_f32_16x16x32_bf16 v[34:37], v[208:211], v[164:167], v[34:37]
	v_mfma_f32_16x16x32_bf16 v[86:89], v[192:195], v[156:159], v[70:73]
	v_mfma_f32_16x16x32_bf16 v[74:77], v[192:195], v[168:171], v[42:45]
	s_waitcnt lgkmcnt(0)
	v_mfma_f32_16x16x32_bf16 v[70:73], v[232:235], v[156:159], v[38:41]
	v_mfma_f32_16x16x32_bf16 v[42:45], v[232:235], v[168:171], v[34:37]
	s_setprio 0
	s_setprio 1
	v_mfma_f32_16x16x32_bf16 v[34:37], v[172:175], v[196:199], v[144:147]
	v_mfma_f32_16x16x32_bf16 v[26:29], v[172:175], v[204:207], v[26:29]
	v_mfma_f32_16x16x32_bf16 v[22:25], v[180:183], v[196:199], v[22:25]
	v_mfma_f32_16x16x32_bf16 v[18:21], v[180:183], v[204:207], v[18:21]
	v_mfma_f32_16x16x32_bf16 v[38:41], v[176:179], v[200:203], v[34:37]
	v_mfma_f32_16x16x32_bf16 v[34:37], v[176:179], v[140:143], v[26:29]
	v_mfma_f32_16x16x32_bf16 v[26:29], v[184:187], v[200:203], v[22:25]
	v_mfma_f32_16x16x32_bf16 v[22:25], v[184:187], v[140:143], v[18:21]
	v_mfma_f32_16x16x32_bf16 v[18:21], v[188:191], v[196:199], v[148:151]
	v_mfma_f32_16x16x32_bf16 v[10:13], v[188:191], v[204:207], v[10:13]
	v_mfma_f32_16x16x32_bf16 v[6:9], v[208:211], v[196:199], v[6:9]
	v_mfma_f32_16x16x32_bf16 v[2:5], v[208:211], v[204:207], v[2:5]
	v_mfma_f32_16x16x32_bf16 v[18:21], v[192:195], v[200:203], v[18:21]
	v_mfma_f32_16x16x32_bf16 v[10:13], v[192:195], v[140:143], v[10:13]
	v_mfma_f32_16x16x32_bf16 v[6:9], v[232:235], v[200:203], v[6:9]
	v_mfma_f32_16x16x32_bf16 v[2:5], v[232:235], v[140:143], v[2:5]
	s_setprio 0
	s_movk_i32 s0, 0x100
	v_cmp_gt_u32_e32 vcc, s0, v130
	s_barrier
	s_and_saveexec_b64 s[0:1], vcc
	s_cbranch_execz .LBB0_1182
	s_barrier

; #define STAGE(P, BASE, LD, br, kt) do { const int _so = (int)(((br) * (LD) + (kt) * BK) * 2); \
;     _Pragma("unroll") for (int _i = 0; _i < 2; ++_i) { \
;       __builtin_amdgcn_raw_ptr_buffer_load_lds(rs##BASE, (__attribute__((address_space(3))) unsigned*)((char*)(P) + tid_ * 16 + _i * 8192), 16, (int)off##LD[_i], _so, 0, 0); } } while (0)
; #define LDA_(dst, b, h) _Pragma("unroll") for (int m = 0; m < 4; ++m) _Pragma("unroll") for (int k = 0; k < 2; ++k) \
;     dst[m][k] = *reinterpret_cast<const bf16x8*>((char*)SA(b, h) + lds_byte(wr * 64 + m * 16 + fr, k * 32 + fq * 8))
; #define LDB_(dst, b, h) _Pragma("unroll") for (int n = 0; n < 2; ++n) _Pragma("unroll") for (int k = 0; k < 2; ++k) \
;     dst[n][k] = *reinterpret_cast<const bf16x8*>((char*)SB(b, h) + lds_byte(wc * 32 + n * 16 + fr, k * 32 + fq * 8))
; #define MMA(ai, bj, At, Bx) do { __builtin_amdgcn_s_setprio(1); \
;     _Pragma("unroll") for (int m = 0; m < 4; ++m) _Pragma("unroll") for (int n = 0; n < 2; ++n) _Pragma("unroll") for (int k = 0; k < 2; ++k) \
;       acc[ai][bj][m][n] = __builtin_amdgcn_mfma_f32_16x16x32_bf16(At[m][k], Bx[n][k], acc[ai][bj][m][n], 0, 0, 0); \
;     __builtin_amdgcn_s_setprio(0); } while (0)
; #define WAIT_L(n) asm volatile("s_waitcnt lgkmcnt(" #n ")" ::: "memory")
; #define BAR __builtin_amdgcn_s_barrier()
; #define SCHED __builtin_amdgcn_sched_barrier(0)
; template <int K, int LDA, int LDB>
; DEVI void gemm_tile(const bf16* __restrict__ A, const bf16* __restrict__ Bt, bf16* shm, acc_t& acc) {
;     ...
;     LDB_(B0, 0, 0); SCHED; LDA_(At, 0, 0); STAGE(SA(1, 1), A, LDA, HALF, t + 1);
;     WAIT_L(8); BAR; WAIT_L(0); MMA(0, 0, At, B0); BAR; SCHED;
;     LDB_(B1, 0, 1); STAGE(SB(0, 0), Bt, LDB, 0, t + 2);
;     BAR; WAIT_L(0); MMA(0, 1, At, B1); BAR;
;     LDA_(At, 0, 1); STAGE(SA(0, 0), A, LDA, 0, t + 2);
;     BAR; WAIT_L(0); MMA(1, 0, At, B0); BAR; SCHED;
.LBB0_1230:
	ds_read_b128 v[166:169], v164
	ds_read_b128 v[170:173], v164 offset:1024
	ds_read_b128 v[174:177], v164 offset:2048
	ds_read_b128 v[178:181], v164 offset:3072
	v_readfirstlane_b32 s44, v158
	s_add_i32 s43, s15, 0xffffff00
	s_mov_b32 m0, s44
	v_readfirstlane_b32 s44, v161
	ds_read_b128 v[182:185], v135
	ds_read_b128 v[186:189], v135 offset:1024
	ds_read_b128 v[190:193], v134
	ds_read_b128 v[194:197], v134 offset:1024
	ds_read_b128 v[198:201], v133
	ds_read_b128 v[202:205], v133 offset:1024
	ds_read_b128 v[206:209], v132
	ds_read_b128 v[210:213], v132 offset:1024
	buffer_load_dwordx4 v141, s[8:11], s43 offen lds
	s_mov_b32 m0, s44
	s_nop 0
	buffer_load_dwordx4 v143, s[8:11], s43 offen lds
	s_waitcnt lgkmcnt(8)
	s_barrier
	s_waitcnt lgkmcnt(0)
	s_setprio 1
	s_waitcnt lgkmcnt(7)
	v_mfma_f32_16x16x32_bf16 v[126:129], v[182:185], v[166:169], v[126:129]
	v_mfma_f32_16x16x32_bf16 v[122:125], v[182:185], v[174:177], v[122:125]
	s_waitcnt lgkmcnt(5)
	v_mfma_f32_16x16x32_bf16 v[118:121], v[190:193], v[166:169], v[118:121]
	v_mfma_f32_16x16x32_bf16 v[114:117], v[190:193], v[174:177], v[114:117]
	s_waitcnt lgkmcnt(3)
	v_mfma_f32_16x16x32_bf16 v[110:113], v[198:201], v[166:169], v[110:113]
	v_mfma_f32_16x16x32_bf16 v[106:109], v[198:201], v[174:177], v[106:109]
	s_waitcnt lgkmcnt(1)
	v_mfma_f32_16x16x32_bf16 v[102:105], v[206:209], v[166:169], v[102:105]
	v_mfma_f32_16x16x32_bf16 v[98:101], v[206:209], v[174:177], v[98:101]
	v_mfma_f32_16x16x32_bf16 v[126:129], v[186:189], v[170:173], v[126:129]
	v_mfma_f32_16x16x32_bf16 v[122:125], v[186:189], v[178:181], v[122:125]
	v_mfma_f32_16x16x32_bf16 v[118:121], v[194:197], v[170:173], v[118:121]
	v_mfma_f32_16x16x32_bf16 v[114:117], v[194:197], v[178:181], v[114:117]
	v_mfma_f32_16x16x32_bf16 v[110:113], v[202:205], v[170:173], v[110:113]
	v_mfma_f32_16x16x32_bf16 v[106:109], v[202:205], v[178:181], v[106:109]
	s_waitcnt lgkmcnt(0)
	v_mfma_f32_16x16x32_bf16 v[102:105], v[210:213], v[170:173], v[102:105]
	v_mfma_f32_16x16x32_bf16 v[98:101], v[210:213], v[178:181], v[98:101]
	s_setprio 0
	s_barrier
	v_readfirstlane_b32 s44, v145
	s_add_i32 s43, s15, 0xfff7ff80
	s_mov_b32 m0, s44
	v_readfirstlane_b32 s44, v146
	ds_read_b128 v[214:217], v156
	ds_read_b128 v[218:221], v156 offset:1024
	ds_read_b128 v[222:225], v156 offset:2048
	ds_read_b128 v[226:229], v156 offset:3072
	buffer_load_dwordx4 v141, s[4:7], s43 offen lds
	s_mov_b32 m0, s44
	s_nop 0
	buffer_load_dwordx4 v143, s[4:7], s43 offen lds
	s_barrier
	s_waitcnt lgkmcnt(0)
	s_setprio 1
	s_waitcnt lgkmcnt(3)
	v_mfma_f32_16x16x32_bf16 v[94:97], v[182:185], v[214:217], v[94:97]
	s_waitcnt lgkmcnt(1)
	v_mfma_f32_16x16x32_bf16 v[90:93], v[182:185], v[222:225], v[90:93]
	v_mfma_f32_16x16x32_bf16 v[86:89], v[190:193], v[214:217], v[86:89]
	v_mfma_f32_16x16x32_bf16 v[82:85], v[190:193], v[222:225], v[82:85]
	v_mfma_f32_16x16x32_bf16 v[78:81], v[198:201], v[214:217], v[78:81]
	v_mfma_f32_16x16x32_bf16 v[74:77], v[198:201], v[222:225], v[74:77]
	v_mfma_f32_16x16x32_bf16 v[70:73], v[206:209], v[214:217], v[70:73]
	v_mfma_f32_16x16x32_bf16 v[66:69], v[206:209], v[222:225], v[66:69]
	v_mfma_f32_16x16x32_bf16 v[94:97], v[186:189], v[218:221], v[94:97]
	s_waitcnt lgkmcnt(0)
	v_mfma_f32_16x16x32_bf16 v[90:93], v[186:189], v[226:229], v[90:93]
	v_mfma_f32_16x16x32_bf16 v[86:89], v[194:197], v[218:221], v[86:89]
	v_mfma_f32_16x16x32_bf16 v[82:85], v[194:197], v[226:229], v[82:85]
	v_mfma_f32_16x16x32_bf16 v[78:81], v[202:205], v[218:221], v[78:81]
	v_mfma_f32_16x16x32_bf16 v[74:77], v[202:205], v[226:229], v[74:77]
	v_mfma_f32_16x16x32_bf16 v[70:73], v[210:213], v[218:221], v[70:73]
	v_mfma_f32_16x16x32_bf16 v[66:69], v[210:213], v[226:229], v[66:69]
	s_setprio 0
	v_readfirstlane_b32 s44, v147
	s_mov_b32 m0, s44
	v_readfirstlane_b32 s44, v148
	s_barrier
	ds_read_b128 v[182:185], v135 offset:16384
	ds_read_b128 v[186:189], v135 offset:17408
	ds_read_b128 v[190:193], v134 offset:16384
	ds_read_b128 v[194:197], v134 offset:17408
	ds_read_b128 v[198:201], v133 offset:16384
	ds_read_b128 v[202:205], v133 offset:17408
	ds_read_b128 v[206:209], v132 offset:16384
	ds_read_b128 v[210:213], v132 offset:17408
	buffer_load_dwordx4 v141, s[8:11], s43 offen lds
	s_mov_b32 m0, s44
	s_nop 0
	buffer_load_dwordx4 v143, s[8:11], s43 offen lds
	s_barrier
	s_waitcnt lgkmcnt(0)
	s_setprio 1
	s_waitcnt lgkmcnt(7)
	v_mfma_f32_16x16x32_bf16 v[62:65], v[182:185], v[166:169], v[62:65]
	v_mfma_f32_16x16x32_bf16 v[58:61], v[182:185], v[174:177], v[58:61]
	s_waitcnt lgkmcnt(5)
	v_mfma_f32_16x16x32_bf16 v[54:57], v[190:193], v[166:169], v[54:57]
	v_mfma_f32_16x16x32_bf16 v[50:53], v[190:193], v[174:177], v[50:53]
	s_waitcnt lgkmcnt(3)
	v_mfma_f32_16x16x32_bf16 v[46:49], v[198:201], v[166:169], v[46:49]
	v_mfma_f32_16x16x32_bf16 v[42:45], v[198:201], v[174:177], v[42:45]
	s_waitcnt lgkmcnt(1)
	v_mfma_f32_16x16x32_bf16 v[38:41], v[206:209], v[166:169], v[38:41]
	v_mfma_f32_16x16x32_bf16 v[34:37], v[206:209], v[174:177], v[34:37]
	v_mfma_f32_16x16x32_bf16 v[62:65], v[186:189], v[170:173], v[62:65]
	v_mfma_f32_16x16x32_bf16 v[58:61], v[186:189], v[178:181], v[58:61]
	v_mfma_f32_16x16x32_bf16 v[54:57], v[194:197], v[170:173], v[54:57]
	v_mfma_f32_16x16x32_bf16 v[50:53], v[194:197], v[178:181], v[50:53]
	v_mfma_f32_16x16x32_bf16 v[46:49], v[202:205], v[170:173], v[46:49]
	v_mfma_f32_16x16x32_bf16 v[42:45], v[202:205], v[178:181], v[42:45]
	s_waitcnt lgkmcnt(0)
	v_mfma_f32_16x16x32_bf16 v[38:41], v[210:213], v[170:173], v[38:41]
	v_mfma_f32_16x16x32_bf16 v[34:37], v[210:213], v[178:181], v[34:37]
	s_setprio 0
	s_barrier
; #define STAGE(P, BASE, LD, br, kt) do { const int _so = (int)(((br) * (LD) + (kt) * BK) * 2); \
;     _Pragma("unroll") for (int _i = 0; _i < 2; ++_i) { \
;       __builtin_amdgcn_raw_ptr_buffer_load_lds(rs##BASE, (__attribute__((address_space(3))) unsigned*)((char*)(P) + tid_ * 16 + _i * 8192), 16, (int)off##LD[_i], _so, 0, 0); } } while (0)
; #define LDA_(dst, b, h) _Pragma("unroll") for (int m = 0; m < 4; ++m) _Pragma("unroll") for (int k = 0; k < 2; ++k) \
;     dst[m][k] = *reinterpret_cast<const bf16x8*>((char*)SA(b, h) + lds_byte(wr * 64 + m * 16 + fr, k * 32 + fq * 8))
; #define LDB_(dst, b, h) _Pragma("unroll") for (int n = 0; n < 2; ++n) _Pragma("unroll") for (int k = 0; k < 2; ++k) \
;     dst[n][k] = *reinterpret_cast<const bf16x8*>((char*)SB(b, h) + lds_byte(wc * 32 + n * 16 + fr, k * 32 + fq * 8))
; #define MMA(ai, bj, At, Bx) do { __builtin_amdgcn_s_setprio(1); \
;     _Pragma("unroll") for (int m = 0; m < 4; ++m) _Pragma("unroll") for (int n = 0; n < 2; ++n) _Pragma("unroll") for (int k = 0; k < 2; ++k) \
;       acc[ai][bj][m][n] = __builtin_amdgcn_mfma_f32_16x16x32_bf16(At[m][k], Bx[n][k], acc[ai][bj][m][n], 0, 0, 0); \
;     __builtin_amdgcn_s_setprio(0); } while (0)
; #define WAIT_V(n) asm volatile("s_waitcnt vmcnt(" #n ")" ::: "memory")
; #define WAIT_L(n) asm volatile("s_waitcnt lgkmcnt(" #n ")" ::: "memory")
; #define BAR __builtin_amdgcn_s_barrier()
; #define SCHED __builtin_amdgcn_sched_barrier(0)
; template <int K, int LDA, int LDB>
; DEVI void gemm_tile(const bf16* __restrict__ A, const bf16* __restrict__ Bt, bf16* shm, acc_t& acc) {
;     ...
;     STAGE(SB(0, 1), Bt, LDB, HALF, t + 2);
;     WAIT_V(6); BAR; MMA(1, 1, At, B1); BAR;
;     LDB_(B0, 1, 0); SCHED; LDA_(At, 1, 0); STAGE(SA(0, 1), A, LDA, HALF, t + 2);
;     WAIT_L(8); BAR; WAIT_L(0); MMA(0, 0, At, B0); BAR; SCHED;
;     LDB_(B1, 1, 1); STAGE(SB(1, 0), Bt, LDB, 0, t + 3);
;     BAR; WAIT_L(0); MMA(0, 1, At, B1); BAR;
;     LDA_(At, 1, 1); STAGE(SA(1, 0), A, LDA, 0, t + 3);
;     BAR; WAIT_L(0); MMA(1, 0, At, B0); BAR; SCHED;
	v_readfirstlane_b32 s44, v149
	s_add_i32 s43, s15, 0xffffff80
	s_mov_b32 m0, s44
	v_readfirstlane_b32 s44, v150
	buffer_load_dwordx4 v141, s[4:7], s43 offen lds
	s_mov_b32 m0, s44
	s_nop 0
	buffer_load_dwordx4 v143, s[4:7], s43 offen lds
	s_waitcnt vmcnt(6)
	s_barrier
	s_setprio 1
	v_mfma_f32_16x16x32_bf16 v[30:33], v[182:185], v[214:217], v[30:33]
	v_mfma_f32_16x16x32_bf16 v[26:29], v[182:185], v[222:225], v[26:29]
	v_mfma_f32_16x16x32_bf16 v[22:25], v[190:193], v[214:217], v[22:25]
	v_mfma_f32_16x16x32_bf16 v[18:21], v[190:193], v[222:225], v[18:21]
	v_mfma_f32_16x16x32_bf16 v[14:17], v[198:201], v[214:217], v[14:17]
	v_mfma_f32_16x16x32_bf16 v[10:13], v[198:201], v[222:225], v[10:13]
	v_mfma_f32_16x16x32_bf16 v[6:9], v[206:209], v[214:217], v[6:9]
	v_mfma_f32_16x16x32_bf16 v[2:5], v[206:209], v[222:225], v[2:5]
	v_mfma_f32_16x16x32_bf16 v[30:33], v[186:189], v[218:221], v[30:33]
	v_mfma_f32_16x16x32_bf16 v[26:29], v[186:189], v[226:229], v[26:29]
	v_mfma_f32_16x16x32_bf16 v[22:25], v[194:197], v[218:221], v[22:25]
	v_mfma_f32_16x16x32_bf16 v[18:21], v[194:197], v[226:229], v[18:21]
	v_mfma_f32_16x16x32_bf16 v[14:17], v[202:205], v[218:221], v[14:17]
	v_mfma_f32_16x16x32_bf16 v[10:13], v[202:205], v[226:229], v[10:13]
	v_mfma_f32_16x16x32_bf16 v[6:9], v[210:213], v[218:221], v[6:9]
	v_mfma_f32_16x16x32_bf16 v[2:5], v[210:213], v[226:229], v[2:5]
	s_setprio 0
	s_barrier
	ds_read_b128 v[166:169], v144
	ds_read_b128 v[170:173], v144 offset:1024
	ds_read_b128 v[174:177], v144 offset:2048
	ds_read_b128 v[178:181], v144 offset:3072
	v_readfirstlane_b32 s44, v151
	s_mov_b32 m0, s44
	v_readfirstlane_b32 s44, v152
	ds_read_b128 v[182:185], v135 offset:32768
	ds_read_b128 v[186:189], v135 offset:33792
	ds_read_b128 v[190:193], v134 offset:32768
	ds_read_b128 v[194:197], v134 offset:33792
	ds_read_b128 v[198:201], v133 offset:32768
	ds_read_b128 v[202:205], v133 offset:33792
	ds_read_b128 v[206:209], v132 offset:32768
	ds_read_b128 v[210:213], v132 offset:33792
	buffer_load_dwordx4 v141, s[8:11], s43 offen lds
	s_mov_b32 m0, s44
	s_nop 0
	buffer_load_dwordx4 v143, s[8:11], s43 offen lds
	s_waitcnt lgkmcnt(8)
	s_barrier
	s_waitcnt lgkmcnt(0)
	s_setprio 1
	s_waitcnt lgkmcnt(7)
	v_mfma_f32_16x16x32_bf16 v[126:129], v[182:185], v[166:169], v[126:129]
	v_mfma_f32_16x16x32_bf16 v[122:125], v[182:185], v[174:177], v[122:125]
	s_waitcnt lgkmcnt(5)
	v_mfma_f32_16x16x32_bf16 v[118:121], v[190:193], v[166:169], v[118:121]
	v_mfma_f32_16x16x32_bf16 v[114:117], v[190:193], v[174:177], v[114:117]
	s_waitcnt lgkmcnt(3)
	v_mfma_f32_16x16x32_bf16 v[110:113], v[198:201], v[166:169], v[110:113]
	v_mfma_f32_16x16x32_bf16 v[106:109], v[198:201], v[174:177], v[106:109]
	s_waitcnt lgkmcnt(1)
	v_mfma_f32_16x16x32_bf16 v[102:105], v[206:209], v[166:169], v[102:105]
	v_mfma_f32_16x16x32_bf16 v[98:101], v[206:209], v[174:177], v[98:101]
	v_mfma_f32_16x16x32_bf16 v[126:129], v[186:189], v[170:173], v[126:129]
	v_mfma_f32_16x16x32_bf16 v[122:125], v[186:189], v[178:181], v[122:125]
	v_mfma_f32_16x16x32_bf16 v[118:121], v[194:197], v[170:173], v[118:121]
	v_mfma_f32_16x16x32_bf16 v[114:117], v[194:197], v[178:181], v[114:117]
	v_mfma_f32_16x16x32_bf16 v[110:113], v[202:205], v[170:173], v[110:113]
	v_mfma_f32_16x16x32_bf16 v[106:109], v[202:205], v[178:181], v[106:109]
	s_waitcnt lgkmcnt(0)
	v_mfma_f32_16x16x32_bf16 v[102:105], v[210:213], v[170:173], v[102:105]
	v_mfma_f32_16x16x32_bf16 v[98:101], v[210:213], v[178:181], v[98:101]
	s_setprio 0
	s_barrier
	v_readfirstlane_b32 s44, v153
	s_add_i32 s43, s15, 0xfff80000
	s_mov_b32 m0, s44
	v_readfirstlane_b32 s44, v154
	ds_read_b128 v[214:217], v142
	ds_read_b128 v[218:221], v142 offset:1024
	ds_read_b128 v[222:225], v142 offset:2048
	ds_read_b128 v[226:229], v142 offset:3072
	buffer_load_dwordx4 v141, s[4:7], s43 offen lds
	s_mov_b32 m0, s44
	s_nop 0
	buffer_load_dwordx4 v143, s[4:7], s43 offen lds
	s_barrier
	s_waitcnt lgkmcnt(0)
	s_setprio 1
	s_waitcnt lgkmcnt(3)
	v_mfma_f32_16x16x32_bf16 v[94:97], v[182:185], v[214:217], v[94:97]
	s_waitcnt lgkmcnt(1)
	v_mfma_f32_16x16x32_bf16 v[90:93], v[182:185], v[222:225], v[90:93]
	v_mfma_f32_16x16x32_bf16 v[86:89], v[190:193], v[214:217], v[86:89]
	v_mfma_f32_16x16x32_bf16 v[82:85], v[190:193], v[222:225], v[82:85]
	v_mfma_f32_16x16x32_bf16 v[78:81], v[198:201], v[214:217], v[78:81]
	v_mfma_f32_16x16x32_bf16 v[74:77], v[198:201], v[222:225], v[74:77]
	v_mfma_f32_16x16x32_bf16 v[70:73], v[206:209], v[214:217], v[70:73]
	v_mfma_f32_16x16x32_bf16 v[66:69], v[206:209], v[222:225], v[66:69]
	v_mfma_f32_16x16x32_bf16 v[94:97], v[186:189], v[218:221], v[94:97]
	s_waitcnt lgkmcnt(0)
	v_mfma_f32_16x16x32_bf16 v[90:93], v[186:189], v[226:229], v[90:93]
	v_mfma_f32_16x16x32_bf16 v[86:89], v[194:197], v[218:221], v[86:89]
	v_mfma_f32_16x16x32_bf16 v[82:85], v[194:197], v[226:229], v[82:85]
	v_mfma_f32_16x16x32_bf16 v[78:81], v[202:205], v[218:221], v[78:81]
	v_mfma_f32_16x16x32_bf16 v[74:77], v[202:205], v[226:229], v[74:77]
	v_mfma_f32_16x16x32_bf16 v[70:73], v[210:213], v[218:221], v[70:73]
	v_mfma_f32_16x16x32_bf16 v[66:69], v[210:213], v[226:229], v[66:69]
	s_setprio 0
	v_readfirstlane_b32 s44, v155
	s_mov_b32 m0, s44
	v_readfirstlane_b32 s44, v157
	s_barrier
	ds_read_b128 v[182:185], v135 offset:49152
	ds_read_b128 v[186:189], v135 offset:50176
	ds_read_b128 v[190:193], v134 offset:49152
	ds_read_b128 v[194:197], v134 offset:50176
	ds_read_b128 v[198:201], v133 offset:49152
	ds_read_b128 v[202:205], v133 offset:50176
	ds_read_b128 v[206:209], v132 offset:49152
	ds_read_b128 v[210:213], v132 offset:50176
	buffer_load_dwordx4 v141, s[8:11], s43 offen lds
	s_mov_b32 m0, s44
	s_nop 0
	buffer_load_dwordx4 v143, s[8:11], s43 offen lds
	s_barrier
; #define STAGE(P, BASE, LD, br, kt) do { const int _so = (int)(((br) * (LD) + (kt) * BK) * 2); \
;     _Pragma("unroll") for (int _i = 0; _i < 2; ++_i) { \
;       __builtin_amdgcn_raw_ptr_buffer_load_lds(rs##BASE, (__attribute__((address_space(3))) unsigned*)((char*)(P) + tid_ * 16 + _i * 8192), 16, (int)off##LD[_i], _so, 0, 0); } } while (0)
; #define LDA_(dst, b, h) _Pragma("unroll") for (int m = 0; m < 4; ++m) _Pragma("unroll") for (int k = 0; k < 2; ++k) \
;     dst[m][k] = *reinterpret_cast<const bf16x8*>((char*)SA(b, h) + lds_byte(wr * 64 + m * 16 + fr, k * 32 + fq * 8))
; #define LDB_(dst, b, h) _Pragma("unroll") for (int n = 0; n < 2; ++n) _Pragma("unroll") for (int k = 0; k < 2; ++k) \
;     dst[n][k] = *reinterpret_cast<const bf16x8*>((char*)SB(b, h) + lds_byte(wc * 32 + n * 16 + fr, k * 32 + fq * 8))
; #define MMA(ai, bj, At, Bx) do { __builtin_amdgcn_s_setprio(1); \
;     _Pragma("unroll") for (int m = 0; m < 4; ++m) _Pragma("unroll") for (int n = 0; n < 2; ++n) _Pragma("unroll") for (int k = 0; k < 2; ++k) \
;       acc[ai][bj][m][n] = __builtin_amdgcn_mfma_f32_16x16x32_bf16(At[m][k], Bx[n][k], acc[ai][bj][m][n], 0, 0, 0); \
;     __builtin_amdgcn_s_setprio(0); } while (0)
; #define WAIT_V(n) asm volatile("s_waitcnt vmcnt(" #n ")" ::: "memory")
; #define WAIT_L(n) asm volatile("s_waitcnt lgkmcnt(" #n ")" ::: "memory")
; #define BAR __builtin_amdgcn_s_barrier()
; #define SCHED __builtin_amdgcn_sched_barrier(0)
; template <int K, int LDA, int LDB>
; DEVI void gemm_tile(const bf16* __restrict__ A, const bf16* __restrict__ Bt, bf16* shm, acc_t& acc) {
;     ...
;     BAR; WAIT_L(0); MMA(1, 0, At, B0); BAR; SCHED;
;     STAGE(SB(1, 1), Bt, LDB, HALF, t + 3);
;     WAIT_V(6); BAR; MMA(1, 1, At, B1); BAR;
;   }
;   { LDB_(B0, 0, 0); LDA_(At, 0, 0); STAGE(SA(1, 1), A, LDA, HALF, nt - 1);
;     BAR; WAIT_L(0); MMA(0, 0, At, B0); BAR;
;     LDB_(B1, 0, 1); BAR; WAIT_L(0); MMA(0, 1, At, B1); BAR;
	s_waitcnt lgkmcnt(0)
	s_setprio 1
	s_waitcnt lgkmcnt(7)
	v_mfma_f32_16x16x32_bf16 v[62:65], v[182:185], v[166:169], v[62:65]
	v_mfma_f32_16x16x32_bf16 v[58:61], v[182:185], v[174:177], v[58:61]
	s_waitcnt lgkmcnt(5)
	v_mfma_f32_16x16x32_bf16 v[54:57], v[190:193], v[166:169], v[54:57]
	v_mfma_f32_16x16x32_bf16 v[50:53], v[190:193], v[174:177], v[50:53]
	s_waitcnt lgkmcnt(3)
	v_mfma_f32_16x16x32_bf16 v[46:49], v[198:201], v[166:169], v[46:49]
	v_mfma_f32_16x16x32_bf16 v[42:45], v[198:201], v[174:177], v[42:45]
	s_waitcnt lgkmcnt(1)
	v_mfma_f32_16x16x32_bf16 v[38:41], v[206:209], v[166:169], v[38:41]
	v_mfma_f32_16x16x32_bf16 v[34:37], v[206:209], v[174:177], v[34:37]
	v_mfma_f32_16x16x32_bf16 v[62:65], v[186:189], v[170:173], v[62:65]
	v_mfma_f32_16x16x32_bf16 v[58:61], v[186:189], v[178:181], v[58:61]
	v_mfma_f32_16x16x32_bf16 v[54:57], v[194:197], v[170:173], v[54:57]
	v_mfma_f32_16x16x32_bf16 v[50:53], v[194:197], v[178:181], v[50:53]
	v_mfma_f32_16x16x32_bf16 v[46:49], v[202:205], v[170:173], v[46:49]
	v_mfma_f32_16x16x32_bf16 v[42:45], v[202:205], v[178:181], v[42:45]
	s_waitcnt lgkmcnt(0)
	v_mfma_f32_16x16x32_bf16 v[38:41], v[210:213], v[170:173], v[38:41]
	v_mfma_f32_16x16x32_bf16 v[34:37], v[210:213], v[178:181], v[34:37]
	s_setprio 0
	s_barrier
	v_readfirstlane_b32 s43, v159
	s_mov_b32 m0, s43
	v_readfirstlane_b32 s43, v160
	buffer_load_dwordx4 v141, s[4:7], s15 offen lds
	s_mov_b32 m0, s43
	s_nop 0
	buffer_load_dwordx4 v143, s[4:7], s15 offen lds
	s_waitcnt vmcnt(6)
	s_barrier
	s_setprio 1
	v_mfma_f32_16x16x32_bf16 v[30:33], v[182:185], v[214:217], v[30:33]
	v_mfma_f32_16x16x32_bf16 v[26:29], v[182:185], v[222:225], v[26:29]
	v_mfma_f32_16x16x32_bf16 v[22:25], v[190:193], v[214:217], v[22:25]
	v_mfma_f32_16x16x32_bf16 v[18:21], v[190:193], v[222:225], v[18:21]
	v_mfma_f32_16x16x32_bf16 v[14:17], v[198:201], v[214:217], v[14:17]
	v_mfma_f32_16x16x32_bf16 v[10:13], v[198:201], v[222:225], v[10:13]
	v_mfma_f32_16x16x32_bf16 v[6:9], v[206:209], v[214:217], v[6:9]
	v_mfma_f32_16x16x32_bf16 v[2:5], v[206:209], v[222:225], v[2:5]
	v_mfma_f32_16x16x32_bf16 v[30:33], v[186:189], v[218:221], v[30:33]
	v_mfma_f32_16x16x32_bf16 v[26:29], v[186:189], v[226:229], v[26:29]
	v_mfma_f32_16x16x32_bf16 v[22:25], v[194:197], v[218:221], v[22:25]
	v_mfma_f32_16x16x32_bf16 v[18:21], v[194:197], v[226:229], v[18:21]
	v_mfma_f32_16x16x32_bf16 v[14:17], v[202:205], v[218:221], v[14:17]
	v_mfma_f32_16x16x32_bf16 v[10:13], v[202:205], v[226:229], v[10:13]
	v_mfma_f32_16x16x32_bf16 v[6:9], v[210:213], v[218:221], v[6:9]
	v_mfma_f32_16x16x32_bf16 v[2:5], v[210:213], v[226:229], v[2:5]
	s_setprio 0
	s_add_i32 s13, s13, 2
	s_addk_i32 s15, 0x100
	s_cmp_lt_u32 s13, 28
	s_cbranch_scc1 .Lrot_24683
	s_barrier
	v_readfirstlane_b32 s4, v158
	s_mov_b32 s10, s6
	s_mov_b32 s11, s7
	s_mov_b32 m0, s4
	v_readfirstlane_b32 s4, v161
	ds_read_b128 v[146:149], v164
	ds_read_b128 v[150:153], v164 offset:1024
	ds_read_b128 v[166:169], v164 offset:2048
	ds_read_b128 v[170:173], v164 offset:3072
	ds_read_b128 v[174:177], v135
	ds_read_b128 v[178:181], v135 offset:1024
	ds_read_b128 v[182:185], v134
	ds_read_b128 v[186:189], v134 offset:1024
	ds_read_b128 v[190:193], v133
	ds_read_b128 v[194:197], v133 offset:1024
	ds_read_b128 v[198:201], v132
	ds_read_b128 v[202:205], v132 offset:1024
	buffer_load_dwordx4 v141, s[8:11], s39 offen lds
	s_mov_b32 m0, s4
	s_nop 0
	buffer_load_dwordx4 v143, s[8:11], s39 offen lds
	s_barrier
	s_waitcnt lgkmcnt(0)
	s_setprio 1
	s_waitcnt lgkmcnt(7)
	v_mfma_f32_16x16x32_bf16 v[126:129], v[174:177], v[146:149], v[126:129]
	s_waitcnt lgkmcnt(5)
	v_mfma_f32_16x16x32_bf16 v[118:121], v[182:185], v[146:149], v[118:121]
	s_waitcnt lgkmcnt(3)
	v_mfma_f32_16x16x32_bf16 v[110:113], v[190:193], v[146:149], v[110:113]
	s_waitcnt lgkmcnt(1)
	v_mfma_f32_16x16x32_bf16 v[102:105], v[198:201], v[146:149], v[102:105]
	v_mfma_f32_16x16x32_bf16 v[126:129], v[178:181], v[150:153], v[126:129]
	v_mfma_f32_16x16x32_bf16 v[122:125], v[174:177], v[166:169], v[122:125]
	v_mfma_f32_16x16x32_bf16 v[118:121], v[186:189], v[150:153], v[118:121]
	v_mfma_f32_16x16x32_bf16 v[114:117], v[182:185], v[166:169], v[114:117]
	v_mfma_f32_16x16x32_bf16 v[110:113], v[194:197], v[150:153], v[110:113]
	v_mfma_f32_16x16x32_bf16 v[106:109], v[190:193], v[166:169], v[106:109]
	s_waitcnt lgkmcnt(0)
	v_mfma_f32_16x16x32_bf16 v[102:105], v[202:205], v[150:153], v[102:105]
	v_mfma_f32_16x16x32_bf16 v[98:101], v[198:201], v[166:169], v[98:101]
	v_mfma_f32_16x16x32_bf16 v[158:161], v[178:181], v[170:173], v[122:125]
	v_mfma_f32_16x16x32_bf16 v[206:209], v[186:189], v[170:173], v[114:117]
	v_mfma_f32_16x16x32_bf16 v[210:213], v[194:197], v[170:173], v[106:109]
	v_mfma_f32_16x16x32_bf16 v[214:217], v[202:205], v[170:173], v[98:101]
	s_setprio 0
	s_barrier
	s_nop 1
	ds_read_b128 v[98:101], v156
	ds_read_b128 v[106:109], v156 offset:1024
	ds_read_b128 v[114:117], v156 offset:2048
	ds_read_b128 v[122:125], v156 offset:3072
	s_barrier
	s_waitcnt lgkmcnt(0)
	s_setprio 1
	s_waitcnt lgkmcnt(3)
	v_mfma_f32_16x16x32_bf16 v[94:97], v[174:177], v[98:101], v[94:97]
	v_mfma_f32_16x16x32_bf16 v[86:89], v[182:185], v[98:101], v[86:89]
	v_mfma_f32_16x16x32_bf16 v[78:81], v[190:193], v[98:101], v[78:81]
	v_mfma_f32_16x16x32_bf16 v[70:73], v[198:201], v[98:101], v[70:73]
	s_waitcnt lgkmcnt(2)
	v_mfma_f32_16x16x32_bf16 v[94:97], v[178:181], v[106:109], v[94:97]
	s_waitcnt lgkmcnt(1)
	v_mfma_f32_16x16x32_bf16 v[90:93], v[174:177], v[114:117], v[90:93]
	v_mfma_f32_16x16x32_bf16 v[86:89], v[186:189], v[106:109], v[86:89]
	v_mfma_f32_16x16x32_bf16 v[82:85], v[182:185], v[114:117], v[82:85]
	v_mfma_f32_16x16x32_bf16 v[78:81], v[194:197], v[106:109], v[78:81]
	v_mfma_f32_16x16x32_bf16 v[74:77], v[190:193], v[114:117], v[74:77]
	v_mfma_f32_16x16x32_bf16 v[70:73], v[202:205], v[106:109], v[70:73]
	v_mfma_f32_16x16x32_bf16 v[66:69], v[198:201], v[114:117], v[66:69]
	s_waitcnt lgkmcnt(0)
	v_mfma_f32_16x16x32_bf16 v[154:157], v[178:181], v[122:125], v[90:93]
	v_mfma_f32_16x16x32_bf16 v[174:177], v[186:189], v[122:125], v[82:85]
	v_mfma_f32_16x16x32_bf16 v[178:181], v[194:197], v[122:125], v[74:77]
	v_mfma_f32_16x16x32_bf16 v[182:185], v[202:205], v[122:125], v[66:69]
	s_setprio 0
	s_barrier
; #define LDA_(dst, b, h) _Pragma("unroll") for (int m = 0; m < 4; ++m) _Pragma("unroll") for (int k = 0; k < 2; ++k) \
;     dst[m][k] = *reinterpret_cast<const bf16x8*>((char*)SA(b, h) + lds_byte(wr * 64 + m * 16 + fr, k * 32 + fq * 8))
; #define LDB_(dst, b, h) _Pragma("unroll") for (int n = 0; n < 2; ++n) _Pragma("unroll") for (int k = 0; k < 2; ++k) \
;     dst[n][k] = *reinterpret_cast<const bf16x8*>((char*)SB(b, h) + lds_byte(wc * 32 + n * 16 + fr, k * 32 + fq * 8))
; #define MMA(ai, bj, At, Bx) do { __builtin_amdgcn_s_setprio(1); \
;     _Pragma("unroll") for (int m = 0; m < 4; ++m) _Pragma("unroll") for (int n = 0; n < 2; ++n) _Pragma("unroll") for (int k = 0; k < 2; ++k) \
;       acc[ai][bj][m][n] = __builtin_amdgcn_mfma_f32_16x16x32_bf16(At[m][k], Bx[n][k], acc[ai][bj][m][n], 0, 0, 0); \
;     __builtin_amdgcn_s_setprio(0); } while (0)
; #define WAIT_V(n) asm volatile("s_waitcnt vmcnt(" #n ")" ::: "memory")
; #define WAIT_L(n) asm volatile("s_waitcnt lgkmcnt(" #n ")" ::: "memory")
; #define BAR __builtin_amdgcn_s_barrier()
; template <int K, int LDA, int LDB>
; DEVI void gemm_tile(const bf16* __restrict__ A, const bf16* __restrict__ Bt, bf16* shm, acc_t& acc) {
;     ...
;     LDA_(At, 0, 1); WAIT_V(4); BAR; WAIT_L(0); MMA(1, 0, At, B0); MMA(1, 1, At, B1); BAR; }
;   { LDB_(B0, 1, 0); LDA_(At, 1, 0); WAIT_V(2); BAR; WAIT_L(0); MMA(0, 0, At, B0); BAR;
	s_nop 0
	ds_read_b128 v[66:69], v135 offset:16384
	ds_read_b128 v[74:77], v135 offset:17408
	ds_read_b128 v[82:85], v134 offset:16384
	ds_read_b128 v[90:93], v134 offset:17408
	ds_read_b128 v[186:189], v133 offset:16384
	ds_read_b128 v[190:193], v133 offset:17408
	ds_read_b128 v[194:197], v132 offset:16384
	ds_read_b128 v[198:201], v132 offset:17408
	s_waitcnt vmcnt(4)
	s_barrier
	s_waitcnt lgkmcnt(0)
	s_setprio 1
	s_waitcnt lgkmcnt(7)
	v_mfma_f32_16x16x32_bf16 v[62:65], v[66:69], v[146:149], v[62:65]
	s_waitcnt lgkmcnt(5)
	v_mfma_f32_16x16x32_bf16 v[54:57], v[82:85], v[146:149], v[54:57]
	s_waitcnt lgkmcnt(3)
	v_mfma_f32_16x16x32_bf16 v[46:49], v[186:189], v[146:149], v[46:49]
	s_waitcnt lgkmcnt(1)
	v_mfma_f32_16x16x32_bf16 v[38:41], v[194:197], v[146:149], v[38:41]
	v_mfma_f32_16x16x32_bf16 v[62:65], v[74:77], v[150:153], v[62:65]
	v_mfma_f32_16x16x32_bf16 v[58:61], v[66:69], v[166:169], v[58:61]
	v_mfma_f32_16x16x32_bf16 v[54:57], v[90:93], v[150:153], v[54:57]
	v_mfma_f32_16x16x32_bf16 v[50:53], v[82:85], v[166:169], v[50:53]
	v_mfma_f32_16x16x32_bf16 v[46:49], v[190:193], v[150:153], v[46:49]
	v_mfma_f32_16x16x32_bf16 v[42:45], v[186:189], v[166:169], v[42:45]
	s_waitcnt lgkmcnt(0)
	v_mfma_f32_16x16x32_bf16 v[38:41], v[198:201], v[150:153], v[38:41]
	v_mfma_f32_16x16x32_bf16 v[34:37], v[194:197], v[166:169], v[34:37]
	v_mfma_f32_16x16x32_bf16 v[202:205], v[74:77], v[170:173], v[58:61]
	v_mfma_f32_16x16x32_bf16 v[218:221], v[90:93], v[170:173], v[50:53]
	v_mfma_f32_16x16x32_bf16 v[222:225], v[190:193], v[170:173], v[42:45]
	v_mfma_f32_16x16x32_bf16 v[146:149], v[198:201], v[170:173], v[34:37]
	s_setprio 0
	s_setprio 1
	v_mfma_f32_16x16x32_bf16 v[30:33], v[66:69], v[98:101], v[30:33]
	v_mfma_f32_16x16x32_bf16 v[22:25], v[82:85], v[98:101], v[22:25]
	v_mfma_f32_16x16x32_bf16 v[14:17], v[186:189], v[98:101], v[14:17]
	v_mfma_f32_16x16x32_bf16 v[6:9], v[194:197], v[98:101], v[6:9]
	v_mfma_f32_16x16x32_bf16 v[30:33], v[74:77], v[106:109], v[30:33]
	v_mfma_f32_16x16x32_bf16 v[26:29], v[66:69], v[114:117], v[26:29]
	v_mfma_f32_16x16x32_bf16 v[22:25], v[90:93], v[106:109], v[22:25]
	v_mfma_f32_16x16x32_bf16 v[18:21], v[82:85], v[114:117], v[18:21]
	v_mfma_f32_16x16x32_bf16 v[14:17], v[190:193], v[106:109], v[14:17]
	v_mfma_f32_16x16x32_bf16 v[10:13], v[186:189], v[114:117], v[10:13]
	v_mfma_f32_16x16x32_bf16 v[6:9], v[198:201], v[106:109], v[6:9]
	v_mfma_f32_16x16x32_bf16 v[2:5], v[194:197], v[114:117], v[2:5]
	v_mfma_f32_16x16x32_bf16 v[150:153], v[74:77], v[122:125], v[26:29]
	v_mfma_f32_16x16x32_bf16 v[164:167], v[90:93], v[122:125], v[18:21]
	v_mfma_f32_16x16x32_bf16 v[168:171], v[190:193], v[122:125], v[10:13]
	v_mfma_f32_16x16x32_bf16 v[186:189], v[198:201], v[122:125], v[2:5]
	s_setprio 0
	s_barrier
	ds_read_b128 v[190:193], v144
	ds_read_b128 v[194:197], v144 offset:1024
	ds_read_b128 v[198:201], v144 offset:2048
	ds_read_b128 v[226:229], v144 offset:3072
	ds_read_b128 v[2:5], v135 offset:32768
	ds_read_b128 v[10:13], v135 offset:33792
	ds_read_b128 v[18:21], v134 offset:32768
	ds_read_b128 v[26:29], v134 offset:33792
	ds_read_b128 v[230:233], v133 offset:32768
	ds_read_b128 v[234:237], v133 offset:33792
	ds_read_b128 v[238:241], v132 offset:32768
	ds_read_b128 v[242:245], v132 offset:33792
	s_waitcnt vmcnt(2)
	s_barrier
	s_waitcnt lgkmcnt(0)
	s_setprio 1
	s_waitcnt lgkmcnt(7)
	v_mfma_f32_16x16x32_bf16 v[34:37], v[2:5], v[190:193], v[126:129]
	s_waitcnt lgkmcnt(6)
	v_mfma_f32_16x16x32_bf16 v[122:125], v[10:13], v[194:197], v[34:37]
	v_mfma_f32_16x16x32_bf16 v[34:37], v[2:5], v[198:201], v[158:161]
	v_mfma_f32_16x16x32_bf16 v[114:117], v[10:13], v[226:229], v[34:37]
	s_waitcnt lgkmcnt(5)
	v_mfma_f32_16x16x32_bf16 v[34:37], v[18:21], v[190:193], v[118:121]
	s_waitcnt lgkmcnt(4)
	v_mfma_f32_16x16x32_bf16 v[106:109], v[26:29], v[194:197], v[34:37]
	v_mfma_f32_16x16x32_bf16 v[34:37], v[18:21], v[198:201], v[206:209]
	v_mfma_f32_16x16x32_bf16 v[98:101], v[26:29], v[226:229], v[34:37]
	s_waitcnt lgkmcnt(3)
	v_mfma_f32_16x16x32_bf16 v[34:37], v[230:233], v[190:193], v[110:113]
	s_waitcnt lgkmcnt(2)
	v_mfma_f32_16x16x32_bf16 v[90:93], v[234:237], v[194:197], v[34:37]
	v_mfma_f32_16x16x32_bf16 v[34:37], v[230:233], v[198:201], v[210:213]
	v_mfma_f32_16x16x32_bf16 v[82:85], v[234:237], v[226:229], v[34:37]
	s_waitcnt lgkmcnt(1)
	v_mfma_f32_16x16x32_bf16 v[34:37], v[238:241], v[190:193], v[102:105]
	s_waitcnt lgkmcnt(0)
	v_mfma_f32_16x16x32_bf16 v[74:77], v[242:245], v[194:197], v[34:37]
	v_mfma_f32_16x16x32_bf16 v[34:37], v[238:241], v[198:201], v[214:217]
	v_mfma_f32_16x16x32_bf16 v[66:69], v[242:245], v[226:229], v[34:37]
	s_setprio 0
	s_barrier
; #define LDA_(dst, b, h) _Pragma("unroll") for (int m = 0; m < 4; ++m) _Pragma("unroll") for (int k = 0; k < 2; ++k) \
;     dst[m][k] = *reinterpret_cast<const bf16x8*>((char*)SA(b, h) + lds_byte(wr * 64 + m * 16 + fr, k * 32 + fq * 8))
; #define LDB_(dst, b, h) _Pragma("unroll") for (int n = 0; n < 2; ++n) _Pragma("unroll") for (int k = 0; k < 2; ++k) \
;     dst[n][k] = *reinterpret_cast<const bf16x8*>((char*)SB(b, h) + lds_byte(wc * 32 + n * 16 + fr, k * 32 + fq * 8))
; #define MMA(ai, bj, At, Bx) do { __builtin_amdgcn_s_setprio(1); \
;     _Pragma("unroll") for (int m = 0; m < 4; ++m) _Pragma("unroll") for (int n = 0; n < 2; ++n) _Pragma("unroll") for (int k = 0; k < 2; ++k) \
;       acc[ai][bj][m][n] = __builtin_amdgcn_mfma_f32_16x16x32_bf16(At[m][k], Bx[n][k], acc[ai][bj][m][n], 0, 0, 0); \
;     __builtin_amdgcn_s_setprio(0); } while (0)
; #define WAIT_V(n) asm volatile("s_waitcnt vmcnt(" #n ")" ::: "memory")
; #define WAIT_L(n) asm volatile("s_waitcnt lgkmcnt(" #n ")" ::: "memory")
; #define BAR __builtin_amdgcn_s_barrier()
; template <int K, int LDA, int LDB>
; DEVI void gemm_tile(const bf16* __restrict__ A, const bf16* __restrict__ Bt, bf16* shm, acc_t& acc) {
;     ...
;     LDB_(B1, 1, 1); WAIT_V(0); BAR; WAIT_L(0); MMA(0, 1, At, B1); BAR;
;     LDA_(At, 1, 1); BAR; WAIT_L(0); MMA(1, 0, At, B0); MMA(1, 1, At, B1); BAR; }
;   if (wr == 0) BAR;
	ds_read_b128 v[158:161], v142
	ds_read_b128 v[206:209], v142 offset:1024
	ds_read_b128 v[210:213], v142 offset:2048
	ds_read_b128 v[142:145], v142 offset:3072
	s_waitcnt vmcnt(0)
	s_barrier
	s_waitcnt lgkmcnt(0)
	s_setprio 1
	s_waitcnt lgkmcnt(3)
	v_mfma_f32_16x16x32_bf16 v[34:37], v[2:5], v[158:161], v[94:97]
	s_waitcnt lgkmcnt(1)
	v_mfma_f32_16x16x32_bf16 v[2:5], v[2:5], v[210:213], v[154:157]
	s_waitcnt lgkmcnt(0)
	v_mfma_f32_16x16x32_bf16 v[50:53], v[10:13], v[142:145], v[2:5]
	v_mfma_f32_16x16x32_bf16 v[2:5], v[18:21], v[158:161], v[86:89]
	v_mfma_f32_16x16x32_bf16 v[42:45], v[26:29], v[206:209], v[2:5]
	v_mfma_f32_16x16x32_bf16 v[2:5], v[18:21], v[210:213], v[174:177]
	v_mfma_f32_16x16x32_bf16 v[58:61], v[10:13], v[206:209], v[34:37]
	v_mfma_f32_16x16x32_bf16 v[34:37], v[26:29], v[142:145], v[2:5]
	v_mfma_f32_16x16x32_bf16 v[2:5], v[230:233], v[158:161], v[78:81]
	v_mfma_f32_16x16x32_bf16 v[26:29], v[234:237], v[206:209], v[2:5]
	v_mfma_f32_16x16x32_bf16 v[2:5], v[230:233], v[210:213], v[178:181]
	v_mfma_f32_16x16x32_bf16 v[18:21], v[234:237], v[142:145], v[2:5]
	v_mfma_f32_16x16x32_bf16 v[2:5], v[238:241], v[158:161], v[70:73]
	v_mfma_f32_16x16x32_bf16 v[10:13], v[242:245], v[206:209], v[2:5]
	v_mfma_f32_16x16x32_bf16 v[2:5], v[238:241], v[210:213], v[182:185]
	v_mfma_f32_16x16x32_bf16 v[2:5], v[242:245], v[142:145], v[2:5]
	s_setprio 0
	s_barrier
	ds_read_b128 v[154:157], v135 offset:49152
	ds_read_b128 v[172:175], v135 offset:50176
	ds_read_b128 v[176:179], v134 offset:49152
	ds_read_b128 v[180:183], v134 offset:50176
	ds_read_b128 v[214:217], v133 offset:49152
	ds_read_b128 v[230:233], v133 offset:50176
	ds_read_b128 v[234:237], v132 offset:49152
	ds_read_b128 v[132:135], v132 offset:50176
	s_barrier
	s_waitcnt lgkmcnt(0)
	s_setprio 1
	s_waitcnt lgkmcnt(7)
	v_mfma_f32_16x16x32_bf16 v[62:65], v[154:157], v[190:193], v[62:65]
	s_waitcnt lgkmcnt(5)
	v_mfma_f32_16x16x32_bf16 v[54:57], v[176:179], v[190:193], v[54:57]
	s_waitcnt lgkmcnt(3)
	v_mfma_f32_16x16x32_bf16 v[46:49], v[214:217], v[190:193], v[46:49]
	s_waitcnt lgkmcnt(1)
	v_mfma_f32_16x16x32_bf16 v[38:41], v[234:237], v[190:193], v[38:41]
	v_mfma_f32_16x16x32_bf16 v[126:129], v[172:175], v[194:197], v[62:65]
	v_mfma_f32_16x16x32_bf16 v[62:65], v[154:157], v[198:201], v[202:205]
	v_mfma_f32_16x16x32_bf16 v[110:113], v[180:183], v[194:197], v[54:57]
	v_mfma_f32_16x16x32_bf16 v[54:57], v[176:179], v[198:201], v[218:221]
	v_mfma_f32_16x16x32_bf16 v[94:97], v[230:233], v[194:197], v[46:49]
	v_mfma_f32_16x16x32_bf16 v[46:49], v[214:217], v[198:201], v[222:225]
	s_waitcnt lgkmcnt(0)
	v_mfma_f32_16x16x32_bf16 v[78:81], v[132:135], v[194:197], v[38:41]
	v_mfma_f32_16x16x32_bf16 v[38:41], v[234:237], v[198:201], v[146:149]
	v_mfma_f32_16x16x32_bf16 v[118:121], v[172:175], v[226:229], v[62:65]
	v_mfma_f32_16x16x32_bf16 v[102:105], v[180:183], v[226:229], v[54:57]
	v_mfma_f32_16x16x32_bf16 v[86:89], v[230:233], v[226:229], v[46:49]
	v_mfma_f32_16x16x32_bf16 v[70:73], v[132:135], v[226:229], v[38:41]
	s_setprio 0
	s_setprio 1
	v_mfma_f32_16x16x32_bf16 v[30:33], v[154:157], v[158:161], v[30:33]
	v_mfma_f32_16x16x32_bf16 v[62:65], v[172:175], v[206:209], v[30:33]
	v_mfma_f32_16x16x32_bf16 v[30:33], v[154:157], v[210:213], v[150:153]
	v_mfma_f32_16x16x32_bf16 v[22:25], v[176:179], v[158:161], v[22:25]
	v_mfma_f32_16x16x32_bf16 v[14:17], v[214:217], v[158:161], v[14:17]
	v_mfma_f32_16x16x32_bf16 v[54:57], v[172:175], v[142:145], v[30:33]
	v_mfma_f32_16x16x32_bf16 v[46:49], v[180:183], v[206:209], v[22:25]
	v_mfma_f32_16x16x32_bf16 v[22:25], v[176:179], v[210:213], v[164:167]
	v_mfma_f32_16x16x32_bf16 v[30:33], v[230:233], v[206:209], v[14:17]
	v_mfma_f32_16x16x32_bf16 v[14:17], v[214:217], v[210:213], v[168:171]
	v_mfma_f32_16x16x32_bf16 v[6:9], v[234:237], v[158:161], v[6:9]
	v_mfma_f32_16x16x32_bf16 v[38:41], v[180:183], v[142:145], v[22:25]
	v_mfma_f32_16x16x32_bf16 v[22:25], v[230:233], v[142:145], v[14:17]
	v_mfma_f32_16x16x32_bf16 v[14:17], v[132:135], v[206:209], v[6:9]
	v_mfma_f32_16x16x32_bf16 v[6:9], v[234:237], v[210:213], v[186:189]
	v_mfma_f32_16x16x32_bf16 v[6:9], v[132:135], v[142:145], v[6:9]
	s_setprio 0
	v_cmp_gt_u32_e32 vcc, s18, v130
	s_barrier
	s_and_saveexec_b64 s[4:5], vcc
	s_cbranch_execz .LBB0_1233
	s_barrier

; #define STAGE(P, BASE, LD, br, kt) do { const int _so = (int)(((br) * (LD) + (kt) * BK) * 2); \
;     _Pragma("unroll") for (int _i = 0; _i < 2; ++_i) { \
;       __builtin_amdgcn_raw_ptr_buffer_load_lds(rs##BASE, (__attribute__((address_space(3))) unsigned*)((char*)(P) + tid_ * 16 + _i * 8192), 16, (int)off##LD[_i], _so, 0, 0); } } while (0)
; #define LDA_(dst, b, h) _Pragma("unroll") for (int m = 0; m < 4; ++m) _Pragma("unroll") for (int k = 0; k < 2; ++k) \
;     dst[m][k] = *reinterpret_cast<const bf16x8*>((char*)SA(b, h) + lds_byte(wr * 64 + m * 16 + fr, k * 32 + fq * 8))
; #define LDB_(dst, b, h) _Pragma("unroll") for (int n = 0; n < 2; ++n) _Pragma("unroll") for (int k = 0; k < 2; ++k) \
;     dst[n][k] = *reinterpret_cast<const bf16x8*>((char*)SB(b, h) + lds_byte(wc * 32 + n * 16 + fr, k * 32 + fq * 8))
; #define MMA(ai, bj, At, Bx) do { __builtin_amdgcn_s_setprio(1); \
;     _Pragma("unroll") for (int m = 0; m < 4; ++m) _Pragma("unroll") for (int n = 0; n < 2; ++n) _Pragma("unroll") for (int k = 0; k < 2; ++k) \
;       acc[ai][bj][m][n] = __builtin_amdgcn_mfma_f32_16x16x32_bf16(At[m][k], Bx[n][k], acc[ai][bj][m][n], 0, 0, 0); \
;     __builtin_amdgcn_s_setprio(0); } while (0)
; #define WAIT_L(n) asm volatile("s_waitcnt lgkmcnt(" #n ")" ::: "memory")
; #define BAR __builtin_amdgcn_s_barrier()
; #define SCHED __builtin_amdgcn_sched_barrier(0)
; template <int K, int LDA, int LDB>
; DEVI void gemm_tile(const bf16* __restrict__ A, const bf16* __restrict__ Bt, bf16* shm, acc_t& acc) {
;     ...
;     LDB_(B0, 0, 0); SCHED; LDA_(At, 0, 0); STAGE(SA(1, 1), A, LDA, HALF, t + 1);
;     WAIT_L(8); BAR; WAIT_L(0); MMA(0, 0, At, B0); BAR; SCHED;
;     LDB_(B1, 0, 1); STAGE(SB(0, 0), Bt, LDB, 0, t + 2);
;     BAR; WAIT_L(0); MMA(0, 1, At, B1); BAR;
;     LDA_(At, 0, 1); STAGE(SA(0, 0), A, LDA, 0, t + 2);
;     BAR; WAIT_L(0); MMA(1, 0, At, B0); BAR; SCHED;
.LBB0_1270:
	ds_read_b128 v[164:167], v160
	ds_read_b128 v[168:171], v160 offset:1024
	ds_read_b128 v[172:175], v160 offset:2048
	ds_read_b128 v[176:179], v160 offset:3072
	v_readfirstlane_b32 s41, v156
	s_add_i32 s40, s7, 0xffffff00
	s_mov_b32 m0, s41
	v_readfirstlane_b32 s41, v159
	ds_read_b128 v[180:183], v138
	ds_read_b128 v[184:187], v138 offset:1024
	ds_read_b128 v[188:191], v137
	ds_read_b128 v[192:195], v137 offset:1024
	ds_read_b128 v[196:199], v133
	ds_read_b128 v[200:203], v133 offset:1024
	ds_read_b128 v[204:207], v132
	ds_read_b128 v[208:211], v132 offset:1024
	buffer_load_dwordx4 v139, s[8:11], s40 offen lds
	s_mov_b32 m0, s41
	s_nop 0
	buffer_load_dwordx4 v141, s[8:11], s40 offen lds
	s_waitcnt lgkmcnt(8)
	s_barrier
	s_waitcnt lgkmcnt(0)
	s_setprio 1
	s_waitcnt lgkmcnt(7)
	v_mfma_f32_16x16x32_bf16 v[126:129], v[180:183], v[164:167], v[126:129]
	v_mfma_f32_16x16x32_bf16 v[122:125], v[180:183], v[172:175], v[122:125]
	s_waitcnt lgkmcnt(5)
	v_mfma_f32_16x16x32_bf16 v[118:121], v[188:191], v[164:167], v[118:121]
	v_mfma_f32_16x16x32_bf16 v[114:117], v[188:191], v[172:175], v[114:117]
	s_waitcnt lgkmcnt(3)
	v_mfma_f32_16x16x32_bf16 v[110:113], v[196:199], v[164:167], v[110:113]
	v_mfma_f32_16x16x32_bf16 v[106:109], v[196:199], v[172:175], v[106:109]
	s_waitcnt lgkmcnt(1)
	v_mfma_f32_16x16x32_bf16 v[102:105], v[204:207], v[164:167], v[102:105]
	v_mfma_f32_16x16x32_bf16 v[98:101], v[204:207], v[172:175], v[98:101]
	v_mfma_f32_16x16x32_bf16 v[126:129], v[184:187], v[168:171], v[126:129]
	v_mfma_f32_16x16x32_bf16 v[122:125], v[184:187], v[176:179], v[122:125]
	v_mfma_f32_16x16x32_bf16 v[118:121], v[192:195], v[168:171], v[118:121]
	v_mfma_f32_16x16x32_bf16 v[114:117], v[192:195], v[176:179], v[114:117]
	v_mfma_f32_16x16x32_bf16 v[110:113], v[200:203], v[168:171], v[110:113]
	v_mfma_f32_16x16x32_bf16 v[106:109], v[200:203], v[176:179], v[106:109]
	s_waitcnt lgkmcnt(0)
	v_mfma_f32_16x16x32_bf16 v[102:105], v[208:211], v[168:171], v[102:105]
	v_mfma_f32_16x16x32_bf16 v[98:101], v[208:211], v[176:179], v[98:101]
	s_setprio 0
	s_barrier
	v_readfirstlane_b32 s41, v143
	s_add_i32 s40, s7, 0xffe9ff80
	s_mov_b32 m0, s41
	v_readfirstlane_b32 s41, v144
	ds_read_b128 v[212:215], v154
	ds_read_b128 v[216:219], v154 offset:1024
	ds_read_b128 v[220:223], v154 offset:2048
	ds_read_b128 v[224:227], v154 offset:3072
	buffer_load_dwordx4 v139, s[0:3], s40 offen lds
	s_mov_b32 m0, s41
	s_nop 0
	buffer_load_dwordx4 v141, s[0:3], s40 offen lds
	s_barrier
	s_waitcnt lgkmcnt(0)
	s_setprio 1
	s_waitcnt lgkmcnt(3)
	v_mfma_f32_16x16x32_bf16 v[94:97], v[180:183], v[212:215], v[94:97]
	s_waitcnt lgkmcnt(1)
	v_mfma_f32_16x16x32_bf16 v[90:93], v[180:183], v[220:223], v[90:93]
	v_mfma_f32_16x16x32_bf16 v[86:89], v[188:191], v[212:215], v[86:89]
	v_mfma_f32_16x16x32_bf16 v[82:85], v[188:191], v[220:223], v[82:85]
	v_mfma_f32_16x16x32_bf16 v[78:81], v[196:199], v[212:215], v[78:81]
	v_mfma_f32_16x16x32_bf16 v[74:77], v[196:199], v[220:223], v[74:77]
	v_mfma_f32_16x16x32_bf16 v[70:73], v[204:207], v[212:215], v[70:73]
	v_mfma_f32_16x16x32_bf16 v[66:69], v[204:207], v[220:223], v[66:69]
	v_mfma_f32_16x16x32_bf16 v[94:97], v[184:187], v[216:219], v[94:97]
	s_waitcnt lgkmcnt(0)
	v_mfma_f32_16x16x32_bf16 v[90:93], v[184:187], v[224:227], v[90:93]
	v_mfma_f32_16x16x32_bf16 v[86:89], v[192:195], v[216:219], v[86:89]
	v_mfma_f32_16x16x32_bf16 v[82:85], v[192:195], v[224:227], v[82:85]
	v_mfma_f32_16x16x32_bf16 v[78:81], v[200:203], v[216:219], v[78:81]
	v_mfma_f32_16x16x32_bf16 v[74:77], v[200:203], v[224:227], v[74:77]
	v_mfma_f32_16x16x32_bf16 v[70:73], v[208:211], v[216:219], v[70:73]
	v_mfma_f32_16x16x32_bf16 v[66:69], v[208:211], v[224:227], v[66:69]
	s_setprio 0
	v_readfirstlane_b32 s41, v145
	s_mov_b32 m0, s41
	v_readfirstlane_b32 s41, v146
	s_barrier
	ds_read_b128 v[180:183], v138 offset:16384
	ds_read_b128 v[184:187], v138 offset:17408
	ds_read_b128 v[188:191], v137 offset:16384
	ds_read_b128 v[192:195], v137 offset:17408
	ds_read_b128 v[196:199], v133 offset:16384
	ds_read_b128 v[200:203], v133 offset:17408
	ds_read_b128 v[204:207], v132 offset:16384
	ds_read_b128 v[208:211], v132 offset:17408
	buffer_load_dwordx4 v139, s[8:11], s40 offen lds
	s_mov_b32 m0, s41
	s_nop 0
	buffer_load_dwordx4 v141, s[8:11], s40 offen lds
	s_barrier
	s_waitcnt lgkmcnt(0)
	s_setprio 1
	s_waitcnt lgkmcnt(7)
	v_mfma_f32_16x16x32_bf16 v[62:65], v[180:183], v[164:167], v[62:65]
	v_mfma_f32_16x16x32_bf16 v[58:61], v[180:183], v[172:175], v[58:61]
	s_waitcnt lgkmcnt(5)
	v_mfma_f32_16x16x32_bf16 v[54:57], v[188:191], v[164:167], v[54:57]
	v_mfma_f32_16x16x32_bf16 v[50:53], v[188:191], v[172:175], v[50:53]
	s_waitcnt lgkmcnt(3)
	v_mfma_f32_16x16x32_bf16 v[46:49], v[196:199], v[164:167], v[46:49]
	v_mfma_f32_16x16x32_bf16 v[42:45], v[196:199], v[172:175], v[42:45]
	s_waitcnt lgkmcnt(1)
	v_mfma_f32_16x16x32_bf16 v[38:41], v[204:207], v[164:167], v[38:41]
	v_mfma_f32_16x16x32_bf16 v[34:37], v[204:207], v[172:175], v[34:37]
	v_mfma_f32_16x16x32_bf16 v[62:65], v[184:187], v[168:171], v[62:65]
	v_mfma_f32_16x16x32_bf16 v[58:61], v[184:187], v[176:179], v[58:61]
	v_mfma_f32_16x16x32_bf16 v[54:57], v[192:195], v[168:171], v[54:57]
	v_mfma_f32_16x16x32_bf16 v[50:53], v[192:195], v[176:179], v[50:53]
	v_mfma_f32_16x16x32_bf16 v[46:49], v[200:203], v[168:171], v[46:49]
	v_mfma_f32_16x16x32_bf16 v[42:45], v[200:203], v[176:179], v[42:45]
	s_waitcnt lgkmcnt(0)
	v_mfma_f32_16x16x32_bf16 v[38:41], v[208:211], v[168:171], v[38:41]
	v_mfma_f32_16x16x32_bf16 v[34:37], v[208:211], v[176:179], v[34:37]
	s_setprio 0
	s_barrier
; #define STAGE(P, BASE, LD, br, kt) do { const int _so = (int)(((br) * (LD) + (kt) * BK) * 2); \
;     _Pragma("unroll") for (int _i = 0; _i < 2; ++_i) { \
;       __builtin_amdgcn_raw_ptr_buffer_load_lds(rs##BASE, (__attribute__((address_space(3))) unsigned*)((char*)(P) + tid_ * 16 + _i * 8192), 16, (int)off##LD[_i], _so, 0, 0); } } while (0)
; #define LDA_(dst, b, h) _Pragma("unroll") for (int m = 0; m < 4; ++m) _Pragma("unroll") for (int k = 0; k < 2; ++k) \
;     dst[m][k] = *reinterpret_cast<const bf16x8*>((char*)SA(b, h) + lds_byte(wr * 64 + m * 16 + fr, k * 32 + fq * 8))
; #define LDB_(dst, b, h) _Pragma("unroll") for (int n = 0; n < 2; ++n) _Pragma("unroll") for (int k = 0; k < 2; ++k) \
;     dst[n][k] = *reinterpret_cast<const bf16x8*>((char*)SB(b, h) + lds_byte(wc * 32 + n * 16 + fr, k * 32 + fq * 8))
; #define MMA(ai, bj, At, Bx) do { __builtin_amdgcn_s_setprio(1); \
;     _Pragma("unroll") for (int m = 0; m < 4; ++m) _Pragma("unroll") for (int n = 0; n < 2; ++n) _Pragma("unroll") for (int k = 0; k < 2; ++k) \
;       acc[ai][bj][m][n] = __builtin_amdgcn_mfma_f32_16x16x32_bf16(At[m][k], Bx[n][k], acc[ai][bj][m][n], 0, 0, 0); \
;     __builtin_amdgcn_s_setprio(0); } while (0)
; #define WAIT_V(n) asm volatile("s_waitcnt vmcnt(" #n ")" ::: "memory")
; #define WAIT_L(n) asm volatile("s_waitcnt lgkmcnt(" #n ")" ::: "memory")
; #define BAR __builtin_amdgcn_s_barrier()
; #define SCHED __builtin_amdgcn_sched_barrier(0)
; template <int K, int LDA, int LDB>
; DEVI void gemm_tile(const bf16* __restrict__ A, const bf16* __restrict__ Bt, bf16* shm, acc_t& acc) {
;     ...
;     STAGE(SB(0, 1), Bt, LDB, HALF, t + 2);
;     WAIT_V(6); BAR; MMA(1, 1, At, B1); BAR;
;     LDB_(B0, 1, 0); SCHED; LDA_(At, 1, 0); STAGE(SA(0, 1), A, LDA, HALF, t + 2);
;     WAIT_L(8); BAR; WAIT_L(0); MMA(0, 0, At, B0); BAR; SCHED;
;     LDB_(B1, 1, 1); STAGE(SB(1, 0), Bt, LDB, 0, t + 3);
;     BAR; WAIT_L(0); MMA(0, 1, At, B1); BAR;
;     LDA_(At, 1, 1); STAGE(SA(1, 0), A, LDA, 0, t + 3);
	v_readfirstlane_b32 s41, v147
	s_add_i32 s40, s7, 0xffffff80
	s_mov_b32 m0, s41
	v_readfirstlane_b32 s41, v148
	buffer_load_dwordx4 v139, s[0:3], s40 offen lds
	s_mov_b32 m0, s41
	s_nop 0
	buffer_load_dwordx4 v141, s[0:3], s40 offen lds
	s_waitcnt vmcnt(6)
	s_barrier
	s_setprio 1
	v_mfma_f32_16x16x32_bf16 v[30:33], v[180:183], v[212:215], v[30:33]
	v_mfma_f32_16x16x32_bf16 v[26:29], v[180:183], v[220:223], v[26:29]
	v_mfma_f32_16x16x32_bf16 v[22:25], v[188:191], v[212:215], v[22:25]
	v_mfma_f32_16x16x32_bf16 v[18:21], v[188:191], v[220:223], v[18:21]
	v_mfma_f32_16x16x32_bf16 v[14:17], v[196:199], v[212:215], v[14:17]
	v_mfma_f32_16x16x32_bf16 v[10:13], v[196:199], v[220:223], v[10:13]
	v_mfma_f32_16x16x32_bf16 v[6:9], v[204:207], v[212:215], v[6:9]
	v_mfma_f32_16x16x32_bf16 v[2:5], v[204:207], v[220:223], v[2:5]
	v_mfma_f32_16x16x32_bf16 v[30:33], v[184:187], v[216:219], v[30:33]
	v_mfma_f32_16x16x32_bf16 v[26:29], v[184:187], v[224:227], v[26:29]
	v_mfma_f32_16x16x32_bf16 v[22:25], v[192:195], v[216:219], v[22:25]
	v_mfma_f32_16x16x32_bf16 v[18:21], v[192:195], v[224:227], v[18:21]
	v_mfma_f32_16x16x32_bf16 v[14:17], v[200:203], v[216:219], v[14:17]
	v_mfma_f32_16x16x32_bf16 v[10:13], v[200:203], v[224:227], v[10:13]
	v_mfma_f32_16x16x32_bf16 v[6:9], v[208:211], v[216:219], v[6:9]
	v_mfma_f32_16x16x32_bf16 v[2:5], v[208:211], v[224:227], v[2:5]
	s_setprio 0
	s_barrier
	ds_read_b128 v[164:167], v142
	ds_read_b128 v[168:171], v142 offset:1024
	ds_read_b128 v[172:175], v142 offset:2048
	ds_read_b128 v[176:179], v142 offset:3072
	v_readfirstlane_b32 s41, v149
	s_mov_b32 m0, s41
	v_readfirstlane_b32 s41, v150
	ds_read_b128 v[180:183], v138 offset:32768
	ds_read_b128 v[184:187], v138 offset:33792
	ds_read_b128 v[188:191], v137 offset:32768
	ds_read_b128 v[192:195], v137 offset:33792
	ds_read_b128 v[196:199], v133 offset:32768
	ds_read_b128 v[200:203], v133 offset:33792
	ds_read_b128 v[204:207], v132 offset:32768
	ds_read_b128 v[208:211], v132 offset:33792
	buffer_load_dwordx4 v139, s[8:11], s40 offen lds
	s_mov_b32 m0, s41
	s_nop 0
	buffer_load_dwordx4 v141, s[8:11], s40 offen lds
	s_waitcnt lgkmcnt(8)
	s_barrier
	s_waitcnt lgkmcnt(0)
	s_setprio 1
	s_waitcnt lgkmcnt(7)
	v_mfma_f32_16x16x32_bf16 v[126:129], v[180:183], v[164:167], v[126:129]
	v_mfma_f32_16x16x32_bf16 v[122:125], v[180:183], v[172:175], v[122:125]
	s_waitcnt lgkmcnt(5)
	v_mfma_f32_16x16x32_bf16 v[118:121], v[188:191], v[164:167], v[118:121]
	v_mfma_f32_16x16x32_bf16 v[114:117], v[188:191], v[172:175], v[114:117]
	s_waitcnt lgkmcnt(3)
	v_mfma_f32_16x16x32_bf16 v[110:113], v[196:199], v[164:167], v[110:113]
	v_mfma_f32_16x16x32_bf16 v[106:109], v[196:199], v[172:175], v[106:109]
	s_waitcnt lgkmcnt(1)
	v_mfma_f32_16x16x32_bf16 v[102:105], v[204:207], v[164:167], v[102:105]
	v_mfma_f32_16x16x32_bf16 v[98:101], v[204:207], v[172:175], v[98:101]
	v_mfma_f32_16x16x32_bf16 v[126:129], v[184:187], v[168:171], v[126:129]
	v_mfma_f32_16x16x32_bf16 v[122:125], v[184:187], v[176:179], v[122:125]
	v_mfma_f32_16x16x32_bf16 v[118:121], v[192:195], v[168:171], v[118:121]
	v_mfma_f32_16x16x32_bf16 v[114:117], v[192:195], v[176:179], v[114:117]
	v_mfma_f32_16x16x32_bf16 v[110:113], v[200:203], v[168:171], v[110:113]
	v_mfma_f32_16x16x32_bf16 v[106:109], v[200:203], v[176:179], v[106:109]
	s_waitcnt lgkmcnt(0)
	v_mfma_f32_16x16x32_bf16 v[102:105], v[208:211], v[168:171], v[102:105]
	v_mfma_f32_16x16x32_bf16 v[98:101], v[208:211], v[176:179], v[98:101]
	s_setprio 0
	s_barrier
	v_readfirstlane_b32 s41, v151
	s_add_i32 s40, s7, 0xffea0000
	s_mov_b32 m0, s41
	v_readfirstlane_b32 s41, v152
	ds_read_b128 v[212:215], v140
	ds_read_b128 v[216:219], v140 offset:1024
	ds_read_b128 v[220:223], v140 offset:2048
	ds_read_b128 v[224:227], v140 offset:3072
	buffer_load_dwordx4 v139, s[0:3], s40 offen lds
	s_mov_b32 m0, s41
	s_nop 0
	buffer_load_dwordx4 v141, s[0:3], s40 offen lds
	s_barrier
	s_waitcnt lgkmcnt(0)
	s_setprio 1
	s_waitcnt lgkmcnt(3)
	v_mfma_f32_16x16x32_bf16 v[94:97], v[180:183], v[212:215], v[94:97]
	s_waitcnt lgkmcnt(1)
	v_mfma_f32_16x16x32_bf16 v[90:93], v[180:183], v[220:223], v[90:93]
	v_mfma_f32_16x16x32_bf16 v[86:89], v[188:191], v[212:215], v[86:89]
	v_mfma_f32_16x16x32_bf16 v[82:85], v[188:191], v[220:223], v[82:85]
	v_mfma_f32_16x16x32_bf16 v[78:81], v[196:199], v[212:215], v[78:81]
	v_mfma_f32_16x16x32_bf16 v[74:77], v[196:199], v[220:223], v[74:77]
	v_mfma_f32_16x16x32_bf16 v[70:73], v[204:207], v[212:215], v[70:73]
	v_mfma_f32_16x16x32_bf16 v[66:69], v[204:207], v[220:223], v[66:69]
	v_mfma_f32_16x16x32_bf16 v[94:97], v[184:187], v[216:219], v[94:97]
	s_waitcnt lgkmcnt(0)
	v_mfma_f32_16x16x32_bf16 v[90:93], v[184:187], v[224:227], v[90:93]
	v_mfma_f32_16x16x32_bf16 v[86:89], v[192:195], v[216:219], v[86:89]
	v_mfma_f32_16x16x32_bf16 v[82:85], v[192:195], v[224:227], v[82:85]
	v_mfma_f32_16x16x32_bf16 v[78:81], v[200:203], v[216:219], v[78:81]
	v_mfma_f32_16x16x32_bf16 v[74:77], v[200:203], v[224:227], v[74:77]
	v_mfma_f32_16x16x32_bf16 v[70:73], v[208:211], v[216:219], v[70:73]
	v_mfma_f32_16x16x32_bf16 v[66:69], v[208:211], v[224:227], v[66:69]
	s_setprio 0
	v_readfirstlane_b32 s41, v153
	s_mov_b32 m0, s41
	v_readfirstlane_b32 s41, v155
	s_barrier
	ds_read_b128 v[180:183], v138 offset:49152
	ds_read_b128 v[184:187], v138 offset:50176
	ds_read_b128 v[188:191], v137 offset:49152
	ds_read_b128 v[192:195], v137 offset:50176
	ds_read_b128 v[196:199], v133 offset:49152
	ds_read_b128 v[200:203], v133 offset:50176
	ds_read_b128 v[204:207], v132 offset:49152
	ds_read_b128 v[208:211], v132 offset:50176
	buffer_load_dwordx4 v139, s[8:11], s40 offen lds
	s_mov_b32 m0, s41
	s_nop 0
	buffer_load_dwordx4 v141, s[8:11], s40 offen lds
	s_barrier
; #define STAGE(P, BASE, LD, br, kt) do { const int _so = (int)(((br) * (LD) + (kt) * BK) * 2); \
;     _Pragma("unroll") for (int _i = 0; _i < 2; ++_i) { \
;       __builtin_amdgcn_raw_ptr_buffer_load_lds(rs##BASE, (__attribute__((address_space(3))) unsigned*)((char*)(P) + tid_ * 16 + _i * 8192), 16, (int)off##LD[_i], _so, 0, 0); } } while (0)
; #define LDA_(dst, b, h) _Pragma("unroll") for (int m = 0; m < 4; ++m) _Pragma("unroll") for (int k = 0; k < 2; ++k) \
;     dst[m][k] = *reinterpret_cast<const bf16x8*>((char*)SA(b, h) + lds_byte(wr * 64 + m * 16 + fr, k * 32 + fq * 8))
; #define LDB_(dst, b, h) _Pragma("unroll") for (int n = 0; n < 2; ++n) _Pragma("unroll") for (int k = 0; k < 2; ++k) \
;     dst[n][k] = *reinterpret_cast<const bf16x8*>((char*)SB(b, h) + lds_byte(wc * 32 + n * 16 + fr, k * 32 + fq * 8))
; #define MMA(ai, bj, At, Bx) do { __builtin_amdgcn_s_setprio(1); \
;     _Pragma("unroll") for (int m = 0; m < 4; ++m) _Pragma("unroll") for (int n = 0; n < 2; ++n) _Pragma("unroll") for (int k = 0; k < 2; ++k) \
;       acc[ai][bj][m][n] = __builtin_amdgcn_mfma_f32_16x16x32_bf16(At[m][k], Bx[n][k], acc[ai][bj][m][n], 0, 0, 0); \
;     __builtin_amdgcn_s_setprio(0); } while (0)
; #define WAIT_V(n) asm volatile("s_waitcnt vmcnt(" #n ")" ::: "memory")
; #define WAIT_L(n) asm volatile("s_waitcnt lgkmcnt(" #n ")" ::: "memory")
; #define BAR __builtin_amdgcn_s_barrier()
; #define SCHED __builtin_amdgcn_sched_barrier(0)
; template <int K, int LDA, int LDB>
; DEVI void gemm_tile(const bf16* __restrict__ A, const bf16* __restrict__ Bt, bf16* shm, acc_t& acc) {
;     ...
;     BAR; WAIT_L(0); MMA(1, 0, At, B0); BAR; SCHED;
;     STAGE(SB(1, 1), Bt, LDB, HALF, t + 3);
;     WAIT_V(6); BAR; MMA(1, 1, At, B1); BAR;
;   }
;   { LDB_(B0, 0, 0); LDA_(At, 0, 0); STAGE(SA(1, 1), A, LDA, HALF, nt - 1);
;     BAR; WAIT_L(0); MMA(0, 0, At, B0); BAR;
;     LDB_(B1, 0, 1); BAR; WAIT_L(0); MMA(0, 1, At, B1); BAR;
	s_waitcnt lgkmcnt(0)
	s_setprio 1
	s_waitcnt lgkmcnt(7)
	v_mfma_f32_16x16x32_bf16 v[62:65], v[180:183], v[164:167], v[62:65]
	v_mfma_f32_16x16x32_bf16 v[58:61], v[180:183], v[172:175], v[58:61]
	s_waitcnt lgkmcnt(5)
	v_mfma_f32_16x16x32_bf16 v[54:57], v[188:191], v[164:167], v[54:57]
	v_mfma_f32_16x16x32_bf16 v[50:53], v[188:191], v[172:175], v[50:53]
	s_waitcnt lgkmcnt(3)
	v_mfma_f32_16x16x32_bf16 v[46:49], v[196:199], v[164:167], v[46:49]
	v_mfma_f32_16x16x32_bf16 v[42:45], v[196:199], v[172:175], v[42:45]
	s_waitcnt lgkmcnt(1)
	v_mfma_f32_16x16x32_bf16 v[38:41], v[204:207], v[164:167], v[38:41]
	v_mfma_f32_16x16x32_bf16 v[34:37], v[204:207], v[172:175], v[34:37]
	v_mfma_f32_16x16x32_bf16 v[62:65], v[184:187], v[168:171], v[62:65]
	v_mfma_f32_16x16x32_bf16 v[58:61], v[184:187], v[176:179], v[58:61]
	v_mfma_f32_16x16x32_bf16 v[54:57], v[192:195], v[168:171], v[54:57]
	v_mfma_f32_16x16x32_bf16 v[50:53], v[192:195], v[176:179], v[50:53]
	v_mfma_f32_16x16x32_bf16 v[46:49], v[200:203], v[168:171], v[46:49]
	v_mfma_f32_16x16x32_bf16 v[42:45], v[200:203], v[176:179], v[42:45]
	s_waitcnt lgkmcnt(0)
	v_mfma_f32_16x16x32_bf16 v[38:41], v[208:211], v[168:171], v[38:41]
	v_mfma_f32_16x16x32_bf16 v[34:37], v[208:211], v[176:179], v[34:37]
	s_setprio 0
	s_barrier
	v_readfirstlane_b32 s40, v157
	s_mov_b32 m0, s40
	v_readfirstlane_b32 s40, v158
	buffer_load_dwordx4 v139, s[0:3], s7 offen lds
	s_mov_b32 m0, s40
	s_nop 0
	buffer_load_dwordx4 v141, s[0:3], s7 offen lds
	s_waitcnt vmcnt(6)
	s_barrier
	s_setprio 1
	v_mfma_f32_16x16x32_bf16 v[30:33], v[180:183], v[212:215], v[30:33]
	v_mfma_f32_16x16x32_bf16 v[26:29], v[180:183], v[220:223], v[26:29]
	v_mfma_f32_16x16x32_bf16 v[22:25], v[188:191], v[212:215], v[22:25]
	v_mfma_f32_16x16x32_bf16 v[18:21], v[188:191], v[220:223], v[18:21]
	v_mfma_f32_16x16x32_bf16 v[14:17], v[196:199], v[212:215], v[14:17]
	v_mfma_f32_16x16x32_bf16 v[10:13], v[196:199], v[220:223], v[10:13]
	v_mfma_f32_16x16x32_bf16 v[6:9], v[204:207], v[212:215], v[6:9]
	v_mfma_f32_16x16x32_bf16 v[2:5], v[204:207], v[220:223], v[2:5]
	v_mfma_f32_16x16x32_bf16 v[30:33], v[184:187], v[216:219], v[30:33]
	v_mfma_f32_16x16x32_bf16 v[26:29], v[184:187], v[224:227], v[26:29]
	v_mfma_f32_16x16x32_bf16 v[22:25], v[192:195], v[216:219], v[22:25]
	v_mfma_f32_16x16x32_bf16 v[18:21], v[192:195], v[224:227], v[18:21]
	v_mfma_f32_16x16x32_bf16 v[14:17], v[200:203], v[216:219], v[14:17]
	v_mfma_f32_16x16x32_bf16 v[10:13], v[200:203], v[224:227], v[10:13]
	v_mfma_f32_16x16x32_bf16 v[6:9], v[208:211], v[216:219], v[6:9]
	v_mfma_f32_16x16x32_bf16 v[2:5], v[208:211], v[224:227], v[2:5]
	s_setprio 0
	s_add_i32 s6, s6, 2
	s_addk_i32 s7, 0x100
	s_cmpk_lt_u32 s6, 0x54
	s_cbranch_scc1 .Lrot_25976
	s_barrier
	v_readfirstlane_b32 s0, v156
	s_mov_b32 s10, s2
	s_mov_b32 s11, s3
	s_mov_b32 m0, s0
	v_readfirstlane_b32 s0, v159
	ds_read_b128 v[144:147], v160
	ds_read_b128 v[148:151], v160 offset:1024
	ds_read_b128 v[164:167], v160 offset:2048
	ds_read_b128 v[168:171], v160 offset:3072
	ds_read_b128 v[172:175], v138
	ds_read_b128 v[176:179], v138 offset:1024
	ds_read_b128 v[180:183], v137
	ds_read_b128 v[184:187], v137 offset:1024
	ds_read_b128 v[188:191], v133
	ds_read_b128 v[192:195], v133 offset:1024
	ds_read_b128 v[196:199], v132
	ds_read_b128 v[200:203], v132 offset:1024
	buffer_load_dwordx4 v139, s[8:11], s34 offen lds
	s_mov_b32 m0, s0
	s_nop 0
	buffer_load_dwordx4 v141, s[8:11], s34 offen lds
	s_barrier
	s_waitcnt lgkmcnt(0)
	s_setprio 1
	s_waitcnt lgkmcnt(7)
	v_mfma_f32_16x16x32_bf16 v[126:129], v[172:175], v[144:147], v[126:129]
	v_mfma_f32_16x16x32_bf16 v[122:125], v[172:175], v[164:167], v[122:125]
	s_waitcnt lgkmcnt(5)
	v_mfma_f32_16x16x32_bf16 v[118:121], v[180:183], v[144:147], v[118:121]
	v_mfma_f32_16x16x32_bf16 v[114:117], v[180:183], v[164:167], v[114:117]
	s_waitcnt lgkmcnt(3)
	v_mfma_f32_16x16x32_bf16 v[110:113], v[188:191], v[144:147], v[110:113]
	v_mfma_f32_16x16x32_bf16 v[106:109], v[188:191], v[164:167], v[106:109]
	s_waitcnt lgkmcnt(1)
	v_mfma_f32_16x16x32_bf16 v[102:105], v[196:199], v[144:147], v[102:105]
	v_mfma_f32_16x16x32_bf16 v[98:101], v[196:199], v[164:167], v[98:101]
	v_mfma_f32_16x16x32_bf16 v[126:129], v[176:179], v[148:151], v[126:129]
	v_mfma_f32_16x16x32_bf16 v[122:125], v[176:179], v[168:171], v[122:125]
	v_mfma_f32_16x16x32_bf16 v[118:121], v[184:187], v[148:151], v[118:121]
	v_mfma_f32_16x16x32_bf16 v[114:117], v[184:187], v[168:171], v[114:117]
	v_mfma_f32_16x16x32_bf16 v[110:113], v[192:195], v[148:151], v[110:113]
	v_mfma_f32_16x16x32_bf16 v[106:109], v[192:195], v[168:171], v[106:109]
	s_waitcnt lgkmcnt(0)
	v_mfma_f32_16x16x32_bf16 v[102:105], v[200:203], v[148:151], v[102:105]
	v_mfma_f32_16x16x32_bf16 v[98:101], v[200:203], v[168:171], v[98:101]
	s_setprio 0
	s_barrier
	ds_read_b128 v[156:159], v154
	ds_read_b128 v[204:207], v154 offset:1024
	ds_read_b128 v[208:211], v154 offset:2048
	ds_read_b128 v[152:155], v154 offset:3072
	s_barrier
	s_waitcnt lgkmcnt(0)
	s_setprio 1
	s_waitcnt lgkmcnt(3)
	v_mfma_f32_16x16x32_bf16 v[94:97], v[172:175], v[156:159], v[94:97]
	s_waitcnt lgkmcnt(1)
	v_mfma_f32_16x16x32_bf16 v[90:93], v[172:175], v[208:211], v[90:93]
	v_mfma_f32_16x16x32_bf16 v[86:89], v[180:183], v[156:159], v[86:89]
	v_mfma_f32_16x16x32_bf16 v[82:85], v[180:183], v[208:211], v[82:85]
	v_mfma_f32_16x16x32_bf16 v[78:81], v[188:191], v[156:159], v[78:81]
	v_mfma_f32_16x16x32_bf16 v[74:77], v[188:191], v[208:211], v[74:77]
	v_mfma_f32_16x16x32_bf16 v[70:73], v[196:199], v[156:159], v[70:73]
	v_mfma_f32_16x16x32_bf16 v[94:97], v[176:179], v[204:207], v[94:97]
	s_waitcnt lgkmcnt(0)
	v_mfma_f32_16x16x32_bf16 v[90:93], v[176:179], v[152:155], v[90:93]
	v_mfma_f32_16x16x32_bf16 v[86:89], v[184:187], v[204:207], v[86:89]
	v_mfma_f32_16x16x32_bf16 v[82:85], v[184:187], v[152:155], v[82:85]
	v_mfma_f32_16x16x32_bf16 v[78:81], v[192:195], v[204:207], v[78:81]
	v_mfma_f32_16x16x32_bf16 v[74:77], v[192:195], v[152:155], v[74:77]
	v_mfma_f32_16x16x32_bf16 v[70:73], v[200:203], v[204:207], v[70:73]
	v_mfma_f32_16x16x32_bf16 v[66:69], v[196:199], v[208:211], v[66:69]
	v_mfma_f32_16x16x32_bf16 v[172:175], v[200:203], v[152:155], v[66:69]
	s_setprio 0
	s_barrier
; #define LDA_(dst, b, h) _Pragma("unroll") for (int m = 0; m < 4; ++m) _Pragma("unroll") for (int k = 0; k < 2; ++k) \
;     dst[m][k] = *reinterpret_cast<const bf16x8*>((char*)SA(b, h) + lds_byte(wr * 64 + m * 16 + fr, k * 32 + fq * 8))
; #define LDB_(dst, b, h) _Pragma("unroll") for (int n = 0; n < 2; ++n) _Pragma("unroll") for (int k = 0; k < 2; ++k) \
;     dst[n][k] = *reinterpret_cast<const bf16x8*>((char*)SB(b, h) + lds_byte(wc * 32 + n * 16 + fr, k * 32 + fq * 8))
; #define MMA(ai, bj, At, Bx) do { __builtin_amdgcn_s_setprio(1); \
;     _Pragma("unroll") for (int m = 0; m < 4; ++m) _Pragma("unroll") for (int n = 0; n < 2; ++n) _Pragma("unroll") for (int k = 0; k < 2; ++k) \
;       acc[ai][bj][m][n] = __builtin_amdgcn_mfma_f32_16x16x32_bf16(At[m][k], Bx[n][k], acc[ai][bj][m][n], 0, 0, 0); \
;     __builtin_amdgcn_s_setprio(0); } while (0)
; #define WAIT_V(n) asm volatile("s_waitcnt vmcnt(" #n ")" ::: "memory")
; #define WAIT_L(n) asm volatile("s_waitcnt lgkmcnt(" #n ")" ::: "memory")
; #define BAR __builtin_amdgcn_s_barrier()
; template <int K, int LDA, int LDB>
; DEVI void gemm_tile(const bf16* __restrict__ A, const bf16* __restrict__ Bt, bf16* shm, acc_t& acc) {
;     ...
;     LDA_(At, 0, 1); WAIT_V(4); BAR; WAIT_L(0); MMA(1, 0, At, B0); MMA(1, 1, At, B1); BAR; }
;   { LDB_(B0, 1, 0); LDA_(At, 1, 0); WAIT_V(2); BAR; WAIT_L(0); MMA(0, 0, At, B0); BAR;
	s_nop 4
	ds_read_b128 v[66:69], v138 offset:16384
	ds_read_b128 v[176:179], v138 offset:17408
	ds_read_b128 v[180:183], v137 offset:16384
	ds_read_b128 v[184:187], v137 offset:17408
	ds_read_b128 v[188:191], v133 offset:16384
	ds_read_b128 v[192:195], v133 offset:17408
	ds_read_b128 v[196:199], v132 offset:16384
	ds_read_b128 v[200:203], v132 offset:17408
	s_waitcnt vmcnt(4)
	s_barrier
	s_waitcnt lgkmcnt(0)
	s_setprio 1
	s_waitcnt lgkmcnt(3)
	v_mfma_f32_16x16x32_bf16 v[42:45], v[188:191], v[164:167], v[42:45]
	s_waitcnt lgkmcnt(1)
	v_mfma_f32_16x16x32_bf16 v[38:41], v[196:199], v[144:147], v[38:41]
	v_mfma_f32_16x16x32_bf16 v[34:37], v[196:199], v[164:167], v[34:37]
	v_mfma_f32_16x16x32_bf16 v[62:65], v[66:69], v[144:147], v[62:65]
	v_mfma_f32_16x16x32_bf16 v[58:61], v[66:69], v[164:167], v[58:61]
	v_mfma_f32_16x16x32_bf16 v[54:57], v[180:183], v[144:147], v[54:57]
	v_mfma_f32_16x16x32_bf16 v[50:53], v[180:183], v[164:167], v[50:53]
	v_mfma_f32_16x16x32_bf16 v[46:49], v[188:191], v[144:147], v[46:49]
	v_mfma_f32_16x16x32_bf16 v[42:45], v[192:195], v[168:171], v[42:45]
	s_waitcnt lgkmcnt(0)
	v_mfma_f32_16x16x32_bf16 v[38:41], v[200:203], v[148:151], v[38:41]
	v_mfma_f32_16x16x32_bf16 v[34:37], v[200:203], v[168:171], v[34:37]
	v_mfma_f32_16x16x32_bf16 v[212:215], v[176:179], v[148:151], v[62:65]
	v_mfma_f32_16x16x32_bf16 v[216:219], v[176:179], v[168:171], v[58:61]
	v_mfma_f32_16x16x32_bf16 v[220:223], v[184:187], v[148:151], v[54:57]
	v_mfma_f32_16x16x32_bf16 v[224:227], v[184:187], v[168:171], v[50:53]
	v_mfma_f32_16x16x32_bf16 v[228:231], v[192:195], v[148:151], v[46:49]
	s_setprio 0
	s_setprio 1
	v_mfma_f32_16x16x32_bf16 v[26:29], v[66:69], v[208:211], v[26:29]
	v_mfma_f32_16x16x32_bf16 v[22:25], v[180:183], v[156:159], v[22:25]
	v_mfma_f32_16x16x32_bf16 v[18:21], v[180:183], v[208:211], v[18:21]
	v_mfma_f32_16x16x32_bf16 v[10:13], v[188:191], v[208:211], v[10:13]
	v_mfma_f32_16x16x32_bf16 v[6:9], v[196:199], v[156:159], v[6:9]
	v_mfma_f32_16x16x32_bf16 v[2:5], v[196:199], v[208:211], v[2:5]
	v_mfma_f32_16x16x32_bf16 v[30:33], v[66:69], v[156:159], v[30:33]
	v_mfma_f32_16x16x32_bf16 v[26:29], v[176:179], v[152:155], v[26:29]
	v_mfma_f32_16x16x32_bf16 v[22:25], v[184:187], v[204:207], v[22:25]
	v_mfma_f32_16x16x32_bf16 v[18:21], v[184:187], v[152:155], v[18:21]
	v_mfma_f32_16x16x32_bf16 v[14:17], v[188:191], v[156:159], v[14:17]
	v_mfma_f32_16x16x32_bf16 v[10:13], v[192:195], v[152:155], v[10:13]
	v_mfma_f32_16x16x32_bf16 v[6:9], v[200:203], v[204:207], v[6:9]
	v_mfma_f32_16x16x32_bf16 v[2:5], v[200:203], v[152:155], v[2:5]
	v_mfma_f32_16x16x32_bf16 v[144:147], v[176:179], v[204:207], v[30:33]
	v_mfma_f32_16x16x32_bf16 v[148:151], v[192:195], v[204:207], v[14:17]
	s_setprio 0
	s_barrier
	ds_read_b128 v[152:155], v142
	ds_read_b128 v[156:159], v142 offset:1024
	ds_read_b128 v[164:167], v142 offset:2048
	ds_read_b128 v[168:171], v142 offset:3072
	ds_read_b128 v[58:61], v138 offset:32768
	ds_read_b128 v[62:65], v138 offset:33792
	ds_read_b128 v[66:69], v137 offset:32768
	ds_read_b128 v[176:179], v137 offset:33792
	ds_read_b128 v[180:183], v133 offset:32768
	ds_read_b128 v[184:187], v133 offset:33792
	ds_read_b128 v[188:191], v132 offset:32768
	ds_read_b128 v[192:195], v132 offset:33792
	s_waitcnt vmcnt(2)
	s_barrier
	s_waitcnt lgkmcnt(0)
	s_setprio 1
	s_waitcnt lgkmcnt(7)
	v_mfma_f32_16x16x32_bf16 v[14:17], v[58:61], v[152:155], v[126:129]
	s_waitcnt lgkmcnt(5)
	v_mfma_f32_16x16x32_bf16 v[30:33], v[66:69], v[152:155], v[118:121]
	s_waitcnt lgkmcnt(3)
	v_mfma_f32_16x16x32_bf16 v[46:49], v[180:183], v[152:155], v[110:113]
	s_waitcnt lgkmcnt(1)
	v_mfma_f32_16x16x32_bf16 v[50:53], v[188:191], v[152:155], v[102:105]
	v_mfma_f32_16x16x32_bf16 v[126:129], v[62:65], v[156:159], v[14:17]
	v_mfma_f32_16x16x32_bf16 v[14:17], v[58:61], v[164:167], v[122:125]
	v_mfma_f32_16x16x32_bf16 v[122:125], v[176:179], v[156:159], v[30:33]
	v_mfma_f32_16x16x32_bf16 v[30:33], v[66:69], v[164:167], v[114:117]
	v_mfma_f32_16x16x32_bf16 v[118:121], v[184:187], v[156:159], v[46:49]
	v_mfma_f32_16x16x32_bf16 v[46:49], v[180:183], v[164:167], v[106:109]
	s_waitcnt lgkmcnt(0)
	v_mfma_f32_16x16x32_bf16 v[114:117], v[192:195], v[156:159], v[50:53]
	v_mfma_f32_16x16x32_bf16 v[50:53], v[188:191], v[164:167], v[98:101]
	v_mfma_f32_16x16x32_bf16 v[14:17], v[62:65], v[168:171], v[14:17]
	v_mfma_f32_16x16x32_bf16 v[30:33], v[176:179], v[168:171], v[30:33]
	v_mfma_f32_16x16x32_bf16 v[46:49], v[184:187], v[168:171], v[46:49]
	v_mfma_f32_16x16x32_bf16 v[54:57], v[192:195], v[168:171], v[50:53]
	s_setprio 0
	s_barrier
; #define LDA_(dst, b, h) _Pragma("unroll") for (int m = 0; m < 4; ++m) _Pragma("unroll") for (int k = 0; k < 2; ++k) \
;     dst[m][k] = *reinterpret_cast<const bf16x8*>((char*)SA(b, h) + lds_byte(wr * 64 + m * 16 + fr, k * 32 + fq * 8))
; #define LDB_(dst, b, h) _Pragma("unroll") for (int n = 0; n < 2; ++n) _Pragma("unroll") for (int k = 0; k < 2; ++k) \
;     dst[n][k] = *reinterpret_cast<const bf16x8*>((char*)SB(b, h) + lds_byte(wc * 32 + n * 16 + fr, k * 32 + fq * 8))
; #define MMA(ai, bj, At, Bx) do { __builtin_amdgcn_s_setprio(1); \
;     _Pragma("unroll") for (int m = 0; m < 4; ++m) _Pragma("unroll") for (int n = 0; n < 2; ++n) _Pragma("unroll") for (int k = 0; k < 2; ++k) \
;       acc[ai][bj][m][n] = __builtin_amdgcn_mfma_f32_16x16x32_bf16(At[m][k], Bx[n][k], acc[ai][bj][m][n], 0, 0, 0); \
;     __builtin_amdgcn_s_setprio(0); } while (0)
; #define WAIT_V(n) asm volatile("s_waitcnt vmcnt(" #n ")" ::: "memory")
; #define WAIT_L(n) asm volatile("s_waitcnt lgkmcnt(" #n ")" ::: "memory")
; #define BAR __builtin_amdgcn_s_barrier()
; template <int K, int LDA, int LDB>
; DEVI void gemm_tile(const bf16* __restrict__ A, const bf16* __restrict__ Bt, bf16* shm, acc_t& acc) {
;     ...
;     LDB_(B1, 1, 1); WAIT_V(0); BAR; WAIT_L(0); MMA(0, 1, At, B1); BAR;
;     LDA_(At, 1, 1); BAR; WAIT_L(0); MMA(1, 0, At, B0); MMA(1, 1, At, B1); BAR; }
;   if (wr == 0) BAR;
	ds_read_b128 v[196:199], v140
	ds_read_b128 v[200:203], v140 offset:1024
	ds_read_b128 v[204:207], v140 offset:2048
	ds_read_b128 v[140:143], v140 offset:3072
	s_waitcnt vmcnt(0)
	s_barrier
	s_waitcnt lgkmcnt(0)
	s_setprio 1
	s_waitcnt lgkmcnt(3)
	v_mfma_f32_16x16x32_bf16 v[50:53], v[58:61], v[196:199], v[94:97]
	s_waitcnt lgkmcnt(1)
	v_mfma_f32_16x16x32_bf16 v[58:61], v[58:61], v[204:207], v[90:93]
	v_mfma_f32_16x16x32_bf16 v[70:73], v[188:191], v[196:199], v[70:73]
	v_mfma_f32_16x16x32_bf16 v[50:53], v[62:65], v[200:203], v[50:53]
	s_waitcnt lgkmcnt(0)
	v_mfma_f32_16x16x32_bf16 v[58:61], v[62:65], v[140:143], v[58:61]
	v_mfma_f32_16x16x32_bf16 v[62:65], v[66:69], v[196:199], v[86:89]
	v_mfma_f32_16x16x32_bf16 v[66:69], v[66:69], v[204:207], v[82:85]
	v_mfma_f32_16x16x32_bf16 v[78:81], v[180:183], v[196:199], v[78:81]
	v_mfma_f32_16x16x32_bf16 v[74:77], v[180:183], v[204:207], v[74:77]
	v_mfma_f32_16x16x32_bf16 v[94:97], v[192:195], v[200:203], v[70:73]
	v_mfma_f32_16x16x32_bf16 v[70:73], v[188:191], v[204:207], v[172:175]
	v_mfma_f32_16x16x32_bf16 v[62:65], v[176:179], v[200:203], v[62:65]
	v_mfma_f32_16x16x32_bf16 v[66:69], v[176:179], v[140:143], v[66:69]
	v_mfma_f32_16x16x32_bf16 v[78:81], v[184:187], v[200:203], v[78:81]
	v_mfma_f32_16x16x32_bf16 v[82:85], v[184:187], v[140:143], v[74:77]
	v_mfma_f32_16x16x32_bf16 v[98:101], v[192:195], v[140:143], v[70:73]
	s_setprio 0
	s_barrier
	ds_read_b128 v[172:175], v138 offset:49152
	ds_read_b128 v[176:179], v138 offset:50176
	ds_read_b128 v[180:183], v137 offset:49152
	ds_read_b128 v[184:187], v137 offset:50176
	ds_read_b128 v[188:191], v133 offset:49152
	ds_read_b128 v[192:195], v133 offset:50176
	ds_read_b128 v[208:211], v132 offset:49152
	ds_read_b128 v[232:235], v132 offset:50176
	s_barrier
	s_waitcnt lgkmcnt(0)
	s_setprio 1
	s_waitcnt lgkmcnt(7)
	v_mfma_f32_16x16x32_bf16 v[70:73], v[172:175], v[152:155], v[212:215]
	s_waitcnt lgkmcnt(6)
	v_mfma_f32_16x16x32_bf16 v[110:113], v[176:179], v[156:159], v[70:73]
	v_mfma_f32_16x16x32_bf16 v[70:73], v[172:175], v[164:167], v[216:219]
	v_mfma_f32_16x16x32_bf16 v[106:109], v[176:179], v[168:171], v[70:73]
	s_waitcnt lgkmcnt(5)
	v_mfma_f32_16x16x32_bf16 v[70:73], v[180:183], v[152:155], v[220:223]
	s_waitcnt lgkmcnt(4)
	v_mfma_f32_16x16x32_bf16 v[102:105], v[184:187], v[156:159], v[70:73]
	v_mfma_f32_16x16x32_bf16 v[70:73], v[180:183], v[164:167], v[224:227]
	v_mfma_f32_16x16x32_bf16 v[90:93], v[184:187], v[168:171], v[70:73]
	s_waitcnt lgkmcnt(3)
	v_mfma_f32_16x16x32_bf16 v[70:73], v[188:191], v[152:155], v[228:231]
	v_mfma_f32_16x16x32_bf16 v[42:45], v[188:191], v[164:167], v[42:45]
	s_waitcnt lgkmcnt(1)
	v_mfma_f32_16x16x32_bf16 v[38:41], v[208:211], v[152:155], v[38:41]
	v_mfma_f32_16x16x32_bf16 v[34:37], v[208:211], v[164:167], v[34:37]
	v_mfma_f32_16x16x32_bf16 v[86:89], v[192:195], v[156:159], v[70:73]
	v_mfma_f32_16x16x32_bf16 v[74:77], v[192:195], v[168:171], v[42:45]
	s_waitcnt lgkmcnt(0)
	v_mfma_f32_16x16x32_bf16 v[70:73], v[232:235], v[156:159], v[38:41]
	v_mfma_f32_16x16x32_bf16 v[42:45], v[232:235], v[168:171], v[34:37]
	s_setprio 0
	s_setprio 1
	v_mfma_f32_16x16x32_bf16 v[34:37], v[172:175], v[196:199], v[144:147]
	v_mfma_f32_16x16x32_bf16 v[26:29], v[172:175], v[204:207], v[26:29]
	v_mfma_f32_16x16x32_bf16 v[22:25], v[180:183], v[196:199], v[22:25]
	v_mfma_f32_16x16x32_bf16 v[18:21], v[180:183], v[204:207], v[18:21]
	v_mfma_f32_16x16x32_bf16 v[38:41], v[176:179], v[200:203], v[34:37]
	v_mfma_f32_16x16x32_bf16 v[34:37], v[176:179], v[140:143], v[26:29]
	v_mfma_f32_16x16x32_bf16 v[26:29], v[184:187], v[200:203], v[22:25]
	v_mfma_f32_16x16x32_bf16 v[22:25], v[184:187], v[140:143], v[18:21]
	v_mfma_f32_16x16x32_bf16 v[18:21], v[188:191], v[196:199], v[148:151]
	v_mfma_f32_16x16x32_bf16 v[10:13], v[188:191], v[204:207], v[10:13]
	v_mfma_f32_16x16x32_bf16 v[6:9], v[208:211], v[196:199], v[6:9]
	v_mfma_f32_16x16x32_bf16 v[2:5], v[208:211], v[204:207], v[2:5]
	v_mfma_f32_16x16x32_bf16 v[18:21], v[192:195], v[200:203], v[18:21]
	v_mfma_f32_16x16x32_bf16 v[10:13], v[192:195], v[140:143], v[10:13]
	v_mfma_f32_16x16x32_bf16 v[6:9], v[232:235], v[200:203], v[6:9]
	v_mfma_f32_16x16x32_bf16 v[2:5], v[232:235], v[140:143], v[2:5]
	s_setprio 0
	s_movk_i32 s0, 0x100
	v_cmp_gt_u32_e32 vcc, s0, v130
	s_barrier
	s_and_saveexec_b64 s[0:1], vcc
	s_cbranch_execz .LBB0_1273
	s_barrier

; #define STAGE(P, BASE, LD, br, kt) do { const int _so = (int)(((br) * (LD) + (kt) * BK) * 2); \
;     _Pragma("unroll") for (int _i = 0; _i < 2; ++_i) { \
;       __builtin_amdgcn_raw_ptr_buffer_load_lds(rs##BASE, (__attribute__((address_space(3))) unsigned*)((char*)(P) + tid_ * 16 + _i * 8192), 16, (int)off##LD[_i], _so, 0, 0); } } while (0)
; #define LDA_(dst, b, h) _Pragma("unroll") for (int m = 0; m < 4; ++m) _Pragma("unroll") for (int k = 0; k < 2; ++k) \
;     dst[m][k] = *reinterpret_cast<const bf16x8*>((char*)SA(b, h) + lds_byte(wr * 64 + m * 16 + fr, k * 32 + fq * 8))
; #define LDB_(dst, b, h) _Pragma("unroll") for (int n = 0; n < 2; ++n) _Pragma("unroll") for (int k = 0; k < 2; ++k) \
;     dst[n][k] = *reinterpret_cast<const bf16x8*>((char*)SB(b, h) + lds_byte(wc * 32 + n * 16 + fr, k * 32 + fq * 8))
; #define MMA(ai, bj, At, Bx) do { __builtin_amdgcn_s_setprio(1); \
;     _Pragma("unroll") for (int m = 0; m < 4; ++m) _Pragma("unroll") for (int n = 0; n < 2; ++n) _Pragma("unroll") for (int k = 0; k < 2; ++k) \
;       acc[ai][bj][m][n] = __builtin_amdgcn_mfma_f32_16x16x32_bf16(At[m][k], Bx[n][k], acc[ai][bj][m][n], 0, 0, 0); \
;     __builtin_amdgcn_s_setprio(0); } while (0)
; #define WAIT_L(n) asm volatile("s_waitcnt lgkmcnt(" #n ")" ::: "memory")
; #define BAR __builtin_amdgcn_s_barrier()
; #define SCHED __builtin_amdgcn_sched_barrier(0)
; template <int K, int LDA, int LDB>
; DEVI void gemm_tile(const bf16* __restrict__ A, const bf16* __restrict__ Bt, bf16* shm, acc_t& acc) {
;     ...
;     LDB_(B0, 0, 0); SCHED; LDA_(At, 0, 0); STAGE(SA(1, 1), A, LDA, HALF, t + 1);
;     WAIT_L(8); BAR; WAIT_L(0); MMA(0, 0, At, B0); BAR; SCHED;
;     LDB_(B1, 0, 1); STAGE(SB(0, 0), Bt, LDB, 0, t + 2);
;     BAR; WAIT_L(0); MMA(0, 1, At, B1); BAR;
;     LDA_(At, 0, 1); STAGE(SA(0, 0), A, LDA, 0, t + 2);
;     BAR; WAIT_L(0); MMA(1, 0, At, B0); BAR; SCHED;
.LBB0_1449:
	ds_read_b128 v[166:169], v165
	ds_read_b128 v[170:173], v165 offset:1024
	ds_read_b128 v[174:177], v165 offset:2048
	ds_read_b128 v[178:181], v165 offset:3072
	v_readfirstlane_b32 s50, v159
	s_add_i32 s49, s23, 0xffffff00
	s_mov_b32 m0, s50
	v_readfirstlane_b32 s50, v164
	ds_read_b128 v[182:185], v135
	ds_read_b128 v[186:189], v135 offset:1024
	ds_read_b128 v[190:193], v134
	ds_read_b128 v[194:197], v134 offset:1024
	ds_read_b128 v[198:201], v133
	ds_read_b128 v[202:205], v133 offset:1024
	ds_read_b128 v[206:209], v132
	ds_read_b128 v[210:213], v132 offset:1024
	buffer_load_dwordx4 v136, s[8:11], s49 offen lds
	s_mov_b32 m0, s50
	s_nop 0
	buffer_load_dwordx4 v144, s[8:11], s49 offen lds
	s_waitcnt lgkmcnt(8)
	s_barrier
	s_waitcnt lgkmcnt(0)
	s_setprio 1
	s_waitcnt lgkmcnt(7)
	v_mfma_f32_16x16x32_bf16 v[126:129], v[182:185], v[166:169], v[126:129]
	v_mfma_f32_16x16x32_bf16 v[122:125], v[182:185], v[174:177], v[122:125]
	s_waitcnt lgkmcnt(5)
	v_mfma_f32_16x16x32_bf16 v[118:121], v[190:193], v[166:169], v[118:121]
	v_mfma_f32_16x16x32_bf16 v[114:117], v[190:193], v[174:177], v[114:117]
	s_waitcnt lgkmcnt(3)
	v_mfma_f32_16x16x32_bf16 v[110:113], v[198:201], v[166:169], v[110:113]
	v_mfma_f32_16x16x32_bf16 v[106:109], v[198:201], v[174:177], v[106:109]
	s_waitcnt lgkmcnt(1)
	v_mfma_f32_16x16x32_bf16 v[102:105], v[206:209], v[166:169], v[102:105]
	v_mfma_f32_16x16x32_bf16 v[98:101], v[206:209], v[174:177], v[98:101]
	v_mfma_f32_16x16x32_bf16 v[126:129], v[186:189], v[170:173], v[126:129]
	v_mfma_f32_16x16x32_bf16 v[122:125], v[186:189], v[178:181], v[122:125]
	v_mfma_f32_16x16x32_bf16 v[118:121], v[194:197], v[170:173], v[118:121]
	v_mfma_f32_16x16x32_bf16 v[114:117], v[194:197], v[178:181], v[114:117]
	v_mfma_f32_16x16x32_bf16 v[110:113], v[202:205], v[170:173], v[110:113]
	v_mfma_f32_16x16x32_bf16 v[106:109], v[202:205], v[178:181], v[106:109]
	s_waitcnt lgkmcnt(0)
	v_mfma_f32_16x16x32_bf16 v[102:105], v[210:213], v[170:173], v[102:105]
	v_mfma_f32_16x16x32_bf16 v[98:101], v[210:213], v[178:181], v[98:101]
	s_setprio 0
	s_barrier
	v_readfirstlane_b32 s50, v146
	s_add_i32 s49, s23, 0xfff7ff80
	s_mov_b32 m0, s50
	v_readfirstlane_b32 s50, v147
	ds_read_b128 v[214:217], v157
	ds_read_b128 v[218:221], v157 offset:1024
	ds_read_b128 v[222:225], v157 offset:2048
	ds_read_b128 v[226:229], v157 offset:3072
	buffer_load_dwordx4 v136, s[4:7], s49 offen lds
	s_mov_b32 m0, s50
	s_nop 0
	buffer_load_dwordx4 v144, s[4:7], s49 offen lds
	s_barrier
	s_waitcnt lgkmcnt(0)
	s_setprio 1
	s_waitcnt lgkmcnt(3)
	v_mfma_f32_16x16x32_bf16 v[94:97], v[182:185], v[214:217], v[94:97]
	s_waitcnt lgkmcnt(1)
	v_mfma_f32_16x16x32_bf16 v[90:93], v[182:185], v[222:225], v[90:93]
	v_mfma_f32_16x16x32_bf16 v[86:89], v[190:193], v[214:217], v[86:89]
	v_mfma_f32_16x16x32_bf16 v[82:85], v[190:193], v[222:225], v[82:85]
	v_mfma_f32_16x16x32_bf16 v[78:81], v[198:201], v[214:217], v[78:81]
	v_mfma_f32_16x16x32_bf16 v[74:77], v[198:201], v[222:225], v[74:77]
	v_mfma_f32_16x16x32_bf16 v[70:73], v[206:209], v[214:217], v[70:73]
	v_mfma_f32_16x16x32_bf16 v[66:69], v[206:209], v[222:225], v[66:69]
	v_mfma_f32_16x16x32_bf16 v[94:97], v[186:189], v[218:221], v[94:97]
	s_waitcnt lgkmcnt(0)
	v_mfma_f32_16x16x32_bf16 v[90:93], v[186:189], v[226:229], v[90:93]
	v_mfma_f32_16x16x32_bf16 v[86:89], v[194:197], v[218:221], v[86:89]
	v_mfma_f32_16x16x32_bf16 v[82:85], v[194:197], v[226:229], v[82:85]
	v_mfma_f32_16x16x32_bf16 v[78:81], v[202:205], v[218:221], v[78:81]
	v_mfma_f32_16x16x32_bf16 v[74:77], v[202:205], v[226:229], v[74:77]
	v_mfma_f32_16x16x32_bf16 v[70:73], v[210:213], v[218:221], v[70:73]
	v_mfma_f32_16x16x32_bf16 v[66:69], v[210:213], v[226:229], v[66:69]
	s_setprio 0
	v_readfirstlane_b32 s50, v148
	s_mov_b32 m0, s50
	v_readfirstlane_b32 s50, v149
	s_barrier
	ds_read_b128 v[182:185], v135 offset:16384
	ds_read_b128 v[186:189], v135 offset:17408
	ds_read_b128 v[190:193], v134 offset:16384
	ds_read_b128 v[194:197], v134 offset:17408
	ds_read_b128 v[198:201], v133 offset:16384
	ds_read_b128 v[202:205], v133 offset:17408
	ds_read_b128 v[206:209], v132 offset:16384
	ds_read_b128 v[210:213], v132 offset:17408
	buffer_load_dwordx4 v136, s[8:11], s49 offen lds
	s_mov_b32 m0, s50
	s_nop 0
	buffer_load_dwordx4 v144, s[8:11], s49 offen lds
	s_barrier
	s_waitcnt lgkmcnt(0)
	s_setprio 1
	s_waitcnt lgkmcnt(7)
	v_mfma_f32_16x16x32_bf16 v[62:65], v[182:185], v[166:169], v[62:65]
	v_mfma_f32_16x16x32_bf16 v[58:61], v[182:185], v[174:177], v[58:61]
	s_waitcnt lgkmcnt(5)
	v_mfma_f32_16x16x32_bf16 v[54:57], v[190:193], v[166:169], v[54:57]
	v_mfma_f32_16x16x32_bf16 v[50:53], v[190:193], v[174:177], v[50:53]
	s_waitcnt lgkmcnt(3)
	v_mfma_f32_16x16x32_bf16 v[46:49], v[198:201], v[166:169], v[46:49]
	v_mfma_f32_16x16x32_bf16 v[42:45], v[198:201], v[174:177], v[42:45]
	s_waitcnt lgkmcnt(1)
	v_mfma_f32_16x16x32_bf16 v[38:41], v[206:209], v[166:169], v[38:41]
	v_mfma_f32_16x16x32_bf16 v[34:37], v[206:209], v[174:177], v[34:37]
	v_mfma_f32_16x16x32_bf16 v[62:65], v[186:189], v[170:173], v[62:65]
	v_mfma_f32_16x16x32_bf16 v[58:61], v[186:189], v[178:181], v[58:61]
	v_mfma_f32_16x16x32_bf16 v[54:57], v[194:197], v[170:173], v[54:57]
	v_mfma_f32_16x16x32_bf16 v[50:53], v[194:197], v[178:181], v[50:53]
	v_mfma_f32_16x16x32_bf16 v[46:49], v[202:205], v[170:173], v[46:49]
	v_mfma_f32_16x16x32_bf16 v[42:45], v[202:205], v[178:181], v[42:45]
	s_waitcnt lgkmcnt(0)
	v_mfma_f32_16x16x32_bf16 v[38:41], v[210:213], v[170:173], v[38:41]
	v_mfma_f32_16x16x32_bf16 v[34:37], v[210:213], v[178:181], v[34:37]
	s_setprio 0
	s_barrier
; #define STAGE(P, BASE, LD, br, kt) do { const int _so = (int)(((br) * (LD) + (kt) * BK) * 2); \
;     _Pragma("unroll") for (int _i = 0; _i < 2; ++_i) { \
;       __builtin_amdgcn_raw_ptr_buffer_load_lds(rs##BASE, (__attribute__((address_space(3))) unsigned*)((char*)(P) + tid_ * 16 + _i * 8192), 16, (int)off##LD[_i], _so, 0, 0); } } while (0)
; #define LDA_(dst, b, h) _Pragma("unroll") for (int m = 0; m < 4; ++m) _Pragma("unroll") for (int k = 0; k < 2; ++k) \
;     dst[m][k] = *reinterpret_cast<const bf16x8*>((char*)SA(b, h) + lds_byte(wr * 64 + m * 16 + fr, k * 32 + fq * 8))
; #define LDB_(dst, b, h) _Pragma("unroll") for (int n = 0; n < 2; ++n) _Pragma("unroll") for (int k = 0; k < 2; ++k) \
;     dst[n][k] = *reinterpret_cast<const bf16x8*>((char*)SB(b, h) + lds_byte(wc * 32 + n * 16 + fr, k * 32 + fq * 8))
; #define MMA(ai, bj, At, Bx) do { __builtin_amdgcn_s_setprio(1); \
;     _Pragma("unroll") for (int m = 0; m < 4; ++m) _Pragma("unroll") for (int n = 0; n < 2; ++n) _Pragma("unroll") for (int k = 0; k < 2; ++k) \
;       acc[ai][bj][m][n] = __builtin_amdgcn_mfma_f32_16x16x32_bf16(At[m][k], Bx[n][k], acc[ai][bj][m][n], 0, 0, 0); \
;     __builtin_amdgcn_s_setprio(0); } while (0)
; #define WAIT_V(n) asm volatile("s_waitcnt vmcnt(" #n ")" ::: "memory")
; #define WAIT_L(n) asm volatile("s_waitcnt lgkmcnt(" #n ")" ::: "memory")
; #define BAR __builtin_amdgcn_s_barrier()
; #define SCHED __builtin_amdgcn_sched_barrier(0)
; template <int K, int LDA, int LDB>
; DEVI void gemm_tile(const bf16* __restrict__ A, const bf16* __restrict__ Bt, bf16* shm, acc_t& acc) {
;     ...
;     STAGE(SB(0, 1), Bt, LDB, HALF, t + 2);
;     WAIT_V(6); BAR; MMA(1, 1, At, B1); BAR;
;     LDB_(B0, 1, 0); SCHED; LDA_(At, 1, 0); STAGE(SA(0, 1), A, LDA, HALF, t + 2);
;     WAIT_L(8); BAR; WAIT_L(0); MMA(0, 0, At, B0); BAR; SCHED;
;     LDB_(B1, 1, 1); STAGE(SB(1, 0), Bt, LDB, 0, t + 3);
;     BAR; WAIT_L(0); MMA(0, 1, At, B1); BAR;
;     LDA_(At, 1, 1); STAGE(SA(1, 0), A, LDA, 0, t + 3);
	v_readfirstlane_b32 s50, v150
	s_add_i32 s49, s23, 0xffffff80
	s_mov_b32 m0, s50
	v_readfirstlane_b32 s50, v151
	buffer_load_dwordx4 v136, s[4:7], s49 offen lds
	s_mov_b32 m0, s50
	s_nop 0
	buffer_load_dwordx4 v144, s[4:7], s49 offen lds
	s_waitcnt vmcnt(6)
	s_barrier
	s_setprio 1
	v_mfma_f32_16x16x32_bf16 v[30:33], v[182:185], v[214:217], v[30:33]
	v_mfma_f32_16x16x32_bf16 v[26:29], v[182:185], v[222:225], v[26:29]
	v_mfma_f32_16x16x32_bf16 v[22:25], v[190:193], v[214:217], v[22:25]
	v_mfma_f32_16x16x32_bf16 v[18:21], v[190:193], v[222:225], v[18:21]
	v_mfma_f32_16x16x32_bf16 v[14:17], v[198:201], v[214:217], v[14:17]
	v_mfma_f32_16x16x32_bf16 v[10:13], v[198:201], v[222:225], v[10:13]
	v_mfma_f32_16x16x32_bf16 v[6:9], v[206:209], v[214:217], v[6:9]
	v_mfma_f32_16x16x32_bf16 v[2:5], v[206:209], v[222:225], v[2:5]
	v_mfma_f32_16x16x32_bf16 v[30:33], v[186:189], v[218:221], v[30:33]
	v_mfma_f32_16x16x32_bf16 v[26:29], v[186:189], v[226:229], v[26:29]
	v_mfma_f32_16x16x32_bf16 v[22:25], v[194:197], v[218:221], v[22:25]
	v_mfma_f32_16x16x32_bf16 v[18:21], v[194:197], v[226:229], v[18:21]
	v_mfma_f32_16x16x32_bf16 v[14:17], v[202:205], v[218:221], v[14:17]
	v_mfma_f32_16x16x32_bf16 v[10:13], v[202:205], v[226:229], v[10:13]
	v_mfma_f32_16x16x32_bf16 v[6:9], v[210:213], v[218:221], v[6:9]
	v_mfma_f32_16x16x32_bf16 v[2:5], v[210:213], v[226:229], v[2:5]
	s_setprio 0
	s_barrier
	ds_read_b128 v[166:169], v145
	ds_read_b128 v[170:173], v145 offset:1024
	ds_read_b128 v[174:177], v145 offset:2048
	ds_read_b128 v[178:181], v145 offset:3072
	v_readfirstlane_b32 s50, v152
	s_mov_b32 m0, s50
	v_readfirstlane_b32 s50, v153
	ds_read_b128 v[182:185], v135 offset:32768
	ds_read_b128 v[186:189], v135 offset:33792
	ds_read_b128 v[190:193], v134 offset:32768
	ds_read_b128 v[194:197], v134 offset:33792
	ds_read_b128 v[198:201], v133 offset:32768
	ds_read_b128 v[202:205], v133 offset:33792
	ds_read_b128 v[206:209], v132 offset:32768
	ds_read_b128 v[210:213], v132 offset:33792
	buffer_load_dwordx4 v136, s[8:11], s49 offen lds
	s_mov_b32 m0, s50
	s_nop 0
	buffer_load_dwordx4 v144, s[8:11], s49 offen lds
	s_waitcnt lgkmcnt(8)
	s_barrier
	s_waitcnt lgkmcnt(0)
	s_setprio 1
	s_waitcnt lgkmcnt(7)
	v_mfma_f32_16x16x32_bf16 v[126:129], v[182:185], v[166:169], v[126:129]
	v_mfma_f32_16x16x32_bf16 v[122:125], v[182:185], v[174:177], v[122:125]
	s_waitcnt lgkmcnt(5)
	v_mfma_f32_16x16x32_bf16 v[118:121], v[190:193], v[166:169], v[118:121]
	v_mfma_f32_16x16x32_bf16 v[114:117], v[190:193], v[174:177], v[114:117]
	s_waitcnt lgkmcnt(3)
	v_mfma_f32_16x16x32_bf16 v[110:113], v[198:201], v[166:169], v[110:113]
	v_mfma_f32_16x16x32_bf16 v[106:109], v[198:201], v[174:177], v[106:109]
	s_waitcnt lgkmcnt(1)
	v_mfma_f32_16x16x32_bf16 v[102:105], v[206:209], v[166:169], v[102:105]
	v_mfma_f32_16x16x32_bf16 v[98:101], v[206:209], v[174:177], v[98:101]
	v_mfma_f32_16x16x32_bf16 v[126:129], v[186:189], v[170:173], v[126:129]
	v_mfma_f32_16x16x32_bf16 v[122:125], v[186:189], v[178:181], v[122:125]
	v_mfma_f32_16x16x32_bf16 v[118:121], v[194:197], v[170:173], v[118:121]
	v_mfma_f32_16x16x32_bf16 v[114:117], v[194:197], v[178:181], v[114:117]
	v_mfma_f32_16x16x32_bf16 v[110:113], v[202:205], v[170:173], v[110:113]
	v_mfma_f32_16x16x32_bf16 v[106:109], v[202:205], v[178:181], v[106:109]
	s_waitcnt lgkmcnt(0)
	v_mfma_f32_16x16x32_bf16 v[102:105], v[210:213], v[170:173], v[102:105]
	v_mfma_f32_16x16x32_bf16 v[98:101], v[210:213], v[178:181], v[98:101]
	s_setprio 0
	s_barrier
	v_readfirstlane_b32 s50, v154
	s_add_i32 s49, s23, 0xfff80000
	s_mov_b32 m0, s50
	v_readfirstlane_b32 s50, v155
	ds_read_b128 v[214:217], v137
	ds_read_b128 v[218:221], v137 offset:1024
	ds_read_b128 v[222:225], v137 offset:2048
	ds_read_b128 v[226:229], v137 offset:3072
	buffer_load_dwordx4 v136, s[4:7], s49 offen lds
	s_mov_b32 m0, s50
	s_nop 0
	buffer_load_dwordx4 v144, s[4:7], s49 offen lds
	s_barrier
	s_waitcnt lgkmcnt(0)
	s_setprio 1
	s_waitcnt lgkmcnt(3)
	v_mfma_f32_16x16x32_bf16 v[94:97], v[182:185], v[214:217], v[94:97]
	s_waitcnt lgkmcnt(1)
	v_mfma_f32_16x16x32_bf16 v[90:93], v[182:185], v[222:225], v[90:93]
	v_mfma_f32_16x16x32_bf16 v[86:89], v[190:193], v[214:217], v[86:89]
	v_mfma_f32_16x16x32_bf16 v[82:85], v[190:193], v[222:225], v[82:85]
	v_mfma_f32_16x16x32_bf16 v[78:81], v[198:201], v[214:217], v[78:81]
	v_mfma_f32_16x16x32_bf16 v[74:77], v[198:201], v[222:225], v[74:77]
	v_mfma_f32_16x16x32_bf16 v[70:73], v[206:209], v[214:217], v[70:73]
	v_mfma_f32_16x16x32_bf16 v[66:69], v[206:209], v[222:225], v[66:69]
	v_mfma_f32_16x16x32_bf16 v[94:97], v[186:189], v[218:221], v[94:97]
	s_waitcnt lgkmcnt(0)
	v_mfma_f32_16x16x32_bf16 v[90:93], v[186:189], v[226:229], v[90:93]
	v_mfma_f32_16x16x32_bf16 v[86:89], v[194:197], v[218:221], v[86:89]
	v_mfma_f32_16x16x32_bf16 v[82:85], v[194:197], v[226:229], v[82:85]
	v_mfma_f32_16x16x32_bf16 v[78:81], v[202:205], v[218:221], v[78:81]
	v_mfma_f32_16x16x32_bf16 v[74:77], v[202:205], v[226:229], v[74:77]
	v_mfma_f32_16x16x32_bf16 v[70:73], v[210:213], v[218:221], v[70:73]
	v_mfma_f32_16x16x32_bf16 v[66:69], v[210:213], v[226:229], v[66:69]
	s_setprio 0
	v_readfirstlane_b32 s50, v156
	s_mov_b32 m0, s50
	v_readfirstlane_b32 s50, v158
	s_barrier
	ds_read_b128 v[182:185], v135 offset:49152
	ds_read_b128 v[186:189], v135 offset:50176
	ds_read_b128 v[190:193], v134 offset:49152
	ds_read_b128 v[194:197], v134 offset:50176
	ds_read_b128 v[198:201], v133 offset:49152
	ds_read_b128 v[202:205], v133 offset:50176
	ds_read_b128 v[206:209], v132 offset:49152
	ds_read_b128 v[210:213], v132 offset:50176
	buffer_load_dwordx4 v136, s[8:11], s49 offen lds
	s_mov_b32 m0, s50
	s_nop 0
	buffer_load_dwordx4 v144, s[8:11], s49 offen lds
	s_barrier
; #define STAGE(P, BASE, LD, br, kt) do { const int _so = (int)(((br) * (LD) + (kt) * BK) * 2); \
;     _Pragma("unroll") for (int _i = 0; _i < 2; ++_i) { \
;       __builtin_amdgcn_raw_ptr_buffer_load_lds(rs##BASE, (__attribute__((address_space(3))) unsigned*)((char*)(P) + tid_ * 16 + _i * 8192), 16, (int)off##LD[_i], _so, 0, 0); } } while (0)
; #define LDA_(dst, b, h) _Pragma("unroll") for (int m = 0; m < 4; ++m) _Pragma("unroll") for (int k = 0; k < 2; ++k) \
;     dst[m][k] = *reinterpret_cast<const bf16x8*>((char*)SA(b, h) + lds_byte(wr * 64 + m * 16 + fr, k * 32 + fq * 8))
; #define LDB_(dst, b, h) _Pragma("unroll") for (int n = 0; n < 2; ++n) _Pragma("unroll") for (int k = 0; k < 2; ++k) \
;     dst[n][k] = *reinterpret_cast<const bf16x8*>((char*)SB(b, h) + lds_byte(wc * 32 + n * 16 + fr, k * 32 + fq * 8))
; #define MMA(ai, bj, At, Bx) do { __builtin_amdgcn_s_setprio(1); \
;     _Pragma("unroll") for (int m = 0; m < 4; ++m) _Pragma("unroll") for (int n = 0; n < 2; ++n) _Pragma("unroll") for (int k = 0; k < 2; ++k) \
;       acc[ai][bj][m][n] = __builtin_amdgcn_mfma_f32_16x16x32_bf16(At[m][k], Bx[n][k], acc[ai][bj][m][n], 0, 0, 0); \
;     __builtin_amdgcn_s_setprio(0); } while (0)
; #define WAIT_V(n) asm volatile("s_waitcnt vmcnt(" #n ")" ::: "memory")
; #define WAIT_L(n) asm volatile("s_waitcnt lgkmcnt(" #n ")" ::: "memory")
; #define BAR __builtin_amdgcn_s_barrier()
; #define SCHED __builtin_amdgcn_sched_barrier(0)
; template <int K, int LDA, int LDB>
; DEVI void gemm_tile(const bf16* __restrict__ A, const bf16* __restrict__ Bt, bf16* shm, acc_t& acc) {
;     ...
;     BAR; WAIT_L(0); MMA(1, 0, At, B0); BAR; SCHED;
;     STAGE(SB(1, 1), Bt, LDB, HALF, t + 3);
;     WAIT_V(6); BAR; MMA(1, 1, At, B1); BAR;
;   }
;   { LDB_(B0, 0, 0); LDA_(At, 0, 0); STAGE(SA(1, 1), A, LDA, HALF, nt - 1);
;     BAR; WAIT_L(0); MMA(0, 0, At, B0); BAR;
;     LDB_(B1, 0, 1); BAR; WAIT_L(0); MMA(0, 1, At, B1); BAR;
	s_waitcnt lgkmcnt(0)
	s_setprio 1
	s_waitcnt lgkmcnt(7)
	v_mfma_f32_16x16x32_bf16 v[62:65], v[182:185], v[166:169], v[62:65]
	v_mfma_f32_16x16x32_bf16 v[58:61], v[182:185], v[174:177], v[58:61]
	s_waitcnt lgkmcnt(5)
	v_mfma_f32_16x16x32_bf16 v[54:57], v[190:193], v[166:169], v[54:57]
	v_mfma_f32_16x16x32_bf16 v[50:53], v[190:193], v[174:177], v[50:53]
	s_waitcnt lgkmcnt(3)
	v_mfma_f32_16x16x32_bf16 v[46:49], v[198:201], v[166:169], v[46:49]
	v_mfma_f32_16x16x32_bf16 v[42:45], v[198:201], v[174:177], v[42:45]
	s_waitcnt lgkmcnt(1)
	v_mfma_f32_16x16x32_bf16 v[38:41], v[206:209], v[166:169], v[38:41]
	v_mfma_f32_16x16x32_bf16 v[34:37], v[206:209], v[174:177], v[34:37]
	v_mfma_f32_16x16x32_bf16 v[62:65], v[186:189], v[170:173], v[62:65]
	v_mfma_f32_16x16x32_bf16 v[58:61], v[186:189], v[178:181], v[58:61]
	v_mfma_f32_16x16x32_bf16 v[54:57], v[194:197], v[170:173], v[54:57]
	v_mfma_f32_16x16x32_bf16 v[50:53], v[194:197], v[178:181], v[50:53]
	v_mfma_f32_16x16x32_bf16 v[46:49], v[202:205], v[170:173], v[46:49]
	v_mfma_f32_16x16x32_bf16 v[42:45], v[202:205], v[178:181], v[42:45]
	s_waitcnt lgkmcnt(0)
	v_mfma_f32_16x16x32_bf16 v[38:41], v[210:213], v[170:173], v[38:41]
	v_mfma_f32_16x16x32_bf16 v[34:37], v[210:213], v[178:181], v[34:37]
	s_setprio 0
	s_barrier
	v_readfirstlane_b32 s49, v160
	s_mov_b32 m0, s49
	v_readfirstlane_b32 s49, v161
	buffer_load_dwordx4 v136, s[4:7], s23 offen lds
	s_mov_b32 m0, s49
	s_nop 0
	buffer_load_dwordx4 v144, s[4:7], s23 offen lds
	s_waitcnt vmcnt(6)
	s_barrier
	s_setprio 1
	v_mfma_f32_16x16x32_bf16 v[30:33], v[182:185], v[214:217], v[30:33]
	v_mfma_f32_16x16x32_bf16 v[26:29], v[182:185], v[222:225], v[26:29]
	v_mfma_f32_16x16x32_bf16 v[22:25], v[190:193], v[214:217], v[22:25]
	v_mfma_f32_16x16x32_bf16 v[18:21], v[190:193], v[222:225], v[18:21]
	v_mfma_f32_16x16x32_bf16 v[14:17], v[198:201], v[214:217], v[14:17]
	v_mfma_f32_16x16x32_bf16 v[10:13], v[198:201], v[222:225], v[10:13]
	v_mfma_f32_16x16x32_bf16 v[6:9], v[206:209], v[214:217], v[6:9]
	v_mfma_f32_16x16x32_bf16 v[2:5], v[206:209], v[222:225], v[2:5]
	v_mfma_f32_16x16x32_bf16 v[30:33], v[186:189], v[218:221], v[30:33]
	v_mfma_f32_16x16x32_bf16 v[26:29], v[186:189], v[226:229], v[26:29]
	v_mfma_f32_16x16x32_bf16 v[22:25], v[194:197], v[218:221], v[22:25]
	v_mfma_f32_16x16x32_bf16 v[18:21], v[194:197], v[226:229], v[18:21]
	v_mfma_f32_16x16x32_bf16 v[14:17], v[202:205], v[218:221], v[14:17]
	v_mfma_f32_16x16x32_bf16 v[10:13], v[202:205], v[226:229], v[10:13]
	v_mfma_f32_16x16x32_bf16 v[6:9], v[210:213], v[218:221], v[6:9]
	v_mfma_f32_16x16x32_bf16 v[2:5], v[210:213], v[226:229], v[2:5]
	s_setprio 0
	s_add_i32 s21, s21, 2
	s_addk_i32 s23, 0x100
	s_cmp_lt_u32 s21, 28
	s_cbranch_scc1 .Lrot_29300
	s_barrier
	v_readfirstlane_b32 s4, v159
	s_mov_b32 s10, s6
	s_mov_b32 s11, s7
	s_mov_b32 m0, s4
	v_readfirstlane_b32 s4, v164
	ds_read_b128 v[146:149], v165
	ds_read_b128 v[150:153], v165 offset:1024
	ds_read_b128 v[166:169], v165 offset:2048
	ds_read_b128 v[170:173], v165 offset:3072
	ds_read_b128 v[174:177], v135
	ds_read_b128 v[178:181], v135 offset:1024
	ds_read_b128 v[182:185], v134
	ds_read_b128 v[186:189], v134 offset:1024
	ds_read_b128 v[190:193], v133
	ds_read_b128 v[194:197], v133 offset:1024
	ds_read_b128 v[198:201], v132
	ds_read_b128 v[202:205], v132 offset:1024
	buffer_load_dwordx4 v136, s[8:11], s44 offen lds
	s_mov_b32 m0, s4
	s_nop 0
	buffer_load_dwordx4 v144, s[8:11], s44 offen lds
	s_barrier
	s_waitcnt lgkmcnt(0)
	s_setprio 1
	s_waitcnt lgkmcnt(7)
	v_mfma_f32_16x16x32_bf16 v[126:129], v[174:177], v[146:149], v[126:129]
	v_mfma_f32_16x16x32_bf16 v[122:125], v[174:177], v[166:169], v[122:125]
	s_waitcnt lgkmcnt(5)
	v_mfma_f32_16x16x32_bf16 v[118:121], v[182:185], v[146:149], v[118:121]
	v_mfma_f32_16x16x32_bf16 v[114:117], v[182:185], v[166:169], v[114:117]
	s_waitcnt lgkmcnt(3)
	v_mfma_f32_16x16x32_bf16 v[110:113], v[190:193], v[146:149], v[110:113]
	v_mfma_f32_16x16x32_bf16 v[106:109], v[190:193], v[166:169], v[106:109]
	s_waitcnt lgkmcnt(1)
	v_mfma_f32_16x16x32_bf16 v[102:105], v[198:201], v[146:149], v[102:105]
	v_mfma_f32_16x16x32_bf16 v[98:101], v[198:201], v[166:169], v[98:101]
	v_mfma_f32_16x16x32_bf16 v[126:129], v[178:181], v[150:153], v[126:129]
	v_mfma_f32_16x16x32_bf16 v[122:125], v[178:181], v[170:173], v[122:125]
	v_mfma_f32_16x16x32_bf16 v[118:121], v[186:189], v[150:153], v[118:121]
	v_mfma_f32_16x16x32_bf16 v[114:117], v[186:189], v[170:173], v[114:117]
	v_mfma_f32_16x16x32_bf16 v[110:113], v[194:197], v[150:153], v[110:113]
	v_mfma_f32_16x16x32_bf16 v[106:109], v[194:197], v[170:173], v[106:109]
	s_waitcnt lgkmcnt(0)
	v_mfma_f32_16x16x32_bf16 v[102:105], v[202:205], v[150:153], v[102:105]
	v_mfma_f32_16x16x32_bf16 v[98:101], v[202:205], v[170:173], v[98:101]
	s_setprio 0
	s_barrier
	ds_read_b128 v[158:161], v157
	ds_read_b128 v[206:209], v157 offset:1024
	ds_read_b128 v[210:213], v157 offset:2048
	ds_read_b128 v[154:157], v157 offset:3072
	s_barrier
	s_waitcnt lgkmcnt(0)
	s_setprio 1
	s_waitcnt lgkmcnt(3)
	v_mfma_f32_16x16x32_bf16 v[94:97], v[174:177], v[158:161], v[94:97]
	s_waitcnt lgkmcnt(1)
	v_mfma_f32_16x16x32_bf16 v[90:93], v[174:177], v[210:213], v[90:93]
	v_mfma_f32_16x16x32_bf16 v[86:89], v[182:185], v[158:161], v[86:89]
	v_mfma_f32_16x16x32_bf16 v[82:85], v[182:185], v[210:213], v[82:85]
	v_mfma_f32_16x16x32_bf16 v[78:81], v[190:193], v[158:161], v[78:81]
	v_mfma_f32_16x16x32_bf16 v[74:77], v[190:193], v[210:213], v[74:77]
	v_mfma_f32_16x16x32_bf16 v[70:73], v[198:201], v[158:161], v[70:73]
	v_mfma_f32_16x16x32_bf16 v[66:69], v[198:201], v[210:213], v[66:69]
	v_mfma_f32_16x16x32_bf16 v[94:97], v[178:181], v[206:209], v[94:97]
	s_waitcnt lgkmcnt(0)
	v_mfma_f32_16x16x32_bf16 v[90:93], v[178:181], v[154:157], v[90:93]
	v_mfma_f32_16x16x32_bf16 v[86:89], v[186:189], v[206:209], v[86:89]
	v_mfma_f32_16x16x32_bf16 v[82:85], v[186:189], v[154:157], v[82:85]
	v_mfma_f32_16x16x32_bf16 v[78:81], v[194:197], v[206:209], v[78:81]
	v_mfma_f32_16x16x32_bf16 v[74:77], v[194:197], v[154:157], v[74:77]
	v_mfma_f32_16x16x32_bf16 v[70:73], v[202:205], v[206:209], v[70:73]
	v_mfma_f32_16x16x32_bf16 v[66:69], v[202:205], v[154:157], v[66:69]
	s_setprio 0
	s_barrier
; #define LDA_(dst, b, h) _Pragma("unroll") for (int m = 0; m < 4; ++m) _Pragma("unroll") for (int k = 0; k < 2; ++k) \
;     dst[m][k] = *reinterpret_cast<const bf16x8*>((char*)SA(b, h) + lds_byte(wr * 64 + m * 16 + fr, k * 32 + fq * 8))
; #define LDB_(dst, b, h) _Pragma("unroll") for (int n = 0; n < 2; ++n) _Pragma("unroll") for (int k = 0; k < 2; ++k) \
;     dst[n][k] = *reinterpret_cast<const bf16x8*>((char*)SB(b, h) + lds_byte(wc * 32 + n * 16 + fr, k * 32 + fq * 8))
; #define MMA(ai, bj, At, Bx) do { __builtin_amdgcn_s_setprio(1); \
;     _Pragma("unroll") for (int m = 0; m < 4; ++m) _Pragma("unroll") for (int n = 0; n < 2; ++n) _Pragma("unroll") for (int k = 0; k < 2; ++k) \
;       acc[ai][bj][m][n] = __builtin_amdgcn_mfma_f32_16x16x32_bf16(At[m][k], Bx[n][k], acc[ai][bj][m][n], 0, 0, 0); \
;     __builtin_amdgcn_s_setprio(0); } while (0)
; #define WAIT_V(n) asm volatile("s_waitcnt vmcnt(" #n ")" ::: "memory")
; #define WAIT_L(n) asm volatile("s_waitcnt lgkmcnt(" #n ")" ::: "memory")
; #define BAR __builtin_amdgcn_s_barrier()
; template <int K, int LDA, int LDB>
; DEVI void gemm_tile(const bf16* __restrict__ A, const bf16* __restrict__ Bt, bf16* shm, acc_t& acc) {
;     ...
;     LDA_(At, 0, 1); WAIT_V(4); BAR; WAIT_L(0); MMA(1, 0, At, B0); MMA(1, 1, At, B1); BAR; }
;   { LDB_(B0, 1, 0); LDA_(At, 1, 0); WAIT_V(2); BAR; WAIT_L(0); MMA(0, 0, At, B0); BAR;
	ds_read_b128 v[174:177], v135 offset:16384
	ds_read_b128 v[178:181], v135 offset:17408
	ds_read_b128 v[182:185], v134 offset:16384
	ds_read_b128 v[186:189], v134 offset:17408
	ds_read_b128 v[190:193], v133 offset:16384
	ds_read_b128 v[194:197], v133 offset:17408
	ds_read_b128 v[198:201], v132 offset:16384
	ds_read_b128 v[202:205], v132 offset:17408
	s_waitcnt vmcnt(4)
	s_barrier
	s_waitcnt lgkmcnt(0)
	s_setprio 1
	s_waitcnt lgkmcnt(7)
	v_mfma_f32_16x16x32_bf16 v[62:65], v[174:177], v[146:149], v[62:65]
	v_mfma_f32_16x16x32_bf16 v[58:61], v[174:177], v[166:169], v[58:61]
	s_waitcnt lgkmcnt(5)
	v_mfma_f32_16x16x32_bf16 v[54:57], v[182:185], v[146:149], v[54:57]
	v_mfma_f32_16x16x32_bf16 v[50:53], v[182:185], v[166:169], v[50:53]
	s_waitcnt lgkmcnt(3)
	v_mfma_f32_16x16x32_bf16 v[46:49], v[190:193], v[146:149], v[46:49]
	v_mfma_f32_16x16x32_bf16 v[42:45], v[190:193], v[166:169], v[42:45]
	s_waitcnt lgkmcnt(1)
	v_mfma_f32_16x16x32_bf16 v[38:41], v[198:201], v[146:149], v[38:41]
	v_mfma_f32_16x16x32_bf16 v[34:37], v[198:201], v[166:169], v[34:37]
	v_mfma_f32_16x16x32_bf16 v[62:65], v[178:181], v[150:153], v[62:65]
	v_mfma_f32_16x16x32_bf16 v[58:61], v[178:181], v[170:173], v[58:61]
	v_mfma_f32_16x16x32_bf16 v[54:57], v[186:189], v[150:153], v[54:57]
	v_mfma_f32_16x16x32_bf16 v[50:53], v[186:189], v[170:173], v[50:53]
	v_mfma_f32_16x16x32_bf16 v[46:49], v[194:197], v[150:153], v[46:49]
	v_mfma_f32_16x16x32_bf16 v[42:45], v[194:197], v[170:173], v[42:45]
	s_waitcnt lgkmcnt(0)
	v_mfma_f32_16x16x32_bf16 v[38:41], v[202:205], v[150:153], v[38:41]
	v_mfma_f32_16x16x32_bf16 v[34:37], v[202:205], v[170:173], v[34:37]
	s_setprio 0
	s_setprio 1
	v_mfma_f32_16x16x32_bf16 v[30:33], v[174:177], v[158:161], v[30:33]
	v_mfma_f32_16x16x32_bf16 v[26:29], v[174:177], v[210:213], v[26:29]
	v_mfma_f32_16x16x32_bf16 v[22:25], v[182:185], v[158:161], v[22:25]
	v_mfma_f32_16x16x32_bf16 v[18:21], v[182:185], v[210:213], v[18:21]
	v_mfma_f32_16x16x32_bf16 v[30:33], v[178:181], v[206:209], v[30:33]
	v_mfma_f32_16x16x32_bf16 v[26:29], v[178:181], v[154:157], v[26:29]
	v_mfma_f32_16x16x32_bf16 v[22:25], v[186:189], v[206:209], v[22:25]
	v_mfma_f32_16x16x32_bf16 v[18:21], v[186:189], v[154:157], v[18:21]
	v_mfma_f32_16x16x32_bf16 v[14:17], v[190:193], v[158:161], v[14:17]
	v_mfma_f32_16x16x32_bf16 v[10:13], v[190:193], v[210:213], v[10:13]
	v_mfma_f32_16x16x32_bf16 v[6:9], v[198:201], v[158:161], v[6:9]
	v_mfma_f32_16x16x32_bf16 v[2:5], v[198:201], v[210:213], v[2:5]
	v_mfma_f32_16x16x32_bf16 v[146:149], v[194:197], v[206:209], v[14:17]
	v_mfma_f32_16x16x32_bf16 v[150:153], v[194:197], v[154:157], v[10:13]
	v_mfma_f32_16x16x32_bf16 v[158:161], v[202:205], v[206:209], v[6:9]
	v_mfma_f32_16x16x32_bf16 v[154:157], v[202:205], v[154:157], v[2:5]
	s_setprio 0
	s_barrier
	ds_read_b128 v[164:167], v145
	ds_read_b128 v[168:171], v145 offset:1024
	ds_read_b128 v[172:175], v145 offset:2048
	ds_read_b128 v[176:179], v145 offset:3072
	ds_read_b128 v[2:5], v135 offset:32768
	ds_read_b128 v[180:183], v135 offset:33792
	ds_read_b128 v[184:187], v134 offset:32768
	ds_read_b128 v[188:191], v134 offset:33792
	ds_read_b128 v[192:195], v133 offset:32768
	ds_read_b128 v[196:199], v133 offset:33792
	ds_read_b128 v[200:203], v132 offset:32768
	ds_read_b128 v[204:207], v132 offset:33792
	s_waitcnt vmcnt(2)
	s_barrier
	s_waitcnt lgkmcnt(0)
	s_setprio 1
	s_waitcnt lgkmcnt(5)
	v_mfma_f32_16x16x32_bf16 v[10:13], v[184:187], v[164:167], v[118:121]
	v_mfma_f32_16x16x32_bf16 v[6:9], v[2:5], v[164:167], v[126:129]
	s_waitcnt lgkmcnt(4)
	v_mfma_f32_16x16x32_bf16 v[126:129], v[188:191], v[168:171], v[10:13]
	v_mfma_f32_16x16x32_bf16 v[10:13], v[184:187], v[172:175], v[114:117]
	v_mfma_f32_16x16x32_bf16 v[14:17], v[180:183], v[168:171], v[6:9]
	v_mfma_f32_16x16x32_bf16 v[6:9], v[2:5], v[172:175], v[122:125]
	v_mfma_f32_16x16x32_bf16 v[122:125], v[188:191], v[176:179], v[10:13]
	s_waitcnt lgkmcnt(3)
	v_mfma_f32_16x16x32_bf16 v[10:13], v[192:195], v[164:167], v[110:113]
	s_waitcnt lgkmcnt(2)
	v_mfma_f32_16x16x32_bf16 v[118:121], v[196:199], v[168:171], v[10:13]
	v_mfma_f32_16x16x32_bf16 v[10:13], v[192:195], v[172:175], v[106:109]
	v_mfma_f32_16x16x32_bf16 v[114:117], v[196:199], v[176:179], v[10:13]
	s_waitcnt lgkmcnt(1)
	v_mfma_f32_16x16x32_bf16 v[10:13], v[200:203], v[164:167], v[102:105]
	s_waitcnt lgkmcnt(0)
	v_mfma_f32_16x16x32_bf16 v[110:113], v[204:207], v[168:171], v[10:13]
	v_mfma_f32_16x16x32_bf16 v[10:13], v[200:203], v[172:175], v[98:101]
	v_mfma_f32_16x16x32_bf16 v[6:9], v[180:183], v[176:179], v[6:9]
	v_mfma_f32_16x16x32_bf16 v[106:109], v[204:207], v[176:179], v[10:13]
	s_setprio 0
	s_barrier
; #define LDA_(dst, b, h) _Pragma("unroll") for (int m = 0; m < 4; ++m) _Pragma("unroll") for (int k = 0; k < 2; ++k) \
;     dst[m][k] = *reinterpret_cast<const bf16x8*>((char*)SA(b, h) + lds_byte(wr * 64 + m * 16 + fr, k * 32 + fq * 8))
; #define LDB_(dst, b, h) _Pragma("unroll") for (int n = 0; n < 2; ++n) _Pragma("unroll") for (int k = 0; k < 2; ++k) \
;     dst[n][k] = *reinterpret_cast<const bf16x8*>((char*)SB(b, h) + lds_byte(wc * 32 + n * 16 + fr, k * 32 + fq * 8))
; #define MMA(ai, bj, At, Bx) do { __builtin_amdgcn_s_setprio(1); \
;     _Pragma("unroll") for (int m = 0; m < 4; ++m) _Pragma("unroll") for (int n = 0; n < 2; ++n) _Pragma("unroll") for (int k = 0; k < 2; ++k) \
;       acc[ai][bj][m][n] = __builtin_amdgcn_mfma_f32_16x16x32_bf16(At[m][k], Bx[n][k], acc[ai][bj][m][n], 0, 0, 0); \
;     __builtin_amdgcn_s_setprio(0); } while (0)
; #define WAIT_V(n) asm volatile("s_waitcnt vmcnt(" #n ")" ::: "memory")
; #define WAIT_L(n) asm volatile("s_waitcnt lgkmcnt(" #n ")" ::: "memory")
; #define BAR __builtin_amdgcn_s_barrier()
; template <int K, int LDA, int LDB>
; DEVI void gemm_tile(const bf16* __restrict__ A, const bf16* __restrict__ Bt, bf16* shm, acc_t& acc) {
;     ...
;     LDB_(B1, 1, 1); WAIT_V(0); BAR; WAIT_L(0); MMA(0, 1, At, B1); BAR;
;     LDA_(At, 1, 1); BAR; WAIT_L(0); MMA(1, 0, At, B0); MMA(1, 1, At, B1); BAR; }
;   if (wr == 0) BAR;
	ds_read_b128 v[208:211], v137
	ds_read_b128 v[212:215], v137 offset:1024
	ds_read_b128 v[216:219], v137 offset:2048
	ds_read_b128 v[220:223], v137 offset:3072
	s_waitcnt vmcnt(0)
	s_barrier
	s_waitcnt lgkmcnt(0)
	s_setprio 1
	s_waitcnt lgkmcnt(3)
	v_mfma_f32_16x16x32_bf16 v[10:13], v[2:5], v[208:211], v[94:97]
	s_waitcnt lgkmcnt(1)
	v_mfma_f32_16x16x32_bf16 v[2:5], v[2:5], v[216:219], v[90:93]
	v_mfma_f32_16x16x32_bf16 v[86:89], v[184:187], v[208:211], v[86:89]
	v_mfma_f32_16x16x32_bf16 v[82:85], v[184:187], v[216:219], v[82:85]
	v_mfma_f32_16x16x32_bf16 v[78:81], v[192:195], v[208:211], v[78:81]
	v_mfma_f32_16x16x32_bf16 v[74:77], v[192:195], v[216:219], v[74:77]
	v_mfma_f32_16x16x32_bf16 v[70:73], v[200:203], v[208:211], v[70:73]
	v_mfma_f32_16x16x32_bf16 v[66:69], v[200:203], v[216:219], v[66:69]
	v_mfma_f32_16x16x32_bf16 v[10:13], v[180:183], v[212:215], v[10:13]
	s_waitcnt lgkmcnt(0)
	v_mfma_f32_16x16x32_bf16 v[2:5], v[180:183], v[220:223], v[2:5]
	v_mfma_f32_16x16x32_bf16 v[102:105], v[188:191], v[212:215], v[86:89]
	v_mfma_f32_16x16x32_bf16 v[98:101], v[188:191], v[220:223], v[82:85]
	v_mfma_f32_16x16x32_bf16 v[94:97], v[196:199], v[212:215], v[78:81]
	v_mfma_f32_16x16x32_bf16 v[90:93], v[196:199], v[220:223], v[74:77]
	v_mfma_f32_16x16x32_bf16 v[86:89], v[204:207], v[212:215], v[70:73]
	v_mfma_f32_16x16x32_bf16 v[78:81], v[204:207], v[220:223], v[66:69]
	s_setprio 0
	s_barrier
	ds_read_b128 v[180:183], v135 offset:49152
	ds_read_b128 v[184:187], v135 offset:50176
	ds_read_b128 v[188:191], v134 offset:49152
	ds_read_b128 v[134:137], v134 offset:50176
	ds_read_b128 v[192:195], v133 offset:49152
	ds_read_b128 v[196:199], v133 offset:50176
	ds_read_b128 v[200:203], v132 offset:49152
	ds_read_b128 v[204:207], v132 offset:50176
	s_barrier
	s_waitcnt lgkmcnt(0)
	s_setprio 1
	s_waitcnt lgkmcnt(7)
	v_mfma_f32_16x16x32_bf16 v[62:65], v[180:183], v[164:167], v[62:65]
	v_mfma_f32_16x16x32_bf16 v[58:61], v[180:183], v[172:175], v[58:61]
	s_waitcnt lgkmcnt(5)
	v_mfma_f32_16x16x32_bf16 v[54:57], v[188:191], v[164:167], v[54:57]
	v_mfma_f32_16x16x32_bf16 v[50:53], v[188:191], v[172:175], v[50:53]
	s_waitcnt lgkmcnt(3)
	v_mfma_f32_16x16x32_bf16 v[46:49], v[192:195], v[164:167], v[46:49]
	v_mfma_f32_16x16x32_bf16 v[42:45], v[192:195], v[172:175], v[42:45]
	s_waitcnt lgkmcnt(1)
	v_mfma_f32_16x16x32_bf16 v[38:41], v[200:203], v[164:167], v[38:41]
	v_mfma_f32_16x16x32_bf16 v[34:37], v[200:203], v[172:175], v[34:37]
	v_mfma_f32_16x16x32_bf16 v[82:85], v[184:187], v[168:171], v[62:65]
	v_mfma_f32_16x16x32_bf16 v[74:77], v[184:187], v[176:179], v[58:61]
	v_mfma_f32_16x16x32_bf16 v[70:73], v[134:137], v[168:171], v[54:57]
	v_mfma_f32_16x16x32_bf16 v[66:69], v[134:137], v[176:179], v[50:53]
	v_mfma_f32_16x16x32_bf16 v[62:65], v[196:199], v[168:171], v[46:49]
	v_mfma_f32_16x16x32_bf16 v[58:61], v[196:199], v[176:179], v[42:45]
	s_waitcnt lgkmcnt(0)
	v_mfma_f32_16x16x32_bf16 v[54:57], v[204:207], v[168:171], v[38:41]
	v_mfma_f32_16x16x32_bf16 v[50:53], v[204:207], v[176:179], v[34:37]
	s_setprio 0
	s_setprio 1
	v_mfma_f32_16x16x32_bf16 v[18:21], v[188:191], v[216:219], v[18:21]
	v_mfma_f32_16x16x32_bf16 v[30:33], v[180:183], v[208:211], v[30:33]
	v_mfma_f32_16x16x32_bf16 v[34:37], v[134:137], v[220:223], v[18:21]
	v_mfma_f32_16x16x32_bf16 v[18:21], v[192:195], v[208:211], v[146:149]
	v_mfma_f32_16x16x32_bf16 v[46:49], v[184:187], v[212:215], v[30:33]
	v_mfma_f32_16x16x32_bf16 v[26:29], v[180:183], v[216:219], v[26:29]
	v_mfma_f32_16x16x32_bf16 v[30:33], v[196:199], v[212:215], v[18:21]
	v_mfma_f32_16x16x32_bf16 v[18:21], v[192:195], v[216:219], v[150:153]
	v_mfma_f32_16x16x32_bf16 v[42:45], v[184:187], v[220:223], v[26:29]
	v_mfma_f32_16x16x32_bf16 v[22:25], v[188:191], v[208:211], v[22:25]
	v_mfma_f32_16x16x32_bf16 v[26:29], v[196:199], v[220:223], v[18:21]
	v_mfma_f32_16x16x32_bf16 v[18:21], v[200:203], v[208:211], v[158:161]
	v_mfma_f32_16x16x32_bf16 v[38:41], v[134:137], v[212:215], v[22:25]
	v_mfma_f32_16x16x32_bf16 v[22:25], v[204:207], v[212:215], v[18:21]
	v_mfma_f32_16x16x32_bf16 v[18:21], v[200:203], v[216:219], v[154:157]
	v_mfma_f32_16x16x32_bf16 v[18:21], v[204:207], v[220:223], v[18:21]
	s_setprio 0
	v_cmp_gt_u32_e32 vcc, s34, v130
	s_barrier
	s_and_saveexec_b64 s[4:5], vcc
	s_cbranch_execz .LBB0_1452
	s_barrier

; #define STAGE(P, BASE, LD, br, kt) do { const int _so = (int)(((br) * (LD) + (kt) * BK) * 2); \
;     _Pragma("unroll") for (int _i = 0; _i < 2; ++_i) { \
;       __builtin_amdgcn_raw_ptr_buffer_load_lds(rs##BASE, (__attribute__((address_space(3))) unsigned*)((char*)(P) + tid_ * 16 + _i * 8192), 16, (int)off##LD[_i], _so, 0, 0); } } while (0)
; #define LDA_(dst, b, h) _Pragma("unroll") for (int m = 0; m < 4; ++m) _Pragma("unroll") for (int k = 0; k < 2; ++k) \
;     dst[m][k] = *reinterpret_cast<const bf16x8*>((char*)SA(b, h) + lds_byte(wr * 64 + m * 16 + fr, k * 32 + fq * 8))
; #define LDB_(dst, b, h) _Pragma("unroll") for (int n = 0; n < 2; ++n) _Pragma("unroll") for (int k = 0; k < 2; ++k) \
;     dst[n][k] = *reinterpret_cast<const bf16x8*>((char*)SB(b, h) + lds_byte(wc * 32 + n * 16 + fr, k * 32 + fq * 8))
; #define MMA(ai, bj, At, Bx) do { __builtin_amdgcn_s_setprio(1); \
;     _Pragma("unroll") for (int m = 0; m < 4; ++m) _Pragma("unroll") for (int n = 0; n < 2; ++n) _Pragma("unroll") for (int k = 0; k < 2; ++k) \
;       acc[ai][bj][m][n] = __builtin_amdgcn_mfma_f32_16x16x32_bf16(At[m][k], Bx[n][k], acc[ai][bj][m][n], 0, 0, 0); \
;     __builtin_amdgcn_s_setprio(0); } while (0)
; #define WAIT_L(n) asm volatile("s_waitcnt lgkmcnt(" #n ")" ::: "memory")
; #define BAR __builtin_amdgcn_s_barrier()
; #define SCHED __builtin_amdgcn_sched_barrier(0)
; template <int K, int LDA, int LDB>
; DEVI void gemm_tile(const bf16* __restrict__ A, const bf16* __restrict__ Bt, bf16* shm, acc_t& acc) {
;     ...
;     LDB_(B0, 0, 0); SCHED; LDA_(At, 0, 0); STAGE(SA(1, 1), A, LDA, HALF, t + 1);
;     WAIT_L(8); BAR; WAIT_L(0); MMA(0, 0, At, B0); BAR; SCHED;
;     LDB_(B1, 0, 1); STAGE(SB(0, 0), Bt, LDB, 0, t + 2);
;     BAR; WAIT_L(0); MMA(0, 1, At, B1); BAR;
;     LDA_(At, 0, 1); STAGE(SA(0, 0), A, LDA, 0, t + 2);
;     BAR; WAIT_L(0); MMA(1, 0, At, B0); BAR; SCHED;
.LBB0_1610:
	ds_read_b128 v[164:167], v161
	ds_read_b128 v[168:171], v161 offset:1024
	ds_read_b128 v[172:175], v161 offset:2048
	ds_read_b128 v[176:179], v161 offset:3072
	v_readfirstlane_b32 s61, v157
	s_add_i32 s60, s13, 0xffffff00
	s_mov_b32 m0, s61
	v_readfirstlane_b32 s61, v160
	ds_read_b128 v[180:183], v139
	ds_read_b128 v[184:187], v139 offset:1024
	ds_read_b128 v[188:191], v138
	ds_read_b128 v[192:195], v138 offset:1024
	ds_read_b128 v[196:199], v135
	ds_read_b128 v[200:203], v135 offset:1024
	ds_read_b128 v[204:207], v134
	ds_read_b128 v[208:211], v134 offset:1024
	buffer_load_dwordx4 v140, s[8:11], s60 offen lds
	s_mov_b32 m0, s61
	s_nop 0
	buffer_load_dwordx4 v142, s[8:11], s60 offen lds
	s_waitcnt lgkmcnt(8)
	s_barrier
	s_waitcnt lgkmcnt(0)
	s_setprio 1
	s_waitcnt lgkmcnt(7)
	v_mfma_f32_16x16x32_bf16 v[126:129], v[180:183], v[164:167], v[126:129]
	v_mfma_f32_16x16x32_bf16 v[122:125], v[180:183], v[172:175], v[122:125]
	s_waitcnt lgkmcnt(5)
	v_mfma_f32_16x16x32_bf16 v[118:121], v[188:191], v[164:167], v[118:121]
	v_mfma_f32_16x16x32_bf16 v[114:117], v[188:191], v[172:175], v[114:117]
	s_waitcnt lgkmcnt(3)
	v_mfma_f32_16x16x32_bf16 v[110:113], v[196:199], v[164:167], v[110:113]
	v_mfma_f32_16x16x32_bf16 v[106:109], v[196:199], v[172:175], v[106:109]
	s_waitcnt lgkmcnt(1)
	v_mfma_f32_16x16x32_bf16 v[102:105], v[204:207], v[164:167], v[102:105]
	v_mfma_f32_16x16x32_bf16 v[98:101], v[204:207], v[172:175], v[98:101]
	v_mfma_f32_16x16x32_bf16 v[126:129], v[184:187], v[168:171], v[126:129]
	v_mfma_f32_16x16x32_bf16 v[122:125], v[184:187], v[176:179], v[122:125]
	v_mfma_f32_16x16x32_bf16 v[118:121], v[192:195], v[168:171], v[118:121]
	v_mfma_f32_16x16x32_bf16 v[114:117], v[192:195], v[176:179], v[114:117]
	v_mfma_f32_16x16x32_bf16 v[110:113], v[200:203], v[168:171], v[110:113]
	v_mfma_f32_16x16x32_bf16 v[106:109], v[200:203], v[176:179], v[106:109]
	s_waitcnt lgkmcnt(0)
	v_mfma_f32_16x16x32_bf16 v[102:105], v[208:211], v[168:171], v[102:105]
	v_mfma_f32_16x16x32_bf16 v[98:101], v[208:211], v[176:179], v[98:101]
	s_setprio 0
	s_barrier
	v_readfirstlane_b32 s61, v144
	s_add_i32 s60, s13, 0xfff7ff80
	s_mov_b32 m0, s61
	v_readfirstlane_b32 s61, v145
	ds_read_b128 v[212:215], v155
	ds_read_b128 v[216:219], v155 offset:1024
	ds_read_b128 v[220:223], v155 offset:2048
	ds_read_b128 v[224:227], v155 offset:3072
	buffer_load_dwordx4 v140, s[0:3], s60 offen lds
	s_mov_b32 m0, s61
	s_nop 0
	buffer_load_dwordx4 v142, s[0:3], s60 offen lds
	s_barrier
	s_waitcnt lgkmcnt(0)
	s_setprio 1
	s_waitcnt lgkmcnt(3)
	v_mfma_f32_16x16x32_bf16 v[94:97], v[180:183], v[212:215], v[94:97]
	s_waitcnt lgkmcnt(1)
	v_mfma_f32_16x16x32_bf16 v[90:93], v[180:183], v[220:223], v[90:93]
	v_mfma_f32_16x16x32_bf16 v[86:89], v[188:191], v[212:215], v[86:89]
	v_mfma_f32_16x16x32_bf16 v[82:85], v[188:191], v[220:223], v[82:85]
	v_mfma_f32_16x16x32_bf16 v[78:81], v[196:199], v[212:215], v[78:81]
	v_mfma_f32_16x16x32_bf16 v[74:77], v[196:199], v[220:223], v[74:77]
	v_mfma_f32_16x16x32_bf16 v[70:73], v[204:207], v[212:215], v[70:73]
	v_mfma_f32_16x16x32_bf16 v[66:69], v[204:207], v[220:223], v[66:69]
	v_mfma_f32_16x16x32_bf16 v[94:97], v[184:187], v[216:219], v[94:97]
	s_waitcnt lgkmcnt(0)
	v_mfma_f32_16x16x32_bf16 v[90:93], v[184:187], v[224:227], v[90:93]
	v_mfma_f32_16x16x32_bf16 v[86:89], v[192:195], v[216:219], v[86:89]
	v_mfma_f32_16x16x32_bf16 v[82:85], v[192:195], v[224:227], v[82:85]
	v_mfma_f32_16x16x32_bf16 v[78:81], v[200:203], v[216:219], v[78:81]
	v_mfma_f32_16x16x32_bf16 v[74:77], v[200:203], v[224:227], v[74:77]
	v_mfma_f32_16x16x32_bf16 v[70:73], v[208:211], v[216:219], v[70:73]
	v_mfma_f32_16x16x32_bf16 v[66:69], v[208:211], v[224:227], v[66:69]
	s_setprio 0
	v_readfirstlane_b32 s61, v146
	s_mov_b32 m0, s61
	v_readfirstlane_b32 s61, v147
	s_barrier
	ds_read_b128 v[180:183], v139 offset:16384
	ds_read_b128 v[184:187], v139 offset:17408
	ds_read_b128 v[188:191], v138 offset:16384
	ds_read_b128 v[192:195], v138 offset:17408
	ds_read_b128 v[196:199], v135 offset:16384
	ds_read_b128 v[200:203], v135 offset:17408
	ds_read_b128 v[204:207], v134 offset:16384
	ds_read_b128 v[208:211], v134 offset:17408
	buffer_load_dwordx4 v140, s[8:11], s60 offen lds
	s_mov_b32 m0, s61
	s_nop 0
	buffer_load_dwordx4 v142, s[8:11], s60 offen lds
	s_barrier
	s_waitcnt lgkmcnt(0)
	s_setprio 1
	s_waitcnt lgkmcnt(7)
	v_mfma_f32_16x16x32_bf16 v[62:65], v[180:183], v[164:167], v[62:65]
	v_mfma_f32_16x16x32_bf16 v[58:61], v[180:183], v[172:175], v[58:61]
	s_waitcnt lgkmcnt(5)
	v_mfma_f32_16x16x32_bf16 v[54:57], v[188:191], v[164:167], v[54:57]
	v_mfma_f32_16x16x32_bf16 v[50:53], v[188:191], v[172:175], v[50:53]
	s_waitcnt lgkmcnt(3)
	v_mfma_f32_16x16x32_bf16 v[46:49], v[196:199], v[164:167], v[46:49]
	v_mfma_f32_16x16x32_bf16 v[42:45], v[196:199], v[172:175], v[42:45]
	s_waitcnt lgkmcnt(1)
	v_mfma_f32_16x16x32_bf16 v[38:41], v[204:207], v[164:167], v[38:41]
	v_mfma_f32_16x16x32_bf16 v[34:37], v[204:207], v[172:175], v[34:37]
	v_mfma_f32_16x16x32_bf16 v[62:65], v[184:187], v[168:171], v[62:65]
	v_mfma_f32_16x16x32_bf16 v[58:61], v[184:187], v[176:179], v[58:61]
	v_mfma_f32_16x16x32_bf16 v[54:57], v[192:195], v[168:171], v[54:57]
	v_mfma_f32_16x16x32_bf16 v[50:53], v[192:195], v[176:179], v[50:53]
	v_mfma_f32_16x16x32_bf16 v[46:49], v[200:203], v[168:171], v[46:49]
	v_mfma_f32_16x16x32_bf16 v[42:45], v[200:203], v[176:179], v[42:45]
	s_waitcnt lgkmcnt(0)
	v_mfma_f32_16x16x32_bf16 v[38:41], v[208:211], v[168:171], v[38:41]
	v_mfma_f32_16x16x32_bf16 v[34:37], v[208:211], v[176:179], v[34:37]
	s_setprio 0
	s_barrier
; #define STAGE(P, BASE, LD, br, kt) do { const int _so = (int)(((br) * (LD) + (kt) * BK) * 2); \
;     _Pragma("unroll") for (int _i = 0; _i < 2; ++_i) { \
;       __builtin_amdgcn_raw_ptr_buffer_load_lds(rs##BASE, (__attribute__((address_space(3))) unsigned*)((char*)(P) + tid_ * 16 + _i * 8192), 16, (int)off##LD[_i], _so, 0, 0); } } while (0)
; #define LDA_(dst, b, h) _Pragma("unroll") for (int m = 0; m < 4; ++m) _Pragma("unroll") for (int k = 0; k < 2; ++k) \
;     dst[m][k] = *reinterpret_cast<const bf16x8*>((char*)SA(b, h) + lds_byte(wr * 64 + m * 16 + fr, k * 32 + fq * 8))
; #define LDB_(dst, b, h) _Pragma("unroll") for (int n = 0; n < 2; ++n) _Pragma("unroll") for (int k = 0; k < 2; ++k) \
;     dst[n][k] = *reinterpret_cast<const bf16x8*>((char*)SB(b, h) + lds_byte(wc * 32 + n * 16 + fr, k * 32 + fq * 8))
; #define MMA(ai, bj, At, Bx) do { __builtin_amdgcn_s_setprio(1); \
;     _Pragma("unroll") for (int m = 0; m < 4; ++m) _Pragma("unroll") for (int n = 0; n < 2; ++n) _Pragma("unroll") for (int k = 0; k < 2; ++k) \
;       acc[ai][bj][m][n] = __builtin_amdgcn_mfma_f32_16x16x32_bf16(At[m][k], Bx[n][k], acc[ai][bj][m][n], 0, 0, 0); \
;     __builtin_amdgcn_s_setprio(0); } while (0)
; #define WAIT_V(n) asm volatile("s_waitcnt vmcnt(" #n ")" ::: "memory")
; #define WAIT_L(n) asm volatile("s_waitcnt lgkmcnt(" #n ")" ::: "memory")
; #define BAR __builtin_amdgcn_s_barrier()
; #define SCHED __builtin_amdgcn_sched_barrier(0)
; template <int K, int LDA, int LDB>
; DEVI void gemm_tile(const bf16* __restrict__ A, const bf16* __restrict__ Bt, bf16* shm, acc_t& acc) {
;     ...
;     STAGE(SB(0, 1), Bt, LDB, HALF, t + 2);
;     WAIT_V(6); BAR; MMA(1, 1, At, B1); BAR;
;     LDB_(B0, 1, 0); SCHED; LDA_(At, 1, 0); STAGE(SA(0, 1), A, LDA, HALF, t + 2);
;     WAIT_L(8); BAR; WAIT_L(0); MMA(0, 0, At, B0); BAR; SCHED;
;     LDB_(B1, 1, 1); STAGE(SB(1, 0), Bt, LDB, 0, t + 3);
;     BAR; WAIT_L(0); MMA(0, 1, At, B1); BAR;
;     LDA_(At, 1, 1); STAGE(SA(1, 0), A, LDA, 0, t + 3);
	v_readfirstlane_b32 s61, v148
	s_add_i32 s60, s13, 0xffffff80
	s_mov_b32 m0, s61
	v_readfirstlane_b32 s61, v149
	buffer_load_dwordx4 v140, s[0:3], s60 offen lds
	s_mov_b32 m0, s61
	s_nop 0
	buffer_load_dwordx4 v142, s[0:3], s60 offen lds
	s_waitcnt vmcnt(6)
	s_barrier
	s_setprio 1
	v_mfma_f32_16x16x32_bf16 v[30:33], v[180:183], v[212:215], v[30:33]
	v_mfma_f32_16x16x32_bf16 v[26:29], v[180:183], v[220:223], v[26:29]
	v_mfma_f32_16x16x32_bf16 v[22:25], v[188:191], v[212:215], v[22:25]
	v_mfma_f32_16x16x32_bf16 v[18:21], v[188:191], v[220:223], v[18:21]
	v_mfma_f32_16x16x32_bf16 v[14:17], v[196:199], v[212:215], v[14:17]
	v_mfma_f32_16x16x32_bf16 v[10:13], v[196:199], v[220:223], v[10:13]
	v_mfma_f32_16x16x32_bf16 v[6:9], v[204:207], v[212:215], v[6:9]
	v_mfma_f32_16x16x32_bf16 v[2:5], v[204:207], v[220:223], v[2:5]
	v_mfma_f32_16x16x32_bf16 v[30:33], v[184:187], v[216:219], v[30:33]
	v_mfma_f32_16x16x32_bf16 v[26:29], v[184:187], v[224:227], v[26:29]
	v_mfma_f32_16x16x32_bf16 v[22:25], v[192:195], v[216:219], v[22:25]
	v_mfma_f32_16x16x32_bf16 v[18:21], v[192:195], v[224:227], v[18:21]
	v_mfma_f32_16x16x32_bf16 v[14:17], v[200:203], v[216:219], v[14:17]
	v_mfma_f32_16x16x32_bf16 v[10:13], v[200:203], v[224:227], v[10:13]
	v_mfma_f32_16x16x32_bf16 v[6:9], v[208:211], v[216:219], v[6:9]
	v_mfma_f32_16x16x32_bf16 v[2:5], v[208:211], v[224:227], v[2:5]
	s_setprio 0
	s_barrier
	ds_read_b128 v[164:167], v143
	ds_read_b128 v[168:171], v143 offset:1024
	ds_read_b128 v[172:175], v143 offset:2048
	ds_read_b128 v[176:179], v143 offset:3072
	v_readfirstlane_b32 s61, v150
	s_mov_b32 m0, s61
	v_readfirstlane_b32 s61, v151
	ds_read_b128 v[180:183], v139 offset:32768
	ds_read_b128 v[184:187], v139 offset:33792
	ds_read_b128 v[188:191], v138 offset:32768
	ds_read_b128 v[192:195], v138 offset:33792
	ds_read_b128 v[196:199], v135 offset:32768
	ds_read_b128 v[200:203], v135 offset:33792
	ds_read_b128 v[204:207], v134 offset:32768
	ds_read_b128 v[208:211], v134 offset:33792
	buffer_load_dwordx4 v140, s[8:11], s60 offen lds
	s_mov_b32 m0, s61
	s_nop 0
	buffer_load_dwordx4 v142, s[8:11], s60 offen lds
	s_waitcnt lgkmcnt(8)
	s_barrier
	s_waitcnt lgkmcnt(0)
	s_setprio 1
	s_waitcnt lgkmcnt(7)
	v_mfma_f32_16x16x32_bf16 v[126:129], v[180:183], v[164:167], v[126:129]
	v_mfma_f32_16x16x32_bf16 v[122:125], v[180:183], v[172:175], v[122:125]
	s_waitcnt lgkmcnt(5)
	v_mfma_f32_16x16x32_bf16 v[118:121], v[188:191], v[164:167], v[118:121]
	v_mfma_f32_16x16x32_bf16 v[114:117], v[188:191], v[172:175], v[114:117]
	s_waitcnt lgkmcnt(3)
	v_mfma_f32_16x16x32_bf16 v[110:113], v[196:199], v[164:167], v[110:113]
	v_mfma_f32_16x16x32_bf16 v[106:109], v[196:199], v[172:175], v[106:109]
	s_waitcnt lgkmcnt(1)
	v_mfma_f32_16x16x32_bf16 v[102:105], v[204:207], v[164:167], v[102:105]
	v_mfma_f32_16x16x32_bf16 v[98:101], v[204:207], v[172:175], v[98:101]
	v_mfma_f32_16x16x32_bf16 v[126:129], v[184:187], v[168:171], v[126:129]
	v_mfma_f32_16x16x32_bf16 v[122:125], v[184:187], v[176:179], v[122:125]
	v_mfma_f32_16x16x32_bf16 v[118:121], v[192:195], v[168:171], v[118:121]
	v_mfma_f32_16x16x32_bf16 v[114:117], v[192:195], v[176:179], v[114:117]
	v_mfma_f32_16x16x32_bf16 v[110:113], v[200:203], v[168:171], v[110:113]
	v_mfma_f32_16x16x32_bf16 v[106:109], v[200:203], v[176:179], v[106:109]
	s_waitcnt lgkmcnt(0)
	v_mfma_f32_16x16x32_bf16 v[102:105], v[208:211], v[168:171], v[102:105]
	v_mfma_f32_16x16x32_bf16 v[98:101], v[208:211], v[176:179], v[98:101]
	s_setprio 0
	s_barrier
	v_readfirstlane_b32 s61, v152
	s_add_i32 s60, s13, 0xfff80000
	s_mov_b32 m0, s61
	v_readfirstlane_b32 s61, v153
	ds_read_b128 v[212:215], v141
	ds_read_b128 v[216:219], v141 offset:1024
	ds_read_b128 v[220:223], v141 offset:2048
	ds_read_b128 v[224:227], v141 offset:3072
	buffer_load_dwordx4 v140, s[0:3], s60 offen lds
	s_mov_b32 m0, s61
	s_nop 0
	buffer_load_dwordx4 v142, s[0:3], s60 offen lds
	s_barrier
	s_waitcnt lgkmcnt(0)
	s_setprio 1
	s_waitcnt lgkmcnt(3)
	v_mfma_f32_16x16x32_bf16 v[94:97], v[180:183], v[212:215], v[94:97]
	s_waitcnt lgkmcnt(1)
	v_mfma_f32_16x16x32_bf16 v[90:93], v[180:183], v[220:223], v[90:93]
	v_mfma_f32_16x16x32_bf16 v[86:89], v[188:191], v[212:215], v[86:89]
	v_mfma_f32_16x16x32_bf16 v[82:85], v[188:191], v[220:223], v[82:85]
	v_mfma_f32_16x16x32_bf16 v[78:81], v[196:199], v[212:215], v[78:81]
	v_mfma_f32_16x16x32_bf16 v[74:77], v[196:199], v[220:223], v[74:77]
	v_mfma_f32_16x16x32_bf16 v[70:73], v[204:207], v[212:215], v[70:73]
	v_mfma_f32_16x16x32_bf16 v[66:69], v[204:207], v[220:223], v[66:69]
	v_mfma_f32_16x16x32_bf16 v[94:97], v[184:187], v[216:219], v[94:97]
	s_waitcnt lgkmcnt(0)
	v_mfma_f32_16x16x32_bf16 v[90:93], v[184:187], v[224:227], v[90:93]
	v_mfma_f32_16x16x32_bf16 v[86:89], v[192:195], v[216:219], v[86:89]
	v_mfma_f32_16x16x32_bf16 v[82:85], v[192:195], v[224:227], v[82:85]
	v_mfma_f32_16x16x32_bf16 v[78:81], v[200:203], v[216:219], v[78:81]
	v_mfma_f32_16x16x32_bf16 v[74:77], v[200:203], v[224:227], v[74:77]
	v_mfma_f32_16x16x32_bf16 v[70:73], v[208:211], v[216:219], v[70:73]
	v_mfma_f32_16x16x32_bf16 v[66:69], v[208:211], v[224:227], v[66:69]
	s_setprio 0
	v_readfirstlane_b32 s61, v154
	s_mov_b32 m0, s61
	v_readfirstlane_b32 s61, v156
	s_barrier
	ds_read_b128 v[180:183], v139 offset:49152
	ds_read_b128 v[184:187], v139 offset:50176
	ds_read_b128 v[188:191], v138 offset:49152
	ds_read_b128 v[192:195], v138 offset:50176
	ds_read_b128 v[196:199], v135 offset:49152
	ds_read_b128 v[200:203], v135 offset:50176
	ds_read_b128 v[204:207], v134 offset:49152
	ds_read_b128 v[208:211], v134 offset:50176
	buffer_load_dwordx4 v140, s[8:11], s60 offen lds
	s_mov_b32 m0, s61
	s_nop 0
	buffer_load_dwordx4 v142, s[8:11], s60 offen lds
	s_barrier
; #define STAGE(P, BASE, LD, br, kt) do { const int _so = (int)(((br) * (LD) + (kt) * BK) * 2); \
;     _Pragma("unroll") for (int _i = 0; _i < 2; ++_i) { \
;       __builtin_amdgcn_raw_ptr_buffer_load_lds(rs##BASE, (__attribute__((address_space(3))) unsigned*)((char*)(P) + tid_ * 16 + _i * 8192), 16, (int)off##LD[_i], _so, 0, 0); } } while (0)
; #define LDA_(dst, b, h) _Pragma("unroll") for (int m = 0; m < 4; ++m) _Pragma("unroll") for (int k = 0; k < 2; ++k) \
;     dst[m][k] = *reinterpret_cast<const bf16x8*>((char*)SA(b, h) + lds_byte(wr * 64 + m * 16 + fr, k * 32 + fq * 8))
; #define LDB_(dst, b, h) _Pragma("unroll") for (int n = 0; n < 2; ++n) _Pragma("unroll") for (int k = 0; k < 2; ++k) \
;     dst[n][k] = *reinterpret_cast<const bf16x8*>((char*)SB(b, h) + lds_byte(wc * 32 + n * 16 + fr, k * 32 + fq * 8))
; #define MMA(ai, bj, At, Bx) do { __builtin_amdgcn_s_setprio(1); \
;     _Pragma("unroll") for (int m = 0; m < 4; ++m) _Pragma("unroll") for (int n = 0; n < 2; ++n) _Pragma("unroll") for (int k = 0; k < 2; ++k) \
;       acc[ai][bj][m][n] = __builtin_amdgcn_mfma_f32_16x16x32_bf16(At[m][k], Bx[n][k], acc[ai][bj][m][n], 0, 0, 0); \
;     __builtin_amdgcn_s_setprio(0); } while (0)
; #define WAIT_V(n) asm volatile("s_waitcnt vmcnt(" #n ")" ::: "memory")
; #define WAIT_L(n) asm volatile("s_waitcnt lgkmcnt(" #n ")" ::: "memory")
; #define BAR __builtin_amdgcn_s_barrier()
; #define SCHED __builtin_amdgcn_sched_barrier(0)
; template <int K, int LDA, int LDB>
; DEVI void gemm_tile(const bf16* __restrict__ A, const bf16* __restrict__ Bt, bf16* shm, acc_t& acc) {
;     ...
;     BAR; WAIT_L(0); MMA(1, 0, At, B0); BAR; SCHED;
;     STAGE(SB(1, 1), Bt, LDB, HALF, t + 3);
;     WAIT_V(6); BAR; MMA(1, 1, At, B1); BAR;
;   }
;   { LDB_(B0, 0, 0); LDA_(At, 0, 0); STAGE(SA(1, 1), A, LDA, HALF, nt - 1);
;     BAR; WAIT_L(0); MMA(0, 0, At, B0); BAR;
;     LDB_(B1, 0, 1); BAR; WAIT_L(0); MMA(0, 1, At, B1); BAR;
	s_waitcnt lgkmcnt(0)
	s_setprio 1
	s_waitcnt lgkmcnt(7)
	v_mfma_f32_16x16x32_bf16 v[62:65], v[180:183], v[164:167], v[62:65]
	v_mfma_f32_16x16x32_bf16 v[58:61], v[180:183], v[172:175], v[58:61]
	s_waitcnt lgkmcnt(5)
	v_mfma_f32_16x16x32_bf16 v[54:57], v[188:191], v[164:167], v[54:57]
	v_mfma_f32_16x16x32_bf16 v[50:53], v[188:191], v[172:175], v[50:53]
	s_waitcnt lgkmcnt(3)
	v_mfma_f32_16x16x32_bf16 v[46:49], v[196:199], v[164:167], v[46:49]
	v_mfma_f32_16x16x32_bf16 v[42:45], v[196:199], v[172:175], v[42:45]
	s_waitcnt lgkmcnt(1)
	v_mfma_f32_16x16x32_bf16 v[38:41], v[204:207], v[164:167], v[38:41]
	v_mfma_f32_16x16x32_bf16 v[34:37], v[204:207], v[172:175], v[34:37]
	v_mfma_f32_16x16x32_bf16 v[62:65], v[184:187], v[168:171], v[62:65]
	v_mfma_f32_16x16x32_bf16 v[58:61], v[184:187], v[176:179], v[58:61]
	v_mfma_f32_16x16x32_bf16 v[54:57], v[192:195], v[168:171], v[54:57]
	v_mfma_f32_16x16x32_bf16 v[50:53], v[192:195], v[176:179], v[50:53]
	v_mfma_f32_16x16x32_bf16 v[46:49], v[200:203], v[168:171], v[46:49]
	v_mfma_f32_16x16x32_bf16 v[42:45], v[200:203], v[176:179], v[42:45]
	s_waitcnt lgkmcnt(0)
	v_mfma_f32_16x16x32_bf16 v[38:41], v[208:211], v[168:171], v[38:41]
	v_mfma_f32_16x16x32_bf16 v[34:37], v[208:211], v[176:179], v[34:37]
	s_setprio 0
	s_barrier
	v_readfirstlane_b32 s60, v158
	s_mov_b32 m0, s60
	v_readfirstlane_b32 s60, v159
	buffer_load_dwordx4 v140, s[0:3], s13 offen lds
	s_mov_b32 m0, s60
	s_nop 0
	buffer_load_dwordx4 v142, s[0:3], s13 offen lds
	s_waitcnt vmcnt(6)
	s_barrier
	s_setprio 1
	v_mfma_f32_16x16x32_bf16 v[30:33], v[180:183], v[212:215], v[30:33]
	v_mfma_f32_16x16x32_bf16 v[26:29], v[180:183], v[220:223], v[26:29]
	v_mfma_f32_16x16x32_bf16 v[22:25], v[188:191], v[212:215], v[22:25]
	v_mfma_f32_16x16x32_bf16 v[18:21], v[188:191], v[220:223], v[18:21]
	v_mfma_f32_16x16x32_bf16 v[14:17], v[196:199], v[212:215], v[14:17]
	v_mfma_f32_16x16x32_bf16 v[10:13], v[196:199], v[220:223], v[10:13]
	v_mfma_f32_16x16x32_bf16 v[6:9], v[204:207], v[212:215], v[6:9]
	v_mfma_f32_16x16x32_bf16 v[2:5], v[204:207], v[220:223], v[2:5]
	v_mfma_f32_16x16x32_bf16 v[30:33], v[184:187], v[216:219], v[30:33]
	v_mfma_f32_16x16x32_bf16 v[26:29], v[184:187], v[224:227], v[26:29]
	v_mfma_f32_16x16x32_bf16 v[22:25], v[192:195], v[216:219], v[22:25]
	v_mfma_f32_16x16x32_bf16 v[18:21], v[192:195], v[224:227], v[18:21]
	v_mfma_f32_16x16x32_bf16 v[14:17], v[200:203], v[216:219], v[14:17]
	v_mfma_f32_16x16x32_bf16 v[10:13], v[200:203], v[224:227], v[10:13]
	v_mfma_f32_16x16x32_bf16 v[6:9], v[208:211], v[216:219], v[6:9]
	v_mfma_f32_16x16x32_bf16 v[2:5], v[208:211], v[224:227], v[2:5]
	s_setprio 0
	s_add_i32 s7, s7, 2
	s_addk_i32 s13, 0x100
	s_cmp_lt_u32 s7, 28
	s_cbranch_scc1 .Lrot_33591
	s_barrier
	v_readfirstlane_b32 s0, v157
	s_mov_b32 s10, s2
	s_mov_b32 s11, s3
	s_mov_b32 m0, s0
	v_readfirstlane_b32 s0, v160
	ds_read_b128 v[144:147], v161
	ds_read_b128 v[148:151], v161 offset:1024
	ds_read_b128 v[164:167], v161 offset:2048
	ds_read_b128 v[168:171], v161 offset:3072
	ds_read_b128 v[172:175], v139
	ds_read_b128 v[176:179], v139 offset:1024
	ds_read_b128 v[180:183], v138
	ds_read_b128 v[184:187], v138 offset:1024
	ds_read_b128 v[188:191], v135
	ds_read_b128 v[192:195], v135 offset:1024
	ds_read_b128 v[196:199], v134
	ds_read_b128 v[200:203], v134 offset:1024
	buffer_load_dwordx4 v140, s[8:11], s35 offen lds
	s_mov_b32 m0, s0
	s_nop 0
	buffer_load_dwordx4 v142, s[8:11], s35 offen lds
	s_barrier
	s_waitcnt lgkmcnt(0)
	s_setprio 1
	s_waitcnt lgkmcnt(7)
	v_mfma_f32_16x16x32_bf16 v[126:129], v[172:175], v[144:147], v[126:129]
	v_mfma_f32_16x16x32_bf16 v[122:125], v[172:175], v[164:167], v[122:125]
	s_waitcnt lgkmcnt(5)
	v_mfma_f32_16x16x32_bf16 v[118:121], v[180:183], v[144:147], v[118:121]
	v_mfma_f32_16x16x32_bf16 v[114:117], v[180:183], v[164:167], v[114:117]
	s_waitcnt lgkmcnt(3)
	v_mfma_f32_16x16x32_bf16 v[110:113], v[188:191], v[144:147], v[110:113]
	v_mfma_f32_16x16x32_bf16 v[106:109], v[188:191], v[164:167], v[106:109]
	s_waitcnt lgkmcnt(1)
	v_mfma_f32_16x16x32_bf16 v[102:105], v[196:199], v[144:147], v[102:105]
	v_mfma_f32_16x16x32_bf16 v[98:101], v[196:199], v[164:167], v[98:101]
	v_mfma_f32_16x16x32_bf16 v[126:129], v[176:179], v[148:151], v[126:129]
	v_mfma_f32_16x16x32_bf16 v[122:125], v[176:179], v[168:171], v[122:125]
	v_mfma_f32_16x16x32_bf16 v[118:121], v[184:187], v[148:151], v[118:121]
	v_mfma_f32_16x16x32_bf16 v[114:117], v[184:187], v[168:171], v[114:117]
	v_mfma_f32_16x16x32_bf16 v[110:113], v[192:195], v[148:151], v[110:113]
	v_mfma_f32_16x16x32_bf16 v[106:109], v[192:195], v[168:171], v[106:109]
	s_waitcnt lgkmcnt(0)
	v_mfma_f32_16x16x32_bf16 v[102:105], v[200:203], v[148:151], v[102:105]
	v_mfma_f32_16x16x32_bf16 v[98:101], v[200:203], v[168:171], v[98:101]
	s_setprio 0
	s_barrier
	ds_read_b128 v[156:159], v155
	ds_read_b128 v[204:207], v155 offset:1024
	ds_read_b128 v[208:211], v155 offset:2048
	ds_read_b128 v[152:155], v155 offset:3072
	s_barrier
	s_waitcnt lgkmcnt(0)
	s_setprio 1
	s_waitcnt lgkmcnt(3)
	v_mfma_f32_16x16x32_bf16 v[94:97], v[172:175], v[156:159], v[94:97]
	s_waitcnt lgkmcnt(1)
	v_mfma_f32_16x16x32_bf16 v[90:93], v[172:175], v[208:211], v[90:93]
	v_mfma_f32_16x16x32_bf16 v[86:89], v[180:183], v[156:159], v[86:89]
	v_mfma_f32_16x16x32_bf16 v[82:85], v[180:183], v[208:211], v[82:85]
	v_mfma_f32_16x16x32_bf16 v[78:81], v[188:191], v[156:159], v[78:81]
	v_mfma_f32_16x16x32_bf16 v[70:73], v[196:199], v[156:159], v[70:73]
	v_mfma_f32_16x16x32_bf16 v[94:97], v[176:179], v[204:207], v[94:97]
	s_waitcnt lgkmcnt(0)
	v_mfma_f32_16x16x32_bf16 v[90:93], v[176:179], v[152:155], v[90:93]
	v_mfma_f32_16x16x32_bf16 v[86:89], v[184:187], v[204:207], v[86:89]
	v_mfma_f32_16x16x32_bf16 v[82:85], v[184:187], v[152:155], v[82:85]
	v_mfma_f32_16x16x32_bf16 v[78:81], v[192:195], v[204:207], v[78:81]
	v_mfma_f32_16x16x32_bf16 v[74:77], v[188:191], v[208:211], v[74:77]
	v_mfma_f32_16x16x32_bf16 v[70:73], v[200:203], v[204:207], v[70:73]
	v_mfma_f32_16x16x32_bf16 v[66:69], v[196:199], v[208:211], v[66:69]
	v_mfma_f32_16x16x32_bf16 v[172:175], v[192:195], v[152:155], v[74:77]
	v_mfma_f32_16x16x32_bf16 v[176:179], v[200:203], v[152:155], v[66:69]
	s_setprio 0
	s_barrier
; #define LDA_(dst, b, h) _Pragma("unroll") for (int m = 0; m < 4; ++m) _Pragma("unroll") for (int k = 0; k < 2; ++k) \
;     dst[m][k] = *reinterpret_cast<const bf16x8*>((char*)SA(b, h) + lds_byte(wr * 64 + m * 16 + fr, k * 32 + fq * 8))
; #define LDB_(dst, b, h) _Pragma("unroll") for (int n = 0; n < 2; ++n) _Pragma("unroll") for (int k = 0; k < 2; ++k) \
;     dst[n][k] = *reinterpret_cast<const bf16x8*>((char*)SB(b, h) + lds_byte(wc * 32 + n * 16 + fr, k * 32 + fq * 8))
; #define MMA(ai, bj, At, Bx) do { __builtin_amdgcn_s_setprio(1); \
;     _Pragma("unroll") for (int m = 0; m < 4; ++m) _Pragma("unroll") for (int n = 0; n < 2; ++n) _Pragma("unroll") for (int k = 0; k < 2; ++k) \
;       acc[ai][bj][m][n] = __builtin_amdgcn_mfma_f32_16x16x32_bf16(At[m][k], Bx[n][k], acc[ai][bj][m][n], 0, 0, 0); \
;     __builtin_amdgcn_s_setprio(0); } while (0)
; #define WAIT_V(n) asm volatile("s_waitcnt vmcnt(" #n ")" ::: "memory")
; #define WAIT_L(n) asm volatile("s_waitcnt lgkmcnt(" #n ")" ::: "memory")
; #define BAR __builtin_amdgcn_s_barrier()
; template <int K, int LDA, int LDB>
; DEVI void gemm_tile(const bf16* __restrict__ A, const bf16* __restrict__ Bt, bf16* shm, acc_t& acc) {
;     ...
;     LDA_(At, 0, 1); WAIT_V(4); BAR; WAIT_L(0); MMA(1, 0, At, B0); MMA(1, 1, At, B1); BAR; }
;   { LDB_(B0, 1, 0); LDA_(At, 1, 0); WAIT_V(2); BAR; WAIT_L(0); MMA(0, 0, At, B0); BAR;
	s_nop 3
	ds_read_b128 v[66:69], v139 offset:16384
	ds_read_b128 v[74:77], v139 offset:17408
	ds_read_b128 v[180:183], v138 offset:16384
	ds_read_b128 v[184:187], v138 offset:17408
	ds_read_b128 v[188:191], v135 offset:16384
	ds_read_b128 v[192:195], v135 offset:17408
	ds_read_b128 v[196:199], v134 offset:16384
	ds_read_b128 v[200:203], v134 offset:17408
	s_waitcnt vmcnt(4)
	s_barrier
	s_waitcnt lgkmcnt(0)
	s_setprio 1
	s_waitcnt lgkmcnt(3)
	v_mfma_f32_16x16x32_bf16 v[46:49], v[188:191], v[144:147], v[46:49]
	s_waitcnt lgkmcnt(1)
	v_mfma_f32_16x16x32_bf16 v[38:41], v[196:199], v[144:147], v[38:41]
	v_mfma_f32_16x16x32_bf16 v[34:37], v[196:199], v[164:167], v[34:37]
	v_mfma_f32_16x16x32_bf16 v[62:65], v[66:69], v[144:147], v[62:65]
	v_mfma_f32_16x16x32_bf16 v[58:61], v[66:69], v[164:167], v[58:61]
	v_mfma_f32_16x16x32_bf16 v[54:57], v[180:183], v[144:147], v[54:57]
	v_mfma_f32_16x16x32_bf16 v[50:53], v[180:183], v[164:167], v[50:53]
	v_mfma_f32_16x16x32_bf16 v[46:49], v[192:195], v[148:151], v[46:49]
	v_mfma_f32_16x16x32_bf16 v[42:45], v[188:191], v[164:167], v[42:45]
	s_waitcnt lgkmcnt(0)
	v_mfma_f32_16x16x32_bf16 v[38:41], v[200:203], v[148:151], v[38:41]
	v_mfma_f32_16x16x32_bf16 v[34:37], v[200:203], v[168:171], v[34:37]
	v_mfma_f32_16x16x32_bf16 v[212:215], v[74:77], v[148:151], v[62:65]
	v_mfma_f32_16x16x32_bf16 v[216:219], v[74:77], v[168:171], v[58:61]
	v_mfma_f32_16x16x32_bf16 v[220:223], v[184:187], v[148:151], v[54:57]
	v_mfma_f32_16x16x32_bf16 v[224:227], v[184:187], v[168:171], v[50:53]
	v_mfma_f32_16x16x32_bf16 v[228:231], v[192:195], v[168:171], v[42:45]
	s_setprio 0
	s_setprio 1
	v_mfma_f32_16x16x32_bf16 v[30:33], v[66:69], v[156:159], v[30:33]
	v_mfma_f32_16x16x32_bf16 v[22:25], v[180:183], v[156:159], v[22:25]
	v_mfma_f32_16x16x32_bf16 v[18:21], v[180:183], v[208:211], v[18:21]
	v_mfma_f32_16x16x32_bf16 v[10:13], v[188:191], v[208:211], v[10:13]
	v_mfma_f32_16x16x32_bf16 v[6:9], v[196:199], v[156:159], v[6:9]
	v_mfma_f32_16x16x32_bf16 v[2:5], v[196:199], v[208:211], v[2:5]
	v_mfma_f32_16x16x32_bf16 v[30:33], v[74:77], v[204:207], v[30:33]
	v_mfma_f32_16x16x32_bf16 v[26:29], v[66:69], v[208:211], v[26:29]
	v_mfma_f32_16x16x32_bf16 v[22:25], v[184:187], v[204:207], v[22:25]
	v_mfma_f32_16x16x32_bf16 v[18:21], v[184:187], v[152:155], v[18:21]
	v_mfma_f32_16x16x32_bf16 v[14:17], v[188:191], v[156:159], v[14:17]
	v_mfma_f32_16x16x32_bf16 v[10:13], v[192:195], v[152:155], v[10:13]
	v_mfma_f32_16x16x32_bf16 v[6:9], v[200:203], v[204:207], v[6:9]
	v_mfma_f32_16x16x32_bf16 v[2:5], v[200:203], v[152:155], v[2:5]
	v_mfma_f32_16x16x32_bf16 v[144:147], v[74:77], v[152:155], v[26:29]
	v_mfma_f32_16x16x32_bf16 v[148:151], v[192:195], v[204:207], v[14:17]
	s_setprio 0
	s_barrier
	ds_read_b128 v[152:155], v143
	ds_read_b128 v[156:159], v143 offset:1024
	ds_read_b128 v[164:167], v143 offset:2048
	ds_read_b128 v[168:171], v143 offset:3072
	ds_read_b128 v[58:61], v139 offset:32768
	ds_read_b128 v[62:65], v139 offset:33792
	ds_read_b128 v[66:69], v138 offset:32768
	ds_read_b128 v[74:77], v138 offset:33792
	ds_read_b128 v[180:183], v135 offset:32768
	ds_read_b128 v[184:187], v135 offset:33792
	ds_read_b128 v[188:191], v134 offset:32768
	ds_read_b128 v[192:195], v134 offset:33792
	s_waitcnt vmcnt(2)
	s_barrier
	s_waitcnt lgkmcnt(0)
	s_setprio 1
	s_waitcnt lgkmcnt(7)
	v_mfma_f32_16x16x32_bf16 v[14:17], v[58:61], v[152:155], v[126:129]
	s_waitcnt lgkmcnt(5)
	v_mfma_f32_16x16x32_bf16 v[26:29], v[66:69], v[152:155], v[118:121]
	s_waitcnt lgkmcnt(3)
	v_mfma_f32_16x16x32_bf16 v[42:45], v[180:183], v[152:155], v[110:113]
	s_waitcnt lgkmcnt(1)
	v_mfma_f32_16x16x32_bf16 v[50:53], v[188:191], v[152:155], v[102:105]
	v_mfma_f32_16x16x32_bf16 v[126:129], v[62:65], v[156:159], v[14:17]
	v_mfma_f32_16x16x32_bf16 v[14:17], v[58:61], v[164:167], v[122:125]
	v_mfma_f32_16x16x32_bf16 v[122:125], v[74:77], v[156:159], v[26:29]
	v_mfma_f32_16x16x32_bf16 v[26:29], v[66:69], v[164:167], v[114:117]
	v_mfma_f32_16x16x32_bf16 v[118:121], v[184:187], v[156:159], v[42:45]
	v_mfma_f32_16x16x32_bf16 v[42:45], v[180:183], v[164:167], v[106:109]
	s_waitcnt lgkmcnt(0)
	v_mfma_f32_16x16x32_bf16 v[114:117], v[192:195], v[156:159], v[50:53]
	v_mfma_f32_16x16x32_bf16 v[50:53], v[188:191], v[164:167], v[98:101]
	v_mfma_f32_16x16x32_bf16 v[14:17], v[62:65], v[168:171], v[14:17]
	v_mfma_f32_16x16x32_bf16 v[26:29], v[74:77], v[168:171], v[26:29]
	v_mfma_f32_16x16x32_bf16 v[42:45], v[184:187], v[168:171], v[42:45]
	v_mfma_f32_16x16x32_bf16 v[54:57], v[192:195], v[168:171], v[50:53]
	s_setprio 0
	s_barrier
; #define LDA_(dst, b, h) _Pragma("unroll") for (int m = 0; m < 4; ++m) _Pragma("unroll") for (int k = 0; k < 2; ++k) \
;     dst[m][k] = *reinterpret_cast<const bf16x8*>((char*)SA(b, h) + lds_byte(wr * 64 + m * 16 + fr, k * 32 + fq * 8))
; #define LDB_(dst, b, h) _Pragma("unroll") for (int n = 0; n < 2; ++n) _Pragma("unroll") for (int k = 0; k < 2; ++k) \
;     dst[n][k] = *reinterpret_cast<const bf16x8*>((char*)SB(b, h) + lds_byte(wc * 32 + n * 16 + fr, k * 32 + fq * 8))
; #define MMA(ai, bj, At, Bx) do { __builtin_amdgcn_s_setprio(1); \
;     _Pragma("unroll") for (int m = 0; m < 4; ++m) _Pragma("unroll") for (int n = 0; n < 2; ++n) _Pragma("unroll") for (int k = 0; k < 2; ++k) \
;       acc[ai][bj][m][n] = __builtin_amdgcn_mfma_f32_16x16x32_bf16(At[m][k], Bx[n][k], acc[ai][bj][m][n], 0, 0, 0); \
;     __builtin_amdgcn_s_setprio(0); } while (0)
; #define WAIT_V(n) asm volatile("s_waitcnt vmcnt(" #n ")" ::: "memory")
; #define WAIT_L(n) asm volatile("s_waitcnt lgkmcnt(" #n ")" ::: "memory")
; #define BAR __builtin_amdgcn_s_barrier()
; template <int K, int LDA, int LDB>
; DEVI void gemm_tile(const bf16* __restrict__ A, const bf16* __restrict__ Bt, bf16* shm, acc_t& acc) {
;     ...
;     LDB_(B1, 1, 1); WAIT_V(0); BAR; WAIT_L(0); MMA(0, 1, At, B1); BAR;
;     LDA_(At, 1, 1); BAR; WAIT_L(0); MMA(1, 0, At, B0); MMA(1, 1, At, B1); BAR; }
;   if (wr == 0) BAR;
	ds_read_b128 v[196:199], v141
	ds_read_b128 v[200:203], v141 offset:1024
	ds_read_b128 v[204:207], v141 offset:2048
	ds_read_b128 v[140:143], v141 offset:3072
	s_waitcnt vmcnt(0)
	s_barrier
	s_waitcnt lgkmcnt(0)
	s_setprio 1
	s_waitcnt lgkmcnt(3)
	v_mfma_f32_16x16x32_bf16 v[50:53], v[58:61], v[196:199], v[94:97]
	s_waitcnt lgkmcnt(1)
	v_mfma_f32_16x16x32_bf16 v[58:61], v[58:61], v[204:207], v[90:93]
	v_mfma_f32_16x16x32_bf16 v[50:53], v[62:65], v[200:203], v[50:53]
	s_waitcnt lgkmcnt(0)
	v_mfma_f32_16x16x32_bf16 v[58:61], v[62:65], v[140:143], v[58:61]
	v_mfma_f32_16x16x32_bf16 v[62:65], v[66:69], v[196:199], v[86:89]
	v_mfma_f32_16x16x32_bf16 v[66:69], v[66:69], v[204:207], v[82:85]
	v_mfma_f32_16x16x32_bf16 v[70:73], v[188:191], v[196:199], v[70:73]
	v_mfma_f32_16x16x32_bf16 v[62:65], v[74:77], v[200:203], v[62:65]
	v_mfma_f32_16x16x32_bf16 v[66:69], v[74:77], v[140:143], v[66:69]
	v_mfma_f32_16x16x32_bf16 v[74:77], v[180:183], v[196:199], v[78:81]
	v_mfma_f32_16x16x32_bf16 v[78:81], v[180:183], v[204:207], v[172:175]
	v_mfma_f32_16x16x32_bf16 v[90:93], v[192:195], v[200:203], v[70:73]
	v_mfma_f32_16x16x32_bf16 v[70:73], v[188:191], v[204:207], v[176:179]
	v_mfma_f32_16x16x32_bf16 v[74:77], v[184:187], v[200:203], v[74:77]
	v_mfma_f32_16x16x32_bf16 v[82:85], v[184:187], v[140:143], v[78:81]
	v_mfma_f32_16x16x32_bf16 v[98:101], v[192:195], v[140:143], v[70:73]
	s_setprio 0
	s_barrier
	ds_read_b128 v[172:175], v139 offset:49152
	ds_read_b128 v[176:179], v139 offset:50176
	ds_read_b128 v[180:183], v138 offset:49152
	ds_read_b128 v[184:187], v138 offset:50176
	ds_read_b128 v[188:191], v135 offset:49152
	ds_read_b128 v[192:195], v135 offset:50176
	ds_read_b128 v[208:211], v134 offset:49152
	ds_read_b128 v[232:235], v134 offset:50176
	s_barrier
	s_waitcnt lgkmcnt(0)
	s_setprio 1
	s_waitcnt lgkmcnt(7)
	v_mfma_f32_16x16x32_bf16 v[70:73], v[172:175], v[152:155], v[212:215]
	s_waitcnt lgkmcnt(6)
	v_mfma_f32_16x16x32_bf16 v[110:113], v[176:179], v[156:159], v[70:73]
	v_mfma_f32_16x16x32_bf16 v[70:73], v[172:175], v[164:167], v[216:219]
	v_mfma_f32_16x16x32_bf16 v[106:109], v[176:179], v[168:171], v[70:73]
	s_waitcnt lgkmcnt(5)
	v_mfma_f32_16x16x32_bf16 v[70:73], v[180:183], v[152:155], v[220:223]
	s_waitcnt lgkmcnt(3)
	v_mfma_f32_16x16x32_bf16 v[46:49], v[188:191], v[152:155], v[46:49]
	v_mfma_f32_16x16x32_bf16 v[102:105], v[184:187], v[156:159], v[70:73]
	v_mfma_f32_16x16x32_bf16 v[70:73], v[180:183], v[164:167], v[224:227]
	s_waitcnt lgkmcnt(2)
	v_mfma_f32_16x16x32_bf16 v[86:89], v[192:195], v[156:159], v[46:49]
	v_mfma_f32_16x16x32_bf16 v[46:49], v[188:191], v[164:167], v[228:231]
	s_waitcnt lgkmcnt(1)
	v_mfma_f32_16x16x32_bf16 v[38:41], v[208:211], v[152:155], v[38:41]
	v_mfma_f32_16x16x32_bf16 v[34:37], v[208:211], v[164:167], v[34:37]
	v_mfma_f32_16x16x32_bf16 v[94:97], v[184:187], v[168:171], v[70:73]
	v_mfma_f32_16x16x32_bf16 v[78:81], v[192:195], v[168:171], v[46:49]
	s_waitcnt lgkmcnt(0)
	v_mfma_f32_16x16x32_bf16 v[70:73], v[232:235], v[156:159], v[38:41]
	v_mfma_f32_16x16x32_bf16 v[46:49], v[232:235], v[168:171], v[34:37]
	s_setprio 0
	s_setprio 1
	v_mfma_f32_16x16x32_bf16 v[30:33], v[172:175], v[196:199], v[30:33]
	v_mfma_f32_16x16x32_bf16 v[38:41], v[176:179], v[200:203], v[30:33]
	v_mfma_f32_16x16x32_bf16 v[30:33], v[172:175], v[204:207], v[144:147]
	v_mfma_f32_16x16x32_bf16 v[22:25], v[180:183], v[196:199], v[22:25]
	v_mfma_f32_16x16x32_bf16 v[18:21], v[180:183], v[204:207], v[18:21]
	v_mfma_f32_16x16x32_bf16 v[34:37], v[176:179], v[140:143], v[30:33]
	v_mfma_f32_16x16x32_bf16 v[30:33], v[184:187], v[200:203], v[22:25]
	v_mfma_f32_16x16x32_bf16 v[22:25], v[184:187], v[140:143], v[18:21]
	v_mfma_f32_16x16x32_bf16 v[18:21], v[188:191], v[196:199], v[148:151]
	v_mfma_f32_16x16x32_bf16 v[10:13], v[188:191], v[204:207], v[10:13]
	v_mfma_f32_16x16x32_bf16 v[6:9], v[208:211], v[196:199], v[6:9]
	v_mfma_f32_16x16x32_bf16 v[2:5], v[208:211], v[204:207], v[2:5]
	v_mfma_f32_16x16x32_bf16 v[18:21], v[192:195], v[200:203], v[18:21]
	v_mfma_f32_16x16x32_bf16 v[10:13], v[192:195], v[140:143], v[10:13]
	v_mfma_f32_16x16x32_bf16 v[6:9], v[232:235], v[200:203], v[6:9]
	v_mfma_f32_16x16x32_bf16 v[2:5], v[232:235], v[140:143], v[2:5]
	s_setprio 0
	s_movk_i32 s0, 0x100
	v_cmp_gt_u32_e32 vcc, s0, v132
	s_barrier
	s_and_saveexec_b64 s[0:1], vcc
	s_cbranch_execz .LBB0_1613
	s_barrier

; #define STAGE(P, BASE, LD, br, kt) do { const int _so = (int)(((br) * (LD) + (kt) * BK) * 2); \
;     _Pragma("unroll") for (int _i = 0; _i < 2; ++_i) { \
;       __builtin_amdgcn_raw_ptr_buffer_load_lds(rs##BASE, (__attribute__((address_space(3))) unsigned*)((char*)(P) + tid_ * 16 + _i * 8192), 16, (int)off##LD[_i], _so, 0, 0); } } while (0)
; #define LDA_(dst, b, h) _Pragma("unroll") for (int m = 0; m < 4; ++m) _Pragma("unroll") for (int k = 0; k < 2; ++k) \
;     dst[m][k] = *reinterpret_cast<const bf16x8*>((char*)SA(b, h) + lds_byte(wr * 64 + m * 16 + fr, k * 32 + fq * 8))
; #define LDB_(dst, b, h) _Pragma("unroll") for (int n = 0; n < 2; ++n) _Pragma("unroll") for (int k = 0; k < 2; ++k) \
;     dst[n][k] = *reinterpret_cast<const bf16x8*>((char*)SB(b, h) + lds_byte(wc * 32 + n * 16 + fr, k * 32 + fq * 8))
; #define MMA(ai, bj, At, Bx) do { __builtin_amdgcn_s_setprio(1); \
;     _Pragma("unroll") for (int m = 0; m < 4; ++m) _Pragma("unroll") for (int n = 0; n < 2; ++n) _Pragma("unroll") for (int k = 0; k < 2; ++k) \
;       acc[ai][bj][m][n] = __builtin_amdgcn_mfma_f32_16x16x32_bf16(At[m][k], Bx[n][k], acc[ai][bj][m][n], 0, 0, 0); \
;     __builtin_amdgcn_s_setprio(0); } while (0)
; #define WAIT_L(n) asm volatile("s_waitcnt lgkmcnt(" #n ")" ::: "memory")
; #define BAR __builtin_amdgcn_s_barrier()
; #define SCHED __builtin_amdgcn_sched_barrier(0)
; template <int K, int LDA, int LDB>
; DEVI void gemm_tile(const bf16* __restrict__ A, const bf16* __restrict__ Bt, bf16* shm, acc_t& acc) {
;     ...
;     LDB_(B0, 0, 0); SCHED; LDA_(At, 0, 0); STAGE(SA(1, 1), A, LDA, HALF, t + 1);
;     WAIT_L(8); BAR; WAIT_L(0); MMA(0, 0, At, B0); BAR; SCHED;
;     LDB_(B1, 0, 1); STAGE(SB(0, 0), Bt, LDB, 0, t + 2);
;     BAR; WAIT_L(0); MMA(0, 1, At, B1); BAR;
;     LDA_(At, 0, 1); STAGE(SA(0, 0), A, LDA, 0, t + 2);
;     BAR; WAIT_L(0); MMA(1, 0, At, B0); BAR; SCHED;
.LBB0_1661:
	ds_read_b128 v[166:169], v165
	ds_read_b128 v[170:173], v165 offset:1024
	ds_read_b128 v[174:177], v165 offset:2048
	ds_read_b128 v[178:181], v165 offset:3072
	v_readfirstlane_b32 s44, v159
	s_add_i32 s43, s15, 0xffffff00
	s_mov_b32 m0, s44
	v_readfirstlane_b32 s44, v164
	ds_read_b128 v[182:185], v137
	ds_read_b128 v[186:189], v137 offset:1024
	ds_read_b128 v[190:193], v136
	ds_read_b128 v[194:197], v136 offset:1024
	ds_read_b128 v[198:201], v135
	ds_read_b128 v[202:205], v135 offset:1024
	ds_read_b128 v[206:209], v134
	ds_read_b128 v[210:213], v134 offset:1024
	buffer_load_dwordx4 v142, s[8:11], s43 offen lds
	s_mov_b32 m0, s44
	s_nop 0
	buffer_load_dwordx4 v144, s[8:11], s43 offen lds
	s_waitcnt lgkmcnt(8)
	s_barrier
	s_waitcnt lgkmcnt(0)
	s_setprio 1
	s_waitcnt lgkmcnt(7)
	v_mfma_f32_16x16x32_bf16 v[126:129], v[182:185], v[166:169], v[126:129]
	v_mfma_f32_16x16x32_bf16 v[122:125], v[182:185], v[174:177], v[122:125]
	s_waitcnt lgkmcnt(5)
	v_mfma_f32_16x16x32_bf16 v[118:121], v[190:193], v[166:169], v[118:121]
	v_mfma_f32_16x16x32_bf16 v[114:117], v[190:193], v[174:177], v[114:117]
	s_waitcnt lgkmcnt(3)
	v_mfma_f32_16x16x32_bf16 v[110:113], v[198:201], v[166:169], v[110:113]
	v_mfma_f32_16x16x32_bf16 v[106:109], v[198:201], v[174:177], v[106:109]
	s_waitcnt lgkmcnt(1)
	v_mfma_f32_16x16x32_bf16 v[102:105], v[206:209], v[166:169], v[102:105]
	v_mfma_f32_16x16x32_bf16 v[98:101], v[206:209], v[174:177], v[98:101]
	v_mfma_f32_16x16x32_bf16 v[126:129], v[186:189], v[170:173], v[126:129]
	v_mfma_f32_16x16x32_bf16 v[122:125], v[186:189], v[178:181], v[122:125]
	v_mfma_f32_16x16x32_bf16 v[118:121], v[194:197], v[170:173], v[118:121]
	v_mfma_f32_16x16x32_bf16 v[114:117], v[194:197], v[178:181], v[114:117]
	v_mfma_f32_16x16x32_bf16 v[110:113], v[202:205], v[170:173], v[110:113]
	v_mfma_f32_16x16x32_bf16 v[106:109], v[202:205], v[178:181], v[106:109]
	s_waitcnt lgkmcnt(0)
	v_mfma_f32_16x16x32_bf16 v[102:105], v[210:213], v[170:173], v[102:105]
	v_mfma_f32_16x16x32_bf16 v[98:101], v[210:213], v[178:181], v[98:101]
	s_setprio 0
	s_barrier
	v_readfirstlane_b32 s44, v146
	s_add_i32 s43, s15, 0xfff7ff80
	s_mov_b32 m0, s44
	v_readfirstlane_b32 s44, v147
	ds_read_b128 v[214:217], v157
	ds_read_b128 v[218:221], v157 offset:1024
	ds_read_b128 v[222:225], v157 offset:2048
	ds_read_b128 v[226:229], v157 offset:3072
	buffer_load_dwordx4 v142, s[4:7], s43 offen lds
	s_mov_b32 m0, s44
	s_nop 0
	buffer_load_dwordx4 v144, s[4:7], s43 offen lds
	s_barrier
	s_waitcnt lgkmcnt(0)
	s_setprio 1
	s_waitcnt lgkmcnt(3)
	v_mfma_f32_16x16x32_bf16 v[94:97], v[182:185], v[214:217], v[94:97]
	s_waitcnt lgkmcnt(1)
	v_mfma_f32_16x16x32_bf16 v[90:93], v[182:185], v[222:225], v[90:93]
	v_mfma_f32_16x16x32_bf16 v[86:89], v[190:193], v[214:217], v[86:89]
	v_mfma_f32_16x16x32_bf16 v[82:85], v[190:193], v[222:225], v[82:85]
	v_mfma_f32_16x16x32_bf16 v[78:81], v[198:201], v[214:217], v[78:81]
	v_mfma_f32_16x16x32_bf16 v[74:77], v[198:201], v[222:225], v[74:77]
	v_mfma_f32_16x16x32_bf16 v[70:73], v[206:209], v[214:217], v[70:73]
	v_mfma_f32_16x16x32_bf16 v[66:69], v[206:209], v[222:225], v[66:69]
	v_mfma_f32_16x16x32_bf16 v[94:97], v[186:189], v[218:221], v[94:97]
	s_waitcnt lgkmcnt(0)
	v_mfma_f32_16x16x32_bf16 v[90:93], v[186:189], v[226:229], v[90:93]
	v_mfma_f32_16x16x32_bf16 v[86:89], v[194:197], v[218:221], v[86:89]
	v_mfma_f32_16x16x32_bf16 v[82:85], v[194:197], v[226:229], v[82:85]
	v_mfma_f32_16x16x32_bf16 v[78:81], v[202:205], v[218:221], v[78:81]
	v_mfma_f32_16x16x32_bf16 v[74:77], v[202:205], v[226:229], v[74:77]
	v_mfma_f32_16x16x32_bf16 v[70:73], v[210:213], v[218:221], v[70:73]
	v_mfma_f32_16x16x32_bf16 v[66:69], v[210:213], v[226:229], v[66:69]
	s_setprio 0
	v_readfirstlane_b32 s44, v148
	s_mov_b32 m0, s44
	v_readfirstlane_b32 s44, v149
	s_barrier
	ds_read_b128 v[182:185], v137 offset:16384
	ds_read_b128 v[186:189], v137 offset:17408
	ds_read_b128 v[190:193], v136 offset:16384
	ds_read_b128 v[194:197], v136 offset:17408
	ds_read_b128 v[198:201], v135 offset:16384
	ds_read_b128 v[202:205], v135 offset:17408
	ds_read_b128 v[206:209], v134 offset:16384
	ds_read_b128 v[210:213], v134 offset:17408
	buffer_load_dwordx4 v142, s[8:11], s43 offen lds
	s_mov_b32 m0, s44
	s_nop 0
	buffer_load_dwordx4 v144, s[8:11], s43 offen lds
	s_barrier
	s_waitcnt lgkmcnt(0)
	s_setprio 1
	s_waitcnt lgkmcnt(7)
	v_mfma_f32_16x16x32_bf16 v[62:65], v[182:185], v[166:169], v[62:65]
	v_mfma_f32_16x16x32_bf16 v[58:61], v[182:185], v[174:177], v[58:61]
	s_waitcnt lgkmcnt(5)
	v_mfma_f32_16x16x32_bf16 v[54:57], v[190:193], v[166:169], v[54:57]
	v_mfma_f32_16x16x32_bf16 v[50:53], v[190:193], v[174:177], v[50:53]
	s_waitcnt lgkmcnt(3)
	v_mfma_f32_16x16x32_bf16 v[46:49], v[198:201], v[166:169], v[46:49]
	v_mfma_f32_16x16x32_bf16 v[42:45], v[198:201], v[174:177], v[42:45]
	s_waitcnt lgkmcnt(1)
	v_mfma_f32_16x16x32_bf16 v[38:41], v[206:209], v[166:169], v[38:41]
	v_mfma_f32_16x16x32_bf16 v[34:37], v[206:209], v[174:177], v[34:37]
	v_mfma_f32_16x16x32_bf16 v[62:65], v[186:189], v[170:173], v[62:65]
	v_mfma_f32_16x16x32_bf16 v[58:61], v[186:189], v[178:181], v[58:61]
	v_mfma_f32_16x16x32_bf16 v[54:57], v[194:197], v[170:173], v[54:57]
	v_mfma_f32_16x16x32_bf16 v[50:53], v[194:197], v[178:181], v[50:53]
	v_mfma_f32_16x16x32_bf16 v[46:49], v[202:205], v[170:173], v[46:49]
	v_mfma_f32_16x16x32_bf16 v[42:45], v[202:205], v[178:181], v[42:45]
	s_waitcnt lgkmcnt(0)
	v_mfma_f32_16x16x32_bf16 v[38:41], v[210:213], v[170:173], v[38:41]
	v_mfma_f32_16x16x32_bf16 v[34:37], v[210:213], v[178:181], v[34:37]
	s_setprio 0
	s_barrier
; #define STAGE(P, BASE, LD, br, kt) do { const int _so = (int)(((br) * (LD) + (kt) * BK) * 2); \
;     _Pragma("unroll") for (int _i = 0; _i < 2; ++_i) { \
;       __builtin_amdgcn_raw_ptr_buffer_load_lds(rs##BASE, (__attribute__((address_space(3))) unsigned*)((char*)(P) + tid_ * 16 + _i * 8192), 16, (int)off##LD[_i], _so, 0, 0); } } while (0)
; #define LDA_(dst, b, h) _Pragma("unroll") for (int m = 0; m < 4; ++m) _Pragma("unroll") for (int k = 0; k < 2; ++k) \
;     dst[m][k] = *reinterpret_cast<const bf16x8*>((char*)SA(b, h) + lds_byte(wr * 64 + m * 16 + fr, k * 32 + fq * 8))
; #define LDB_(dst, b, h) _Pragma("unroll") for (int n = 0; n < 2; ++n) _Pragma("unroll") for (int k = 0; k < 2; ++k) \
;     dst[n][k] = *reinterpret_cast<const bf16x8*>((char*)SB(b, h) + lds_byte(wc * 32 + n * 16 + fr, k * 32 + fq * 8))
; #define MMA(ai, bj, At, Bx) do { __builtin_amdgcn_s_setprio(1); \
;     _Pragma("unroll") for (int m = 0; m < 4; ++m) _Pragma("unroll") for (int n = 0; n < 2; ++n) _Pragma("unroll") for (int k = 0; k < 2; ++k) \
;       acc[ai][bj][m][n] = __builtin_amdgcn_mfma_f32_16x16x32_bf16(At[m][k], Bx[n][k], acc[ai][bj][m][n], 0, 0, 0); \
;     __builtin_amdgcn_s_setprio(0); } while (0)
; #define WAIT_V(n) asm volatile("s_waitcnt vmcnt(" #n ")" ::: "memory")
; #define WAIT_L(n) asm volatile("s_waitcnt lgkmcnt(" #n ")" ::: "memory")
; #define BAR __builtin_amdgcn_s_barrier()
; #define SCHED __builtin_amdgcn_sched_barrier(0)
; template <int K, int LDA, int LDB>
; DEVI void gemm_tile(const bf16* __restrict__ A, const bf16* __restrict__ Bt, bf16* shm, acc_t& acc) {
;     ...
;     STAGE(SB(0, 1), Bt, LDB, HALF, t + 2);
;     WAIT_V(6); BAR; MMA(1, 1, At, B1); BAR;
;     LDB_(B0, 1, 0); SCHED; LDA_(At, 1, 0); STAGE(SA(0, 1), A, LDA, HALF, t + 2);
;     WAIT_L(8); BAR; WAIT_L(0); MMA(0, 0, At, B0); BAR; SCHED;
;     LDB_(B1, 1, 1); STAGE(SB(1, 0), Bt, LDB, 0, t + 3);
;     BAR; WAIT_L(0); MMA(0, 1, At, B1); BAR;
;     LDA_(At, 1, 1); STAGE(SA(1, 0), A, LDA, 0, t + 3);
	v_readfirstlane_b32 s44, v150
	s_add_i32 s43, s15, 0xffffff80
	s_mov_b32 m0, s44
	v_readfirstlane_b32 s44, v151
	buffer_load_dwordx4 v142, s[4:7], s43 offen lds
	s_mov_b32 m0, s44
	s_nop 0
	buffer_load_dwordx4 v144, s[4:7], s43 offen lds
	s_waitcnt vmcnt(6)
	s_barrier
	s_setprio 1
	v_mfma_f32_16x16x32_bf16 v[30:33], v[182:185], v[214:217], v[30:33]
	v_mfma_f32_16x16x32_bf16 v[26:29], v[182:185], v[222:225], v[26:29]
	v_mfma_f32_16x16x32_bf16 v[22:25], v[190:193], v[214:217], v[22:25]
	v_mfma_f32_16x16x32_bf16 v[18:21], v[190:193], v[222:225], v[18:21]
	v_mfma_f32_16x16x32_bf16 v[14:17], v[198:201], v[214:217], v[14:17]
	v_mfma_f32_16x16x32_bf16 v[10:13], v[198:201], v[222:225], v[10:13]
	v_mfma_f32_16x16x32_bf16 v[6:9], v[206:209], v[214:217], v[6:9]
	v_mfma_f32_16x16x32_bf16 v[2:5], v[206:209], v[222:225], v[2:5]
	v_mfma_f32_16x16x32_bf16 v[30:33], v[186:189], v[218:221], v[30:33]
	v_mfma_f32_16x16x32_bf16 v[26:29], v[186:189], v[226:229], v[26:29]
	v_mfma_f32_16x16x32_bf16 v[22:25], v[194:197], v[218:221], v[22:25]
	v_mfma_f32_16x16x32_bf16 v[18:21], v[194:197], v[226:229], v[18:21]
	v_mfma_f32_16x16x32_bf16 v[14:17], v[202:205], v[218:221], v[14:17]
	v_mfma_f32_16x16x32_bf16 v[10:13], v[202:205], v[226:229], v[10:13]
	v_mfma_f32_16x16x32_bf16 v[6:9], v[210:213], v[218:221], v[6:9]
	v_mfma_f32_16x16x32_bf16 v[2:5], v[210:213], v[226:229], v[2:5]
	s_setprio 0
	s_barrier
	ds_read_b128 v[166:169], v145
	ds_read_b128 v[170:173], v145 offset:1024
	ds_read_b128 v[174:177], v145 offset:2048
	ds_read_b128 v[178:181], v145 offset:3072
	v_readfirstlane_b32 s44, v152
	s_mov_b32 m0, s44
	v_readfirstlane_b32 s44, v153
	ds_read_b128 v[182:185], v137 offset:32768
	ds_read_b128 v[186:189], v137 offset:33792
	ds_read_b128 v[190:193], v136 offset:32768
	ds_read_b128 v[194:197], v136 offset:33792
	ds_read_b128 v[198:201], v135 offset:32768
	ds_read_b128 v[202:205], v135 offset:33792
	ds_read_b128 v[206:209], v134 offset:32768
	ds_read_b128 v[210:213], v134 offset:33792
	buffer_load_dwordx4 v142, s[8:11], s43 offen lds
	s_mov_b32 m0, s44
	s_nop 0
	buffer_load_dwordx4 v144, s[8:11], s43 offen lds
	s_waitcnt lgkmcnt(8)
	s_barrier
	s_waitcnt lgkmcnt(0)
	s_setprio 1
	s_waitcnt lgkmcnt(7)
	v_mfma_f32_16x16x32_bf16 v[126:129], v[182:185], v[166:169], v[126:129]
	v_mfma_f32_16x16x32_bf16 v[122:125], v[182:185], v[174:177], v[122:125]
	s_waitcnt lgkmcnt(5)
	v_mfma_f32_16x16x32_bf16 v[118:121], v[190:193], v[166:169], v[118:121]
	v_mfma_f32_16x16x32_bf16 v[114:117], v[190:193], v[174:177], v[114:117]
	s_waitcnt lgkmcnt(3)
	v_mfma_f32_16x16x32_bf16 v[110:113], v[198:201], v[166:169], v[110:113]
	v_mfma_f32_16x16x32_bf16 v[106:109], v[198:201], v[174:177], v[106:109]
	s_waitcnt lgkmcnt(1)
	v_mfma_f32_16x16x32_bf16 v[102:105], v[206:209], v[166:169], v[102:105]
	v_mfma_f32_16x16x32_bf16 v[98:101], v[206:209], v[174:177], v[98:101]
	v_mfma_f32_16x16x32_bf16 v[126:129], v[186:189], v[170:173], v[126:129]
	v_mfma_f32_16x16x32_bf16 v[122:125], v[186:189], v[178:181], v[122:125]
	v_mfma_f32_16x16x32_bf16 v[118:121], v[194:197], v[170:173], v[118:121]
	v_mfma_f32_16x16x32_bf16 v[114:117], v[194:197], v[178:181], v[114:117]
	v_mfma_f32_16x16x32_bf16 v[110:113], v[202:205], v[170:173], v[110:113]
	v_mfma_f32_16x16x32_bf16 v[106:109], v[202:205], v[178:181], v[106:109]
	s_waitcnt lgkmcnt(0)
	v_mfma_f32_16x16x32_bf16 v[102:105], v[210:213], v[170:173], v[102:105]
	v_mfma_f32_16x16x32_bf16 v[98:101], v[210:213], v[178:181], v[98:101]
	s_setprio 0
	s_barrier
	v_readfirstlane_b32 s44, v154
	s_add_i32 s43, s15, 0xfff80000
	s_mov_b32 m0, s44
	v_readfirstlane_b32 s44, v155
	ds_read_b128 v[214:217], v143
	ds_read_b128 v[218:221], v143 offset:1024
	ds_read_b128 v[222:225], v143 offset:2048
	ds_read_b128 v[226:229], v143 offset:3072
	buffer_load_dwordx4 v142, s[4:7], s43 offen lds
	s_mov_b32 m0, s44
	s_nop 0
	buffer_load_dwordx4 v144, s[4:7], s43 offen lds
	s_barrier
	s_waitcnt lgkmcnt(0)
	s_setprio 1
	s_waitcnt lgkmcnt(3)
	v_mfma_f32_16x16x32_bf16 v[94:97], v[182:185], v[214:217], v[94:97]
	s_waitcnt lgkmcnt(1)
	v_mfma_f32_16x16x32_bf16 v[90:93], v[182:185], v[222:225], v[90:93]
	v_mfma_f32_16x16x32_bf16 v[86:89], v[190:193], v[214:217], v[86:89]
	v_mfma_f32_16x16x32_bf16 v[82:85], v[190:193], v[222:225], v[82:85]
	v_mfma_f32_16x16x32_bf16 v[78:81], v[198:201], v[214:217], v[78:81]
	v_mfma_f32_16x16x32_bf16 v[74:77], v[198:201], v[222:225], v[74:77]
	v_mfma_f32_16x16x32_bf16 v[70:73], v[206:209], v[214:217], v[70:73]
	v_mfma_f32_16x16x32_bf16 v[66:69], v[206:209], v[222:225], v[66:69]
	v_mfma_f32_16x16x32_bf16 v[94:97], v[186:189], v[218:221], v[94:97]
	s_waitcnt lgkmcnt(0)
	v_mfma_f32_16x16x32_bf16 v[90:93], v[186:189], v[226:229], v[90:93]
	v_mfma_f32_16x16x32_bf16 v[86:89], v[194:197], v[218:221], v[86:89]
	v_mfma_f32_16x16x32_bf16 v[82:85], v[194:197], v[226:229], v[82:85]
	v_mfma_f32_16x16x32_bf16 v[78:81], v[202:205], v[218:221], v[78:81]
	v_mfma_f32_16x16x32_bf16 v[74:77], v[202:205], v[226:229], v[74:77]
	v_mfma_f32_16x16x32_bf16 v[70:73], v[210:213], v[218:221], v[70:73]
	v_mfma_f32_16x16x32_bf16 v[66:69], v[210:213], v[226:229], v[66:69]
	s_setprio 0
	v_readfirstlane_b32 s44, v156
	s_mov_b32 m0, s44
	v_readfirstlane_b32 s44, v158
	s_barrier
	ds_read_b128 v[182:185], v137 offset:49152
	ds_read_b128 v[186:189], v137 offset:50176
	ds_read_b128 v[190:193], v136 offset:49152
	ds_read_b128 v[194:197], v136 offset:50176
	ds_read_b128 v[198:201], v135 offset:49152
	ds_read_b128 v[202:205], v135 offset:50176
	ds_read_b128 v[206:209], v134 offset:49152
	ds_read_b128 v[210:213], v134 offset:50176
	buffer_load_dwordx4 v142, s[8:11], s43 offen lds
	s_mov_b32 m0, s44
	s_nop 0
	buffer_load_dwordx4 v144, s[8:11], s43 offen lds
	s_barrier
; #define STAGE(P, BASE, LD, br, kt) do { const int _so = (int)(((br) * (LD) + (kt) * BK) * 2); \
;     _Pragma("unroll") for (int _i = 0; _i < 2; ++_i) { \
;       __builtin_amdgcn_raw_ptr_buffer_load_lds(rs##BASE, (__attribute__((address_space(3))) unsigned*)((char*)(P) + tid_ * 16 + _i * 8192), 16, (int)off##LD[_i], _so, 0, 0); } } while (0)
; #define LDA_(dst, b, h) _Pragma("unroll") for (int m = 0; m < 4; ++m) _Pragma("unroll") for (int k = 0; k < 2; ++k) \
;     dst[m][k] = *reinterpret_cast<const bf16x8*>((char*)SA(b, h) + lds_byte(wr * 64 + m * 16 + fr, k * 32 + fq * 8))
; #define LDB_(dst, b, h) _Pragma("unroll") for (int n = 0; n < 2; ++n) _Pragma("unroll") for (int k = 0; k < 2; ++k) \
;     dst[n][k] = *reinterpret_cast<const bf16x8*>((char*)SB(b, h) + lds_byte(wc * 32 + n * 16 + fr, k * 32 + fq * 8))
; #define MMA(ai, bj, At, Bx) do { __builtin_amdgcn_s_setprio(1); \
;     _Pragma("unroll") for (int m = 0; m < 4; ++m) _Pragma("unroll") for (int n = 0; n < 2; ++n) _Pragma("unroll") for (int k = 0; k < 2; ++k) \
;       acc[ai][bj][m][n] = __builtin_amdgcn_mfma_f32_16x16x32_bf16(At[m][k], Bx[n][k], acc[ai][bj][m][n], 0, 0, 0); \
;     __builtin_amdgcn_s_setprio(0); } while (0)
; #define WAIT_V(n) asm volatile("s_waitcnt vmcnt(" #n ")" ::: "memory")
; #define WAIT_L(n) asm volatile("s_waitcnt lgkmcnt(" #n ")" ::: "memory")
; #define BAR __builtin_amdgcn_s_barrier()
; #define SCHED __builtin_amdgcn_sched_barrier(0)
; template <int K, int LDA, int LDB>
; DEVI void gemm_tile(const bf16* __restrict__ A, const bf16* __restrict__ Bt, bf16* shm, acc_t& acc) {
;     ...
;     BAR; WAIT_L(0); MMA(1, 0, At, B0); BAR; SCHED;
;     STAGE(SB(1, 1), Bt, LDB, HALF, t + 3);
;     WAIT_V(6); BAR; MMA(1, 1, At, B1); BAR;
;   }
;   { LDB_(B0, 0, 0); LDA_(At, 0, 0); STAGE(SA(1, 1), A, LDA, HALF, nt - 1);
;     BAR; WAIT_L(0); MMA(0, 0, At, B0); BAR;
;     LDB_(B1, 0, 1); BAR; WAIT_L(0); MMA(0, 1, At, B1); BAR;
	s_waitcnt lgkmcnt(0)
	s_setprio 1
	s_waitcnt lgkmcnt(7)
	v_mfma_f32_16x16x32_bf16 v[62:65], v[182:185], v[166:169], v[62:65]
	v_mfma_f32_16x16x32_bf16 v[58:61], v[182:185], v[174:177], v[58:61]
	s_waitcnt lgkmcnt(5)
	v_mfma_f32_16x16x32_bf16 v[54:57], v[190:193], v[166:169], v[54:57]
	v_mfma_f32_16x16x32_bf16 v[50:53], v[190:193], v[174:177], v[50:53]
	s_waitcnt lgkmcnt(3)
	v_mfma_f32_16x16x32_bf16 v[46:49], v[198:201], v[166:169], v[46:49]
	v_mfma_f32_16x16x32_bf16 v[42:45], v[198:201], v[174:177], v[42:45]
	s_waitcnt lgkmcnt(1)
	v_mfma_f32_16x16x32_bf16 v[38:41], v[206:209], v[166:169], v[38:41]
	v_mfma_f32_16x16x32_bf16 v[34:37], v[206:209], v[174:177], v[34:37]
	v_mfma_f32_16x16x32_bf16 v[62:65], v[186:189], v[170:173], v[62:65]
	v_mfma_f32_16x16x32_bf16 v[58:61], v[186:189], v[178:181], v[58:61]
	v_mfma_f32_16x16x32_bf16 v[54:57], v[194:197], v[170:173], v[54:57]
	v_mfma_f32_16x16x32_bf16 v[50:53], v[194:197], v[178:181], v[50:53]
	v_mfma_f32_16x16x32_bf16 v[46:49], v[202:205], v[170:173], v[46:49]
	v_mfma_f32_16x16x32_bf16 v[42:45], v[202:205], v[178:181], v[42:45]
	s_waitcnt lgkmcnt(0)
	v_mfma_f32_16x16x32_bf16 v[38:41], v[210:213], v[170:173], v[38:41]
	v_mfma_f32_16x16x32_bf16 v[34:37], v[210:213], v[178:181], v[34:37]
	s_setprio 0
	s_barrier
	v_readfirstlane_b32 s43, v160
	s_mov_b32 m0, s43
	v_readfirstlane_b32 s43, v161
	buffer_load_dwordx4 v142, s[4:7], s15 offen lds
	s_mov_b32 m0, s43
	s_nop 0
	buffer_load_dwordx4 v144, s[4:7], s15 offen lds
	s_waitcnt vmcnt(6)
	s_barrier
	s_setprio 1
	v_mfma_f32_16x16x32_bf16 v[30:33], v[182:185], v[214:217], v[30:33]
	v_mfma_f32_16x16x32_bf16 v[26:29], v[182:185], v[222:225], v[26:29]
	v_mfma_f32_16x16x32_bf16 v[22:25], v[190:193], v[214:217], v[22:25]
	v_mfma_f32_16x16x32_bf16 v[18:21], v[190:193], v[222:225], v[18:21]
	v_mfma_f32_16x16x32_bf16 v[14:17], v[198:201], v[214:217], v[14:17]
	v_mfma_f32_16x16x32_bf16 v[10:13], v[198:201], v[222:225], v[10:13]
	v_mfma_f32_16x16x32_bf16 v[6:9], v[206:209], v[214:217], v[6:9]
	v_mfma_f32_16x16x32_bf16 v[2:5], v[206:209], v[222:225], v[2:5]
	v_mfma_f32_16x16x32_bf16 v[30:33], v[186:189], v[218:221], v[30:33]
	v_mfma_f32_16x16x32_bf16 v[26:29], v[186:189], v[226:229], v[26:29]
	v_mfma_f32_16x16x32_bf16 v[22:25], v[194:197], v[218:221], v[22:25]
	v_mfma_f32_16x16x32_bf16 v[18:21], v[194:197], v[226:229], v[18:21]
	v_mfma_f32_16x16x32_bf16 v[14:17], v[202:205], v[218:221], v[14:17]
	v_mfma_f32_16x16x32_bf16 v[10:13], v[202:205], v[226:229], v[10:13]
	v_mfma_f32_16x16x32_bf16 v[6:9], v[210:213], v[218:221], v[6:9]
	v_mfma_f32_16x16x32_bf16 v[2:5], v[210:213], v[226:229], v[2:5]
	s_setprio 0
	s_add_i32 s13, s13, 2
	s_addk_i32 s15, 0x100
	s_cmp_lt_u32 s13, 28
	s_cbranch_scc1 .Lrot_36170
	s_barrier
	v_readfirstlane_b32 s4, v159
	s_mov_b32 s10, s6
	s_mov_b32 s11, s7
	s_mov_b32 m0, s4
	v_readfirstlane_b32 s4, v164
	ds_read_b128 v[146:149], v165
	ds_read_b128 v[150:153], v165 offset:1024
	ds_read_b128 v[166:169], v165 offset:2048
	ds_read_b128 v[170:173], v165 offset:3072
	ds_read_b128 v[174:177], v137
	ds_read_b128 v[178:181], v137 offset:1024
	ds_read_b128 v[182:185], v136
	ds_read_b128 v[186:189], v136 offset:1024
	ds_read_b128 v[190:193], v135
	ds_read_b128 v[194:197], v135 offset:1024
	ds_read_b128 v[198:201], v134
	ds_read_b128 v[202:205], v134 offset:1024
	buffer_load_dwordx4 v142, s[8:11], s39 offen lds
	s_mov_b32 m0, s4
	s_nop 0
	buffer_load_dwordx4 v144, s[8:11], s39 offen lds
	s_barrier
	s_waitcnt lgkmcnt(0)
	s_setprio 1
	s_waitcnt lgkmcnt(7)
	v_mfma_f32_16x16x32_bf16 v[126:129], v[174:177], v[146:149], v[126:129]
	s_waitcnt lgkmcnt(5)
	v_mfma_f32_16x16x32_bf16 v[118:121], v[182:185], v[146:149], v[118:121]
	s_waitcnt lgkmcnt(3)
	v_mfma_f32_16x16x32_bf16 v[110:113], v[190:193], v[146:149], v[110:113]
	s_waitcnt lgkmcnt(1)
	v_mfma_f32_16x16x32_bf16 v[102:105], v[198:201], v[146:149], v[102:105]
	v_mfma_f32_16x16x32_bf16 v[126:129], v[178:181], v[150:153], v[126:129]
	v_mfma_f32_16x16x32_bf16 v[122:125], v[174:177], v[166:169], v[122:125]
	v_mfma_f32_16x16x32_bf16 v[118:121], v[186:189], v[150:153], v[118:121]
	v_mfma_f32_16x16x32_bf16 v[114:117], v[182:185], v[166:169], v[114:117]
	v_mfma_f32_16x16x32_bf16 v[110:113], v[194:197], v[150:153], v[110:113]
	v_mfma_f32_16x16x32_bf16 v[106:109], v[190:193], v[166:169], v[106:109]
	s_waitcnt lgkmcnt(0)
	v_mfma_f32_16x16x32_bf16 v[102:105], v[202:205], v[150:153], v[102:105]
	v_mfma_f32_16x16x32_bf16 v[98:101], v[198:201], v[166:169], v[98:101]
	v_mfma_f32_16x16x32_bf16 v[158:161], v[178:181], v[170:173], v[122:125]
	v_mfma_f32_16x16x32_bf16 v[206:209], v[186:189], v[170:173], v[114:117]
	v_mfma_f32_16x16x32_bf16 v[210:213], v[194:197], v[170:173], v[106:109]
	v_mfma_f32_16x16x32_bf16 v[214:217], v[202:205], v[170:173], v[98:101]
	s_setprio 0
	s_barrier
	s_nop 1
	ds_read_b128 v[98:101], v157
	ds_read_b128 v[106:109], v157 offset:1024
	ds_read_b128 v[114:117], v157 offset:2048
	ds_read_b128 v[122:125], v157 offset:3072
	s_barrier
	s_waitcnt lgkmcnt(0)
	s_setprio 1
	s_waitcnt lgkmcnt(3)
	v_mfma_f32_16x16x32_bf16 v[94:97], v[174:177], v[98:101], v[94:97]
	v_mfma_f32_16x16x32_bf16 v[86:89], v[182:185], v[98:101], v[86:89]
	v_mfma_f32_16x16x32_bf16 v[78:81], v[190:193], v[98:101], v[78:81]
	v_mfma_f32_16x16x32_bf16 v[70:73], v[198:201], v[98:101], v[70:73]
	s_waitcnt lgkmcnt(2)
	v_mfma_f32_16x16x32_bf16 v[94:97], v[178:181], v[106:109], v[94:97]
	s_waitcnt lgkmcnt(1)
	v_mfma_f32_16x16x32_bf16 v[90:93], v[174:177], v[114:117], v[90:93]
	v_mfma_f32_16x16x32_bf16 v[86:89], v[186:189], v[106:109], v[86:89]
	v_mfma_f32_16x16x32_bf16 v[82:85], v[182:185], v[114:117], v[82:85]
	v_mfma_f32_16x16x32_bf16 v[78:81], v[194:197], v[106:109], v[78:81]
	v_mfma_f32_16x16x32_bf16 v[74:77], v[190:193], v[114:117], v[74:77]
	v_mfma_f32_16x16x32_bf16 v[70:73], v[202:205], v[106:109], v[70:73]
	v_mfma_f32_16x16x32_bf16 v[66:69], v[198:201], v[114:117], v[66:69]
	s_waitcnt lgkmcnt(0)
	v_mfma_f32_16x16x32_bf16 v[154:157], v[178:181], v[122:125], v[90:93]
	v_mfma_f32_16x16x32_bf16 v[174:177], v[186:189], v[122:125], v[82:85]
	v_mfma_f32_16x16x32_bf16 v[178:181], v[194:197], v[122:125], v[74:77]
	v_mfma_f32_16x16x32_bf16 v[182:185], v[202:205], v[122:125], v[66:69]
	s_setprio 0
	s_barrier
; #define LDA_(dst, b, h) _Pragma("unroll") for (int m = 0; m < 4; ++m) _Pragma("unroll") for (int k = 0; k < 2; ++k) \
;     dst[m][k] = *reinterpret_cast<const bf16x8*>((char*)SA(b, h) + lds_byte(wr * 64 + m * 16 + fr, k * 32 + fq * 8))
; #define LDB_(dst, b, h) _Pragma("unroll") for (int n = 0; n < 2; ++n) _Pragma("unroll") for (int k = 0; k < 2; ++k) \
;     dst[n][k] = *reinterpret_cast<const bf16x8*>((char*)SB(b, h) + lds_byte(wc * 32 + n * 16 + fr, k * 32 + fq * 8))
; #define MMA(ai, bj, At, Bx) do { __builtin_amdgcn_s_setprio(1); \
;     _Pragma("unroll") for (int m = 0; m < 4; ++m) _Pragma("unroll") for (int n = 0; n < 2; ++n) _Pragma("unroll") for (int k = 0; k < 2; ++k) \
;       acc[ai][bj][m][n] = __builtin_amdgcn_mfma_f32_16x16x32_bf16(At[m][k], Bx[n][k], acc[ai][bj][m][n], 0, 0, 0); \
;     __builtin_amdgcn_s_setprio(0); } while (0)
; #define WAIT_V(n) asm volatile("s_waitcnt vmcnt(" #n ")" ::: "memory")
; #define WAIT_L(n) asm volatile("s_waitcnt lgkmcnt(" #n ")" ::: "memory")
; #define BAR __builtin_amdgcn_s_barrier()
; template <int K, int LDA, int LDB>
; DEVI void gemm_tile(const bf16* __restrict__ A, const bf16* __restrict__ Bt, bf16* shm, acc_t& acc) {
;     ...
;     LDA_(At, 0, 1); WAIT_V(4); BAR; WAIT_L(0); MMA(1, 0, At, B0); MMA(1, 1, At, B1); BAR; }
;   { LDB_(B0, 1, 0); LDA_(At, 1, 0); WAIT_V(2); BAR; WAIT_L(0); MMA(0, 0, At, B0); BAR;
	s_nop 0
	ds_read_b128 v[66:69], v137 offset:16384
	ds_read_b128 v[74:77], v137 offset:17408
	ds_read_b128 v[82:85], v136 offset:16384
	ds_read_b128 v[90:93], v136 offset:17408
	ds_read_b128 v[186:189], v135 offset:16384
	ds_read_b128 v[190:193], v135 offset:17408
	ds_read_b128 v[194:197], v134 offset:16384
	ds_read_b128 v[198:201], v134 offset:17408
	s_waitcnt vmcnt(4)
	s_barrier
	s_waitcnt lgkmcnt(0)
	s_setprio 1
	s_waitcnt lgkmcnt(7)
	v_mfma_f32_16x16x32_bf16 v[62:65], v[66:69], v[146:149], v[62:65]
	s_waitcnt lgkmcnt(5)
	v_mfma_f32_16x16x32_bf16 v[54:57], v[82:85], v[146:149], v[54:57]
	s_waitcnt lgkmcnt(3)
	v_mfma_f32_16x16x32_bf16 v[46:49], v[186:189], v[146:149], v[46:49]
	s_waitcnt lgkmcnt(1)
	v_mfma_f32_16x16x32_bf16 v[38:41], v[194:197], v[146:149], v[38:41]
	v_mfma_f32_16x16x32_bf16 v[62:65], v[74:77], v[150:153], v[62:65]
	v_mfma_f32_16x16x32_bf16 v[58:61], v[66:69], v[166:169], v[58:61]
	v_mfma_f32_16x16x32_bf16 v[54:57], v[90:93], v[150:153], v[54:57]
	v_mfma_f32_16x16x32_bf16 v[50:53], v[82:85], v[166:169], v[50:53]
	v_mfma_f32_16x16x32_bf16 v[46:49], v[190:193], v[150:153], v[46:49]
	v_mfma_f32_16x16x32_bf16 v[42:45], v[186:189], v[166:169], v[42:45]
	s_waitcnt lgkmcnt(0)
	v_mfma_f32_16x16x32_bf16 v[38:41], v[198:201], v[150:153], v[38:41]
	v_mfma_f32_16x16x32_bf16 v[34:37], v[194:197], v[166:169], v[34:37]
	v_mfma_f32_16x16x32_bf16 v[202:205], v[74:77], v[170:173], v[58:61]
	v_mfma_f32_16x16x32_bf16 v[218:221], v[90:93], v[170:173], v[50:53]
	v_mfma_f32_16x16x32_bf16 v[222:225], v[190:193], v[170:173], v[42:45]
	v_mfma_f32_16x16x32_bf16 v[146:149], v[198:201], v[170:173], v[34:37]
	s_setprio 0
	s_setprio 1
	v_mfma_f32_16x16x32_bf16 v[30:33], v[66:69], v[98:101], v[30:33]
	v_mfma_f32_16x16x32_bf16 v[22:25], v[82:85], v[98:101], v[22:25]
	v_mfma_f32_16x16x32_bf16 v[14:17], v[186:189], v[98:101], v[14:17]
	v_mfma_f32_16x16x32_bf16 v[6:9], v[194:197], v[98:101], v[6:9]
	v_mfma_f32_16x16x32_bf16 v[30:33], v[74:77], v[106:109], v[30:33]
	v_mfma_f32_16x16x32_bf16 v[26:29], v[66:69], v[114:117], v[26:29]
	v_mfma_f32_16x16x32_bf16 v[22:25], v[90:93], v[106:109], v[22:25]
	v_mfma_f32_16x16x32_bf16 v[18:21], v[82:85], v[114:117], v[18:21]
	v_mfma_f32_16x16x32_bf16 v[14:17], v[190:193], v[106:109], v[14:17]
	v_mfma_f32_16x16x32_bf16 v[10:13], v[186:189], v[114:117], v[10:13]
	v_mfma_f32_16x16x32_bf16 v[6:9], v[198:201], v[106:109], v[6:9]
	v_mfma_f32_16x16x32_bf16 v[2:5], v[194:197], v[114:117], v[2:5]
	v_mfma_f32_16x16x32_bf16 v[150:153], v[74:77], v[122:125], v[26:29]
	v_mfma_f32_16x16x32_bf16 v[164:167], v[90:93], v[122:125], v[18:21]
	v_mfma_f32_16x16x32_bf16 v[168:171], v[190:193], v[122:125], v[10:13]
	v_mfma_f32_16x16x32_bf16 v[186:189], v[198:201], v[122:125], v[2:5]
	s_setprio 0
	s_barrier
	ds_read_b128 v[190:193], v145
	ds_read_b128 v[194:197], v145 offset:1024
	ds_read_b128 v[198:201], v145 offset:2048
	ds_read_b128 v[226:229], v145 offset:3072
	ds_read_b128 v[2:5], v137 offset:32768
	ds_read_b128 v[10:13], v137 offset:33792
	ds_read_b128 v[18:21], v136 offset:32768
	ds_read_b128 v[26:29], v136 offset:33792
	ds_read_b128 v[230:233], v135 offset:32768
	ds_read_b128 v[234:237], v135 offset:33792
	ds_read_b128 v[238:241], v134 offset:32768
	ds_read_b128 v[242:245], v134 offset:33792
	s_waitcnt vmcnt(2)
	s_barrier
	s_waitcnt lgkmcnt(0)
	s_setprio 1
	s_waitcnt lgkmcnt(7)
	v_mfma_f32_16x16x32_bf16 v[34:37], v[2:5], v[190:193], v[126:129]
	s_waitcnt lgkmcnt(6)
	v_mfma_f32_16x16x32_bf16 v[122:125], v[10:13], v[194:197], v[34:37]
	v_mfma_f32_16x16x32_bf16 v[34:37], v[2:5], v[198:201], v[158:161]
	v_mfma_f32_16x16x32_bf16 v[114:117], v[10:13], v[226:229], v[34:37]
	s_waitcnt lgkmcnt(5)
	v_mfma_f32_16x16x32_bf16 v[34:37], v[18:21], v[190:193], v[118:121]
	s_waitcnt lgkmcnt(4)
	v_mfma_f32_16x16x32_bf16 v[106:109], v[26:29], v[194:197], v[34:37]
	v_mfma_f32_16x16x32_bf16 v[34:37], v[18:21], v[198:201], v[206:209]
	v_mfma_f32_16x16x32_bf16 v[98:101], v[26:29], v[226:229], v[34:37]
	s_waitcnt lgkmcnt(3)
	v_mfma_f32_16x16x32_bf16 v[34:37], v[230:233], v[190:193], v[110:113]
	s_waitcnt lgkmcnt(2)
	v_mfma_f32_16x16x32_bf16 v[90:93], v[234:237], v[194:197], v[34:37]
	v_mfma_f32_16x16x32_bf16 v[34:37], v[230:233], v[198:201], v[210:213]
	v_mfma_f32_16x16x32_bf16 v[82:85], v[234:237], v[226:229], v[34:37]
	s_waitcnt lgkmcnt(1)
	v_mfma_f32_16x16x32_bf16 v[34:37], v[238:241], v[190:193], v[102:105]
	s_waitcnt lgkmcnt(0)
	v_mfma_f32_16x16x32_bf16 v[74:77], v[242:245], v[194:197], v[34:37]
	v_mfma_f32_16x16x32_bf16 v[34:37], v[238:241], v[198:201], v[214:217]
	v_mfma_f32_16x16x32_bf16 v[66:69], v[242:245], v[226:229], v[34:37]
	s_setprio 0
	s_barrier
; #define LDA_(dst, b, h) _Pragma("unroll") for (int m = 0; m < 4; ++m) _Pragma("unroll") for (int k = 0; k < 2; ++k) \
;     dst[m][k] = *reinterpret_cast<const bf16x8*>((char*)SA(b, h) + lds_byte(wr * 64 + m * 16 + fr, k * 32 + fq * 8))
; #define LDB_(dst, b, h) _Pragma("unroll") for (int n = 0; n < 2; ++n) _Pragma("unroll") for (int k = 0; k < 2; ++k) \
;     dst[n][k] = *reinterpret_cast<const bf16x8*>((char*)SB(b, h) + lds_byte(wc * 32 + n * 16 + fr, k * 32 + fq * 8))
; #define MMA(ai, bj, At, Bx) do { __builtin_amdgcn_s_setprio(1); \
;     _Pragma("unroll") for (int m = 0; m < 4; ++m) _Pragma("unroll") for (int n = 0; n < 2; ++n) _Pragma("unroll") for (int k = 0; k < 2; ++k) \
;       acc[ai][bj][m][n] = __builtin_amdgcn_mfma_f32_16x16x32_bf16(At[m][k], Bx[n][k], acc[ai][bj][m][n], 0, 0, 0); \
;     __builtin_amdgcn_s_setprio(0); } while (0)
; #define WAIT_V(n) asm volatile("s_waitcnt vmcnt(" #n ")" ::: "memory")
; #define WAIT_L(n) asm volatile("s_waitcnt lgkmcnt(" #n ")" ::: "memory")
; #define BAR __builtin_amdgcn_s_barrier()
; template <int K, int LDA, int LDB>
; DEVI void gemm_tile(const bf16* __restrict__ A, const bf16* __restrict__ Bt, bf16* shm, acc_t& acc) {
;     ...
;   { LDB_(B0, 1, 0); LDA_(At, 1, 0); WAIT_V(2); BAR; WAIT_L(0); MMA(0, 0, At, B0); BAR;
;     LDB_(B1, 1, 1); WAIT_V(0); BAR; WAIT_L(0); MMA(0, 1, At, B1); BAR;
;     LDA_(At, 1, 1); BAR; WAIT_L(0); MMA(1, 0, At, B0); MMA(1, 1, At, B1); BAR; }
;   if (wr == 0) BAR;
	ds_read_b128 v[158:161], v143
	ds_read_b128 v[206:209], v143 offset:1024
	ds_read_b128 v[210:213], v143 offset:2048
	ds_read_b128 v[142:145], v143 offset:3072
	s_waitcnt vmcnt(0)
	s_barrier
	s_waitcnt lgkmcnt(0)
	s_setprio 1
	s_waitcnt lgkmcnt(3)
	v_mfma_f32_16x16x32_bf16 v[34:37], v[2:5], v[158:161], v[94:97]
	s_waitcnt lgkmcnt(1)
	v_mfma_f32_16x16x32_bf16 v[2:5], v[2:5], v[210:213], v[154:157]
	s_waitcnt lgkmcnt(0)
	v_mfma_f32_16x16x32_bf16 v[50:53], v[10:13], v[142:145], v[2:5]
	v_mfma_f32_16x16x32_bf16 v[2:5], v[18:21], v[158:161], v[86:89]
	v_mfma_f32_16x16x32_bf16 v[42:45], v[26:29], v[206:209], v[2:5]
	v_mfma_f32_16x16x32_bf16 v[2:5], v[18:21], v[210:213], v[174:177]
	v_mfma_f32_16x16x32_bf16 v[58:61], v[10:13], v[206:209], v[34:37]
	v_mfma_f32_16x16x32_bf16 v[34:37], v[26:29], v[142:145], v[2:5]
	v_mfma_f32_16x16x32_bf16 v[2:5], v[230:233], v[158:161], v[78:81]
	v_mfma_f32_16x16x32_bf16 v[26:29], v[234:237], v[206:209], v[2:5]
	v_mfma_f32_16x16x32_bf16 v[2:5], v[230:233], v[210:213], v[178:181]
	v_mfma_f32_16x16x32_bf16 v[18:21], v[234:237], v[142:145], v[2:5]
	v_mfma_f32_16x16x32_bf16 v[2:5], v[238:241], v[158:161], v[70:73]
	v_mfma_f32_16x16x32_bf16 v[10:13], v[242:245], v[206:209], v[2:5]
	v_mfma_f32_16x16x32_bf16 v[2:5], v[238:241], v[210:213], v[182:185]
	v_mfma_f32_16x16x32_bf16 v[2:5], v[242:245], v[142:145], v[2:5]
	s_setprio 0
	s_barrier
	ds_read_b128 v[154:157], v137 offset:49152
	ds_read_b128 v[172:175], v137 offset:50176
	ds_read_b128 v[176:179], v136 offset:49152
	ds_read_b128 v[180:183], v136 offset:50176
	ds_read_b128 v[214:217], v135 offset:49152
	ds_read_b128 v[230:233], v135 offset:50176
	ds_read_b128 v[234:237], v134 offset:49152
	ds_read_b128 v[134:137], v134 offset:50176
	s_barrier
	s_waitcnt lgkmcnt(0)
	s_setprio 1
	s_waitcnt lgkmcnt(7)
	v_mfma_f32_16x16x32_bf16 v[62:65], v[154:157], v[190:193], v[62:65]
	s_waitcnt lgkmcnt(5)
	v_mfma_f32_16x16x32_bf16 v[54:57], v[176:179], v[190:193], v[54:57]
	s_waitcnt lgkmcnt(3)
	v_mfma_f32_16x16x32_bf16 v[46:49], v[214:217], v[190:193], v[46:49]
	s_waitcnt lgkmcnt(1)
	v_mfma_f32_16x16x32_bf16 v[38:41], v[234:237], v[190:193], v[38:41]
	v_mfma_f32_16x16x32_bf16 v[126:129], v[172:175], v[194:197], v[62:65]
	v_mfma_f32_16x16x32_bf16 v[62:65], v[154:157], v[198:201], v[202:205]
	v_mfma_f32_16x16x32_bf16 v[110:113], v[180:183], v[194:197], v[54:57]
	v_mfma_f32_16x16x32_bf16 v[54:57], v[176:179], v[198:201], v[218:221]
	v_mfma_f32_16x16x32_bf16 v[94:97], v[230:233], v[194:197], v[46:49]
	v_mfma_f32_16x16x32_bf16 v[46:49], v[214:217], v[198:201], v[222:225]
	s_waitcnt lgkmcnt(0)
	v_mfma_f32_16x16x32_bf16 v[78:81], v[134:137], v[194:197], v[38:41]
	v_mfma_f32_16x16x32_bf16 v[38:41], v[234:237], v[198:201], v[146:149]
	v_mfma_f32_16x16x32_bf16 v[118:121], v[172:175], v[226:229], v[62:65]
	v_mfma_f32_16x16x32_bf16 v[102:105], v[180:183], v[226:229], v[54:57]
	v_mfma_f32_16x16x32_bf16 v[86:89], v[230:233], v[226:229], v[46:49]
	v_mfma_f32_16x16x32_bf16 v[70:73], v[134:137], v[226:229], v[38:41]
	s_setprio 0
	s_setprio 1
	v_mfma_f32_16x16x32_bf16 v[30:33], v[154:157], v[158:161], v[30:33]
	v_mfma_f32_16x16x32_bf16 v[62:65], v[172:175], v[206:209], v[30:33]
	v_mfma_f32_16x16x32_bf16 v[30:33], v[154:157], v[210:213], v[150:153]
	v_mfma_f32_16x16x32_bf16 v[22:25], v[176:179], v[158:161], v[22:25]
	v_mfma_f32_16x16x32_bf16 v[14:17], v[214:217], v[158:161], v[14:17]
	v_mfma_f32_16x16x32_bf16 v[54:57], v[172:175], v[142:145], v[30:33]
	v_mfma_f32_16x16x32_bf16 v[46:49], v[180:183], v[206:209], v[22:25]
	v_mfma_f32_16x16x32_bf16 v[22:25], v[176:179], v[210:213], v[164:167]
	v_mfma_f32_16x16x32_bf16 v[30:33], v[230:233], v[206:209], v[14:17]
	v_mfma_f32_16x16x32_bf16 v[14:17], v[214:217], v[210:213], v[168:171]
	v_mfma_f32_16x16x32_bf16 v[6:9], v[234:237], v[158:161], v[6:9]
	v_mfma_f32_16x16x32_bf16 v[38:41], v[180:183], v[142:145], v[22:25]
	v_mfma_f32_16x16x32_bf16 v[22:25], v[230:233], v[142:145], v[14:17]
	v_mfma_f32_16x16x32_bf16 v[14:17], v[134:137], v[206:209], v[6:9]
	v_mfma_f32_16x16x32_bf16 v[6:9], v[234:237], v[210:213], v[186:189]
	v_mfma_f32_16x16x32_bf16 v[6:9], v[134:137], v[142:145], v[6:9]
	s_setprio 0
	v_cmp_gt_u32_e32 vcc, s18, v132
	s_barrier
	s_and_saveexec_b64 s[4:5], vcc
	s_cbranch_execz .LBB0_1664
	s_barrier

; #define STAGE(P, BASE, LD, br, kt) do { const int _so = (int)(((br) * (LD) + (kt) * BK) * 2); \
;     _Pragma("unroll") for (int _i = 0; _i < 2; ++_i) { \
;       __builtin_amdgcn_raw_ptr_buffer_load_lds(rs##BASE, (__attribute__((address_space(3))) unsigned*)((char*)(P) + tid_ * 16 + _i * 8192), 16, (int)off##LD[_i], _so, 0, 0); } } while (0)
; #define LDA_(dst, b, h) _Pragma("unroll") for (int m = 0; m < 4; ++m) _Pragma("unroll") for (int k = 0; k < 2; ++k) \
;     dst[m][k] = *reinterpret_cast<const bf16x8*>((char*)SA(b, h) + lds_byte(wr * 64 + m * 16 + fr, k * 32 + fq * 8))
; #define LDB_(dst, b, h) _Pragma("unroll") for (int n = 0; n < 2; ++n) _Pragma("unroll") for (int k = 0; k < 2; ++k) \
;     dst[n][k] = *reinterpret_cast<const bf16x8*>((char*)SB(b, h) + lds_byte(wc * 32 + n * 16 + fr, k * 32 + fq * 8))
; #define MMA(ai, bj, At, Bx) do { __builtin_amdgcn_s_setprio(1); \
;     _Pragma("unroll") for (int m = 0; m < 4; ++m) _Pragma("unroll") for (int n = 0; n < 2; ++n) _Pragma("unroll") for (int k = 0; k < 2; ++k) \
;       acc[ai][bj][m][n] = __builtin_amdgcn_mfma_f32_16x16x32_bf16(At[m][k], Bx[n][k], acc[ai][bj][m][n], 0, 0, 0); \
;     __builtin_amdgcn_s_setprio(0); } while (0)
; #define WAIT_L(n) asm volatile("s_waitcnt lgkmcnt(" #n ")" ::: "memory")
; #define BAR __builtin_amdgcn_s_barrier()
; #define SCHED __builtin_amdgcn_sched_barrier(0)
; template <int K, int LDA, int LDB>
; DEVI void gemm_tile(const bf16* __restrict__ A, const bf16* __restrict__ Bt, bf16* shm, acc_t& acc) {
;     ...
;     LDB_(B0, 0, 0); SCHED; LDA_(At, 0, 0); STAGE(SA(1, 1), A, LDA, HALF, t + 1);
;     WAIT_L(8); BAR; WAIT_L(0); MMA(0, 0, At, B0); BAR; SCHED;
;     LDB_(B1, 0, 1); STAGE(SB(0, 0), Bt, LDB, 0, t + 2);
;     BAR; WAIT_L(0); MMA(0, 1, At, B1); BAR;
;     LDA_(At, 0, 1); STAGE(SA(0, 0), A, LDA, 0, t + 2);
;     BAR; WAIT_L(0); MMA(1, 0, At, B0); BAR; SCHED;
.LBB0_1701:
	ds_read_b128 v[164:167], v161
	ds_read_b128 v[168:171], v161 offset:1024
	ds_read_b128 v[172:175], v161 offset:2048
	ds_read_b128 v[176:179], v161 offset:3072
	v_readfirstlane_b32 s61, v157
	s_add_i32 s60, s7, 0xffffff00
	s_mov_b32 m0, s61
	v_readfirstlane_b32 s61, v160
	ds_read_b128 v[180:183], v139
	ds_read_b128 v[184:187], v139 offset:1024
	ds_read_b128 v[188:191], v138
	ds_read_b128 v[192:195], v138 offset:1024
	ds_read_b128 v[196:199], v135
	ds_read_b128 v[200:203], v135 offset:1024
	ds_read_b128 v[204:207], v134
	ds_read_b128 v[208:211], v134 offset:1024
	buffer_load_dwordx4 v140, s[8:11], s60 offen lds
	s_mov_b32 m0, s61
	s_nop 0
	buffer_load_dwordx4 v142, s[8:11], s60 offen lds
	s_waitcnt lgkmcnt(8)
	s_barrier
	s_waitcnt lgkmcnt(0)
	s_setprio 1
	s_waitcnt lgkmcnt(7)
	v_mfma_f32_16x16x32_bf16 v[126:129], v[180:183], v[164:167], v[126:129]
	v_mfma_f32_16x16x32_bf16 v[122:125], v[180:183], v[172:175], v[122:125]
	s_waitcnt lgkmcnt(5)
	v_mfma_f32_16x16x32_bf16 v[118:121], v[188:191], v[164:167], v[118:121]
	v_mfma_f32_16x16x32_bf16 v[114:117], v[188:191], v[172:175], v[114:117]
	s_waitcnt lgkmcnt(3)
	v_mfma_f32_16x16x32_bf16 v[110:113], v[196:199], v[164:167], v[110:113]
	v_mfma_f32_16x16x32_bf16 v[106:109], v[196:199], v[172:175], v[106:109]
	s_waitcnt lgkmcnt(1)
	v_mfma_f32_16x16x32_bf16 v[102:105], v[204:207], v[164:167], v[102:105]
	v_mfma_f32_16x16x32_bf16 v[98:101], v[204:207], v[172:175], v[98:101]
	v_mfma_f32_16x16x32_bf16 v[126:129], v[184:187], v[168:171], v[126:129]
	v_mfma_f32_16x16x32_bf16 v[122:125], v[184:187], v[176:179], v[122:125]
	v_mfma_f32_16x16x32_bf16 v[118:121], v[192:195], v[168:171], v[118:121]
	v_mfma_f32_16x16x32_bf16 v[114:117], v[192:195], v[176:179], v[114:117]
	v_mfma_f32_16x16x32_bf16 v[110:113], v[200:203], v[168:171], v[110:113]
	v_mfma_f32_16x16x32_bf16 v[106:109], v[200:203], v[176:179], v[106:109]
	s_waitcnt lgkmcnt(0)
	v_mfma_f32_16x16x32_bf16 v[102:105], v[208:211], v[168:171], v[102:105]
	v_mfma_f32_16x16x32_bf16 v[98:101], v[208:211], v[176:179], v[98:101]
	s_setprio 0
	s_barrier
	v_readfirstlane_b32 s61, v144
	s_add_i32 s60, s7, 0xffe9ff80
	s_mov_b32 m0, s61
	v_readfirstlane_b32 s61, v145
	ds_read_b128 v[212:215], v155
	ds_read_b128 v[216:219], v155 offset:1024
	ds_read_b128 v[220:223], v155 offset:2048
	ds_read_b128 v[224:227], v155 offset:3072
	buffer_load_dwordx4 v140, s[0:3], s60 offen lds
	s_mov_b32 m0, s61
	s_nop 0
	buffer_load_dwordx4 v142, s[0:3], s60 offen lds
	s_barrier
	s_waitcnt lgkmcnt(0)
	s_setprio 1
	s_waitcnt lgkmcnt(3)
	v_mfma_f32_16x16x32_bf16 v[94:97], v[180:183], v[212:215], v[94:97]
	s_waitcnt lgkmcnt(1)
	v_mfma_f32_16x16x32_bf16 v[90:93], v[180:183], v[220:223], v[90:93]
	v_mfma_f32_16x16x32_bf16 v[86:89], v[188:191], v[212:215], v[86:89]
	v_mfma_f32_16x16x32_bf16 v[82:85], v[188:191], v[220:223], v[82:85]
	v_mfma_f32_16x16x32_bf16 v[78:81], v[196:199], v[212:215], v[78:81]
	v_mfma_f32_16x16x32_bf16 v[74:77], v[196:199], v[220:223], v[74:77]
	v_mfma_f32_16x16x32_bf16 v[70:73], v[204:207], v[212:215], v[70:73]
	v_mfma_f32_16x16x32_bf16 v[66:69], v[204:207], v[220:223], v[66:69]
	v_mfma_f32_16x16x32_bf16 v[94:97], v[184:187], v[216:219], v[94:97]
	s_waitcnt lgkmcnt(0)
	v_mfma_f32_16x16x32_bf16 v[90:93], v[184:187], v[224:227], v[90:93]
	v_mfma_f32_16x16x32_bf16 v[86:89], v[192:195], v[216:219], v[86:89]
	v_mfma_f32_16x16x32_bf16 v[82:85], v[192:195], v[224:227], v[82:85]
	v_mfma_f32_16x16x32_bf16 v[78:81], v[200:203], v[216:219], v[78:81]
	v_mfma_f32_16x16x32_bf16 v[74:77], v[200:203], v[224:227], v[74:77]
	v_mfma_f32_16x16x32_bf16 v[70:73], v[208:211], v[216:219], v[70:73]
	v_mfma_f32_16x16x32_bf16 v[66:69], v[208:211], v[224:227], v[66:69]
	s_setprio 0
	v_readfirstlane_b32 s61, v146
	s_mov_b32 m0, s61
	v_readfirstlane_b32 s61, v147
	s_barrier
	ds_read_b128 v[180:183], v139 offset:16384
	ds_read_b128 v[184:187], v139 offset:17408
	ds_read_b128 v[188:191], v138 offset:16384
	ds_read_b128 v[192:195], v138 offset:17408
	ds_read_b128 v[196:199], v135 offset:16384
	ds_read_b128 v[200:203], v135 offset:17408
	ds_read_b128 v[204:207], v134 offset:16384
	ds_read_b128 v[208:211], v134 offset:17408
	buffer_load_dwordx4 v140, s[8:11], s60 offen lds
	s_mov_b32 m0, s61
	s_nop 0
	buffer_load_dwordx4 v142, s[8:11], s60 offen lds
	s_barrier
	s_waitcnt lgkmcnt(0)
	s_setprio 1
	s_waitcnt lgkmcnt(7)
	v_mfma_f32_16x16x32_bf16 v[62:65], v[180:183], v[164:167], v[62:65]
	v_mfma_f32_16x16x32_bf16 v[58:61], v[180:183], v[172:175], v[58:61]
	s_waitcnt lgkmcnt(5)
	v_mfma_f32_16x16x32_bf16 v[54:57], v[188:191], v[164:167], v[54:57]
	v_mfma_f32_16x16x32_bf16 v[50:53], v[188:191], v[172:175], v[50:53]
	s_waitcnt lgkmcnt(3)
	v_mfma_f32_16x16x32_bf16 v[46:49], v[196:199], v[164:167], v[46:49]
	v_mfma_f32_16x16x32_bf16 v[42:45], v[196:199], v[172:175], v[42:45]
	s_waitcnt lgkmcnt(1)
	v_mfma_f32_16x16x32_bf16 v[38:41], v[204:207], v[164:167], v[38:41]
	v_mfma_f32_16x16x32_bf16 v[34:37], v[204:207], v[172:175], v[34:37]
	v_mfma_f32_16x16x32_bf16 v[62:65], v[184:187], v[168:171], v[62:65]
	v_mfma_f32_16x16x32_bf16 v[58:61], v[184:187], v[176:179], v[58:61]
	v_mfma_f32_16x16x32_bf16 v[54:57], v[192:195], v[168:171], v[54:57]
	v_mfma_f32_16x16x32_bf16 v[50:53], v[192:195], v[176:179], v[50:53]
	v_mfma_f32_16x16x32_bf16 v[46:49], v[200:203], v[168:171], v[46:49]
	v_mfma_f32_16x16x32_bf16 v[42:45], v[200:203], v[176:179], v[42:45]
	s_waitcnt lgkmcnt(0)
	v_mfma_f32_16x16x32_bf16 v[38:41], v[208:211], v[168:171], v[38:41]
	v_mfma_f32_16x16x32_bf16 v[34:37], v[208:211], v[176:179], v[34:37]
	s_setprio 0
	s_barrier
; #define STAGE(P, BASE, LD, br, kt) do { const int _so = (int)(((br) * (LD) + (kt) * BK) * 2); \
;     _Pragma("unroll") for (int _i = 0; _i < 2; ++_i) { \
;       __builtin_amdgcn_raw_ptr_buffer_load_lds(rs##BASE, (__attribute__((address_space(3))) unsigned*)((char*)(P) + tid_ * 16 + _i * 8192), 16, (int)off##LD[_i], _so, 0, 0); } } while (0)
; #define LDA_(dst, b, h) _Pragma("unroll") for (int m = 0; m < 4; ++m) _Pragma("unroll") for (int k = 0; k < 2; ++k) \
;     dst[m][k] = *reinterpret_cast<const bf16x8*>((char*)SA(b, h) + lds_byte(wr * 64 + m * 16 + fr, k * 32 + fq * 8))
; #define LDB_(dst, b, h) _Pragma("unroll") for (int n = 0; n < 2; ++n) _Pragma("unroll") for (int k = 0; k < 2; ++k) \
;     dst[n][k] = *reinterpret_cast<const bf16x8*>((char*)SB(b, h) + lds_byte(wc * 32 + n * 16 + fr, k * 32 + fq * 8))
; #define MMA(ai, bj, At, Bx) do { __builtin_amdgcn_s_setprio(1); \
;     _Pragma("unroll") for (int m = 0; m < 4; ++m) _Pragma("unroll") for (int n = 0; n < 2; ++n) _Pragma("unroll") for (int k = 0; k < 2; ++k) \
;       acc[ai][bj][m][n] = __builtin_amdgcn_mfma_f32_16x16x32_bf16(At[m][k], Bx[n][k], acc[ai][bj][m][n], 0, 0, 0); \
;     __builtin_amdgcn_s_setprio(0); } while (0)
; #define WAIT_V(n) asm volatile("s_waitcnt vmcnt(" #n ")" ::: "memory")
; #define WAIT_L(n) asm volatile("s_waitcnt lgkmcnt(" #n ")" ::: "memory")
; #define BAR __builtin_amdgcn_s_barrier()
; #define SCHED __builtin_amdgcn_sched_barrier(0)
; template <int K, int LDA, int LDB>
; DEVI void gemm_tile(const bf16* __restrict__ A, const bf16* __restrict__ Bt, bf16* shm, acc_t& acc) {
;     ...
;     STAGE(SB(0, 1), Bt, LDB, HALF, t + 2);
;     WAIT_V(6); BAR; MMA(1, 1, At, B1); BAR;
;     LDB_(B0, 1, 0); SCHED; LDA_(At, 1, 0); STAGE(SA(0, 1), A, LDA, HALF, t + 2);
;     WAIT_L(8); BAR; WAIT_L(0); MMA(0, 0, At, B0); BAR; SCHED;
;     LDB_(B1, 1, 1); STAGE(SB(1, 0), Bt, LDB, 0, t + 3);
;     BAR; WAIT_L(0); MMA(0, 1, At, B1); BAR;
;     LDA_(At, 1, 1); STAGE(SA(1, 0), A, LDA, 0, t + 3);
	v_readfirstlane_b32 s61, v148
	s_add_i32 s60, s7, 0xffffff80
	s_mov_b32 m0, s61
	v_readfirstlane_b32 s61, v149
	buffer_load_dwordx4 v140, s[0:3], s60 offen lds
	s_mov_b32 m0, s61
	s_nop 0
	buffer_load_dwordx4 v142, s[0:3], s60 offen lds
	s_waitcnt vmcnt(6)
	s_barrier
	s_setprio 1
	v_mfma_f32_16x16x32_bf16 v[30:33], v[180:183], v[212:215], v[30:33]
	v_mfma_f32_16x16x32_bf16 v[26:29], v[180:183], v[220:223], v[26:29]
	v_mfma_f32_16x16x32_bf16 v[22:25], v[188:191], v[212:215], v[22:25]
	v_mfma_f32_16x16x32_bf16 v[18:21], v[188:191], v[220:223], v[18:21]
	v_mfma_f32_16x16x32_bf16 v[14:17], v[196:199], v[212:215], v[14:17]
	v_mfma_f32_16x16x32_bf16 v[10:13], v[196:199], v[220:223], v[10:13]
	v_mfma_f32_16x16x32_bf16 v[6:9], v[204:207], v[212:215], v[6:9]
	v_mfma_f32_16x16x32_bf16 v[2:5], v[204:207], v[220:223], v[2:5]
	v_mfma_f32_16x16x32_bf16 v[30:33], v[184:187], v[216:219], v[30:33]
	v_mfma_f32_16x16x32_bf16 v[26:29], v[184:187], v[224:227], v[26:29]
	v_mfma_f32_16x16x32_bf16 v[22:25], v[192:195], v[216:219], v[22:25]
	v_mfma_f32_16x16x32_bf16 v[18:21], v[192:195], v[224:227], v[18:21]
	v_mfma_f32_16x16x32_bf16 v[14:17], v[200:203], v[216:219], v[14:17]
	v_mfma_f32_16x16x32_bf16 v[10:13], v[200:203], v[224:227], v[10:13]
	v_mfma_f32_16x16x32_bf16 v[6:9], v[208:211], v[216:219], v[6:9]
	v_mfma_f32_16x16x32_bf16 v[2:5], v[208:211], v[224:227], v[2:5]
	s_setprio 0
	s_barrier
	ds_read_b128 v[164:167], v143
	ds_read_b128 v[168:171], v143 offset:1024
	ds_read_b128 v[172:175], v143 offset:2048
	ds_read_b128 v[176:179], v143 offset:3072
	v_readfirstlane_b32 s61, v150
	s_mov_b32 m0, s61
	v_readfirstlane_b32 s61, v151
	ds_read_b128 v[180:183], v139 offset:32768
	ds_read_b128 v[184:187], v139 offset:33792
	ds_read_b128 v[188:191], v138 offset:32768
	ds_read_b128 v[192:195], v138 offset:33792
	ds_read_b128 v[196:199], v135 offset:32768
	ds_read_b128 v[200:203], v135 offset:33792
	ds_read_b128 v[204:207], v134 offset:32768
	ds_read_b128 v[208:211], v134 offset:33792
	buffer_load_dwordx4 v140, s[8:11], s60 offen lds
	s_mov_b32 m0, s61
	s_nop 0
	buffer_load_dwordx4 v142, s[8:11], s60 offen lds
	s_waitcnt lgkmcnt(8)
	s_barrier
	s_waitcnt lgkmcnt(0)
	s_setprio 1
	s_waitcnt lgkmcnt(7)
	v_mfma_f32_16x16x32_bf16 v[126:129], v[180:183], v[164:167], v[126:129]
	v_mfma_f32_16x16x32_bf16 v[122:125], v[180:183], v[172:175], v[122:125]
	s_waitcnt lgkmcnt(5)
	v_mfma_f32_16x16x32_bf16 v[118:121], v[188:191], v[164:167], v[118:121]
	v_mfma_f32_16x16x32_bf16 v[114:117], v[188:191], v[172:175], v[114:117]
	s_waitcnt lgkmcnt(3)
	v_mfma_f32_16x16x32_bf16 v[110:113], v[196:199], v[164:167], v[110:113]
	v_mfma_f32_16x16x32_bf16 v[106:109], v[196:199], v[172:175], v[106:109]
	s_waitcnt lgkmcnt(1)
	v_mfma_f32_16x16x32_bf16 v[102:105], v[204:207], v[164:167], v[102:105]
	v_mfma_f32_16x16x32_bf16 v[98:101], v[204:207], v[172:175], v[98:101]
	v_mfma_f32_16x16x32_bf16 v[126:129], v[184:187], v[168:171], v[126:129]
	v_mfma_f32_16x16x32_bf16 v[122:125], v[184:187], v[176:179], v[122:125]
	v_mfma_f32_16x16x32_bf16 v[118:121], v[192:195], v[168:171], v[118:121]
	v_mfma_f32_16x16x32_bf16 v[114:117], v[192:195], v[176:179], v[114:117]
	v_mfma_f32_16x16x32_bf16 v[110:113], v[200:203], v[168:171], v[110:113]
	v_mfma_f32_16x16x32_bf16 v[106:109], v[200:203], v[176:179], v[106:109]
	s_waitcnt lgkmcnt(0)
	v_mfma_f32_16x16x32_bf16 v[102:105], v[208:211], v[168:171], v[102:105]
	v_mfma_f32_16x16x32_bf16 v[98:101], v[208:211], v[176:179], v[98:101]
	s_setprio 0
	s_barrier
	v_readfirstlane_b32 s61, v152
	s_add_i32 s60, s7, 0xffea0000
	s_mov_b32 m0, s61
	v_readfirstlane_b32 s61, v153
	ds_read_b128 v[212:215], v141
	ds_read_b128 v[216:219], v141 offset:1024
	ds_read_b128 v[220:223], v141 offset:2048
	ds_read_b128 v[224:227], v141 offset:3072
	buffer_load_dwordx4 v140, s[0:3], s60 offen lds
	s_mov_b32 m0, s61
	s_nop 0
	buffer_load_dwordx4 v142, s[0:3], s60 offen lds
	s_barrier
	s_waitcnt lgkmcnt(0)
	s_setprio 1
	s_waitcnt lgkmcnt(3)
	v_mfma_f32_16x16x32_bf16 v[94:97], v[180:183], v[212:215], v[94:97]
	s_waitcnt lgkmcnt(1)
	v_mfma_f32_16x16x32_bf16 v[90:93], v[180:183], v[220:223], v[90:93]
	v_mfma_f32_16x16x32_bf16 v[86:89], v[188:191], v[212:215], v[86:89]
	v_mfma_f32_16x16x32_bf16 v[82:85], v[188:191], v[220:223], v[82:85]
	v_mfma_f32_16x16x32_bf16 v[78:81], v[196:199], v[212:215], v[78:81]
	v_mfma_f32_16x16x32_bf16 v[74:77], v[196:199], v[220:223], v[74:77]
	v_mfma_f32_16x16x32_bf16 v[70:73], v[204:207], v[212:215], v[70:73]
	v_mfma_f32_16x16x32_bf16 v[66:69], v[204:207], v[220:223], v[66:69]
	v_mfma_f32_16x16x32_bf16 v[94:97], v[184:187], v[216:219], v[94:97]
	s_waitcnt lgkmcnt(0)
	v_mfma_f32_16x16x32_bf16 v[90:93], v[184:187], v[224:227], v[90:93]
	v_mfma_f32_16x16x32_bf16 v[86:89], v[192:195], v[216:219], v[86:89]
	v_mfma_f32_16x16x32_bf16 v[82:85], v[192:195], v[224:227], v[82:85]
	v_mfma_f32_16x16x32_bf16 v[78:81], v[200:203], v[216:219], v[78:81]
	v_mfma_f32_16x16x32_bf16 v[74:77], v[200:203], v[224:227], v[74:77]
	v_mfma_f32_16x16x32_bf16 v[70:73], v[208:211], v[216:219], v[70:73]
	v_mfma_f32_16x16x32_bf16 v[66:69], v[208:211], v[224:227], v[66:69]
	s_setprio 0
	v_readfirstlane_b32 s61, v154
	s_mov_b32 m0, s61
	v_readfirstlane_b32 s61, v156
	s_barrier
	ds_read_b128 v[180:183], v139 offset:49152
	ds_read_b128 v[184:187], v139 offset:50176
	ds_read_b128 v[188:191], v138 offset:49152
	ds_read_b128 v[192:195], v138 offset:50176
	ds_read_b128 v[196:199], v135 offset:49152
	ds_read_b128 v[200:203], v135 offset:50176
	ds_read_b128 v[204:207], v134 offset:49152
	ds_read_b128 v[208:211], v134 offset:50176
	buffer_load_dwordx4 v140, s[8:11], s60 offen lds
	s_mov_b32 m0, s61
	s_nop 0
	buffer_load_dwordx4 v142, s[8:11], s60 offen lds
	s_barrier
; #define STAGE(P, BASE, LD, br, kt) do { const int _so = (int)(((br) * (LD) + (kt) * BK) * 2); \
;     _Pragma("unroll") for (int _i = 0; _i < 2; ++_i) { \
;       __builtin_amdgcn_raw_ptr_buffer_load_lds(rs##BASE, (__attribute__((address_space(3))) unsigned*)((char*)(P) + tid_ * 16 + _i * 8192), 16, (int)off##LD[_i], _so, 0, 0); } } while (0)
; #define LDA_(dst, b, h) _Pragma("unroll") for (int m = 0; m < 4; ++m) _Pragma("unroll") for (int k = 0; k < 2; ++k) \
;     dst[m][k] = *reinterpret_cast<const bf16x8*>((char*)SA(b, h) + lds_byte(wr * 64 + m * 16 + fr, k * 32 + fq * 8))
; #define LDB_(dst, b, h) _Pragma("unroll") for (int n = 0; n < 2; ++n) _Pragma("unroll") for (int k = 0; k < 2; ++k) \
;     dst[n][k] = *reinterpret_cast<const bf16x8*>((char*)SB(b, h) + lds_byte(wc * 32 + n * 16 + fr, k * 32 + fq * 8))
; #define MMA(ai, bj, At, Bx) do { __builtin_amdgcn_s_setprio(1); \
;     _Pragma("unroll") for (int m = 0; m < 4; ++m) _Pragma("unroll") for (int n = 0; n < 2; ++n) _Pragma("unroll") for (int k = 0; k < 2; ++k) \
;       acc[ai][bj][m][n] = __builtin_amdgcn_mfma_f32_16x16x32_bf16(At[m][k], Bx[n][k], acc[ai][bj][m][n], 0, 0, 0); \
;     __builtin_amdgcn_s_setprio(0); } while (0)
; #define WAIT_V(n) asm volatile("s_waitcnt vmcnt(" #n ")" ::: "memory")
; #define WAIT_L(n) asm volatile("s_waitcnt lgkmcnt(" #n ")" ::: "memory")
; #define BAR __builtin_amdgcn_s_barrier()
; #define SCHED __builtin_amdgcn_sched_barrier(0)
; template <int K, int LDA, int LDB>
; DEVI void gemm_tile(const bf16* __restrict__ A, const bf16* __restrict__ Bt, bf16* shm, acc_t& acc) {
;     ...
;     BAR; WAIT_L(0); MMA(1, 0, At, B0); BAR; SCHED;
;     STAGE(SB(1, 1), Bt, LDB, HALF, t + 3);
;     WAIT_V(6); BAR; MMA(1, 1, At, B1); BAR;
;   }
;   { LDB_(B0, 0, 0); LDA_(At, 0, 0); STAGE(SA(1, 1), A, LDA, HALF, nt - 1);
;     BAR; WAIT_L(0); MMA(0, 0, At, B0); BAR;
;     LDB_(B1, 0, 1); BAR; WAIT_L(0); MMA(0, 1, At, B1); BAR;
	s_waitcnt lgkmcnt(0)
	s_setprio 1
	s_waitcnt lgkmcnt(7)
	v_mfma_f32_16x16x32_bf16 v[62:65], v[180:183], v[164:167], v[62:65]
	v_mfma_f32_16x16x32_bf16 v[58:61], v[180:183], v[172:175], v[58:61]
	s_waitcnt lgkmcnt(5)
	v_mfma_f32_16x16x32_bf16 v[54:57], v[188:191], v[164:167], v[54:57]
	v_mfma_f32_16x16x32_bf16 v[50:53], v[188:191], v[172:175], v[50:53]
	s_waitcnt lgkmcnt(3)
	v_mfma_f32_16x16x32_bf16 v[46:49], v[196:199], v[164:167], v[46:49]
	v_mfma_f32_16x16x32_bf16 v[42:45], v[196:199], v[172:175], v[42:45]
	s_waitcnt lgkmcnt(1)
	v_mfma_f32_16x16x32_bf16 v[38:41], v[204:207], v[164:167], v[38:41]
	v_mfma_f32_16x16x32_bf16 v[34:37], v[204:207], v[172:175], v[34:37]
	v_mfma_f32_16x16x32_bf16 v[62:65], v[184:187], v[168:171], v[62:65]
	v_mfma_f32_16x16x32_bf16 v[58:61], v[184:187], v[176:179], v[58:61]
	v_mfma_f32_16x16x32_bf16 v[54:57], v[192:195], v[168:171], v[54:57]
	v_mfma_f32_16x16x32_bf16 v[50:53], v[192:195], v[176:179], v[50:53]
	v_mfma_f32_16x16x32_bf16 v[46:49], v[200:203], v[168:171], v[46:49]
	v_mfma_f32_16x16x32_bf16 v[42:45], v[200:203], v[176:179], v[42:45]
	s_waitcnt lgkmcnt(0)
	v_mfma_f32_16x16x32_bf16 v[38:41], v[208:211], v[168:171], v[38:41]
	v_mfma_f32_16x16x32_bf16 v[34:37], v[208:211], v[176:179], v[34:37]
	s_setprio 0
	s_barrier
	v_readfirstlane_b32 s60, v158
	s_mov_b32 m0, s60
	v_readfirstlane_b32 s60, v159
	buffer_load_dwordx4 v140, s[0:3], s7 offen lds
	s_mov_b32 m0, s60
	s_nop 0
	buffer_load_dwordx4 v142, s[0:3], s7 offen lds
	s_waitcnt vmcnt(6)
	s_barrier
	s_setprio 1
	v_mfma_f32_16x16x32_bf16 v[30:33], v[180:183], v[212:215], v[30:33]
	v_mfma_f32_16x16x32_bf16 v[26:29], v[180:183], v[220:223], v[26:29]
	v_mfma_f32_16x16x32_bf16 v[22:25], v[188:191], v[212:215], v[22:25]
	v_mfma_f32_16x16x32_bf16 v[18:21], v[188:191], v[220:223], v[18:21]
	v_mfma_f32_16x16x32_bf16 v[14:17], v[196:199], v[212:215], v[14:17]
	v_mfma_f32_16x16x32_bf16 v[10:13], v[196:199], v[220:223], v[10:13]
	v_mfma_f32_16x16x32_bf16 v[6:9], v[204:207], v[212:215], v[6:9]
	v_mfma_f32_16x16x32_bf16 v[2:5], v[204:207], v[220:223], v[2:5]
	v_mfma_f32_16x16x32_bf16 v[30:33], v[184:187], v[216:219], v[30:33]
	v_mfma_f32_16x16x32_bf16 v[26:29], v[184:187], v[224:227], v[26:29]
	v_mfma_f32_16x16x32_bf16 v[22:25], v[192:195], v[216:219], v[22:25]
	v_mfma_f32_16x16x32_bf16 v[18:21], v[192:195], v[224:227], v[18:21]
	v_mfma_f32_16x16x32_bf16 v[14:17], v[200:203], v[216:219], v[14:17]
	v_mfma_f32_16x16x32_bf16 v[10:13], v[200:203], v[224:227], v[10:13]
	v_mfma_f32_16x16x32_bf16 v[6:9], v[208:211], v[216:219], v[6:9]
	v_mfma_f32_16x16x32_bf16 v[2:5], v[208:211], v[224:227], v[2:5]
	s_setprio 0
	s_add_i32 s6, s6, 2
	s_addk_i32 s7, 0x100
	s_cmpk_lt_u32 s6, 0x54
	s_cbranch_scc1 .Lrot_37483
	s_barrier
	v_readfirstlane_b32 s0, v157
	s_mov_b32 s10, s2
	s_mov_b32 s11, s3
	s_mov_b32 m0, s0
	v_readfirstlane_b32 s0, v160
	ds_read_b128 v[144:147], v161
	ds_read_b128 v[148:151], v161 offset:1024
	ds_read_b128 v[164:167], v161 offset:2048
	ds_read_b128 v[168:171], v161 offset:3072
	ds_read_b128 v[172:175], v139
	ds_read_b128 v[176:179], v139 offset:1024
	ds_read_b128 v[180:183], v138
	ds_read_b128 v[184:187], v138 offset:1024
	ds_read_b128 v[188:191], v135
	ds_read_b128 v[192:195], v135 offset:1024
	ds_read_b128 v[196:199], v134
	ds_read_b128 v[200:203], v134 offset:1024
	buffer_load_dwordx4 v140, s[8:11], s34 offen lds
	s_mov_b32 m0, s0
	s_nop 0
	buffer_load_dwordx4 v142, s[8:11], s34 offen lds
	s_barrier
	s_waitcnt lgkmcnt(0)
	s_setprio 1
	s_waitcnt lgkmcnt(7)
	v_mfma_f32_16x16x32_bf16 v[126:129], v[172:175], v[144:147], v[126:129]
	v_mfma_f32_16x16x32_bf16 v[122:125], v[172:175], v[164:167], v[122:125]
	s_waitcnt lgkmcnt(5)
	v_mfma_f32_16x16x32_bf16 v[118:121], v[180:183], v[144:147], v[118:121]
	v_mfma_f32_16x16x32_bf16 v[114:117], v[180:183], v[164:167], v[114:117]
	s_waitcnt lgkmcnt(3)
	v_mfma_f32_16x16x32_bf16 v[110:113], v[188:191], v[144:147], v[110:113]
	v_mfma_f32_16x16x32_bf16 v[106:109], v[188:191], v[164:167], v[106:109]
	s_waitcnt lgkmcnt(1)
	v_mfma_f32_16x16x32_bf16 v[102:105], v[196:199], v[144:147], v[102:105]
	v_mfma_f32_16x16x32_bf16 v[98:101], v[196:199], v[164:167], v[98:101]
	v_mfma_f32_16x16x32_bf16 v[126:129], v[176:179], v[148:151], v[126:129]
	v_mfma_f32_16x16x32_bf16 v[122:125], v[176:179], v[168:171], v[122:125]
	v_mfma_f32_16x16x32_bf16 v[118:121], v[184:187], v[148:151], v[118:121]
	v_mfma_f32_16x16x32_bf16 v[114:117], v[184:187], v[168:171], v[114:117]
	v_mfma_f32_16x16x32_bf16 v[110:113], v[192:195], v[148:151], v[110:113]
	v_mfma_f32_16x16x32_bf16 v[106:109], v[192:195], v[168:171], v[106:109]
	s_waitcnt lgkmcnt(0)
	v_mfma_f32_16x16x32_bf16 v[102:105], v[200:203], v[148:151], v[102:105]
	v_mfma_f32_16x16x32_bf16 v[98:101], v[200:203], v[168:171], v[98:101]
	s_setprio 0
	s_barrier
	ds_read_b128 v[156:159], v155
	ds_read_b128 v[204:207], v155 offset:1024
	ds_read_b128 v[208:211], v155 offset:2048
	ds_read_b128 v[152:155], v155 offset:3072
	s_barrier
	s_waitcnt lgkmcnt(0)
	s_setprio 1
	s_waitcnt lgkmcnt(3)
	v_mfma_f32_16x16x32_bf16 v[94:97], v[172:175], v[156:159], v[94:97]
	s_waitcnt lgkmcnt(1)
	v_mfma_f32_16x16x32_bf16 v[90:93], v[172:175], v[208:211], v[90:93]
	v_mfma_f32_16x16x32_bf16 v[86:89], v[180:183], v[156:159], v[86:89]
	v_mfma_f32_16x16x32_bf16 v[82:85], v[180:183], v[208:211], v[82:85]
	v_mfma_f32_16x16x32_bf16 v[78:81], v[188:191], v[156:159], v[78:81]
	v_mfma_f32_16x16x32_bf16 v[70:73], v[196:199], v[156:159], v[70:73]
	v_mfma_f32_16x16x32_bf16 v[94:97], v[176:179], v[204:207], v[94:97]
	s_waitcnt lgkmcnt(0)
	v_mfma_f32_16x16x32_bf16 v[90:93], v[176:179], v[152:155], v[90:93]
	v_mfma_f32_16x16x32_bf16 v[86:89], v[184:187], v[204:207], v[86:89]
	v_mfma_f32_16x16x32_bf16 v[82:85], v[184:187], v[152:155], v[82:85]
	v_mfma_f32_16x16x32_bf16 v[78:81], v[192:195], v[204:207], v[78:81]
	v_mfma_f32_16x16x32_bf16 v[74:77], v[188:191], v[208:211], v[74:77]
	v_mfma_f32_16x16x32_bf16 v[70:73], v[200:203], v[204:207], v[70:73]
	v_mfma_f32_16x16x32_bf16 v[66:69], v[196:199], v[208:211], v[66:69]
	v_mfma_f32_16x16x32_bf16 v[172:175], v[192:195], v[152:155], v[74:77]
	v_mfma_f32_16x16x32_bf16 v[176:179], v[200:203], v[152:155], v[66:69]
	s_setprio 0
	s_barrier
; #define LDA_(dst, b, h) _Pragma("unroll") for (int m = 0; m < 4; ++m) _Pragma("unroll") for (int k = 0; k < 2; ++k) \
;     dst[m][k] = *reinterpret_cast<const bf16x8*>((char*)SA(b, h) + lds_byte(wr * 64 + m * 16 + fr, k * 32 + fq * 8))
; #define LDB_(dst, b, h) _Pragma("unroll") for (int n = 0; n < 2; ++n) _Pragma("unroll") for (int k = 0; k < 2; ++k) \
;     dst[n][k] = *reinterpret_cast<const bf16x8*>((char*)SB(b, h) + lds_byte(wc * 32 + n * 16 + fr, k * 32 + fq * 8))
; #define MMA(ai, bj, At, Bx) do { __builtin_amdgcn_s_setprio(1); \
;     _Pragma("unroll") for (int m = 0; m < 4; ++m) _Pragma("unroll") for (int n = 0; n < 2; ++n) _Pragma("unroll") for (int k = 0; k < 2; ++k) \
;       acc[ai][bj][m][n] = __builtin_amdgcn_mfma_f32_16x16x32_bf16(At[m][k], Bx[n][k], acc[ai][bj][m][n], 0, 0, 0); \
;     __builtin_amdgcn_s_setprio(0); } while (0)
; #define WAIT_V(n) asm volatile("s_waitcnt vmcnt(" #n ")" ::: "memory")
; #define WAIT_L(n) asm volatile("s_waitcnt lgkmcnt(" #n ")" ::: "memory")
; #define BAR __builtin_amdgcn_s_barrier()
; template <int K, int LDA, int LDB>
; DEVI void gemm_tile(const bf16* __restrict__ A, const bf16* __restrict__ Bt, bf16* shm, acc_t& acc) {
;     ...
;     LDA_(At, 0, 1); WAIT_V(4); BAR; WAIT_L(0); MMA(1, 0, At, B0); MMA(1, 1, At, B1); BAR; }
;   { LDB_(B0, 1, 0); LDA_(At, 1, 0); WAIT_V(2); BAR; WAIT_L(0); MMA(0, 0, At, B0); BAR;
	s_nop 3
	ds_read_b128 v[66:69], v139 offset:16384
	ds_read_b128 v[74:77], v139 offset:17408
	ds_read_b128 v[180:183], v138 offset:16384
	ds_read_b128 v[184:187], v138 offset:17408
	ds_read_b128 v[188:191], v135 offset:16384
	ds_read_b128 v[192:195], v135 offset:17408
	ds_read_b128 v[196:199], v134 offset:16384
	ds_read_b128 v[200:203], v134 offset:17408
	s_waitcnt vmcnt(4)
	s_barrier
	s_waitcnt lgkmcnt(0)
	s_setprio 1
	s_waitcnt lgkmcnt(3)
	v_mfma_f32_16x16x32_bf16 v[46:49], v[188:191], v[144:147], v[46:49]
	s_waitcnt lgkmcnt(1)
	v_mfma_f32_16x16x32_bf16 v[38:41], v[196:199], v[144:147], v[38:41]
	v_mfma_f32_16x16x32_bf16 v[34:37], v[196:199], v[164:167], v[34:37]
	v_mfma_f32_16x16x32_bf16 v[62:65], v[66:69], v[144:147], v[62:65]
	v_mfma_f32_16x16x32_bf16 v[58:61], v[66:69], v[164:167], v[58:61]
	v_mfma_f32_16x16x32_bf16 v[54:57], v[180:183], v[144:147], v[54:57]
	v_mfma_f32_16x16x32_bf16 v[50:53], v[180:183], v[164:167], v[50:53]
	v_mfma_f32_16x16x32_bf16 v[46:49], v[192:195], v[148:151], v[46:49]
	v_mfma_f32_16x16x32_bf16 v[42:45], v[188:191], v[164:167], v[42:45]
	s_waitcnt lgkmcnt(0)
	v_mfma_f32_16x16x32_bf16 v[38:41], v[200:203], v[148:151], v[38:41]
	v_mfma_f32_16x16x32_bf16 v[34:37], v[200:203], v[168:171], v[34:37]
	v_mfma_f32_16x16x32_bf16 v[212:215], v[74:77], v[148:151], v[62:65]
	v_mfma_f32_16x16x32_bf16 v[216:219], v[74:77], v[168:171], v[58:61]
	v_mfma_f32_16x16x32_bf16 v[220:223], v[184:187], v[148:151], v[54:57]
	v_mfma_f32_16x16x32_bf16 v[224:227], v[184:187], v[168:171], v[50:53]
	v_mfma_f32_16x16x32_bf16 v[228:231], v[192:195], v[168:171], v[42:45]
	s_setprio 0
	s_setprio 1
	v_mfma_f32_16x16x32_bf16 v[30:33], v[66:69], v[156:159], v[30:33]
	v_mfma_f32_16x16x32_bf16 v[22:25], v[180:183], v[156:159], v[22:25]
	v_mfma_f32_16x16x32_bf16 v[18:21], v[180:183], v[208:211], v[18:21]
	v_mfma_f32_16x16x32_bf16 v[10:13], v[188:191], v[208:211], v[10:13]
	v_mfma_f32_16x16x32_bf16 v[6:9], v[196:199], v[156:159], v[6:9]
	v_mfma_f32_16x16x32_bf16 v[2:5], v[196:199], v[208:211], v[2:5]
	v_mfma_f32_16x16x32_bf16 v[30:33], v[74:77], v[204:207], v[30:33]
	v_mfma_f32_16x16x32_bf16 v[26:29], v[66:69], v[208:211], v[26:29]
	v_mfma_f32_16x16x32_bf16 v[22:25], v[184:187], v[204:207], v[22:25]
	v_mfma_f32_16x16x32_bf16 v[18:21], v[184:187], v[152:155], v[18:21]
	v_mfma_f32_16x16x32_bf16 v[14:17], v[188:191], v[156:159], v[14:17]
	v_mfma_f32_16x16x32_bf16 v[10:13], v[192:195], v[152:155], v[10:13]
	v_mfma_f32_16x16x32_bf16 v[6:9], v[200:203], v[204:207], v[6:9]
	v_mfma_f32_16x16x32_bf16 v[2:5], v[200:203], v[152:155], v[2:5]
	v_mfma_f32_16x16x32_bf16 v[144:147], v[74:77], v[152:155], v[26:29]
	v_mfma_f32_16x16x32_bf16 v[148:151], v[192:195], v[204:207], v[14:17]
	s_setprio 0
	s_barrier
	ds_read_b128 v[152:155], v143
	ds_read_b128 v[156:159], v143 offset:1024
	ds_read_b128 v[164:167], v143 offset:2048
	ds_read_b128 v[168:171], v143 offset:3072
	ds_read_b128 v[58:61], v139 offset:32768
	ds_read_b128 v[62:65], v139 offset:33792
	ds_read_b128 v[66:69], v138 offset:32768
	ds_read_b128 v[74:77], v138 offset:33792
	ds_read_b128 v[180:183], v135 offset:32768
	ds_read_b128 v[184:187], v135 offset:33792
	ds_read_b128 v[188:191], v134 offset:32768
	ds_read_b128 v[192:195], v134 offset:33792
	s_waitcnt vmcnt(2)
	s_barrier
	s_waitcnt lgkmcnt(0)
	s_setprio 1
	s_waitcnt lgkmcnt(7)
	v_mfma_f32_16x16x32_bf16 v[14:17], v[58:61], v[152:155], v[126:129]
	s_waitcnt lgkmcnt(5)
	v_mfma_f32_16x16x32_bf16 v[26:29], v[66:69], v[152:155], v[118:121]
	s_waitcnt lgkmcnt(3)
	v_mfma_f32_16x16x32_bf16 v[42:45], v[180:183], v[152:155], v[110:113]
	s_waitcnt lgkmcnt(1)
	v_mfma_f32_16x16x32_bf16 v[50:53], v[188:191], v[152:155], v[102:105]
	v_mfma_f32_16x16x32_bf16 v[126:129], v[62:65], v[156:159], v[14:17]
	v_mfma_f32_16x16x32_bf16 v[14:17], v[58:61], v[164:167], v[122:125]
	v_mfma_f32_16x16x32_bf16 v[122:125], v[74:77], v[156:159], v[26:29]
	v_mfma_f32_16x16x32_bf16 v[26:29], v[66:69], v[164:167], v[114:117]
	v_mfma_f32_16x16x32_bf16 v[118:121], v[184:187], v[156:159], v[42:45]
	v_mfma_f32_16x16x32_bf16 v[42:45], v[180:183], v[164:167], v[106:109]
	s_waitcnt lgkmcnt(0)
	v_mfma_f32_16x16x32_bf16 v[114:117], v[192:195], v[156:159], v[50:53]
	v_mfma_f32_16x16x32_bf16 v[50:53], v[188:191], v[164:167], v[98:101]
	v_mfma_f32_16x16x32_bf16 v[14:17], v[62:65], v[168:171], v[14:17]
	v_mfma_f32_16x16x32_bf16 v[26:29], v[74:77], v[168:171], v[26:29]
	v_mfma_f32_16x16x32_bf16 v[42:45], v[184:187], v[168:171], v[42:45]
	v_mfma_f32_16x16x32_bf16 v[54:57], v[192:195], v[168:171], v[50:53]
	s_setprio 0
	s_barrier
; #define LDA_(dst, b, h) _Pragma("unroll") for (int m = 0; m < 4; ++m) _Pragma("unroll") for (int k = 0; k < 2; ++k) \
;     dst[m][k] = *reinterpret_cast<const bf16x8*>((char*)SA(b, h) + lds_byte(wr * 64 + m * 16 + fr, k * 32 + fq * 8))
; #define LDB_(dst, b, h) _Pragma("unroll") for (int n = 0; n < 2; ++n) _Pragma("unroll") for (int k = 0; k < 2; ++k) \
;     dst[n][k] = *reinterpret_cast<const bf16x8*>((char*)SB(b, h) + lds_byte(wc * 32 + n * 16 + fr, k * 32 + fq * 8))
; #define MMA(ai, bj, At, Bx) do { __builtin_amdgcn_s_setprio(1); \
;     _Pragma("unroll") for (int m = 0; m < 4; ++m) _Pragma("unroll") for (int n = 0; n < 2; ++n) _Pragma("unroll") for (int k = 0; k < 2; ++k) \
;       acc[ai][bj][m][n] = __builtin_amdgcn_mfma_f32_16x16x32_bf16(At[m][k], Bx[n][k], acc[ai][bj][m][n], 0, 0, 0); \
;     __builtin_amdgcn_s_setprio(0); } while (0)
; #define WAIT_V(n) asm volatile("s_waitcnt vmcnt(" #n ")" ::: "memory")
; #define WAIT_L(n) asm volatile("s_waitcnt lgkmcnt(" #n ")" ::: "memory")
; #define BAR __builtin_amdgcn_s_barrier()
; template <int K, int LDA, int LDB>
; DEVI void gemm_tile(const bf16* __restrict__ A, const bf16* __restrict__ Bt, bf16* shm, acc_t& acc) {
;     ...
;   { LDB_(B0, 1, 0); LDA_(At, 1, 0); WAIT_V(2); BAR; WAIT_L(0); MMA(0, 0, At, B0); BAR;
;     LDB_(B1, 1, 1); WAIT_V(0); BAR; WAIT_L(0); MMA(0, 1, At, B1); BAR;
;     LDA_(At, 1, 1); BAR; WAIT_L(0); MMA(1, 0, At, B0); MMA(1, 1, At, B1); BAR; }
;   if (wr == 0) BAR;
	ds_read_b128 v[196:199], v141
	ds_read_b128 v[200:203], v141 offset:1024
	ds_read_b128 v[204:207], v141 offset:2048
	ds_read_b128 v[140:143], v141 offset:3072
	s_waitcnt vmcnt(0)
	s_barrier
	s_waitcnt lgkmcnt(0)
	s_setprio 1
	s_waitcnt lgkmcnt(3)
	v_mfma_f32_16x16x32_bf16 v[50:53], v[58:61], v[196:199], v[94:97]
	s_waitcnt lgkmcnt(1)
	v_mfma_f32_16x16x32_bf16 v[58:61], v[58:61], v[204:207], v[90:93]
	v_mfma_f32_16x16x32_bf16 v[50:53], v[62:65], v[200:203], v[50:53]
	s_waitcnt lgkmcnt(0)
	v_mfma_f32_16x16x32_bf16 v[58:61], v[62:65], v[140:143], v[58:61]
	v_mfma_f32_16x16x32_bf16 v[62:65], v[66:69], v[196:199], v[86:89]
	v_mfma_f32_16x16x32_bf16 v[66:69], v[66:69], v[204:207], v[82:85]
	v_mfma_f32_16x16x32_bf16 v[70:73], v[188:191], v[196:199], v[70:73]
	v_mfma_f32_16x16x32_bf16 v[62:65], v[74:77], v[200:203], v[62:65]
	v_mfma_f32_16x16x32_bf16 v[66:69], v[74:77], v[140:143], v[66:69]
	v_mfma_f32_16x16x32_bf16 v[74:77], v[180:183], v[196:199], v[78:81]
	v_mfma_f32_16x16x32_bf16 v[78:81], v[180:183], v[204:207], v[172:175]
	v_mfma_f32_16x16x32_bf16 v[90:93], v[192:195], v[200:203], v[70:73]
	v_mfma_f32_16x16x32_bf16 v[70:73], v[188:191], v[204:207], v[176:179]
	v_mfma_f32_16x16x32_bf16 v[74:77], v[184:187], v[200:203], v[74:77]
	v_mfma_f32_16x16x32_bf16 v[82:85], v[184:187], v[140:143], v[78:81]
	v_mfma_f32_16x16x32_bf16 v[98:101], v[192:195], v[140:143], v[70:73]
	s_setprio 0
	s_barrier
	ds_read_b128 v[172:175], v139 offset:49152
	ds_read_b128 v[176:179], v139 offset:50176
	ds_read_b128 v[180:183], v138 offset:49152
	ds_read_b128 v[184:187], v138 offset:50176
	ds_read_b128 v[188:191], v135 offset:49152
	ds_read_b128 v[192:195], v135 offset:50176
	ds_read_b128 v[208:211], v134 offset:49152
	ds_read_b128 v[232:235], v134 offset:50176
	s_barrier
	s_waitcnt lgkmcnt(0)
	s_setprio 1
	s_waitcnt lgkmcnt(7)
	v_mfma_f32_16x16x32_bf16 v[70:73], v[172:175], v[152:155], v[212:215]
	s_waitcnt lgkmcnt(6)
	v_mfma_f32_16x16x32_bf16 v[110:113], v[176:179], v[156:159], v[70:73]
	v_mfma_f32_16x16x32_bf16 v[70:73], v[172:175], v[164:167], v[216:219]
	v_mfma_f32_16x16x32_bf16 v[106:109], v[176:179], v[168:171], v[70:73]
	s_waitcnt lgkmcnt(5)
	v_mfma_f32_16x16x32_bf16 v[70:73], v[180:183], v[152:155], v[220:223]
	s_waitcnt lgkmcnt(3)
	v_mfma_f32_16x16x32_bf16 v[46:49], v[188:191], v[152:155], v[46:49]
	v_mfma_f32_16x16x32_bf16 v[102:105], v[184:187], v[156:159], v[70:73]
	v_mfma_f32_16x16x32_bf16 v[70:73], v[180:183], v[164:167], v[224:227]
	s_waitcnt lgkmcnt(2)
	v_mfma_f32_16x16x32_bf16 v[86:89], v[192:195], v[156:159], v[46:49]
	v_mfma_f32_16x16x32_bf16 v[46:49], v[188:191], v[164:167], v[228:231]
	s_waitcnt lgkmcnt(1)
	v_mfma_f32_16x16x32_bf16 v[38:41], v[208:211], v[152:155], v[38:41]
	v_mfma_f32_16x16x32_bf16 v[34:37], v[208:211], v[164:167], v[34:37]
	v_mfma_f32_16x16x32_bf16 v[94:97], v[184:187], v[168:171], v[70:73]
	v_mfma_f32_16x16x32_bf16 v[78:81], v[192:195], v[168:171], v[46:49]
	s_waitcnt lgkmcnt(0)
	v_mfma_f32_16x16x32_bf16 v[70:73], v[232:235], v[156:159], v[38:41]
	v_mfma_f32_16x16x32_bf16 v[46:49], v[232:235], v[168:171], v[34:37]
	s_setprio 0
	s_setprio 1
	v_mfma_f32_16x16x32_bf16 v[30:33], v[172:175], v[196:199], v[30:33]
	v_mfma_f32_16x16x32_bf16 v[38:41], v[176:179], v[200:203], v[30:33]
	v_mfma_f32_16x16x32_bf16 v[30:33], v[172:175], v[204:207], v[144:147]
	v_mfma_f32_16x16x32_bf16 v[22:25], v[180:183], v[196:199], v[22:25]
	v_mfma_f32_16x16x32_bf16 v[18:21], v[180:183], v[204:207], v[18:21]
	v_mfma_f32_16x16x32_bf16 v[34:37], v[176:179], v[140:143], v[30:33]
	v_mfma_f32_16x16x32_bf16 v[30:33], v[184:187], v[200:203], v[22:25]
	v_mfma_f32_16x16x32_bf16 v[22:25], v[184:187], v[140:143], v[18:21]
	v_mfma_f32_16x16x32_bf16 v[18:21], v[188:191], v[196:199], v[148:151]
	v_mfma_f32_16x16x32_bf16 v[10:13], v[188:191], v[204:207], v[10:13]
	v_mfma_f32_16x16x32_bf16 v[6:9], v[208:211], v[196:199], v[6:9]
	v_mfma_f32_16x16x32_bf16 v[2:5], v[208:211], v[204:207], v[2:5]
	v_mfma_f32_16x16x32_bf16 v[18:21], v[192:195], v[200:203], v[18:21]
	v_mfma_f32_16x16x32_bf16 v[10:13], v[192:195], v[140:143], v[10:13]
	v_mfma_f32_16x16x32_bf16 v[6:9], v[232:235], v[200:203], v[6:9]
	v_mfma_f32_16x16x32_bf16 v[2:5], v[232:235], v[140:143], v[2:5]
	s_setprio 0
	s_movk_i32 s0, 0x100
	v_cmp_gt_u32_e32 vcc, s0, v132
	s_barrier
	s_and_saveexec_b64 s[0:1], vcc
	s_cbranch_execz .LBB0_1704
	s_barrier

; #define STAGE(P, BASE, LD, br, kt) do { const int _so = (int)(((br) * (LD) + (kt) * BK) * 2); \
;     _Pragma("unroll") for (int _i = 0; _i < 2; ++_i) { \
;       __builtin_amdgcn_raw_ptr_buffer_load_lds(rs##BASE, (__attribute__((address_space(3))) unsigned*)((char*)(P) + tid_ * 16 + _i * 8192), 16, (int)off##LD[_i], _so, 0, 0); } } while (0)
; #define LDA_(dst, b, h) _Pragma("unroll") for (int m = 0; m < 4; ++m) _Pragma("unroll") for (int k = 0; k < 2; ++k) \
;     dst[m][k] = *reinterpret_cast<const bf16x8*>((char*)SA(b, h) + lds_byte(wr * 64 + m * 16 + fr, k * 32 + fq * 8))
; #define LDB_(dst, b, h) _Pragma("unroll") for (int n = 0; n < 2; ++n) _Pragma("unroll") for (int k = 0; k < 2; ++k) \
;     dst[n][k] = *reinterpret_cast<const bf16x8*>((char*)SB(b, h) + lds_byte(wc * 32 + n * 16 + fr, k * 32 + fq * 8))
; #define MMA(ai, bj, At, Bx) do { __builtin_amdgcn_s_setprio(1); \
;     _Pragma("unroll") for (int m = 0; m < 4; ++m) _Pragma("unroll") for (int n = 0; n < 2; ++n) _Pragma("unroll") for (int k = 0; k < 2; ++k) \
;       acc[ai][bj][m][n] = __builtin_amdgcn_mfma_f32_16x16x32_bf16(At[m][k], Bx[n][k], acc[ai][bj][m][n], 0, 0, 0); \
;     __builtin_amdgcn_s_setprio(0); } while (0)
; #define WAIT_L(n) asm volatile("s_waitcnt lgkmcnt(" #n ")" ::: "memory")
; #define BAR __builtin_amdgcn_s_barrier()
; #define SCHED __builtin_amdgcn_sched_barrier(0)
; template <int K, int LDA, int LDB>
; DEVI void gemm_tile(const bf16* __restrict__ A, const bf16* __restrict__ Bt, bf16* shm, acc_t& acc) {
;     ...
;     LDB_(B0, 0, 0); SCHED; LDA_(At, 0, 0); STAGE(SA(1, 1), A, LDA, HALF, t + 1);
;     WAIT_L(8); BAR; WAIT_L(0); MMA(0, 0, At, B0); BAR; SCHED;
;     LDB_(B1, 0, 1); STAGE(SB(0, 0), Bt, LDB, 0, t + 2);
;     BAR; WAIT_L(0); MMA(0, 1, At, B1); BAR;
;     LDA_(At, 0, 1); STAGE(SA(0, 0), A, LDA, 0, t + 2);
;     BAR; WAIT_L(0); MMA(1, 0, At, B0); BAR; SCHED;
.LBB0_1901:
	ds_read_b128 v[164:167], v162
	ds_read_b128 v[168:171], v162 offset:1024
	ds_read_b128 v[172:175], v162 offset:2048
	ds_read_b128 v[176:179], v162 offset:3072
	v_readfirstlane_b32 s40, v158
	s_add_i32 s39, s15, 0xffffff00
	s_mov_b32 m0, s40
	v_readfirstlane_b32 s40, v161
	ds_read_b128 v[180:183], v137
	ds_read_b128 v[184:187], v137 offset:1024
	ds_read_b128 v[188:191], v136
	ds_read_b128 v[192:195], v136 offset:1024
	ds_read_b128 v[196:199], v135
	ds_read_b128 v[200:203], v135 offset:1024
	ds_read_b128 v[204:207], v134
	ds_read_b128 v[208:211], v134 offset:1024
	buffer_load_dwordx4 v141, s[8:11], s39 offen lds
	s_mov_b32 m0, s40
	s_nop 0
	buffer_load_dwordx4 v143, s[8:11], s39 offen lds
	s_waitcnt lgkmcnt(8)
	s_barrier
	s_waitcnt lgkmcnt(0)
	s_setprio 1
	s_waitcnt lgkmcnt(7)
	v_mfma_f32_16x16x32_bf16 v[126:129], v[180:183], v[164:167], v[126:129]
	v_mfma_f32_16x16x32_bf16 v[122:125], v[180:183], v[172:175], v[122:125]
	s_waitcnt lgkmcnt(5)
	v_mfma_f32_16x16x32_bf16 v[118:121], v[188:191], v[164:167], v[118:121]
	v_mfma_f32_16x16x32_bf16 v[114:117], v[188:191], v[172:175], v[114:117]
	s_waitcnt lgkmcnt(3)
	v_mfma_f32_16x16x32_bf16 v[110:113], v[196:199], v[164:167], v[110:113]
	v_mfma_f32_16x16x32_bf16 v[106:109], v[196:199], v[172:175], v[106:109]
	s_waitcnt lgkmcnt(1)
	v_mfma_f32_16x16x32_bf16 v[102:105], v[204:207], v[164:167], v[102:105]
	v_mfma_f32_16x16x32_bf16 v[98:101], v[204:207], v[172:175], v[98:101]
	v_mfma_f32_16x16x32_bf16 v[126:129], v[184:187], v[168:171], v[126:129]
	v_mfma_f32_16x16x32_bf16 v[122:125], v[184:187], v[176:179], v[122:125]
	v_mfma_f32_16x16x32_bf16 v[118:121], v[192:195], v[168:171], v[118:121]
	v_mfma_f32_16x16x32_bf16 v[114:117], v[192:195], v[176:179], v[114:117]
	v_mfma_f32_16x16x32_bf16 v[110:113], v[200:203], v[168:171], v[110:113]
	v_mfma_f32_16x16x32_bf16 v[106:109], v[200:203], v[176:179], v[106:109]
	s_waitcnt lgkmcnt(0)
	v_mfma_f32_16x16x32_bf16 v[102:105], v[208:211], v[168:171], v[102:105]
	v_mfma_f32_16x16x32_bf16 v[98:101], v[208:211], v[176:179], v[98:101]
	s_setprio 0
	s_barrier
	v_readfirstlane_b32 s40, v145
	s_add_i32 s39, s15, 0xfff7ff80
	s_mov_b32 m0, s40
	v_readfirstlane_b32 s40, v146
	ds_read_b128 v[212:215], v156
	ds_read_b128 v[216:219], v156 offset:1024
	ds_read_b128 v[220:223], v156 offset:2048
	ds_read_b128 v[224:227], v156 offset:3072
	buffer_load_dwordx4 v141, s[4:7], s39 offen lds
	s_mov_b32 m0, s40
	s_nop 0
	buffer_load_dwordx4 v143, s[4:7], s39 offen lds
	s_barrier
	s_waitcnt lgkmcnt(0)
	s_setprio 1
	s_waitcnt lgkmcnt(3)
	v_mfma_f32_16x16x32_bf16 v[94:97], v[180:183], v[212:215], v[94:97]
	s_waitcnt lgkmcnt(1)
	v_mfma_f32_16x16x32_bf16 v[90:93], v[180:183], v[220:223], v[90:93]
	v_mfma_f32_16x16x32_bf16 v[86:89], v[188:191], v[212:215], v[86:89]
	v_mfma_f32_16x16x32_bf16 v[82:85], v[188:191], v[220:223], v[82:85]
	v_mfma_f32_16x16x32_bf16 v[78:81], v[196:199], v[212:215], v[78:81]
	v_mfma_f32_16x16x32_bf16 v[74:77], v[196:199], v[220:223], v[74:77]
	v_mfma_f32_16x16x32_bf16 v[70:73], v[204:207], v[212:215], v[70:73]
	v_mfma_f32_16x16x32_bf16 v[66:69], v[204:207], v[220:223], v[66:69]
	v_mfma_f32_16x16x32_bf16 v[94:97], v[184:187], v[216:219], v[94:97]
	s_waitcnt lgkmcnt(0)
	v_mfma_f32_16x16x32_bf16 v[90:93], v[184:187], v[224:227], v[90:93]
	v_mfma_f32_16x16x32_bf16 v[86:89], v[192:195], v[216:219], v[86:89]
	v_mfma_f32_16x16x32_bf16 v[82:85], v[192:195], v[224:227], v[82:85]
	v_mfma_f32_16x16x32_bf16 v[78:81], v[200:203], v[216:219], v[78:81]
	v_mfma_f32_16x16x32_bf16 v[74:77], v[200:203], v[224:227], v[74:77]
	v_mfma_f32_16x16x32_bf16 v[70:73], v[208:211], v[216:219], v[70:73]
	v_mfma_f32_16x16x32_bf16 v[66:69], v[208:211], v[224:227], v[66:69]
	s_setprio 0
	v_readfirstlane_b32 s40, v147
	s_mov_b32 m0, s40
	v_readfirstlane_b32 s40, v148
	s_barrier
	ds_read_b128 v[180:183], v137 offset:16384
	ds_read_b128 v[184:187], v137 offset:17408
	ds_read_b128 v[188:191], v136 offset:16384
	ds_read_b128 v[192:195], v136 offset:17408
	ds_read_b128 v[196:199], v135 offset:16384
	ds_read_b128 v[200:203], v135 offset:17408
	ds_read_b128 v[204:207], v134 offset:16384
	ds_read_b128 v[208:211], v134 offset:17408
	buffer_load_dwordx4 v141, s[8:11], s39 offen lds
	s_mov_b32 m0, s40
	s_nop 0
	buffer_load_dwordx4 v143, s[8:11], s39 offen lds
	s_barrier
	s_waitcnt lgkmcnt(0)
	s_setprio 1
	s_waitcnt lgkmcnt(7)
	v_mfma_f32_16x16x32_bf16 v[62:65], v[180:183], v[164:167], v[62:65]
	v_mfma_f32_16x16x32_bf16 v[58:61], v[180:183], v[172:175], v[58:61]
	s_waitcnt lgkmcnt(5)
	v_mfma_f32_16x16x32_bf16 v[54:57], v[188:191], v[164:167], v[54:57]
	v_mfma_f32_16x16x32_bf16 v[50:53], v[188:191], v[172:175], v[50:53]
	s_waitcnt lgkmcnt(3)
	v_mfma_f32_16x16x32_bf16 v[46:49], v[196:199], v[164:167], v[46:49]
	v_mfma_f32_16x16x32_bf16 v[42:45], v[196:199], v[172:175], v[42:45]
	s_waitcnt lgkmcnt(1)
	v_mfma_f32_16x16x32_bf16 v[38:41], v[204:207], v[164:167], v[38:41]
	v_mfma_f32_16x16x32_bf16 v[34:37], v[204:207], v[172:175], v[34:37]
	v_mfma_f32_16x16x32_bf16 v[62:65], v[184:187], v[168:171], v[62:65]
	v_mfma_f32_16x16x32_bf16 v[58:61], v[184:187], v[176:179], v[58:61]
	v_mfma_f32_16x16x32_bf16 v[54:57], v[192:195], v[168:171], v[54:57]
	v_mfma_f32_16x16x32_bf16 v[50:53], v[192:195], v[176:179], v[50:53]
	v_mfma_f32_16x16x32_bf16 v[46:49], v[200:203], v[168:171], v[46:49]
	v_mfma_f32_16x16x32_bf16 v[42:45], v[200:203], v[176:179], v[42:45]
	s_waitcnt lgkmcnt(0)
	v_mfma_f32_16x16x32_bf16 v[38:41], v[208:211], v[168:171], v[38:41]
	v_mfma_f32_16x16x32_bf16 v[34:37], v[208:211], v[176:179], v[34:37]
	s_setprio 0
	s_barrier
; #define STAGE(P, BASE, LD, br, kt) do { const int _so = (int)(((br) * (LD) + (kt) * BK) * 2); \
;     _Pragma("unroll") for (int _i = 0; _i < 2; ++_i) { \
;       __builtin_amdgcn_raw_ptr_buffer_load_lds(rs##BASE, (__attribute__((address_space(3))) unsigned*)((char*)(P) + tid_ * 16 + _i * 8192), 16, (int)off##LD[_i], _so, 0, 0); } } while (0)
; #define LDA_(dst, b, h) _Pragma("unroll") for (int m = 0; m < 4; ++m) _Pragma("unroll") for (int k = 0; k < 2; ++k) \
;     dst[m][k] = *reinterpret_cast<const bf16x8*>((char*)SA(b, h) + lds_byte(wr * 64 + m * 16 + fr, k * 32 + fq * 8))
; #define LDB_(dst, b, h) _Pragma("unroll") for (int n = 0; n < 2; ++n) _Pragma("unroll") for (int k = 0; k < 2; ++k) \
;     dst[n][k] = *reinterpret_cast<const bf16x8*>((char*)SB(b, h) + lds_byte(wc * 32 + n * 16 + fr, k * 32 + fq * 8))
; #define MMA(ai, bj, At, Bx) do { __builtin_amdgcn_s_setprio(1); \
;     _Pragma("unroll") for (int m = 0; m < 4; ++m) _Pragma("unroll") for (int n = 0; n < 2; ++n) _Pragma("unroll") for (int k = 0; k < 2; ++k) \
;       acc[ai][bj][m][n] = __builtin_amdgcn_mfma_f32_16x16x32_bf16(At[m][k], Bx[n][k], acc[ai][bj][m][n], 0, 0, 0); \
;     __builtin_amdgcn_s_setprio(0); } while (0)
; #define WAIT_V(n) asm volatile("s_waitcnt vmcnt(" #n ")" ::: "memory")
; #define WAIT_L(n) asm volatile("s_waitcnt lgkmcnt(" #n ")" ::: "memory")
; #define BAR __builtin_amdgcn_s_barrier()
; #define SCHED __builtin_amdgcn_sched_barrier(0)
; template <int K, int LDA, int LDB>
; DEVI void gemm_tile(const bf16* __restrict__ A, const bf16* __restrict__ Bt, bf16* shm, acc_t& acc) {
;     ...
;     STAGE(SB(0, 1), Bt, LDB, HALF, t + 2);
;     WAIT_V(6); BAR; MMA(1, 1, At, B1); BAR;
;     LDB_(B0, 1, 0); SCHED; LDA_(At, 1, 0); STAGE(SA(0, 1), A, LDA, HALF, t + 2);
;     WAIT_L(8); BAR; WAIT_L(0); MMA(0, 0, At, B0); BAR; SCHED;
;     LDB_(B1, 1, 1); STAGE(SB(1, 0), Bt, LDB, 0, t + 3);
;     BAR; WAIT_L(0); MMA(0, 1, At, B1); BAR;
;     LDA_(At, 1, 1); STAGE(SA(1, 0), A, LDA, 0, t + 3);
	v_readfirstlane_b32 s40, v149
	s_add_i32 s39, s15, 0xffffff80
	s_mov_b32 m0, s40
	v_readfirstlane_b32 s40, v150
	buffer_load_dwordx4 v141, s[4:7], s39 offen lds
	s_mov_b32 m0, s40
	s_nop 0
	buffer_load_dwordx4 v143, s[4:7], s39 offen lds
	s_waitcnt vmcnt(6)
	s_barrier
	s_setprio 1
	v_mfma_f32_16x16x32_bf16 v[30:33], v[180:183], v[212:215], v[30:33]
	v_mfma_f32_16x16x32_bf16 v[26:29], v[180:183], v[220:223], v[26:29]
	v_mfma_f32_16x16x32_bf16 v[22:25], v[188:191], v[212:215], v[22:25]
	v_mfma_f32_16x16x32_bf16 v[18:21], v[188:191], v[220:223], v[18:21]
	v_mfma_f32_16x16x32_bf16 v[14:17], v[196:199], v[212:215], v[14:17]
	v_mfma_f32_16x16x32_bf16 v[10:13], v[196:199], v[220:223], v[10:13]
	v_mfma_f32_16x16x32_bf16 v[6:9], v[204:207], v[212:215], v[6:9]
	v_mfma_f32_16x16x32_bf16 v[2:5], v[204:207], v[220:223], v[2:5]
	v_mfma_f32_16x16x32_bf16 v[30:33], v[184:187], v[216:219], v[30:33]
	v_mfma_f32_16x16x32_bf16 v[26:29], v[184:187], v[224:227], v[26:29]
	v_mfma_f32_16x16x32_bf16 v[22:25], v[192:195], v[216:219], v[22:25]
	v_mfma_f32_16x16x32_bf16 v[18:21], v[192:195], v[224:227], v[18:21]
	v_mfma_f32_16x16x32_bf16 v[14:17], v[200:203], v[216:219], v[14:17]
	v_mfma_f32_16x16x32_bf16 v[10:13], v[200:203], v[224:227], v[10:13]
	v_mfma_f32_16x16x32_bf16 v[6:9], v[208:211], v[216:219], v[6:9]
	v_mfma_f32_16x16x32_bf16 v[2:5], v[208:211], v[224:227], v[2:5]
	s_setprio 0
	s_barrier
	ds_read_b128 v[164:167], v144
	ds_read_b128 v[168:171], v144 offset:1024
	ds_read_b128 v[172:175], v144 offset:2048
	ds_read_b128 v[176:179], v144 offset:3072
	v_readfirstlane_b32 s40, v151
	s_mov_b32 m0, s40
	v_readfirstlane_b32 s40, v152
	ds_read_b128 v[180:183], v137 offset:32768
	ds_read_b128 v[184:187], v137 offset:33792
	ds_read_b128 v[188:191], v136 offset:32768
	ds_read_b128 v[192:195], v136 offset:33792
	ds_read_b128 v[196:199], v135 offset:32768
	ds_read_b128 v[200:203], v135 offset:33792
	ds_read_b128 v[204:207], v134 offset:32768
	ds_read_b128 v[208:211], v134 offset:33792
	buffer_load_dwordx4 v141, s[8:11], s39 offen lds
	s_mov_b32 m0, s40
	s_nop 0
	buffer_load_dwordx4 v143, s[8:11], s39 offen lds
	s_waitcnt lgkmcnt(8)
	s_barrier
	s_waitcnt lgkmcnt(0)
	s_setprio 1
	s_waitcnt lgkmcnt(7)
	v_mfma_f32_16x16x32_bf16 v[126:129], v[180:183], v[164:167], v[126:129]
	v_mfma_f32_16x16x32_bf16 v[122:125], v[180:183], v[172:175], v[122:125]
	s_waitcnt lgkmcnt(5)
	v_mfma_f32_16x16x32_bf16 v[118:121], v[188:191], v[164:167], v[118:121]
	v_mfma_f32_16x16x32_bf16 v[114:117], v[188:191], v[172:175], v[114:117]
	s_waitcnt lgkmcnt(3)
	v_mfma_f32_16x16x32_bf16 v[110:113], v[196:199], v[164:167], v[110:113]
	v_mfma_f32_16x16x32_bf16 v[106:109], v[196:199], v[172:175], v[106:109]
	s_waitcnt lgkmcnt(1)
	v_mfma_f32_16x16x32_bf16 v[102:105], v[204:207], v[164:167], v[102:105]
	v_mfma_f32_16x16x32_bf16 v[98:101], v[204:207], v[172:175], v[98:101]
	v_mfma_f32_16x16x32_bf16 v[126:129], v[184:187], v[168:171], v[126:129]
	v_mfma_f32_16x16x32_bf16 v[122:125], v[184:187], v[176:179], v[122:125]
	v_mfma_f32_16x16x32_bf16 v[118:121], v[192:195], v[168:171], v[118:121]
	v_mfma_f32_16x16x32_bf16 v[114:117], v[192:195], v[176:179], v[114:117]
	v_mfma_f32_16x16x32_bf16 v[110:113], v[200:203], v[168:171], v[110:113]
	v_mfma_f32_16x16x32_bf16 v[106:109], v[200:203], v[176:179], v[106:109]
	s_waitcnt lgkmcnt(0)
	v_mfma_f32_16x16x32_bf16 v[102:105], v[208:211], v[168:171], v[102:105]
	v_mfma_f32_16x16x32_bf16 v[98:101], v[208:211], v[176:179], v[98:101]
	s_setprio 0
	s_barrier
	v_readfirstlane_b32 s40, v153
	s_add_i32 s39, s15, 0xfff80000
	s_mov_b32 m0, s40
	v_readfirstlane_b32 s40, v154
	ds_read_b128 v[212:215], v142
	ds_read_b128 v[216:219], v142 offset:1024
	ds_read_b128 v[220:223], v142 offset:2048
	ds_read_b128 v[224:227], v142 offset:3072
	buffer_load_dwordx4 v141, s[4:7], s39 offen lds
	s_mov_b32 m0, s40
	s_nop 0
	buffer_load_dwordx4 v143, s[4:7], s39 offen lds
	s_barrier
	s_waitcnt lgkmcnt(0)
	s_setprio 1
	s_waitcnt lgkmcnt(3)
	v_mfma_f32_16x16x32_bf16 v[94:97], v[180:183], v[212:215], v[94:97]
	s_waitcnt lgkmcnt(1)
	v_mfma_f32_16x16x32_bf16 v[90:93], v[180:183], v[220:223], v[90:93]
	v_mfma_f32_16x16x32_bf16 v[86:89], v[188:191], v[212:215], v[86:89]
	v_mfma_f32_16x16x32_bf16 v[82:85], v[188:191], v[220:223], v[82:85]
	v_mfma_f32_16x16x32_bf16 v[78:81], v[196:199], v[212:215], v[78:81]
	v_mfma_f32_16x16x32_bf16 v[74:77], v[196:199], v[220:223], v[74:77]
	v_mfma_f32_16x16x32_bf16 v[70:73], v[204:207], v[212:215], v[70:73]
	v_mfma_f32_16x16x32_bf16 v[66:69], v[204:207], v[220:223], v[66:69]
	v_mfma_f32_16x16x32_bf16 v[94:97], v[184:187], v[216:219], v[94:97]
	s_waitcnt lgkmcnt(0)
	v_mfma_f32_16x16x32_bf16 v[90:93], v[184:187], v[224:227], v[90:93]
	v_mfma_f32_16x16x32_bf16 v[86:89], v[192:195], v[216:219], v[86:89]
	v_mfma_f32_16x16x32_bf16 v[82:85], v[192:195], v[224:227], v[82:85]
	v_mfma_f32_16x16x32_bf16 v[78:81], v[200:203], v[216:219], v[78:81]
	v_mfma_f32_16x16x32_bf16 v[74:77], v[200:203], v[224:227], v[74:77]
	v_mfma_f32_16x16x32_bf16 v[70:73], v[208:211], v[216:219], v[70:73]
	v_mfma_f32_16x16x32_bf16 v[66:69], v[208:211], v[224:227], v[66:69]
	s_setprio 0
	v_readfirstlane_b32 s40, v155
	s_mov_b32 m0, s40
	v_readfirstlane_b32 s40, v157
	s_barrier
	ds_read_b128 v[180:183], v137 offset:49152
	ds_read_b128 v[184:187], v137 offset:50176
	ds_read_b128 v[188:191], v136 offset:49152
	ds_read_b128 v[192:195], v136 offset:50176
	ds_read_b128 v[196:199], v135 offset:49152
	ds_read_b128 v[200:203], v135 offset:50176
	ds_read_b128 v[204:207], v134 offset:49152
	ds_read_b128 v[208:211], v134 offset:50176
	buffer_load_dwordx4 v141, s[8:11], s39 offen lds
	s_mov_b32 m0, s40
	s_nop 0
	buffer_load_dwordx4 v143, s[8:11], s39 offen lds
	s_barrier
; #define STAGE(P, BASE, LD, br, kt) do { const int _so = (int)(((br) * (LD) + (kt) * BK) * 2); \
;     _Pragma("unroll") for (int _i = 0; _i < 2; ++_i) { \
;       __builtin_amdgcn_raw_ptr_buffer_load_lds(rs##BASE, (__attribute__((address_space(3))) unsigned*)((char*)(P) + tid_ * 16 + _i * 8192), 16, (int)off##LD[_i], _so, 0, 0); } } while (0)
; #define LDA_(dst, b, h) _Pragma("unroll") for (int m = 0; m < 4; ++m) _Pragma("unroll") for (int k = 0; k < 2; ++k) \
;     dst[m][k] = *reinterpret_cast<const bf16x8*>((char*)SA(b, h) + lds_byte(wr * 64 + m * 16 + fr, k * 32 + fq * 8))
; #define LDB_(dst, b, h) _Pragma("unroll") for (int n = 0; n < 2; ++n) _Pragma("unroll") for (int k = 0; k < 2; ++k) \
;     dst[n][k] = *reinterpret_cast<const bf16x8*>((char*)SB(b, h) + lds_byte(wc * 32 + n * 16 + fr, k * 32 + fq * 8))
; #define MMA(ai, bj, At, Bx) do { __builtin_amdgcn_s_setprio(1); \
;     _Pragma("unroll") for (int m = 0; m < 4; ++m) _Pragma("unroll") for (int n = 0; n < 2; ++n) _Pragma("unroll") for (int k = 0; k < 2; ++k) \
;       acc[ai][bj][m][n] = __builtin_amdgcn_mfma_f32_16x16x32_bf16(At[m][k], Bx[n][k], acc[ai][bj][m][n], 0, 0, 0); \
;     __builtin_amdgcn_s_setprio(0); } while (0)
; #define WAIT_V(n) asm volatile("s_waitcnt vmcnt(" #n ")" ::: "memory")
; #define WAIT_L(n) asm volatile("s_waitcnt lgkmcnt(" #n ")" ::: "memory")
; #define BAR __builtin_amdgcn_s_barrier()
; #define SCHED __builtin_amdgcn_sched_barrier(0)
; template <int K, int LDA, int LDB>
; DEVI void gemm_tile(const bf16* __restrict__ A, const bf16* __restrict__ Bt, bf16* shm, acc_t& acc) {
;     ...
;     BAR; WAIT_L(0); MMA(1, 0, At, B0); BAR; SCHED;
;     STAGE(SB(1, 1), Bt, LDB, HALF, t + 3);
;     WAIT_V(6); BAR; MMA(1, 1, At, B1); BAR;
;   }
;   { LDB_(B0, 0, 0); LDA_(At, 0, 0); STAGE(SA(1, 1), A, LDA, HALF, nt - 1);
;     BAR; WAIT_L(0); MMA(0, 0, At, B0); BAR;
;     LDB_(B1, 0, 1); BAR; WAIT_L(0); MMA(0, 1, At, B1); BAR;
	s_waitcnt lgkmcnt(0)
	s_setprio 1
	s_waitcnt lgkmcnt(7)
	v_mfma_f32_16x16x32_bf16 v[62:65], v[180:183], v[164:167], v[62:65]
	v_mfma_f32_16x16x32_bf16 v[58:61], v[180:183], v[172:175], v[58:61]
	s_waitcnt lgkmcnt(5)
	v_mfma_f32_16x16x32_bf16 v[54:57], v[188:191], v[164:167], v[54:57]
	v_mfma_f32_16x16x32_bf16 v[50:53], v[188:191], v[172:175], v[50:53]
	s_waitcnt lgkmcnt(3)
	v_mfma_f32_16x16x32_bf16 v[46:49], v[196:199], v[164:167], v[46:49]
	v_mfma_f32_16x16x32_bf16 v[42:45], v[196:199], v[172:175], v[42:45]
	s_waitcnt lgkmcnt(1)
	v_mfma_f32_16x16x32_bf16 v[38:41], v[204:207], v[164:167], v[38:41]
	v_mfma_f32_16x16x32_bf16 v[34:37], v[204:207], v[172:175], v[34:37]
	v_mfma_f32_16x16x32_bf16 v[62:65], v[184:187], v[168:171], v[62:65]
	v_mfma_f32_16x16x32_bf16 v[58:61], v[184:187], v[176:179], v[58:61]
	v_mfma_f32_16x16x32_bf16 v[54:57], v[192:195], v[168:171], v[54:57]
	v_mfma_f32_16x16x32_bf16 v[50:53], v[192:195], v[176:179], v[50:53]
	v_mfma_f32_16x16x32_bf16 v[46:49], v[200:203], v[168:171], v[46:49]
	v_mfma_f32_16x16x32_bf16 v[42:45], v[200:203], v[176:179], v[42:45]
	s_waitcnt lgkmcnt(0)
	v_mfma_f32_16x16x32_bf16 v[38:41], v[208:211], v[168:171], v[38:41]
	v_mfma_f32_16x16x32_bf16 v[34:37], v[208:211], v[176:179], v[34:37]
	s_setprio 0
	s_barrier
	v_readfirstlane_b32 s39, v159
	s_mov_b32 m0, s39
	v_readfirstlane_b32 s39, v160
	buffer_load_dwordx4 v141, s[4:7], s15 offen lds
	s_mov_b32 m0, s39
	s_nop 0
	buffer_load_dwordx4 v143, s[4:7], s15 offen lds
	s_waitcnt vmcnt(6)
	s_barrier
	s_setprio 1
	v_mfma_f32_16x16x32_bf16 v[30:33], v[180:183], v[212:215], v[30:33]
	v_mfma_f32_16x16x32_bf16 v[26:29], v[180:183], v[220:223], v[26:29]
	v_mfma_f32_16x16x32_bf16 v[22:25], v[188:191], v[212:215], v[22:25]
	v_mfma_f32_16x16x32_bf16 v[18:21], v[188:191], v[220:223], v[18:21]
	v_mfma_f32_16x16x32_bf16 v[14:17], v[196:199], v[212:215], v[14:17]
	v_mfma_f32_16x16x32_bf16 v[10:13], v[196:199], v[220:223], v[10:13]
	v_mfma_f32_16x16x32_bf16 v[6:9], v[204:207], v[212:215], v[6:9]
	v_mfma_f32_16x16x32_bf16 v[2:5], v[204:207], v[220:223], v[2:5]
	v_mfma_f32_16x16x32_bf16 v[30:33], v[184:187], v[216:219], v[30:33]
	v_mfma_f32_16x16x32_bf16 v[26:29], v[184:187], v[224:227], v[26:29]
	v_mfma_f32_16x16x32_bf16 v[22:25], v[192:195], v[216:219], v[22:25]
	v_mfma_f32_16x16x32_bf16 v[18:21], v[192:195], v[224:227], v[18:21]
	v_mfma_f32_16x16x32_bf16 v[14:17], v[200:203], v[216:219], v[14:17]
	v_mfma_f32_16x16x32_bf16 v[10:13], v[200:203], v[224:227], v[10:13]
	v_mfma_f32_16x16x32_bf16 v[6:9], v[208:211], v[216:219], v[6:9]
	v_mfma_f32_16x16x32_bf16 v[2:5], v[208:211], v[224:227], v[2:5]
	s_setprio 0
	s_add_i32 s13, s13, 2
	s_addk_i32 s15, 0x100
	s_cmp_lt_u32 s13, 28
	s_cbranch_scc1 .Lrot_41224
	s_barrier
	v_readfirstlane_b32 s4, v158
	s_mov_b32 s10, s6
	s_mov_b32 s11, s7
	s_mov_b32 m0, s4
	v_readfirstlane_b32 s4, v161
	ds_read_b128 v[146:149], v162
	ds_read_b128 v[150:153], v162 offset:1024
	ds_read_b128 v[164:167], v162 offset:2048
	ds_read_b128 v[168:171], v162 offset:3072
	ds_read_b128 v[172:175], v137
	ds_read_b128 v[176:179], v137 offset:1024
	ds_read_b128 v[180:183], v136
	ds_read_b128 v[184:187], v136 offset:1024
	ds_read_b128 v[188:191], v135
	ds_read_b128 v[192:195], v135 offset:1024
	ds_read_b128 v[196:199], v134
	ds_read_b128 v[200:203], v134 offset:1024
	buffer_load_dwordx4 v141, s[8:11], s36 offen lds
	s_mov_b32 m0, s4
	s_nop 0
	buffer_load_dwordx4 v143, s[8:11], s36 offen lds
	s_barrier
	s_waitcnt lgkmcnt(0)
	s_setprio 1
	s_waitcnt lgkmcnt(7)
	v_mfma_f32_16x16x32_bf16 v[126:129], v[172:175], v[146:149], v[126:129]
	v_mfma_f32_16x16x32_bf16 v[122:125], v[172:175], v[164:167], v[122:125]
	s_waitcnt lgkmcnt(5)
	v_mfma_f32_16x16x32_bf16 v[118:121], v[180:183], v[146:149], v[118:121]
	v_mfma_f32_16x16x32_bf16 v[114:117], v[180:183], v[164:167], v[114:117]
	s_waitcnt lgkmcnt(3)
	v_mfma_f32_16x16x32_bf16 v[110:113], v[188:191], v[146:149], v[110:113]
	v_mfma_f32_16x16x32_bf16 v[106:109], v[188:191], v[164:167], v[106:109]
	s_waitcnt lgkmcnt(1)
	v_mfma_f32_16x16x32_bf16 v[102:105], v[196:199], v[146:149], v[102:105]
	v_mfma_f32_16x16x32_bf16 v[98:101], v[196:199], v[164:167], v[98:101]
	v_mfma_f32_16x16x32_bf16 v[126:129], v[176:179], v[150:153], v[126:129]
	v_mfma_f32_16x16x32_bf16 v[122:125], v[176:179], v[168:171], v[122:125]
	v_mfma_f32_16x16x32_bf16 v[118:121], v[184:187], v[150:153], v[118:121]
	v_mfma_f32_16x16x32_bf16 v[114:117], v[184:187], v[168:171], v[114:117]
	v_mfma_f32_16x16x32_bf16 v[110:113], v[192:195], v[150:153], v[110:113]
	v_mfma_f32_16x16x32_bf16 v[106:109], v[192:195], v[168:171], v[106:109]
	s_waitcnt lgkmcnt(0)
	v_mfma_f32_16x16x32_bf16 v[102:105], v[200:203], v[150:153], v[102:105]
	v_mfma_f32_16x16x32_bf16 v[98:101], v[200:203], v[168:171], v[98:101]
	s_setprio 0
	s_barrier
	ds_read_b128 v[158:161], v156
	ds_read_b128 v[204:207], v156 offset:1024
	ds_read_b128 v[208:211], v156 offset:2048
	ds_read_b128 v[154:157], v156 offset:3072
	s_barrier
	s_waitcnt lgkmcnt(0)
	s_setprio 1
	s_waitcnt lgkmcnt(3)
	v_mfma_f32_16x16x32_bf16 v[94:97], v[172:175], v[158:161], v[94:97]
	s_waitcnt lgkmcnt(1)
	v_mfma_f32_16x16x32_bf16 v[90:93], v[172:175], v[208:211], v[90:93]
	v_mfma_f32_16x16x32_bf16 v[86:89], v[180:183], v[158:161], v[86:89]
	v_mfma_f32_16x16x32_bf16 v[82:85], v[180:183], v[208:211], v[82:85]
	v_mfma_f32_16x16x32_bf16 v[78:81], v[188:191], v[158:161], v[78:81]
	v_mfma_f32_16x16x32_bf16 v[74:77], v[188:191], v[208:211], v[74:77]
	v_mfma_f32_16x16x32_bf16 v[70:73], v[196:199], v[158:161], v[70:73]
	v_mfma_f32_16x16x32_bf16 v[66:69], v[196:199], v[208:211], v[66:69]
	v_mfma_f32_16x16x32_bf16 v[94:97], v[176:179], v[204:207], v[94:97]
	s_waitcnt lgkmcnt(0)
	v_mfma_f32_16x16x32_bf16 v[90:93], v[176:179], v[154:157], v[90:93]
	v_mfma_f32_16x16x32_bf16 v[86:89], v[184:187], v[204:207], v[86:89]
	v_mfma_f32_16x16x32_bf16 v[82:85], v[184:187], v[154:157], v[82:85]
	v_mfma_f32_16x16x32_bf16 v[78:81], v[192:195], v[204:207], v[78:81]
	v_mfma_f32_16x16x32_bf16 v[74:77], v[192:195], v[154:157], v[74:77]
	v_mfma_f32_16x16x32_bf16 v[70:73], v[200:203], v[204:207], v[70:73]
	v_mfma_f32_16x16x32_bf16 v[66:69], v[200:203], v[154:157], v[66:69]
	s_setprio 0
	s_barrier
; #define LDA_(dst, b, h) _Pragma("unroll") for (int m = 0; m < 4; ++m) _Pragma("unroll") for (int k = 0; k < 2; ++k) \
;     dst[m][k] = *reinterpret_cast<const bf16x8*>((char*)SA(b, h) + lds_byte(wr * 64 + m * 16 + fr, k * 32 + fq * 8))
; #define LDB_(dst, b, h) _Pragma("unroll") for (int n = 0; n < 2; ++n) _Pragma("unroll") for (int k = 0; k < 2; ++k) \
;     dst[n][k] = *reinterpret_cast<const bf16x8*>((char*)SB(b, h) + lds_byte(wc * 32 + n * 16 + fr, k * 32 + fq * 8))
; #define MMA(ai, bj, At, Bx) do { __builtin_amdgcn_s_setprio(1); \
;     _Pragma("unroll") for (int m = 0; m < 4; ++m) _Pragma("unroll") for (int n = 0; n < 2; ++n) _Pragma("unroll") for (int k = 0; k < 2; ++k) \
;       acc[ai][bj][m][n] = __builtin_amdgcn_mfma_f32_16x16x32_bf16(At[m][k], Bx[n][k], acc[ai][bj][m][n], 0, 0, 0); \
;     __builtin_amdgcn_s_setprio(0); } while (0)
; #define WAIT_V(n) asm volatile("s_waitcnt vmcnt(" #n ")" ::: "memory")
; #define WAIT_L(n) asm volatile("s_waitcnt lgkmcnt(" #n ")" ::: "memory")
; #define BAR __builtin_amdgcn_s_barrier()
; template <int K, int LDA, int LDB>
; DEVI void gemm_tile(const bf16* __restrict__ A, const bf16* __restrict__ Bt, bf16* shm, acc_t& acc) {
;     ...
;     LDA_(At, 0, 1); WAIT_V(4); BAR; WAIT_L(0); MMA(1, 0, At, B0); MMA(1, 1, At, B1); BAR; }
;   { LDB_(B0, 1, 0); LDA_(At, 1, 0); WAIT_V(2); BAR; WAIT_L(0); MMA(0, 0, At, B0); BAR;
	ds_read_b128 v[172:175], v137 offset:16384
	ds_read_b128 v[176:179], v137 offset:17408
	ds_read_b128 v[180:183], v136 offset:16384
	ds_read_b128 v[184:187], v136 offset:17408
	ds_read_b128 v[188:191], v135 offset:16384
	ds_read_b128 v[192:195], v135 offset:17408
	ds_read_b128 v[196:199], v134 offset:16384
	ds_read_b128 v[200:203], v134 offset:17408
	s_waitcnt vmcnt(4)
	s_barrier
	s_waitcnt lgkmcnt(0)
	s_setprio 1
	s_waitcnt lgkmcnt(7)
	v_mfma_f32_16x16x32_bf16 v[58:61], v[172:175], v[164:167], v[58:61]
	s_waitcnt lgkmcnt(5)
	v_mfma_f32_16x16x32_bf16 v[54:57], v[180:183], v[146:149], v[54:57]
	v_mfma_f32_16x16x32_bf16 v[50:53], v[180:183], v[164:167], v[50:53]
	s_waitcnt lgkmcnt(3)
	v_mfma_f32_16x16x32_bf16 v[46:49], v[188:191], v[146:149], v[46:49]
	v_mfma_f32_16x16x32_bf16 v[42:45], v[188:191], v[164:167], v[42:45]
	s_waitcnt lgkmcnt(1)
	v_mfma_f32_16x16x32_bf16 v[38:41], v[196:199], v[146:149], v[38:41]
	v_mfma_f32_16x16x32_bf16 v[34:37], v[196:199], v[164:167], v[34:37]
	v_mfma_f32_16x16x32_bf16 v[62:65], v[172:175], v[146:149], v[62:65]
	v_mfma_f32_16x16x32_bf16 v[58:61], v[176:179], v[168:171], v[58:61]
	v_mfma_f32_16x16x32_bf16 v[54:57], v[184:187], v[150:153], v[54:57]
	v_mfma_f32_16x16x32_bf16 v[50:53], v[184:187], v[168:171], v[50:53]
	v_mfma_f32_16x16x32_bf16 v[46:49], v[192:195], v[150:153], v[46:49]
	v_mfma_f32_16x16x32_bf16 v[42:45], v[192:195], v[168:171], v[42:45]
	s_waitcnt lgkmcnt(0)
	v_mfma_f32_16x16x32_bf16 v[38:41], v[200:203], v[150:153], v[38:41]
	v_mfma_f32_16x16x32_bf16 v[34:37], v[200:203], v[168:171], v[34:37]
	v_mfma_f32_16x16x32_bf16 v[212:215], v[176:179], v[150:153], v[62:65]
	s_setprio 0
	s_setprio 1
	v_mfma_f32_16x16x32_bf16 v[30:33], v[172:175], v[158:161], v[30:33]
	v_mfma_f32_16x16x32_bf16 v[26:29], v[172:175], v[208:211], v[26:29]
	v_mfma_f32_16x16x32_bf16 v[22:25], v[180:183], v[158:161], v[22:25]
	v_mfma_f32_16x16x32_bf16 v[18:21], v[180:183], v[208:211], v[18:21]
	v_mfma_f32_16x16x32_bf16 v[14:17], v[188:191], v[158:161], v[14:17]
	v_mfma_f32_16x16x32_bf16 v[10:13], v[188:191], v[208:211], v[10:13]
	v_mfma_f32_16x16x32_bf16 v[6:9], v[196:199], v[158:161], v[6:9]
	v_mfma_f32_16x16x32_bf16 v[2:5], v[196:199], v[208:211], v[2:5]
	v_mfma_f32_16x16x32_bf16 v[30:33], v[176:179], v[204:207], v[30:33]
	v_mfma_f32_16x16x32_bf16 v[26:29], v[176:179], v[154:157], v[26:29]
	v_mfma_f32_16x16x32_bf16 v[22:25], v[184:187], v[204:207], v[22:25]
	v_mfma_f32_16x16x32_bf16 v[18:21], v[184:187], v[154:157], v[18:21]
	v_mfma_f32_16x16x32_bf16 v[14:17], v[192:195], v[204:207], v[14:17]
	v_mfma_f32_16x16x32_bf16 v[10:13], v[192:195], v[154:157], v[10:13]
	v_mfma_f32_16x16x32_bf16 v[6:9], v[200:203], v[204:207], v[6:9]
	v_mfma_f32_16x16x32_bf16 v[2:5], v[200:203], v[154:157], v[2:5]
	s_setprio 0
	s_barrier
	ds_read_b128 v[146:149], v144
	ds_read_b128 v[150:153], v144 offset:1024
	ds_read_b128 v[154:157], v144 offset:2048
	ds_read_b128 v[158:161], v144 offset:3072
	ds_read_b128 v[62:65], v137 offset:32768
	ds_read_b128 v[162:165], v137 offset:33792
	ds_read_b128 v[166:169], v136 offset:32768
	ds_read_b128 v[170:173], v136 offset:33792
	ds_read_b128 v[174:177], v135 offset:32768
	ds_read_b128 v[178:181], v135 offset:33792
	ds_read_b128 v[182:185], v134 offset:32768
	ds_read_b128 v[186:189], v134 offset:33792
	s_waitcnt vmcnt(2)
	s_barrier
	s_waitcnt lgkmcnt(0)
	s_setprio 1
	s_waitcnt lgkmcnt(7)
	v_mfma_f32_16x16x32_bf16 v[126:129], v[62:65], v[146:149], v[126:129]
	v_mfma_f32_16x16x32_bf16 v[122:125], v[62:65], v[154:157], v[122:125]
	s_waitcnt lgkmcnt(5)
	v_mfma_f32_16x16x32_bf16 v[118:121], v[166:169], v[146:149], v[118:121]
	v_mfma_f32_16x16x32_bf16 v[114:117], v[166:169], v[154:157], v[114:117]
	s_waitcnt lgkmcnt(3)
	v_mfma_f32_16x16x32_bf16 v[110:113], v[174:177], v[146:149], v[110:113]
	v_mfma_f32_16x16x32_bf16 v[106:109], v[174:177], v[154:157], v[106:109]
	s_waitcnt lgkmcnt(1)
	v_mfma_f32_16x16x32_bf16 v[102:105], v[182:185], v[146:149], v[102:105]
	v_mfma_f32_16x16x32_bf16 v[98:101], v[182:185], v[154:157], v[98:101]
	v_mfma_f32_16x16x32_bf16 v[126:129], v[162:165], v[150:153], v[126:129]
	v_mfma_f32_16x16x32_bf16 v[122:125], v[162:165], v[158:161], v[122:125]
	v_mfma_f32_16x16x32_bf16 v[118:121], v[170:173], v[150:153], v[118:121]
	v_mfma_f32_16x16x32_bf16 v[114:117], v[170:173], v[158:161], v[114:117]
	v_mfma_f32_16x16x32_bf16 v[110:113], v[178:181], v[150:153], v[110:113]
	v_mfma_f32_16x16x32_bf16 v[106:109], v[178:181], v[158:161], v[106:109]
	s_waitcnt lgkmcnt(0)
	v_mfma_f32_16x16x32_bf16 v[102:105], v[186:189], v[150:153], v[102:105]
	v_mfma_f32_16x16x32_bf16 v[98:101], v[186:189], v[158:161], v[98:101]
	s_setprio 0
	s_barrier
; #define LDA_(dst, b, h) _Pragma("unroll") for (int m = 0; m < 4; ++m) _Pragma("unroll") for (int k = 0; k < 2; ++k) \
;     dst[m][k] = *reinterpret_cast<const bf16x8*>((char*)SA(b, h) + lds_byte(wr * 64 + m * 16 + fr, k * 32 + fq * 8))
; #define LDB_(dst, b, h) _Pragma("unroll") for (int n = 0; n < 2; ++n) _Pragma("unroll") for (int k = 0; k < 2; ++k) \
;     dst[n][k] = *reinterpret_cast<const bf16x8*>((char*)SB(b, h) + lds_byte(wc * 32 + n * 16 + fr, k * 32 + fq * 8))
; #define MMA(ai, bj, At, Bx) do { __builtin_amdgcn_s_setprio(1); \
;     _Pragma("unroll") for (int m = 0; m < 4; ++m) _Pragma("unroll") for (int n = 0; n < 2; ++n) _Pragma("unroll") for (int k = 0; k < 2; ++k) \
;       acc[ai][bj][m][n] = __builtin_amdgcn_mfma_f32_16x16x32_bf16(At[m][k], Bx[n][k], acc[ai][bj][m][n], 0, 0, 0); \
;     __builtin_amdgcn_s_setprio(0); } while (0)
; #define WAIT_V(n) asm volatile("s_waitcnt vmcnt(" #n ")" ::: "memory")
; #define WAIT_L(n) asm volatile("s_waitcnt lgkmcnt(" #n ")" ::: "memory")
; #define BAR __builtin_amdgcn_s_barrier()
; template <int K, int LDA, int LDB>
; DEVI void gemm_tile(const bf16* __restrict__ A, const bf16* __restrict__ Bt, bf16* shm, acc_t& acc) {
;     ...
;   { LDB_(B0, 1, 0); LDA_(At, 1, 0); WAIT_V(2); BAR; WAIT_L(0); MMA(0, 0, At, B0); BAR;
;     LDB_(B1, 1, 1); WAIT_V(0); BAR; WAIT_L(0); MMA(0, 1, At, B1); BAR;
;     LDA_(At, 1, 1); BAR; WAIT_L(0); MMA(1, 0, At, B0); MMA(1, 1, At, B1); BAR; }
;   if (wr == 0) BAR;
	ds_read_b128 v[190:193], v142
	ds_read_b128 v[194:197], v142 offset:1024
	ds_read_b128 v[198:201], v142 offset:2048
	ds_read_b128 v[142:145], v142 offset:3072
	s_waitcnt vmcnt(0)
	s_barrier
	s_waitcnt lgkmcnt(0)
	s_setprio 1
	s_waitcnt lgkmcnt(3)
	v_mfma_f32_16x16x32_bf16 v[94:97], v[62:65], v[190:193], v[94:97]
	s_waitcnt lgkmcnt(1)
	v_mfma_f32_16x16x32_bf16 v[62:65], v[62:65], v[198:201], v[90:93]
	s_waitcnt lgkmcnt(0)
	v_mfma_f32_16x16x32_bf16 v[90:93], v[162:165], v[142:145], v[62:65]
	v_mfma_f32_16x16x32_bf16 v[62:65], v[166:169], v[190:193], v[86:89]
	v_mfma_f32_16x16x32_bf16 v[86:89], v[170:173], v[194:197], v[62:65]
	v_mfma_f32_16x16x32_bf16 v[62:65], v[166:169], v[198:201], v[82:85]
	v_mfma_f32_16x16x32_bf16 v[82:85], v[170:173], v[142:145], v[62:65]
	v_mfma_f32_16x16x32_bf16 v[62:65], v[174:177], v[190:193], v[78:81]
	v_mfma_f32_16x16x32_bf16 v[78:81], v[178:181], v[194:197], v[62:65]
	v_mfma_f32_16x16x32_bf16 v[62:65], v[174:177], v[198:201], v[74:77]
	v_mfma_f32_16x16x32_bf16 v[74:77], v[178:181], v[142:145], v[62:65]
	v_mfma_f32_16x16x32_bf16 v[62:65], v[182:185], v[190:193], v[70:73]
	v_mfma_f32_16x16x32_bf16 v[70:73], v[186:189], v[194:197], v[62:65]
	v_mfma_f32_16x16x32_bf16 v[62:65], v[182:185], v[198:201], v[66:69]
	v_mfma_f32_16x16x32_bf16 v[94:97], v[162:165], v[194:197], v[94:97]
	v_mfma_f32_16x16x32_bf16 v[62:65], v[186:189], v[142:145], v[62:65]
	s_setprio 0
	s_barrier
	ds_read_b128 v[162:165], v137 offset:49152
	ds_read_b128 v[166:169], v137 offset:50176
	ds_read_b128 v[170:173], v136 offset:49152
	ds_read_b128 v[174:177], v136 offset:50176
	ds_read_b128 v[178:181], v135 offset:49152
	ds_read_b128 v[182:185], v135 offset:50176
	ds_read_b128 v[186:189], v134 offset:49152
	ds_read_b128 v[134:137], v134 offset:50176
	s_barrier
	s_waitcnt lgkmcnt(0)
	s_setprio 1
	s_waitcnt lgkmcnt(7)
	v_mfma_f32_16x16x32_bf16 v[66:69], v[162:165], v[146:149], v[212:215]
	v_mfma_f32_16x16x32_bf16 v[58:61], v[162:165], v[154:157], v[58:61]
	s_waitcnt lgkmcnt(5)
	v_mfma_f32_16x16x32_bf16 v[54:57], v[170:173], v[146:149], v[54:57]
	v_mfma_f32_16x16x32_bf16 v[50:53], v[170:173], v[154:157], v[50:53]
	s_waitcnt lgkmcnt(3)
	v_mfma_f32_16x16x32_bf16 v[46:49], v[178:181], v[146:149], v[46:49]
	v_mfma_f32_16x16x32_bf16 v[42:45], v[178:181], v[154:157], v[42:45]
	s_waitcnt lgkmcnt(1)
	v_mfma_f32_16x16x32_bf16 v[38:41], v[186:189], v[146:149], v[38:41]
	v_mfma_f32_16x16x32_bf16 v[34:37], v[186:189], v[154:157], v[34:37]
	v_mfma_f32_16x16x32_bf16 v[66:69], v[166:169], v[150:153], v[66:69]
	v_mfma_f32_16x16x32_bf16 v[58:61], v[166:169], v[158:161], v[58:61]
	v_mfma_f32_16x16x32_bf16 v[54:57], v[174:177], v[150:153], v[54:57]
	v_mfma_f32_16x16x32_bf16 v[50:53], v[174:177], v[158:161], v[50:53]
	v_mfma_f32_16x16x32_bf16 v[46:49], v[182:185], v[150:153], v[46:49]
	v_mfma_f32_16x16x32_bf16 v[42:45], v[182:185], v[158:161], v[42:45]
	s_waitcnt lgkmcnt(0)
	v_mfma_f32_16x16x32_bf16 v[38:41], v[134:137], v[150:153], v[38:41]
	v_mfma_f32_16x16x32_bf16 v[34:37], v[134:137], v[158:161], v[34:37]
	s_setprio 0
	s_setprio 1
	v_mfma_f32_16x16x32_bf16 v[30:33], v[162:165], v[190:193], v[30:33]
	v_mfma_f32_16x16x32_bf16 v[26:29], v[162:165], v[198:201], v[26:29]
	v_mfma_f32_16x16x32_bf16 v[22:25], v[170:173], v[190:193], v[22:25]
	v_mfma_f32_16x16x32_bf16 v[18:21], v[170:173], v[198:201], v[18:21]
	v_mfma_f32_16x16x32_bf16 v[14:17], v[178:181], v[190:193], v[14:17]
	v_mfma_f32_16x16x32_bf16 v[10:13], v[178:181], v[198:201], v[10:13]
	v_mfma_f32_16x16x32_bf16 v[6:9], v[186:189], v[190:193], v[6:9]
	v_mfma_f32_16x16x32_bf16 v[2:5], v[186:189], v[198:201], v[2:5]
	v_mfma_f32_16x16x32_bf16 v[30:33], v[166:169], v[194:197], v[30:33]
	v_mfma_f32_16x16x32_bf16 v[26:29], v[166:169], v[142:145], v[26:29]
	v_mfma_f32_16x16x32_bf16 v[22:25], v[174:177], v[194:197], v[22:25]
	v_mfma_f32_16x16x32_bf16 v[18:21], v[174:177], v[142:145], v[18:21]
	v_mfma_f32_16x16x32_bf16 v[14:17], v[182:185], v[194:197], v[14:17]
	v_mfma_f32_16x16x32_bf16 v[10:13], v[182:185], v[142:145], v[10:13]
	v_mfma_f32_16x16x32_bf16 v[6:9], v[134:137], v[194:197], v[6:9]
	v_mfma_f32_16x16x32_bf16 v[2:5], v[134:137], v[142:145], v[2:5]
	s_setprio 0
	v_cmp_gt_u32_e32 vcc, s16, v132
	s_barrier
	s_and_saveexec_b64 s[4:5], vcc
	s_cbranch_execz .LBB0_1904
	s_barrier

; #define STAGE(P, BASE, LD, br, kt) do { const int _so = (int)(((br) * (LD) + (kt) * BK) * 2); \
;     _Pragma("unroll") for (int _i = 0; _i < 2; ++_i) { \
;       __builtin_amdgcn_raw_ptr_buffer_load_lds(rs##BASE, (__attribute__((address_space(3))) unsigned*)((char*)(P) + tid_ * 16 + _i * 8192), 16, (int)off##LD[_i], _so, 0, 0); } } while (0)
; #define LDA_(dst, b, h) _Pragma("unroll") for (int m = 0; m < 4; ++m) _Pragma("unroll") for (int k = 0; k < 2; ++k) \
;     dst[m][k] = *reinterpret_cast<const bf16x8*>((char*)SA(b, h) + lds_byte(wr * 64 + m * 16 + fr, k * 32 + fq * 8))
; #define LDB_(dst, b, h) _Pragma("unroll") for (int n = 0; n < 2; ++n) _Pragma("unroll") for (int k = 0; k < 2; ++k) \
;     dst[n][k] = *reinterpret_cast<const bf16x8*>((char*)SB(b, h) + lds_byte(wc * 32 + n * 16 + fr, k * 32 + fq * 8))
; #define MMA(ai, bj, At, Bx) do { __builtin_amdgcn_s_setprio(1); \
;     _Pragma("unroll") for (int m = 0; m < 4; ++m) _Pragma("unroll") for (int n = 0; n < 2; ++n) _Pragma("unroll") for (int k = 0; k < 2; ++k) \
;       acc[ai][bj][m][n] = __builtin_amdgcn_mfma_f32_16x16x32_bf16(At[m][k], Bx[n][k], acc[ai][bj][m][n], 0, 0, 0); \
;     __builtin_amdgcn_s_setprio(0); } while (0)
; #define WAIT_L(n) asm volatile("s_waitcnt lgkmcnt(" #n ")" ::: "memory")
; #define BAR __builtin_amdgcn_s_barrier()
; #define SCHED __builtin_amdgcn_sched_barrier(0)
; template <int K, int LDA, int LDB>
; DEVI void gemm_tile(const bf16* __restrict__ A, const bf16* __restrict__ Bt, bf16* shm, acc_t& acc) {
;     ...
;     LDB_(B0, 0, 0); SCHED; LDA_(At, 0, 0); STAGE(SA(1, 1), A, LDA, HALF, t + 1);
;     WAIT_L(8); BAR; WAIT_L(0); MMA(0, 0, At, B0); BAR; SCHED;
;     LDB_(B1, 0, 1); STAGE(SB(0, 0), Bt, LDB, 0, t + 2);
;     BAR; WAIT_L(0); MMA(0, 1, At, B1); BAR;
;     LDA_(At, 0, 1); STAGE(SA(0, 0), A, LDA, 0, t + 2);
;     BAR; WAIT_L(0); MMA(1, 0, At, B0); BAR; SCHED;
.LBB0_1948:
	ds_read_b128 v[162:165], v161
	ds_read_b128 v[166:169], v161 offset:1024
	ds_read_b128 v[170:173], v161 offset:2048
	ds_read_b128 v[174:177], v161 offset:3072
	v_readfirstlane_b32 s42, v157
	s_add_i32 s41, s40, 0xfff9ff00
	s_mov_b32 m0, s42
	v_readfirstlane_b32 s42, v160
	ds_read_b128 v[178:181], v141
	ds_read_b128 v[182:185], v141 offset:1024
	ds_read_b128 v[186:189], v140
	ds_read_b128 v[190:193], v140 offset:1024
	ds_read_b128 v[194:197], v139
	ds_read_b128 v[198:201], v139 offset:1024
	ds_read_b128 v[202:205], v135
	ds_read_b128 v[206:209], v135 offset:1024
	buffer_load_dwordx4 v132, s[4:7], s41 offen lds
	s_mov_b32 m0, s42
	s_nop 0
	buffer_load_dwordx4 v136, s[4:7], s41 offen lds
	s_waitcnt lgkmcnt(8)
	s_barrier
	s_waitcnt lgkmcnt(0)
	s_setprio 1
	s_waitcnt lgkmcnt(7)
	v_mfma_f32_16x16x32_bf16 v[126:129], v[178:181], v[162:165], v[126:129]
	v_mfma_f32_16x16x32_bf16 v[122:125], v[178:181], v[170:173], v[122:125]
	s_waitcnt lgkmcnt(5)
	v_mfma_f32_16x16x32_bf16 v[118:121], v[186:189], v[162:165], v[118:121]
	v_mfma_f32_16x16x32_bf16 v[114:117], v[186:189], v[170:173], v[114:117]
	s_waitcnt lgkmcnt(3)
	v_mfma_f32_16x16x32_bf16 v[110:113], v[194:197], v[162:165], v[110:113]
	v_mfma_f32_16x16x32_bf16 v[106:109], v[194:197], v[170:173], v[106:109]
	s_waitcnt lgkmcnt(1)
	v_mfma_f32_16x16x32_bf16 v[102:105], v[202:205], v[162:165], v[102:105]
	v_mfma_f32_16x16x32_bf16 v[98:101], v[202:205], v[170:173], v[98:101]
	v_mfma_f32_16x16x32_bf16 v[126:129], v[182:185], v[166:169], v[126:129]
	v_mfma_f32_16x16x32_bf16 v[122:125], v[182:185], v[174:177], v[122:125]
	v_mfma_f32_16x16x32_bf16 v[118:121], v[190:193], v[166:169], v[118:121]
	v_mfma_f32_16x16x32_bf16 v[114:117], v[190:193], v[174:177], v[114:117]
	v_mfma_f32_16x16x32_bf16 v[110:113], v[198:201], v[166:169], v[110:113]
	v_mfma_f32_16x16x32_bf16 v[106:109], v[198:201], v[174:177], v[106:109]
	s_waitcnt lgkmcnt(0)
	v_mfma_f32_16x16x32_bf16 v[102:105], v[206:209], v[166:169], v[102:105]
	v_mfma_f32_16x16x32_bf16 v[98:101], v[206:209], v[174:177], v[98:101]
	s_setprio 0
	s_barrier
	v_readfirstlane_b32 s42, v144
	s_add_i32 s41, s40, 0xfff7ff80
	s_mov_b32 m0, s42
	v_readfirstlane_b32 s42, v145
	ds_read_b128 v[210:213], v155
	ds_read_b128 v[214:217], v155 offset:1024
	ds_read_b128 v[218:221], v155 offset:2048
	ds_read_b128 v[222:225], v155 offset:3072
	buffer_load_dwordx4 v134, s[0:3], s41 offen lds
	s_mov_b32 m0, s42
	s_nop 0
	buffer_load_dwordx4 v138, s[0:3], s41 offen lds
	s_barrier
	s_waitcnt lgkmcnt(0)
	s_setprio 1
	s_waitcnt lgkmcnt(3)
	v_mfma_f32_16x16x32_bf16 v[94:97], v[178:181], v[210:213], v[94:97]
	s_waitcnt lgkmcnt(1)
	v_mfma_f32_16x16x32_bf16 v[90:93], v[178:181], v[218:221], v[90:93]
	v_mfma_f32_16x16x32_bf16 v[86:89], v[186:189], v[210:213], v[86:89]
	v_mfma_f32_16x16x32_bf16 v[82:85], v[186:189], v[218:221], v[82:85]
	v_mfma_f32_16x16x32_bf16 v[78:81], v[194:197], v[210:213], v[78:81]
	v_mfma_f32_16x16x32_bf16 v[74:77], v[194:197], v[218:221], v[74:77]
	v_mfma_f32_16x16x32_bf16 v[70:73], v[202:205], v[210:213], v[70:73]
	v_mfma_f32_16x16x32_bf16 v[66:69], v[202:205], v[218:221], v[66:69]
	v_mfma_f32_16x16x32_bf16 v[94:97], v[182:185], v[214:217], v[94:97]
	s_waitcnt lgkmcnt(0)
	v_mfma_f32_16x16x32_bf16 v[90:93], v[182:185], v[222:225], v[90:93]
	v_mfma_f32_16x16x32_bf16 v[86:89], v[190:193], v[214:217], v[86:89]
	v_mfma_f32_16x16x32_bf16 v[82:85], v[190:193], v[222:225], v[82:85]
	v_mfma_f32_16x16x32_bf16 v[78:81], v[198:201], v[214:217], v[78:81]
	v_mfma_f32_16x16x32_bf16 v[74:77], v[198:201], v[222:225], v[74:77]
	v_mfma_f32_16x16x32_bf16 v[70:73], v[206:209], v[214:217], v[70:73]
	v_mfma_f32_16x16x32_bf16 v[66:69], v[206:209], v[222:225], v[66:69]
	s_setprio 0
	v_readfirstlane_b32 s42, v146
	s_mov_b32 m0, s42
	v_readfirstlane_b32 s42, v147
	s_barrier
	ds_read_b128 v[178:181], v141 offset:16384
	ds_read_b128 v[182:185], v141 offset:17408
	ds_read_b128 v[186:189], v140 offset:16384
	ds_read_b128 v[190:193], v140 offset:17408
	ds_read_b128 v[194:197], v139 offset:16384
	ds_read_b128 v[198:201], v139 offset:17408
	ds_read_b128 v[202:205], v135 offset:16384
	ds_read_b128 v[206:209], v135 offset:17408
	buffer_load_dwordx4 v132, s[4:7], s41 offen lds
	s_mov_b32 m0, s42
	s_nop 0
	buffer_load_dwordx4 v136, s[4:7], s41 offen lds
	s_barrier
	s_waitcnt lgkmcnt(0)
	s_setprio 1
	s_waitcnt lgkmcnt(7)
	v_mfma_f32_16x16x32_bf16 v[62:65], v[178:181], v[162:165], v[62:65]
	v_mfma_f32_16x16x32_bf16 v[58:61], v[178:181], v[170:173], v[58:61]
	s_waitcnt lgkmcnt(5)
	v_mfma_f32_16x16x32_bf16 v[54:57], v[186:189], v[162:165], v[54:57]
	v_mfma_f32_16x16x32_bf16 v[50:53], v[186:189], v[170:173], v[50:53]
	s_waitcnt lgkmcnt(3)
	v_mfma_f32_16x16x32_bf16 v[46:49], v[194:197], v[162:165], v[46:49]
	v_mfma_f32_16x16x32_bf16 v[42:45], v[194:197], v[170:173], v[42:45]
	s_waitcnt lgkmcnt(1)
	v_mfma_f32_16x16x32_bf16 v[38:41], v[202:205], v[162:165], v[38:41]
	v_mfma_f32_16x16x32_bf16 v[34:37], v[202:205], v[170:173], v[34:37]
	v_mfma_f32_16x16x32_bf16 v[62:65], v[182:185], v[166:169], v[62:65]
	v_mfma_f32_16x16x32_bf16 v[58:61], v[182:185], v[174:177], v[58:61]
	v_mfma_f32_16x16x32_bf16 v[54:57], v[190:193], v[166:169], v[54:57]
	v_mfma_f32_16x16x32_bf16 v[50:53], v[190:193], v[174:177], v[50:53]
	v_mfma_f32_16x16x32_bf16 v[46:49], v[198:201], v[166:169], v[46:49]
	v_mfma_f32_16x16x32_bf16 v[42:45], v[198:201], v[174:177], v[42:45]
	s_waitcnt lgkmcnt(0)
	v_mfma_f32_16x16x32_bf16 v[38:41], v[206:209], v[166:169], v[38:41]
	v_mfma_f32_16x16x32_bf16 v[34:37], v[206:209], v[174:177], v[34:37]
	s_setprio 0
	s_barrier
; #define STAGE(P, BASE, LD, br, kt) do { const int _so = (int)(((br) * (LD) + (kt) * BK) * 2); \
;     _Pragma("unroll") for (int _i = 0; _i < 2; ++_i) { \
;       __builtin_amdgcn_raw_ptr_buffer_load_lds(rs##BASE, (__attribute__((address_space(3))) unsigned*)((char*)(P) + tid_ * 16 + _i * 8192), 16, (int)off##LD[_i], _so, 0, 0); } } while (0)
; #define LDA_(dst, b, h) _Pragma("unroll") for (int m = 0; m < 4; ++m) _Pragma("unroll") for (int k = 0; k < 2; ++k) \
;     dst[m][k] = *reinterpret_cast<const bf16x8*>((char*)SA(b, h) + lds_byte(wr * 64 + m * 16 + fr, k * 32 + fq * 8))
; #define LDB_(dst, b, h) _Pragma("unroll") for (int n = 0; n < 2; ++n) _Pragma("unroll") for (int k = 0; k < 2; ++k) \
;     dst[n][k] = *reinterpret_cast<const bf16x8*>((char*)SB(b, h) + lds_byte(wc * 32 + n * 16 + fr, k * 32 + fq * 8))
; #define MMA(ai, bj, At, Bx) do { __builtin_amdgcn_s_setprio(1); \
;     _Pragma("unroll") for (int m = 0; m < 4; ++m) _Pragma("unroll") for (int n = 0; n < 2; ++n) _Pragma("unroll") for (int k = 0; k < 2; ++k) \
;       acc[ai][bj][m][n] = __builtin_amdgcn_mfma_f32_16x16x32_bf16(At[m][k], Bx[n][k], acc[ai][bj][m][n], 0, 0, 0); \
;     __builtin_amdgcn_s_setprio(0); } while (0)
; #define WAIT_V(n) asm volatile("s_waitcnt vmcnt(" #n ")" ::: "memory")
; #define WAIT_L(n) asm volatile("s_waitcnt lgkmcnt(" #n ")" ::: "memory")
; #define BAR __builtin_amdgcn_s_barrier()
; #define SCHED __builtin_amdgcn_sched_barrier(0)
; template <int K, int LDA, int LDB>
; DEVI void gemm_tile(const bf16* __restrict__ A, const bf16* __restrict__ Bt, bf16* shm, acc_t& acc) {
;     ...
;     STAGE(SB(0, 1), Bt, LDB, HALF, t + 2);
;     WAIT_V(6); BAR; MMA(1, 1, At, B1); BAR;
;     LDB_(B0, 1, 0); SCHED; LDA_(At, 1, 0); STAGE(SA(0, 1), A, LDA, HALF, t + 2);
;     WAIT_L(8); BAR; WAIT_L(0); MMA(0, 0, At, B0); BAR; SCHED;
;     LDB_(B1, 1, 1); STAGE(SB(1, 0), Bt, LDB, 0, t + 3);
;     BAR; WAIT_L(0); MMA(0, 1, At, B1); BAR;
;     LDA_(At, 1, 1); STAGE(SA(1, 0), A, LDA, 0, t + 3);
	v_readfirstlane_b32 s42, v148
	s_add_i32 s41, s40, 0xffffff80
	s_mov_b32 m0, s42
	v_readfirstlane_b32 s42, v149
	buffer_load_dwordx4 v134, s[0:3], s41 offen lds
	s_mov_b32 m0, s42
	s_nop 0
	buffer_load_dwordx4 v138, s[0:3], s41 offen lds
	s_waitcnt vmcnt(6)
	s_barrier
	s_setprio 1
	v_mfma_f32_16x16x32_bf16 v[30:33], v[178:181], v[210:213], v[30:33]
	v_mfma_f32_16x16x32_bf16 v[26:29], v[178:181], v[218:221], v[26:29]
	v_mfma_f32_16x16x32_bf16 v[22:25], v[186:189], v[210:213], v[22:25]
	v_mfma_f32_16x16x32_bf16 v[18:21], v[186:189], v[218:221], v[18:21]
	v_mfma_f32_16x16x32_bf16 v[14:17], v[194:197], v[210:213], v[14:17]
	v_mfma_f32_16x16x32_bf16 v[10:13], v[194:197], v[218:221], v[10:13]
	v_mfma_f32_16x16x32_bf16 v[6:9], v[202:205], v[210:213], v[6:9]
	v_mfma_f32_16x16x32_bf16 v[2:5], v[202:205], v[218:221], v[2:5]
	v_mfma_f32_16x16x32_bf16 v[30:33], v[182:185], v[214:217], v[30:33]
	v_mfma_f32_16x16x32_bf16 v[26:29], v[182:185], v[222:225], v[26:29]
	v_mfma_f32_16x16x32_bf16 v[22:25], v[190:193], v[214:217], v[22:25]
	v_mfma_f32_16x16x32_bf16 v[18:21], v[190:193], v[222:225], v[18:21]
	v_mfma_f32_16x16x32_bf16 v[14:17], v[198:201], v[214:217], v[14:17]
	v_mfma_f32_16x16x32_bf16 v[10:13], v[198:201], v[222:225], v[10:13]
	v_mfma_f32_16x16x32_bf16 v[6:9], v[206:209], v[214:217], v[6:9]
	v_mfma_f32_16x16x32_bf16 v[2:5], v[206:209], v[222:225], v[2:5]
	s_setprio 0
	s_barrier
	ds_read_b128 v[162:165], v143
	ds_read_b128 v[166:169], v143 offset:1024
	ds_read_b128 v[170:173], v143 offset:2048
	ds_read_b128 v[174:177], v143 offset:3072
	v_readfirstlane_b32 s42, v150
	s_add_i32 s41, s40, 0xfff9ff80
	s_mov_b32 m0, s42
	v_readfirstlane_b32 s42, v151
	ds_read_b128 v[178:181], v141 offset:32768
	ds_read_b128 v[182:185], v141 offset:33792
	ds_read_b128 v[186:189], v140 offset:32768
	ds_read_b128 v[190:193], v140 offset:33792
	ds_read_b128 v[194:197], v139 offset:32768
	ds_read_b128 v[198:201], v139 offset:33792
	ds_read_b128 v[202:205], v135 offset:32768
	ds_read_b128 v[206:209], v135 offset:33792
	buffer_load_dwordx4 v132, s[4:7], s41 offen lds
	s_mov_b32 m0, s42
	s_nop 0
	buffer_load_dwordx4 v136, s[4:7], s41 offen lds
	s_waitcnt lgkmcnt(8)
	s_barrier
	s_waitcnt lgkmcnt(0)
	s_setprio 1
	s_waitcnt lgkmcnt(7)
	v_mfma_f32_16x16x32_bf16 v[126:129], v[178:181], v[162:165], v[126:129]
	v_mfma_f32_16x16x32_bf16 v[122:125], v[178:181], v[170:173], v[122:125]
	s_waitcnt lgkmcnt(5)
	v_mfma_f32_16x16x32_bf16 v[118:121], v[186:189], v[162:165], v[118:121]
	v_mfma_f32_16x16x32_bf16 v[114:117], v[186:189], v[170:173], v[114:117]
	s_waitcnt lgkmcnt(3)
	v_mfma_f32_16x16x32_bf16 v[110:113], v[194:197], v[162:165], v[110:113]
	v_mfma_f32_16x16x32_bf16 v[106:109], v[194:197], v[170:173], v[106:109]
	s_waitcnt lgkmcnt(1)
	v_mfma_f32_16x16x32_bf16 v[102:105], v[202:205], v[162:165], v[102:105]
	v_mfma_f32_16x16x32_bf16 v[98:101], v[202:205], v[170:173], v[98:101]
	v_mfma_f32_16x16x32_bf16 v[126:129], v[182:185], v[166:169], v[126:129]
	v_mfma_f32_16x16x32_bf16 v[122:125], v[182:185], v[174:177], v[122:125]
	v_mfma_f32_16x16x32_bf16 v[118:121], v[190:193], v[166:169], v[118:121]
	v_mfma_f32_16x16x32_bf16 v[114:117], v[190:193], v[174:177], v[114:117]
	v_mfma_f32_16x16x32_bf16 v[110:113], v[198:201], v[166:169], v[110:113]
	v_mfma_f32_16x16x32_bf16 v[106:109], v[198:201], v[174:177], v[106:109]
	s_waitcnt lgkmcnt(0)
	v_mfma_f32_16x16x32_bf16 v[102:105], v[206:209], v[166:169], v[102:105]
	v_mfma_f32_16x16x32_bf16 v[98:101], v[206:209], v[174:177], v[98:101]
	s_setprio 0
	s_barrier
	v_readfirstlane_b32 s42, v152
	s_add_i32 s41, s40, 0xfff80000
	s_mov_b32 m0, s42
	v_readfirstlane_b32 s42, v153
	ds_read_b128 v[210:213], v142
	ds_read_b128 v[214:217], v142 offset:1024
	ds_read_b128 v[218:221], v142 offset:2048
	ds_read_b128 v[222:225], v142 offset:3072
	buffer_load_dwordx4 v134, s[0:3], s41 offen lds
	s_mov_b32 m0, s42
	s_nop 0
	buffer_load_dwordx4 v138, s[0:3], s41 offen lds
	s_barrier
	s_waitcnt lgkmcnt(0)
	s_setprio 1
	s_waitcnt lgkmcnt(3)
	v_mfma_f32_16x16x32_bf16 v[94:97], v[178:181], v[210:213], v[94:97]
	s_waitcnt lgkmcnt(1)
	v_mfma_f32_16x16x32_bf16 v[90:93], v[178:181], v[218:221], v[90:93]
	v_mfma_f32_16x16x32_bf16 v[86:89], v[186:189], v[210:213], v[86:89]
	v_mfma_f32_16x16x32_bf16 v[82:85], v[186:189], v[218:221], v[82:85]
	v_mfma_f32_16x16x32_bf16 v[78:81], v[194:197], v[210:213], v[78:81]
	v_mfma_f32_16x16x32_bf16 v[74:77], v[194:197], v[218:221], v[74:77]
	v_mfma_f32_16x16x32_bf16 v[70:73], v[202:205], v[210:213], v[70:73]
	v_mfma_f32_16x16x32_bf16 v[66:69], v[202:205], v[218:221], v[66:69]
	v_mfma_f32_16x16x32_bf16 v[94:97], v[182:185], v[214:217], v[94:97]
	s_waitcnt lgkmcnt(0)
	v_mfma_f32_16x16x32_bf16 v[90:93], v[182:185], v[222:225], v[90:93]
	v_mfma_f32_16x16x32_bf16 v[86:89], v[190:193], v[214:217], v[86:89]
	v_mfma_f32_16x16x32_bf16 v[82:85], v[190:193], v[222:225], v[82:85]
	v_mfma_f32_16x16x32_bf16 v[78:81], v[198:201], v[214:217], v[78:81]
	v_mfma_f32_16x16x32_bf16 v[74:77], v[198:201], v[222:225], v[74:77]
	v_mfma_f32_16x16x32_bf16 v[70:73], v[206:209], v[214:217], v[70:73]
	v_mfma_f32_16x16x32_bf16 v[66:69], v[206:209], v[222:225], v[66:69]
	s_setprio 0
	v_readfirstlane_b32 s42, v154
	s_mov_b32 m0, s42
	v_readfirstlane_b32 s42, v156
	s_barrier
	ds_read_b128 v[178:181], v141 offset:49152
	ds_read_b128 v[182:185], v141 offset:50176
	ds_read_b128 v[186:189], v140 offset:49152
	ds_read_b128 v[190:193], v140 offset:50176
	ds_read_b128 v[194:197], v139 offset:49152
	ds_read_b128 v[198:201], v139 offset:50176
	ds_read_b128 v[202:205], v135 offset:49152
	ds_read_b128 v[206:209], v135 offset:50176
	buffer_load_dwordx4 v132, s[4:7], s41 offen lds
	s_mov_b32 m0, s42
	s_nop 0
	buffer_load_dwordx4 v136, s[4:7], s41 offen lds
	s_barrier
; #define STAGE(P, BASE, LD, br, kt) do { const int _so = (int)(((br) * (LD) + (kt) * BK) * 2); \
;     _Pragma("unroll") for (int _i = 0; _i < 2; ++_i) { \
;       __builtin_amdgcn_raw_ptr_buffer_load_lds(rs##BASE, (__attribute__((address_space(3))) unsigned*)((char*)(P) + tid_ * 16 + _i * 8192), 16, (int)off##LD[_i], _so, 0, 0); } } while (0)
; #define LDA_(dst, b, h) _Pragma("unroll") for (int m = 0; m < 4; ++m) _Pragma("unroll") for (int k = 0; k < 2; ++k) \
;     dst[m][k] = *reinterpret_cast<const bf16x8*>((char*)SA(b, h) + lds_byte(wr * 64 + m * 16 + fr, k * 32 + fq * 8))
; #define LDB_(dst, b, h) _Pragma("unroll") for (int n = 0; n < 2; ++n) _Pragma("unroll") for (int k = 0; k < 2; ++k) \
;     dst[n][k] = *reinterpret_cast<const bf16x8*>((char*)SB(b, h) + lds_byte(wc * 32 + n * 16 + fr, k * 32 + fq * 8))
; #define MMA(ai, bj, At, Bx) do { __builtin_amdgcn_s_setprio(1); \
;     _Pragma("unroll") for (int m = 0; m < 4; ++m) _Pragma("unroll") for (int n = 0; n < 2; ++n) _Pragma("unroll") for (int k = 0; k < 2; ++k) \
;       acc[ai][bj][m][n] = __builtin_amdgcn_mfma_f32_16x16x32_bf16(At[m][k], Bx[n][k], acc[ai][bj][m][n], 0, 0, 0); \
;     __builtin_amdgcn_s_setprio(0); } while (0)
; #define WAIT_V(n) asm volatile("s_waitcnt vmcnt(" #n ")" ::: "memory")
; #define WAIT_L(n) asm volatile("s_waitcnt lgkmcnt(" #n ")" ::: "memory")
; #define BAR __builtin_amdgcn_s_barrier()
; #define SCHED __builtin_amdgcn_sched_barrier(0)
; template <int K, int LDA, int LDB>
; DEVI void gemm_tile(const bf16* __restrict__ A, const bf16* __restrict__ Bt, bf16* shm, acc_t& acc) {
;     ...
;     BAR; WAIT_L(0); MMA(1, 0, At, B0); BAR; SCHED;
;     STAGE(SB(1, 1), Bt, LDB, HALF, t + 3);
;     WAIT_V(6); BAR; MMA(1, 1, At, B1); BAR;
;   }
;   { LDB_(B0, 0, 0); LDA_(At, 0, 0); STAGE(SA(1, 1), A, LDA, HALF, nt - 1);
;     BAR; WAIT_L(0); MMA(0, 0, At, B0); BAR;
;     LDB_(B1, 0, 1); BAR; WAIT_L(0); MMA(0, 1, At, B1); BAR;
	s_waitcnt lgkmcnt(0)
	s_setprio 1
	s_waitcnt lgkmcnt(7)
	v_mfma_f32_16x16x32_bf16 v[62:65], v[178:181], v[162:165], v[62:65]
	v_mfma_f32_16x16x32_bf16 v[58:61], v[178:181], v[170:173], v[58:61]
	s_waitcnt lgkmcnt(5)
	v_mfma_f32_16x16x32_bf16 v[54:57], v[186:189], v[162:165], v[54:57]
	v_mfma_f32_16x16x32_bf16 v[50:53], v[186:189], v[170:173], v[50:53]
	s_waitcnt lgkmcnt(3)
	v_mfma_f32_16x16x32_bf16 v[46:49], v[194:197], v[162:165], v[46:49]
	v_mfma_f32_16x16x32_bf16 v[42:45], v[194:197], v[170:173], v[42:45]
	s_waitcnt lgkmcnt(1)
	v_mfma_f32_16x16x32_bf16 v[38:41], v[202:205], v[162:165], v[38:41]
	v_mfma_f32_16x16x32_bf16 v[34:37], v[202:205], v[170:173], v[34:37]
	v_mfma_f32_16x16x32_bf16 v[62:65], v[182:185], v[166:169], v[62:65]
	v_mfma_f32_16x16x32_bf16 v[58:61], v[182:185], v[174:177], v[58:61]
	v_mfma_f32_16x16x32_bf16 v[54:57], v[190:193], v[166:169], v[54:57]
	v_mfma_f32_16x16x32_bf16 v[50:53], v[190:193], v[174:177], v[50:53]
	v_mfma_f32_16x16x32_bf16 v[46:49], v[198:201], v[166:169], v[46:49]
	v_mfma_f32_16x16x32_bf16 v[42:45], v[198:201], v[174:177], v[42:45]
	s_waitcnt lgkmcnt(0)
	v_mfma_f32_16x16x32_bf16 v[38:41], v[206:209], v[166:169], v[38:41]
	v_mfma_f32_16x16x32_bf16 v[34:37], v[206:209], v[174:177], v[34:37]
	s_setprio 0
	s_barrier
	v_readfirstlane_b32 s41, v158
	s_mov_b32 m0, s41
	v_readfirstlane_b32 s41, v159
	buffer_load_dwordx4 v134, s[0:3], s40 offen lds
	s_mov_b32 m0, s41
	s_nop 0
	buffer_load_dwordx4 v138, s[0:3], s40 offen lds
	s_waitcnt vmcnt(6)
	s_barrier
	s_setprio 1
	v_mfma_f32_16x16x32_bf16 v[30:33], v[178:181], v[210:213], v[30:33]
	v_mfma_f32_16x16x32_bf16 v[26:29], v[178:181], v[218:221], v[26:29]
	v_mfma_f32_16x16x32_bf16 v[22:25], v[186:189], v[210:213], v[22:25]
	v_mfma_f32_16x16x32_bf16 v[18:21], v[186:189], v[218:221], v[18:21]
	v_mfma_f32_16x16x32_bf16 v[14:17], v[194:197], v[210:213], v[14:17]
	v_mfma_f32_16x16x32_bf16 v[10:13], v[194:197], v[218:221], v[10:13]
	v_mfma_f32_16x16x32_bf16 v[6:9], v[202:205], v[210:213], v[6:9]
	v_mfma_f32_16x16x32_bf16 v[2:5], v[202:205], v[218:221], v[2:5]
	v_mfma_f32_16x16x32_bf16 v[30:33], v[182:185], v[214:217], v[30:33]
	v_mfma_f32_16x16x32_bf16 v[26:29], v[182:185], v[222:225], v[26:29]
	v_mfma_f32_16x16x32_bf16 v[22:25], v[190:193], v[214:217], v[22:25]
	v_mfma_f32_16x16x32_bf16 v[18:21], v[190:193], v[222:225], v[18:21]
	v_mfma_f32_16x16x32_bf16 v[14:17], v[198:201], v[214:217], v[14:17]
	v_mfma_f32_16x16x32_bf16 v[10:13], v[198:201], v[222:225], v[10:13]
	v_mfma_f32_16x16x32_bf16 v[6:9], v[206:209], v[214:217], v[6:9]
	v_mfma_f32_16x16x32_bf16 v[2:5], v[206:209], v[222:225], v[2:5]
	s_setprio 0
	s_add_i32 s11, s11, 2
	s_addk_i32 s40, 0x100
	s_cmp_lt_u32 s11, 4
	s_cbranch_scc1 .Lrot_42732
	s_barrier
	v_readfirstlane_b32 s0, v157
	s_mov_b32 s6, s2
	s_mov_b32 s7, s3
	s_mov_b32 m0, s0
	v_readfirstlane_b32 s0, v160
	ds_read_b128 v[144:147], v161
	ds_read_b128 v[148:151], v161 offset:1024
	ds_read_b128 v[162:165], v161 offset:2048
	ds_read_b128 v[166:169], v161 offset:3072
	ds_read_b128 v[170:173], v141
	ds_read_b128 v[174:177], v141 offset:1024
	ds_read_b128 v[178:181], v140
	ds_read_b128 v[182:185], v140 offset:1024
	ds_read_b128 v[186:189], v139
	ds_read_b128 v[190:193], v139 offset:1024
	ds_read_b128 v[194:197], v135
	ds_read_b128 v[198:201], v135 offset:1024
	buffer_load_dwordx4 v132, s[4:7], s38 offen lds
	s_mov_b32 m0, s0
	s_nop 0
	buffer_load_dwordx4 v136, s[4:7], s38 offen lds
	s_barrier
	s_waitcnt lgkmcnt(0)
	s_setprio 1
	s_waitcnt lgkmcnt(7)
	v_mfma_f32_16x16x32_bf16 v[126:129], v[170:173], v[144:147], v[126:129]
	v_mfma_f32_16x16x32_bf16 v[122:125], v[170:173], v[162:165], v[122:125]
	s_waitcnt lgkmcnt(5)
	v_mfma_f32_16x16x32_bf16 v[118:121], v[178:181], v[144:147], v[118:121]
	v_mfma_f32_16x16x32_bf16 v[114:117], v[178:181], v[162:165], v[114:117]
	s_waitcnt lgkmcnt(3)
	v_mfma_f32_16x16x32_bf16 v[110:113], v[186:189], v[144:147], v[110:113]
	v_mfma_f32_16x16x32_bf16 v[106:109], v[186:189], v[162:165], v[106:109]
	s_waitcnt lgkmcnt(1)
	v_mfma_f32_16x16x32_bf16 v[102:105], v[194:197], v[144:147], v[102:105]
	v_mfma_f32_16x16x32_bf16 v[98:101], v[194:197], v[162:165], v[98:101]
	v_mfma_f32_16x16x32_bf16 v[126:129], v[174:177], v[148:151], v[126:129]
	v_mfma_f32_16x16x32_bf16 v[122:125], v[174:177], v[166:169], v[122:125]
	v_mfma_f32_16x16x32_bf16 v[118:121], v[182:185], v[148:151], v[118:121]
	v_mfma_f32_16x16x32_bf16 v[114:117], v[182:185], v[166:169], v[114:117]
	v_mfma_f32_16x16x32_bf16 v[110:113], v[190:193], v[148:151], v[110:113]
	v_mfma_f32_16x16x32_bf16 v[106:109], v[190:193], v[166:169], v[106:109]
	s_waitcnt lgkmcnt(0)
	v_mfma_f32_16x16x32_bf16 v[102:105], v[198:201], v[148:151], v[102:105]
	v_mfma_f32_16x16x32_bf16 v[98:101], v[198:201], v[166:169], v[98:101]
	s_setprio 0
	s_barrier
	ds_read_b128 v[156:159], v155
	ds_read_b128 v[202:205], v155 offset:1024
	ds_read_b128 v[206:209], v155 offset:2048
	ds_read_b128 v[152:155], v155 offset:3072
	s_barrier
	s_waitcnt lgkmcnt(0)
	s_setprio 1
	s_waitcnt lgkmcnt(1)
	v_mfma_f32_16x16x32_bf16 v[90:93], v[170:173], v[206:209], v[90:93]
	v_mfma_f32_16x16x32_bf16 v[86:89], v[178:181], v[156:159], v[86:89]
	v_mfma_f32_16x16x32_bf16 v[82:85], v[178:181], v[206:209], v[82:85]
	v_mfma_f32_16x16x32_bf16 v[78:81], v[186:189], v[156:159], v[78:81]
	v_mfma_f32_16x16x32_bf16 v[74:77], v[186:189], v[206:209], v[74:77]
	v_mfma_f32_16x16x32_bf16 v[70:73], v[194:197], v[156:159], v[70:73]
	v_mfma_f32_16x16x32_bf16 v[66:69], v[194:197], v[206:209], v[66:69]
	v_mfma_f32_16x16x32_bf16 v[94:97], v[170:173], v[156:159], v[94:97]
	s_waitcnt lgkmcnt(0)
	v_mfma_f32_16x16x32_bf16 v[90:93], v[174:177], v[152:155], v[90:93]
	v_mfma_f32_16x16x32_bf16 v[86:89], v[182:185], v[202:205], v[86:89]
	v_mfma_f32_16x16x32_bf16 v[82:85], v[182:185], v[152:155], v[82:85]
	v_mfma_f32_16x16x32_bf16 v[78:81], v[190:193], v[202:205], v[78:81]
	v_mfma_f32_16x16x32_bf16 v[74:77], v[190:193], v[152:155], v[74:77]
	v_mfma_f32_16x16x32_bf16 v[70:73], v[198:201], v[202:205], v[70:73]
	v_mfma_f32_16x16x32_bf16 v[66:69], v[198:201], v[152:155], v[66:69]
	v_mfma_f32_16x16x32_bf16 v[210:213], v[174:177], v[202:205], v[94:97]
	s_setprio 0
	s_barrier
; #define LDA_(dst, b, h) _Pragma("unroll") for (int m = 0; m < 4; ++m) _Pragma("unroll") for (int k = 0; k < 2; ++k) \
;     dst[m][k] = *reinterpret_cast<const bf16x8*>((char*)SA(b, h) + lds_byte(wr * 64 + m * 16 + fr, k * 32 + fq * 8))
; #define LDB_(dst, b, h) _Pragma("unroll") for (int n = 0; n < 2; ++n) _Pragma("unroll") for (int k = 0; k < 2; ++k) \
;     dst[n][k] = *reinterpret_cast<const bf16x8*>((char*)SB(b, h) + lds_byte(wc * 32 + n * 16 + fr, k * 32 + fq * 8))
; #define MMA(ai, bj, At, Bx) do { __builtin_amdgcn_s_setprio(1); \
;     _Pragma("unroll") for (int m = 0; m < 4; ++m) _Pragma("unroll") for (int n = 0; n < 2; ++n) _Pragma("unroll") for (int k = 0; k < 2; ++k) \
;       acc[ai][bj][m][n] = __builtin_amdgcn_mfma_f32_16x16x32_bf16(At[m][k], Bx[n][k], acc[ai][bj][m][n], 0, 0, 0); \
;     __builtin_amdgcn_s_setprio(0); } while (0)
; #define WAIT_V(n) asm volatile("s_waitcnt vmcnt(" #n ")" ::: "memory")
; #define WAIT_L(n) asm volatile("s_waitcnt lgkmcnt(" #n ")" ::: "memory")
; #define BAR __builtin_amdgcn_s_barrier()
; template <int K, int LDA, int LDB>
; DEVI void gemm_tile(const bf16* __restrict__ A, const bf16* __restrict__ Bt, bf16* shm, acc_t& acc) {
;     ...
;     LDA_(At, 0, 1); WAIT_V(4); BAR; WAIT_L(0); MMA(1, 0, At, B0); MMA(1, 1, At, B1); BAR; }
;   { LDB_(B0, 1, 0); LDA_(At, 1, 0); WAIT_V(2); BAR; WAIT_L(0); MMA(0, 0, At, B0); BAR;
	s_nop 0
	ds_read_b128 v[94:97], v141 offset:16384
	ds_read_b128 v[170:173], v141 offset:17408
	ds_read_b128 v[174:177], v140 offset:16384
	ds_read_b128 v[178:181], v140 offset:17408
	ds_read_b128 v[182:185], v139 offset:16384
	ds_read_b128 v[186:189], v139 offset:17408
	ds_read_b128 v[190:193], v135 offset:16384
	ds_read_b128 v[194:197], v135 offset:17408
	s_waitcnt vmcnt(4)
	s_barrier
	s_waitcnt lgkmcnt(0)
	s_setprio 1
	s_waitcnt lgkmcnt(7)
	v_mfma_f32_16x16x32_bf16 v[58:61], v[94:97], v[162:165], v[58:61]
	s_waitcnt lgkmcnt(5)
	v_mfma_f32_16x16x32_bf16 v[54:57], v[174:177], v[144:147], v[54:57]
	v_mfma_f32_16x16x32_bf16 v[50:53], v[174:177], v[162:165], v[50:53]
	s_waitcnt lgkmcnt(3)
	v_mfma_f32_16x16x32_bf16 v[46:49], v[182:185], v[144:147], v[46:49]
	v_mfma_f32_16x16x32_bf16 v[42:45], v[182:185], v[162:165], v[42:45]
	s_waitcnt lgkmcnt(1)
	v_mfma_f32_16x16x32_bf16 v[38:41], v[190:193], v[144:147], v[38:41]
	v_mfma_f32_16x16x32_bf16 v[34:37], v[190:193], v[162:165], v[34:37]
	v_mfma_f32_16x16x32_bf16 v[62:65], v[94:97], v[144:147], v[62:65]
	v_mfma_f32_16x16x32_bf16 v[58:61], v[170:173], v[166:169], v[58:61]
	v_mfma_f32_16x16x32_bf16 v[54:57], v[178:181], v[148:151], v[54:57]
	v_mfma_f32_16x16x32_bf16 v[50:53], v[178:181], v[166:169], v[50:53]
	v_mfma_f32_16x16x32_bf16 v[46:49], v[186:189], v[148:151], v[46:49]
	v_mfma_f32_16x16x32_bf16 v[42:45], v[186:189], v[166:169], v[42:45]
	s_waitcnt lgkmcnt(0)
	v_mfma_f32_16x16x32_bf16 v[38:41], v[194:197], v[148:151], v[38:41]
	v_mfma_f32_16x16x32_bf16 v[34:37], v[194:197], v[166:169], v[34:37]
	v_mfma_f32_16x16x32_bf16 v[198:201], v[170:173], v[148:151], v[62:65]
	s_setprio 0
	s_setprio 1
	v_mfma_f32_16x16x32_bf16 v[30:33], v[94:97], v[156:159], v[30:33]
	v_mfma_f32_16x16x32_bf16 v[26:29], v[94:97], v[206:209], v[26:29]
	v_mfma_f32_16x16x32_bf16 v[22:25], v[174:177], v[156:159], v[22:25]
	v_mfma_f32_16x16x32_bf16 v[18:21], v[174:177], v[206:209], v[18:21]
	v_mfma_f32_16x16x32_bf16 v[14:17], v[182:185], v[156:159], v[14:17]
	v_mfma_f32_16x16x32_bf16 v[10:13], v[182:185], v[206:209], v[10:13]
	v_mfma_f32_16x16x32_bf16 v[6:9], v[190:193], v[156:159], v[6:9]
	v_mfma_f32_16x16x32_bf16 v[2:5], v[190:193], v[206:209], v[2:5]
	v_mfma_f32_16x16x32_bf16 v[30:33], v[170:173], v[202:205], v[30:33]
	v_mfma_f32_16x16x32_bf16 v[26:29], v[170:173], v[152:155], v[26:29]
	v_mfma_f32_16x16x32_bf16 v[22:25], v[178:181], v[202:205], v[22:25]
	v_mfma_f32_16x16x32_bf16 v[18:21], v[178:181], v[152:155], v[18:21]
	v_mfma_f32_16x16x32_bf16 v[14:17], v[186:189], v[202:205], v[14:17]
	v_mfma_f32_16x16x32_bf16 v[10:13], v[186:189], v[152:155], v[10:13]
	v_mfma_f32_16x16x32_bf16 v[6:9], v[194:197], v[202:205], v[6:9]
	v_mfma_f32_16x16x32_bf16 v[2:5], v[194:197], v[152:155], v[2:5]
	s_setprio 0
	s_barrier
	ds_read_b128 v[144:147], v143
	ds_read_b128 v[148:151], v143 offset:1024
	ds_read_b128 v[152:155], v143 offset:2048
	ds_read_b128 v[156:159], v143 offset:3072
	ds_read_b128 v[62:65], v141 offset:32768
	ds_read_b128 v[160:163], v141 offset:33792
	ds_read_b128 v[164:167], v140 offset:32768
	ds_read_b128 v[168:171], v140 offset:33792
	ds_read_b128 v[172:175], v139 offset:32768
	ds_read_b128 v[176:179], v139 offset:33792
	ds_read_b128 v[180:183], v135 offset:32768
	ds_read_b128 v[184:187], v135 offset:33792
	s_waitcnt vmcnt(2)
	s_barrier
	s_waitcnt lgkmcnt(0)
	s_setprio 1
	s_waitcnt lgkmcnt(7)
	v_mfma_f32_16x16x32_bf16 v[94:97], v[62:65], v[144:147], v[126:129]
	s_waitcnt lgkmcnt(6)
	v_mfma_f32_16x16x32_bf16 v[126:129], v[160:163], v[148:151], v[94:97]
	v_mfma_f32_16x16x32_bf16 v[94:97], v[62:65], v[152:155], v[122:125]
	v_mfma_f32_16x16x32_bf16 v[122:125], v[160:163], v[156:159], v[94:97]
	s_waitcnt lgkmcnt(5)
	v_mfma_f32_16x16x32_bf16 v[94:97], v[164:167], v[144:147], v[118:121]
	s_waitcnt lgkmcnt(4)
	v_mfma_f32_16x16x32_bf16 v[118:121], v[168:171], v[148:151], v[94:97]
	v_mfma_f32_16x16x32_bf16 v[94:97], v[164:167], v[152:155], v[114:117]
	v_mfma_f32_16x16x32_bf16 v[114:117], v[168:171], v[156:159], v[94:97]
	s_waitcnt lgkmcnt(3)
	v_mfma_f32_16x16x32_bf16 v[94:97], v[172:175], v[144:147], v[110:113]
	s_waitcnt lgkmcnt(2)
	v_mfma_f32_16x16x32_bf16 v[110:113], v[176:179], v[148:151], v[94:97]
	v_mfma_f32_16x16x32_bf16 v[94:97], v[172:175], v[152:155], v[106:109]
	v_mfma_f32_16x16x32_bf16 v[106:109], v[176:179], v[156:159], v[94:97]
	s_waitcnt lgkmcnt(1)
	v_mfma_f32_16x16x32_bf16 v[94:97], v[180:183], v[144:147], v[102:105]
	s_waitcnt lgkmcnt(0)
	v_mfma_f32_16x16x32_bf16 v[102:105], v[184:187], v[148:151], v[94:97]
	v_mfma_f32_16x16x32_bf16 v[94:97], v[180:183], v[152:155], v[98:101]
	v_mfma_f32_16x16x32_bf16 v[94:97], v[184:187], v[156:159], v[94:97]
	s_setprio 0
	s_barrier
; #define LDA_(dst, b, h) _Pragma("unroll") for (int m = 0; m < 4; ++m) _Pragma("unroll") for (int k = 0; k < 2; ++k) \
;     dst[m][k] = *reinterpret_cast<const bf16x8*>((char*)SA(b, h) + lds_byte(wr * 64 + m * 16 + fr, k * 32 + fq * 8))
; #define LDB_(dst, b, h) _Pragma("unroll") for (int n = 0; n < 2; ++n) _Pragma("unroll") for (int k = 0; k < 2; ++k) \
;     dst[n][k] = *reinterpret_cast<const bf16x8*>((char*)SB(b, h) + lds_byte(wc * 32 + n * 16 + fr, k * 32 + fq * 8))
; #define MMA(ai, bj, At, Bx) do { __builtin_amdgcn_s_setprio(1); \
;     _Pragma("unroll") for (int m = 0; m < 4; ++m) _Pragma("unroll") for (int n = 0; n < 2; ++n) _Pragma("unroll") for (int k = 0; k < 2; ++k) \
;       acc[ai][bj][m][n] = __builtin_amdgcn_mfma_f32_16x16x32_bf16(At[m][k], Bx[n][k], acc[ai][bj][m][n], 0, 0, 0); \
;     __builtin_amdgcn_s_setprio(0); } while (0)
; #define WAIT_V(n) asm volatile("s_waitcnt vmcnt(" #n ")" ::: "memory")
; #define WAIT_L(n) asm volatile("s_waitcnt lgkmcnt(" #n ")" ::: "memory")
; #define BAR __builtin_amdgcn_s_barrier()
; template <int K, int LDA, int LDB>
; DEVI void gemm_tile(const bf16* __restrict__ A, const bf16* __restrict__ Bt, bf16* shm, acc_t& acc) {
;     ...
;   { LDB_(B0, 1, 0); LDA_(At, 1, 0); WAIT_V(2); BAR; WAIT_L(0); MMA(0, 0, At, B0); BAR;
;     LDB_(B1, 1, 1); WAIT_V(0); BAR; WAIT_L(0); MMA(0, 1, At, B1); BAR;
;     LDA_(At, 1, 1); BAR; WAIT_L(0); MMA(1, 0, At, B0); MMA(1, 1, At, B1); BAR; }
;   if (wr == 0) BAR;
	ds_read_b128 v[188:191], v142
	ds_read_b128 v[192:195], v142 offset:1024
	ds_read_b128 v[202:205], v142 offset:2048
	ds_read_b128 v[206:209], v142 offset:3072
	s_waitcnt vmcnt(0)
	s_barrier
	s_waitcnt lgkmcnt(0)
	s_setprio 1
	s_waitcnt lgkmcnt(3)
	v_mfma_f32_16x16x32_bf16 v[98:101], v[62:65], v[188:191], v[210:213]
	s_waitcnt lgkmcnt(1)
	v_mfma_f32_16x16x32_bf16 v[62:65], v[62:65], v[202:205], v[90:93]
	s_waitcnt lgkmcnt(0)
	v_mfma_f32_16x16x32_bf16 v[90:93], v[160:163], v[206:209], v[62:65]
	v_mfma_f32_16x16x32_bf16 v[62:65], v[164:167], v[188:191], v[86:89]
	v_mfma_f32_16x16x32_bf16 v[86:89], v[168:171], v[192:195], v[62:65]
	v_mfma_f32_16x16x32_bf16 v[62:65], v[164:167], v[202:205], v[82:85]
	v_mfma_f32_16x16x32_bf16 v[82:85], v[168:171], v[206:209], v[62:65]
	v_mfma_f32_16x16x32_bf16 v[62:65], v[172:175], v[188:191], v[78:81]
	v_mfma_f32_16x16x32_bf16 v[78:81], v[176:179], v[192:195], v[62:65]
	v_mfma_f32_16x16x32_bf16 v[62:65], v[172:175], v[202:205], v[74:77]
	v_mfma_f32_16x16x32_bf16 v[74:77], v[176:179], v[206:209], v[62:65]
	v_mfma_f32_16x16x32_bf16 v[62:65], v[180:183], v[188:191], v[70:73]
	v_mfma_f32_16x16x32_bf16 v[70:73], v[184:187], v[192:195], v[62:65]
	v_mfma_f32_16x16x32_bf16 v[62:65], v[180:183], v[202:205], v[66:69]
	v_mfma_f32_16x16x32_bf16 v[98:101], v[160:163], v[192:195], v[98:101]
	v_mfma_f32_16x16x32_bf16 v[62:65], v[184:187], v[206:209], v[62:65]
	s_setprio 0
	s_barrier
	ds_read_b128 v[160:163], v141 offset:49152
	ds_read_b128 v[164:167], v141 offset:50176
	ds_read_b128 v[168:171], v140 offset:49152
	ds_read_b128 v[140:143], v140 offset:50176
	ds_read_b128 v[172:175], v139 offset:49152
	ds_read_b128 v[176:179], v139 offset:50176
	ds_read_b128 v[180:183], v135 offset:49152
	ds_read_b128 v[184:187], v135 offset:50176
	s_barrier
	s_waitcnt lgkmcnt(0)
	s_setprio 1
	s_waitcnt lgkmcnt(7)
	v_mfma_f32_16x16x32_bf16 v[66:69], v[160:163], v[144:147], v[198:201]
	v_mfma_f32_16x16x32_bf16 v[58:61], v[160:163], v[152:155], v[58:61]
	s_waitcnt lgkmcnt(5)
	v_mfma_f32_16x16x32_bf16 v[54:57], v[168:171], v[144:147], v[54:57]
	v_mfma_f32_16x16x32_bf16 v[50:53], v[168:171], v[152:155], v[50:53]
	s_waitcnt lgkmcnt(3)
	v_mfma_f32_16x16x32_bf16 v[46:49], v[172:175], v[144:147], v[46:49]
	v_mfma_f32_16x16x32_bf16 v[42:45], v[172:175], v[152:155], v[42:45]
	s_waitcnt lgkmcnt(1)
	v_mfma_f32_16x16x32_bf16 v[38:41], v[180:183], v[144:147], v[38:41]
	v_mfma_f32_16x16x32_bf16 v[34:37], v[180:183], v[152:155], v[34:37]
	v_mfma_f32_16x16x32_bf16 v[66:69], v[164:167], v[148:151], v[66:69]
	v_mfma_f32_16x16x32_bf16 v[58:61], v[164:167], v[156:159], v[58:61]
	v_mfma_f32_16x16x32_bf16 v[54:57], v[140:143], v[148:151], v[54:57]
	v_mfma_f32_16x16x32_bf16 v[50:53], v[140:143], v[156:159], v[50:53]
	v_mfma_f32_16x16x32_bf16 v[46:49], v[176:179], v[148:151], v[46:49]
	v_mfma_f32_16x16x32_bf16 v[42:45], v[176:179], v[156:159], v[42:45]
	s_waitcnt lgkmcnt(0)
	v_mfma_f32_16x16x32_bf16 v[38:41], v[184:187], v[148:151], v[38:41]
	v_mfma_f32_16x16x32_bf16 v[34:37], v[184:187], v[156:159], v[34:37]
	s_setprio 0
	s_setprio 1
	v_mfma_f32_16x16x32_bf16 v[30:33], v[160:163], v[188:191], v[30:33]
	v_mfma_f32_16x16x32_bf16 v[26:29], v[160:163], v[202:205], v[26:29]
	v_mfma_f32_16x16x32_bf16 v[22:25], v[168:171], v[188:191], v[22:25]
	v_mfma_f32_16x16x32_bf16 v[18:21], v[168:171], v[202:205], v[18:21]
	v_mfma_f32_16x16x32_bf16 v[14:17], v[172:175], v[188:191], v[14:17]
	v_mfma_f32_16x16x32_bf16 v[10:13], v[172:175], v[202:205], v[10:13]
	v_mfma_f32_16x16x32_bf16 v[6:9], v[180:183], v[188:191], v[6:9]
	v_mfma_f32_16x16x32_bf16 v[2:5], v[180:183], v[202:205], v[2:5]
	v_mfma_f32_16x16x32_bf16 v[30:33], v[164:167], v[192:195], v[30:33]
	v_mfma_f32_16x16x32_bf16 v[26:29], v[164:167], v[206:209], v[26:29]
	v_mfma_f32_16x16x32_bf16 v[22:25], v[140:143], v[192:195], v[22:25]
	v_mfma_f32_16x16x32_bf16 v[18:21], v[140:143], v[206:209], v[18:21]
	v_mfma_f32_16x16x32_bf16 v[14:17], v[176:179], v[192:195], v[14:17]
	v_mfma_f32_16x16x32_bf16 v[10:13], v[176:179], v[206:209], v[10:13]
	v_mfma_f32_16x16x32_bf16 v[6:9], v[184:187], v[192:195], v[6:9]
	v_mfma_f32_16x16x32_bf16 v[2:5], v[184:187], v[206:209], v[2:5]
	s_setprio 0
	v_cmp_gt_u32_e32 vcc, s37, v137
	s_barrier
	s_and_saveexec_b64 s[0:1], vcc
	s_cbranch_execz .LBB0_1951
	s_barrier

; #define STAGE(P, BASE, LD, br, kt) do { const int _so = (int)(((br) * (LD) + (kt) * BK) * 2); \
;     _Pragma("unroll") for (int _i = 0; _i < 2; ++_i) { \
;       __builtin_amdgcn_raw_ptr_buffer_load_lds(rs##BASE, (__attribute__((address_space(3))) unsigned*)((char*)(P) + tid_ * 16 + _i * 8192), 16, (int)off##LD[_i], _so, 0, 0); } } while (0)
; #define LDA_(dst, b, h) _Pragma("unroll") for (int m = 0; m < 4; ++m) _Pragma("unroll") for (int k = 0; k < 2; ++k) \
;     dst[m][k] = *reinterpret_cast<const bf16x8*>((char*)SA(b, h) + lds_byte(wr * 64 + m * 16 + fr, k * 32 + fq * 8))
; #define LDB_(dst, b, h) _Pragma("unroll") for (int n = 0; n < 2; ++n) _Pragma("unroll") for (int k = 0; k < 2; ++k) \
;     dst[n][k] = *reinterpret_cast<const bf16x8*>((char*)SB(b, h) + lds_byte(wc * 32 + n * 16 + fr, k * 32 + fq * 8))
; #define MMA(ai, bj, At, Bx) do { __builtin_amdgcn_s_setprio(1); \
;     _Pragma("unroll") for (int m = 0; m < 4; ++m) _Pragma("unroll") for (int n = 0; n < 2; ++n) _Pragma("unroll") for (int k = 0; k < 2; ++k) \
;       acc[ai][bj][m][n] = __builtin_amdgcn_mfma_f32_16x16x32_bf16(At[m][k], Bx[n][k], acc[ai][bj][m][n], 0, 0, 0); \
;     __builtin_amdgcn_s_setprio(0); } while (0)
; #define WAIT_L(n) asm volatile("s_waitcnt lgkmcnt(" #n ")" ::: "memory")
; #define BAR __builtin_amdgcn_s_barrier()
; #define SCHED __builtin_amdgcn_sched_barrier(0)
; template <int K, int LDA, int LDB>
; DEVI void gemm_tile(const bf16* __restrict__ A, const bf16* __restrict__ Bt, bf16* shm, acc_t& acc) {
;     ...
;     LDB_(B0, 0, 0); SCHED; LDA_(At, 0, 0); STAGE(SA(1, 1), A, LDA, HALF, t + 1);
;     WAIT_L(8); BAR; WAIT_L(0); MMA(0, 0, At, B0); BAR; SCHED;
;     LDB_(B1, 0, 1); STAGE(SB(0, 0), Bt, LDB, 0, t + 2);
;     BAR; WAIT_L(0); MMA(0, 1, At, B1); BAR;
;     LDA_(At, 0, 1); STAGE(SA(0, 0), A, LDA, 0, t + 2);
;     BAR; WAIT_L(0); MMA(1, 0, At, B0); BAR; SCHED;
.LBB0_2010:
	ds_read_b128 v[162:165], v160
	ds_read_b128 v[166:169], v160 offset:1024
	ds_read_b128 v[170:173], v160 offset:2048
	ds_read_b128 v[174:177], v160 offset:3072
	v_readfirstlane_b32 s69, v156
	s_add_i32 s68, s13, 0xffffff00
	s_mov_b32 m0, s69
	v_readfirstlane_b32 s69, v159
	ds_read_b128 v[178:181], v138
	ds_read_b128 v[182:185], v138 offset:1024
	ds_read_b128 v[186:189], v137
	ds_read_b128 v[190:193], v137 offset:1024
	ds_read_b128 v[194:197], v136
	ds_read_b128 v[198:201], v136 offset:1024
	ds_read_b128 v[202:205], v135
	ds_read_b128 v[206:209], v135 offset:1024
	buffer_load_dwordx4 v139, s[8:11], s68 offen lds
	s_mov_b32 m0, s69
	s_nop 0
	buffer_load_dwordx4 v141, s[8:11], s68 offen lds
	s_waitcnt lgkmcnt(8)
	s_barrier
	s_waitcnt lgkmcnt(0)
	s_setprio 1
	s_waitcnt lgkmcnt(7)
	v_mfma_f32_16x16x32_bf16 v[126:129], v[178:181], v[162:165], v[126:129]
	v_mfma_f32_16x16x32_bf16 v[122:125], v[178:181], v[170:173], v[122:125]
	s_waitcnt lgkmcnt(5)
	v_mfma_f32_16x16x32_bf16 v[118:121], v[186:189], v[162:165], v[118:121]
	v_mfma_f32_16x16x32_bf16 v[114:117], v[186:189], v[170:173], v[114:117]
	s_waitcnt lgkmcnt(3)
	v_mfma_f32_16x16x32_bf16 v[110:113], v[194:197], v[162:165], v[110:113]
	v_mfma_f32_16x16x32_bf16 v[106:109], v[194:197], v[170:173], v[106:109]
	s_waitcnt lgkmcnt(1)
	v_mfma_f32_16x16x32_bf16 v[102:105], v[202:205], v[162:165], v[102:105]
	v_mfma_f32_16x16x32_bf16 v[98:101], v[202:205], v[170:173], v[98:101]
	v_mfma_f32_16x16x32_bf16 v[126:129], v[182:185], v[166:169], v[126:129]
	v_mfma_f32_16x16x32_bf16 v[122:125], v[182:185], v[174:177], v[122:125]
	v_mfma_f32_16x16x32_bf16 v[118:121], v[190:193], v[166:169], v[118:121]
	v_mfma_f32_16x16x32_bf16 v[114:117], v[190:193], v[174:177], v[114:117]
	v_mfma_f32_16x16x32_bf16 v[110:113], v[198:201], v[166:169], v[110:113]
	v_mfma_f32_16x16x32_bf16 v[106:109], v[198:201], v[174:177], v[106:109]
	s_waitcnt lgkmcnt(0)
	v_mfma_f32_16x16x32_bf16 v[102:105], v[206:209], v[166:169], v[102:105]
	v_mfma_f32_16x16x32_bf16 v[98:101], v[206:209], v[174:177], v[98:101]
	s_setprio 0
	s_barrier
	v_readfirstlane_b32 s69, v143
	s_add_i32 s68, s13, 0xfff7ff80
	s_mov_b32 m0, s69
	v_readfirstlane_b32 s69, v144
	ds_read_b128 v[210:213], v154
	ds_read_b128 v[214:217], v154 offset:1024
	ds_read_b128 v[218:221], v154 offset:2048
	ds_read_b128 v[222:225], v154 offset:3072
	buffer_load_dwordx4 v139, s[0:3], s68 offen lds
	s_mov_b32 m0, s69
	s_nop 0
	buffer_load_dwordx4 v141, s[0:3], s68 offen lds
	s_barrier
	s_waitcnt lgkmcnt(0)
	s_setprio 1
	s_waitcnt lgkmcnt(3)
	v_mfma_f32_16x16x32_bf16 v[94:97], v[178:181], v[210:213], v[94:97]
	s_waitcnt lgkmcnt(1)
	v_mfma_f32_16x16x32_bf16 v[90:93], v[178:181], v[218:221], v[90:93]
	v_mfma_f32_16x16x32_bf16 v[86:89], v[186:189], v[210:213], v[86:89]
	v_mfma_f32_16x16x32_bf16 v[82:85], v[186:189], v[218:221], v[82:85]
	v_mfma_f32_16x16x32_bf16 v[78:81], v[194:197], v[210:213], v[78:81]
	v_mfma_f32_16x16x32_bf16 v[74:77], v[194:197], v[218:221], v[74:77]
	v_mfma_f32_16x16x32_bf16 v[70:73], v[202:205], v[210:213], v[70:73]
	v_mfma_f32_16x16x32_bf16 v[66:69], v[202:205], v[218:221], v[66:69]
	v_mfma_f32_16x16x32_bf16 v[94:97], v[182:185], v[214:217], v[94:97]
	s_waitcnt lgkmcnt(0)
	v_mfma_f32_16x16x32_bf16 v[90:93], v[182:185], v[222:225], v[90:93]
	v_mfma_f32_16x16x32_bf16 v[86:89], v[190:193], v[214:217], v[86:89]
	v_mfma_f32_16x16x32_bf16 v[82:85], v[190:193], v[222:225], v[82:85]
	v_mfma_f32_16x16x32_bf16 v[78:81], v[198:201], v[214:217], v[78:81]
	v_mfma_f32_16x16x32_bf16 v[74:77], v[198:201], v[222:225], v[74:77]
	v_mfma_f32_16x16x32_bf16 v[70:73], v[206:209], v[214:217], v[70:73]
	v_mfma_f32_16x16x32_bf16 v[66:69], v[206:209], v[222:225], v[66:69]
	s_setprio 0
	v_readfirstlane_b32 s69, v145
	s_mov_b32 m0, s69
	v_readfirstlane_b32 s69, v146
	s_barrier
	ds_read_b128 v[178:181], v138 offset:16384
	ds_read_b128 v[182:185], v138 offset:17408
	ds_read_b128 v[186:189], v137 offset:16384
	ds_read_b128 v[190:193], v137 offset:17408
	ds_read_b128 v[194:197], v136 offset:16384
	ds_read_b128 v[198:201], v136 offset:17408
	ds_read_b128 v[202:205], v135 offset:16384
	ds_read_b128 v[206:209], v135 offset:17408
	buffer_load_dwordx4 v139, s[8:11], s68 offen lds
	s_mov_b32 m0, s69
	s_nop 0
	buffer_load_dwordx4 v141, s[8:11], s68 offen lds
	s_barrier
	s_waitcnt lgkmcnt(0)
	s_setprio 1
	s_waitcnt lgkmcnt(7)
	v_mfma_f32_16x16x32_bf16 v[62:65], v[178:181], v[162:165], v[62:65]
	v_mfma_f32_16x16x32_bf16 v[58:61], v[178:181], v[170:173], v[58:61]
	s_waitcnt lgkmcnt(5)
	v_mfma_f32_16x16x32_bf16 v[54:57], v[186:189], v[162:165], v[54:57]
	v_mfma_f32_16x16x32_bf16 v[50:53], v[186:189], v[170:173], v[50:53]
	s_waitcnt lgkmcnt(3)
	v_mfma_f32_16x16x32_bf16 v[46:49], v[194:197], v[162:165], v[46:49]
	v_mfma_f32_16x16x32_bf16 v[42:45], v[194:197], v[170:173], v[42:45]
	s_waitcnt lgkmcnt(1)
	v_mfma_f32_16x16x32_bf16 v[38:41], v[202:205], v[162:165], v[38:41]
	v_mfma_f32_16x16x32_bf16 v[34:37], v[202:205], v[170:173], v[34:37]
	v_mfma_f32_16x16x32_bf16 v[62:65], v[182:185], v[166:169], v[62:65]
	v_mfma_f32_16x16x32_bf16 v[58:61], v[182:185], v[174:177], v[58:61]
	v_mfma_f32_16x16x32_bf16 v[54:57], v[190:193], v[166:169], v[54:57]
	v_mfma_f32_16x16x32_bf16 v[50:53], v[190:193], v[174:177], v[50:53]
	v_mfma_f32_16x16x32_bf16 v[46:49], v[198:201], v[166:169], v[46:49]
	v_mfma_f32_16x16x32_bf16 v[42:45], v[198:201], v[174:177], v[42:45]
	s_waitcnt lgkmcnt(0)
	v_mfma_f32_16x16x32_bf16 v[38:41], v[206:209], v[166:169], v[38:41]
	v_mfma_f32_16x16x32_bf16 v[34:37], v[206:209], v[174:177], v[34:37]
	s_setprio 0
	s_barrier
; #define STAGE(P, BASE, LD, br, kt) do { const int _so = (int)(((br) * (LD) + (kt) * BK) * 2); \
;     _Pragma("unroll") for (int _i = 0; _i < 2; ++_i) { \
;       __builtin_amdgcn_raw_ptr_buffer_load_lds(rs##BASE, (__attribute__((address_space(3))) unsigned*)((char*)(P) + tid_ * 16 + _i * 8192), 16, (int)off##LD[_i], _so, 0, 0); } } while (0)
; #define LDA_(dst, b, h) _Pragma("unroll") for (int m = 0; m < 4; ++m) _Pragma("unroll") for (int k = 0; k < 2; ++k) \
;     dst[m][k] = *reinterpret_cast<const bf16x8*>((char*)SA(b, h) + lds_byte(wr * 64 + m * 16 + fr, k * 32 + fq * 8))
; #define LDB_(dst, b, h) _Pragma("unroll") for (int n = 0; n < 2; ++n) _Pragma("unroll") for (int k = 0; k < 2; ++k) \
;     dst[n][k] = *reinterpret_cast<const bf16x8*>((char*)SB(b, h) + lds_byte(wc * 32 + n * 16 + fr, k * 32 + fq * 8))
; #define MMA(ai, bj, At, Bx) do { __builtin_amdgcn_s_setprio(1); \
;     _Pragma("unroll") for (int m = 0; m < 4; ++m) _Pragma("unroll") for (int n = 0; n < 2; ++n) _Pragma("unroll") for (int k = 0; k < 2; ++k) \
;       acc[ai][bj][m][n] = __builtin_amdgcn_mfma_f32_16x16x32_bf16(At[m][k], Bx[n][k], acc[ai][bj][m][n], 0, 0, 0); \
;     __builtin_amdgcn_s_setprio(0); } while (0)
; #define WAIT_V(n) asm volatile("s_waitcnt vmcnt(" #n ")" ::: "memory")
; #define WAIT_L(n) asm volatile("s_waitcnt lgkmcnt(" #n ")" ::: "memory")
; #define BAR __builtin_amdgcn_s_barrier()
; #define SCHED __builtin_amdgcn_sched_barrier(0)
; template <int K, int LDA, int LDB>
; DEVI void gemm_tile(const bf16* __restrict__ A, const bf16* __restrict__ Bt, bf16* shm, acc_t& acc) {
;     ...
;     STAGE(SB(0, 1), Bt, LDB, HALF, t + 2);
;     WAIT_V(6); BAR; MMA(1, 1, At, B1); BAR;
;     LDB_(B0, 1, 0); SCHED; LDA_(At, 1, 0); STAGE(SA(0, 1), A, LDA, HALF, t + 2);
;     WAIT_L(8); BAR; WAIT_L(0); MMA(0, 0, At, B0); BAR; SCHED;
;     LDB_(B1, 1, 1); STAGE(SB(1, 0), Bt, LDB, 0, t + 3);
;     BAR; WAIT_L(0); MMA(0, 1, At, B1); BAR;
;     LDA_(At, 1, 1); STAGE(SA(1, 0), A, LDA, 0, t + 3);
	v_readfirstlane_b32 s69, v147
	s_add_i32 s68, s13, 0xffffff80
	s_mov_b32 m0, s69
	v_readfirstlane_b32 s69, v148
	buffer_load_dwordx4 v139, s[0:3], s68 offen lds
	s_mov_b32 m0, s69
	s_nop 0
	buffer_load_dwordx4 v141, s[0:3], s68 offen lds
	s_waitcnt vmcnt(6)
	s_barrier
	s_setprio 1
	v_mfma_f32_16x16x32_bf16 v[30:33], v[178:181], v[210:213], v[30:33]
	v_mfma_f32_16x16x32_bf16 v[26:29], v[178:181], v[218:221], v[26:29]
	v_mfma_f32_16x16x32_bf16 v[22:25], v[186:189], v[210:213], v[22:25]
	v_mfma_f32_16x16x32_bf16 v[18:21], v[186:189], v[218:221], v[18:21]
	v_mfma_f32_16x16x32_bf16 v[14:17], v[194:197], v[210:213], v[14:17]
	v_mfma_f32_16x16x32_bf16 v[10:13], v[194:197], v[218:221], v[10:13]
	v_mfma_f32_16x16x32_bf16 v[6:9], v[202:205], v[210:213], v[6:9]
	v_mfma_f32_16x16x32_bf16 v[2:5], v[202:205], v[218:221], v[2:5]
	v_mfma_f32_16x16x32_bf16 v[30:33], v[182:185], v[214:217], v[30:33]
	v_mfma_f32_16x16x32_bf16 v[26:29], v[182:185], v[222:225], v[26:29]
	v_mfma_f32_16x16x32_bf16 v[22:25], v[190:193], v[214:217], v[22:25]
	v_mfma_f32_16x16x32_bf16 v[18:21], v[190:193], v[222:225], v[18:21]
	v_mfma_f32_16x16x32_bf16 v[14:17], v[198:201], v[214:217], v[14:17]
	v_mfma_f32_16x16x32_bf16 v[10:13], v[198:201], v[222:225], v[10:13]
	v_mfma_f32_16x16x32_bf16 v[6:9], v[206:209], v[214:217], v[6:9]
	v_mfma_f32_16x16x32_bf16 v[2:5], v[206:209], v[222:225], v[2:5]
	s_setprio 0
	s_barrier
	ds_read_b128 v[162:165], v142
	ds_read_b128 v[166:169], v142 offset:1024
	ds_read_b128 v[170:173], v142 offset:2048
	ds_read_b128 v[174:177], v142 offset:3072
	v_readfirstlane_b32 s69, v149
	s_mov_b32 m0, s69
	v_readfirstlane_b32 s69, v150
	ds_read_b128 v[178:181], v138 offset:32768
	ds_read_b128 v[182:185], v138 offset:33792
	ds_read_b128 v[186:189], v137 offset:32768
	ds_read_b128 v[190:193], v137 offset:33792
	ds_read_b128 v[194:197], v136 offset:32768
	ds_read_b128 v[198:201], v136 offset:33792
	ds_read_b128 v[202:205], v135 offset:32768
	ds_read_b128 v[206:209], v135 offset:33792
	buffer_load_dwordx4 v139, s[8:11], s68 offen lds
	s_mov_b32 m0, s69
	s_nop 0
	buffer_load_dwordx4 v141, s[8:11], s68 offen lds
	s_waitcnt lgkmcnt(8)
	s_barrier
	s_waitcnt lgkmcnt(0)
	s_setprio 1
	s_waitcnt lgkmcnt(7)
	v_mfma_f32_16x16x32_bf16 v[126:129], v[178:181], v[162:165], v[126:129]
	v_mfma_f32_16x16x32_bf16 v[122:125], v[178:181], v[170:173], v[122:125]
	s_waitcnt lgkmcnt(5)
	v_mfma_f32_16x16x32_bf16 v[118:121], v[186:189], v[162:165], v[118:121]
	v_mfma_f32_16x16x32_bf16 v[114:117], v[186:189], v[170:173], v[114:117]
	s_waitcnt lgkmcnt(3)
	v_mfma_f32_16x16x32_bf16 v[110:113], v[194:197], v[162:165], v[110:113]
	v_mfma_f32_16x16x32_bf16 v[106:109], v[194:197], v[170:173], v[106:109]
	s_waitcnt lgkmcnt(1)
	v_mfma_f32_16x16x32_bf16 v[102:105], v[202:205], v[162:165], v[102:105]
	v_mfma_f32_16x16x32_bf16 v[98:101], v[202:205], v[170:173], v[98:101]
	v_mfma_f32_16x16x32_bf16 v[126:129], v[182:185], v[166:169], v[126:129]
	v_mfma_f32_16x16x32_bf16 v[122:125], v[182:185], v[174:177], v[122:125]
	v_mfma_f32_16x16x32_bf16 v[118:121], v[190:193], v[166:169], v[118:121]
	v_mfma_f32_16x16x32_bf16 v[114:117], v[190:193], v[174:177], v[114:117]
	v_mfma_f32_16x16x32_bf16 v[110:113], v[198:201], v[166:169], v[110:113]
	v_mfma_f32_16x16x32_bf16 v[106:109], v[198:201], v[174:177], v[106:109]
	s_waitcnt lgkmcnt(0)
	v_mfma_f32_16x16x32_bf16 v[102:105], v[206:209], v[166:169], v[102:105]
	v_mfma_f32_16x16x32_bf16 v[98:101], v[206:209], v[174:177], v[98:101]
	s_setprio 0
	s_barrier
	v_readfirstlane_b32 s69, v151
	s_add_i32 s68, s13, 0xfff80000
	s_mov_b32 m0, s69
	v_readfirstlane_b32 s69, v152
	ds_read_b128 v[210:213], v140
	ds_read_b128 v[214:217], v140 offset:1024
	ds_read_b128 v[218:221], v140 offset:2048
	ds_read_b128 v[222:225], v140 offset:3072
	buffer_load_dwordx4 v139, s[0:3], s68 offen lds
	s_mov_b32 m0, s69
	s_nop 0
	buffer_load_dwordx4 v141, s[0:3], s68 offen lds
	s_barrier
	s_waitcnt lgkmcnt(0)
	s_setprio 1
	s_waitcnt lgkmcnt(3)
	v_mfma_f32_16x16x32_bf16 v[94:97], v[178:181], v[210:213], v[94:97]
	s_waitcnt lgkmcnt(1)
	v_mfma_f32_16x16x32_bf16 v[90:93], v[178:181], v[218:221], v[90:93]
	v_mfma_f32_16x16x32_bf16 v[86:89], v[186:189], v[210:213], v[86:89]
	v_mfma_f32_16x16x32_bf16 v[82:85], v[186:189], v[218:221], v[82:85]
	v_mfma_f32_16x16x32_bf16 v[78:81], v[194:197], v[210:213], v[78:81]
	v_mfma_f32_16x16x32_bf16 v[74:77], v[194:197], v[218:221], v[74:77]
	v_mfma_f32_16x16x32_bf16 v[70:73], v[202:205], v[210:213], v[70:73]
	v_mfma_f32_16x16x32_bf16 v[66:69], v[202:205], v[218:221], v[66:69]
	v_mfma_f32_16x16x32_bf16 v[94:97], v[182:185], v[214:217], v[94:97]
	s_waitcnt lgkmcnt(0)
	v_mfma_f32_16x16x32_bf16 v[90:93], v[182:185], v[222:225], v[90:93]
	v_mfma_f32_16x16x32_bf16 v[86:89], v[190:193], v[214:217], v[86:89]
	v_mfma_f32_16x16x32_bf16 v[82:85], v[190:193], v[222:225], v[82:85]
	v_mfma_f32_16x16x32_bf16 v[78:81], v[198:201], v[214:217], v[78:81]
	v_mfma_f32_16x16x32_bf16 v[74:77], v[198:201], v[222:225], v[74:77]
	v_mfma_f32_16x16x32_bf16 v[70:73], v[206:209], v[214:217], v[70:73]
	v_mfma_f32_16x16x32_bf16 v[66:69], v[206:209], v[222:225], v[66:69]
	s_setprio 0
	v_readfirstlane_b32 s69, v153
	s_mov_b32 m0, s69
	v_readfirstlane_b32 s69, v155
	s_barrier
	ds_read_b128 v[178:181], v138 offset:49152
	ds_read_b128 v[182:185], v138 offset:50176
	ds_read_b128 v[186:189], v137 offset:49152
	ds_read_b128 v[190:193], v137 offset:50176
	ds_read_b128 v[194:197], v136 offset:49152
	ds_read_b128 v[198:201], v136 offset:50176
	ds_read_b128 v[202:205], v135 offset:49152
	ds_read_b128 v[206:209], v135 offset:50176
	buffer_load_dwordx4 v139, s[8:11], s68 offen lds
	s_mov_b32 m0, s69
	s_nop 0
	buffer_load_dwordx4 v141, s[8:11], s68 offen lds
	s_barrier
; #define STAGE(P, BASE, LD, br, kt) do { const int _so = (int)(((br) * (LD) + (kt) * BK) * 2); \
;     _Pragma("unroll") for (int _i = 0; _i < 2; ++_i) { \
;       __builtin_amdgcn_raw_ptr_buffer_load_lds(rs##BASE, (__attribute__((address_space(3))) unsigned*)((char*)(P) + tid_ * 16 + _i * 8192), 16, (int)off##LD[_i], _so, 0, 0); } } while (0)
; #define LDA_(dst, b, h) _Pragma("unroll") for (int m = 0; m < 4; ++m) _Pragma("unroll") for (int k = 0; k < 2; ++k) \
;     dst[m][k] = *reinterpret_cast<const bf16x8*>((char*)SA(b, h) + lds_byte(wr * 64 + m * 16 + fr, k * 32 + fq * 8))
; #define LDB_(dst, b, h) _Pragma("unroll") for (int n = 0; n < 2; ++n) _Pragma("unroll") for (int k = 0; k < 2; ++k) \
;     dst[n][k] = *reinterpret_cast<const bf16x8*>((char*)SB(b, h) + lds_byte(wc * 32 + n * 16 + fr, k * 32 + fq * 8))
; #define MMA(ai, bj, At, Bx) do { __builtin_amdgcn_s_setprio(1); \
;     _Pragma("unroll") for (int m = 0; m < 4; ++m) _Pragma("unroll") for (int n = 0; n < 2; ++n) _Pragma("unroll") for (int k = 0; k < 2; ++k) \
;       acc[ai][bj][m][n] = __builtin_amdgcn_mfma_f32_16x16x32_bf16(At[m][k], Bx[n][k], acc[ai][bj][m][n], 0, 0, 0); \
;     __builtin_amdgcn_s_setprio(0); } while (0)
; #define WAIT_V(n) asm volatile("s_waitcnt vmcnt(" #n ")" ::: "memory")
; #define WAIT_L(n) asm volatile("s_waitcnt lgkmcnt(" #n ")" ::: "memory")
; #define BAR __builtin_amdgcn_s_barrier()
; #define SCHED __builtin_amdgcn_sched_barrier(0)
; template <int K, int LDA, int LDB>
; DEVI void gemm_tile(const bf16* __restrict__ A, const bf16* __restrict__ Bt, bf16* shm, acc_t& acc) {
;     ...
;     BAR; WAIT_L(0); MMA(1, 0, At, B0); BAR; SCHED;
;     STAGE(SB(1, 1), Bt, LDB, HALF, t + 3);
;     WAIT_V(6); BAR; MMA(1, 1, At, B1); BAR;
;   }
;   { LDB_(B0, 0, 0); LDA_(At, 0, 0); STAGE(SA(1, 1), A, LDA, HALF, nt - 1);
;     BAR; WAIT_L(0); MMA(0, 0, At, B0); BAR;
;     LDB_(B1, 0, 1); BAR; WAIT_L(0); MMA(0, 1, At, B1); BAR;
	s_waitcnt lgkmcnt(0)
	s_setprio 1
	s_waitcnt lgkmcnt(7)
	v_mfma_f32_16x16x32_bf16 v[62:65], v[178:181], v[162:165], v[62:65]
	v_mfma_f32_16x16x32_bf16 v[58:61], v[178:181], v[170:173], v[58:61]
	s_waitcnt lgkmcnt(5)
	v_mfma_f32_16x16x32_bf16 v[54:57], v[186:189], v[162:165], v[54:57]
	v_mfma_f32_16x16x32_bf16 v[50:53], v[186:189], v[170:173], v[50:53]
	s_waitcnt lgkmcnt(3)
	v_mfma_f32_16x16x32_bf16 v[46:49], v[194:197], v[162:165], v[46:49]
	v_mfma_f32_16x16x32_bf16 v[42:45], v[194:197], v[170:173], v[42:45]
	s_waitcnt lgkmcnt(1)
	v_mfma_f32_16x16x32_bf16 v[38:41], v[202:205], v[162:165], v[38:41]
	v_mfma_f32_16x16x32_bf16 v[34:37], v[202:205], v[170:173], v[34:37]
	v_mfma_f32_16x16x32_bf16 v[62:65], v[182:185], v[166:169], v[62:65]
	v_mfma_f32_16x16x32_bf16 v[58:61], v[182:185], v[174:177], v[58:61]
	v_mfma_f32_16x16x32_bf16 v[54:57], v[190:193], v[166:169], v[54:57]
	v_mfma_f32_16x16x32_bf16 v[50:53], v[190:193], v[174:177], v[50:53]
	v_mfma_f32_16x16x32_bf16 v[46:49], v[198:201], v[166:169], v[46:49]
	v_mfma_f32_16x16x32_bf16 v[42:45], v[198:201], v[174:177], v[42:45]
	s_waitcnt lgkmcnt(0)
	v_mfma_f32_16x16x32_bf16 v[38:41], v[206:209], v[166:169], v[38:41]
	v_mfma_f32_16x16x32_bf16 v[34:37], v[206:209], v[174:177], v[34:37]
	s_setprio 0
	s_barrier
	v_readfirstlane_b32 s68, v157
	s_mov_b32 m0, s68
	v_readfirstlane_b32 s68, v158
	buffer_load_dwordx4 v139, s[0:3], s13 offen lds
	s_mov_b32 m0, s68
	s_nop 0
	buffer_load_dwordx4 v141, s[0:3], s13 offen lds
	s_waitcnt vmcnt(6)
	s_barrier
	s_setprio 1
	v_mfma_f32_16x16x32_bf16 v[30:33], v[178:181], v[210:213], v[30:33]
	v_mfma_f32_16x16x32_bf16 v[26:29], v[178:181], v[218:221], v[26:29]
	v_mfma_f32_16x16x32_bf16 v[22:25], v[186:189], v[210:213], v[22:25]
	v_mfma_f32_16x16x32_bf16 v[18:21], v[186:189], v[218:221], v[18:21]
	v_mfma_f32_16x16x32_bf16 v[14:17], v[194:197], v[210:213], v[14:17]
	v_mfma_f32_16x16x32_bf16 v[10:13], v[194:197], v[218:221], v[10:13]
	v_mfma_f32_16x16x32_bf16 v[6:9], v[202:205], v[210:213], v[6:9]
	v_mfma_f32_16x16x32_bf16 v[2:5], v[202:205], v[218:221], v[2:5]
	v_mfma_f32_16x16x32_bf16 v[30:33], v[182:185], v[214:217], v[30:33]
	v_mfma_f32_16x16x32_bf16 v[26:29], v[182:185], v[222:225], v[26:29]
	v_mfma_f32_16x16x32_bf16 v[22:25], v[190:193], v[214:217], v[22:25]
	v_mfma_f32_16x16x32_bf16 v[18:21], v[190:193], v[222:225], v[18:21]
	v_mfma_f32_16x16x32_bf16 v[14:17], v[198:201], v[214:217], v[14:17]
	v_mfma_f32_16x16x32_bf16 v[10:13], v[198:201], v[222:225], v[10:13]
	v_mfma_f32_16x16x32_bf16 v[6:9], v[206:209], v[214:217], v[6:9]
	v_mfma_f32_16x16x32_bf16 v[2:5], v[206:209], v[222:225], v[2:5]
	s_setprio 0
	s_add_i32 s7, s7, 2
	s_addk_i32 s13, 0x100
	s_cmp_lt_u32 s7, 28
	s_cbranch_scc1 .Lrot_44699
	s_barrier
	v_readfirstlane_b32 s0, v156
	s_mov_b32 s10, s2
	s_mov_b32 s11, s3
	s_mov_b32 m0, s0
	v_readfirstlane_b32 s0, v159
	ds_read_b128 v[144:147], v160
	ds_read_b128 v[148:151], v160 offset:1024
	ds_read_b128 v[162:165], v160 offset:2048
	ds_read_b128 v[166:169], v160 offset:3072
	ds_read_b128 v[170:173], v138
	ds_read_b128 v[174:177], v138 offset:1024
	ds_read_b128 v[178:181], v137
	ds_read_b128 v[182:185], v137 offset:1024
	ds_read_b128 v[186:189], v136
	ds_read_b128 v[190:193], v136 offset:1024
	ds_read_b128 v[194:197], v135
	ds_read_b128 v[198:201], v135 offset:1024
	buffer_load_dwordx4 v139, s[8:11], s38 offen lds
	s_mov_b32 m0, s0
	s_nop 0
	buffer_load_dwordx4 v141, s[8:11], s38 offen lds
	s_barrier
	s_waitcnt lgkmcnt(0)
	s_setprio 1
	s_waitcnt lgkmcnt(7)
	v_mfma_f32_16x16x32_bf16 v[126:129], v[170:173], v[144:147], v[126:129]
	v_mfma_f32_16x16x32_bf16 v[122:125], v[170:173], v[162:165], v[122:125]
	s_waitcnt lgkmcnt(5)
	v_mfma_f32_16x16x32_bf16 v[118:121], v[178:181], v[144:147], v[118:121]
	v_mfma_f32_16x16x32_bf16 v[114:117], v[178:181], v[162:165], v[114:117]
	s_waitcnt lgkmcnt(3)
	v_mfma_f32_16x16x32_bf16 v[110:113], v[186:189], v[144:147], v[110:113]
	v_mfma_f32_16x16x32_bf16 v[106:109], v[186:189], v[162:165], v[106:109]
	s_waitcnt lgkmcnt(1)
	v_mfma_f32_16x16x32_bf16 v[102:105], v[194:197], v[144:147], v[102:105]
	v_mfma_f32_16x16x32_bf16 v[98:101], v[194:197], v[162:165], v[98:101]
	v_mfma_f32_16x16x32_bf16 v[126:129], v[174:177], v[148:151], v[126:129]
	v_mfma_f32_16x16x32_bf16 v[122:125], v[174:177], v[166:169], v[122:125]
	v_mfma_f32_16x16x32_bf16 v[118:121], v[182:185], v[148:151], v[118:121]
	v_mfma_f32_16x16x32_bf16 v[114:117], v[182:185], v[166:169], v[114:117]
	v_mfma_f32_16x16x32_bf16 v[110:113], v[190:193], v[148:151], v[110:113]
	v_mfma_f32_16x16x32_bf16 v[106:109], v[190:193], v[166:169], v[106:109]
	s_waitcnt lgkmcnt(0)
	v_mfma_f32_16x16x32_bf16 v[102:105], v[198:201], v[148:151], v[102:105]
	v_mfma_f32_16x16x32_bf16 v[98:101], v[198:201], v[166:169], v[98:101]
	s_setprio 0
	s_barrier
	ds_read_b128 v[156:159], v154
	ds_read_b128 v[202:205], v154 offset:1024
	ds_read_b128 v[206:209], v154 offset:2048
	ds_read_b128 v[152:155], v154 offset:3072
	s_barrier
	s_waitcnt lgkmcnt(0)
	s_setprio 1
	s_waitcnt lgkmcnt(3)
	v_mfma_f32_16x16x32_bf16 v[94:97], v[170:173], v[156:159], v[94:97]
	s_waitcnt lgkmcnt(1)
	v_mfma_f32_16x16x32_bf16 v[90:93], v[170:173], v[206:209], v[90:93]
	v_mfma_f32_16x16x32_bf16 v[86:89], v[178:181], v[156:159], v[86:89]
	v_mfma_f32_16x16x32_bf16 v[78:81], v[186:189], v[156:159], v[78:81]
	v_mfma_f32_16x16x32_bf16 v[70:73], v[194:197], v[156:159], v[70:73]
	v_mfma_f32_16x16x32_bf16 v[94:97], v[174:177], v[202:205], v[94:97]
	s_waitcnt lgkmcnt(0)
	v_mfma_f32_16x16x32_bf16 v[90:93], v[174:177], v[152:155], v[90:93]
	v_mfma_f32_16x16x32_bf16 v[86:89], v[182:185], v[202:205], v[86:89]
	v_mfma_f32_16x16x32_bf16 v[82:85], v[178:181], v[206:209], v[82:85]
	v_mfma_f32_16x16x32_bf16 v[78:81], v[190:193], v[202:205], v[78:81]
	v_mfma_f32_16x16x32_bf16 v[74:77], v[186:189], v[206:209], v[74:77]
	v_mfma_f32_16x16x32_bf16 v[70:73], v[198:201], v[202:205], v[70:73]
	v_mfma_f32_16x16x32_bf16 v[66:69], v[194:197], v[206:209], v[66:69]
	v_mfma_f32_16x16x32_bf16 v[170:173], v[182:185], v[152:155], v[82:85]
	v_mfma_f32_16x16x32_bf16 v[174:177], v[190:193], v[152:155], v[74:77]
	v_mfma_f32_16x16x32_bf16 v[178:181], v[198:201], v[152:155], v[66:69]
	s_setprio 0
	s_barrier
; #define LDA_(dst, b, h) _Pragma("unroll") for (int m = 0; m < 4; ++m) _Pragma("unroll") for (int k = 0; k < 2; ++k) \
;     dst[m][k] = *reinterpret_cast<const bf16x8*>((char*)SA(b, h) + lds_byte(wr * 64 + m * 16 + fr, k * 32 + fq * 8))
; #define LDB_(dst, b, h) _Pragma("unroll") for (int n = 0; n < 2; ++n) _Pragma("unroll") for (int k = 0; k < 2; ++k) \
;     dst[n][k] = *reinterpret_cast<const bf16x8*>((char*)SB(b, h) + lds_byte(wc * 32 + n * 16 + fr, k * 32 + fq * 8))
; #define MMA(ai, bj, At, Bx) do { __builtin_amdgcn_s_setprio(1); \
;     _Pragma("unroll") for (int m = 0; m < 4; ++m) _Pragma("unroll") for (int n = 0; n < 2; ++n) _Pragma("unroll") for (int k = 0; k < 2; ++k) \
;       acc[ai][bj][m][n] = __builtin_amdgcn_mfma_f32_16x16x32_bf16(At[m][k], Bx[n][k], acc[ai][bj][m][n], 0, 0, 0); \
;     __builtin_amdgcn_s_setprio(0); } while (0)
; #define WAIT_V(n) asm volatile("s_waitcnt vmcnt(" #n ")" ::: "memory")
; #define WAIT_L(n) asm volatile("s_waitcnt lgkmcnt(" #n ")" ::: "memory")
; #define BAR __builtin_amdgcn_s_barrier()
; template <int K, int LDA, int LDB>
; DEVI void gemm_tile(const bf16* __restrict__ A, const bf16* __restrict__ Bt, bf16* shm, acc_t& acc) {
;     ...
;     LDA_(At, 0, 1); WAIT_V(4); BAR; WAIT_L(0); MMA(1, 0, At, B0); MMA(1, 1, At, B1); BAR; }
;   { LDB_(B0, 1, 0); LDA_(At, 1, 0); WAIT_V(2); BAR; WAIT_L(0); MMA(0, 0, At, B0); BAR;
	s_nop 2
	ds_read_b128 v[66:69], v138 offset:16384
	ds_read_b128 v[74:77], v138 offset:17408
	ds_read_b128 v[82:85], v137 offset:16384
	ds_read_b128 v[182:185], v137 offset:17408
	ds_read_b128 v[186:189], v136 offset:16384
	ds_read_b128 v[190:193], v136 offset:17408
	ds_read_b128 v[194:197], v135 offset:16384
	ds_read_b128 v[198:201], v135 offset:17408
	s_waitcnt vmcnt(4)
	s_barrier
	s_waitcnt lgkmcnt(0)
	s_setprio 1
	s_waitcnt lgkmcnt(7)
	v_mfma_f32_16x16x32_bf16 v[58:61], v[66:69], v[162:165], v[58:61]
	s_waitcnt lgkmcnt(3)
	v_mfma_f32_16x16x32_bf16 v[46:49], v[186:189], v[144:147], v[46:49]
	s_waitcnt lgkmcnt(1)
	v_mfma_f32_16x16x32_bf16 v[38:41], v[194:197], v[144:147], v[38:41]
	v_mfma_f32_16x16x32_bf16 v[62:65], v[66:69], v[144:147], v[62:65]
	v_mfma_f32_16x16x32_bf16 v[58:61], v[74:77], v[166:169], v[58:61]
	v_mfma_f32_16x16x32_bf16 v[54:57], v[82:85], v[144:147], v[54:57]
	v_mfma_f32_16x16x32_bf16 v[50:53], v[82:85], v[162:165], v[50:53]
	v_mfma_f32_16x16x32_bf16 v[46:49], v[190:193], v[148:151], v[46:49]
	v_mfma_f32_16x16x32_bf16 v[42:45], v[186:189], v[162:165], v[42:45]
	s_waitcnt lgkmcnt(0)
	v_mfma_f32_16x16x32_bf16 v[38:41], v[198:201], v[148:151], v[38:41]
	v_mfma_f32_16x16x32_bf16 v[34:37], v[194:197], v[162:165], v[34:37]
	v_mfma_f32_16x16x32_bf16 v[210:213], v[74:77], v[148:151], v[62:65]
	v_mfma_f32_16x16x32_bf16 v[214:217], v[182:185], v[148:151], v[54:57]
	v_mfma_f32_16x16x32_bf16 v[218:221], v[182:185], v[166:169], v[50:53]
	v_mfma_f32_16x16x32_bf16 v[222:225], v[190:193], v[166:169], v[42:45]
	v_mfma_f32_16x16x32_bf16 v[144:147], v[198:201], v[166:169], v[34:37]
	s_setprio 0
	s_setprio 1
	v_mfma_f32_16x16x32_bf16 v[30:33], v[66:69], v[156:159], v[30:33]
	v_mfma_f32_16x16x32_bf16 v[26:29], v[66:69], v[206:209], v[26:29]
	v_mfma_f32_16x16x32_bf16 v[22:25], v[82:85], v[156:159], v[22:25]
	v_mfma_f32_16x16x32_bf16 v[18:21], v[82:85], v[206:209], v[18:21]
	v_mfma_f32_16x16x32_bf16 v[14:17], v[186:189], v[156:159], v[14:17]
	v_mfma_f32_16x16x32_bf16 v[10:13], v[186:189], v[206:209], v[10:13]
	v_mfma_f32_16x16x32_bf16 v[6:9], v[194:197], v[156:159], v[6:9]
	v_mfma_f32_16x16x32_bf16 v[2:5], v[194:197], v[206:209], v[2:5]
	v_mfma_f32_16x16x32_bf16 v[30:33], v[74:77], v[202:205], v[30:33]
	v_mfma_f32_16x16x32_bf16 v[26:29], v[74:77], v[152:155], v[26:29]
	v_mfma_f32_16x16x32_bf16 v[22:25], v[182:185], v[202:205], v[22:25]
	v_mfma_f32_16x16x32_bf16 v[18:21], v[182:185], v[152:155], v[18:21]
	v_mfma_f32_16x16x32_bf16 v[14:17], v[190:193], v[202:205], v[14:17]
	v_mfma_f32_16x16x32_bf16 v[10:13], v[190:193], v[152:155], v[10:13]
	v_mfma_f32_16x16x32_bf16 v[6:9], v[198:201], v[202:205], v[6:9]
	v_mfma_f32_16x16x32_bf16 v[2:5], v[198:201], v[152:155], v[2:5]
	s_setprio 0
	s_barrier
	ds_read_b128 v[148:151], v142
	ds_read_b128 v[152:155], v142 offset:1024
	ds_read_b128 v[156:159], v142 offset:2048
	ds_read_b128 v[160:163], v142 offset:3072
	ds_read_b128 v[50:53], v138 offset:32768
	ds_read_b128 v[66:69], v138 offset:33792
	ds_read_b128 v[164:167], v137 offset:32768
	ds_read_b128 v[182:185], v137 offset:33792
	ds_read_b128 v[186:189], v136 offset:32768
	ds_read_b128 v[190:193], v136 offset:33792
	ds_read_b128 v[194:197], v135 offset:32768
	ds_read_b128 v[198:201], v135 offset:33792
	s_waitcnt vmcnt(2)
	s_barrier
	s_waitcnt lgkmcnt(0)
	s_setprio 1
	s_waitcnt lgkmcnt(7)
	v_mfma_f32_16x16x32_bf16 v[34:37], v[50:53], v[148:151], v[126:129]
	s_waitcnt lgkmcnt(5)
	v_mfma_f32_16x16x32_bf16 v[42:45], v[164:167], v[148:151], v[118:121]
	s_waitcnt lgkmcnt(3)
	v_mfma_f32_16x16x32_bf16 v[54:57], v[186:189], v[148:151], v[110:113]
	s_waitcnt lgkmcnt(1)
	v_mfma_f32_16x16x32_bf16 v[62:65], v[194:197], v[148:151], v[102:105]
	v_mfma_f32_16x16x32_bf16 v[126:129], v[66:69], v[152:155], v[34:37]
	v_mfma_f32_16x16x32_bf16 v[34:37], v[50:53], v[156:159], v[122:125]
	v_mfma_f32_16x16x32_bf16 v[122:125], v[182:185], v[152:155], v[42:45]
	v_mfma_f32_16x16x32_bf16 v[42:45], v[164:167], v[156:159], v[114:117]
	v_mfma_f32_16x16x32_bf16 v[118:121], v[190:193], v[152:155], v[54:57]
	v_mfma_f32_16x16x32_bf16 v[54:57], v[186:189], v[156:159], v[106:109]
	s_waitcnt lgkmcnt(0)
	v_mfma_f32_16x16x32_bf16 v[114:117], v[198:201], v[152:155], v[62:65]
	v_mfma_f32_16x16x32_bf16 v[62:65], v[194:197], v[156:159], v[98:101]
	v_mfma_f32_16x16x32_bf16 v[34:37], v[66:69], v[160:163], v[34:37]
	v_mfma_f32_16x16x32_bf16 v[42:45], v[182:185], v[160:163], v[42:45]
	v_mfma_f32_16x16x32_bf16 v[54:57], v[190:193], v[160:163], v[54:57]
	v_mfma_f32_16x16x32_bf16 v[74:77], v[198:201], v[160:163], v[62:65]
	s_setprio 0
	s_barrier
; #define LDA_(dst, b, h) _Pragma("unroll") for (int m = 0; m < 4; ++m) _Pragma("unroll") for (int k = 0; k < 2; ++k) \
;     dst[m][k] = *reinterpret_cast<const bf16x8*>((char*)SA(b, h) + lds_byte(wr * 64 + m * 16 + fr, k * 32 + fq * 8))
; #define LDB_(dst, b, h) _Pragma("unroll") for (int n = 0; n < 2; ++n) _Pragma("unroll") for (int k = 0; k < 2; ++k) \
;     dst[n][k] = *reinterpret_cast<const bf16x8*>((char*)SB(b, h) + lds_byte(wc * 32 + n * 16 + fr, k * 32 + fq * 8))
; #define MMA(ai, bj, At, Bx) do { __builtin_amdgcn_s_setprio(1); \
;     _Pragma("unroll") for (int m = 0; m < 4; ++m) _Pragma("unroll") for (int n = 0; n < 2; ++n) _Pragma("unroll") for (int k = 0; k < 2; ++k) \
;       acc[ai][bj][m][n] = __builtin_amdgcn_mfma_f32_16x16x32_bf16(At[m][k], Bx[n][k], acc[ai][bj][m][n], 0, 0, 0); \
;     __builtin_amdgcn_s_setprio(0); } while (0)
; #define WAIT_V(n) asm volatile("s_waitcnt vmcnt(" #n ")" ::: "memory")
; #define WAIT_L(n) asm volatile("s_waitcnt lgkmcnt(" #n ")" ::: "memory")
; #define BAR __builtin_amdgcn_s_barrier()
; template <int K, int LDA, int LDB>
; DEVI void gemm_tile(const bf16* __restrict__ A, const bf16* __restrict__ Bt, bf16* shm, acc_t& acc) {
;     ...
;   { LDB_(B0, 1, 0); LDA_(At, 1, 0); WAIT_V(2); BAR; WAIT_L(0); MMA(0, 0, At, B0); BAR;
;     LDB_(B1, 1, 1); WAIT_V(0); BAR; WAIT_L(0); MMA(0, 1, At, B1); BAR;
;     LDA_(At, 1, 1); BAR; WAIT_L(0); MMA(1, 0, At, B0); MMA(1, 1, At, B1); BAR; }
;   if (wr == 0) BAR;
	ds_read_b128 v[202:205], v140
	ds_read_b128 v[206:209], v140 offset:1024
	ds_read_b128 v[226:229], v140 offset:2048
	ds_read_b128 v[140:143], v140 offset:3072
	s_waitcnt vmcnt(0)
	s_barrier
	s_waitcnt lgkmcnt(0)
	s_setprio 1
	s_waitcnt lgkmcnt(3)
	v_mfma_f32_16x16x32_bf16 v[62:65], v[50:53], v[202:205], v[94:97]
	s_waitcnt lgkmcnt(1)
	v_mfma_f32_16x16x32_bf16 v[50:53], v[50:53], v[226:229], v[90:93]
	v_mfma_f32_16x16x32_bf16 v[62:65], v[66:69], v[206:209], v[62:65]
	s_waitcnt lgkmcnt(0)
	v_mfma_f32_16x16x32_bf16 v[50:53], v[66:69], v[140:143], v[50:53]
	v_mfma_f32_16x16x32_bf16 v[66:69], v[164:167], v[202:205], v[86:89]
	v_mfma_f32_16x16x32_bf16 v[78:81], v[186:189], v[202:205], v[78:81]
	v_mfma_f32_16x16x32_bf16 v[70:73], v[194:197], v[202:205], v[70:73]
	v_mfma_f32_16x16x32_bf16 v[82:85], v[182:185], v[206:209], v[66:69]
	v_mfma_f32_16x16x32_bf16 v[66:69], v[164:167], v[226:229], v[170:173]
	v_mfma_f32_16x16x32_bf16 v[98:101], v[190:193], v[206:209], v[78:81]
	v_mfma_f32_16x16x32_bf16 v[78:81], v[186:189], v[226:229], v[174:177]
	v_mfma_f32_16x16x32_bf16 v[110:113], v[198:201], v[206:209], v[70:73]
	v_mfma_f32_16x16x32_bf16 v[70:73], v[194:197], v[226:229], v[178:181]
	v_mfma_f32_16x16x32_bf16 v[66:69], v[182:185], v[140:143], v[66:69]
	v_mfma_f32_16x16x32_bf16 v[86:89], v[190:193], v[140:143], v[78:81]
	v_mfma_f32_16x16x32_bf16 v[102:105], v[198:201], v[140:143], v[70:73]
	s_setprio 0
	s_barrier
	ds_read_b128 v[164:167], v138 offset:49152
	ds_read_b128 v[168:171], v138 offset:50176
	ds_read_b128 v[172:175], v137 offset:49152
	ds_read_b128 v[176:179], v137 offset:50176
	ds_read_b128 v[180:183], v136 offset:49152
	ds_read_b128 v[136:139], v136 offset:50176
	ds_read_b128 v[184:187], v135 offset:49152
	ds_read_b128 v[188:191], v135 offset:50176
	s_barrier
	s_waitcnt lgkmcnt(0)
	s_setprio 1
	s_waitcnt lgkmcnt(7)
	v_mfma_f32_16x16x32_bf16 v[58:61], v[164:167], v[156:159], v[58:61]
	v_mfma_f32_16x16x32_bf16 v[70:73], v[164:167], v[148:151], v[210:213]
	s_waitcnt lgkmcnt(6)
	v_mfma_f32_16x16x32_bf16 v[94:97], v[168:171], v[160:163], v[58:61]
	s_waitcnt lgkmcnt(5)
	v_mfma_f32_16x16x32_bf16 v[58:61], v[172:175], v[148:151], v[214:217]
	s_waitcnt lgkmcnt(3)
	v_mfma_f32_16x16x32_bf16 v[46:49], v[180:183], v[148:151], v[46:49]
	v_mfma_f32_16x16x32_bf16 v[106:109], v[168:171], v[152:155], v[70:73]
	v_mfma_f32_16x16x32_bf16 v[90:93], v[176:179], v[152:155], v[58:61]
	v_mfma_f32_16x16x32_bf16 v[58:61], v[172:175], v[156:159], v[218:221]
	s_waitcnt lgkmcnt(2)
	v_mfma_f32_16x16x32_bf16 v[70:73], v[136:139], v[152:155], v[46:49]
	v_mfma_f32_16x16x32_bf16 v[46:49], v[180:183], v[156:159], v[222:225]
	s_waitcnt lgkmcnt(1)
	v_mfma_f32_16x16x32_bf16 v[38:41], v[184:187], v[148:151], v[38:41]
	v_mfma_f32_16x16x32_bf16 v[78:81], v[176:179], v[160:163], v[58:61]
	v_mfma_f32_16x16x32_bf16 v[58:61], v[136:139], v[160:163], v[46:49]
	s_waitcnt lgkmcnt(0)
	v_mfma_f32_16x16x32_bf16 v[46:49], v[188:191], v[152:155], v[38:41]
	v_mfma_f32_16x16x32_bf16 v[38:41], v[184:187], v[156:159], v[144:147]
	v_mfma_f32_16x16x32_bf16 v[38:41], v[188:191], v[160:163], v[38:41]
	s_setprio 0
	s_setprio 1
	v_mfma_f32_16x16x32_bf16 v[30:33], v[164:167], v[202:205], v[30:33]
	v_mfma_f32_16x16x32_bf16 v[26:29], v[164:167], v[226:229], v[26:29]
	v_mfma_f32_16x16x32_bf16 v[22:25], v[172:175], v[202:205], v[22:25]
	v_mfma_f32_16x16x32_bf16 v[18:21], v[172:175], v[226:229], v[18:21]
	v_mfma_f32_16x16x32_bf16 v[14:17], v[180:183], v[202:205], v[14:17]
	v_mfma_f32_16x16x32_bf16 v[10:13], v[180:183], v[226:229], v[10:13]
	v_mfma_f32_16x16x32_bf16 v[6:9], v[184:187], v[202:205], v[6:9]
	v_mfma_f32_16x16x32_bf16 v[2:5], v[184:187], v[226:229], v[2:5]
	v_mfma_f32_16x16x32_bf16 v[30:33], v[168:171], v[206:209], v[30:33]
	v_mfma_f32_16x16x32_bf16 v[26:29], v[168:171], v[140:143], v[26:29]
	v_mfma_f32_16x16x32_bf16 v[22:25], v[176:179], v[206:209], v[22:25]
	v_mfma_f32_16x16x32_bf16 v[18:21], v[176:179], v[140:143], v[18:21]
	v_mfma_f32_16x16x32_bf16 v[14:17], v[136:139], v[206:209], v[14:17]
	v_mfma_f32_16x16x32_bf16 v[10:13], v[136:139], v[140:143], v[10:13]
	v_mfma_f32_16x16x32_bf16 v[6:9], v[188:191], v[206:209], v[6:9]
	v_mfma_f32_16x16x32_bf16 v[2:5], v[188:191], v[140:143], v[2:5]
	s_setprio 0
	v_cmp_gt_u32_e32 vcc, s37, v132
	s_barrier
	s_and_saveexec_b64 s[0:1], vcc
	s_cbranch_execz .LBB0_2013
	s_barrier

; #define STAGE(P, BASE, LD, br, kt) do { const int _so = (int)(((br) * (LD) + (kt) * BK) * 2); \
;     _Pragma("unroll") for (int _i = 0; _i < 2; ++_i) { \
;       __builtin_amdgcn_raw_ptr_buffer_load_lds(rs##BASE, (__attribute__((address_space(3))) unsigned*)((char*)(P) + tid_ * 16 + _i * 8192), 16, (int)off##LD[_i], _so, 0, 0); } } while (0)
; #define LDA_(dst, b, h) _Pragma("unroll") for (int m = 0; m < 4; ++m) _Pragma("unroll") for (int k = 0; k < 2; ++k) \
;     dst[m][k] = *reinterpret_cast<const bf16x8*>((char*)SA(b, h) + lds_byte(wr * 64 + m * 16 + fr, k * 32 + fq * 8))
; #define LDB_(dst, b, h) _Pragma("unroll") for (int n = 0; n < 2; ++n) _Pragma("unroll") for (int k = 0; k < 2; ++k) \
;     dst[n][k] = *reinterpret_cast<const bf16x8*>((char*)SB(b, h) + lds_byte(wc * 32 + n * 16 + fr, k * 32 + fq * 8))
; #define MMA(ai, bj, At, Bx) do { __builtin_amdgcn_s_setprio(1); \
;     _Pragma("unroll") for (int m = 0; m < 4; ++m) _Pragma("unroll") for (int n = 0; n < 2; ++n) _Pragma("unroll") for (int k = 0; k < 2; ++k) \
;       acc[ai][bj][m][n] = __builtin_amdgcn_mfma_f32_16x16x32_bf16(At[m][k], Bx[n][k], acc[ai][bj][m][n], 0, 0, 0); \
;     __builtin_amdgcn_s_setprio(0); } while (0)
; #define WAIT_L(n) asm volatile("s_waitcnt lgkmcnt(" #n ")" ::: "memory")
; #define BAR __builtin_amdgcn_s_barrier()
; #define SCHED __builtin_amdgcn_sched_barrier(0)
; template <int K, int LDA, int LDB>
; DEVI void gemm_tile(const bf16* __restrict__ A, const bf16* __restrict__ Bt, bf16* shm, acc_t& acc) {
;     ...
;     LDB_(B0, 0, 0); SCHED; LDA_(At, 0, 0); STAGE(SA(1, 1), A, LDA, HALF, t + 1);
;     WAIT_L(8); BAR; WAIT_L(0); MMA(0, 0, At, B0); BAR; SCHED;
;     LDB_(B1, 0, 1); STAGE(SB(0, 0), Bt, LDB, 0, t + 2);
;     BAR; WAIT_L(0); MMA(0, 1, At, B1); BAR;
;     LDA_(At, 0, 1); STAGE(SA(0, 0), A, LDA, 0, t + 2);
;     BAR; WAIT_L(0); MMA(1, 0, At, B0); BAR; SCHED;
.LBB0_2061:
	ds_read_b128 v[164:167], v162
	ds_read_b128 v[168:171], v162 offset:1024
	ds_read_b128 v[172:175], v162 offset:2048
	ds_read_b128 v[176:179], v162 offset:3072
	v_readfirstlane_b32 s44, v158
	s_add_i32 s43, s15, 0xffffff00
	s_mov_b32 m0, s44
	v_readfirstlane_b32 s44, v161
	ds_read_b128 v[180:183], v137
	ds_read_b128 v[184:187], v137 offset:1024
	ds_read_b128 v[188:191], v136
	ds_read_b128 v[192:195], v136 offset:1024
	ds_read_b128 v[196:199], v135
	ds_read_b128 v[200:203], v135 offset:1024
	ds_read_b128 v[204:207], v134
	ds_read_b128 v[208:211], v134 offset:1024
	buffer_load_dwordx4 v141, s[8:11], s43 offen lds
	s_mov_b32 m0, s44
	s_nop 0
	buffer_load_dwordx4 v143, s[8:11], s43 offen lds
	s_waitcnt lgkmcnt(8)
	s_barrier
	s_waitcnt lgkmcnt(0)
	s_setprio 1
	s_waitcnt lgkmcnt(7)
	v_mfma_f32_16x16x32_bf16 v[126:129], v[180:183], v[164:167], v[126:129]
	v_mfma_f32_16x16x32_bf16 v[122:125], v[180:183], v[172:175], v[122:125]
	s_waitcnt lgkmcnt(5)
	v_mfma_f32_16x16x32_bf16 v[118:121], v[188:191], v[164:167], v[118:121]
	v_mfma_f32_16x16x32_bf16 v[114:117], v[188:191], v[172:175], v[114:117]
	s_waitcnt lgkmcnt(3)
	v_mfma_f32_16x16x32_bf16 v[110:113], v[196:199], v[164:167], v[110:113]
	v_mfma_f32_16x16x32_bf16 v[106:109], v[196:199], v[172:175], v[106:109]
	s_waitcnt lgkmcnt(1)
	v_mfma_f32_16x16x32_bf16 v[102:105], v[204:207], v[164:167], v[102:105]
	v_mfma_f32_16x16x32_bf16 v[98:101], v[204:207], v[172:175], v[98:101]
	v_mfma_f32_16x16x32_bf16 v[126:129], v[184:187], v[168:171], v[126:129]
	v_mfma_f32_16x16x32_bf16 v[122:125], v[184:187], v[176:179], v[122:125]
	v_mfma_f32_16x16x32_bf16 v[118:121], v[192:195], v[168:171], v[118:121]
	v_mfma_f32_16x16x32_bf16 v[114:117], v[192:195], v[176:179], v[114:117]
	v_mfma_f32_16x16x32_bf16 v[110:113], v[200:203], v[168:171], v[110:113]
	v_mfma_f32_16x16x32_bf16 v[106:109], v[200:203], v[176:179], v[106:109]
	s_waitcnt lgkmcnt(0)
	v_mfma_f32_16x16x32_bf16 v[102:105], v[208:211], v[168:171], v[102:105]
	v_mfma_f32_16x16x32_bf16 v[98:101], v[208:211], v[176:179], v[98:101]
	s_setprio 0
	s_barrier
	v_readfirstlane_b32 s44, v145
	s_add_i32 s43, s15, 0xfff7ff80
	s_mov_b32 m0, s44
	v_readfirstlane_b32 s44, v146
	ds_read_b128 v[212:215], v156
	ds_read_b128 v[216:219], v156 offset:1024
	ds_read_b128 v[220:223], v156 offset:2048
	ds_read_b128 v[224:227], v156 offset:3072
	buffer_load_dwordx4 v141, s[4:7], s43 offen lds
	s_mov_b32 m0, s44
	s_nop 0
	buffer_load_dwordx4 v143, s[4:7], s43 offen lds
	s_barrier
	s_waitcnt lgkmcnt(0)
	s_setprio 1
	s_waitcnt lgkmcnt(3)
	v_mfma_f32_16x16x32_bf16 v[94:97], v[180:183], v[212:215], v[94:97]
	s_waitcnt lgkmcnt(1)
	v_mfma_f32_16x16x32_bf16 v[90:93], v[180:183], v[220:223], v[90:93]
	v_mfma_f32_16x16x32_bf16 v[86:89], v[188:191], v[212:215], v[86:89]
	v_mfma_f32_16x16x32_bf16 v[82:85], v[188:191], v[220:223], v[82:85]
	v_mfma_f32_16x16x32_bf16 v[78:81], v[196:199], v[212:215], v[78:81]
	v_mfma_f32_16x16x32_bf16 v[74:77], v[196:199], v[220:223], v[74:77]
	v_mfma_f32_16x16x32_bf16 v[70:73], v[204:207], v[212:215], v[70:73]
	v_mfma_f32_16x16x32_bf16 v[66:69], v[204:207], v[220:223], v[66:69]
	v_mfma_f32_16x16x32_bf16 v[94:97], v[184:187], v[216:219], v[94:97]
	s_waitcnt lgkmcnt(0)
	v_mfma_f32_16x16x32_bf16 v[90:93], v[184:187], v[224:227], v[90:93]
	v_mfma_f32_16x16x32_bf16 v[86:89], v[192:195], v[216:219], v[86:89]
	v_mfma_f32_16x16x32_bf16 v[82:85], v[192:195], v[224:227], v[82:85]
	v_mfma_f32_16x16x32_bf16 v[78:81], v[200:203], v[216:219], v[78:81]
	v_mfma_f32_16x16x32_bf16 v[74:77], v[200:203], v[224:227], v[74:77]
	v_mfma_f32_16x16x32_bf16 v[70:73], v[208:211], v[216:219], v[70:73]
	v_mfma_f32_16x16x32_bf16 v[66:69], v[208:211], v[224:227], v[66:69]
	s_setprio 0
	v_readfirstlane_b32 s44, v147
	s_mov_b32 m0, s44
	v_readfirstlane_b32 s44, v148
	s_barrier
	ds_read_b128 v[180:183], v137 offset:16384
	ds_read_b128 v[184:187], v137 offset:17408
	ds_read_b128 v[188:191], v136 offset:16384
	ds_read_b128 v[192:195], v136 offset:17408
	ds_read_b128 v[196:199], v135 offset:16384
	ds_read_b128 v[200:203], v135 offset:17408
	ds_read_b128 v[204:207], v134 offset:16384
	ds_read_b128 v[208:211], v134 offset:17408
	buffer_load_dwordx4 v141, s[8:11], s43 offen lds
	s_mov_b32 m0, s44
	s_nop 0
	buffer_load_dwordx4 v143, s[8:11], s43 offen lds
	s_barrier
	s_waitcnt lgkmcnt(0)
	s_setprio 1
	s_waitcnt lgkmcnt(7)
	v_mfma_f32_16x16x32_bf16 v[62:65], v[180:183], v[164:167], v[62:65]
	v_mfma_f32_16x16x32_bf16 v[58:61], v[180:183], v[172:175], v[58:61]
	s_waitcnt lgkmcnt(5)
	v_mfma_f32_16x16x32_bf16 v[54:57], v[188:191], v[164:167], v[54:57]
	v_mfma_f32_16x16x32_bf16 v[50:53], v[188:191], v[172:175], v[50:53]
	s_waitcnt lgkmcnt(3)
	v_mfma_f32_16x16x32_bf16 v[46:49], v[196:199], v[164:167], v[46:49]
	v_mfma_f32_16x16x32_bf16 v[42:45], v[196:199], v[172:175], v[42:45]
	s_waitcnt lgkmcnt(1)
	v_mfma_f32_16x16x32_bf16 v[38:41], v[204:207], v[164:167], v[38:41]
	v_mfma_f32_16x16x32_bf16 v[34:37], v[204:207], v[172:175], v[34:37]
	v_mfma_f32_16x16x32_bf16 v[62:65], v[184:187], v[168:171], v[62:65]
	v_mfma_f32_16x16x32_bf16 v[58:61], v[184:187], v[176:179], v[58:61]
	v_mfma_f32_16x16x32_bf16 v[54:57], v[192:195], v[168:171], v[54:57]
	v_mfma_f32_16x16x32_bf16 v[50:53], v[192:195], v[176:179], v[50:53]
	v_mfma_f32_16x16x32_bf16 v[46:49], v[200:203], v[168:171], v[46:49]
	v_mfma_f32_16x16x32_bf16 v[42:45], v[200:203], v[176:179], v[42:45]
	s_waitcnt lgkmcnt(0)
	v_mfma_f32_16x16x32_bf16 v[38:41], v[208:211], v[168:171], v[38:41]
	v_mfma_f32_16x16x32_bf16 v[34:37], v[208:211], v[176:179], v[34:37]
	s_setprio 0
	s_barrier
; #define STAGE(P, BASE, LD, br, kt) do { const int _so = (int)(((br) * (LD) + (kt) * BK) * 2); \
;     _Pragma("unroll") for (int _i = 0; _i < 2; ++_i) { \
;       __builtin_amdgcn_raw_ptr_buffer_load_lds(rs##BASE, (__attribute__((address_space(3))) unsigned*)((char*)(P) + tid_ * 16 + _i * 8192), 16, (int)off##LD[_i], _so, 0, 0); } } while (0)
; #define LDA_(dst, b, h) _Pragma("unroll") for (int m = 0; m < 4; ++m) _Pragma("unroll") for (int k = 0; k < 2; ++k) \
;     dst[m][k] = *reinterpret_cast<const bf16x8*>((char*)SA(b, h) + lds_byte(wr * 64 + m * 16 + fr, k * 32 + fq * 8))
; #define LDB_(dst, b, h) _Pragma("unroll") for (int n = 0; n < 2; ++n) _Pragma("unroll") for (int k = 0; k < 2; ++k) \
;     dst[n][k] = *reinterpret_cast<const bf16x8*>((char*)SB(b, h) + lds_byte(wc * 32 + n * 16 + fr, k * 32 + fq * 8))
; #define MMA(ai, bj, At, Bx) do { __builtin_amdgcn_s_setprio(1); \
;     _Pragma("unroll") for (int m = 0; m < 4; ++m) _Pragma("unroll") for (int n = 0; n < 2; ++n) _Pragma("unroll") for (int k = 0; k < 2; ++k) \
;       acc[ai][bj][m][n] = __builtin_amdgcn_mfma_f32_16x16x32_bf16(At[m][k], Bx[n][k], acc[ai][bj][m][n], 0, 0, 0); \
;     __builtin_amdgcn_s_setprio(0); } while (0)
; #define WAIT_V(n) asm volatile("s_waitcnt vmcnt(" #n ")" ::: "memory")
; #define WAIT_L(n) asm volatile("s_waitcnt lgkmcnt(" #n ")" ::: "memory")
; #define BAR __builtin_amdgcn_s_barrier()
; #define SCHED __builtin_amdgcn_sched_barrier(0)
; template <int K, int LDA, int LDB>
; DEVI void gemm_tile(const bf16* __restrict__ A, const bf16* __restrict__ Bt, bf16* shm, acc_t& acc) {
;     ...
;     STAGE(SB(0, 1), Bt, LDB, HALF, t + 2);
;     WAIT_V(6); BAR; MMA(1, 1, At, B1); BAR;
;     LDB_(B0, 1, 0); SCHED; LDA_(At, 1, 0); STAGE(SA(0, 1), A, LDA, HALF, t + 2);
;     WAIT_L(8); BAR; WAIT_L(0); MMA(0, 0, At, B0); BAR; SCHED;
;     LDB_(B1, 1, 1); STAGE(SB(1, 0), Bt, LDB, 0, t + 3);
;     BAR; WAIT_L(0); MMA(0, 1, At, B1); BAR;
;     LDA_(At, 1, 1); STAGE(SA(1, 0), A, LDA, 0, t + 3);
	v_readfirstlane_b32 s44, v149
	s_add_i32 s43, s15, 0xffffff80
	s_mov_b32 m0, s44
	v_readfirstlane_b32 s44, v150
	buffer_load_dwordx4 v141, s[4:7], s43 offen lds
	s_mov_b32 m0, s44
	s_nop 0
	buffer_load_dwordx4 v143, s[4:7], s43 offen lds
	s_waitcnt vmcnt(6)
	s_barrier
	s_setprio 1
	v_mfma_f32_16x16x32_bf16 v[30:33], v[180:183], v[212:215], v[30:33]
	v_mfma_f32_16x16x32_bf16 v[26:29], v[180:183], v[220:223], v[26:29]
	v_mfma_f32_16x16x32_bf16 v[22:25], v[188:191], v[212:215], v[22:25]
	v_mfma_f32_16x16x32_bf16 v[18:21], v[188:191], v[220:223], v[18:21]
	v_mfma_f32_16x16x32_bf16 v[14:17], v[196:199], v[212:215], v[14:17]
	v_mfma_f32_16x16x32_bf16 v[10:13], v[196:199], v[220:223], v[10:13]
	v_mfma_f32_16x16x32_bf16 v[6:9], v[204:207], v[212:215], v[6:9]
	v_mfma_f32_16x16x32_bf16 v[2:5], v[204:207], v[220:223], v[2:5]
	v_mfma_f32_16x16x32_bf16 v[30:33], v[184:187], v[216:219], v[30:33]
	v_mfma_f32_16x16x32_bf16 v[26:29], v[184:187], v[224:227], v[26:29]
	v_mfma_f32_16x16x32_bf16 v[22:25], v[192:195], v[216:219], v[22:25]
	v_mfma_f32_16x16x32_bf16 v[18:21], v[192:195], v[224:227], v[18:21]
	v_mfma_f32_16x16x32_bf16 v[14:17], v[200:203], v[216:219], v[14:17]
	v_mfma_f32_16x16x32_bf16 v[10:13], v[200:203], v[224:227], v[10:13]
	v_mfma_f32_16x16x32_bf16 v[6:9], v[208:211], v[216:219], v[6:9]
	v_mfma_f32_16x16x32_bf16 v[2:5], v[208:211], v[224:227], v[2:5]
	s_setprio 0
	s_barrier
	ds_read_b128 v[164:167], v144
	ds_read_b128 v[168:171], v144 offset:1024
	ds_read_b128 v[172:175], v144 offset:2048
	ds_read_b128 v[176:179], v144 offset:3072
	v_readfirstlane_b32 s44, v151
	s_mov_b32 m0, s44
	v_readfirstlane_b32 s44, v152
	ds_read_b128 v[180:183], v137 offset:32768
	ds_read_b128 v[184:187], v137 offset:33792
	ds_read_b128 v[188:191], v136 offset:32768
	ds_read_b128 v[192:195], v136 offset:33792
	ds_read_b128 v[196:199], v135 offset:32768
	ds_read_b128 v[200:203], v135 offset:33792
	ds_read_b128 v[204:207], v134 offset:32768
	ds_read_b128 v[208:211], v134 offset:33792
	buffer_load_dwordx4 v141, s[8:11], s43 offen lds
	s_mov_b32 m0, s44
	s_nop 0
	buffer_load_dwordx4 v143, s[8:11], s43 offen lds
	s_waitcnt lgkmcnt(8)
	s_barrier
	s_waitcnt lgkmcnt(0)
	s_setprio 1
	s_waitcnt lgkmcnt(7)
	v_mfma_f32_16x16x32_bf16 v[126:129], v[180:183], v[164:167], v[126:129]
	v_mfma_f32_16x16x32_bf16 v[122:125], v[180:183], v[172:175], v[122:125]
	s_waitcnt lgkmcnt(5)
	v_mfma_f32_16x16x32_bf16 v[118:121], v[188:191], v[164:167], v[118:121]
	v_mfma_f32_16x16x32_bf16 v[114:117], v[188:191], v[172:175], v[114:117]
	s_waitcnt lgkmcnt(3)
	v_mfma_f32_16x16x32_bf16 v[110:113], v[196:199], v[164:167], v[110:113]
	v_mfma_f32_16x16x32_bf16 v[106:109], v[196:199], v[172:175], v[106:109]
	s_waitcnt lgkmcnt(1)
	v_mfma_f32_16x16x32_bf16 v[102:105], v[204:207], v[164:167], v[102:105]
	v_mfma_f32_16x16x32_bf16 v[98:101], v[204:207], v[172:175], v[98:101]
	v_mfma_f32_16x16x32_bf16 v[126:129], v[184:187], v[168:171], v[126:129]
	v_mfma_f32_16x16x32_bf16 v[122:125], v[184:187], v[176:179], v[122:125]
	v_mfma_f32_16x16x32_bf16 v[118:121], v[192:195], v[168:171], v[118:121]
	v_mfma_f32_16x16x32_bf16 v[114:117], v[192:195], v[176:179], v[114:117]
	v_mfma_f32_16x16x32_bf16 v[110:113], v[200:203], v[168:171], v[110:113]
	v_mfma_f32_16x16x32_bf16 v[106:109], v[200:203], v[176:179], v[106:109]
	s_waitcnt lgkmcnt(0)
	v_mfma_f32_16x16x32_bf16 v[102:105], v[208:211], v[168:171], v[102:105]
	v_mfma_f32_16x16x32_bf16 v[98:101], v[208:211], v[176:179], v[98:101]
	s_setprio 0
	s_barrier
	v_readfirstlane_b32 s44, v153
	s_add_i32 s43, s15, 0xfff80000
	s_mov_b32 m0, s44
	v_readfirstlane_b32 s44, v154
	ds_read_b128 v[212:215], v142
	ds_read_b128 v[216:219], v142 offset:1024
	ds_read_b128 v[220:223], v142 offset:2048
	ds_read_b128 v[224:227], v142 offset:3072
	buffer_load_dwordx4 v141, s[4:7], s43 offen lds
	s_mov_b32 m0, s44
	s_nop 0
	buffer_load_dwordx4 v143, s[4:7], s43 offen lds
	s_barrier
	s_waitcnt lgkmcnt(0)
	s_setprio 1
	s_waitcnt lgkmcnt(3)
	v_mfma_f32_16x16x32_bf16 v[94:97], v[180:183], v[212:215], v[94:97]
	s_waitcnt lgkmcnt(1)
	v_mfma_f32_16x16x32_bf16 v[90:93], v[180:183], v[220:223], v[90:93]
	v_mfma_f32_16x16x32_bf16 v[86:89], v[188:191], v[212:215], v[86:89]
	v_mfma_f32_16x16x32_bf16 v[82:85], v[188:191], v[220:223], v[82:85]
	v_mfma_f32_16x16x32_bf16 v[78:81], v[196:199], v[212:215], v[78:81]
	v_mfma_f32_16x16x32_bf16 v[74:77], v[196:199], v[220:223], v[74:77]
	v_mfma_f32_16x16x32_bf16 v[70:73], v[204:207], v[212:215], v[70:73]
	v_mfma_f32_16x16x32_bf16 v[66:69], v[204:207], v[220:223], v[66:69]
	v_mfma_f32_16x16x32_bf16 v[94:97], v[184:187], v[216:219], v[94:97]
	s_waitcnt lgkmcnt(0)
	v_mfma_f32_16x16x32_bf16 v[90:93], v[184:187], v[224:227], v[90:93]
	v_mfma_f32_16x16x32_bf16 v[86:89], v[192:195], v[216:219], v[86:89]
	v_mfma_f32_16x16x32_bf16 v[82:85], v[192:195], v[224:227], v[82:85]
	v_mfma_f32_16x16x32_bf16 v[78:81], v[200:203], v[216:219], v[78:81]
	v_mfma_f32_16x16x32_bf16 v[74:77], v[200:203], v[224:227], v[74:77]
	v_mfma_f32_16x16x32_bf16 v[70:73], v[208:211], v[216:219], v[70:73]
	v_mfma_f32_16x16x32_bf16 v[66:69], v[208:211], v[224:227], v[66:69]
	s_setprio 0
	v_readfirstlane_b32 s44, v155
	s_mov_b32 m0, s44
	v_readfirstlane_b32 s44, v157
	s_barrier
	ds_read_b128 v[180:183], v137 offset:49152
	ds_read_b128 v[184:187], v137 offset:50176
	ds_read_b128 v[188:191], v136 offset:49152
	ds_read_b128 v[192:195], v136 offset:50176
	ds_read_b128 v[196:199], v135 offset:49152
	ds_read_b128 v[200:203], v135 offset:50176
	ds_read_b128 v[204:207], v134 offset:49152
	ds_read_b128 v[208:211], v134 offset:50176
	buffer_load_dwordx4 v141, s[8:11], s43 offen lds
	s_mov_b32 m0, s44
	s_nop 0
	buffer_load_dwordx4 v143, s[8:11], s43 offen lds
	s_barrier
; #define STAGE(P, BASE, LD, br, kt) do { const int _so = (int)(((br) * (LD) + (kt) * BK) * 2); \
;     _Pragma("unroll") for (int _i = 0; _i < 2; ++_i) { \
;       __builtin_amdgcn_raw_ptr_buffer_load_lds(rs##BASE, (__attribute__((address_space(3))) unsigned*)((char*)(P) + tid_ * 16 + _i * 8192), 16, (int)off##LD[_i], _so, 0, 0); } } while (0)
; #define LDA_(dst, b, h) _Pragma("unroll") for (int m = 0; m < 4; ++m) _Pragma("unroll") for (int k = 0; k < 2; ++k) \
;     dst[m][k] = *reinterpret_cast<const bf16x8*>((char*)SA(b, h) + lds_byte(wr * 64 + m * 16 + fr, k * 32 + fq * 8))
; #define LDB_(dst, b, h) _Pragma("unroll") for (int n = 0; n < 2; ++n) _Pragma("unroll") for (int k = 0; k < 2; ++k) \
;     dst[n][k] = *reinterpret_cast<const bf16x8*>((char*)SB(b, h) + lds_byte(wc * 32 + n * 16 + fr, k * 32 + fq * 8))
; #define MMA(ai, bj, At, Bx) do { __builtin_amdgcn_s_setprio(1); \
;     _Pragma("unroll") for (int m = 0; m < 4; ++m) _Pragma("unroll") for (int n = 0; n < 2; ++n) _Pragma("unroll") for (int k = 0; k < 2; ++k) \
;       acc[ai][bj][m][n] = __builtin_amdgcn_mfma_f32_16x16x32_bf16(At[m][k], Bx[n][k], acc[ai][bj][m][n], 0, 0, 0); \
;     __builtin_amdgcn_s_setprio(0); } while (0)
; #define WAIT_V(n) asm volatile("s_waitcnt vmcnt(" #n ")" ::: "memory")
; #define WAIT_L(n) asm volatile("s_waitcnt lgkmcnt(" #n ")" ::: "memory")
; #define BAR __builtin_amdgcn_s_barrier()
; #define SCHED __builtin_amdgcn_sched_barrier(0)
; template <int K, int LDA, int LDB>
; DEVI void gemm_tile(const bf16* __restrict__ A, const bf16* __restrict__ Bt, bf16* shm, acc_t& acc) {
;     ...
;     BAR; WAIT_L(0); MMA(1, 0, At, B0); BAR; SCHED;
;     STAGE(SB(1, 1), Bt, LDB, HALF, t + 3);
;     WAIT_V(6); BAR; MMA(1, 1, At, B1); BAR;
;   }
;   { LDB_(B0, 0, 0); LDA_(At, 0, 0); STAGE(SA(1, 1), A, LDA, HALF, nt - 1);
;     BAR; WAIT_L(0); MMA(0, 0, At, B0); BAR;
;     LDB_(B1, 0, 1); BAR; WAIT_L(0); MMA(0, 1, At, B1); BAR;
	s_waitcnt lgkmcnt(0)
	s_setprio 1
	s_waitcnt lgkmcnt(7)
	v_mfma_f32_16x16x32_bf16 v[62:65], v[180:183], v[164:167], v[62:65]
	v_mfma_f32_16x16x32_bf16 v[58:61], v[180:183], v[172:175], v[58:61]
	s_waitcnt lgkmcnt(5)
	v_mfma_f32_16x16x32_bf16 v[54:57], v[188:191], v[164:167], v[54:57]
	v_mfma_f32_16x16x32_bf16 v[50:53], v[188:191], v[172:175], v[50:53]
	s_waitcnt lgkmcnt(3)
	v_mfma_f32_16x16x32_bf16 v[46:49], v[196:199], v[164:167], v[46:49]
	v_mfma_f32_16x16x32_bf16 v[42:45], v[196:199], v[172:175], v[42:45]
	s_waitcnt lgkmcnt(1)
	v_mfma_f32_16x16x32_bf16 v[38:41], v[204:207], v[164:167], v[38:41]
	v_mfma_f32_16x16x32_bf16 v[34:37], v[204:207], v[172:175], v[34:37]
	v_mfma_f32_16x16x32_bf16 v[62:65], v[184:187], v[168:171], v[62:65]
	v_mfma_f32_16x16x32_bf16 v[58:61], v[184:187], v[176:179], v[58:61]
	v_mfma_f32_16x16x32_bf16 v[54:57], v[192:195], v[168:171], v[54:57]
	v_mfma_f32_16x16x32_bf16 v[50:53], v[192:195], v[176:179], v[50:53]
	v_mfma_f32_16x16x32_bf16 v[46:49], v[200:203], v[168:171], v[46:49]
	v_mfma_f32_16x16x32_bf16 v[42:45], v[200:203], v[176:179], v[42:45]
	s_waitcnt lgkmcnt(0)
	v_mfma_f32_16x16x32_bf16 v[38:41], v[208:211], v[168:171], v[38:41]
	v_mfma_f32_16x16x32_bf16 v[34:37], v[208:211], v[176:179], v[34:37]
	s_setprio 0
	s_barrier
	v_readfirstlane_b32 s43, v159
	s_mov_b32 m0, s43
	v_readfirstlane_b32 s43, v160
	buffer_load_dwordx4 v141, s[4:7], s15 offen lds
	s_mov_b32 m0, s43
	s_nop 0
	buffer_load_dwordx4 v143, s[4:7], s15 offen lds
	s_waitcnt vmcnt(6)
	s_barrier
	s_setprio 1
	v_mfma_f32_16x16x32_bf16 v[30:33], v[180:183], v[212:215], v[30:33]
	v_mfma_f32_16x16x32_bf16 v[26:29], v[180:183], v[220:223], v[26:29]
	v_mfma_f32_16x16x32_bf16 v[22:25], v[188:191], v[212:215], v[22:25]
	v_mfma_f32_16x16x32_bf16 v[18:21], v[188:191], v[220:223], v[18:21]
	v_mfma_f32_16x16x32_bf16 v[14:17], v[196:199], v[212:215], v[14:17]
	v_mfma_f32_16x16x32_bf16 v[10:13], v[196:199], v[220:223], v[10:13]
	v_mfma_f32_16x16x32_bf16 v[6:9], v[204:207], v[212:215], v[6:9]
	v_mfma_f32_16x16x32_bf16 v[2:5], v[204:207], v[220:223], v[2:5]
	v_mfma_f32_16x16x32_bf16 v[30:33], v[184:187], v[216:219], v[30:33]
	v_mfma_f32_16x16x32_bf16 v[26:29], v[184:187], v[224:227], v[26:29]
	v_mfma_f32_16x16x32_bf16 v[22:25], v[192:195], v[216:219], v[22:25]
	v_mfma_f32_16x16x32_bf16 v[18:21], v[192:195], v[224:227], v[18:21]
	v_mfma_f32_16x16x32_bf16 v[14:17], v[200:203], v[216:219], v[14:17]
	v_mfma_f32_16x16x32_bf16 v[10:13], v[200:203], v[224:227], v[10:13]
	v_mfma_f32_16x16x32_bf16 v[6:9], v[208:211], v[216:219], v[6:9]
	v_mfma_f32_16x16x32_bf16 v[2:5], v[208:211], v[224:227], v[2:5]
	s_setprio 0
	s_add_i32 s13, s13, 2
	s_addk_i32 s15, 0x100
	s_cmp_lt_u32 s13, 28
	s_cbranch_scc1 .Lrot_47279
	s_barrier
	v_readfirstlane_b32 s4, v158
	s_mov_b32 s10, s6
	s_mov_b32 s11, s7
	s_mov_b32 m0, s4
	v_readfirstlane_b32 s4, v161
	ds_read_b128 v[146:149], v162
	ds_read_b128 v[150:153], v162 offset:1024
	ds_read_b128 v[164:167], v162 offset:2048
	ds_read_b128 v[168:171], v162 offset:3072
	ds_read_b128 v[172:175], v137
	ds_read_b128 v[176:179], v137 offset:1024
	ds_read_b128 v[180:183], v136
	ds_read_b128 v[184:187], v136 offset:1024
	ds_read_b128 v[188:191], v135
	ds_read_b128 v[192:195], v135 offset:1024
	ds_read_b128 v[196:199], v134
	ds_read_b128 v[200:203], v134 offset:1024
	buffer_load_dwordx4 v141, s[8:11], s39 offen lds
	s_mov_b32 m0, s4
	s_nop 0
	buffer_load_dwordx4 v143, s[8:11], s39 offen lds
	s_barrier
	s_waitcnt lgkmcnt(0)
	s_setprio 1
	s_waitcnt lgkmcnt(7)
	v_mfma_f32_16x16x32_bf16 v[126:129], v[172:175], v[146:149], v[126:129]
	s_waitcnt lgkmcnt(5)
	v_mfma_f32_16x16x32_bf16 v[118:121], v[180:183], v[146:149], v[118:121]
	s_waitcnt lgkmcnt(3)
	v_mfma_f32_16x16x32_bf16 v[110:113], v[188:191], v[146:149], v[110:113]
	s_waitcnt lgkmcnt(1)
	v_mfma_f32_16x16x32_bf16 v[102:105], v[196:199], v[146:149], v[102:105]
	v_mfma_f32_16x16x32_bf16 v[126:129], v[176:179], v[150:153], v[126:129]
	v_mfma_f32_16x16x32_bf16 v[122:125], v[172:175], v[164:167], v[122:125]
	v_mfma_f32_16x16x32_bf16 v[118:121], v[184:187], v[150:153], v[118:121]
	v_mfma_f32_16x16x32_bf16 v[114:117], v[180:183], v[164:167], v[114:117]
	v_mfma_f32_16x16x32_bf16 v[110:113], v[192:195], v[150:153], v[110:113]
	v_mfma_f32_16x16x32_bf16 v[106:109], v[188:191], v[164:167], v[106:109]
	s_waitcnt lgkmcnt(0)
	v_mfma_f32_16x16x32_bf16 v[102:105], v[200:203], v[150:153], v[102:105]
	v_mfma_f32_16x16x32_bf16 v[98:101], v[196:199], v[164:167], v[98:101]
	v_mfma_f32_16x16x32_bf16 v[158:161], v[176:179], v[168:171], v[122:125]
	v_mfma_f32_16x16x32_bf16 v[204:207], v[184:187], v[168:171], v[114:117]
	v_mfma_f32_16x16x32_bf16 v[208:211], v[192:195], v[168:171], v[106:109]
	v_mfma_f32_16x16x32_bf16 v[212:215], v[200:203], v[168:171], v[98:101]
	s_setprio 0
	s_barrier
	s_nop 1
	ds_read_b128 v[98:101], v156
	ds_read_b128 v[106:109], v156 offset:1024
	ds_read_b128 v[114:117], v156 offset:2048
	ds_read_b128 v[122:125], v156 offset:3072
	s_barrier
	s_waitcnt lgkmcnt(0)
	s_setprio 1
	s_waitcnt lgkmcnt(3)
	v_mfma_f32_16x16x32_bf16 v[94:97], v[172:175], v[98:101], v[94:97]
	v_mfma_f32_16x16x32_bf16 v[86:89], v[180:183], v[98:101], v[86:89]
	v_mfma_f32_16x16x32_bf16 v[78:81], v[188:191], v[98:101], v[78:81]
	v_mfma_f32_16x16x32_bf16 v[70:73], v[196:199], v[98:101], v[70:73]
	s_waitcnt lgkmcnt(2)
	v_mfma_f32_16x16x32_bf16 v[94:97], v[176:179], v[106:109], v[94:97]
	s_waitcnt lgkmcnt(1)
	v_mfma_f32_16x16x32_bf16 v[90:93], v[172:175], v[114:117], v[90:93]
	v_mfma_f32_16x16x32_bf16 v[86:89], v[184:187], v[106:109], v[86:89]
	v_mfma_f32_16x16x32_bf16 v[82:85], v[180:183], v[114:117], v[82:85]
	v_mfma_f32_16x16x32_bf16 v[78:81], v[192:195], v[106:109], v[78:81]
	v_mfma_f32_16x16x32_bf16 v[74:77], v[188:191], v[114:117], v[74:77]
	v_mfma_f32_16x16x32_bf16 v[70:73], v[200:203], v[106:109], v[70:73]
	v_mfma_f32_16x16x32_bf16 v[66:69], v[196:199], v[114:117], v[66:69]
	s_waitcnt lgkmcnt(0)
	v_mfma_f32_16x16x32_bf16 v[154:157], v[176:179], v[122:125], v[90:93]
	v_mfma_f32_16x16x32_bf16 v[172:175], v[184:187], v[122:125], v[82:85]
	v_mfma_f32_16x16x32_bf16 v[176:179], v[192:195], v[122:125], v[74:77]
	v_mfma_f32_16x16x32_bf16 v[180:183], v[200:203], v[122:125], v[66:69]
	s_setprio 0
	s_barrier
; #define LDA_(dst, b, h) _Pragma("unroll") for (int m = 0; m < 4; ++m) _Pragma("unroll") for (int k = 0; k < 2; ++k) \
;     dst[m][k] = *reinterpret_cast<const bf16x8*>((char*)SA(b, h) + lds_byte(wr * 64 + m * 16 + fr, k * 32 + fq * 8))
; #define LDB_(dst, b, h) _Pragma("unroll") for (int n = 0; n < 2; ++n) _Pragma("unroll") for (int k = 0; k < 2; ++k) \
;     dst[n][k] = *reinterpret_cast<const bf16x8*>((char*)SB(b, h) + lds_byte(wc * 32 + n * 16 + fr, k * 32 + fq * 8))
; #define MMA(ai, bj, At, Bx) do { __builtin_amdgcn_s_setprio(1); \
;     _Pragma("unroll") for (int m = 0; m < 4; ++m) _Pragma("unroll") for (int n = 0; n < 2; ++n) _Pragma("unroll") for (int k = 0; k < 2; ++k) \
;       acc[ai][bj][m][n] = __builtin_amdgcn_mfma_f32_16x16x32_bf16(At[m][k], Bx[n][k], acc[ai][bj][m][n], 0, 0, 0); \
;     __builtin_amdgcn_s_setprio(0); } while (0)
; #define WAIT_V(n) asm volatile("s_waitcnt vmcnt(" #n ")" ::: "memory")
; #define WAIT_L(n) asm volatile("s_waitcnt lgkmcnt(" #n ")" ::: "memory")
; #define BAR __builtin_amdgcn_s_barrier()
; template <int K, int LDA, int LDB>
; DEVI void gemm_tile(const bf16* __restrict__ A, const bf16* __restrict__ Bt, bf16* shm, acc_t& acc) {
;     ...
;     LDA_(At, 0, 1); WAIT_V(4); BAR; WAIT_L(0); MMA(1, 0, At, B0); MMA(1, 1, At, B1); BAR; }
;   { LDB_(B0, 1, 0); LDA_(At, 1, 0); WAIT_V(2); BAR; WAIT_L(0); MMA(0, 0, At, B0); BAR;
	s_nop 0
	ds_read_b128 v[66:69], v137 offset:16384
	ds_read_b128 v[74:77], v137 offset:17408
	ds_read_b128 v[82:85], v136 offset:16384
	ds_read_b128 v[90:93], v136 offset:17408
	ds_read_b128 v[184:187], v135 offset:16384
	ds_read_b128 v[188:191], v135 offset:17408
	ds_read_b128 v[192:195], v134 offset:16384
	ds_read_b128 v[196:199], v134 offset:17408
	s_waitcnt vmcnt(4)
	s_barrier
	s_waitcnt lgkmcnt(0)
	s_setprio 1
	s_waitcnt lgkmcnt(7)
	v_mfma_f32_16x16x32_bf16 v[62:65], v[66:69], v[146:149], v[62:65]
	s_waitcnt lgkmcnt(5)
	v_mfma_f32_16x16x32_bf16 v[54:57], v[82:85], v[146:149], v[54:57]
	s_waitcnt lgkmcnt(3)
	v_mfma_f32_16x16x32_bf16 v[46:49], v[184:187], v[146:149], v[46:49]
	s_waitcnt lgkmcnt(1)
	v_mfma_f32_16x16x32_bf16 v[38:41], v[192:195], v[146:149], v[38:41]
	v_mfma_f32_16x16x32_bf16 v[62:65], v[74:77], v[150:153], v[62:65]
	v_mfma_f32_16x16x32_bf16 v[58:61], v[66:69], v[164:167], v[58:61]
	v_mfma_f32_16x16x32_bf16 v[54:57], v[90:93], v[150:153], v[54:57]
	v_mfma_f32_16x16x32_bf16 v[50:53], v[82:85], v[164:167], v[50:53]
	v_mfma_f32_16x16x32_bf16 v[46:49], v[188:191], v[150:153], v[46:49]
	v_mfma_f32_16x16x32_bf16 v[42:45], v[184:187], v[164:167], v[42:45]
	s_waitcnt lgkmcnt(0)
	v_mfma_f32_16x16x32_bf16 v[38:41], v[196:199], v[150:153], v[38:41]
	v_mfma_f32_16x16x32_bf16 v[34:37], v[192:195], v[164:167], v[34:37]
	v_mfma_f32_16x16x32_bf16 v[200:203], v[74:77], v[168:171], v[58:61]
	v_mfma_f32_16x16x32_bf16 v[216:219], v[90:93], v[168:171], v[50:53]
	v_mfma_f32_16x16x32_bf16 v[220:223], v[188:191], v[168:171], v[42:45]
	v_mfma_f32_16x16x32_bf16 v[146:149], v[196:199], v[168:171], v[34:37]
	s_setprio 0
	s_setprio 1
	v_mfma_f32_16x16x32_bf16 v[30:33], v[66:69], v[98:101], v[30:33]
	v_mfma_f32_16x16x32_bf16 v[22:25], v[82:85], v[98:101], v[22:25]
	v_mfma_f32_16x16x32_bf16 v[14:17], v[184:187], v[98:101], v[14:17]
	v_mfma_f32_16x16x32_bf16 v[6:9], v[192:195], v[98:101], v[6:9]
	v_mfma_f32_16x16x32_bf16 v[30:33], v[74:77], v[106:109], v[30:33]
	v_mfma_f32_16x16x32_bf16 v[26:29], v[66:69], v[114:117], v[26:29]
	v_mfma_f32_16x16x32_bf16 v[22:25], v[90:93], v[106:109], v[22:25]
	v_mfma_f32_16x16x32_bf16 v[18:21], v[82:85], v[114:117], v[18:21]
	v_mfma_f32_16x16x32_bf16 v[14:17], v[188:191], v[106:109], v[14:17]
	v_mfma_f32_16x16x32_bf16 v[10:13], v[184:187], v[114:117], v[10:13]
	v_mfma_f32_16x16x32_bf16 v[6:9], v[196:199], v[106:109], v[6:9]
	v_mfma_f32_16x16x32_bf16 v[2:5], v[192:195], v[114:117], v[2:5]
	v_mfma_f32_16x16x32_bf16 v[150:153], v[74:77], v[122:125], v[26:29]
	v_mfma_f32_16x16x32_bf16 v[162:165], v[90:93], v[122:125], v[18:21]
	v_mfma_f32_16x16x32_bf16 v[166:169], v[188:191], v[122:125], v[10:13]
	v_mfma_f32_16x16x32_bf16 v[184:187], v[196:199], v[122:125], v[2:5]
	s_setprio 0
	s_barrier
	ds_read_b128 v[188:191], v144
	ds_read_b128 v[192:195], v144 offset:1024
	ds_read_b128 v[196:199], v144 offset:2048
	ds_read_b128 v[224:227], v144 offset:3072
	ds_read_b128 v[2:5], v137 offset:32768
	ds_read_b128 v[10:13], v137 offset:33792
	ds_read_b128 v[18:21], v136 offset:32768
	ds_read_b128 v[26:29], v136 offset:33792
	ds_read_b128 v[228:231], v135 offset:32768
	ds_read_b128 v[232:235], v135 offset:33792
	ds_read_b128 v[236:239], v134 offset:32768
	ds_read_b128 v[240:243], v134 offset:33792
	s_waitcnt vmcnt(2)
	s_barrier
	s_waitcnt lgkmcnt(0)
	s_setprio 1
	s_waitcnt lgkmcnt(7)
	v_mfma_f32_16x16x32_bf16 v[34:37], v[2:5], v[188:191], v[126:129]
	s_waitcnt lgkmcnt(6)
	v_mfma_f32_16x16x32_bf16 v[122:125], v[10:13], v[192:195], v[34:37]
	v_mfma_f32_16x16x32_bf16 v[34:37], v[2:5], v[196:199], v[158:161]
	v_mfma_f32_16x16x32_bf16 v[114:117], v[10:13], v[224:227], v[34:37]
	s_waitcnt lgkmcnt(5)
	v_mfma_f32_16x16x32_bf16 v[34:37], v[18:21], v[188:191], v[118:121]
	s_waitcnt lgkmcnt(4)
	v_mfma_f32_16x16x32_bf16 v[106:109], v[26:29], v[192:195], v[34:37]
	v_mfma_f32_16x16x32_bf16 v[34:37], v[18:21], v[196:199], v[204:207]
	v_mfma_f32_16x16x32_bf16 v[98:101], v[26:29], v[224:227], v[34:37]
	s_waitcnt lgkmcnt(3)
	v_mfma_f32_16x16x32_bf16 v[34:37], v[228:231], v[188:191], v[110:113]
	s_waitcnt lgkmcnt(2)
	v_mfma_f32_16x16x32_bf16 v[90:93], v[232:235], v[192:195], v[34:37]
	v_mfma_f32_16x16x32_bf16 v[34:37], v[228:231], v[196:199], v[208:211]
	v_mfma_f32_16x16x32_bf16 v[82:85], v[232:235], v[224:227], v[34:37]
	s_waitcnt lgkmcnt(1)
	v_mfma_f32_16x16x32_bf16 v[34:37], v[236:239], v[188:191], v[102:105]
	s_waitcnt lgkmcnt(0)
	v_mfma_f32_16x16x32_bf16 v[74:77], v[240:243], v[192:195], v[34:37]
	v_mfma_f32_16x16x32_bf16 v[34:37], v[236:239], v[196:199], v[212:215]
	v_mfma_f32_16x16x32_bf16 v[66:69], v[240:243], v[224:227], v[34:37]
	s_setprio 0
	s_barrier
; #define LDA_(dst, b, h) _Pragma("unroll") for (int m = 0; m < 4; ++m) _Pragma("unroll") for (int k = 0; k < 2; ++k) \
;     dst[m][k] = *reinterpret_cast<const bf16x8*>((char*)SA(b, h) + lds_byte(wr * 64 + m * 16 + fr, k * 32 + fq * 8))
; #define LDB_(dst, b, h) _Pragma("unroll") for (int n = 0; n < 2; ++n) _Pragma("unroll") for (int k = 0; k < 2; ++k) \
;     dst[n][k] = *reinterpret_cast<const bf16x8*>((char*)SB(b, h) + lds_byte(wc * 32 + n * 16 + fr, k * 32 + fq * 8))
; #define MMA(ai, bj, At, Bx) do { __builtin_amdgcn_s_setprio(1); \
;     _Pragma("unroll") for (int m = 0; m < 4; ++m) _Pragma("unroll") for (int n = 0; n < 2; ++n) _Pragma("unroll") for (int k = 0; k < 2; ++k) \
;       acc[ai][bj][m][n] = __builtin_amdgcn_mfma_f32_16x16x32_bf16(At[m][k], Bx[n][k], acc[ai][bj][m][n], 0, 0, 0); \
;     __builtin_amdgcn_s_setprio(0); } while (0)
; #define WAIT_V(n) asm volatile("s_waitcnt vmcnt(" #n ")" ::: "memory")
; #define WAIT_L(n) asm volatile("s_waitcnt lgkmcnt(" #n ")" ::: "memory")
; #define BAR __builtin_amdgcn_s_barrier()
; template <int K, int LDA, int LDB>
; DEVI void gemm_tile(const bf16* __restrict__ A, const bf16* __restrict__ Bt, bf16* shm, acc_t& acc) {
;     ...
;     LDB_(B1, 1, 1); WAIT_V(0); BAR; WAIT_L(0); MMA(0, 1, At, B1); BAR;
;     LDA_(At, 1, 1); BAR; WAIT_L(0); MMA(1, 0, At, B0); MMA(1, 1, At, B1); BAR; }
;   if (wr == 0) BAR;
	ds_read_b128 v[158:161], v142
	ds_read_b128 v[204:207], v142 offset:1024
	ds_read_b128 v[208:211], v142 offset:2048
	ds_read_b128 v[142:145], v142 offset:3072
	s_waitcnt vmcnt(0)
	s_barrier
	s_waitcnt lgkmcnt(0)
	s_setprio 1
	s_waitcnt lgkmcnt(3)
	v_mfma_f32_16x16x32_bf16 v[34:37], v[2:5], v[158:161], v[94:97]
	s_waitcnt lgkmcnt(1)
	v_mfma_f32_16x16x32_bf16 v[2:5], v[2:5], v[208:211], v[154:157]
	s_waitcnt lgkmcnt(0)
	v_mfma_f32_16x16x32_bf16 v[50:53], v[10:13], v[142:145], v[2:5]
	v_mfma_f32_16x16x32_bf16 v[2:5], v[18:21], v[158:161], v[86:89]
	v_mfma_f32_16x16x32_bf16 v[42:45], v[26:29], v[204:207], v[2:5]
	v_mfma_f32_16x16x32_bf16 v[2:5], v[18:21], v[208:211], v[172:175]
	v_mfma_f32_16x16x32_bf16 v[58:61], v[10:13], v[204:207], v[34:37]
	v_mfma_f32_16x16x32_bf16 v[34:37], v[26:29], v[142:145], v[2:5]
	v_mfma_f32_16x16x32_bf16 v[2:5], v[228:231], v[158:161], v[78:81]
	v_mfma_f32_16x16x32_bf16 v[26:29], v[232:235], v[204:207], v[2:5]
	v_mfma_f32_16x16x32_bf16 v[2:5], v[228:231], v[208:211], v[176:179]
	v_mfma_f32_16x16x32_bf16 v[18:21], v[232:235], v[142:145], v[2:5]
	v_mfma_f32_16x16x32_bf16 v[2:5], v[236:239], v[158:161], v[70:73]
	v_mfma_f32_16x16x32_bf16 v[10:13], v[240:243], v[204:207], v[2:5]
	v_mfma_f32_16x16x32_bf16 v[2:5], v[236:239], v[208:211], v[180:183]
	v_mfma_f32_16x16x32_bf16 v[2:5], v[240:243], v[142:145], v[2:5]
	s_setprio 0
	s_barrier
	ds_read_b128 v[154:157], v137 offset:49152
	ds_read_b128 v[170:173], v137 offset:50176
	ds_read_b128 v[174:177], v136 offset:49152
	ds_read_b128 v[178:181], v136 offset:50176
	ds_read_b128 v[212:215], v135 offset:49152
	ds_read_b128 v[228:231], v135 offset:50176
	ds_read_b128 v[232:235], v134 offset:49152
	ds_read_b128 v[134:137], v134 offset:50176
	s_barrier
	s_waitcnt lgkmcnt(0)
	s_setprio 1
	s_waitcnt lgkmcnt(7)
	v_mfma_f32_16x16x32_bf16 v[62:65], v[154:157], v[188:191], v[62:65]
	s_waitcnt lgkmcnt(5)
	v_mfma_f32_16x16x32_bf16 v[54:57], v[174:177], v[188:191], v[54:57]
	s_waitcnt lgkmcnt(3)
	v_mfma_f32_16x16x32_bf16 v[46:49], v[212:215], v[188:191], v[46:49]
	s_waitcnt lgkmcnt(1)
	v_mfma_f32_16x16x32_bf16 v[38:41], v[232:235], v[188:191], v[38:41]
	v_mfma_f32_16x16x32_bf16 v[126:129], v[170:173], v[192:195], v[62:65]
	v_mfma_f32_16x16x32_bf16 v[62:65], v[154:157], v[196:199], v[200:203]
	v_mfma_f32_16x16x32_bf16 v[110:113], v[178:181], v[192:195], v[54:57]
	v_mfma_f32_16x16x32_bf16 v[54:57], v[174:177], v[196:199], v[216:219]
	v_mfma_f32_16x16x32_bf16 v[94:97], v[228:231], v[192:195], v[46:49]
	v_mfma_f32_16x16x32_bf16 v[46:49], v[212:215], v[196:199], v[220:223]
	s_waitcnt lgkmcnt(0)
	v_mfma_f32_16x16x32_bf16 v[78:81], v[134:137], v[192:195], v[38:41]
	v_mfma_f32_16x16x32_bf16 v[38:41], v[232:235], v[196:199], v[146:149]
	v_mfma_f32_16x16x32_bf16 v[118:121], v[170:173], v[224:227], v[62:65]
	v_mfma_f32_16x16x32_bf16 v[102:105], v[178:181], v[224:227], v[54:57]
	v_mfma_f32_16x16x32_bf16 v[86:89], v[228:231], v[224:227], v[46:49]
	v_mfma_f32_16x16x32_bf16 v[70:73], v[134:137], v[224:227], v[38:41]
	s_setprio 0
	s_setprio 1
	v_mfma_f32_16x16x32_bf16 v[30:33], v[154:157], v[158:161], v[30:33]
	v_mfma_f32_16x16x32_bf16 v[62:65], v[170:173], v[204:207], v[30:33]
	v_mfma_f32_16x16x32_bf16 v[30:33], v[154:157], v[208:211], v[150:153]
	v_mfma_f32_16x16x32_bf16 v[22:25], v[174:177], v[158:161], v[22:25]
	v_mfma_f32_16x16x32_bf16 v[14:17], v[212:215], v[158:161], v[14:17]
	v_mfma_f32_16x16x32_bf16 v[54:57], v[170:173], v[142:145], v[30:33]
	v_mfma_f32_16x16x32_bf16 v[46:49], v[178:181], v[204:207], v[22:25]
	v_mfma_f32_16x16x32_bf16 v[22:25], v[174:177], v[208:211], v[162:165]
	v_mfma_f32_16x16x32_bf16 v[30:33], v[228:231], v[204:207], v[14:17]
	v_mfma_f32_16x16x32_bf16 v[14:17], v[212:215], v[208:211], v[166:169]
	v_mfma_f32_16x16x32_bf16 v[6:9], v[232:235], v[158:161], v[6:9]
	v_mfma_f32_16x16x32_bf16 v[38:41], v[178:181], v[142:145], v[22:25]
	v_mfma_f32_16x16x32_bf16 v[22:25], v[228:231], v[142:145], v[14:17]
	v_mfma_f32_16x16x32_bf16 v[14:17], v[134:137], v[204:207], v[6:9]
	v_mfma_f32_16x16x32_bf16 v[6:9], v[232:235], v[208:211], v[184:187]
	v_mfma_f32_16x16x32_bf16 v[6:9], v[134:137], v[142:145], v[6:9]
	s_setprio 0
	v_cmp_gt_u32_e32 vcc, s18, v132
	s_barrier
	s_and_saveexec_b64 s[4:5], vcc
	s_cbranch_execz .LBB0_2064
	s_barrier

; #define STAGE(P, BASE, LD, br, kt) do { const int _so = (int)(((br) * (LD) + (kt) * BK) * 2); \
;     _Pragma("unroll") for (int _i = 0; _i < 2; ++_i) { \
;       __builtin_amdgcn_raw_ptr_buffer_load_lds(rs##BASE, (__attribute__((address_space(3))) unsigned*)((char*)(P) + tid_ * 16 + _i * 8192), 16, (int)off##LD[_i], _so, 0, 0); } } while (0)
; #define LDA_(dst, b, h) _Pragma("unroll") for (int m = 0; m < 4; ++m) _Pragma("unroll") for (int k = 0; k < 2; ++k) \
;     dst[m][k] = *reinterpret_cast<const bf16x8*>((char*)SA(b, h) + lds_byte(wr * 64 + m * 16 + fr, k * 32 + fq * 8))
; #define LDB_(dst, b, h) _Pragma("unroll") for (int n = 0; n < 2; ++n) _Pragma("unroll") for (int k = 0; k < 2; ++k) \
;     dst[n][k] = *reinterpret_cast<const bf16x8*>((char*)SB(b, h) + lds_byte(wc * 32 + n * 16 + fr, k * 32 + fq * 8))
; #define MMA(ai, bj, At, Bx) do { __builtin_amdgcn_s_setprio(1); \
;     _Pragma("unroll") for (int m = 0; m < 4; ++m) _Pragma("unroll") for (int n = 0; n < 2; ++n) _Pragma("unroll") for (int k = 0; k < 2; ++k) \
;       acc[ai][bj][m][n] = __builtin_amdgcn_mfma_f32_16x16x32_bf16(At[m][k], Bx[n][k], acc[ai][bj][m][n], 0, 0, 0); \
;     __builtin_amdgcn_s_setprio(0); } while (0)
; #define WAIT_V(n) asm volatile("s_waitcnt vmcnt(" #n ")" ::: "memory")
; #define WAIT_L(n) asm volatile("s_waitcnt lgkmcnt(" #n ")" ::: "memory")
; #define BAR __builtin_amdgcn_s_barrier()
; #define SCHED __builtin_amdgcn_sched_barrier(0)
; template <int K, int LDA, int LDB>
; DEVI void gemm_tile(const bf16* __restrict__ A, const bf16* __restrict__ Bt, bf16* shm, acc_t& acc) {
;     ...
;     LDB_(B0, 0, 0); SCHED; LDA_(At, 0, 0); STAGE(SA(1, 1), A, LDA, HALF, t + 1);
;     WAIT_L(8); BAR; WAIT_L(0); MMA(0, 0, At, B0); BAR; SCHED;
;     LDB_(B1, 0, 1); STAGE(SB(0, 0), Bt, LDB, 0, t + 2);
;     BAR; WAIT_L(0); MMA(0, 1, At, B1); BAR;
;     LDA_(At, 0, 1); STAGE(SA(0, 0), A, LDA, 0, t + 2);
;     BAR; WAIT_L(0); MMA(1, 0, At, B0); BAR; SCHED;
;     STAGE(SB(0, 1), Bt, LDB, HALF, t + 2);
;     WAIT_V(6); BAR; MMA(1, 1, At, B1); BAR;
.LBB0_2101:
	ds_read_b128 v[162:165], v160
	ds_read_b128 v[166:169], v160 offset:1024
	ds_read_b128 v[170:173], v160 offset:2048
	ds_read_b128 v[174:177], v160 offset:3072
	v_readfirstlane_b32 s67, v156
	s_add_i32 s66, s7, 0xffffff00
	s_mov_b32 m0, s67
	v_readfirstlane_b32 s67, v159
	ds_read_b128 v[178:181], v138
	ds_read_b128 v[182:185], v138 offset:1024
	ds_read_b128 v[186:189], v137
	ds_read_b128 v[190:193], v137 offset:1024
	ds_read_b128 v[194:197], v136
	ds_read_b128 v[198:201], v136 offset:1024
	ds_read_b128 v[202:205], v135
	ds_read_b128 v[206:209], v135 offset:1024
	buffer_load_dwordx4 v139, s[8:11], s66 offen lds
	s_mov_b32 m0, s67
	s_nop 0
	buffer_load_dwordx4 v141, s[8:11], s66 offen lds
	s_waitcnt lgkmcnt(8)
	s_barrier
	s_waitcnt lgkmcnt(0)
	s_setprio 1
	s_waitcnt lgkmcnt(7)
	v_mfma_f32_16x16x32_bf16 v[126:129], v[178:181], v[162:165], v[126:129]
	v_mfma_f32_16x16x32_bf16 v[122:125], v[178:181], v[170:173], v[122:125]
	s_waitcnt lgkmcnt(5)
	v_mfma_f32_16x16x32_bf16 v[118:121], v[186:189], v[162:165], v[118:121]
	v_mfma_f32_16x16x32_bf16 v[114:117], v[186:189], v[170:173], v[114:117]
	s_waitcnt lgkmcnt(3)
	v_mfma_f32_16x16x32_bf16 v[110:113], v[194:197], v[162:165], v[110:113]
	v_mfma_f32_16x16x32_bf16 v[106:109], v[194:197], v[170:173], v[106:109]
	s_waitcnt lgkmcnt(1)
	v_mfma_f32_16x16x32_bf16 v[102:105], v[202:205], v[162:165], v[102:105]
	v_mfma_f32_16x16x32_bf16 v[98:101], v[202:205], v[170:173], v[98:101]
	v_mfma_f32_16x16x32_bf16 v[126:129], v[182:185], v[166:169], v[126:129]
	v_mfma_f32_16x16x32_bf16 v[122:125], v[182:185], v[174:177], v[122:125]
	v_mfma_f32_16x16x32_bf16 v[118:121], v[190:193], v[166:169], v[118:121]
	v_mfma_f32_16x16x32_bf16 v[114:117], v[190:193], v[174:177], v[114:117]
	v_mfma_f32_16x16x32_bf16 v[110:113], v[198:201], v[166:169], v[110:113]
	v_mfma_f32_16x16x32_bf16 v[106:109], v[198:201], v[174:177], v[106:109]
	s_waitcnt lgkmcnt(0)
	v_mfma_f32_16x16x32_bf16 v[102:105], v[206:209], v[166:169], v[102:105]
	v_mfma_f32_16x16x32_bf16 v[98:101], v[206:209], v[174:177], v[98:101]
	s_setprio 0
	s_barrier
	v_readfirstlane_b32 s67, v143
	s_add_i32 s66, s7, 0xffe9ff80
	s_mov_b32 m0, s67
	v_readfirstlane_b32 s67, v144
	ds_read_b128 v[210:213], v154
	ds_read_b128 v[214:217], v154 offset:1024
	ds_read_b128 v[218:221], v154 offset:2048
	ds_read_b128 v[222:225], v154 offset:3072
	buffer_load_dwordx4 v139, s[0:3], s66 offen lds
	s_mov_b32 m0, s67
	s_nop 0
	buffer_load_dwordx4 v141, s[0:3], s66 offen lds
	s_barrier
	s_waitcnt lgkmcnt(0)
	s_setprio 1
	s_waitcnt lgkmcnt(3)
	v_mfma_f32_16x16x32_bf16 v[94:97], v[178:181], v[210:213], v[94:97]
	s_waitcnt lgkmcnt(1)
	v_mfma_f32_16x16x32_bf16 v[90:93], v[178:181], v[218:221], v[90:93]
	v_mfma_f32_16x16x32_bf16 v[86:89], v[186:189], v[210:213], v[86:89]
	v_mfma_f32_16x16x32_bf16 v[82:85], v[186:189], v[218:221], v[82:85]
	v_mfma_f32_16x16x32_bf16 v[78:81], v[194:197], v[210:213], v[78:81]
	v_mfma_f32_16x16x32_bf16 v[74:77], v[194:197], v[218:221], v[74:77]
	v_mfma_f32_16x16x32_bf16 v[70:73], v[202:205], v[210:213], v[70:73]
	v_mfma_f32_16x16x32_bf16 v[66:69], v[202:205], v[218:221], v[66:69]
	v_mfma_f32_16x16x32_bf16 v[94:97], v[182:185], v[214:217], v[94:97]
	s_waitcnt lgkmcnt(0)
	v_mfma_f32_16x16x32_bf16 v[90:93], v[182:185], v[222:225], v[90:93]
	v_mfma_f32_16x16x32_bf16 v[86:89], v[190:193], v[214:217], v[86:89]
	v_mfma_f32_16x16x32_bf16 v[82:85], v[190:193], v[222:225], v[82:85]
	v_mfma_f32_16x16x32_bf16 v[78:81], v[198:201], v[214:217], v[78:81]
	v_mfma_f32_16x16x32_bf16 v[74:77], v[198:201], v[222:225], v[74:77]
	v_mfma_f32_16x16x32_bf16 v[70:73], v[206:209], v[214:217], v[70:73]
	v_mfma_f32_16x16x32_bf16 v[66:69], v[206:209], v[222:225], v[66:69]
	s_setprio 0
	v_readfirstlane_b32 s67, v145
	s_mov_b32 m0, s67
	v_readfirstlane_b32 s67, v146
	s_barrier
	ds_read_b128 v[178:181], v138 offset:16384
	ds_read_b128 v[182:185], v138 offset:17408
	ds_read_b128 v[186:189], v137 offset:16384
	ds_read_b128 v[190:193], v137 offset:17408
	ds_read_b128 v[194:197], v136 offset:16384
	ds_read_b128 v[198:201], v136 offset:17408
	ds_read_b128 v[202:205], v135 offset:16384
	ds_read_b128 v[206:209], v135 offset:17408
	buffer_load_dwordx4 v139, s[8:11], s66 offen lds
	s_mov_b32 m0, s67
	s_nop 0
	buffer_load_dwordx4 v141, s[8:11], s66 offen lds
	s_barrier
	s_waitcnt lgkmcnt(0)
	s_setprio 1
	s_waitcnt lgkmcnt(7)
	v_mfma_f32_16x16x32_bf16 v[62:65], v[178:181], v[162:165], v[62:65]
	v_mfma_f32_16x16x32_bf16 v[58:61], v[178:181], v[170:173], v[58:61]
	s_waitcnt lgkmcnt(5)
	v_mfma_f32_16x16x32_bf16 v[54:57], v[186:189], v[162:165], v[54:57]
	v_mfma_f32_16x16x32_bf16 v[50:53], v[186:189], v[170:173], v[50:53]
	s_waitcnt lgkmcnt(3)
	v_mfma_f32_16x16x32_bf16 v[46:49], v[194:197], v[162:165], v[46:49]
	v_mfma_f32_16x16x32_bf16 v[42:45], v[194:197], v[170:173], v[42:45]
	s_waitcnt lgkmcnt(1)
	v_mfma_f32_16x16x32_bf16 v[38:41], v[202:205], v[162:165], v[38:41]
	v_mfma_f32_16x16x32_bf16 v[34:37], v[202:205], v[170:173], v[34:37]
	v_mfma_f32_16x16x32_bf16 v[62:65], v[182:185], v[166:169], v[62:65]
	v_mfma_f32_16x16x32_bf16 v[58:61], v[182:185], v[174:177], v[58:61]
	v_mfma_f32_16x16x32_bf16 v[54:57], v[190:193], v[166:169], v[54:57]
	v_mfma_f32_16x16x32_bf16 v[50:53], v[190:193], v[174:177], v[50:53]
	v_mfma_f32_16x16x32_bf16 v[46:49], v[198:201], v[166:169], v[46:49]
	v_mfma_f32_16x16x32_bf16 v[42:45], v[198:201], v[174:177], v[42:45]
	s_waitcnt lgkmcnt(0)
	v_mfma_f32_16x16x32_bf16 v[38:41], v[206:209], v[166:169], v[38:41]
	v_mfma_f32_16x16x32_bf16 v[34:37], v[206:209], v[174:177], v[34:37]
	s_setprio 0
	s_barrier
; #define STAGE(P, BASE, LD, br, kt) do { const int _so = (int)(((br) * (LD) + (kt) * BK) * 2); \
;     _Pragma("unroll") for (int _i = 0; _i < 2; ++_i) { \
;       __builtin_amdgcn_raw_ptr_buffer_load_lds(rs##BASE, (__attribute__((address_space(3))) unsigned*)((char*)(P) + tid_ * 16 + _i * 8192), 16, (int)off##LD[_i], _so, 0, 0); } } while (0)
; #define LDA_(dst, b, h) _Pragma("unroll") for (int m = 0; m < 4; ++m) _Pragma("unroll") for (int k = 0; k < 2; ++k) \
;     dst[m][k] = *reinterpret_cast<const bf16x8*>((char*)SA(b, h) + lds_byte(wr * 64 + m * 16 + fr, k * 32 + fq * 8))
; #define LDB_(dst, b, h) _Pragma("unroll") for (int n = 0; n < 2; ++n) _Pragma("unroll") for (int k = 0; k < 2; ++k) \
;     dst[n][k] = *reinterpret_cast<const bf16x8*>((char*)SB(b, h) + lds_byte(wc * 32 + n * 16 + fr, k * 32 + fq * 8))
; #define MMA(ai, bj, At, Bx) do { __builtin_amdgcn_s_setprio(1); \
;     _Pragma("unroll") for (int m = 0; m < 4; ++m) _Pragma("unroll") for (int n = 0; n < 2; ++n) _Pragma("unroll") for (int k = 0; k < 2; ++k) \
;       acc[ai][bj][m][n] = __builtin_amdgcn_mfma_f32_16x16x32_bf16(At[m][k], Bx[n][k], acc[ai][bj][m][n], 0, 0, 0); \
;     __builtin_amdgcn_s_setprio(0); } while (0)
; #define WAIT_V(n) asm volatile("s_waitcnt vmcnt(" #n ")" ::: "memory")
; #define WAIT_L(n) asm volatile("s_waitcnt lgkmcnt(" #n ")" ::: "memory")
; #define BAR __builtin_amdgcn_s_barrier()
; #define SCHED __builtin_amdgcn_sched_barrier(0)
; template <int K, int LDA, int LDB>
; DEVI void gemm_tile(const bf16* __restrict__ A, const bf16* __restrict__ Bt, bf16* shm, acc_t& acc) {
;     ...
;     STAGE(SB(0, 1), Bt, LDB, HALF, t + 2);
;     WAIT_V(6); BAR; MMA(1, 1, At, B1); BAR;
;     LDB_(B0, 1, 0); SCHED; LDA_(At, 1, 0); STAGE(SA(0, 1), A, LDA, HALF, t + 2);
;     WAIT_L(8); BAR; WAIT_L(0); MMA(0, 0, At, B0); BAR; SCHED;
;     LDB_(B1, 1, 1); STAGE(SB(1, 0), Bt, LDB, 0, t + 3);
;     BAR; WAIT_L(0); MMA(0, 1, At, B1); BAR;
;     LDA_(At, 1, 1); STAGE(SA(1, 0), A, LDA, 0, t + 3);
	v_readfirstlane_b32 s67, v147
	s_add_i32 s66, s7, 0xffffff80
	s_mov_b32 m0, s67
	v_readfirstlane_b32 s67, v148
	buffer_load_dwordx4 v139, s[0:3], s66 offen lds
	s_mov_b32 m0, s67
	s_nop 0
	buffer_load_dwordx4 v141, s[0:3], s66 offen lds
	s_waitcnt vmcnt(6)
	s_barrier
	s_setprio 1
	v_mfma_f32_16x16x32_bf16 v[30:33], v[178:181], v[210:213], v[30:33]
	v_mfma_f32_16x16x32_bf16 v[26:29], v[178:181], v[218:221], v[26:29]
	v_mfma_f32_16x16x32_bf16 v[22:25], v[186:189], v[210:213], v[22:25]
	v_mfma_f32_16x16x32_bf16 v[18:21], v[186:189], v[218:221], v[18:21]
	v_mfma_f32_16x16x32_bf16 v[14:17], v[194:197], v[210:213], v[14:17]
	v_mfma_f32_16x16x32_bf16 v[10:13], v[194:197], v[218:221], v[10:13]
	v_mfma_f32_16x16x32_bf16 v[6:9], v[202:205], v[210:213], v[6:9]
	v_mfma_f32_16x16x32_bf16 v[2:5], v[202:205], v[218:221], v[2:5]
	v_mfma_f32_16x16x32_bf16 v[30:33], v[182:185], v[214:217], v[30:33]
	v_mfma_f32_16x16x32_bf16 v[26:29], v[182:185], v[222:225], v[26:29]
	v_mfma_f32_16x16x32_bf16 v[22:25], v[190:193], v[214:217], v[22:25]
	v_mfma_f32_16x16x32_bf16 v[18:21], v[190:193], v[222:225], v[18:21]
	v_mfma_f32_16x16x32_bf16 v[14:17], v[198:201], v[214:217], v[14:17]
	v_mfma_f32_16x16x32_bf16 v[10:13], v[198:201], v[222:225], v[10:13]
	v_mfma_f32_16x16x32_bf16 v[6:9], v[206:209], v[214:217], v[6:9]
	v_mfma_f32_16x16x32_bf16 v[2:5], v[206:209], v[222:225], v[2:5]
	s_setprio 0
	s_barrier
	ds_read_b128 v[162:165], v142
	ds_read_b128 v[166:169], v142 offset:1024
	ds_read_b128 v[170:173], v142 offset:2048
	ds_read_b128 v[174:177], v142 offset:3072
	v_readfirstlane_b32 s67, v149
	s_mov_b32 m0, s67
	v_readfirstlane_b32 s67, v150
	ds_read_b128 v[178:181], v138 offset:32768
	ds_read_b128 v[182:185], v138 offset:33792
	ds_read_b128 v[186:189], v137 offset:32768
	ds_read_b128 v[190:193], v137 offset:33792
	ds_read_b128 v[194:197], v136 offset:32768
	ds_read_b128 v[198:201], v136 offset:33792
	ds_read_b128 v[202:205], v135 offset:32768
	ds_read_b128 v[206:209], v135 offset:33792
	buffer_load_dwordx4 v139, s[8:11], s66 offen lds
	s_mov_b32 m0, s67
	s_nop 0
	buffer_load_dwordx4 v141, s[8:11], s66 offen lds
	s_waitcnt lgkmcnt(8)
	s_barrier
	s_waitcnt lgkmcnt(0)
	s_setprio 1
	s_waitcnt lgkmcnt(7)
	v_mfma_f32_16x16x32_bf16 v[126:129], v[178:181], v[162:165], v[126:129]
	v_mfma_f32_16x16x32_bf16 v[122:125], v[178:181], v[170:173], v[122:125]
	s_waitcnt lgkmcnt(5)
	v_mfma_f32_16x16x32_bf16 v[118:121], v[186:189], v[162:165], v[118:121]
	v_mfma_f32_16x16x32_bf16 v[114:117], v[186:189], v[170:173], v[114:117]
	s_waitcnt lgkmcnt(3)
	v_mfma_f32_16x16x32_bf16 v[110:113], v[194:197], v[162:165], v[110:113]
	v_mfma_f32_16x16x32_bf16 v[106:109], v[194:197], v[170:173], v[106:109]
	s_waitcnt lgkmcnt(1)
	v_mfma_f32_16x16x32_bf16 v[102:105], v[202:205], v[162:165], v[102:105]
	v_mfma_f32_16x16x32_bf16 v[98:101], v[202:205], v[170:173], v[98:101]
	v_mfma_f32_16x16x32_bf16 v[126:129], v[182:185], v[166:169], v[126:129]
	v_mfma_f32_16x16x32_bf16 v[122:125], v[182:185], v[174:177], v[122:125]
	v_mfma_f32_16x16x32_bf16 v[118:121], v[190:193], v[166:169], v[118:121]
	v_mfma_f32_16x16x32_bf16 v[114:117], v[190:193], v[174:177], v[114:117]
	v_mfma_f32_16x16x32_bf16 v[110:113], v[198:201], v[166:169], v[110:113]
	v_mfma_f32_16x16x32_bf16 v[106:109], v[198:201], v[174:177], v[106:109]
	s_waitcnt lgkmcnt(0)
	v_mfma_f32_16x16x32_bf16 v[102:105], v[206:209], v[166:169], v[102:105]
	v_mfma_f32_16x16x32_bf16 v[98:101], v[206:209], v[174:177], v[98:101]
	s_setprio 0
	s_barrier
	v_readfirstlane_b32 s67, v151
	s_add_i32 s66, s7, 0xffea0000
	s_mov_b32 m0, s67
	v_readfirstlane_b32 s67, v152
	ds_read_b128 v[210:213], v140
	ds_read_b128 v[214:217], v140 offset:1024
	ds_read_b128 v[218:221], v140 offset:2048
	ds_read_b128 v[222:225], v140 offset:3072
	buffer_load_dwordx4 v139, s[0:3], s66 offen lds
	s_mov_b32 m0, s67
	s_nop 0
	buffer_load_dwordx4 v141, s[0:3], s66 offen lds
	s_barrier
	s_waitcnt lgkmcnt(0)
	s_setprio 1
	s_waitcnt lgkmcnt(3)
	v_mfma_f32_16x16x32_bf16 v[94:97], v[178:181], v[210:213], v[94:97]
	s_waitcnt lgkmcnt(1)
	v_mfma_f32_16x16x32_bf16 v[90:93], v[178:181], v[218:221], v[90:93]
	v_mfma_f32_16x16x32_bf16 v[86:89], v[186:189], v[210:213], v[86:89]
	v_mfma_f32_16x16x32_bf16 v[82:85], v[186:189], v[218:221], v[82:85]
	v_mfma_f32_16x16x32_bf16 v[78:81], v[194:197], v[210:213], v[78:81]
	v_mfma_f32_16x16x32_bf16 v[74:77], v[194:197], v[218:221], v[74:77]
	v_mfma_f32_16x16x32_bf16 v[70:73], v[202:205], v[210:213], v[70:73]
	v_mfma_f32_16x16x32_bf16 v[66:69], v[202:205], v[218:221], v[66:69]
	v_mfma_f32_16x16x32_bf16 v[94:97], v[182:185], v[214:217], v[94:97]
	s_waitcnt lgkmcnt(0)
	v_mfma_f32_16x16x32_bf16 v[90:93], v[182:185], v[222:225], v[90:93]
	v_mfma_f32_16x16x32_bf16 v[86:89], v[190:193], v[214:217], v[86:89]
	v_mfma_f32_16x16x32_bf16 v[82:85], v[190:193], v[222:225], v[82:85]
	v_mfma_f32_16x16x32_bf16 v[78:81], v[198:201], v[214:217], v[78:81]
	v_mfma_f32_16x16x32_bf16 v[74:77], v[198:201], v[222:225], v[74:77]
	v_mfma_f32_16x16x32_bf16 v[70:73], v[206:209], v[214:217], v[70:73]
	v_mfma_f32_16x16x32_bf16 v[66:69], v[206:209], v[222:225], v[66:69]
	s_setprio 0
	v_readfirstlane_b32 s67, v153
	s_mov_b32 m0, s67
	v_readfirstlane_b32 s67, v155
	s_barrier
	ds_read_b128 v[178:181], v138 offset:49152
	ds_read_b128 v[182:185], v138 offset:50176
	ds_read_b128 v[186:189], v137 offset:49152
	ds_read_b128 v[190:193], v137 offset:50176
	ds_read_b128 v[194:197], v136 offset:49152
	ds_read_b128 v[198:201], v136 offset:50176
	ds_read_b128 v[202:205], v135 offset:49152
	ds_read_b128 v[206:209], v135 offset:50176
	buffer_load_dwordx4 v139, s[8:11], s66 offen lds
	s_mov_b32 m0, s67
	s_nop 0
	buffer_load_dwordx4 v141, s[8:11], s66 offen lds
	s_barrier
; #define STAGE(P, BASE, LD, br, kt) do { const int _so = (int)(((br) * (LD) + (kt) * BK) * 2); \
;     _Pragma("unroll") for (int _i = 0; _i < 2; ++_i) { \
;       __builtin_amdgcn_raw_ptr_buffer_load_lds(rs##BASE, (__attribute__((address_space(3))) unsigned*)((char*)(P) + tid_ * 16 + _i * 8192), 16, (int)off##LD[_i], _so, 0, 0); } } while (0)
; #define LDA_(dst, b, h) _Pragma("unroll") for (int m = 0; m < 4; ++m) _Pragma("unroll") for (int k = 0; k < 2; ++k) \
;     dst[m][k] = *reinterpret_cast<const bf16x8*>((char*)SA(b, h) + lds_byte(wr * 64 + m * 16 + fr, k * 32 + fq * 8))
; #define LDB_(dst, b, h) _Pragma("unroll") for (int n = 0; n < 2; ++n) _Pragma("unroll") for (int k = 0; k < 2; ++k) \
;     dst[n][k] = *reinterpret_cast<const bf16x8*>((char*)SB(b, h) + lds_byte(wc * 32 + n * 16 + fr, k * 32 + fq * 8))
; #define MMA(ai, bj, At, Bx) do { __builtin_amdgcn_s_setprio(1); \
;     _Pragma("unroll") for (int m = 0; m < 4; ++m) _Pragma("unroll") for (int n = 0; n < 2; ++n) _Pragma("unroll") for (int k = 0; k < 2; ++k) \
;       acc[ai][bj][m][n] = __builtin_amdgcn_mfma_f32_16x16x32_bf16(At[m][k], Bx[n][k], acc[ai][bj][m][n], 0, 0, 0); \
;     __builtin_amdgcn_s_setprio(0); } while (0)
; #define WAIT_V(n) asm volatile("s_waitcnt vmcnt(" #n ")" ::: "memory")
; #define WAIT_L(n) asm volatile("s_waitcnt lgkmcnt(" #n ")" ::: "memory")
; #define BAR __builtin_amdgcn_s_barrier()
; #define SCHED __builtin_amdgcn_sched_barrier(0)
; template <int K, int LDA, int LDB>
; DEVI void gemm_tile(const bf16* __restrict__ A, const bf16* __restrict__ Bt, bf16* shm, acc_t& acc) {
;     ...
;     BAR; WAIT_L(0); MMA(1, 0, At, B0); BAR; SCHED;
;     STAGE(SB(1, 1), Bt, LDB, HALF, t + 3);
;     WAIT_V(6); BAR; MMA(1, 1, At, B1); BAR;
;   }
;   { LDB_(B0, 0, 0); LDA_(At, 0, 0); STAGE(SA(1, 1), A, LDA, HALF, nt - 1);
;     BAR; WAIT_L(0); MMA(0, 0, At, B0); BAR;
;     LDB_(B1, 0, 1); BAR; WAIT_L(0); MMA(0, 1, At, B1); BAR;
	s_waitcnt lgkmcnt(0)
	s_setprio 1
	s_waitcnt lgkmcnt(7)
	v_mfma_f32_16x16x32_bf16 v[62:65], v[178:181], v[162:165], v[62:65]
	v_mfma_f32_16x16x32_bf16 v[58:61], v[178:181], v[170:173], v[58:61]
	s_waitcnt lgkmcnt(5)
	v_mfma_f32_16x16x32_bf16 v[54:57], v[186:189], v[162:165], v[54:57]
	v_mfma_f32_16x16x32_bf16 v[50:53], v[186:189], v[170:173], v[50:53]
	s_waitcnt lgkmcnt(3)
	v_mfma_f32_16x16x32_bf16 v[46:49], v[194:197], v[162:165], v[46:49]
	v_mfma_f32_16x16x32_bf16 v[42:45], v[194:197], v[170:173], v[42:45]
	s_waitcnt lgkmcnt(1)
	v_mfma_f32_16x16x32_bf16 v[38:41], v[202:205], v[162:165], v[38:41]
	v_mfma_f32_16x16x32_bf16 v[34:37], v[202:205], v[170:173], v[34:37]
	v_mfma_f32_16x16x32_bf16 v[62:65], v[182:185], v[166:169], v[62:65]
	v_mfma_f32_16x16x32_bf16 v[58:61], v[182:185], v[174:177], v[58:61]
	v_mfma_f32_16x16x32_bf16 v[54:57], v[190:193], v[166:169], v[54:57]
	v_mfma_f32_16x16x32_bf16 v[50:53], v[190:193], v[174:177], v[50:53]
	v_mfma_f32_16x16x32_bf16 v[46:49], v[198:201], v[166:169], v[46:49]
	v_mfma_f32_16x16x32_bf16 v[42:45], v[198:201], v[174:177], v[42:45]
	s_waitcnt lgkmcnt(0)
	v_mfma_f32_16x16x32_bf16 v[38:41], v[206:209], v[166:169], v[38:41]
	v_mfma_f32_16x16x32_bf16 v[34:37], v[206:209], v[174:177], v[34:37]
	s_setprio 0
	s_barrier
	v_readfirstlane_b32 s66, v157
	s_mov_b32 m0, s66
	v_readfirstlane_b32 s66, v158
	buffer_load_dwordx4 v139, s[0:3], s7 offen lds
	s_mov_b32 m0, s66
	s_nop 0
	buffer_load_dwordx4 v141, s[0:3], s7 offen lds
	s_waitcnt vmcnt(6)
	s_barrier
	s_setprio 1
	v_mfma_f32_16x16x32_bf16 v[30:33], v[178:181], v[210:213], v[30:33]
	v_mfma_f32_16x16x32_bf16 v[26:29], v[178:181], v[218:221], v[26:29]
	v_mfma_f32_16x16x32_bf16 v[22:25], v[186:189], v[210:213], v[22:25]
	v_mfma_f32_16x16x32_bf16 v[18:21], v[186:189], v[218:221], v[18:21]
	v_mfma_f32_16x16x32_bf16 v[14:17], v[194:197], v[210:213], v[14:17]
	v_mfma_f32_16x16x32_bf16 v[10:13], v[194:197], v[218:221], v[10:13]
	v_mfma_f32_16x16x32_bf16 v[6:9], v[202:205], v[210:213], v[6:9]
	v_mfma_f32_16x16x32_bf16 v[2:5], v[202:205], v[218:221], v[2:5]
	v_mfma_f32_16x16x32_bf16 v[30:33], v[182:185], v[214:217], v[30:33]
	v_mfma_f32_16x16x32_bf16 v[26:29], v[182:185], v[222:225], v[26:29]
	v_mfma_f32_16x16x32_bf16 v[22:25], v[190:193], v[214:217], v[22:25]
	v_mfma_f32_16x16x32_bf16 v[18:21], v[190:193], v[222:225], v[18:21]
	v_mfma_f32_16x16x32_bf16 v[14:17], v[198:201], v[214:217], v[14:17]
	v_mfma_f32_16x16x32_bf16 v[10:13], v[198:201], v[222:225], v[10:13]
	v_mfma_f32_16x16x32_bf16 v[6:9], v[206:209], v[214:217], v[6:9]
	v_mfma_f32_16x16x32_bf16 v[2:5], v[206:209], v[222:225], v[2:5]
	s_setprio 0
	s_add_i32 s6, s6, 2
	s_addk_i32 s7, 0x100
	s_cmpk_lt_u32 s6, 0x54
	s_cbranch_scc1 .Lrot_48600
	s_barrier
	v_readfirstlane_b32 s0, v156
	s_mov_b32 s10, s2
	s_mov_b32 s11, s3
	s_mov_b32 m0, s0
	v_readfirstlane_b32 s0, v159
	ds_read_b128 v[144:147], v160
	ds_read_b128 v[148:151], v160 offset:1024
	ds_read_b128 v[162:165], v160 offset:2048
	ds_read_b128 v[166:169], v160 offset:3072
	ds_read_b128 v[170:173], v138
	ds_read_b128 v[174:177], v138 offset:1024
	ds_read_b128 v[178:181], v137
	ds_read_b128 v[182:185], v137 offset:1024
	ds_read_b128 v[186:189], v136
	ds_read_b128 v[190:193], v136 offset:1024
	ds_read_b128 v[194:197], v135
	ds_read_b128 v[198:201], v135 offset:1024
	buffer_load_dwordx4 v139, s[8:11], s35 offen lds
	s_mov_b32 m0, s0
	s_nop 0
	buffer_load_dwordx4 v141, s[8:11], s35 offen lds
	s_barrier
	s_waitcnt lgkmcnt(0)
	s_setprio 1
	s_waitcnt lgkmcnt(7)
	v_mfma_f32_16x16x32_bf16 v[126:129], v[170:173], v[144:147], v[126:129]
	v_mfma_f32_16x16x32_bf16 v[122:125], v[170:173], v[162:165], v[122:125]
	s_waitcnt lgkmcnt(5)
	v_mfma_f32_16x16x32_bf16 v[118:121], v[178:181], v[144:147], v[118:121]
	v_mfma_f32_16x16x32_bf16 v[114:117], v[178:181], v[162:165], v[114:117]
	s_waitcnt lgkmcnt(3)
	v_mfma_f32_16x16x32_bf16 v[110:113], v[186:189], v[144:147], v[110:113]
	v_mfma_f32_16x16x32_bf16 v[106:109], v[186:189], v[162:165], v[106:109]
	s_waitcnt lgkmcnt(1)
	v_mfma_f32_16x16x32_bf16 v[102:105], v[194:197], v[144:147], v[102:105]
	v_mfma_f32_16x16x32_bf16 v[98:101], v[194:197], v[162:165], v[98:101]
	v_mfma_f32_16x16x32_bf16 v[126:129], v[174:177], v[148:151], v[126:129]
	v_mfma_f32_16x16x32_bf16 v[122:125], v[174:177], v[166:169], v[122:125]
	v_mfma_f32_16x16x32_bf16 v[118:121], v[182:185], v[148:151], v[118:121]
	v_mfma_f32_16x16x32_bf16 v[114:117], v[182:185], v[166:169], v[114:117]
	v_mfma_f32_16x16x32_bf16 v[110:113], v[190:193], v[148:151], v[110:113]
	v_mfma_f32_16x16x32_bf16 v[106:109], v[190:193], v[166:169], v[106:109]
	s_waitcnt lgkmcnt(0)
	v_mfma_f32_16x16x32_bf16 v[102:105], v[198:201], v[148:151], v[102:105]
	v_mfma_f32_16x16x32_bf16 v[98:101], v[198:201], v[166:169], v[98:101]
	s_setprio 0
	s_barrier
	ds_read_b128 v[156:159], v154
	ds_read_b128 v[202:205], v154 offset:1024
	ds_read_b128 v[206:209], v154 offset:2048
	ds_read_b128 v[152:155], v154 offset:3072
	s_barrier
	s_waitcnt lgkmcnt(0)
	s_setprio 1
	s_waitcnt lgkmcnt(3)
	v_mfma_f32_16x16x32_bf16 v[94:97], v[170:173], v[156:159], v[94:97]
	s_waitcnt lgkmcnt(1)
	v_mfma_f32_16x16x32_bf16 v[90:93], v[170:173], v[206:209], v[90:93]
	v_mfma_f32_16x16x32_bf16 v[86:89], v[178:181], v[156:159], v[86:89]
	v_mfma_f32_16x16x32_bf16 v[82:85], v[178:181], v[206:209], v[82:85]
	v_mfma_f32_16x16x32_bf16 v[74:77], v[186:189], v[206:209], v[74:77]
	v_mfma_f32_16x16x32_bf16 v[94:97], v[174:177], v[202:205], v[94:97]
	s_waitcnt lgkmcnt(0)
	v_mfma_f32_16x16x32_bf16 v[90:93], v[174:177], v[152:155], v[90:93]
	v_mfma_f32_16x16x32_bf16 v[86:89], v[182:185], v[202:205], v[86:89]
	v_mfma_f32_16x16x32_bf16 v[82:85], v[182:185], v[152:155], v[82:85]
	v_mfma_f32_16x16x32_bf16 v[78:81], v[186:189], v[156:159], v[78:81]
	v_mfma_f32_16x16x32_bf16 v[74:77], v[190:193], v[152:155], v[74:77]
	v_mfma_f32_16x16x32_bf16 v[70:73], v[194:197], v[156:159], v[70:73]
	v_mfma_f32_16x16x32_bf16 v[66:69], v[194:197], v[206:209], v[66:69]
	v_mfma_f32_16x16x32_bf16 v[170:173], v[190:193], v[202:205], v[78:81]
	v_mfma_f32_16x16x32_bf16 v[174:177], v[198:201], v[202:205], v[70:73]
	v_mfma_f32_16x16x32_bf16 v[178:181], v[198:201], v[152:155], v[66:69]
	s_setprio 0
	s_barrier
; #define LDA_(dst, b, h) _Pragma("unroll") for (int m = 0; m < 4; ++m) _Pragma("unroll") for (int k = 0; k < 2; ++k) \
;     dst[m][k] = *reinterpret_cast<const bf16x8*>((char*)SA(b, h) + lds_byte(wr * 64 + m * 16 + fr, k * 32 + fq * 8))
; #define LDB_(dst, b, h) _Pragma("unroll") for (int n = 0; n < 2; ++n) _Pragma("unroll") for (int k = 0; k < 2; ++k) \
;     dst[n][k] = *reinterpret_cast<const bf16x8*>((char*)SB(b, h) + lds_byte(wc * 32 + n * 16 + fr, k * 32 + fq * 8))
; #define MMA(ai, bj, At, Bx) do { __builtin_amdgcn_s_setprio(1); \
;     _Pragma("unroll") for (int m = 0; m < 4; ++m) _Pragma("unroll") for (int n = 0; n < 2; ++n) _Pragma("unroll") for (int k = 0; k < 2; ++k) \
;       acc[ai][bj][m][n] = __builtin_amdgcn_mfma_f32_16x16x32_bf16(At[m][k], Bx[n][k], acc[ai][bj][m][n], 0, 0, 0); \
;     __builtin_amdgcn_s_setprio(0); } while (0)
; #define WAIT_V(n) asm volatile("s_waitcnt vmcnt(" #n ")" ::: "memory")
; #define WAIT_L(n) asm volatile("s_waitcnt lgkmcnt(" #n ")" ::: "memory")
; #define BAR __builtin_amdgcn_s_barrier()
; template <int K, int LDA, int LDB>
; DEVI void gemm_tile(const bf16* __restrict__ A, const bf16* __restrict__ Bt, bf16* shm, acc_t& acc) {
;     ...
;     LDA_(At, 0, 1); WAIT_V(4); BAR; WAIT_L(0); MMA(1, 0, At, B0); MMA(1, 1, At, B1); BAR; }
;   { LDB_(B0, 1, 0); LDA_(At, 1, 0); WAIT_V(2); BAR; WAIT_L(0); MMA(0, 0, At, B0); BAR;
	s_nop 2
	ds_read_b128 v[66:69], v138 offset:16384
	ds_read_b128 v[70:73], v138 offset:17408
	ds_read_b128 v[78:81], v137 offset:16384
	ds_read_b128 v[182:185], v137 offset:17408
	ds_read_b128 v[186:189], v136 offset:16384
	ds_read_b128 v[190:193], v136 offset:17408
	ds_read_b128 v[194:197], v135 offset:16384
	ds_read_b128 v[198:201], v135 offset:17408
	s_waitcnt vmcnt(4)
	s_barrier
	s_waitcnt lgkmcnt(0)
	s_setprio 1
	s_waitcnt lgkmcnt(7)
	v_mfma_f32_16x16x32_bf16 v[62:65], v[66:69], v[144:147], v[62:65]
	s_waitcnt lgkmcnt(3)
	v_mfma_f32_16x16x32_bf16 v[46:49], v[186:189], v[144:147], v[46:49]
	s_waitcnt lgkmcnt(1)
	v_mfma_f32_16x16x32_bf16 v[38:41], v[194:197], v[144:147], v[38:41]
	v_mfma_f32_16x16x32_bf16 v[34:37], v[194:197], v[162:165], v[34:37]
	v_mfma_f32_16x16x32_bf16 v[62:65], v[70:73], v[148:151], v[62:65]
	v_mfma_f32_16x16x32_bf16 v[58:61], v[66:69], v[162:165], v[58:61]
	v_mfma_f32_16x16x32_bf16 v[54:57], v[78:81], v[144:147], v[54:57]
	v_mfma_f32_16x16x32_bf16 v[50:53], v[78:81], v[162:165], v[50:53]
	v_mfma_f32_16x16x32_bf16 v[46:49], v[190:193], v[148:151], v[46:49]
	v_mfma_f32_16x16x32_bf16 v[42:45], v[186:189], v[162:165], v[42:45]
	s_waitcnt lgkmcnt(0)
	v_mfma_f32_16x16x32_bf16 v[38:41], v[198:201], v[148:151], v[38:41]
	v_mfma_f32_16x16x32_bf16 v[34:37], v[198:201], v[166:169], v[34:37]
	v_mfma_f32_16x16x32_bf16 v[210:213], v[70:73], v[166:169], v[58:61]
	v_mfma_f32_16x16x32_bf16 v[214:217], v[182:185], v[148:151], v[54:57]
	v_mfma_f32_16x16x32_bf16 v[218:221], v[182:185], v[166:169], v[50:53]
	v_mfma_f32_16x16x32_bf16 v[222:225], v[190:193], v[166:169], v[42:45]
	s_setprio 0
	s_setprio 1
	v_mfma_f32_16x16x32_bf16 v[26:29], v[66:69], v[206:209], v[26:29]
	v_mfma_f32_16x16x32_bf16 v[22:25], v[78:81], v[156:159], v[22:25]
	v_mfma_f32_16x16x32_bf16 v[18:21], v[78:81], v[206:209], v[18:21]
	v_mfma_f32_16x16x32_bf16 v[14:17], v[186:189], v[156:159], v[14:17]
	v_mfma_f32_16x16x32_bf16 v[10:13], v[186:189], v[206:209], v[10:13]
	v_mfma_f32_16x16x32_bf16 v[6:9], v[194:197], v[156:159], v[6:9]
	v_mfma_f32_16x16x32_bf16 v[2:5], v[194:197], v[206:209], v[2:5]
	v_mfma_f32_16x16x32_bf16 v[30:33], v[66:69], v[156:159], v[30:33]
	v_mfma_f32_16x16x32_bf16 v[26:29], v[70:73], v[152:155], v[26:29]
	v_mfma_f32_16x16x32_bf16 v[22:25], v[182:185], v[202:205], v[22:25]
	v_mfma_f32_16x16x32_bf16 v[18:21], v[182:185], v[152:155], v[18:21]
	v_mfma_f32_16x16x32_bf16 v[14:17], v[190:193], v[202:205], v[14:17]
	v_mfma_f32_16x16x32_bf16 v[10:13], v[190:193], v[152:155], v[10:13]
	v_mfma_f32_16x16x32_bf16 v[6:9], v[198:201], v[202:205], v[6:9]
	v_mfma_f32_16x16x32_bf16 v[2:5], v[198:201], v[152:155], v[2:5]
	v_mfma_f32_16x16x32_bf16 v[144:147], v[70:73], v[202:205], v[30:33]
	s_setprio 0
	s_barrier
	ds_read_b128 v[148:151], v142
	ds_read_b128 v[152:155], v142 offset:1024
	ds_read_b128 v[156:159], v142 offset:2048
	ds_read_b128 v[160:163], v142 offset:3072
	ds_read_b128 v[50:53], v138 offset:32768
	ds_read_b128 v[66:69], v138 offset:33792
	ds_read_b128 v[164:167], v137 offset:32768
	ds_read_b128 v[182:185], v137 offset:33792
	ds_read_b128 v[186:189], v136 offset:32768
	ds_read_b128 v[190:193], v136 offset:33792
	ds_read_b128 v[194:197], v135 offset:32768
	ds_read_b128 v[198:201], v135 offset:33792
	s_waitcnt vmcnt(2)
	s_barrier
	s_waitcnt lgkmcnt(0)
	s_setprio 1
	s_waitcnt lgkmcnt(7)
	v_mfma_f32_16x16x32_bf16 v[30:33], v[50:53], v[148:151], v[126:129]
	s_waitcnt lgkmcnt(5)
	v_mfma_f32_16x16x32_bf16 v[42:45], v[164:167], v[148:151], v[118:121]
	s_waitcnt lgkmcnt(3)
	v_mfma_f32_16x16x32_bf16 v[54:57], v[186:189], v[148:151], v[110:113]
	s_waitcnt lgkmcnt(1)
	v_mfma_f32_16x16x32_bf16 v[58:61], v[194:197], v[148:151], v[102:105]
	v_mfma_f32_16x16x32_bf16 v[126:129], v[66:69], v[152:155], v[30:33]
	v_mfma_f32_16x16x32_bf16 v[30:33], v[50:53], v[156:159], v[122:125]
	v_mfma_f32_16x16x32_bf16 v[122:125], v[182:185], v[152:155], v[42:45]
	v_mfma_f32_16x16x32_bf16 v[42:45], v[164:167], v[156:159], v[114:117]
	v_mfma_f32_16x16x32_bf16 v[118:121], v[190:193], v[152:155], v[54:57]
	v_mfma_f32_16x16x32_bf16 v[54:57], v[186:189], v[156:159], v[106:109]
	s_waitcnt lgkmcnt(0)
	v_mfma_f32_16x16x32_bf16 v[114:117], v[198:201], v[152:155], v[58:61]
	v_mfma_f32_16x16x32_bf16 v[58:61], v[194:197], v[156:159], v[98:101]
	v_mfma_f32_16x16x32_bf16 v[30:33], v[66:69], v[160:163], v[30:33]
	v_mfma_f32_16x16x32_bf16 v[42:45], v[182:185], v[160:163], v[42:45]
	v_mfma_f32_16x16x32_bf16 v[54:57], v[190:193], v[160:163], v[54:57]
	v_mfma_f32_16x16x32_bf16 v[70:73], v[198:201], v[160:163], v[58:61]
	s_setprio 0
	s_barrier
; #define LDA_(dst, b, h) _Pragma("unroll") for (int m = 0; m < 4; ++m) _Pragma("unroll") for (int k = 0; k < 2; ++k) \
;     dst[m][k] = *reinterpret_cast<const bf16x8*>((char*)SA(b, h) + lds_byte(wr * 64 + m * 16 + fr, k * 32 + fq * 8))
; #define LDB_(dst, b, h) _Pragma("unroll") for (int n = 0; n < 2; ++n) _Pragma("unroll") for (int k = 0; k < 2; ++k) \
;     dst[n][k] = *reinterpret_cast<const bf16x8*>((char*)SB(b, h) + lds_byte(wc * 32 + n * 16 + fr, k * 32 + fq * 8))
; #define MMA(ai, bj, At, Bx) do { __builtin_amdgcn_s_setprio(1); \
;     _Pragma("unroll") for (int m = 0; m < 4; ++m) _Pragma("unroll") for (int n = 0; n < 2; ++n) _Pragma("unroll") for (int k = 0; k < 2; ++k) \
;       acc[ai][bj][m][n] = __builtin_amdgcn_mfma_f32_16x16x32_bf16(At[m][k], Bx[n][k], acc[ai][bj][m][n], 0, 0, 0); \
;     __builtin_amdgcn_s_setprio(0); } while (0)
; #define WAIT_V(n) asm volatile("s_waitcnt vmcnt(" #n ")" ::: "memory")
; #define WAIT_L(n) asm volatile("s_waitcnt lgkmcnt(" #n ")" ::: "memory")
; #define BAR __builtin_amdgcn_s_barrier()
; template <int K, int LDA, int LDB>
; DEVI void gemm_tile(const bf16* __restrict__ A, const bf16* __restrict__ Bt, bf16* shm, acc_t& acc) {
;     ...
;     LDB_(B1, 1, 1); WAIT_V(0); BAR; WAIT_L(0); MMA(0, 1, At, B1); BAR;
;     LDA_(At, 1, 1); BAR; WAIT_L(0); MMA(1, 0, At, B0); MMA(1, 1, At, B1); BAR; }
;   if (wr == 0) BAR;
	ds_read_b128 v[202:205], v140
	ds_read_b128 v[206:209], v140 offset:1024
	ds_read_b128 v[226:229], v140 offset:2048
	ds_read_b128 v[140:143], v140 offset:3072
	s_waitcnt vmcnt(0)
	s_barrier
	s_waitcnt lgkmcnt(0)
	s_setprio 1
	s_waitcnt lgkmcnt(3)
	v_mfma_f32_16x16x32_bf16 v[58:61], v[50:53], v[202:205], v[94:97]
	s_waitcnt lgkmcnt(1)
	v_mfma_f32_16x16x32_bf16 v[50:53], v[50:53], v[226:229], v[90:93]
	v_mfma_f32_16x16x32_bf16 v[58:61], v[66:69], v[206:209], v[58:61]
	s_waitcnt lgkmcnt(0)
	v_mfma_f32_16x16x32_bf16 v[50:53], v[66:69], v[140:143], v[50:53]
	v_mfma_f32_16x16x32_bf16 v[66:69], v[164:167], v[202:205], v[86:89]
	v_mfma_f32_16x16x32_bf16 v[78:81], v[182:185], v[206:209], v[66:69]
	v_mfma_f32_16x16x32_bf16 v[66:69], v[164:167], v[226:229], v[82:85]
	v_mfma_f32_16x16x32_bf16 v[82:85], v[186:189], v[202:205], v[170:173]
	v_mfma_f32_16x16x32_bf16 v[74:77], v[186:189], v[226:229], v[74:77]
	v_mfma_f32_16x16x32_bf16 v[94:97], v[190:193], v[206:209], v[82:85]
	v_mfma_f32_16x16x32_bf16 v[82:85], v[190:193], v[140:143], v[74:77]
	v_mfma_f32_16x16x32_bf16 v[74:77], v[194:197], v[202:205], v[174:177]
	v_mfma_f32_16x16x32_bf16 v[110:113], v[198:201], v[206:209], v[74:77]
	v_mfma_f32_16x16x32_bf16 v[74:77], v[194:197], v[226:229], v[178:181]
	v_mfma_f32_16x16x32_bf16 v[66:69], v[182:185], v[140:143], v[66:69]
	v_mfma_f32_16x16x32_bf16 v[98:101], v[198:201], v[140:143], v[74:77]
	s_setprio 0
	s_barrier
	ds_read_b128 v[164:167], v138 offset:49152
	ds_read_b128 v[168:171], v138 offset:50176
	ds_read_b128 v[172:175], v137 offset:49152
	ds_read_b128 v[176:179], v137 offset:50176
	ds_read_b128 v[180:183], v136 offset:49152
	ds_read_b128 v[136:139], v136 offset:50176
	ds_read_b128 v[184:187], v135 offset:49152
	ds_read_b128 v[188:191], v135 offset:50176
	s_barrier
	s_waitcnt lgkmcnt(0)
	s_setprio 1
	s_waitcnt lgkmcnt(7)
	v_mfma_f32_16x16x32_bf16 v[62:65], v[164:167], v[148:151], v[62:65]
	s_waitcnt lgkmcnt(6)
	v_mfma_f32_16x16x32_bf16 v[106:109], v[168:171], v[152:155], v[62:65]
	v_mfma_f32_16x16x32_bf16 v[62:65], v[164:167], v[156:159], v[210:213]
	v_mfma_f32_16x16x32_bf16 v[102:105], v[168:171], v[160:163], v[62:65]
	s_waitcnt lgkmcnt(5)
	v_mfma_f32_16x16x32_bf16 v[62:65], v[172:175], v[148:151], v[214:217]
	s_waitcnt lgkmcnt(3)
	v_mfma_f32_16x16x32_bf16 v[46:49], v[180:183], v[148:151], v[46:49]
	v_mfma_f32_16x16x32_bf16 v[90:93], v[176:179], v[152:155], v[62:65]
	v_mfma_f32_16x16x32_bf16 v[62:65], v[172:175], v[156:159], v[218:221]
	s_waitcnt lgkmcnt(2)
	v_mfma_f32_16x16x32_bf16 v[74:77], v[136:139], v[152:155], v[46:49]
	v_mfma_f32_16x16x32_bf16 v[46:49], v[180:183], v[156:159], v[222:225]
	s_waitcnt lgkmcnt(1)
	v_mfma_f32_16x16x32_bf16 v[38:41], v[184:187], v[148:151], v[38:41]
	v_mfma_f32_16x16x32_bf16 v[34:37], v[184:187], v[156:159], v[34:37]
	v_mfma_f32_16x16x32_bf16 v[86:89], v[176:179], v[160:163], v[62:65]
	v_mfma_f32_16x16x32_bf16 v[62:65], v[136:139], v[160:163], v[46:49]
	s_waitcnt lgkmcnt(0)
	v_mfma_f32_16x16x32_bf16 v[46:49], v[188:191], v[152:155], v[38:41]
	v_mfma_f32_16x16x32_bf16 v[38:41], v[188:191], v[160:163], v[34:37]
	s_setprio 0
	s_setprio 1
	v_mfma_f32_16x16x32_bf16 v[34:37], v[164:167], v[202:205], v[144:147]
	v_mfma_f32_16x16x32_bf16 v[26:29], v[164:167], v[226:229], v[26:29]
	v_mfma_f32_16x16x32_bf16 v[22:25], v[172:175], v[202:205], v[22:25]
	v_mfma_f32_16x16x32_bf16 v[18:21], v[172:175], v[226:229], v[18:21]
	v_mfma_f32_16x16x32_bf16 v[14:17], v[180:183], v[202:205], v[14:17]
	v_mfma_f32_16x16x32_bf16 v[10:13], v[180:183], v[226:229], v[10:13]
	v_mfma_f32_16x16x32_bf16 v[6:9], v[184:187], v[202:205], v[6:9]
	v_mfma_f32_16x16x32_bf16 v[2:5], v[184:187], v[226:229], v[2:5]
	v_mfma_f32_16x16x32_bf16 v[34:37], v[168:171], v[206:209], v[34:37]
	v_mfma_f32_16x16x32_bf16 v[26:29], v[168:171], v[140:143], v[26:29]
	v_mfma_f32_16x16x32_bf16 v[22:25], v[176:179], v[206:209], v[22:25]
	v_mfma_f32_16x16x32_bf16 v[18:21], v[176:179], v[140:143], v[18:21]
	v_mfma_f32_16x16x32_bf16 v[14:17], v[136:139], v[206:209], v[14:17]
	v_mfma_f32_16x16x32_bf16 v[10:13], v[136:139], v[140:143], v[10:13]
	v_mfma_f32_16x16x32_bf16 v[6:9], v[188:191], v[206:209], v[6:9]
	v_mfma_f32_16x16x32_bf16 v[2:5], v[188:191], v[140:143], v[2:5]
	s_setprio 0
	v_cmp_gt_u32_e32 vcc, s34, v132
	s_barrier
	s_and_saveexec_b64 s[0:1], vcc
	s_cbranch_execz .LBB0_2104
	s_barrier
